# padded packed producers recomputed with exchanged lanes (op_sel_hi[0]=0) so the hazard pad is not needed: 144 more pads removed
# speedup vs baseline: 1.0009x; 1.0009x over previous
.LBB0_24:
	s_waitcnt vmcnt(5)
	v_add_u32_e32 v2, 0xffffc000, v78
	v_cmp_gt_i32_e32 vcc, s33, v78
	v_add_u32_e32 v80, s31, v78
	s_nop 0
	v_cndmask_b32_e32 v3, 0, v79, vcc
	v_cndmask_b32_e32 v2, v2, v78, vcc
	v_cndmask_b32_e32 v5, v85, v86, vcc
	v_cndmask_b32_e32 v4, v87, v88, vcc
	v_lshlrev_b64 v[2:3], 13, v[2:3]
	v_lshl_add_u64 v[2:3], v[4:5], 0, v[2:3]
	v_lshl_add_u64 v[4:5], v[2:3], 0, v[68:69]
	global_load_dwordx4 v[54:57], v[4:5], off nt
	global_load_dwordx4 v[50:53], v[4:5], off offset:16 nt
	global_load_dwordx4 v[30:33], v[4:5], off offset:2048 nt
	global_load_dwordx4 v[26:29], v[4:5], off offset:2064 nt
	v_lshl_add_u64 v[4:5], v[2:3], 0, v[74:75]
	v_lshl_add_u64 v[2:3], v[2:3], 0, v[76:77]
	global_load_dwordx4 v[58:61], v[4:5], off offset:16 nt
	global_load_dwordx4 v[42:45], v[2:3], off nt
	global_load_dwordx4 v[46:49], v[2:3], off offset:16 nt
	global_load_dwordx4 v[90:93], v[4:5], off nt
	v_cmp_gt_i32_e32 vcc, s30, v80
	s_waitcnt vmcnt(7)
	v_pk_mul_f32 v[2:3], v[56:57], v[56:57]
	v_pk_mul_f32 v[4:5], v[54:55], v[54:55]
	s_waitcnt vmcnt(6)
	v_pk_mul_f32 v[6:7], v[52:53], v[52:53]
	v_pk_mul_f32 v[8:9], v[50:51], v[50:51]
	s_waitcnt vmcnt(5)
	v_pk_mul_f32 v[10:11], v[32:33], v[32:33]
	v_pk_mul_f32 v[12:13], v[30:31], v[30:31]
	s_waitcnt vmcnt(4)
	v_pk_mul_f32 v[14:15], v[28:29], v[28:29]
	v_pk_mul_f32 v[16:17], v[26:27], v[26:27]
	v_pk_mov_b32 v[38:39], v[4:5], v[2:3] op_sel:[1,0]
	v_mov_b32_e32 v5, v3
	v_mov_b32_e32 v2, v6
	v_mov_b32_e32 v3, v8
	v_mov_b32_e32 v8, v7
	v_pk_mov_b32 v[6:7], v[12:13], v[10:11] op_sel:[1,0]
	v_mov_b32_e32 v13, v11
	s_waitcnt vmcnt(3)
	v_mov_b32_e32 v20, v59
	s_waitcnt vmcnt(2)
	v_mov_b32_e32 v21, v43
	v_mov_b32_e32 v24, v61
	s_waitcnt vmcnt(1)
	v_mov_b32_e32 v25, v47
	s_waitcnt vmcnt(0)
	v_mul_f32_e32 v34, v91, v91
	v_mul_f32_e32 v37, v44, v44
	v_mul_f32_e32 v36, v93, v93
	v_mov_b32_e32 v10, v14
	v_mov_b32_e32 v11, v16
	v_mov_b32_e32 v16, v15
	v_pk_add_f32 v[4:5], v[38:39], v[4:5]
	v_pk_add_f32 v[6:7], v[6:7], v[12:13]
	v_mul_f32_e32 v40, v45, v45
	v_pk_mul_f32 v[14:15], v[20:21], v[20:21]
	v_pk_mul_f32 v[20:21], v[24:25], v[24:25]
	v_pk_fma_f32 v[24:25], v[90:91], v[90:91], v[34:35] op_sel_hi:[1,1,0]
	v_pk_fma_f32 v[34:35], v[92:93], v[92:93], v[36:37] op_sel_hi:[1,1,0]
	v_pk_add_f32 v[2:3], v[2:3], v[8:9]
	v_pk_add_f32 v[8:9], v[10:11], v[16:17]
	v_pk_add_f32 v[4:5], v[4:5], v[4:5] op_sel:[0,1] op_sel_hi:[1,0]
	v_pk_add_f32 v[6:7], v[6:7], v[6:7] op_sel:[0,1] op_sel_hi:[1,0]
	v_mov_b32_e32 v18, v58
	v_mov_b32_e32 v19, v42
	v_mov_b32_e32 v25, v37
	v_mov_b32_e32 v35, v40
	v_pk_add_f32 v[4:5], v[4:5], v[2:3] op_sel:[0,1] op_sel_hi:[1,0]
	v_pk_add_f32 v[6:7], v[6:7], v[8:9] op_sel:[0,1] op_sel_hi:[1,0]
	v_mov_b32_e32 v22, v60
	v_mov_b32_e32 v23, v46
	v_pk_fma_f32 v[10:11], v[18:19], v[18:19], v[14:15]
	v_pk_add_f32 v[14:15], v[24:25], v[34:35]
	v_pk_add_f32 v[2:3], v[2:3], v[4:5]
	v_pk_add_f32 v[4:5], v[8:9], v[6:7]
	v_pk_fma_f32 v[12:13], v[22:23], v[22:23], v[20:21]
	v_pk_add_f32 v[10:11], v[10:11], v[14:15]
	v_mul_f32_e32 v3, v48, v48
	v_mul_f32_e32 v5, v49, v49
	v_pk_add_f32 v[6:7], v[10:11], v[12:13]
	v_pk_add_f32 v[2:3], v[2:3], v[4:5]
	v_cndmask_b32_e32 v4, v78, v80, vcc
	v_pk_add_f32 v[2:3], v[2:3], v[6:7]
	v_add_u32_e32 v6, 0xffffc000, v4
	v_add_f32_e32 v2, v2, v3
	ds_bpermute_b32 v3, v1, v2
	v_cmp_gt_i32_e64 s[0:1], s33, v4
	s_waitcnt lgkmcnt(0)
	v_add_f32_e32 v2, v2, v3
	ds_bpermute_b32 v3, v63, v2
	s_waitcnt lgkmcnt(0)
	v_add_f32_e32 v2, v2, v3
	ds_bpermute_b32 v5, v65, v2
	v_ashrrev_i32_e32 v3, 31, v4
	v_cndmask_b32_e64 v3, 0, v3, s[0:1]
	s_waitcnt lgkmcnt(0)
	v_add_f32_e32 v7, v2, v5
	ds_bpermute_b32 v8, v82, v7
	v_cndmask_b32_e64 v2, v6, v4, s[0:1]
	v_cndmask_b32_e64 v5, v85, v86, s[0:1]
	v_cndmask_b32_e64 v4, v87, v88, s[0:1]
	v_lshlrev_b64 v[2:3], 13, v[2:3]
	s_waitcnt lgkmcnt(0)
	v_add_f32_e32 v10, v7, v8
	ds_bpermute_b32 v11, v83, v10
	v_lshl_add_u64 v[2:3], v[4:5], 0, v[2:3]
	v_lshl_add_u64 v[4:5], v[2:3], 0, v[68:69]
	v_lshl_add_u64 v[6:7], v[2:3], 0, v[74:75]
	v_lshl_add_u64 v[8:9], v[2:3], 0, v[76:77]
	s_waitcnt lgkmcnt(0)
	v_add_f32_e32 v2, v10, v11
	ds_bpermute_b32 v3, v84, v2
	global_load_dwordx4 v[34:37], v[4:5], off offset:16 nt
	global_load_dwordx4 v[38:41], v[4:5], off nt
	global_load_dwordx4 v[18:21], v[4:5], off offset:2064 nt
	global_load_dwordx4 v[22:25], v[4:5], off offset:2048 nt
	s_waitcnt lgkmcnt(0)
	v_add_f32_e32 v2, v2, v3
	v_fmamk_f32 v2, v2, 0x3a000000, v89
	v_mul_f32_e32 v3, 0x4b800000, v2
	v_cmp_gt_f32_e64 s[0:1], s35, v2
	s_nop 1
	v_cndmask_b32_e64 v2, v2, v3, s[0:1]
	v_rsq_f32_e32 v81, v2
	global_load_dwordx4 v[10:13], v[6:7], off offset:16 nt
	global_load_dwordx4 v[14:17], v[6:7], off nt
	global_load_dwordx4 v[2:5], v[8:9], off offset:16 nt
	s_nop 0
	global_load_dwordx4 v[6:9], v[8:9], off nt
	v_mul_f32_e32 v94, 0x45800000, v81
	v_cndmask_b32_e64 v94, v81, v94, s[0:1]
	v_pk_mul_f32 v[56:57], v[56:57], v[94:95] op_sel_hi:[1,0]
	v_pk_mul_f32 v[54:55], v[54:55], v[94:95] op_sel_hi:[1,0]
	v_pk_mul_f32 v[52:53], v[52:53], v[94:95] op_sel_hi:[1,0]
	v_pk_mul_f32 v[50:51], v[50:51], v[94:95] op_sel_hi:[1,0]
	v_bfe_u32 v81, v54, 16, 1
	v_bfe_u32 v96, v56, 16, 1
	v_bfe_u32 v98, v50, 16, 1
	v_bfe_u32 v99, v51, 16, 1
	v_bfe_u32 v100, v52, 16, 1
	v_bfe_u32 v95, v55, 16, 1
	v_bfe_u32 v97, v57, 16, 1
	v_bfe_u32 v101, v53, 16, 1
	v_add3_u32 v54, v54, v81, s60
	v_add3_u32 v56, v56, v96, s60
	v_add3_u32 v50, v50, v98, s60
	v_add3_u32 v81, v51, v99, s60
	v_add3_u32 v51, v52, v100, s60
	v_add3_u32 v55, v55, v95, s60
	v_add3_u32 v57, v57, v97, s60
	v_add3_u32 v53, v53, v101, s60
	v_lshrrev_b32_e32 v52, 16, v54
	v_lshrrev_b32_e32 v54, 16, v56
	v_lshrrev_b32_e32 v56, 16, v50
	v_lshrrev_b32_e32 v95, 16, v51
	v_and_or_b32 v50, v55, s61, v52
	v_and_or_b32 v51, v57, s61, v54
	v_and_or_b32 v52, v81, s61, v56
	v_and_or_b32 v53, v53, s61, v95
	v_pk_mul_f32 v[30:31], v[30:31], v[94:95] op_sel_hi:[1,0]
	global_store_dwordx4 v[72:73], v[50:53], off offset:-3072
	v_pk_mul_f32 v[32:33], v[32:33], v[94:95] op_sel_hi:[1,0]
	s_nop 0
	v_pk_mul_f32 v[50:51], v[28:29], v[94:95] op_sel_hi:[1,0]
	v_pk_mul_f32 v[28:29], v[26:27], v[94:95] op_sel_hi:[1,0]
	v_bfe_u32 v26, v30, 16, 1
	v_add3_u32 v26, v30, v26, s60
	v_bfe_u32 v27, v31, 16, 1
	v_bfe_u32 v30, v32, 16, 1
	v_add3_u32 v27, v31, v27, s60
	v_add3_u32 v30, v32, v30, s60
	v_bfe_u32 v31, v33, 16, 1
	v_add3_u32 v31, v33, v31, s60
	v_lshrrev_b32_e32 v26, 16, v26
	v_lshrrev_b32_e32 v30, 16, v30
	v_and_or_b32 v26, v27, s61, v26
	v_and_or_b32 v27, v31, s61, v30
	v_bfe_u32 v30, v28, 16, 1
	v_add3_u32 v28, v28, v30, s60
	v_bfe_u32 v30, v29, 16, 1
	v_add3_u32 v29, v29, v30, s60
	v_lshrrev_b32_e32 v28, 16, v28
	v_and_or_b32 v28, v29, s61, v28
	v_bfe_u32 v29, v50, 16, 1
	v_add3_u32 v29, v50, v29, s60
	v_bfe_u32 v30, v51, 16, 1
	v_add3_u32 v30, v51, v30, s60
	v_lshrrev_b32_e32 v29, 16, v29
	v_and_or_b32 v29, v30, s61, v29
	global_store_dwordx4 v[72:73], v[26:29], off offset:-2048
	v_pk_mul_f32 v[32:33], v[58:59], v[94:95] op_sel_hi:[1,0]
	v_pk_mul_f32 v[30:31], v[60:61], v[94:95] op_sel_hi:[1,0]
	v_pk_mul_f32 v[28:29], v[90:91], v[94:95] op_sel_hi:[1,0]
	v_pk_mul_f32 v[26:27], v[92:93], v[94:95] op_sel_hi:[1,0]
	v_bfe_u32 v50, v28, 16, 1
	v_add3_u32 v28, v28, v50, s60
	v_bfe_u32 v50, v29, 16, 1
	v_add3_u32 v29, v29, v50, s60
	v_bfe_u32 v50, v26, 16, 1
	v_add3_u32 v26, v26, v50, s60
	v_bfe_u32 v50, v27, 16, 1
	v_lshrrev_b32_e32 v28, 16, v28
	v_add3_u32 v27, v27, v50, s60
	v_lshrrev_b32_e32 v50, 16, v26
	v_and_or_b32 v26, v29, s61, v28
	v_bfe_u32 v28, v32, 16, 1
	v_add3_u32 v28, v32, v28, s60
	v_bfe_u32 v29, v33, 16, 1
	v_add3_u32 v29, v33, v29, s60
	v_lshrrev_b32_e32 v28, 16, v28
	v_and_or_b32 v28, v29, s61, v28
	v_bfe_u32 v29, v30, 16, 1
	v_add3_u32 v29, v30, v29, s60
	v_bfe_u32 v30, v31, 16, 1
	v_add3_u32 v30, v31, v30, s60
	v_lshrrev_b32_e32 v29, 16, v29
	v_and_or_b32 v27, v27, s61, v50
	v_and_or_b32 v29, v30, s61, v29
	global_store_dwordx4 v[72:73], v[26:29], off offset:-1024
	v_pk_mul_f32 v[32:33], v[46:47], v[94:95] op_sel_hi:[1,0]
	v_pk_mul_f32 v[30:31], v[48:49], v[94:95] op_sel_hi:[1,0]
	v_pk_mul_f32 v[28:29], v[42:43], v[94:95] op_sel_hi:[1,0]
	v_pk_mul_f32 v[26:27], v[44:45], v[94:95] op_sel_hi:[1,0]
	v_bfe_u32 v42, v28, 16, 1
	v_add3_u32 v28, v28, v42, s60
	v_bfe_u32 v42, v29, 16, 1
	v_add3_u32 v29, v29, v42, s60
	v_bfe_u32 v42, v26, 16, 1
	v_add3_u32 v26, v26, v42, s60
	v_bfe_u32 v42, v27, 16, 1
	v_lshrrev_b32_e32 v28, 16, v28
	v_add3_u32 v27, v27, v42, s60
	v_lshrrev_b32_e32 v42, 16, v26
	v_and_or_b32 v26, v29, s61, v28
	v_bfe_u32 v28, v32, 16, 1
	v_add3_u32 v28, v32, v28, s60
	v_bfe_u32 v29, v33, 16, 1
	v_add3_u32 v29, v33, v29, s60
	v_lshrrev_b32_e32 v28, 16, v28
	v_and_or_b32 v28, v29, s61, v28
	v_bfe_u32 v29, v30, 16, 1
	v_add3_u32 v29, v30, v29, s60
	v_bfe_u32 v30, v31, 16, 1
	v_add3_u32 v30, v31, v30, s60
	v_lshrrev_b32_e32 v29, 16, v29
	v_and_or_b32 v27, v27, s61, v42
	v_and_or_b32 v29, v30, s61, v29
	global_store_dwordx4 v[72:73], v[26:29], off
	s_and_saveexec_b64 s[0:1], vcc
	s_cbranch_execz .LBB0_23
	s_waitcnt vmcnt(10)
	v_pk_mul_f32 v[26:27], v[40:41], v[40:41]
	v_pk_mul_f32 v[28:29], v[38:39], v[38:39]
	s_waitcnt vmcnt(4)
	v_mul_f32_e32 v44, v9, v9
	v_pk_mov_b32 v[30:31], v[28:29], v[26:27] op_sel:[1,0]
	v_mov_b32_e32 v29, v27
	v_pk_add_f32 v[26:27], v[30:31], v[28:29]
	v_pk_mul_f32 v[28:29], v[36:37], v[36:37]
	v_pk_mul_f32 v[30:31], v[34:35], v[34:35]
	v_mov_b32_e32 v32, v28
	v_mov_b32_e32 v33, v30
	v_mov_b32_e32 v30, v29
	v_pk_add_f32 v[26:27], v[26:27], v[26:27] op_sel:[0,1] op_sel_hi:[1,0]
	v_pk_add_f32 v[28:29], v[32:33], v[30:31]
	v_pk_mul_f32 v[30:31], v[22:23], v[22:23]
	v_pk_add_f32 v[26:27], v[26:27], v[28:29] op_sel:[0,1] op_sel_hi:[1,0]
	v_ashrrev_i32_e32 v81, 31, v80
	v_pk_add_f32 v[26:27], v[28:29], v[26:27]
	v_pk_mul_f32 v[28:29], v[24:25], v[24:25]
	v_mul_f32_e32 v27, v4, v4
	v_pk_mov_b32 v[32:33], v[30:31], v[28:29] op_sel:[1,0]
	v_mov_b32_e32 v31, v29
	v_pk_add_f32 v[28:29], v[32:33], v[30:31]
	v_pk_mul_f32 v[30:31], v[20:21], v[20:21]
	v_pk_mul_f32 v[32:33], v[18:19], v[18:19]
	v_mov_b32_e32 v42, v30
	v_mov_b32_e32 v43, v32
	v_mov_b32_e32 v32, v31
	v_pk_add_f32 v[28:29], v[28:29], v[28:29] op_sel:[0,1] op_sel_hi:[1,0]
	v_pk_add_f32 v[30:31], v[42:43], v[32:33]
	v_mov_b32_e32 v32, v11
	v_pk_add_f32 v[28:29], v[28:29], v[30:31] op_sel:[0,1] op_sel_hi:[1,0]
	v_mov_b32_e32 v33, v7
	v_pk_add_f32 v[28:29], v[30:31], v[28:29]
	v_mov_b32_e32 v30, v10
	v_mov_b32_e32 v31, v6
	v_pk_mul_f32 v[32:33], v[32:33], v[32:33]
	v_mul_f32_e32 v42, v8, v8
	v_pk_fma_f32 v[30:31], v[30:31], v[30:31], v[32:33]
	v_mul_f32_e32 v32, v15, v15
	v_pk_fma_f32 v[32:33], v[14:15], v[14:15], v[32:33] op_sel_hi:[1,1,0]
	v_mul_f32_e32 v29, v5, v5
	v_mov_b32_e32 v33, v42
	v_mul_f32_e32 v42, v17, v17
	v_pk_fma_f32 v[42:43], v[16:17], v[16:17], v[42:43] op_sel_hi:[1,1,0]
	v_pk_add_f32 v[26:27], v[26:27], v[28:29]
	v_mov_b32_e32 v43, v44
	v_pk_add_f32 v[32:33], v[32:33], v[42:43]
	v_mov_b32_e32 v42, v13
	v_mov_b32_e32 v43, v3
	v_pk_add_f32 v[30:31], v[30:31], v[32:33]
	v_mov_b32_e32 v32, v12
	v_mov_b32_e32 v33, v2
	v_pk_mul_f32 v[42:43], v[42:43], v[42:43]
	s_nop 0
	v_pk_fma_f32 v[32:33], v[32:33], v[32:33], v[42:43] op_sel:[1,1,1] op_sel_hi:[0,0,0]
	v_pk_add_f32 v[30:31], v[30:31], v[32:33] op_sel:[0,1] op_sel_hi:[1,0]
	v_lshlrev_b64 v[32:33], 12, v[80:81]
	v_pk_add_f32 v[26:27], v[26:27], v[30:31]
	v_lshl_add_u64 v[32:33], v[70:71], 0, v[32:33]
	v_add_f32_e32 v26, v26, v27
	ds_bpermute_b32 v27, v1, v26
	s_waitcnt lgkmcnt(0)
	v_add_f32_e32 v26, v26, v27
	ds_bpermute_b32 v27, v63, v26
	s_waitcnt lgkmcnt(0)
	v_add_f32_e32 v26, v26, v27
	ds_bpermute_b32 v27, v65, v26
	s_waitcnt lgkmcnt(0)
	v_add_f32_e32 v26, v26, v27
	ds_bpermute_b32 v27, v82, v26
	s_waitcnt lgkmcnt(0)
	v_add_f32_e32 v26, v26, v27
	ds_bpermute_b32 v27, v83, v26
	s_waitcnt lgkmcnt(0)
	v_add_f32_e32 v26, v26, v27
	ds_bpermute_b32 v27, v84, v26
	s_waitcnt lgkmcnt(0)
	v_add_f32_e32 v26, v26, v27
	v_fmamk_f32 v26, v26, 0x3a000000, v89
	v_mul_f32_e32 v27, 0x4b800000, v26
	v_cmp_gt_f32_e32 vcc, s35, v26
	s_nop 1
	v_cndmask_b32_e32 v26, v26, v27, vcc
	v_rsq_f32_e32 v26, v26
	s_nop 0
	v_mul_f32_e32 v27, 0x45800000, v26
	v_cndmask_b32_e32 v30, v26, v27, vcc
	v_pk_mul_f32 v[26:27], v[38:39], v[30:31] op_sel_hi:[1,0]
	v_pk_mul_f32 v[28:29], v[40:41], v[30:31] op_sel_hi:[1,0]
	v_pk_mul_f32 v[36:37], v[36:37], v[30:31] op_sel_hi:[1,0]
	v_pk_mul_f32 v[34:35], v[34:35], v[30:31] op_sel_hi:[1,0]
	v_bfe_u32 v31, v26, 16, 1
	v_add3_u32 v26, v26, v31, s60
	v_bfe_u32 v31, v27, 16, 1
	v_lshrrev_b32_e32 v26, 16, v26
	v_add3_u32 v27, v27, v31, s60
	v_and_or_b32 v26, v27, s61, v26
	v_bfe_u32 v27, v28, 16, 1
	v_add3_u32 v27, v28, v27, s60
	v_bfe_u32 v28, v29, 16, 1
	v_lshrrev_b32_e32 v27, 16, v27
	v_add3_u32 v28, v29, v28, s60
	v_and_or_b32 v27, v28, s61, v27
	v_bfe_u32 v28, v34, 16, 1
	v_add3_u32 v28, v34, v28, s60
	v_bfe_u32 v29, v35, 16, 1
	v_lshrrev_b32_e32 v28, 16, v28
	v_add3_u32 v29, v35, v29, s60
	v_and_or_b32 v28, v29, s61, v28
	v_bfe_u32 v29, v36, 16, 1
	v_add3_u32 v29, v36, v29, s60
	v_bfe_u32 v31, v37, 16, 1
	v_lshrrev_b32_e32 v29, 16, v29
	v_add3_u32 v31, v37, v31, s60
	v_and_or_b32 v29, v31, s61, v29
	v_pk_mul_f32 v[22:23], v[22:23], v[30:31] op_sel_hi:[1,0]
	global_store_dwordx4 v[32:33], v[26:29], off
	v_pk_mul_f32 v[24:25], v[24:25], v[30:31] op_sel_hi:[1,0]
	v_pk_mul_f32 v[14:15], v[14:15], v[30:31] op_sel_hi:[1,0]
	v_pk_mul_f32 v[26:27], v[20:21], v[30:31] op_sel_hi:[1,0]
	v_pk_mul_f32 v[20:21], v[18:19], v[30:31] op_sel_hi:[1,0]
	v_bfe_u32 v18, v22, 16, 1
	v_add3_u32 v18, v22, v18, s60
	v_bfe_u32 v19, v23, 16, 1
	v_lshrrev_b32_e32 v18, 16, v18
	v_add3_u32 v19, v23, v19, s60
	v_and_or_b32 v18, v19, s61, v18
	v_bfe_u32 v19, v24, 16, 1
	v_add3_u32 v19, v24, v19, s60
	v_bfe_u32 v22, v25, 16, 1
	v_lshrrev_b32_e32 v19, 16, v19
	v_add3_u32 v22, v25, v22, s60
	v_and_or_b32 v19, v22, s61, v19
	v_bfe_u32 v22, v20, 16, 1
	v_add3_u32 v20, v20, v22, s60
	v_bfe_u32 v22, v21, 16, 1
	v_lshrrev_b32_e32 v20, 16, v20
	v_add3_u32 v21, v21, v22, s60
	v_and_or_b32 v20, v21, s61, v20
	v_bfe_u32 v21, v26, 16, 1
	v_add3_u32 v21, v26, v21, s60
	v_bfe_u32 v22, v27, 16, 1
	v_lshrrev_b32_e32 v21, 16, v21
	v_add3_u32 v22, v27, v22, s60
	v_and_or_b32 v21, v22, s61, v21
	global_store_dwordx4 v[32:33], v[18:21], off offset:1024
	v_pk_mul_f32 v[16:17], v[16:17], v[30:31] op_sel_hi:[1,0]
	v_pk_mul_f32 v[6:7], v[6:7], v[30:31] op_sel_hi:[1,0]
	v_pk_mul_f32 v[18:19], v[12:13], v[30:31] op_sel_hi:[1,0]
	v_pk_mul_f32 v[12:13], v[10:11], v[30:31] op_sel_hi:[1,0]
	v_bfe_u32 v10, v14, 16, 1
	v_add3_u32 v10, v14, v10, s60
	v_bfe_u32 v11, v15, 16, 1
	v_lshrrev_b32_e32 v10, 16, v10
	v_add3_u32 v11, v15, v11, s60
	v_and_or_b32 v10, v11, s61, v10
	v_bfe_u32 v11, v16, 16, 1
	v_add3_u32 v11, v16, v11, s60
	v_bfe_u32 v14, v17, 16, 1
	v_lshrrev_b32_e32 v11, 16, v11
	v_add3_u32 v14, v17, v14, s60
	v_and_or_b32 v11, v14, s61, v11
	v_bfe_u32 v14, v12, 16, 1
	v_add3_u32 v12, v12, v14, s60
	v_bfe_u32 v14, v13, 16, 1
	v_lshrrev_b32_e32 v12, 16, v12
	v_add3_u32 v13, v13, v14, s60
	v_and_or_b32 v12, v13, s61, v12
	v_bfe_u32 v13, v18, 16, 1
	v_add3_u32 v13, v18, v13, s60
	v_bfe_u32 v14, v19, 16, 1
	v_lshrrev_b32_e32 v13, 16, v13
	v_add3_u32 v14, v19, v14, s60
	v_and_or_b32 v13, v14, s61, v13
	global_store_dwordx4 v[32:33], v[10:13], off offset:2048
	v_pk_mul_f32 v[8:9], v[8:9], v[30:31] op_sel_hi:[1,0]
	s_nop 0
	v_pk_mul_f32 v[10:11], v[4:5], v[30:31] op_sel_hi:[1,0]
	v_pk_mul_f32 v[4:5], v[2:3], v[30:31] op_sel_hi:[1,0]
	v_bfe_u32 v2, v6, 16, 1
	v_add3_u32 v2, v6, v2, s60
	v_bfe_u32 v3, v7, 16, 1
	v_lshrrev_b32_e32 v2, 16, v2
	v_add3_u32 v3, v7, v3, s60
	v_and_or_b32 v2, v3, s61, v2
	v_bfe_u32 v3, v8, 16, 1
	v_add3_u32 v3, v8, v3, s60
	v_bfe_u32 v6, v9, 16, 1
	v_lshrrev_b32_e32 v3, 16, v3
	v_add3_u32 v6, v9, v6, s60
	v_and_or_b32 v3, v6, s61, v3
	v_bfe_u32 v6, v4, 16, 1
	v_add3_u32 v4, v4, v6, s60
	v_bfe_u32 v6, v5, 16, 1
	v_lshrrev_b32_e32 v4, 16, v4
	v_add3_u32 v5, v5, v6, s60
	v_and_or_b32 v4, v5, s61, v4
	v_bfe_u32 v5, v10, 16, 1
	v_add3_u32 v5, v10, v5, s60
	v_bfe_u32 v6, v11, 16, 1
	v_lshrrev_b32_e32 v5, 16, v5
	v_add3_u32 v6, v11, v6, s60
	v_and_or_b32 v5, v6, s61, v5
	global_store_dwordx4 v[32:33], v[2:5], off offset:3072
	s_branch .LBB0_23

.LBB0_134:
	global_load_dword v6, v[22:23], off
	v_lshrrev_b32_e32 v26, 2, v11
	v_add_u32_e32 v25, 0x200, v25
	v_and_b32_e32 v26, 0x3ffffff8, v26
	v_cmp_lt_u32_e32 vcc, s34, v25
	v_add_u32_e32 v11, 8, v11
	v_lshl_add_u64 v[22:23], v[22:23], 0, s[26:27]
	v_add_u32_e32 v26, v24, v26
	v_add_u32_e32 v24, 64, v24
	s_or_b64 s[62:63], vcc, s[62:63]
	s_waitcnt vmcnt(0)
	ds_write_b64 v26, v[6:7]
	s_andn2_b64 exec, exec, s[62:63]
	s_cbranch_execnz .LBB0_134
	s_or_b64 exec, exec, s[62:63]
	v_mov_b32_e32 v6, v62
	s_waitcnt lgkmcnt(0)
	s_barrier
	s_mov_b32 s43, s40
	v_and_b32_e32 v11, 15, v6
	v_cvt_f32_ubyte0_e32 v22, v11
	v_mul_f32_e32 v23, 0x3b800000, v22
	v_sin_f32_e32 v22, v23
	v_cos_f32_e32 v24, v23
	v_lshlrev_b32_e32 v6, 4, v6
	v_and_b32_e32 v6, 0xffffff00, v6
	v_xor_b32_e32 v25, 0x80000000, v22
	v_mov_b32_e32 v23, v25
	v_pk_mul_f32 v[26:27], v[24:25], v[22:23] op_sel:[1,0] op_sel_hi:[0,1]
	v_pk_fma_f32 v[26:27], v[24:25], v[24:25], v[26:27] op_sel_hi:[1,0,1]
	v_lshlrev_b32_e32 v11, 3, v11
	v_xor_b32_e32 v32, 0x80000000, v27
	v_mov_b32_e32 v33, v27
	v_pk_mul_f32 v[30:31], v[26:27], v[32:33] op_sel:[1,0] op_sel_hi:[0,1]
	v_pk_fma_f32 v[30:31], v[26:27], v[26:27], v[30:31] op_sel_hi:[1,0,1]
	v_pk_mul_f32 v[28:29], v[22:23], v[26:27] op_sel:[0,1] op_sel_hi:[1,0]
	v_xor_b32_e32 v34, 0x80000000, v31
	v_mov_b32_e32 v35, v31
	v_pk_mul_f32 v[50:51], v[30:31], v[34:35] op_sel:[1,0] op_sel_hi:[0,1]
	v_pk_fma_f32 v[50:51], v[30:31], v[30:31], v[50:51] op_sel_hi:[1,0,1]
	v_pk_mul_f32 v[36:37], v[22:23], v[30:31] op_sel:[0,1] op_sel_hi:[1,0]
	v_pk_mul_f32 v[70:71], v[34:35], v[50:51] op_sel:[0,1] op_sel_hi:[1,0]
	v_pk_mul_f32 v[54:55], v[22:23], v[50:51] op_sel:[0,1] op_sel_hi:[1,0]
	v_pk_fma_f32 v[70:71], v[30:31], v[50:51], v[70:71] op_sel_hi:[0,1,1]
	v_pk_mul_f32 v[74:75], v[22:23], v[70:71] op_sel:[0,1] op_sel_hi:[1,0]
	v_pk_fma_f32 v[28:29], v[24:25], v[26:27], v[28:29] op_sel_hi:[0,1,1]
	v_pk_fma_f32 v[36:37], v[24:25], v[30:31], v[36:37] op_sel_hi:[0,1,1]
	v_pk_fma_f32 v[54:55], v[24:25], v[50:51], v[54:55] op_sel_hi:[0,1,1]
	v_pk_fma_f32 v[74:75], v[24:25], v[70:71], v[74:75] op_sel_hi:[0,1,1]
	v_lshlrev_b32_e32 v25, 3, v6
	v_add3_u32 v11, 0, v11, v25
	v_ashrrev_i32_e32 v25, 2, v6
	v_add_u32_e32 v25, v11, v25
	ds_read2_b64 v[92:95], v25 offset1:16
	ds_read2_b64 v[96:99], v25 offset0:33 offset1:49
	ds_read2_b64 v[100:103], v25 offset0:66 offset1:82
	ds_read2_b64 v[104:107], v25 offset0:132 offset1:148
	ds_read2_b64 v[108:111], v25 offset0:99 offset1:115
	ds_read2_b64 v[112:115], v25 offset0:165 offset1:181
	ds_read2_b64 v[116:119], v25 offset0:198 offset1:214
	ds_read2_b64 v[120:123], v25 offset0:231 offset1:247
	s_waitcnt lgkmcnt(4)
	v_pk_add_f32 v[124:125], v[92:93], v[104:105]
	v_pk_add_f32 v[92:93], v[92:93], v[104:105] neg_lo:[0,1] neg_hi:[0,1]
	v_pk_add_f32 v[104:105], v[94:95], v[106:107]
	v_pk_add_f32 v[94:95], v[94:95], v[106:107] neg_lo:[0,1] neg_hi:[0,1]
	s_mov_b32 s45, s36
	v_pk_mul_f32 v[106:107], v[94:95], s[38:39]
	s_waitcnt lgkmcnt(1)
	v_pk_add_f32 v[126:127], v[102:103], v[118:119]
	v_pk_fma_f32 v[94:95], v[94:95], s[36:37], v[106:107] op_sel:[0,0,1] op_sel_hi:[1,0,0]
	v_pk_add_f32 v[106:107], v[96:97], v[112:113]
	v_pk_add_f32 v[96:97], v[96:97], v[112:113] neg_lo:[0,1] neg_hi:[0,1]
	v_pk_add_f32 v[102:103], v[102:103], v[118:119] neg_lo:[0,1] neg_hi:[0,1]
	v_pk_mul_f32 v[112:113], v[96:97], s[42:43]
	s_mov_b32 s62, s39
	v_pk_mul_f32 v[118:119], v[102:103], s[44:45]
	v_pk_fma_f32 v[96:97], v[96:97], s[40:41], v[112:113] op_sel:[0,0,1] op_sel_hi:[1,0,0]
	v_pk_add_f32 v[112:113], v[98:99], v[114:115]
	v_pk_add_f32 v[98:99], v[98:99], v[114:115] neg_lo:[0,1] neg_hi:[0,1]
	v_pk_fma_f32 v[102:103], v[102:103], s[62:63], v[118:119] op_sel:[0,0,1] op_sel_hi:[1,0,0] neg_lo:[1,0,0] neg_hi:[1,0,0]
	s_waitcnt lgkmcnt(0)
	v_pk_add_f32 v[118:119], v[108:109], v[120:121]
	v_pk_add_f32 v[108:109], v[108:109], v[120:121] neg_lo:[0,1] neg_hi:[0,1]
	v_pk_mul_f32 v[114:115], v[98:99], s[44:45]
	v_pk_mul_f32 v[120:121], v[108:109], s[42:43]
	v_pk_fma_f32 v[98:99], v[98:99], s[62:63], v[114:115] op_sel:[0,0,1] op_sel_hi:[1,0,0]
	v_pk_add_f32 v[114:115], v[100:101], v[116:117]
	v_pk_add_f32 v[116:117], v[100:101], v[116:117] neg_lo:[0,1] neg_hi:[0,1]
	v_pk_fma_f32 v[108:109], v[108:109], s[40:41], v[120:121] op_sel:[0,0,1] op_sel_hi:[1,0,0] neg_lo:[1,0,0] neg_hi:[1,0,0]
	v_pk_add_f32 v[120:121], v[110:111], v[122:123]
	v_pk_add_f32 v[110:111], v[110:111], v[122:123] op_sel:[1,1] op_sel_hi:[0,0] neg_lo:[0,1] neg_hi:[0,1]
	v_pk_mul_f32 v[122:123], v[110:111], s[38:39] op_sel:[1,0] op_sel_hi:[0,1]
	s_nop 0
	v_pk_fma_f32 v[110:111], v[110:111], s[36:37], v[122:123] op_sel:[1,0,1] op_sel_hi:[0,0,0] neg_lo:[1,0,0] neg_hi:[1,0,0]
	v_pk_add_f32 v[122:123], v[124:125], v[114:115]
	v_pk_add_f32 v[114:115], v[124:125], v[114:115] neg_lo:[0,1] neg_hi:[0,1]
	v_pk_add_f32 v[124:125], v[104:105], v[126:127]
	v_pk_add_f32 v[104:105], v[104:105], v[126:127] neg_lo:[0,1] neg_hi:[0,1]
	v_pk_add_f32 v[128:129], v[112:113], v[120:121]
	v_pk_add_f32 v[112:113], v[112:113], v[120:121] neg_lo:[0,1] neg_hi:[0,1]
	v_pk_add_f32 v[100:101], v[92:93], v[116:117] op_sel:[0,1] op_sel_hi:[1,0] neg_hi:[0,1]
	v_pk_add_f32 v[92:93], v[92:93], v[116:117] op_sel:[0,1] op_sel_hi:[1,0] neg_lo:[0,1]
	v_pk_add_f32 v[116:117], v[94:95], v[102:103]
	v_pk_add_f32 v[94:95], v[94:95], v[102:103] neg_lo:[0,1] neg_hi:[0,1]
	v_pk_mul_f32 v[126:127], v[104:105], s[42:43]
	v_pk_mul_f32 v[120:121], v[112:113], s[42:43]
	v_pk_mul_f32 v[102:103], v[94:95], s[42:43]
	v_pk_fma_f32 v[104:105], v[104:105], s[40:41], v[126:127] op_sel:[0,0,1] op_sel_hi:[1,0,0]
	v_pk_add_f32 v[126:127], v[106:107], v[118:119]
	v_pk_add_f32 v[118:119], v[106:107], v[118:119] neg_lo:[0,1] neg_hi:[0,1]
	v_pk_fma_f32 v[112:113], v[112:113], s[40:41], v[120:121] op_sel:[0,0,1] op_sel_hi:[1,0,0] neg_lo:[1,0,0] neg_hi:[1,0,0]
	v_pk_fma_f32 v[94:95], v[94:95], s[40:41], v[102:103] op_sel:[0,0,1] op_sel_hi:[1,0,0]
	v_pk_add_f32 v[102:103], v[96:97], v[108:109]
	v_pk_add_f32 v[120:121], v[98:99], v[110:111]
	v_pk_add_f32 v[98:99], v[98:99], v[110:111] neg_lo:[0,1] neg_hi:[0,1]
	v_pk_add_f32 v[96:97], v[96:97], v[108:109] neg_lo:[0,1] neg_hi:[0,1]
	v_pk_mul_f32 v[110:111], v[98:99], s[42:43]
	v_pk_add_f32 v[130:131], v[100:101], v[102:103]
	v_pk_add_f32 v[100:101], v[100:101], v[102:103] neg_lo:[0,1] neg_hi:[0,1]
	v_pk_add_f32 v[102:103], v[116:117], v[120:121]
	v_pk_add_f32 v[120:121], v[116:117], v[120:121] neg_lo:[0,1] neg_hi:[0,1]
	v_xor_b32_e32 v38, 0x80000000, v29
	v_mov_b32_e32 v39, v29
	v_pk_mul_f32 v[42:43], v[32:33], v[30:31] op_sel:[0,1] op_sel_hi:[1,0]
	v_xor_b32_e32 v109, 0x80000000, v96
	v_pk_fma_f32 v[98:99], v[98:99], s[40:41], v[110:111] op_sel:[0,0,1] op_sel_hi:[1,0,0] neg_lo:[1,0,0] neg_hi:[1,0,0]
	v_pk_add_f32 v[106:107], v[114:115], v[118:119] op_sel:[0,1] op_sel_hi:[1,0] neg_hi:[0,1]
	v_pk_add_f32 v[114:115], v[114:115], v[118:119] op_sel:[0,1] op_sel_hi:[1,0] neg_lo:[0,1]
	v_pk_add_f32 v[118:119], v[104:105], v[112:113]
	v_pk_add_f32 v[112:113], v[104:105], v[112:113] neg_lo:[0,1] neg_hi:[0,1]
	v_mov_b32_e32 v108, v97
	v_xor_b32_e32 v40, 0x80000000, v37
	v_mov_b32_e32 v41, v37
	v_pk_fma_f32 v[42:43], v[26:27], v[30:31], v[42:43] op_sel_hi:[0,1,1]
	v_pk_mul_f32 v[46:47], v[30:31], v[38:39] op_sel:[1,0] op_sel_hi:[0,1]
	v_pk_add_f32 v[96:97], v[92:93], v[108:109]
	v_pk_add_f32 v[92:93], v[92:93], v[108:109] neg_lo:[0,1] neg_hi:[0,1]
	v_pk_add_f32 v[108:109], v[94:95], v[98:99]
	v_pk_add_f32 v[98:99], v[94:95], v[98:99] neg_lo:[0,1] neg_hi:[0,1]
	v_pk_add_f32 v[116:117], v[100:101], v[120:121] op_sel:[0,1] op_sel_hi:[1,0] neg_hi:[0,1]
	v_xor_b32_e32 v44, 0x80000000, v43
	v_mov_b32_e32 v45, v43
	v_pk_fma_f32 v[46:47], v[30:31], v[28:29], v[46:47] op_sel_hi:[1,0,1]
	v_pk_add_f32 v[104:105], v[114:115], v[112:113] op_sel:[0,1] op_sel_hi:[1,0] neg_hi:[0,1]
	v_pk_add_f32 v[100:101], v[100:101], v[120:121] op_sel:[0,1] op_sel_hi:[1,0] neg_lo:[0,1]
	v_pk_mul_f32 v[120:121], v[40:41], v[116:117] op_sel:[0,1] op_sel_hi:[1,0]
	v_xor_b32_e32 v48, 0x80000000, v47
	v_mov_b32_e32 v49, v47
	v_pk_add_f32 v[110:111], v[122:123], v[126:127]
	v_pk_add_f32 v[122:123], v[122:123], v[126:127] neg_lo:[0,1] neg_hi:[0,1]
	v_pk_add_f32 v[126:127], v[124:125], v[128:129]
	v_pk_add_f32 v[94:95], v[92:93], v[98:99] op_sel:[0,1] op_sel_hi:[1,0] neg_hi:[0,1]
	v_pk_fma_f32 v[116:117], v[36:37], v[116:117], v[120:121] op_sel_hi:[0,1,1]
	v_pk_mul_f32 v[120:121], v[44:45], v[104:105] op_sel:[0,1] op_sel_hi:[1,0]
	v_xor_b32_e32 v52, 0x80000000, v51
	v_mov_b32_e32 v53, v51
	v_pk_mul_f32 v[58:59], v[32:33], v[50:51] op_sel:[0,1] op_sel_hi:[1,0]
	v_pk_add_f32 v[132:133], v[110:111], v[126:127]
	v_pk_add_f32 v[110:111], v[110:111], v[126:127] neg_lo:[0,1] neg_hi:[0,1]
	v_pk_fma_f32 v[104:105], v[42:43], v[104:105], v[120:121] op_sel_hi:[0,1,1]
	v_pk_mul_f32 v[120:121], v[48:49], v[94:95] op_sel:[0,1] op_sel_hi:[1,0]
	v_xor_b32_e32 v56, 0x80000000, v55
	v_mov_b32_e32 v57, v55
	v_pk_fma_f32 v[58:59], v[26:27], v[50:51], v[58:59] op_sel_hi:[0,1,1]
	v_pk_mul_f32 v[66:67], v[38:39], v[50:51] op_sel:[0,1] op_sel_hi:[1,0]
	v_pk_add_f32 v[112:113], v[114:115], v[112:113] op_sel:[0,1] op_sel_hi:[1,0] neg_lo:[0,1]
	v_pk_add_f32 v[114:115], v[130:131], v[102:103]
	v_pk_add_f32 v[102:103], v[130:131], v[102:103] neg_lo:[0,1] neg_hi:[0,1]
	v_pk_fma_f32 v[94:95], v[46:47], v[94:95], v[120:121] op_sel_hi:[0,1,1]
	v_pk_mul_f32 v[120:121], v[52:53], v[110:111] op_sel:[0,1] op_sel_hi:[1,0]
	v_xor_b32_e32 v60, 0x80000000, v59
	v_mov_b32_e32 v61, v59
	v_pk_fma_f32 v[66:67], v[28:29], v[50:51], v[66:67] op_sel_hi:[0,1,1]
	v_pk_add_f32 v[128:129], v[124:125], v[128:129] neg_lo:[0,1] neg_hi:[0,1]
	v_pk_add_f32 v[126:127], v[106:107], v[118:119]
	v_pk_add_f32 v[106:107], v[106:107], v[118:119] neg_lo:[0,1] neg_hi:[0,1]
	v_pk_fma_f32 v[110:111], v[50:51], v[110:111], v[120:121] op_sel_hi:[0,1,1]
	v_pk_mul_f32 v[120:121], v[56:57], v[102:103] op_sel:[0,1] op_sel_hi:[1,0]
	v_xor_b32_e32 v68, 0x80000000, v67
	v_mov_b32_e32 v69, v67
	v_pk_add_f32 v[118:119], v[96:97], v[108:109]
	v_pk_add_f32 v[96:97], v[96:97], v[108:109] neg_lo:[0,1] neg_hi:[0,1]
	v_pk_fma_f32 v[102:103], v[54:55], v[102:103], v[120:121] op_sel_hi:[0,1,1]
	v_pk_mul_f32 v[120:121], v[60:61], v[106:107] op_sel:[0,1] op_sel_hi:[1,0]
	v_xor_b32_e32 v72, 0x80000000, v71
	v_mov_b32_e32 v73, v71
	v_pk_mul_f32 v[78:79], v[32:33], v[70:71] op_sel:[0,1] op_sel_hi:[1,0]
	v_pk_add_f32 v[124:125], v[122:123], v[128:129] op_sel:[0,1] op_sel_hi:[1,0] neg_hi:[0,1]
	v_pk_add_f32 v[122:123], v[122:123], v[128:129] op_sel:[0,1] op_sel_hi:[1,0] neg_lo:[0,1]
	v_pk_fma_f32 v[106:107], v[58:59], v[106:107], v[120:121] op_sel_hi:[0,1,1]
	v_pk_mul_f32 v[120:121], v[68:69], v[96:97] op_sel:[0,1] op_sel_hi:[1,0]
	v_xor_b32_e32 v76, 0x80000000, v75
	v_mov_b32_e32 v77, v75
	v_pk_fma_f32 v[78:79], v[26:27], v[70:71], v[78:79] op_sel_hi:[0,1,1]
	v_pk_mul_f32 v[82:83], v[38:39], v[70:71] op_sel:[0,1] op_sel_hi:[1,0]
	v_pk_fma_f32 v[96:97], v[66:67], v[96:97], v[120:121] op_sel_hi:[0,1,1]
	v_pk_mul_f32 v[120:121], v[72:73], v[122:123] op_sel:[0,1] op_sel_hi:[1,0]
	v_xor_b32_e32 v80, 0x80000000, v79
	v_mov_b32_e32 v81, v79
	v_pk_fma_f32 v[82:83], v[28:29], v[70:71], v[82:83] op_sel_hi:[0,1,1]
	v_pk_add_f32 v[92:93], v[92:93], v[98:99] op_sel:[0,1] op_sel_hi:[1,0] neg_lo:[0,1]
	v_pk_mul_f32 v[98:99], v[22:23], v[114:115] op_sel:[0,1] op_sel_hi:[1,0]
	v_pk_fma_f32 v[120:121], v[70:71], v[122:123], v[120:121] op_sel_hi:[0,1,1]
	v_pk_mul_f32 v[122:123], v[76:77], v[100:101] op_sel:[0,1] op_sel_hi:[1,0]
	v_xor_b32_e32 v84, 0x80000000, v83
	v_mov_b32_e32 v85, v83
	v_pk_fma_f32 v[98:99], v[24:25], v[114:115], v[98:99] op_sel_hi:[0,1,1]
	v_pk_mul_f32 v[114:115], v[38:39], v[118:119] op_sel:[0,1] op_sel_hi:[1,0]
	v_pk_fma_f32 v[100:101], v[74:75], v[100:101], v[122:123] op_sel_hi:[0,1,1]
	v_pk_mul_f32 v[122:123], v[80:81], v[112:113] op_sel:[0,1] op_sel_hi:[1,0]
	v_add_u32_e32 v6, 0x2000, v6
	v_pk_mul_f32 v[108:109], v[32:33], v[126:127] op_sel:[0,1] op_sel_hi:[1,0]
	v_pk_fma_f32 v[114:115], v[28:29], v[118:119], v[114:115] op_sel_hi:[0,1,1]
	v_pk_mul_f32 v[118:119], v[34:35], v[124:125] op_sel:[0,1] op_sel_hi:[1,0]
	v_pk_fma_f32 v[112:113], v[78:79], v[112:113], v[122:123] op_sel_hi:[0,1,1]
	v_pk_mul_f32 v[122:123], v[84:85], v[92:93] op_sel:[0,1] op_sel_hi:[1,0]
	v_ashrrev_i32_e32 v6, 2, v6
	v_pk_fma_f32 v[108:109], v[26:27], v[126:127], v[108:109] op_sel_hi:[0,1,1]
	v_pk_fma_f32 v[118:119], v[30:31], v[124:125], v[118:119] op_sel_hi:[0,1,1]
	v_pk_fma_f32 v[92:93], v[82:83], v[92:93], v[122:123] op_sel_hi:[0,1,1]
	ds_write2_b64 v25, v[132:133], v[110:111] offset1:16
	ds_write2_b64 v25, v[118:119], v[120:121] offset0:33 offset1:49
	ds_write2_b64 v25, v[108:109], v[106:107] offset0:66 offset1:82
	ds_write2_b64 v25, v[104:105], v[112:113] offset0:99 offset1:115
	ds_write2_b64 v25, v[98:99], v[102:103] offset0:132 offset1:148
	ds_write2_b64 v25, v[116:117], v[100:101] offset0:165 offset1:181
	ds_write2_b64 v25, v[114:115], v[96:97] offset0:198 offset1:214
	ds_write2_b64 v25, v[94:95], v[92:93] offset0:231 offset1:247
	v_add3_u32 v6, v11, v6, s35
	ds_read2_b64 v[92:95], v6 offset1:16
	ds_read2_b64 v[96:99], v6 offset0:33 offset1:49
	ds_read2_b64 v[100:103], v6 offset0:66 offset1:82
	ds_read2_b64 v[104:107], v6 offset0:132 offset1:148
	ds_read2_b64 v[108:111], v6 offset0:99 offset1:115
	ds_read2_b64 v[112:115], v6 offset0:165 offset1:181
	ds_read2_b64 v[116:119], v6 offset0:198 offset1:214
	ds_read2_b64 v[120:123], v6 offset0:231 offset1:247
	s_waitcnt lgkmcnt(4)
	v_pk_add_f32 v[124:125], v[92:93], v[104:105]
	v_pk_add_f32 v[92:93], v[92:93], v[104:105] neg_lo:[0,1] neg_hi:[0,1]
	v_pk_add_f32 v[104:105], v[94:95], v[106:107]
	v_pk_add_f32 v[94:95], v[94:95], v[106:107] neg_lo:[0,1] neg_hi:[0,1]
	s_waitcnt lgkmcnt(1)
	v_pk_add_f32 v[126:127], v[102:103], v[118:119]
	v_pk_mul_f32 v[106:107], v[94:95], s[38:39]
	v_pk_add_f32 v[102:103], v[102:103], v[118:119] neg_lo:[0,1] neg_hi:[0,1]
	v_pk_fma_f32 v[94:95], v[94:95], s[36:37], v[106:107] op_sel:[0,0,1] op_sel_hi:[1,0,0]
	v_pk_add_f32 v[106:107], v[96:97], v[112:113]
	v_pk_add_f32 v[96:97], v[96:97], v[112:113] neg_lo:[0,1] neg_hi:[0,1]
	v_pk_mul_f32 v[118:119], v[102:103], s[44:45]
	v_pk_mul_f32 v[112:113], v[96:97], s[42:43]
	v_pk_fma_f32 v[102:103], v[102:103], s[62:63], v[118:119] op_sel:[0,0,1] op_sel_hi:[1,0,0] neg_lo:[1,0,0] neg_hi:[1,0,0]
	s_waitcnt lgkmcnt(0)
	v_pk_add_f32 v[118:119], v[108:109], v[120:121]
	v_pk_add_f32 v[108:109], v[108:109], v[120:121] neg_lo:[0,1] neg_hi:[0,1]
	v_pk_fma_f32 v[96:97], v[96:97], s[40:41], v[112:113] op_sel:[0,0,1] op_sel_hi:[1,0,0]
	v_pk_add_f32 v[112:113], v[98:99], v[114:115]
	v_pk_add_f32 v[98:99], v[98:99], v[114:115] neg_lo:[0,1] neg_hi:[0,1]
	v_pk_mul_f32 v[120:121], v[108:109], s[42:43]
	v_pk_mul_f32 v[114:115], v[98:99], s[44:45]
	v_pk_fma_f32 v[108:109], v[108:109], s[40:41], v[120:121] op_sel:[0,0,1] op_sel_hi:[1,0,0] neg_lo:[1,0,0] neg_hi:[1,0,0]
	v_pk_add_f32 v[120:121], v[110:111], v[122:123]
	v_pk_add_f32 v[110:111], v[110:111], v[122:123] neg_lo:[0,1] neg_hi:[0,1]
	v_pk_fma_f32 v[98:99], v[98:99], s[62:63], v[114:115] op_sel:[0,0,1] op_sel_hi:[1,0,0]
	v_pk_add_f32 v[114:115], v[100:101], v[116:117]
	v_pk_mul_f32 v[122:123], v[110:111], s[38:39]
	v_pk_add_f32 v[116:117], v[100:101], v[116:117] neg_lo:[0,1] neg_hi:[0,1]
	v_pk_fma_f32 v[110:111], v[110:111], s[36:37], v[122:123] op_sel:[0,0,1] op_sel_hi:[1,0,0] neg_lo:[1,0,0] neg_hi:[1,0,0]
	v_pk_add_f32 v[122:123], v[124:125], v[114:115]
	v_pk_add_f32 v[114:115], v[124:125], v[114:115] neg_lo:[0,1] neg_hi:[0,1]
	v_pk_add_f32 v[124:125], v[104:105], v[126:127]
	v_pk_add_f32 v[104:105], v[104:105], v[126:127] op_sel:[1,1] op_sel_hi:[0,0] neg_lo:[0,1] neg_hi:[0,1]
	v_pk_mul_f32 v[126:127], v[104:105], s[42:43] op_sel:[1,0] op_sel_hi:[0,1]
	v_pk_add_f32 v[128:129], v[112:113], v[120:121]
	v_pk_add_f32 v[112:113], v[112:113], v[120:121] neg_lo:[0,1] neg_hi:[0,1]
	v_pk_fma_f32 v[104:105], v[104:105], s[40:41], v[126:127] op_sel:[1,0,1] op_sel_hi:[0,0,0]
	v_pk_add_f32 v[126:127], v[106:107], v[118:119]
	v_pk_add_f32 v[118:119], v[106:107], v[118:119] neg_lo:[0,1] neg_hi:[0,1]
	v_pk_mul_f32 v[120:121], v[112:113], s[42:43]
	v_pk_add_f32 v[100:101], v[92:93], v[116:117] op_sel:[0,1] op_sel_hi:[1,0] neg_hi:[0,1]
	v_pk_add_f32 v[92:93], v[92:93], v[116:117] op_sel:[0,1] op_sel_hi:[1,0] neg_lo:[0,1]
	v_pk_add_f32 v[116:117], v[94:95], v[102:103]
	v_pk_add_f32 v[94:95], v[94:95], v[102:103] neg_lo:[0,1] neg_hi:[0,1]
	v_pk_fma_f32 v[112:113], v[112:113], s[40:41], v[120:121] op_sel:[0,0,1] op_sel_hi:[1,0,0] neg_lo:[1,0,0] neg_hi:[1,0,0]
	v_pk_mul_f32 v[102:103], v[94:95], s[42:43] op_sel:[1,1] op_sel_hi:[0,0]
	v_pk_fma_f32 v[94:95], v[94:95], s[40:41], v[102:103] op_sel_hi:[1,0,1]
	v_pk_add_f32 v[102:103], v[96:97], v[108:109]
	v_pk_add_f32 v[120:121], v[98:99], v[110:111]
	v_pk_add_f32 v[98:99], v[98:99], v[110:111] neg_lo:[0,1] neg_hi:[0,1]
	v_pk_add_f32 v[106:107], v[114:115], v[118:119] op_sel:[0,1] op_sel_hi:[1,0] neg_hi:[0,1]
	v_pk_add_f32 v[114:115], v[114:115], v[118:119] op_sel:[0,1] op_sel_hi:[1,0] neg_lo:[0,1]
	v_pk_add_f32 v[118:119], v[104:105], v[112:113]
	v_pk_add_f32 v[112:113], v[104:105], v[112:113] neg_lo:[0,1] neg_hi:[0,1]
	v_pk_add_f32 v[108:109], v[96:97], v[108:109] neg_lo:[0,1] neg_hi:[0,1]
	v_pk_mul_f32 v[110:111], v[98:99], s[42:43]
	v_pk_add_f32 v[130:131], v[100:101], v[102:103]
	v_pk_add_f32 v[100:101], v[100:101], v[102:103] neg_lo:[0,1] neg_hi:[0,1]
	v_pk_add_f32 v[102:103], v[116:117], v[120:121]
	v_pk_fma_f32 v[98:99], v[98:99], s[40:41], v[110:111] op_sel:[0,0,1] op_sel_hi:[1,0,0] neg_lo:[1,0,0] neg_hi:[1,0,0]
	v_pk_add_f32 v[110:111], v[122:123], v[126:127]
	v_pk_add_f32 v[122:123], v[122:123], v[126:127] neg_lo:[0,1] neg_hi:[0,1]
	v_pk_add_f32 v[126:127], v[124:125], v[128:129]
	v_pk_add_f32 v[104:105], v[114:115], v[112:113] op_sel:[0,1] op_sel_hi:[1,0] neg_hi:[0,1]
	v_pk_add_f32 v[112:113], v[114:115], v[112:113] op_sel:[0,1] op_sel_hi:[1,0] neg_lo:[0,1]
	v_pk_add_f32 v[114:115], v[130:131], v[102:103]
	v_pk_add_f32 v[124:125], v[124:125], v[128:129] neg_lo:[0,1] neg_hi:[0,1]
	v_pk_add_f32 v[96:97], v[92:93], v[108:109] op_sel:[0,1] op_sel_hi:[1,0] neg_hi:[0,1]
	v_pk_add_f32 v[92:93], v[92:93], v[108:109] op_sel:[0,1] op_sel_hi:[1,0] neg_lo:[0,1]
	v_pk_add_f32 v[108:109], v[94:95], v[98:99]
	v_pk_add_f32 v[132:133], v[110:111], v[126:127]
	v_pk_add_f32 v[110:111], v[110:111], v[126:127] neg_lo:[0,1] neg_hi:[0,1]
	v_pk_add_f32 v[126:127], v[106:107], v[118:119]
	v_pk_mul_f32 v[22:23], v[22:23], v[114:115] op_sel:[0,1] op_sel_hi:[1,0]
	v_xor_b32_e32 v129, 0x80000000, v124
	v_pk_add_f32 v[116:117], v[116:117], v[120:121] neg_lo:[0,1] neg_hi:[0,1]
	v_mov_b32_e32 v128, v125
	v_pk_add_f32 v[106:107], v[106:107], v[118:119] neg_lo:[0,1] neg_hi:[0,1]
	v_pk_add_f32 v[118:119], v[96:97], v[108:109]
	v_pk_fma_f32 v[22:23], v[24:25], v[114:115], v[22:23] op_sel_hi:[0,1,1]
	v_pk_mul_f32 v[24:25], v[32:33], v[126:127] op_sel:[0,1] op_sel_hi:[1,0]
	v_xor_b32_e32 v121, 0x80000000, v116
	v_pk_add_f32 v[94:95], v[94:95], v[98:99] neg_lo:[0,1] neg_hi:[0,1]
	v_pk_add_f32 v[124:125], v[122:123], v[128:129]
	v_mov_b32_e32 v120, v117
	v_pk_fma_f32 v[24:25], v[26:27], v[126:127], v[24:25] op_sel_hi:[0,1,1]
	v_pk_mul_f32 v[26:27], v[38:39], v[118:119] op_sel:[0,1] op_sel_hi:[1,0]
	v_xor_b32_e32 v99, 0x80000000, v94
	v_pk_add_f32 v[116:117], v[100:101], v[120:121]
	v_mov_b32_e32 v98, v95
	v_pk_fma_f32 v[26:27], v[28:29], v[118:119], v[26:27] op_sel_hi:[0,1,1]
	v_pk_mul_f32 v[28:29], v[34:35], v[124:125] op_sel:[0,1] op_sel_hi:[1,0]
	v_pk_add_f32 v[94:95], v[92:93], v[98:99]
	v_pk_fma_f32 v[28:29], v[30:31], v[124:125], v[28:29] op_sel_hi:[0,1,1]
	v_pk_mul_f32 v[30:31], v[40:41], v[116:117] op_sel:[0,1] op_sel_hi:[1,0]
	v_pk_add_f32 v[122:123], v[122:123], v[128:129] neg_lo:[0,1] neg_hi:[0,1]
	v_pk_add_f32 v[102:103], v[130:131], v[102:103] neg_lo:[0,1] neg_hi:[0,1]
	v_pk_add_f32 v[100:101], v[100:101], v[120:121] neg_lo:[0,1] neg_hi:[0,1]
	v_pk_add_f32 v[96:97], v[96:97], v[108:109] neg_lo:[0,1] neg_hi:[0,1]
	v_pk_add_f32 v[92:93], v[92:93], v[98:99] neg_lo:[0,1] neg_hi:[0,1]
	v_pk_fma_f32 v[30:31], v[36:37], v[116:117], v[30:31] op_sel_hi:[0,1,1]
	v_pk_mul_f32 v[32:33], v[44:45], v[104:105] op_sel:[0,1] op_sel_hi:[1,0]
	v_pk_mul_f32 v[34:35], v[48:49], v[94:95] op_sel:[0,1] op_sel_hi:[1,0]
	v_pk_mul_f32 v[36:37], v[52:53], v[110:111] op_sel:[0,1] op_sel_hi:[1,0]
	v_pk_fma_f32 v[32:33], v[42:43], v[104:105], v[32:33] op_sel_hi:[0,1,1]
	v_pk_fma_f32 v[34:35], v[46:47], v[94:95], v[34:35] op_sel_hi:[0,1,1]
	v_pk_fma_f32 v[36:37], v[50:51], v[110:111], v[36:37] op_sel_hi:[0,1,1]
	v_pk_mul_f32 v[38:39], v[56:57], v[102:103] op_sel:[0,1] op_sel_hi:[1,0]
	v_pk_mul_f32 v[40:41], v[60:61], v[106:107] op_sel:[0,1] op_sel_hi:[1,0]
	v_pk_mul_f32 v[42:43], v[68:69], v[96:97] op_sel:[0,1] op_sel_hi:[1,0]
	v_pk_mul_f32 v[44:45], v[72:73], v[122:123] op_sel:[0,1] op_sel_hi:[1,0]
	v_pk_mul_f32 v[46:47], v[76:77], v[100:101] op_sel:[0,1] op_sel_hi:[1,0]
	v_pk_mul_f32 v[48:49], v[80:81], v[112:113] op_sel:[0,1] op_sel_hi:[1,0]
	v_pk_mul_f32 v[50:51], v[84:85], v[92:93] op_sel:[0,1] op_sel_hi:[1,0]
	v_pk_fma_f32 v[38:39], v[54:55], v[102:103], v[38:39] op_sel_hi:[0,1,1]
	v_pk_fma_f32 v[40:41], v[58:59], v[106:107], v[40:41] op_sel_hi:[0,1,1]
	v_pk_fma_f32 v[42:43], v[66:67], v[96:97], v[42:43] op_sel_hi:[0,1,1]
	v_pk_fma_f32 v[44:45], v[70:71], v[122:123], v[44:45] op_sel_hi:[0,1,1]
	v_pk_fma_f32 v[46:47], v[74:75], v[100:101], v[46:47] op_sel_hi:[0,1,1]
	v_pk_fma_f32 v[48:49], v[78:79], v[112:113], v[48:49] op_sel_hi:[0,1,1]
	v_pk_fma_f32 v[50:51], v[82:83], v[92:93], v[50:51] op_sel_hi:[0,1,1]
	ds_write2_b64 v6, v[132:133], v[36:37] offset1:16
	ds_write2_b64 v6, v[28:29], v[44:45] offset0:33 offset1:49
	ds_write2_b64 v6, v[24:25], v[40:41] offset0:66 offset1:82
	ds_write2_b64 v6, v[32:33], v[48:49] offset0:99 offset1:115
	ds_write2_b64 v6, v[22:23], v[38:39] offset0:132 offset1:148
	ds_write2_b64 v6, v[30:31], v[46:47] offset0:165 offset1:181
	ds_write2_b64 v6, v[26:27], v[42:43] offset0:198 offset1:214
	ds_write2_b64 v6, v[34:35], v[50:51] offset0:231 offset1:247
	v_mov_b32_e32 v6, v62
	s_waitcnt lgkmcnt(0)
	s_barrier
	s_lshl_b32 s24, s71, 6
	v_bfe_i32 v11, v6, 1, 27
	v_lshl_add_u32 v68, v6, 7, 0
	v_lshl_add_u32 v11, v11, 3, v68
	ds_read2_b64 v[22:25], v11 offset1:1
	ds_read2_b64 v[26:29], v11 offset0:2 offset1:3
	ds_read2_b64 v[30:33], v11 offset0:8 offset1:9
	ds_read2_b64 v[34:37], v11 offset0:4 offset1:5
	ds_read2_b64 v[38:41], v11 offset0:6 offset1:7
	ds_read2_b64 v[42:45], v11 offset0:10 offset1:11
	ds_read2_b64 v[46:49], v11 offset0:12 offset1:13
	ds_read2_b64 v[50:53], v11 offset0:14 offset1:15
	s_waitcnt lgkmcnt(5)
	v_pk_add_f32 v[54:55], v[22:23], v[30:31]
	v_pk_add_f32 v[22:23], v[22:23], v[30:31] neg_lo:[0,1] neg_hi:[0,1]
	v_pk_add_f32 v[30:31], v[24:25], v[32:33]
	v_pk_add_f32 v[24:25], v[24:25], v[32:33] neg_lo:[0,1] neg_hi:[0,1]
	s_waitcnt lgkmcnt(1)
	v_pk_add_f32 v[56:57], v[36:37], v[48:49]
	v_pk_mul_f32 v[32:33], v[24:25], s[38:39]
	v_pk_add_f32 v[36:37], v[36:37], v[48:49] neg_lo:[0,1] neg_hi:[0,1]
	v_pk_fma_f32 v[24:25], v[24:25], s[36:37], v[32:33] op_sel:[0,0,1] op_sel_hi:[1,0,0]
	v_pk_add_f32 v[32:33], v[26:27], v[42:43]
	v_pk_add_f32 v[26:27], v[26:27], v[42:43] neg_lo:[0,1] neg_hi:[0,1]
	v_pk_mul_f32 v[48:49], v[36:37], s[44:45]
	v_pk_mul_f32 v[42:43], v[26:27], s[42:43]
	v_pk_fma_f32 v[36:37], v[36:37], s[62:63], v[48:49] op_sel:[0,0,1] op_sel_hi:[1,0,0] neg_lo:[1,0,0] neg_hi:[1,0,0]
	v_pk_fma_f32 v[26:27], v[26:27], s[40:41], v[42:43] op_sel:[0,0,1] op_sel_hi:[1,0,0]
	v_pk_add_f32 v[42:43], v[28:29], v[44:45]
	v_pk_add_f32 v[28:29], v[28:29], v[44:45] neg_lo:[0,1] neg_hi:[0,1]
	s_waitcnt lgkmcnt(0)
	v_pk_add_f32 v[48:49], v[38:39], v[50:51]
	v_pk_add_f32 v[38:39], v[38:39], v[50:51] neg_lo:[0,1] neg_hi:[0,1]
	v_pk_mul_f32 v[44:45], v[28:29], s[44:45]
	v_pk_mul_f32 v[50:51], v[38:39], s[42:43]
	v_pk_fma_f32 v[28:29], v[28:29], s[62:63], v[44:45] op_sel:[0,0,1] op_sel_hi:[1,0,0]
	v_pk_add_f32 v[44:45], v[34:35], v[46:47]
	v_pk_add_f32 v[46:47], v[34:35], v[46:47] neg_lo:[0,1] neg_hi:[0,1]
	v_pk_fma_f32 v[38:39], v[38:39], s[40:41], v[50:51] op_sel:[0,0,1] op_sel_hi:[1,0,0] neg_lo:[1,0,0] neg_hi:[1,0,0]
	v_pk_add_f32 v[50:51], v[40:41], v[52:53]
	v_pk_add_f32 v[40:41], v[40:41], v[52:53] op_sel:[1,1] op_sel_hi:[0,0] neg_lo:[0,1] neg_hi:[0,1]
	v_pk_mul_f32 v[52:53], v[40:41], s[38:39] op_sel:[1,0] op_sel_hi:[0,1]
	v_pk_add_f32 v[58:59], v[42:43], v[50:51]
	v_pk_add_f32 v[42:43], v[42:43], v[50:51] neg_lo:[0,1] neg_hi:[0,1]
	v_pk_fma_f32 v[40:41], v[40:41], s[36:37], v[52:53] op_sel:[1,0,1] op_sel_hi:[0,0,0] neg_lo:[1,0,0] neg_hi:[1,0,0]
	v_pk_add_f32 v[52:53], v[54:55], v[44:45]
	v_pk_add_f32 v[44:45], v[54:55], v[44:45] neg_lo:[0,1] neg_hi:[0,1]
	v_pk_add_f32 v[54:55], v[30:31], v[56:57]
	v_pk_add_f32 v[30:31], v[30:31], v[56:57] neg_lo:[0,1] neg_hi:[0,1]
	v_pk_mul_f32 v[50:51], v[42:43], s[42:43]
	v_pk_add_f32 v[34:35], v[22:23], v[46:47] op_sel:[0,1] op_sel_hi:[1,0] neg_hi:[0,1]
	v_pk_add_f32 v[22:23], v[22:23], v[46:47] op_sel:[0,1] op_sel_hi:[1,0] neg_lo:[0,1]
	v_pk_add_f32 v[46:47], v[24:25], v[36:37]
	v_pk_add_f32 v[24:25], v[24:25], v[36:37] neg_lo:[0,1] neg_hi:[0,1]
	v_pk_mul_f32 v[56:57], v[30:31], s[42:43]
	v_pk_fma_f32 v[42:43], v[42:43], s[40:41], v[50:51] op_sel:[0,0,1] op_sel_hi:[1,0,0] neg_lo:[1,0,0] neg_hi:[1,0,0]
	v_pk_mul_f32 v[36:37], v[24:25], s[42:43]
	v_pk_add_f32 v[50:51], v[28:29], v[40:41]
	v_pk_add_f32 v[28:29], v[28:29], v[40:41] neg_lo:[0,1] neg_hi:[0,1]
	v_pk_fma_f32 v[30:31], v[30:31], s[40:41], v[56:57] op_sel:[0,0,1] op_sel_hi:[1,0,0]
	v_pk_add_f32 v[56:57], v[32:33], v[48:49]
	v_pk_add_f32 v[48:49], v[32:33], v[48:49] neg_lo:[0,1] neg_hi:[0,1]
	v_pk_fma_f32 v[24:25], v[24:25], s[40:41], v[36:37] op_sel:[0,0,1] op_sel_hi:[1,0,0]
	v_pk_add_f32 v[36:37], v[26:27], v[38:39]
	v_pk_add_f32 v[38:39], v[26:27], v[38:39] neg_lo:[0,1] neg_hi:[0,1]
	v_pk_mul_f32 v[40:41], v[28:29], s[42:43] op_sel:[1,1] op_sel_hi:[0,0]
	v_pk_fma_f32 v[28:29], v[28:29], s[40:41], v[40:41] op_sel_hi:[1,0,1] neg_lo:[1,0,0] neg_hi:[1,0,0]
	v_lshl_add_u32 v6, v6, 4, v90
	v_pk_add_f32 v[40:41], v[52:53], v[56:57]
	v_pk_add_f32 v[52:53], v[52:53], v[56:57] neg_lo:[0,1] neg_hi:[0,1]
	v_pk_add_f32 v[56:57], v[54:55], v[58:59]
	v_pk_add_f32 v[58:59], v[54:55], v[58:59] neg_lo:[0,1] neg_hi:[0,1]
	v_pk_add_f32 v[32:33], v[44:45], v[48:49] op_sel:[0,1] op_sel_hi:[1,0] neg_hi:[0,1]
	v_pk_add_f32 v[44:45], v[44:45], v[48:49] op_sel:[0,1] op_sel_hi:[1,0] neg_lo:[0,1]
	v_pk_add_f32 v[48:49], v[30:31], v[42:43]
	v_pk_add_f32 v[42:43], v[30:31], v[42:43] neg_lo:[0,1] neg_hi:[0,1]
	v_pk_add_f32 v[60:61], v[34:35], v[36:37]
	v_pk_add_f32 v[34:35], v[34:35], v[36:37] neg_lo:[0,1] neg_hi:[0,1]
	v_pk_add_f32 v[36:37], v[46:47], v[50:51]
	v_pk_add_f32 v[50:51], v[46:47], v[50:51] neg_lo:[0,1] neg_hi:[0,1]
	v_pk_add_f32 v[26:27], v[22:23], v[38:39] op_sel:[0,1] op_sel_hi:[1,0] neg_hi:[0,1]
	v_pk_add_f32 v[22:23], v[22:23], v[38:39] op_sel:[0,1] op_sel_hi:[1,0] neg_lo:[0,1]
	v_pk_add_f32 v[38:39], v[24:25], v[28:29]
	v_pk_add_f32 v[28:29], v[24:25], v[28:29] neg_lo:[0,1] neg_hi:[0,1]
	v_ashrrev_i32_e32 v6, 5, v6
	v_pk_add_f32 v[66:67], v[40:41], v[56:57]
	v_pk_add_f32 v[40:41], v[40:41], v[56:57] neg_lo:[0,1] neg_hi:[0,1]
	v_lshlrev_b32_e32 v6, 3, v6
	v_pk_add_f32 v[54:55], v[52:53], v[58:59] op_sel:[0,1] op_sel_hi:[1,0] neg_hi:[0,1]
	v_pk_add_f32 v[52:53], v[52:53], v[58:59] op_sel:[0,1] op_sel_hi:[1,0] neg_lo:[0,1]
	v_pk_add_f32 v[56:57], v[32:33], v[48:49]
	v_pk_add_f32 v[32:33], v[32:33], v[48:49] neg_lo:[0,1] neg_hi:[0,1]
	v_pk_add_f32 v[30:31], v[44:45], v[42:43] op_sel:[0,1] op_sel_hi:[1,0] neg_hi:[0,1]
	v_pk_add_f32 v[42:43], v[44:45], v[42:43] op_sel:[0,1] op_sel_hi:[1,0] neg_lo:[0,1]
	v_pk_add_f32 v[44:45], v[60:61], v[36:37]
	v_pk_add_f32 v[36:37], v[60:61], v[36:37] neg_lo:[0,1] neg_hi:[0,1]
	v_pk_add_f32 v[46:47], v[34:35], v[50:51] op_sel:[0,1] op_sel_hi:[1,0] neg_hi:[0,1]
	v_pk_add_f32 v[34:35], v[34:35], v[50:51] op_sel:[0,1] op_sel_hi:[1,0] neg_lo:[0,1]
	v_pk_add_f32 v[48:49], v[26:27], v[38:39]
	v_pk_add_f32 v[26:27], v[26:27], v[38:39] neg_lo:[0,1] neg_hi:[0,1]
	v_pk_add_f32 v[24:25], v[22:23], v[28:29] op_sel:[0,1] op_sel_hi:[1,0] neg_hi:[0,1]
	v_pk_add_f32 v[22:23], v[22:23], v[28:29] op_sel:[0,1] op_sel_hi:[1,0] neg_lo:[0,1]
	ds_write2_b64 v11, v[66:67], v[40:41] offset1:1
	ds_write2_b64 v11, v[54:55], v[52:53] offset0:2 offset1:3
	ds_write2_b64 v11, v[56:57], v[32:33] offset0:4 offset1:5
	ds_write2_b64 v11, v[30:31], v[42:43] offset0:6 offset1:7
	ds_write2_b64 v11, v[44:45], v[36:37] offset0:8 offset1:9
	ds_write2_b64 v11, v[46:47], v[34:35] offset0:10 offset1:11
	ds_write2_b64 v11, v[48:49], v[26:27] offset0:12 offset1:13
	ds_write2_b64 v11, v[24:25], v[22:23] offset0:14 offset1:15
	v_add3_u32 v6, v68, v6, s35
	ds_read2_b64 v[22:25], v6 offset1:1
	ds_read2_b64 v[26:29], v6 offset0:2 offset1:3
	ds_read2_b64 v[30:33], v6 offset0:8 offset1:9
	ds_read2_b64 v[34:37], v6 offset0:4 offset1:5
	ds_read2_b64 v[38:41], v6 offset0:6 offset1:7
	ds_read2_b64 v[42:45], v6 offset0:10 offset1:11
	ds_read2_b64 v[46:49], v6 offset0:12 offset1:13
	ds_read2_b64 v[50:53], v6 offset0:14 offset1:15
	s_waitcnt lgkmcnt(5)
	v_pk_add_f32 v[54:55], v[22:23], v[30:31]
	v_pk_add_f32 v[22:23], v[22:23], v[30:31] neg_lo:[0,1] neg_hi:[0,1]
	v_pk_add_f32 v[30:31], v[24:25], v[32:33]
	v_pk_add_f32 v[24:25], v[24:25], v[32:33] neg_lo:[0,1] neg_hi:[0,1]
	s_waitcnt lgkmcnt(1)
	v_pk_add_f32 v[56:57], v[36:37], v[48:49]
	v_pk_mul_f32 v[32:33], v[24:25], s[38:39]
	v_pk_add_f32 v[36:37], v[36:37], v[48:49] neg_lo:[0,1] neg_hi:[0,1]
	v_pk_fma_f32 v[24:25], v[24:25], s[36:37], v[32:33] op_sel:[0,0,1] op_sel_hi:[1,0,0]
	v_pk_add_f32 v[32:33], v[26:27], v[42:43]
	v_pk_add_f32 v[26:27], v[26:27], v[42:43] neg_lo:[0,1] neg_hi:[0,1]
	v_pk_mul_f32 v[48:49], v[36:37], s[44:45]
	v_pk_mul_f32 v[42:43], v[26:27], s[42:43]
	v_pk_fma_f32 v[36:37], v[36:37], s[62:63], v[48:49] op_sel:[0,0,1] op_sel_hi:[1,0,0] neg_lo:[1,0,0] neg_hi:[1,0,0]
	v_pk_fma_f32 v[26:27], v[26:27], s[40:41], v[42:43] op_sel:[0,0,1] op_sel_hi:[1,0,0]
	v_pk_add_f32 v[42:43], v[28:29], v[44:45]
	v_pk_add_f32 v[28:29], v[28:29], v[44:45] neg_lo:[0,1] neg_hi:[0,1]
	s_waitcnt lgkmcnt(0)
	v_pk_add_f32 v[48:49], v[38:39], v[50:51]
	v_pk_add_f32 v[38:39], v[38:39], v[50:51] neg_lo:[0,1] neg_hi:[0,1]
	v_pk_mul_f32 v[44:45], v[28:29], s[44:45]
	v_pk_mul_f32 v[50:51], v[38:39], s[42:43]
	v_pk_fma_f32 v[28:29], v[28:29], s[62:63], v[44:45] op_sel:[0,0,1] op_sel_hi:[1,0,0]
	v_pk_add_f32 v[44:45], v[34:35], v[46:47]
	v_pk_add_f32 v[46:47], v[34:35], v[46:47] neg_lo:[0,1] neg_hi:[0,1]
	v_pk_fma_f32 v[38:39], v[38:39], s[40:41], v[50:51] op_sel:[0,0,1] op_sel_hi:[1,0,0] neg_lo:[1,0,0] neg_hi:[1,0,0]
	v_pk_add_f32 v[50:51], v[40:41], v[52:53]
	v_pk_add_f32 v[40:41], v[40:41], v[52:53] op_sel:[1,1] op_sel_hi:[0,0] neg_lo:[0,1] neg_hi:[0,1]
	v_pk_mul_f32 v[52:53], v[40:41], s[38:39] op_sel:[1,0] op_sel_hi:[0,1]
	v_pk_add_f32 v[58:59], v[42:43], v[50:51]
	v_pk_add_f32 v[42:43], v[42:43], v[50:51] neg_lo:[0,1] neg_hi:[0,1]
	v_pk_fma_f32 v[40:41], v[40:41], s[36:37], v[52:53] op_sel:[1,0,1] op_sel_hi:[0,0,0] neg_lo:[1,0,0] neg_hi:[1,0,0]
	v_pk_mul_f32 v[50:51], v[42:43], s[42:43]
	v_pk_add_f32 v[34:35], v[22:23], v[46:47] op_sel:[0,1] op_sel_hi:[1,0] neg_hi:[0,1]
	v_pk_add_f32 v[22:23], v[22:23], v[46:47] op_sel:[0,1] op_sel_hi:[1,0] neg_lo:[0,1]
	v_pk_add_f32 v[46:47], v[24:25], v[36:37]
	v_pk_add_f32 v[24:25], v[24:25], v[36:37] neg_lo:[0,1] neg_hi:[0,1]
	v_pk_add_f32 v[52:53], v[54:55], v[44:45]
	v_pk_add_f32 v[44:45], v[54:55], v[44:45] neg_lo:[0,1] neg_hi:[0,1]
	v_pk_add_f32 v[54:55], v[30:31], v[56:57]
	v_pk_add_f32 v[30:31], v[30:31], v[56:57] neg_lo:[0,1] neg_hi:[0,1]
	v_pk_fma_f32 v[42:43], v[42:43], s[40:41], v[50:51] op_sel:[0,0,1] op_sel_hi:[1,0,0] neg_lo:[1,0,0] neg_hi:[1,0,0]
	v_pk_mul_f32 v[36:37], v[24:25], s[42:43]
	v_pk_add_f32 v[50:51], v[28:29], v[40:41]
	v_pk_add_f32 v[28:29], v[28:29], v[40:41] neg_lo:[0,1] neg_hi:[0,1]
	s_and_b32 s24, s24, 0xc0
	v_pk_mul_f32 v[56:57], v[30:31], s[42:43]
	v_pk_fma_f32 v[24:25], v[24:25], s[40:41], v[36:37] op_sel:[0,0,1] op_sel_hi:[1,0,0]
	v_pk_add_f32 v[36:37], v[26:27], v[38:39]
	v_pk_add_f32 v[38:39], v[26:27], v[38:39] neg_lo:[0,1] neg_hi:[0,1]
	v_pk_mul_f32 v[40:41], v[28:29], s[42:43]
	s_lshl_b64 s[62:63], s[50:51], 19
	v_pk_fma_f32 v[30:31], v[30:31], s[40:41], v[56:57] op_sel:[0,0,1] op_sel_hi:[1,0,0]
	v_pk_add_f32 v[56:57], v[32:33], v[48:49]
	v_pk_add_f32 v[48:49], v[32:33], v[48:49] neg_lo:[0,1] neg_hi:[0,1]
	s_nop 0
	v_pk_fma_f32 v[28:29], v[28:29], s[40:41], v[40:41] op_sel:[0,0,1] op_sel_hi:[1,0,0] neg_lo:[1,0,0] neg_hi:[1,0,0]
	s_add_u32 s43, s3, s62
	s_nop 0
	s_nop 0
	v_pk_add_f32 v[26:27], v[22:23], v[38:39] op_sel:[0,1] op_sel_hi:[1,0] neg_hi:[0,1]
	v_pk_add_f32 v[22:23], v[22:23], v[38:39] op_sel:[0,1] op_sel_hi:[1,0] neg_lo:[0,1]
	v_pk_add_f32 v[38:39], v[24:25], v[28:29]
	v_pk_add_f32 v[24:25], v[24:25], v[28:29] neg_lo:[0,1] neg_hi:[0,1]
	s_addc_u32 s45, s29, s63
	s_lshl_b32 s64, s24, 2
	v_pk_add_f32 v[40:41], v[52:53], v[56:57]
	v_pk_add_f32 v[52:53], v[52:53], v[56:57] neg_lo:[0,1] neg_hi:[0,1]
	v_pk_add_f32 v[56:57], v[54:55], v[58:59]
	v_pk_add_f32 v[54:55], v[54:55], v[58:59] neg_lo:[0,1] neg_hi:[0,1]
	v_pk_add_f32 v[32:33], v[44:45], v[48:49] op_sel:[0,1] op_sel_hi:[1,0] neg_hi:[0,1]
	v_pk_add_f32 v[44:45], v[44:45], v[48:49] op_sel:[0,1] op_sel_hi:[1,0] neg_lo:[0,1]
	v_pk_add_f32 v[48:49], v[30:31], v[42:43]
	v_pk_add_f32 v[42:43], v[30:31], v[42:43] neg_lo:[0,1] neg_hi:[0,1]
	v_pk_add_f32 v[60:61], v[34:35], v[36:37]
	v_pk_add_f32 v[34:35], v[34:35], v[36:37] neg_lo:[0,1] neg_hi:[0,1]
	v_pk_add_f32 v[36:37], v[46:47], v[50:51]
	v_pk_add_f32 v[46:47], v[46:47], v[50:51] neg_lo:[0,1] neg_hi:[0,1]
	v_xor_b32_e32 v29, 0x80000000, v24
	v_mov_b32_e32 v28, v25
	s_add_u32 s64, s43, s64
	v_xor_b32_e32 v59, 0x80000000, v54
	s_nop 0
	v_xor_b32_e32 v51, 0x80000000, v46
	v_pk_add_f32 v[66:67], v[40:41], v[56:57]
	v_pk_add_f32 v[40:41], v[40:41], v[56:57] neg_lo:[0,1] neg_hi:[0,1]
	v_mov_b32_e32 v58, v55
	v_mov_b32_e32 v50, v47
	v_pk_add_f32 v[24:25], v[22:23], v[28:29]
	v_pk_add_f32 v[22:23], v[22:23], v[28:29] neg_lo:[0,1] neg_hi:[0,1]
	s_addc_u32 s65, s45, 0
	v_pk_add_f32 v[54:55], v[52:53], v[58:59]
	v_pk_add_f32 v[52:53], v[52:53], v[58:59] neg_lo:[0,1] neg_hi:[0,1]
	v_pk_add_f32 v[56:57], v[32:33], v[48:49]
	v_pk_add_f32 v[32:33], v[32:33], v[48:49] neg_lo:[0,1] neg_hi:[0,1]
	v_pk_add_f32 v[30:31], v[44:45], v[42:43] op_sel:[0,1] op_sel_hi:[1,0] neg_hi:[0,1]
	v_pk_add_f32 v[42:43], v[44:45], v[42:43] op_sel:[0,1] op_sel_hi:[1,0] neg_lo:[0,1]
	v_pk_add_f32 v[44:45], v[60:61], v[36:37]
	v_pk_add_f32 v[36:37], v[60:61], v[36:37] neg_lo:[0,1] neg_hi:[0,1]
	v_pk_add_f32 v[46:47], v[34:35], v[50:51]
	v_pk_add_f32 v[34:35], v[34:35], v[50:51] neg_lo:[0,1] neg_hi:[0,1]
	v_pk_add_f32 v[48:49], v[26:27], v[38:39]
	v_pk_add_f32 v[26:27], v[26:27], v[38:39] neg_lo:[0,1] neg_hi:[0,1]
	ds_write2_b64 v6, v[66:67], v[40:41] offset1:1
	ds_write2_b64 v6, v[54:55], v[52:53] offset0:2 offset1:3
	ds_write2_b64 v6, v[56:57], v[32:33] offset0:4 offset1:5
	ds_write2_b64 v6, v[30:31], v[42:43] offset0:6 offset1:7
	ds_write2_b64 v6, v[44:45], v[36:37] offset0:8 offset1:9
	ds_write2_b64 v6, v[46:47], v[34:35] offset0:10 offset1:11
	ds_write2_b64 v6, v[48:49], v[26:27] offset0:12 offset1:13
	ds_write2_b64 v6, v[24:25], v[22:23] offset0:14 offset1:15
	v_lshl_add_u64 v[22:23], s[64:65], 0, v[20:21]
	s_mov_b64 s[64:65], 0
	v_mov_b32_e32 v11, v9
	v_mov_b64_e32 v[24:25], v[62:63]
	s_waitcnt lgkmcnt(0)
	s_barrier

.LBB0_275:
	s_or_b64 exec, exec, s[10:11]
	v_mov_b32_e32 v40, v1
	s_mov_b32 s73, s50
	v_ashrrev_i32_e32 v42, 31, v40
	v_lshrrev_b32_e32 v42, 23, v42
	v_add_u32_e32 v42, v40, v42
	v_ashrrev_i32_e32 v42, 9, v42
	v_mul_i32_i24_e32 v44, 0x200, v42
	v_sub_u32_e32 v70, v40, v44
	v_lshlrev_b32_e32 v40, 14, v42
	v_lshlrev_b32_e32 v42, 1, v70
	v_bfrev_b32_e32 v42, v42
	v_lshrrev_b32_e32 v42, 22, v42
	v_sub_u32_e32 v42, 0x400, v42
	v_bfrev_b32_e32 v42, v42
	v_lshrrev_b32_e32 v42, 18, v42
	v_and_b32_e32 v42, 0x3ff0, v42
	v_cmp_eq_u32_e64 s[10:11], 0, v70
	v_lshl_add_u32 v44, v70, 5, v40
	v_lshlrev_b32_e32 v45, 3, v44
	v_cndmask_b32_e64 v42, v42, 16, s[10:11]
	v_or_b32_e32 v40, v42, v40
	v_ashrrev_i32_e32 v44, 2, v44
	v_ashrrev_i32_e32 v42, 5, v40
	v_add3_u32 v44, 0, v45, v44
	v_lshlrev_b32_e32 v40, 3, v40
	v_lshlrev_b32_e32 v42, 3, v42
	v_add3_u32 v40, 0, v40, v42
	ds_read2_b64 v[46:49], v44 offset1:1
	ds_read2_b64 v[50:53], v44 offset0:2 offset1:3
	ds_read2_b64 v[76:79], v40 offset1:1
	ds_read2_b64 v[80:83], v40 offset0:2 offset1:3
	ds_read2_b64 v[54:57], v44 offset0:4 offset1:5
	ds_read2_b64 v[58:61], v44 offset0:6 offset1:7
	ds_read2_b64 v[84:87], v40 offset0:4 offset1:5
	ds_read2_b64 v[88:91], v40 offset0:6 offset1:7
	ds_read2_b64 v[62:65], v44 offset0:8 offset1:9
	ds_read2_b64 v[66:69], v44 offset0:10 offset1:11
	ds_read2_b64 v[100:103], v40 offset0:8 offset1:9
	ds_read2_b64 v[104:107], v40 offset0:10 offset1:11
	ds_read2_b64 v[72:75], v44 offset0:12 offset1:13
	ds_read2_b64 v[92:95], v44 offset0:14 offset1:15
	ds_read2_b64 v[108:111], v40 offset0:12 offset1:13
	ds_read2_b64 v[112:115], v40 offset0:14 offset1:15
	s_waitcnt lgkmcnt(7)
	v_pk_add_f32 v[96:97], v[46:47], v[62:63]
	v_pk_add_f32 v[46:47], v[46:47], v[62:63] neg_lo:[0,1] neg_hi:[0,1]
	v_pk_add_f32 v[62:63], v[48:49], v[64:65]
	v_pk_add_f32 v[48:49], v[48:49], v[64:65] neg_lo:[0,1] neg_hi:[0,1]
	s_waitcnt lgkmcnt(3)
	v_pk_add_f32 v[98:99], v[56:57], v[74:75]
	v_pk_mul_f32 v[64:65], v[48:49], s[62:63]
	v_pk_add_f32 v[56:57], v[56:57], v[74:75] neg_lo:[0,1] neg_hi:[0,1]
	v_pk_fma_f32 v[48:49], v[48:49], s[50:51], v[64:65] op_sel:[0,0,1] op_sel_hi:[1,0,0]
	v_pk_add_f32 v[64:65], v[50:51], v[66:67]
	v_pk_add_f32 v[50:51], v[50:51], v[66:67] neg_lo:[0,1] neg_hi:[0,1]
	s_mov_b32 s80, s63
	v_pk_mul_f32 v[74:75], v[56:57], s[72:73]
	s_mov_b32 s78, s69
	v_pk_mul_f32 v[66:67], v[50:51], s[68:69]
	v_pk_fma_f32 v[56:57], v[56:57], s[80:81], v[74:75] op_sel:[0,0,1] op_sel_hi:[1,0,0] neg_lo:[1,0,0] neg_hi:[1,0,0]
	s_waitcnt lgkmcnt(2)
	v_pk_add_f32 v[74:75], v[58:59], v[92:93]
	v_pk_add_f32 v[58:59], v[58:59], v[92:93] neg_lo:[0,1] neg_hi:[0,1]
	v_pk_fma_f32 v[50:51], v[50:51], s[78:79], v[66:67] op_sel:[0,0,1] op_sel_hi:[1,0,0]
	v_pk_add_f32 v[66:67], v[52:53], v[68:69]
	v_pk_add_f32 v[52:53], v[52:53], v[68:69] neg_lo:[0,1] neg_hi:[0,1]
	v_pk_mul_f32 v[92:93], v[58:59], s[68:69]
	v_pk_mul_f32 v[68:69], v[52:53], s[72:73]
	v_pk_fma_f32 v[58:59], v[58:59], s[78:79], v[92:93] op_sel:[0,0,1] op_sel_hi:[1,0,0] neg_lo:[1,0,0] neg_hi:[1,0,0]
	v_pk_add_f32 v[92:93], v[60:61], v[94:95]
	v_pk_add_f32 v[60:61], v[60:61], v[94:95] neg_lo:[0,1] neg_hi:[0,1]
	v_pk_fma_f32 v[52:53], v[52:53], s[80:81], v[68:69] op_sel:[0,0,1] op_sel_hi:[1,0,0]
	v_pk_add_f32 v[68:69], v[54:55], v[72:73]
	v_pk_add_f32 v[54:55], v[54:55], v[72:73] neg_lo:[0,1] neg_hi:[0,1]
	v_pk_mul_f32 v[94:95], v[60:61], s[62:63]
	v_pk_add_f32 v[116:117], v[66:67], v[92:93]
	v_pk_add_f32 v[66:67], v[66:67], v[92:93] neg_lo:[0,1] neg_hi:[0,1]
	v_xor_b32_e32 v73, 0x80000000, v54
	v_pk_fma_f32 v[60:61], v[60:61], s[50:51], v[94:95] op_sel:[0,0,1] op_sel_hi:[1,0,0] neg_lo:[1,0,0] neg_hi:[1,0,0]
	v_pk_add_f32 v[94:95], v[96:97], v[68:69]
	v_pk_add_f32 v[68:69], v[96:97], v[68:69] neg_lo:[0,1] neg_hi:[0,1]
	v_pk_add_f32 v[96:97], v[62:63], v[98:99]
	v_pk_add_f32 v[62:63], v[62:63], v[98:99] neg_lo:[0,1] neg_hi:[0,1]
	v_pk_mul_f32 v[92:93], v[66:67], s[68:69]
	v_mov_b32_e32 v72, v55
	v_pk_mul_f32 v[98:99], v[62:63], s[68:69]
	v_pk_fma_f32 v[66:67], v[66:67], s[78:79], v[92:93] op_sel:[0,0,1] op_sel_hi:[1,0,0] neg_lo:[1,0,0] neg_hi:[1,0,0]
	v_pk_add_f32 v[54:55], v[46:47], v[72:73]
	v_pk_add_f32 v[46:47], v[46:47], v[72:73] neg_lo:[0,1] neg_hi:[0,1]
	v_pk_add_f32 v[72:73], v[48:49], v[56:57]
	v_pk_add_f32 v[48:49], v[48:49], v[56:57] neg_lo:[0,1] neg_hi:[0,1]
	v_pk_add_f32 v[92:93], v[52:53], v[60:61]
	v_pk_add_f32 v[52:53], v[52:53], v[60:61] neg_lo:[0,1] neg_hi:[0,1]
	v_pk_fma_f32 v[62:63], v[62:63], s[78:79], v[98:99] op_sel:[0,0,1] op_sel_hi:[1,0,0]
	v_pk_add_f32 v[98:99], v[64:65], v[74:75]
	v_pk_mul_f32 v[56:57], v[48:49], s[68:69]
	v_pk_mul_f32 v[60:61], v[52:53], s[68:69]
	v_pk_fma_f32 v[48:49], v[48:49], s[78:79], v[56:57] op_sel:[0,0,1] op_sel_hi:[1,0,0]
	v_pk_add_f32 v[56:57], v[50:51], v[58:59]
	v_pk_fma_f32 v[52:53], v[52:53], s[78:79], v[60:61] op_sel:[0,0,1] op_sel_hi:[1,0,0] neg_lo:[1,0,0] neg_hi:[1,0,0]
	v_pk_add_f32 v[60:61], v[94:95], v[98:99]
	v_pk_add_f32 v[118:119], v[94:95], v[98:99] neg_lo:[0,1] neg_hi:[0,1]
	v_pk_add_f32 v[94:95], v[96:97], v[116:117]
	v_pk_add_f32 v[116:117], v[96:97], v[116:117] neg_lo:[0,1] neg_hi:[0,1]
	v_pk_add_f32 v[128:129], v[54:55], v[56:57]
	v_pk_add_f32 v[54:55], v[54:55], v[56:57] neg_lo:[0,1] neg_hi:[0,1]
	v_pk_add_f32 v[56:57], v[72:73], v[92:93]
	v_pk_add_f32 v[92:93], v[72:73], v[92:93] neg_lo:[0,1] neg_hi:[0,1]
	v_pk_add_f32 v[96:97], v[78:79], v[102:103]
	v_pk_add_f32 v[78:79], v[78:79], v[102:103] neg_lo:[0,1] neg_hi:[0,1]
	v_xor_b32_e32 v131, 0x80000000, v92
	v_mov_b32_e32 v130, v93
	v_pk_add_f32 v[92:93], v[76:77], v[100:101]
	v_pk_add_f32 v[76:77], v[76:77], v[100:101] neg_lo:[0,1] neg_hi:[0,1]
	v_pk_mul_f32 v[100:101], v[78:79], s[62:63]
	v_bfrev_b32_e32 v40, v70
	v_pk_fma_f32 v[78:79], v[78:79], s[50:51], v[100:101] op_sel:[0,0,1] op_sel_hi:[1,0,0]
	v_pk_add_f32 v[100:101], v[80:81], v[104:105]
	v_pk_add_f32 v[80:81], v[80:81], v[104:105] neg_lo:[0,1] neg_hi:[0,1]
	v_lshrrev_b32_e32 v40, 23, v40
	v_pk_mul_f32 v[102:103], v[80:81], s[68:69]
	v_cvt_f32_u32_e32 v40, v40
	v_pk_fma_f32 v[80:81], v[80:81], s[78:79], v[102:103] op_sel:[0,0,1] op_sel_hi:[1,0,0]
	v_pk_add_f32 v[102:103], v[82:83], v[106:107]
	v_pk_add_f32 v[82:83], v[82:83], v[106:107] neg_lo:[0,1] neg_hi:[0,1]
	v_mul_f32_e32 v40, 0x38000000, v40
	v_pk_mul_f32 v[104:105], v[82:83], s[72:73]
	v_ashrrev_i32_e32 v71, 31, v70
	v_pk_fma_f32 v[82:83], v[82:83], s[80:81], v[104:105] op_sel:[0,0,1] op_sel_hi:[1,0,0]
	s_waitcnt lgkmcnt(1)
	v_pk_add_f32 v[104:105], v[84:85], v[108:109]
	v_pk_add_f32 v[106:107], v[84:85], v[108:109] neg_lo:[0,1] neg_hi:[0,1]
	v_pk_add_f32 v[74:75], v[64:65], v[74:75] neg_lo:[0,1] neg_hi:[0,1]
	v_pk_add_f32 v[84:85], v[86:87], v[110:111]
	v_pk_add_f32 v[86:87], v[86:87], v[110:111] neg_lo:[0,1] neg_hi:[0,1]
	v_cndmask_b32_e64 v40, v40, v154, s[10:11]
	v_pk_mul_f32 v[108:109], v[86:87], s[72:73]
	v_lshl_add_u64 v[44:45], v[70:71], 3, s[26:27]
	v_pk_fma_f32 v[86:87], v[86:87], s[80:81], v[108:109] op_sel:[0,0,1] op_sel_hi:[1,0,0] neg_lo:[1,0,0] neg_hi:[1,0,0]
	s_waitcnt lgkmcnt(0)
	v_pk_add_f32 v[108:109], v[88:89], v[112:113]
	v_pk_add_f32 v[88:89], v[88:89], v[112:113] op_sel:[1,1] op_sel_hi:[0,0] neg_lo:[0,1] neg_hi:[0,1]
	v_pk_mul_f32 v[110:111], v[88:89], s[68:69] op_sel:[1,0] op_sel_hi:[0,1]
	v_pk_add_f32 v[50:51], v[50:51], v[58:59] neg_lo:[0,1] neg_hi:[0,1]
	v_pk_fma_f32 v[88:89], v[88:89], s[78:79], v[110:111] op_sel:[1,0,1] op_sel_hi:[0,0,0] neg_lo:[1,0,0] neg_hi:[1,0,0]
	v_pk_add_f32 v[110:111], v[90:91], v[114:115]
	v_pk_add_f32 v[90:91], v[90:91], v[114:115] op_sel:[1,1] op_sel_hi:[0,0] neg_lo:[0,1] neg_hi:[0,1]
	v_pk_mul_f32 v[112:113], v[90:91], s[62:63] op_sel:[1,0] op_sel_hi:[0,1]
	v_pk_add_f32 v[124:125], v[62:63], v[66:67]
	v_pk_fma_f32 v[90:91], v[90:91], s[50:51], v[112:113] op_sel:[1,0,1] op_sel_hi:[0,0,0] neg_lo:[1,0,0] neg_hi:[1,0,0]
	v_pk_add_f32 v[112:113], v[92:93], v[104:105]
	v_pk_add_f32 v[92:93], v[92:93], v[104:105] neg_lo:[0,1] neg_hi:[0,1]
	v_pk_add_f32 v[104:105], v[96:97], v[84:85]
	v_pk_add_f32 v[84:85], v[96:97], v[84:85] neg_lo:[0,1] neg_hi:[0,1]
	v_pk_add_f32 v[66:67], v[62:63], v[66:67] neg_lo:[0,1] neg_hi:[0,1]
	v_pk_mul_f32 v[96:97], v[84:85], s[68:69]
	v_cos_f32_e32 v71, v40
	v_pk_fma_f32 v[84:85], v[84:85], s[78:79], v[96:97] op_sel:[0,0,1] op_sel_hi:[1,0,0]
	v_pk_add_f32 v[96:97], v[100:101], v[108:109]
	v_pk_add_f32 v[108:109], v[100:101], v[108:109] neg_lo:[0,1] neg_hi:[0,1]
	v_cmp_ne_u32_e32 vcc, 0, v70
	s_nop 0
	s_nop 0
	v_pk_add_f32 v[100:101], v[102:103], v[110:111]
	v_pk_add_f32 v[102:103], v[102:103], v[110:111] neg_lo:[0,1] neg_hi:[0,1]
	v_xor_b32_e32 v59, 0x80000000, v50
	v_pk_mul_f32 v[110:111], v[102:103], s[68:69]
	v_pk_add_f32 v[64:65], v[68:69], v[74:75] op_sel:[0,1] op_sel_hi:[1,0] neg_hi:[0,1]
	v_pk_fma_f32 v[102:103], v[102:103], s[78:79], v[110:111] op_sel:[0,0,1] op_sel_hi:[1,0,0] neg_lo:[1,0,0] neg_hi:[1,0,0]
	v_pk_add_f32 v[110:111], v[76:77], v[106:107] op_sel:[0,1] op_sel_hi:[1,0] neg_hi:[0,1]
	v_pk_add_f32 v[76:77], v[76:77], v[106:107] op_sel:[0,1] op_sel_hi:[1,0] neg_lo:[0,1]
	v_pk_add_f32 v[106:107], v[78:79], v[86:87]
	v_pk_add_f32 v[78:79], v[78:79], v[86:87] neg_lo:[0,1] neg_hi:[0,1]
	v_pk_add_f32 v[122:123], v[68:69], v[74:75] op_sel:[0,1] op_sel_hi:[1,0] neg_lo:[0,1]
	v_pk_mul_f32 v[86:87], v[78:79], s[68:69]
	v_xor_b32_e32 v127, 0x80000000, v66
	v_pk_fma_f32 v[78:79], v[78:79], s[78:79], v[86:87] op_sel:[0,0,1] op_sel_hi:[1,0,0]
	v_pk_add_f32 v[86:87], v[80:81], v[88:89]
	v_pk_add_f32 v[88:89], v[80:81], v[88:89] neg_lo:[0,1] neg_hi:[0,1]
	v_mov_b32_e32 v58, v51
	v_pk_add_f32 v[80:81], v[82:83], v[90:91]
	v_pk_add_f32 v[82:83], v[82:83], v[90:91] neg_lo:[0,1] neg_hi:[0,1]
	v_mov_b32_e32 v126, v67
	v_pk_mul_f32 v[90:91], v[82:83], s[68:69]
	v_sin_f32_e32 v70, v40
	v_pk_fma_f32 v[82:83], v[82:83], s[78:79], v[90:91] op_sel:[0,0,1] op_sel_hi:[1,0,0] neg_lo:[1,0,0] neg_hi:[1,0,0]
	v_pk_add_f32 v[132:133], v[46:47], v[58:59]
	v_pk_add_f32 v[156:157], v[46:47], v[58:59] neg_lo:[0,1] neg_hi:[0,1]
	v_pk_add_f32 v[46:47], v[48:49], v[52:53]
	v_pk_add_f32 v[52:53], v[48:49], v[52:53] neg_lo:[0,1] neg_hi:[0,1]
	v_pk_add_f32 v[98:99], v[60:61], v[94:95]
	v_pk_add_f32 v[94:95], v[60:61], v[94:95] neg_lo:[0,1] neg_hi:[0,1]
	v_pk_add_f32 v[74:75], v[118:119], v[116:117] op_sel:[0,1] op_sel_hi:[1,0] neg_hi:[0,1]
	v_pk_add_f32 v[68:69], v[118:119], v[116:117] op_sel:[0,1] op_sel_hi:[1,0] neg_lo:[0,1]
	v_pk_add_f32 v[72:73], v[64:65], v[124:125]
	v_pk_add_f32 v[62:63], v[64:65], v[124:125] neg_lo:[0,1] neg_hi:[0,1]
	v_pk_add_f32 v[60:61], v[122:123], v[126:127]
	v_pk_add_f32 v[66:67], v[122:123], v[126:127] neg_lo:[0,1] neg_hi:[0,1]
	v_pk_add_f32 v[114:115], v[112:113], v[96:97]
	v_pk_add_f32 v[96:97], v[112:113], v[96:97] neg_lo:[0,1] neg_hi:[0,1]
	v_pk_add_f32 v[112:113], v[104:105], v[100:101]
	v_pk_add_f32 v[100:101], v[104:105], v[100:101] neg_lo:[0,1] neg_hi:[0,1]
	v_pk_add_f32 v[104:105], v[92:93], v[108:109] op_sel:[0,1] op_sel_hi:[1,0] neg_hi:[0,1]
	v_pk_add_f32 v[92:93], v[92:93], v[108:109] op_sel:[0,1] op_sel_hi:[1,0] neg_lo:[0,1]
	v_pk_add_f32 v[108:109], v[84:85], v[102:103]
	v_pk_add_f32 v[102:103], v[84:85], v[102:103] neg_lo:[0,1] neg_hi:[0,1]
	v_pk_add_f32 v[118:119], v[106:107], v[80:81]
	v_pk_add_f32 v[106:107], v[106:107], v[80:81] neg_lo:[0,1] neg_hi:[0,1]
	v_pk_add_f32 v[122:123], v[76:77], v[88:89] op_sel:[0,1] op_sel_hi:[1,0] neg_hi:[0,1]
	v_pk_add_f32 v[124:125], v[76:77], v[88:89] op_sel:[0,1] op_sel_hi:[1,0] neg_lo:[0,1]
	v_pk_add_f32 v[76:77], v[78:79], v[82:83] neg_lo:[0,1] neg_hi:[0,1]
	v_xor_b32_e32 v159, 0x80000000, v52
	v_pk_add_f32 v[64:65], v[128:129], v[56:57]
	v_pk_add_f32 v[50:51], v[128:129], v[56:57] neg_lo:[0,1] neg_hi:[0,1]
	v_mov_b32_e32 v158, v53
	v_pk_add_f32 v[116:117], v[110:111], v[86:87]
	v_pk_add_f32 v[110:111], v[110:111], v[86:87] neg_lo:[0,1] neg_hi:[0,1]
	v_pk_add_f32 v[126:127], v[78:79], v[82:83]
	v_xor_b32_e32 v129, 0x80000000, v76
	v_mov_b32_e32 v128, v77
	v_pk_add_f32 v[56:57], v[54:55], v[130:131]
	v_pk_add_f32 v[58:59], v[54:55], v[130:131] neg_lo:[0,1] neg_hi:[0,1]
	v_pk_add_f32 v[54:55], v[132:133], v[46:47]
	v_pk_add_f32 v[48:49], v[132:133], v[46:47] neg_lo:[0,1] neg_hi:[0,1]
	v_pk_add_f32 v[46:47], v[156:157], v[158:159]
	v_pk_add_f32 v[52:53], v[156:157], v[158:159] neg_lo:[0,1] neg_hi:[0,1]
	v_pk_add_f32 v[90:91], v[114:115], v[112:113]
	v_pk_add_f32 v[86:87], v[114:115], v[112:113] neg_lo:[0,1] neg_hi:[0,1]
	v_pk_add_f32 v[80:81], v[96:97], v[100:101] op_sel:[0,1] op_sel_hi:[1,0] neg_hi:[0,1]
	v_pk_add_f32 v[84:85], v[96:97], v[100:101] op_sel:[0,1] op_sel_hi:[1,0] neg_lo:[0,1]
	v_pk_add_f32 v[76:77], v[104:105], v[108:109]
	v_pk_add_f32 v[78:79], v[104:105], v[108:109] neg_lo:[0,1] neg_hi:[0,1]
	v_pk_add_f32 v[82:83], v[92:93], v[102:103] op_sel:[0,1] op_sel_hi:[1,0] neg_hi:[0,1]
	v_pk_add_f32 v[88:89], v[92:93], v[102:103] op_sel:[0,1] op_sel_hi:[1,0] neg_lo:[0,1]
	v_pk_add_f32 v[92:93], v[116:117], v[118:119]
	v_pk_add_f32 v[100:101], v[116:117], v[118:119] neg_lo:[0,1] neg_hi:[0,1]
	v_pk_add_f32 v[102:103], v[110:111], v[106:107] op_sel:[0,1] op_sel_hi:[1,0] neg_hi:[0,1]
	v_pk_add_f32 v[106:107], v[110:111], v[106:107] op_sel:[0,1] op_sel_hi:[1,0] neg_lo:[0,1]
	v_pk_add_f32 v[108:109], v[122:123], v[126:127]
	v_pk_add_f32 v[110:111], v[122:123], v[126:127] neg_lo:[0,1] neg_hi:[0,1]
	v_pk_add_f32 v[112:113], v[124:125], v[128:129]
	v_pk_add_f32 v[118:119], v[124:125], v[128:129] neg_lo:[0,1] neg_hi:[0,1]
	v_mul_f32_e32 v40, 0x3f3504f3, v71
	v_mul_f32_e32 v104, 0xbec3ef15, v71
	v_mul_f32_e32 v96, 0xbf6c835e, v71
	s_and_saveexec_b64 s[10:11], vcc
	s_xor_b64 s[10:11], exec, s[10:11]
	s_cbranch_execz .LBB0_277
	v_pk_add_f32 v[114:115], v[98:99], v[118:119]
	v_pk_add_f32 v[98:99], v[98:99], v[118:119] neg_lo:[0,1] neg_hi:[0,1]
	v_mul_f32_e32 v42, 0.5, v114
	v_pk_fma_f32 v[116:117], v[70:71], 0, v[70:71] op_sel:[0,0,1] op_sel_hi:[1,0,0] neg_lo:[1,0,0]
	v_mov_b32_e32 v114, v98
	v_pk_mul_f32 v[114:115], v[114:115], s[74:75]
	s_mov_b32 s78, s63
	v_pk_mul_f32 v[118:119], v[116:117], v[114:115] op_sel:[0,1] op_sel_hi:[1,0]
	v_pk_mul_f32 v[114:115], v[116:117], v[114:115]
	s_mov_b32 s79, s50
	v_sub_f32_e32 v97, v114, v115
	v_fma_mixlo_f16 v105, v99, s75, v97
	v_fma_f32 v97, v99, 0.5, -v97
	v_cvt_f16_f32_sdwa v97, -v97 dst_sel:WORD_1 dst_unused:UNUSED_PAD src0_sel:DWORD
	v_pk_add_f32 v[98:99], v[118:119], v[118:119] op_sel:[0,1] op_sel_hi:[0,1]
	s_waitcnt vmcnt(0)
	v_pk_add_f32 v[114:115], v[42:43], v[98:99]
	v_pk_add_f32 v[98:99], v[42:43], v[98:99] op_sel_hi:[0,1] neg_lo:[0,1] neg_hi:[0,1]
	v_cvt_pk_f16_f32 v42, v114, v99
	v_lshlrev_b32_e32 v98, 16, v105
	v_or_b32_sdwa v99, v97, v42 dst_sel:DWORD dst_unused:UNUSED_PAD src0_sel:DWORD src1_sel:WORD_1
	v_or_b32_sdwa v98, v98, v42 dst_sel:DWORD dst_unused:UNUSED_PAD src0_sel:DWORD src1_sel:WORD_0
	global_store_dwordx2 v[44:45], v[98:99], off
	v_pk_add_f32 v[98:99], v[94:95], v[112:113]
	v_pk_add_f32 v[94:95], v[94:95], v[112:113] neg_lo:[0,1] neg_hi:[0,1]
	v_mul_f32_e32 v42, 0.5, v98
	v_mov_b32_e32 v98, v71
	v_mov_b32_e32 v112, v71
	v_mov_b32_e32 v113, v70
	v_pk_fma_f32 v[114:115], v[70:71], 0, v[112:113] op_sel_hi:[1,0,1] neg_lo:[0,0,1] neg_hi:[0,0,1]
	v_pk_fma_f32 v[116:117], v[70:71], 0, v[98:99] op_sel_hi:[1,0,1]
	v_mov_b32_e32 v98, v94
	v_pk_mov_b32 v[114:115], v[114:115], v[116:117] op_sel:[1,0]
	v_pk_mul_f32 v[98:99], v[98:99], s[74:75]
	s_mov_b32 s51, s63
	v_pk_mul_f32 v[116:117], v[114:115], v[98:99] op_sel:[0,1] op_sel_hi:[1,0]
	v_pk_mul_f32 v[98:99], v[114:115], v[98:99]
	v_pk_add_f32 v[114:115], v[74:75], v[110:111]
	v_sub_f32_e32 v94, v98, v99
	v_fma_mixlo_f16 v97, v95, s75, v94
	v_fma_f32 v94, v95, 0.5, -v94
	v_cvt_f16_f32_sdwa v105, -v94 dst_sel:WORD_1 dst_unused:UNUSED_PAD src0_sel:DWORD
	v_pk_add_f32 v[94:95], v[116:117], v[116:117] op_sel:[0,1] op_sel_hi:[0,1]
	v_pk_add_f32 v[98:99], v[42:43], v[94:95]
	v_pk_add_f32 v[94:95], v[42:43], v[94:95] op_sel_hi:[0,1] neg_lo:[0,1] neg_hi:[0,1]
	v_cvt_pk_f16_f32 v42, v98, v95
	v_lshlrev_b32_e32 v94, 16, v97
	v_add_co_u32_e32 v98, vcc, s31, v44
	v_or_b32_sdwa v95, v105, v42 dst_sel:DWORD dst_unused:UNUSED_PAD src0_sel:DWORD src1_sel:WORD_1
	v_or_b32_sdwa v94, v94, v42 dst_sel:DWORD dst_unused:UNUSED_PAD src0_sel:DWORD src1_sel:WORD_0
	v_addc_co_u32_e32 v99, vcc, 0, v45, vcc
	global_store_dwordx2 v[98:99], v[94:95], off offset:-4096
	v_pk_mul_f32 v[94:95], v[112:113], s[68:69]
	v_pk_add_f32 v[74:75], v[74:75], v[110:111] neg_lo:[0,1] neg_hi:[0,1]
	v_mul_f32_e32 v42, 0.5, v114
	v_pk_add_f32 v[110:111], v[40:41], v[94:95] op_sel:[0,1] op_sel_hi:[0,1] neg_lo:[0,1] neg_hi:[0,1]
	v_pk_fma_f32 v[116:117], v[112:113], s[68:69], v[40:41] op_sel_hi:[1,1,0]
	v_mov_b32_e32 v114, v74
	v_mov_b32_e32 v111, v117
	v_pk_mul_f32 v[114:115], v[114:115], s[74:75]
	s_mov_b32 s45, s41
	v_pk_mul_f32 v[116:117], v[110:111], v[114:115] op_sel:[0,1] op_sel_hi:[1,0]
	v_pk_mul_f32 v[114:115], v[110:111], v[114:115]
	s_mov_b32 s65, s67
	v_sub_f32_e32 v40, v114, v115
	v_fma_mixlo_f16 v97, v75, s75, v40
	v_fma_f32 v40, v75, 0.5, -v40
	v_cvt_f16_f32_sdwa v40, -v40 dst_sel:WORD_1 dst_unused:UNUSED_PAD src0_sel:DWORD
	v_pk_add_f32 v[74:75], v[116:117], v[116:117] op_sel:[0,1] op_sel_hi:[0,1]
	v_pk_add_f32 v[114:115], v[42:43], v[74:75]
	v_pk_add_f32 v[74:75], v[42:43], v[74:75] op_sel_hi:[0,1] neg_lo:[0,1] neg_hi:[0,1]
	v_cvt_pk_f16_f32 v42, v114, v75
	v_lshlrev_b32_e32 v74, 16, v97
	v_or_b32_sdwa v75, v40, v42 dst_sel:DWORD dst_unused:UNUSED_PAD src0_sel:DWORD src1_sel:WORD_1
	v_or_b32_sdwa v74, v74, v42 dst_sel:DWORD dst_unused:UNUSED_PAD src0_sel:DWORD src1_sel:WORD_0
	global_store_dwordx2 v[98:99], v[74:75], off
	v_pk_fma_f32 v[74:75], v[112:113], s[68:69], v[94:95] op_sel:[0,0,1] op_sel_hi:[1,1,0] neg_lo:[0,0,1] neg_hi:[0,0,1]
	v_pk_add_f32 v[94:95], v[68:69], v[108:109]
	v_pk_add_f32 v[68:69], v[68:69], v[108:109] neg_lo:[0,1] neg_hi:[0,1]
	v_mul_f32_e32 v40, 0.5, v94
	v_mov_b32_e32 v94, v68
	v_pk_mul_f32 v[94:95], v[94:95], s[74:75]
	v_mov_b32_e32 v75, v110
	v_mov_b32_e32 v111, v74
	v_pk_mul_f32 v[74:75], v[74:75], v[94:95]
	v_pk_mul_f32 v[98:99], v[110:111], v[94:95]
	v_sub_f32_e32 v42, v74, v75
	v_fma_mixlo_f16 v94, v69, s75, v42
	v_fma_f32 v42, v69, 0.5, -v42
	v_cvt_f16_f32_sdwa v42, -v42 dst_sel:WORD_1 dst_unused:UNUSED_PAD src0_sel:DWORD
	v_pk_add_f32 v[68:69], v[98:99], v[98:99] op_sel:[1,0] op_sel_hi:[1,0]
	s_nop 0
	v_pk_add_f32 v[74:75], v[40:41], v[68:69]
	v_pk_add_f32 v[68:69], v[40:41], v[68:69] op_sel_hi:[0,1] neg_lo:[0,1] neg_hi:[0,1]
	v_cvt_pk_f16_f32 v40, v74, v69
	v_lshlrev_b32_e32 v68, 16, v94
	v_add_co_u32_e32 v74, vcc, s30, v44
	v_or_b32_sdwa v69, v42, v40 dst_sel:DWORD dst_unused:UNUSED_PAD src0_sel:DWORD src1_sel:WORD_1
	v_or_b32_sdwa v68, v68, v40 dst_sel:DWORD dst_unused:UNUSED_PAD src0_sel:DWORD src1_sel:WORD_0
	v_addc_co_u32_e32 v75, vcc, 0, v45, vcc
	global_store_dwordx2 v[74:75], v[68:69], off offset:-4096
	v_mov_b32_e32 v42, v71
	v_pk_mul_f32 v[68:69], v[70:71], s[78:79] op_sel_hi:[0,1]
	v_pk_add_f32 v[94:95], v[72:73], v[106:107]
	v_pk_add_f32 v[72:73], v[72:73], v[106:107] neg_lo:[0,1] neg_hi:[0,1]
	v_mul_f32_e32 v40, 0.5, v94
	v_pk_fma_f32 v[98:99], v[42:43], s[50:51], v[68:69] op_sel_hi:[0,1,1] neg_lo:[0,0,1] neg_hi:[0,0,1]
	v_pk_fma_f32 v[106:107], v[42:43], s[50:51], v[68:69] op_sel_hi:[0,1,1]
	v_mov_b32_e32 v94, v72
	v_mov_b32_e32 v108, v98
	v_mov_b32_e32 v109, v107
	v_pk_mul_f32 v[94:95], v[94:95], s[74:75]
	s_mov_b32 s78, s41
	v_pk_mul_f32 v[110:111], v[108:109], v[94:95] op_sel:[0,1] op_sel_hi:[1,0]
	v_pk_mul_f32 v[94:95], v[108:109], v[94:95]
	s_mov_b32 s79, s44
	v_sub_f32_e32 v72, v94, v95
	v_fma_mixlo_f16 v97, v73, s75, v72
	v_fma_f32 v72, v73, 0.5, -v72
	v_cvt_f16_f32_sdwa v105, -v72 dst_sel:WORD_1 dst_unused:UNUSED_PAD src0_sel:DWORD
	v_pk_add_f32 v[72:73], v[110:111], v[110:111] op_sel:[0,1] op_sel_hi:[0,1]
	v_pk_add_f32 v[94:95], v[40:41], v[72:73]
	v_pk_add_f32 v[72:73], v[40:41], v[72:73] op_sel_hi:[0,1] neg_lo:[0,1] neg_hi:[0,1]
	v_cvt_pk_f16_f32 v40, v94, v73
	v_lshlrev_b32_e32 v72, 16, v97
	v_or_b32_sdwa v73, v105, v40 dst_sel:DWORD dst_unused:UNUSED_PAD src0_sel:DWORD src1_sel:WORD_1
	v_or_b32_sdwa v72, v72, v40 dst_sel:DWORD dst_unused:UNUSED_PAD src0_sel:DWORD src1_sel:WORD_0
	global_store_dwordx2 v[74:75], v[72:73], off
	v_pk_add_f32 v[72:73], v[62:63], v[102:103]
	v_sub_f32_e32 v75, v63, v103
	v_mov_b32_e32 v105, v62
	v_pk_mov_b32 v[62:63], v[68:69], v[102:103] op_sel:[1,0]
	v_mul_f32_e32 v40, 0.5, v73
	v_pk_add_f32 v[62:63], v[104:105], v[62:63] neg_lo:[0,1] neg_hi:[0,1]
	v_mul_f32_e32 v74, 0.5, v72
	v_pk_mul_f32 v[94:95], v[62:63], v[40:41]
	s_nop 0
	v_mul_f32_e32 v62, v62, v95
	v_fma_f32 v40, -v98, v40, v62
	v_fma_mixlo_f16 v69, v75, s75, v40
	v_fma_f32 v40, v75, 0.5, -v40
	v_pk_fma_f32 v[102:103], v[98:99], v[94:95], v[94:95] op_sel:[0,1,0] op_sel_hi:[1,0,1]
	v_cvt_f16_f32_sdwa v40, -v40 dst_sel:WORD_1 dst_unused:UNUSED_PAD src0_sel:DWORD
	v_pk_add_f32 v[62:63], v[74:75], v[102:103]
	v_lshlrev_b32_e32 v69, 16, v69
	v_fma_f32 v63, v72, 0.5, -v102
	v_cvt_pk_f16_f32 v62, v62, v63
	v_add_co_u32_e32 v72, vcc, s33, v44
	v_or_b32_sdwa v63, v40, v62 dst_sel:DWORD dst_unused:UNUSED_PAD src0_sel:DWORD src1_sel:WORD_1
	v_or_b32_sdwa v62, v69, v62 dst_sel:DWORD dst_unused:UNUSED_PAD src0_sel:DWORD src1_sel:WORD_0
	v_addc_co_u32_e32 v73, vcc, 0, v45, vcc
	global_store_dwordx2 v[72:73], v[62:63], off offset:-4096
	v_pk_add_f32 v[62:63], v[100:101], v[60:61]
	v_pk_add_f32 v[60:61], v[60:61], v[100:101] neg_lo:[0,1] neg_hi:[0,1]
	v_mul_f32_e32 v40, 0.5, v62
	v_mov_b32_e32 v62, v60
	v_pk_mov_b32 v[74:75], v[98:99], v[106:107] op_sel:[1,0]
	v_pk_mul_f32 v[62:63], v[62:63], s[74:75] op_sel:[1,1] op_sel_hi:[0,0]
	v_pk_mul_f32 v[94:95], v[74:75], v[62:63]
	v_pk_mul_f32 v[62:63], v[62:63], v[74:75] op_sel:[1,0] op_sel_hi:[0,1]
	v_sub_f32_e32 v60, v62, v63
	v_fma_mixlo_f16 v69, v61, s75, v60
	v_fma_f32 v60, v61, 0.5, -v60
	v_cvt_f16_f32_sdwa v97, -v60 dst_sel:WORD_1 dst_unused:UNUSED_PAD src0_sel:DWORD
	v_pk_add_f32 v[60:61], v[94:95], v[94:95] op_sel:[0,1] op_sel_hi:[0,1]
	v_pk_add_f32 v[62:63], v[40:41], v[60:61]
	v_pk_add_f32 v[60:61], v[40:41], v[60:61] op_sel_hi:[0,1] neg_lo:[0,1] neg_hi:[0,1]
	v_cvt_pk_f16_f32 v40, v62, v61
	v_lshlrev_b32_e32 v60, 16, v69
	v_or_b32_sdwa v61, v97, v40 dst_sel:DWORD dst_unused:UNUSED_PAD src0_sel:DWORD src1_sel:WORD_1
	v_or_b32_sdwa v60, v60, v40 dst_sel:DWORD dst_unused:UNUSED_PAD src0_sel:DWORD src1_sel:WORD_0
	global_store_dwordx2 v[72:73], v[60:61], off
	v_pk_add_f32 v[60:61], v[92:93], v[66:67]
	v_mov_b32_e32 v97, v66
	v_mov_b32_e32 v69, v92
	v_sub_f32_e32 v63, v67, v93
	v_mul_f32_e32 v40, 0.5, v61
	v_pk_add_f32 v[66:67], v[96:97], v[68:69] neg_lo:[0,1] neg_hi:[0,1]
	v_mul_f32_e32 v62, 0.5, v60
	v_pk_mul_f32 v[68:69], v[66:67], v[40:41]
	s_nop 0
	v_mul_f32_e32 v61, v66, v69
	v_fma_f32 v40, -v99, v40, v61
	v_fma_mixlo_f16 v61, v63, s75, v40
	v_fma_f32 v40, v63, 0.5, -v40
	v_cvt_f16_f32_sdwa v40, -v40 dst_sel:WORD_1 dst_unused:UNUSED_PAD src0_sel:DWORD
	v_pk_fma_f32 v[72:73], v[74:75], v[68:69], v[68:69] op_sel:[0,1,0] op_sel_hi:[1,0,1]
	v_pk_add_f32 v[66:67], v[64:65], v[88:89]
	v_pk_add_f32 v[62:63], v[62:63], v[72:73]
	v_fma_f32 v60, v60, 0.5, -v72
	v_cvt_pk_f16_f32 v60, v62, v60
	v_lshlrev_b32_e32 v62, 16, v61
	v_or_b32_sdwa v61, v40, v60 dst_sel:DWORD dst_unused:UNUSED_PAD src0_sel:DWORD src1_sel:WORD_1
	v_or_b32_sdwa v60, v62, v60 dst_sel:DWORD dst_unused:UNUSED_PAD src0_sel:DWORD src1_sel:WORD_0
	v_add_co_u32_e32 v62, vcc, s34, v44
	v_pk_add_f32 v[64:65], v[64:65], v[88:89] neg_lo:[0,1] neg_hi:[0,1]
	s_nop 0
	v_addc_co_u32_e32 v63, vcc, 0, v45, vcc
	global_store_dwordx2 v[62:63], v[60:61], off offset:-4096
	v_pk_mul_f32 v[60:61], v[70:71], s[44:45] op_sel_hi:[0,1]
	v_mul_f32_e32 v40, 0.5, v66
	v_pk_fma_f32 v[68:69], v[42:43], s[78:79], v[60:61] op_sel_hi:[0,1,1] neg_lo:[0,0,1] neg_hi:[0,0,1]
	v_pk_fma_f32 v[72:73], v[42:43], s[78:79], v[60:61] op_sel_hi:[0,1,1]
	v_mov_b32_e32 v66, v64
	v_mov_b32_e32 v74, v68
	v_mov_b32_e32 v75, v73
	v_pk_mul_f32 v[66:67], v[66:67], s[74:75]
	s_mov_b32 s78, s67
	v_pk_mul_f32 v[88:89], v[74:75], v[66:67] op_sel:[0,1] op_sel_hi:[1,0]
	v_pk_mul_f32 v[66:67], v[74:75], v[66:67]
	s_mov_b32 s79, s64
	v_sub_f32_e32 v64, v66, v67
	v_fma_mixlo_f16 v74, v65, s75, v64
	v_fma_f32 v64, v65, 0.5, -v64
	v_cvt_f16_f32_sdwa v75, -v64 dst_sel:WORD_1 dst_unused:UNUSED_PAD src0_sel:DWORD
	v_pk_add_f32 v[64:65], v[88:89], v[88:89] op_sel:[0,1] op_sel_hi:[0,1]
	v_pk_add_f32 v[66:67], v[40:41], v[64:65]
	v_pk_add_f32 v[64:65], v[40:41], v[64:65] op_sel_hi:[0,1] neg_lo:[0,1] neg_hi:[0,1]
	v_cvt_pk_f16_f32 v40, v66, v65
	v_lshlrev_b32_e32 v64, 16, v74
	v_or_b32_sdwa v65, v75, v40 dst_sel:DWORD dst_unused:UNUSED_PAD src0_sel:DWORD src1_sel:WORD_1
	v_or_b32_sdwa v64, v64, v40 dst_sel:DWORD dst_unused:UNUSED_PAD src0_sel:DWORD src1_sel:WORD_0
	global_store_dwordx2 v[62:63], v[64:65], off
	v_mul_f32_e32 v62, 0xbe47c5c2, v71
	v_pk_add_f32 v[64:65], v[50:51], v[82:83]
	v_sub_f32_e32 v67, v51, v83
	v_mov_b32_e32 v63, v50
	v_pk_mov_b32 v[50:51], v[60:61], v[82:83] op_sel:[1,0]
	v_mul_f32_e32 v40, 0.5, v65
	v_pk_add_f32 v[50:51], v[62:63], v[50:51] neg_lo:[0,1] neg_hi:[0,1]
	v_mul_f32_e32 v66, 0.5, v64
	v_pk_mul_f32 v[62:63], v[50:51], v[40:41]
	s_nop 0
	v_mul_f32_e32 v50, v50, v63
	v_fma_f32 v40, -v68, v40, v50
	v_fma_mixlo_f16 v61, v67, s75, v40
	v_fma_f32 v40, v67, 0.5, -v40
	v_pk_fma_f32 v[74:75], v[68:69], v[62:63], v[62:63] op_sel:[0,1,0] op_sel_hi:[1,0,1]
	v_cvt_f16_f32_sdwa v40, -v40 dst_sel:WORD_1 dst_unused:UNUSED_PAD src0_sel:DWORD
	v_pk_add_f32 v[50:51], v[66:67], v[74:75]
	v_lshlrev_b32_e32 v61, 16, v61
	v_fma_f32 v51, v64, 0.5, -v74
	v_cvt_pk_f16_f32 v50, v50, v51
	v_add_co_u32_e32 v62, vcc, s35, v44
	v_or_b32_sdwa v51, v40, v50 dst_sel:DWORD dst_unused:UNUSED_PAD src0_sel:DWORD src1_sel:WORD_1
	v_or_b32_sdwa v50, v61, v50 dst_sel:DWORD dst_unused:UNUSED_PAD src0_sel:DWORD src1_sel:WORD_0
	v_addc_co_u32_e32 v63, vcc, 0, v45, vcc
	global_store_dwordx2 v[62:63], v[50:51], off offset:-4096
	v_pk_mul_f32 v[50:51], v[70:71], s[64:65] op_sel_hi:[0,1]
	v_pk_add_f32 v[64:65], v[78:79], v[56:57]
	v_pk_add_f32 v[56:57], v[56:57], v[78:79] neg_lo:[0,1] neg_hi:[0,1]
	v_mul_f32_e32 v40, 0.5, v64
	v_pk_fma_f32 v[66:67], v[42:43], s[78:79], v[50:51] op_sel_hi:[0,1,1] neg_lo:[0,0,1] neg_hi:[0,0,1]
	v_pk_fma_f32 v[74:75], v[42:43], s[78:79], v[50:51] op_sel_hi:[0,1,1]
	v_mov_b32_e32 v64, v56
	v_mov_b32_e32 v78, v66
	v_mov_b32_e32 v79, v75
	v_pk_mul_f32 v[64:65], v[64:65], s[74:75] op_sel:[1,1] op_sel_hi:[0,0]
	v_pk_mul_f32 v[82:83], v[78:79], v[64:65]
	v_pk_mul_f32 v[64:65], v[64:65], v[78:79] op_sel:[1,0] op_sel_hi:[0,1]
	v_sub_f32_e32 v42, v64, v65
	v_fma_mixlo_f16 v61, v57, s75, v42
	v_fma_f32 v42, v57, 0.5, -v42
	v_cvt_f16_f32_sdwa v42, -v42 dst_sel:WORD_1 dst_unused:UNUSED_PAD src0_sel:DWORD
	v_pk_add_f32 v[56:57], v[82:83], v[82:83] op_sel:[0,1] op_sel_hi:[0,1]
	v_pk_add_f32 v[64:65], v[40:41], v[56:57]
	v_pk_add_f32 v[56:57], v[40:41], v[56:57] op_sel_hi:[0,1] neg_lo:[0,1] neg_hi:[0,1]
	v_cvt_pk_f16_f32 v40, v64, v57
	v_lshlrev_b32_e32 v56, 16, v61
	v_or_b32_sdwa v57, v42, v40 dst_sel:DWORD dst_unused:UNUSED_PAD src0_sel:DWORD src1_sel:WORD_1
	v_or_b32_sdwa v56, v56, v40 dst_sel:DWORD dst_unused:UNUSED_PAD src0_sel:DWORD src1_sel:WORD_0
	global_store_dwordx2 v[62:63], v[56:57], off
	v_mul_f32_e32 v56, 0xbf54db31, v71
	v_pk_add_f32 v[62:63], v[76:77], v[58:59]
	v_sub_f32_e32 v61, v59, v77
	v_mov_b32_e32 v57, v58
	v_pk_mov_b32 v[58:59], v[50:51], v[76:77] op_sel:[1,0]
	v_mul_f32_e32 v40, 0.5, v63
	v_pk_add_f32 v[56:57], v[56:57], v[58:59] neg_lo:[0,1] neg_hi:[0,1]
	v_mul_f32_e32 v42, 0.5, v62
	v_pk_mul_f32 v[58:59], v[56:57], v[40:41]
	s_nop 0
	v_mul_f32_e32 v51, v56, v59
	v_fma_f32 v40, -v66, v40, v51
	v_fma_mixlo_f16 v51, v61, s75, v40
	v_fma_f32 v40, v61, 0.5, -v40
	v_cvt_f16_f32_sdwa v40, -v40 dst_sel:WORD_1 dst_unused:UNUSED_PAD src0_sel:DWORD
	v_pk_fma_f32 v[64:65], v[66:67], v[58:59], v[58:59] op_sel:[0,1,0] op_sel_hi:[1,0,1]
	v_lshlrev_b32_e32 v51, 16, v51
	v_pk_add_f32 v[56:57], v[42:43], v[64:65]
	v_fma_f32 v42, v62, 0.5, -v64
	v_cvt_pk_f16_f32 v42, v56, v42
	v_add_co_u32_e32 v58, vcc, s39, v44
	v_or_b32_sdwa v57, v40, v42 dst_sel:DWORD dst_unused:UNUSED_PAD src0_sel:DWORD src1_sel:WORD_1
	v_or_b32_sdwa v56, v51, v42 dst_sel:DWORD dst_unused:UNUSED_PAD src0_sel:DWORD src1_sel:WORD_0
	v_addc_co_u32_e32 v59, vcc, 0, v45, vcc
	global_store_dwordx2 v[58:59], v[56:57], off offset:-4096
	v_pk_add_f32 v[56:57], v[84:85], v[54:55]
	v_pk_add_f32 v[54:55], v[54:55], v[84:85] neg_lo:[0,1] neg_hi:[0,1]
	v_mul_f32_e32 v40, 0.5, v56
	v_mov_b32_e32 v56, v54
	v_pk_mov_b32 v[62:63], v[66:67], v[74:75] op_sel:[1,0]
	v_pk_mul_f32 v[56:57], v[56:57], s[74:75] op_sel:[1,1] op_sel_hi:[0,0]
	v_pk_mul_f32 v[64:65], v[62:63], v[56:57]
	v_pk_mul_f32 v[56:57], v[56:57], v[62:63] op_sel:[1,0] op_sel_hi:[0,1]
	v_sub_f32_e32 v42, v56, v57
	v_fma_mixlo_f16 v51, v55, s75, v42
	v_fma_f32 v42, v55, 0.5, -v42
	v_cvt_f16_f32_sdwa v42, -v42 dst_sel:WORD_1 dst_unused:UNUSED_PAD src0_sel:DWORD
	v_pk_add_f32 v[54:55], v[64:65], v[64:65] op_sel:[0,1] op_sel_hi:[0,1]
	v_pk_add_f32 v[56:57], v[40:41], v[54:55]
	v_pk_add_f32 v[54:55], v[40:41], v[54:55] op_sel_hi:[0,1] neg_lo:[0,1] neg_hi:[0,1]
	v_cvt_pk_f16_f32 v40, v56, v55
	v_lshlrev_b32_e32 v51, 16, v51
	v_or_b32_sdwa v55, v42, v40 dst_sel:DWORD dst_unused:UNUSED_PAD src0_sel:DWORD src1_sel:WORD_1
	v_or_b32_sdwa v54, v51, v40 dst_sel:DWORD dst_unused:UNUSED_PAD src0_sel:DWORD src1_sel:WORD_0
	global_store_dwordx2 v[58:59], v[54:55], off
	v_mul_f32_e32 v54, 0xbf0e39da, v71
	v_pk_add_f32 v[56:57], v[80:81], v[48:49]
	v_mov_b32_e32 v55, v48
	v_mov_b32_e32 v51, v80
	v_sub_f32_e32 v58, v49, v81
	v_mul_f32_e32 v40, 0.5, v57
	v_pk_add_f32 v[48:49], v[54:55], v[50:51] neg_lo:[0,1] neg_hi:[0,1]
	v_mul_f32_e32 v42, 0.5, v56
	v_pk_mul_f32 v[50:51], v[48:49], v[40:41]
	s_nop 0
	v_mul_f32_e32 v48, v48, v51
	v_fma_f32 v40, -v67, v40, v48
	v_pk_fma_f32 v[54:55], v[62:63], v[50:51], v[50:51] op_sel:[0,1,0] op_sel_hi:[1,0,1]
	v_fma_mixlo_f16 v50, v58, s75, v40
	v_fma_f32 v40, v58, 0.5, -v40
	v_cvt_f16_f32_sdwa v40, -v40 dst_sel:WORD_1 dst_unused:UNUSED_PAD src0_sel:DWORD
	v_pk_add_f32 v[48:49], v[42:43], v[54:55]
	v_fma_f32 v42, v56, 0.5, -v54
	v_cvt_pk_f16_f32 v42, v48, v42
	v_lshlrev_b32_e32 v48, 16, v50
	v_add_co_u32_e32 v50, vcc, s43, v44
	v_or_b32_sdwa v49, v40, v42 dst_sel:DWORD dst_unused:UNUSED_PAD src0_sel:DWORD src1_sel:WORD_1
	v_or_b32_sdwa v48, v48, v42 dst_sel:DWORD dst_unused:UNUSED_PAD src0_sel:DWORD src1_sel:WORD_0
	v_addc_co_u32_e32 v51, vcc, 0, v45, vcc
	global_store_dwordx2 v[50:51], v[48:49], off offset:-4096
	v_pk_add_f32 v[48:49], v[86:87], v[46:47]
	v_pk_add_f32 v[46:47], v[46:47], v[86:87] neg_lo:[0,1] neg_hi:[0,1]
	v_mul_f32_e32 v40, 0.5, v48
	v_mov_b32_e32 v48, v46
	v_pk_mov_b32 v[54:55], v[68:69], v[72:73] op_sel:[1,0]
	v_pk_mul_f32 v[48:49], v[48:49], s[74:75] op_sel:[1,1] op_sel_hi:[0,0]
	v_pk_mul_f32 v[56:57], v[54:55], v[48:49]
	v_pk_mul_f32 v[48:49], v[48:49], v[54:55] op_sel:[1,0] op_sel_hi:[0,1]
	v_sub_f32_e32 v42, v48, v49
	v_fma_mixlo_f16 v54, v47, s75, v42
	v_fma_f32 v42, v47, 0.5, -v42
	v_pk_add_f32 v[46:47], v[56:57], v[56:57] op_sel:[0,1] op_sel_hi:[0,1]
	v_pk_add_f32 v[48:49], v[40:41], v[46:47]
	v_pk_add_f32 v[46:47], v[40:41], v[46:47] op_sel_hi:[0,1] neg_lo:[0,1] neg_hi:[0,1]
	v_cvt_pk_f16_f32 v56, v48, v47
	v_pk_add_f32 v[46:47], v[52:53], v[90:91]
	v_pk_add_f32 v[48:49], v[52:53], v[90:91] neg_lo:[0,1] neg_hi:[0,1]
	v_mov_b32_e32 v52, v46
	v_mov_b32_e32 v53, v49
	v_mov_b32_e32 v49, v47
	v_pk_mul_f32 v[46:47], v[48:49], s[74:75]
	v_fma_f32 v40, v71, s40, -v60
	v_pk_mul_f32 v[48:49], v[68:69], v[46:47] op_sel:[1,0]
	v_lshlrev_b32_e32 v57, 16, v54
	v_pk_fma_f32 v[54:55], v[40:41], v[46:47], v[48:49] op_sel:[0,1,0] op_sel_hi:[0,0,1] neg_hi:[0,0,1]
	s_nop 0
	s_nop 0
	v_pk_fma_f32 v[46:47], v[52:53], 0.5, v[54:55] op_sel_hi:[1,0,1]
	v_cvt_f16_f32_sdwa v42, -v42 dst_sel:WORD_1 dst_unused:UNUSED_PAD src0_sel:DWORD
	v_cvt_f16_f32_e32 v40, v46
	v_cvt_f16_f32_sdwa v48, v47 dst_sel:WORD_1 dst_unused:UNUSED_PAD src0_sel:DWORD
	v_or_b32_sdwa v46, v57, v56 dst_sel:DWORD dst_unused:UNUSED_PAD src0_sel:DWORD src1_sel:WORD_0
	v_or_b32_sdwa v47, v42, v56 dst_sel:DWORD dst_unused:UNUSED_PAD src0_sel:DWORD src1_sel:WORD_1
	v_pk_fma_f32 v[116:117], v[52:53], 0.5, v[54:55] op_sel_hi:[1,0,1] neg_lo:[0,0,1] neg_hi:[0,0,1]
	v_or_b32_e32 v114, v48, v40
	global_store_dwordx2 v[50:51], v[46:47], off
.LBB0_277:
	s_andn2_saveexec_b64 s[10:11], s[10:11]
	s_cbranch_execz .LBB0_270
	v_pk_add_f32 v[114:115], v[90:91], v[118:119]
	v_pk_add_f32 v[90:91], v[90:91], v[118:119] neg_lo:[0,1] neg_hi:[0,1]
	v_mul_f32_e32 v42, 0.5, v114
	v_pk_fma_f32 v[116:117], v[70:71], 0, v[70:71] op_sel:[0,0,1] op_sel_hi:[1,0,0] neg_lo:[1,0,0]
	v_mov_b32_e32 v114, v90
	v_pk_mul_f32 v[114:115], v[114:115], s[74:75]
	s_mov_b32 s78, s63
	v_pk_mul_f32 v[118:119], v[116:117], v[114:115] op_sel:[0,1] op_sel_hi:[1,0]
	v_pk_mul_f32 v[114:115], v[116:117], v[114:115]
	s_mov_b32 s79, s50
	v_sub_f32_e32 v90, v114, v115
	v_fma_mixlo_f16 v97, v91, s75, v90
	v_fma_f32 v90, v91, 0.5, -v90
	v_cvt_f16_f32_sdwa v105, -v90 dst_sel:WORD_1 dst_unused:UNUSED_PAD src0_sel:DWORD
	v_pk_add_f32 v[90:91], v[118:119], v[118:119] op_sel:[0,1] op_sel_hi:[0,1]
	s_waitcnt vmcnt(0)
	v_pk_add_f32 v[114:115], v[42:43], v[90:91]
	v_pk_add_f32 v[90:91], v[42:43], v[90:91] op_sel_hi:[0,1] neg_lo:[0,1] neg_hi:[0,1]
	v_cvt_pk_f16_f32 v42, v114, v91
	v_lshlrev_b32_e32 v90, 16, v97
	v_or_b32_sdwa v91, v105, v42 dst_sel:DWORD dst_unused:UNUSED_PAD src0_sel:DWORD src1_sel:WORD_1
	v_or_b32_sdwa v90, v90, v42 dst_sel:DWORD dst_unused:UNUSED_PAD src0_sel:DWORD src1_sel:WORD_0
	global_store_dwordx2 v[44:45], v[90:91], off
	v_pk_add_f32 v[90:91], v[86:87], v[112:113]
	v_pk_add_f32 v[86:87], v[86:87], v[112:113] neg_lo:[0,1] neg_hi:[0,1]
	v_mul_f32_e32 v42, 0.5, v90
	v_mov_b32_e32 v90, v71
	v_mov_b32_e32 v112, v71
	v_mov_b32_e32 v113, v70
	v_pk_fma_f32 v[114:115], v[70:71], 0, v[112:113] op_sel_hi:[1,0,1] neg_lo:[0,0,1] neg_hi:[0,0,1]
	v_pk_fma_f32 v[116:117], v[70:71], 0, v[90:91] op_sel_hi:[1,0,1]
	v_mov_b32_e32 v90, v86
	v_pk_mov_b32 v[114:115], v[114:115], v[116:117] op_sel:[1,0]
	v_pk_mul_f32 v[90:91], v[90:91], s[74:75]
	s_mov_b32 s51, s63
	v_pk_mul_f32 v[116:117], v[114:115], v[90:91] op_sel:[0,1] op_sel_hi:[1,0]
	v_pk_mul_f32 v[90:91], v[114:115], v[90:91]
	v_pk_add_f32 v[114:115], v[80:81], v[110:111]
	v_sub_f32_e32 v86, v90, v91
	v_fma_mixlo_f16 v97, v87, s75, v86
	v_fma_f32 v86, v87, 0.5, -v86
	v_cvt_f16_f32_sdwa v105, -v86 dst_sel:WORD_1 dst_unused:UNUSED_PAD src0_sel:DWORD
	v_pk_add_f32 v[86:87], v[116:117], v[116:117] op_sel:[0,1] op_sel_hi:[0,1]
	v_pk_add_f32 v[90:91], v[42:43], v[86:87]
	v_pk_add_f32 v[86:87], v[42:43], v[86:87] op_sel_hi:[0,1] neg_lo:[0,1] neg_hi:[0,1]
	v_cvt_pk_f16_f32 v42, v90, v87
	v_lshlrev_b32_e32 v86, 16, v97
	v_add_co_u32_e32 v90, vcc, s31, v44
	v_or_b32_sdwa v87, v105, v42 dst_sel:DWORD dst_unused:UNUSED_PAD src0_sel:DWORD src1_sel:WORD_1
	v_or_b32_sdwa v86, v86, v42 dst_sel:DWORD dst_unused:UNUSED_PAD src0_sel:DWORD src1_sel:WORD_0
	v_addc_co_u32_e32 v91, vcc, 0, v45, vcc
	global_store_dwordx2 v[90:91], v[86:87], off offset:-4096
	v_pk_mul_f32 v[86:87], v[112:113], s[68:69]
	v_pk_add_f32 v[80:81], v[80:81], v[110:111] neg_lo:[0,1] neg_hi:[0,1]
	v_mul_f32_e32 v42, 0.5, v114
	v_pk_add_f32 v[110:111], v[40:41], v[86:87] op_sel:[0,1] op_sel_hi:[0,1] neg_lo:[0,1] neg_hi:[0,1]
	v_pk_fma_f32 v[116:117], v[112:113], s[68:69], v[40:41] op_sel_hi:[1,1,0]
	v_mov_b32_e32 v114, v80
	v_mov_b32_e32 v111, v117
	v_pk_mul_f32 v[114:115], v[114:115], s[74:75]
	v_mov_b32_e32 v105, v78
	v_pk_mul_f32 v[116:117], v[110:111], v[114:115] op_sel:[0,1] op_sel_hi:[1,0]
	v_pk_mul_f32 v[114:115], v[110:111], v[114:115]
	s_mov_b32 s45, s41
	v_sub_f32_e32 v40, v114, v115
	v_fma_mixlo_f16 v97, v81, s75, v40
	v_fma_f32 v40, v81, 0.5, -v40
	v_cvt_f16_f32_sdwa v40, -v40 dst_sel:WORD_1 dst_unused:UNUSED_PAD src0_sel:DWORD
	v_pk_add_f32 v[80:81], v[116:117], v[116:117] op_sel:[0,1] op_sel_hi:[0,1]
	v_pk_add_f32 v[114:115], v[42:43], v[80:81]
	v_pk_add_f32 v[80:81], v[42:43], v[80:81] op_sel_hi:[0,1] neg_lo:[0,1] neg_hi:[0,1]
	v_cvt_pk_f16_f32 v42, v114, v81
	v_lshlrev_b32_e32 v80, 16, v97
	v_or_b32_sdwa v81, v40, v42 dst_sel:DWORD dst_unused:UNUSED_PAD src0_sel:DWORD src1_sel:WORD_1
	v_or_b32_sdwa v80, v80, v42 dst_sel:DWORD dst_unused:UNUSED_PAD src0_sel:DWORD src1_sel:WORD_0
	global_store_dwordx2 v[90:91], v[80:81], off
	v_pk_fma_f32 v[80:81], v[112:113], s[68:69], v[86:87] op_sel:[0,0,1] op_sel_hi:[1,1,0] neg_lo:[0,0,1] neg_hi:[0,0,1]
	v_pk_add_f32 v[86:87], v[84:85], v[108:109]
	v_pk_add_f32 v[84:85], v[84:85], v[108:109] neg_lo:[0,1] neg_hi:[0,1]
	v_mul_f32_e32 v40, 0.5, v86
	v_mov_b32_e32 v86, v84
	v_pk_mul_f32 v[86:87], v[86:87], s[74:75]
	v_mov_b32_e32 v81, v110
	v_mov_b32_e32 v111, v80
	v_pk_mul_f32 v[80:81], v[80:81], v[86:87]
	v_pk_mul_f32 v[90:91], v[110:111], v[86:87]
	v_sub_f32_e32 v42, v80, v81
	v_fma_mixlo_f16 v86, v85, s75, v42
	v_fma_f32 v42, v85, 0.5, -v42
	v_cvt_f16_f32_sdwa v42, -v42 dst_sel:WORD_1 dst_unused:UNUSED_PAD src0_sel:DWORD
	v_pk_add_f32 v[80:81], v[90:91], v[90:91] op_sel:[1,0] op_sel_hi:[1,0]
	s_mov_b32 s80, s41
	v_pk_add_f32 v[84:85], v[40:41], v[80:81]
	v_pk_add_f32 v[80:81], v[40:41], v[80:81] op_sel_hi:[0,1] neg_lo:[0,1] neg_hi:[0,1]
	v_cvt_pk_f16_f32 v40, v84, v81
	v_lshlrev_b32_e32 v80, 16, v86
	v_add_co_u32_e32 v84, vcc, s30, v44
	v_or_b32_sdwa v81, v42, v40 dst_sel:DWORD dst_unused:UNUSED_PAD src0_sel:DWORD src1_sel:WORD_1
	v_or_b32_sdwa v80, v80, v40 dst_sel:DWORD dst_unused:UNUSED_PAD src0_sel:DWORD src1_sel:WORD_0
	v_addc_co_u32_e32 v85, vcc, 0, v45, vcc
	global_store_dwordx2 v[84:85], v[80:81], off offset:-4096
	v_mov_b32_e32 v40, v71
	v_pk_mul_f32 v[70:71], v[70:71], s[78:79] op_sel_hi:[0,1]
	v_pk_add_f32 v[80:81], v[76:77], v[106:107]
	v_pk_add_f32 v[76:77], v[76:77], v[106:107] neg_lo:[0,1] neg_hi:[0,1]
	v_mul_f32_e32 v42, 0.5, v80
	v_pk_fma_f32 v[86:87], v[40:41], s[50:51], v[70:71] op_sel_hi:[0,1,1] neg_lo:[0,0,1] neg_hi:[0,0,1]
	v_pk_fma_f32 v[90:91], v[40:41], s[50:51], v[70:71] op_sel_hi:[0,1,1]
	v_mov_b32_e32 v80, v76
	v_mov_b32_e32 v106, v86
	v_mov_b32_e32 v107, v91
	v_pk_mul_f32 v[80:81], v[80:81], s[74:75]
	s_mov_b32 s81, s44
	v_pk_mul_f32 v[108:109], v[106:107], v[80:81] op_sel:[0,1] op_sel_hi:[1,0]
	v_pk_mul_f32 v[80:81], v[106:107], v[80:81]
	s_mov_b32 s65, s67
	v_sub_f32_e32 v40, v80, v81
	v_fma_mixlo_f16 v97, v77, s75, v40
	v_fma_f32 v40, v77, 0.5, -v40
	v_cvt_f16_f32_sdwa v40, -v40 dst_sel:WORD_1 dst_unused:UNUSED_PAD src0_sel:DWORD
	v_pk_add_f32 v[76:77], v[108:109], v[108:109] op_sel:[0,1] op_sel_hi:[0,1]
	v_pk_add_f32 v[80:81], v[42:43], v[76:77]
	v_pk_add_f32 v[76:77], v[42:43], v[76:77] op_sel_hi:[0,1] neg_lo:[0,1] neg_hi:[0,1]
	v_cvt_pk_f16_f32 v42, v80, v77
	v_lshlrev_b32_e32 v76, 16, v97
	v_or_b32_sdwa v77, v40, v42 dst_sel:DWORD dst_unused:UNUSED_PAD src0_sel:DWORD src1_sel:WORD_1
	v_or_b32_sdwa v76, v76, v42 dst_sel:DWORD dst_unused:UNUSED_PAD src0_sel:DWORD src1_sel:WORD_0
	global_store_dwordx2 v[84:85], v[76:77], off
	v_pk_add_f32 v[76:77], v[78:79], v[102:103]
	v_sub_f32_e32 v97, v79, v103
	v_pk_mov_b32 v[78:79], v[70:71], v[102:103] op_sel:[1,0]
	v_mul_f32_e32 v40, 0.5, v77
	v_pk_add_f32 v[78:79], v[104:105], v[78:79] neg_lo:[0,1] neg_hi:[0,1]
	v_mul_f32_e32 v42, 0.5, v76
	v_pk_mul_f32 v[80:81], v[78:79], v[40:41]
	s_mov_b32 s82, s69
	v_mul_f32_e32 v71, v78, v81
	v_fma_f32 v40, -v86, v40, v71
	v_fma_mixlo_f16 v71, v97, s75, v40
	v_fma_f32 v40, v97, 0.5, -v40
	v_cvt_f16_f32_sdwa v40, -v40 dst_sel:WORD_1 dst_unused:UNUSED_PAD src0_sel:DWORD
	v_pk_fma_f32 v[84:85], v[86:87], v[80:81], v[80:81] op_sel:[0,1,0] op_sel_hi:[1,0,1]
	v_lshlrev_b32_e32 v71, 16, v71
	v_pk_add_f32 v[78:79], v[42:43], v[84:85]
	v_fma_f32 v42, v76, 0.5, -v84
	v_cvt_pk_f16_f32 v42, v78, v42
	v_add_co_u32_e32 v78, vcc, s33, v44
	v_or_b32_sdwa v77, v40, v42 dst_sel:DWORD dst_unused:UNUSED_PAD src0_sel:DWORD src1_sel:WORD_1
	v_or_b32_sdwa v76, v71, v42 dst_sel:DWORD dst_unused:UNUSED_PAD src0_sel:DWORD src1_sel:WORD_0
	v_addc_co_u32_e32 v79, vcc, 0, v45, vcc
	global_store_dwordx2 v[78:79], v[76:77], off offset:-4096
	v_pk_add_f32 v[76:77], v[100:101], v[82:83]
	v_pk_add_f32 v[80:81], v[82:83], v[100:101] neg_lo:[0,1] neg_hi:[0,1]
	v_mul_f32_e32 v40, 0.5, v76
	v_mov_b32_e32 v76, v80
	v_pk_mov_b32 v[82:83], v[86:87], v[90:91] op_sel:[1,0]
	v_pk_mul_f32 v[76:77], v[76:77], s[74:75]
	v_mov_b32_e32 v97, v88
	v_pk_mul_f32 v[84:85], v[82:83], v[76:77] op_sel:[0,1] op_sel_hi:[1,0]
	v_pk_mul_f32 v[76:77], v[82:83], v[76:77]
	s_nop 0
	v_sub_f32_e32 v42, v76, v77
	v_fma_mixlo_f16 v71, v81, s75, v42
	v_fma_f32 v42, v81, 0.5, -v42
	v_cvt_f16_f32_sdwa v42, -v42 dst_sel:WORD_1 dst_unused:UNUSED_PAD src0_sel:DWORD
	v_pk_add_f32 v[76:77], v[84:85], v[84:85] op_sel:[0,1] op_sel_hi:[0,1]
	v_pk_add_f32 v[80:81], v[40:41], v[76:77]
	v_pk_add_f32 v[76:77], v[40:41], v[76:77] op_sel_hi:[0,1] neg_lo:[0,1] neg_hi:[0,1]
	v_cvt_pk_f16_f32 v40, v80, v77
	v_lshlrev_b32_e32 v71, 16, v71
	v_or_b32_sdwa v77, v42, v40 dst_sel:DWORD dst_unused:UNUSED_PAD src0_sel:DWORD src1_sel:WORD_1
	v_or_b32_sdwa v76, v71, v40 dst_sel:DWORD dst_unused:UNUSED_PAD src0_sel:DWORD src1_sel:WORD_0
	global_store_dwordx2 v[78:79], v[76:77], off
	v_pk_add_f32 v[76:77], v[92:93], v[88:89]
	v_mov_b32_e32 v71, v92
	v_mul_f32_e32 v40, 0.5, v77
	v_pk_add_f32 v[70:71], v[96:97], v[70:71] neg_lo:[0,1] neg_hi:[0,1]
	v_sub_f32_e32 v84, v89, v93
	v_pk_mul_f32 v[78:79], v[70:71], v[40:41]
	v_mul_f32_e32 v42, 0.5, v76
	v_mul_f32_e32 v70, v70, v79
	v_fma_f32 v40, -v87, v40, v70
	v_fma_mixlo_f16 v77, v84, s75, v40
	v_fma_f32 v40, v84, 0.5, -v40
	v_cvt_f16_f32_sdwa v40, -v40 dst_sel:WORD_1 dst_unused:UNUSED_PAD src0_sel:DWORD
	v_pk_fma_f32 v[80:81], v[82:83], v[78:79], v[78:79] op_sel:[0,1,0] op_sel_hi:[1,0,1]
	s_nop 0
	v_pk_add_f32 v[70:71], v[42:43], v[80:81]
	v_fma_f32 v42, v76, 0.5, -v80
	v_cvt_pk_f16_f32 v42, v70, v42
	v_lshlrev_b32_e32 v70, 16, v77
	v_or_b32_sdwa v71, v40, v42 dst_sel:DWORD dst_unused:UNUSED_PAD src0_sel:DWORD src1_sel:WORD_1
	v_sub_f32_e32 v40, v98, v99
	v_or_b32_sdwa v70, v70, v42 dst_sel:DWORD dst_unused:UNUSED_PAD src0_sel:DWORD src1_sel:WORD_0
	v_add_co_u32_e32 v76, vcc, s34, v44
	v_cvt_f16_f32_sdwa v42, -v95 dst_sel:WORD_1 dst_unused:UNUSED_PAD src0_sel:DWORD
	v_cvt_f16_f32_sdwa v40, v40 dst_sel:WORD_1 dst_unused:UNUSED_PAD src0_sel:DWORD
	v_addc_co_u32_e32 v77, vcc, 0, v45, vcc
	global_store_dwordx2 v[76:77], v[70:71], off offset:-4096
	v_pk_add_f32 v[70:71], v[98:99], v[98:99] op_sel:[0,1] op_sel_hi:[1,0]
	s_nop 0
	v_cvt_pk_f16_f32 v70, v70, v94
	v_or_b32_sdwa v71, v42, v70 dst_sel:DWORD dst_unused:UNUSED_PAD src0_sel:DWORD src1_sel:WORD_1
	v_or_b32_sdwa v70, v40, v70 dst_sel:DWORD dst_unused:UNUSED_PAD src0_sel:DWORD src1_sel:WORD_0
	global_store_dwordx2 v[76:77], v[70:71], off
	v_pk_add_f32 v[70:71], v[64:65], v[52:53]
	v_pk_add_f32 v[52:53], v[64:65], v[52:53] neg_lo:[0,1] neg_hi:[0,1]
	v_mul_f32_e32 v40, 0.5, v70
	v_mov_b32_e32 v70, v52
	v_pk_mul_f32 v[64:65], v[70:71], s[74:75] op_sel:[1,1] op_sel_hi:[0,0]
	v_pk_mul_f32 v[70:71], v[64:65], s[44:45] op_sel:[1,0] op_sel_hi:[0,1]
	v_pk_mul_f32 v[64:65], v[64:65], s[80:81] op_sel:[1,0] op_sel_hi:[0,1]
	s_mov_b32 s80, s67
	v_sub_f32_e32 v42, v64, v65
	v_fma_mixlo_f16 v76, v53, s75, v42
	v_fma_f32 v42, v53, 0.5, -v42
	v_cvt_f16_f32_sdwa v42, -v42 dst_sel:WORD_1 dst_unused:UNUSED_PAD src0_sel:DWORD
	v_pk_add_f32 v[52:53], v[70:71], v[70:71] op_sel:[1,0] op_sel_hi:[1,0]
	s_mov_b32 s81, s64
	v_pk_add_f32 v[64:65], v[40:41], v[52:53]
	v_pk_add_f32 v[52:53], v[40:41], v[52:53] op_sel_hi:[0,1] neg_lo:[0,1] neg_hi:[0,1]
	v_cvt_pk_f16_f32 v40, v64, v53
	v_lshlrev_b32_e32 v52, 16, v76
	v_add_co_u32_e32 v64, vcc, s35, v44
	v_or_b32_sdwa v53, v42, v40 dst_sel:DWORD dst_unused:UNUSED_PAD src0_sel:DWORD src1_sel:WORD_1
	v_or_b32_sdwa v52, v52, v40 dst_sel:DWORD dst_unused:UNUSED_PAD src0_sel:DWORD src1_sel:WORD_0
	v_addc_co_u32_e32 v65, vcc, 0, v45, vcc
	global_store_dwordx2 v[64:65], v[52:53], off offset:-4096
	v_pk_add_f32 v[52:53], v[72:73], v[66:67]
	v_pk_add_f32 v[66:67], v[72:73], v[66:67] neg_lo:[0,1] neg_hi:[0,1]
	v_mul_f32_e32 v40, 0.5, v52
	v_mov_b32_e32 v52, v66
	v_pk_mul_f32 v[52:53], v[52:53], s[74:75] op_sel:[1,1] op_sel_hi:[0,0]
	v_pk_mul_f32 v[70:71], v[52:53], s[78:79] op_sel:[1,0] op_sel_hi:[0,1]
	v_pk_mul_f32 v[52:53], v[52:53], s[50:51] op_sel:[1,0] op_sel_hi:[0,1]
	s_nop 0
	v_sub_f32_e32 v42, v52, v53
	v_fma_mixlo_f16 v72, v67, s75, v42
	v_fma_f32 v42, v67, 0.5, -v42
	v_cvt_f16_f32_sdwa v42, -v42 dst_sel:WORD_1 dst_unused:UNUSED_PAD src0_sel:DWORD
	v_pk_add_f32 v[52:53], v[70:71], v[70:71] op_sel:[1,0] op_sel_hi:[1,0]
	s_nop 0
	v_pk_add_f32 v[66:67], v[40:41], v[52:53]
	v_pk_add_f32 v[52:53], v[40:41], v[52:53] op_sel_hi:[0,1] neg_lo:[0,1] neg_hi:[0,1]
	v_cvt_pk_f16_f32 v40, v66, v53
	v_lshlrev_b32_e32 v52, 16, v72
	v_or_b32_sdwa v53, v42, v40 dst_sel:DWORD dst_unused:UNUSED_PAD src0_sel:DWORD src1_sel:WORD_1
	v_or_b32_sdwa v52, v52, v40 dst_sel:DWORD dst_unused:UNUSED_PAD src0_sel:DWORD src1_sel:WORD_0
	global_store_dwordx2 v[64:65], v[52:53], off
	v_pk_add_f32 v[52:53], v[54:55], v[58:59]
	v_pk_add_f32 v[54:55], v[54:55], v[58:59] neg_lo:[0,1] neg_hi:[0,1]
	v_mul_f32_e32 v40, 0.5, v52
	v_mov_b32_e32 v52, v54
	v_pk_mul_f32 v[52:53], v[52:53], s[74:75] op_sel:[1,1] op_sel_hi:[0,0]
	v_pk_mul_f32 v[58:59], v[52:53], s[80:81] op_sel:[1,0] op_sel_hi:[0,1]
	v_pk_mul_f32 v[52:53], v[52:53], s[64:65] op_sel:[1,0] op_sel_hi:[0,1]
	s_nop 0
	v_sub_f32_e32 v42, v52, v53
	v_fma_mixlo_f16 v64, v55, s75, v42
	v_fma_f32 v42, v55, 0.5, -v42
	v_cvt_f16_f32_sdwa v42, -v42 dst_sel:WORD_1 dst_unused:UNUSED_PAD src0_sel:DWORD
	v_pk_add_f32 v[52:53], v[58:59], v[58:59] op_sel:[1,0] op_sel_hi:[1,0]
	v_pk_add_f32 v[58:59], v[74:75], v[68:69] neg_lo:[0,1] neg_hi:[0,1]
	v_pk_add_f32 v[54:55], v[40:41], v[52:53]
	v_pk_add_f32 v[52:53], v[40:41], v[52:53] op_sel_hi:[0,1] neg_lo:[0,1] neg_hi:[0,1]
	v_cvt_pk_f16_f32 v40, v54, v53
	v_lshlrev_b32_e32 v52, 16, v64
	v_add_co_u32_e32 v54, vcc, s39, v44
	v_or_b32_sdwa v53, v42, v40 dst_sel:DWORD dst_unused:UNUSED_PAD src0_sel:DWORD src1_sel:WORD_1
	v_or_b32_sdwa v52, v52, v40 dst_sel:DWORD dst_unused:UNUSED_PAD src0_sel:DWORD src1_sel:WORD_0
	v_addc_co_u32_e32 v55, vcc, 0, v45, vcc
	global_store_dwordx2 v[54:55], v[52:53], off offset:-4096
	v_pk_add_f32 v[52:53], v[74:75], v[68:69]
	s_nop 0
	v_mul_f32_e32 v40, 0.5, v52
	v_mov_b32_e32 v52, v58
	v_pk_mul_f32 v[52:53], v[52:53], s[74:75] op_sel:[1,1] op_sel_hi:[0,0]
	v_pk_mul_f32 v[52:53], s[82:83], v[52:53] op_sel:[0,1] op_sel_hi:[0,0]
	v_sub_f32_e32 v42, v52, v53
	v_fma_mixlo_f16 v64, v59, s75, v42
	v_fma_f32 v42, v59, 0.5, -v42
	v_cvt_f16_f32_sdwa v42, -v42 dst_sel:WORD_1 dst_unused:UNUSED_PAD src0_sel:DWORD
	v_pk_add_f32 v[52:53], v[52:53], v[52:53] op_sel:[1,0] op_sel_hi:[1,0]
	s_nop 0
	v_pk_add_f32 v[58:59], v[40:41], v[52:53]
	v_pk_add_f32 v[52:53], v[40:41], v[52:53] op_sel_hi:[0,1] neg_lo:[0,1] neg_hi:[0,1]
	v_cvt_pk_f16_f32 v40, v58, v53
	v_lshlrev_b32_e32 v52, 16, v64
	v_or_b32_sdwa v53, v42, v40 dst_sel:DWORD dst_unused:UNUSED_PAD src0_sel:DWORD src1_sel:WORD_1
	v_or_b32_sdwa v52, v52, v40 dst_sel:DWORD dst_unused:UNUSED_PAD src0_sel:DWORD src1_sel:WORD_0
	global_store_dwordx2 v[54:55], v[52:53], off
	v_pk_add_f32 v[52:53], v[56:57], v[48:49]
	v_pk_add_f32 v[48:49], v[56:57], v[48:49] neg_lo:[0,1] neg_hi:[0,1]
	v_mul_f32_e32 v40, 0.5, v52
	v_mov_b32_e32 v52, v48
	v_pk_mul_f32 v[52:53], v[52:53], s[74:75] op_sel:[1,1] op_sel_hi:[0,0]
	v_pk_mul_f32 v[54:55], v[52:53], s[64:65] op_sel:[1,0] op_sel_hi:[0,1]
	v_pk_mul_f32 v[52:53], v[52:53], s[80:81] op_sel:[1,0] op_sel_hi:[0,1]
	s_nop 0
	v_sub_f32_e32 v42, v52, v53
	v_fma_mixlo_f16 v56, v49, s75, v42
	v_fma_f32 v42, v49, 0.5, -v42
	v_cvt_f16_f32_sdwa v42, -v42 dst_sel:WORD_1 dst_unused:UNUSED_PAD src0_sel:DWORD
	v_pk_add_f32 v[48:49], v[54:55], v[54:55] op_sel:[1,0] op_sel_hi:[1,0]
	v_pk_add_f32 v[54:55], v[60:61], v[62:63] neg_lo:[0,1] neg_hi:[0,1]
	v_pk_add_f32 v[52:53], v[40:41], v[48:49]
	v_pk_add_f32 v[48:49], v[40:41], v[48:49] op_sel_hi:[0,1] neg_lo:[0,1] neg_hi:[0,1]
	v_cvt_pk_f16_f32 v40, v52, v49
	v_lshlrev_b32_e32 v48, 16, v56
	v_add_co_u32_e32 v52, vcc, s43, v44
	v_or_b32_sdwa v49, v42, v40 dst_sel:DWORD dst_unused:UNUSED_PAD src0_sel:DWORD src1_sel:WORD_1
	v_or_b32_sdwa v48, v48, v40 dst_sel:DWORD dst_unused:UNUSED_PAD src0_sel:DWORD src1_sel:WORD_0
	v_addc_co_u32_e32 v53, vcc, 0, v45, vcc
	global_store_dwordx2 v[52:53], v[48:49], off offset:-4096
	v_pk_add_f32 v[48:49], v[62:63], v[60:61]
	s_nop 0
	v_mul_f32_e32 v40, 0.5, v48
	v_mov_b32_e32 v48, v54
	v_pk_mul_f32 v[48:49], v[48:49], s[74:75] op_sel:[1,1] op_sel_hi:[0,0]
	v_pk_mul_f32 v[56:57], v[48:49], s[50:51] op_sel:[1,0] op_sel_hi:[0,1]
	v_pk_mul_f32 v[48:49], v[48:49], s[78:79] op_sel:[1,0] op_sel_hi:[0,1]
	s_mov_b32 s78, s41
	v_sub_f32_e32 v42, v48, v49
	v_pk_add_f32 v[48:49], v[56:57], v[56:57] op_sel:[1,0] op_sel_hi:[1,0]
	v_fma_mixlo_f16 v58, v55, s75, v42
	v_fma_f32 v42, v55, 0.5, -v42
	v_pk_add_f32 v[54:55], v[40:41], v[48:49]
	v_pk_add_f32 v[48:49], v[40:41], v[48:49] op_sel_hi:[0,1] neg_lo:[0,1] neg_hi:[0,1]
	v_cvt_pk_f16_f32 v40, v54, v49
	v_pk_add_f32 v[48:49], v[46:47], v[50:51]
	v_pk_add_f32 v[46:47], v[46:47], v[50:51] neg_lo:[0,1] neg_hi:[0,1]
	v_mov_b32_e32 v50, v48
	v_mov_b32_e32 v51, v47
	v_mov_b32_e32 v47, v49
	v_pk_mul_f32 v[46:47], v[46:47], s[74:75]
	v_cvt_f16_f32_sdwa v42, -v42 dst_sel:WORD_1 dst_unused:UNUSED_PAD src0_sel:DWORD
	v_pk_mul_f32 v[48:49], v[46:47], s[44:45] op_sel_hi:[1,0]
	v_lshlrev_b32_e32 v56, 16, v58
	v_pk_fma_f32 v[54:55], v[46:47], s[78:79], v[48:49] op_sel:[0,0,1] op_sel_hi:[1,0,0] neg_hi:[1,0,0]
	s_nop 0
	s_nop 0
	s_nop 0
	v_pk_fma_f32 v[46:47], v[50:51], 0.5, v[54:55] op_sel_hi:[1,0,1]
	v_pk_fma_f32 v[116:117], v[50:51], 0.5, v[54:55] op_sel_hi:[1,0,1] neg_lo:[0,0,1] neg_hi:[0,0,1]
	v_cvt_f16_f32_e32 v48, v46
	v_cvt_f16_f32_sdwa v49, v47 dst_sel:WORD_1 dst_unused:UNUSED_PAD src0_sel:DWORD
	v_or_b32_sdwa v47, v42, v40 dst_sel:DWORD dst_unused:UNUSED_PAD src0_sel:DWORD src1_sel:WORD_1
	v_or_b32_sdwa v46, v56, v40 dst_sel:DWORD dst_unused:UNUSED_PAD src0_sel:DWORD src1_sel:WORD_0
	global_store_dwordx2 v[52:53], v[46:47], off
	v_or_b32_e32 v114, v49, v48
	s_branch .LBB0_270

.LBB0_428:
	s_ashr_i32 s17, s16, 31
	s_lshl_b64 s[6:7], s[16:17], 2
	s_add_u32 s6, s48, s6
	s_addc_u32 s7, s49, s7
	global_load_dwordx2 v[40:41], v151, s[6:7]
	s_waitcnt vmcnt(0)
	v_cvt_f32_f16_e32 v36, v10
	v_cvt_f32_f16_sdwa v42, v10 dst_sel:DWORD dst_unused:UNUSED_PAD src0_sel:WORD_1
	v_cvt_f32_f16_e32 v43, v11
	v_cvt_f32_f16_e32 v45, v12
	v_cvt_f32_f16_sdwa v46, v12 dst_sel:DWORD dst_unused:UNUSED_PAD src0_sel:WORD_1
	v_cvt_f32_f16_e32 v47, v13
	v_cvt_f32_f16_sdwa v12, v13 dst_sel:DWORD dst_unused:UNUSED_PAD src0_sel:WORD_1
	v_cvt_f32_f16_e32 v13, v30
	v_cvt_f32_f16_sdwa v50, v26 dst_sel:DWORD dst_unused:UNUSED_PAD src0_sel:WORD_1
	v_cvt_f32_f16_e32 v51, v27
	v_cvt_f32_f16_sdwa v44, v11 dst_sel:DWORD dst_unused:UNUSED_PAD src0_sel:WORD_1
	v_cvt_f32_f16_sdwa v48, v30 dst_sel:DWORD dst_unused:UNUSED_PAD src0_sel:WORD_1
	v_cvt_f32_f16_e32 v49, v31
	v_cvt_f32_f16_sdwa v30, v31 dst_sel:DWORD dst_unused:UNUSED_PAD src0_sel:WORD_1
	v_cvt_f32_f16_e32 v31, v32
	v_cvt_f32_f16_sdwa v11, v33 dst_sel:DWORD dst_unused:UNUSED_PAD src0_sel:WORD_1
	v_cvt_f32_f16_sdwa v32, v32 dst_sel:DWORD dst_unused:UNUSED_PAD src0_sel:WORD_1
	v_cvt_f32_f16_e32 v33, v33
	v_cvt_f32_f16_sdwa v26, v27 dst_sel:DWORD dst_unused:UNUSED_PAD src0_sel:WORD_1
	v_cvt_f32_f16_e32 v27, v28
	v_cvt_f32_f16_sdwa v52, v28 dst_sel:DWORD dst_unused:UNUSED_PAD src0_sel:WORD_1
	v_cvt_f32_f16_e32 v53, v29
	v_cvt_f32_f16_e32 v28, v22
	v_cvt_f32_f16_sdwa v54, v22 dst_sel:DWORD dst_unused:UNUSED_PAD src0_sel:WORD_1
	v_cvt_f32_f16_e32 v55, v23
	v_cvt_f32_f16_sdwa v22, v23 dst_sel:DWORD dst_unused:UNUSED_PAD src0_sel:WORD_1
	v_cvt_f32_f16_e32 v23, v24
	v_cvt_f32_f16_sdwa v56, v24 dst_sel:DWORD dst_unused:UNUSED_PAD src0_sel:WORD_1
	v_cvt_f32_f16_e32 v57, v25
	v_cvt_f32_f16_sdwa v29, v29 dst_sel:DWORD dst_unused:UNUSED_PAD src0_sel:WORD_1
	v_cvt_f32_f16_sdwa v25, v25 dst_sel:DWORD dst_unused:UNUSED_PAD src0_sel:WORD_1
	v_cvt_f32_f16_e32 v24, v38
	v_cvt_f32_f16_sdwa v60, v19 dst_sel:DWORD dst_unused:UNUSED_PAD src0_sel:WORD_1
	v_cvt_f32_f16_e32 v61, v20
	v_cvt_f32_f16_e32 v38, v18
	v_cvt_f32_f16_e32 v59, v19
	v_mul_f32_e32 v19, 0x3b800000, v36
	v_pk_mul_f32 v[42:43], v[42:43], s[24:25] op_sel_hi:[1,0]
	v_pk_mul_f32 v[12:13], v[12:13], s[24:25] op_sel_hi:[1,0]
	v_pk_mul_f32 v[50:51], v[50:51], s[24:25] op_sel_hi:[1,0]
	v_pk_mul_f32 v[44:45], v[44:45], s[24:25] op_sel_hi:[1,0]
	v_pk_mul_f32 v[46:47], v[46:47], s[24:25] op_sel_hi:[1,0]
	v_pk_mul_f32 v[48:49], v[48:49], s[24:25] op_sel_hi:[1,0]
	v_pk_mul_f32 v[30:31], v[30:31], s[24:25] op_sel_hi:[1,0]
	v_mul_f32_e32 v11, 0x3b800000, v11
	v_pk_mul_f32 v[32:33], v[32:33], s[24:25] op_sel_hi:[1,0]
	v_pk_mul_f32 v[26:27], v[26:27], s[24:25] op_sel_hi:[1,0]
	v_pk_mul_f32 v[52:53], v[52:53], s[24:25] op_sel_hi:[1,0]
	v_pk_mul_f32 v[54:55], v[54:55], s[24:25] op_sel_hi:[1,0]
	v_pk_mul_f32 v[22:23], v[22:23], s[24:25] op_sel_hi:[1,0]
	v_pk_mul_f32 v[56:57], v[56:57], s[24:25] op_sel_hi:[1,0]
	ds_write2_b32 v131, v42, v43 offset0:1 offset1:2
	ds_write2_b32 v131, v44, v45 offset0:3 offset1:4
	ds_write2_b32 v131, v46, v47 offset0:5 offset1:6
	ds_write2_b32 v131, v12, v13 offset0:7 offset1:8
	ds_write2_b32 v131, v48, v49 offset0:9 offset1:10
	ds_write2_b32 v131, v30, v31 offset0:11 offset1:12
	ds_write2_b32 v131, v32, v33 offset0:13 offset1:14
	v_pk_mov_b32 v[12:13], v[50:51], v[50:51] op_sel:[1,0]
	v_pk_mul_f32 v[28:29], v[28:29], s[24:25] op_sel_hi:[1,0]
	v_pk_mul_f32 v[24:25], v[24:25], s[24:25] op_sel_hi:[1,0]
	v_pk_mov_b32 v[26:27], v[26:27], v[26:27] op_sel:[1,0]
	v_pk_mov_b32 v[30:31], v[52:53], v[52:53] op_sel:[1,0]
	v_pk_mov_b32 v[32:33], v[54:55], v[54:55] op_sel:[1,0]
	v_pk_mov_b32 v[22:23], v[22:23], v[22:23] op_sel:[1,0]
	v_pk_mov_b32 v[42:43], v[56:57], v[56:57] op_sel:[1,0]
	v_cvt_f32_f16_sdwa v58, v18 dst_sel:DWORD dst_unused:UNUSED_PAD src0_sel:WORD_1
	v_mul_f32_e32 v36, 0x3b800000, v38
	s_mov_b32 s6, s65
	v_pk_mul_f32 v[58:59], v[58:59], s[24:25] op_sel_hi:[1,0]
	v_fma_mix_f32 v10, v10, s24, v40 op_sel_hi:[1,0,0]
	s_nop 0
	v_cndmask_b32_e64 v10, v19, v10, s[4:5]
	ds_write2_b32 v131, v10, v11 offset1:15
	ds_write_b64 v132, v[12:13] offset:32824
	ds_write_b64 v133, v[26:27] offset:32824
	ds_write_b64 v134, v[30:31] offset:32824
	ds_write_b64 v135, v[28:29] offset:32824
	ds_write_b64 v136, v[32:33] offset:32824
	ds_write_b64 v137, v[22:23] offset:32824
	ds_write_b64 v138, v[42:43] offset:32824
	ds_write_b64 v139, v[24:25] offset:32824
	v_cvt_f32_f16_sdwa v10, v20 dst_sel:DWORD dst_unused:UNUSED_PAD src0_sel:WORD_1
	v_cvt_f32_f16_e32 v11, v21
	v_pk_mul_f32 v[12:13], v[60:61], s[24:25] op_sel_hi:[1,0]
	v_fma_mix_f32 v18, v18, s24, v41 op_sel_hi:[1,0,0]
	ds_write2_b32 v140, v12, v13 offset0:3 offset1:4
	v_cvt_f32_f16_sdwa v12, v21 dst_sel:DWORD dst_unused:UNUSED_PAD src0_sel:WORD_1
	v_cvt_f32_f16_e32 v13, v14
	v_cndmask_b32_e64 v36, v36, v18, s[4:5]
	v_cvt_f32_f16_sdwa v18, v14 dst_sel:DWORD dst_unused:UNUSED_PAD src0_sel:WORD_1
	v_cvt_f32_f16_e32 v19, v15
	v_pk_mul_f32 v[10:11], v[10:11], s[24:25] op_sel_hi:[1,0]
	ds_write2_b32 v140, v10, v11 offset0:5 offset1:6
	v_pk_mul_f32 v[10:11], v[12:13], s[24:25] op_sel_hi:[1,0]
	ds_write2_b32 v140, v10, v11 offset0:7 offset1:8
	v_pk_mul_f32 v[10:11], v[18:19], s[24:25] op_sel_hi:[1,0]
	ds_write2_b32 v140, v10, v11 offset0:9 offset1:10
	v_cvt_f32_f16_sdwa v10, v15 dst_sel:DWORD dst_unused:UNUSED_PAD src0_sel:WORD_1
	v_cvt_f32_f16_e32 v11, v16
	v_cvt_f32_f16_sdwa v12, v16 dst_sel:DWORD dst_unused:UNUSED_PAD src0_sel:WORD_1
	v_cvt_f32_f16_e32 v13, v17
	v_cvt_f32_f16_sdwa v14, v17 dst_sel:DWORD dst_unused:UNUSED_PAD src0_sel:WORD_1
	v_pk_mul_f32 v[10:11], v[10:11], s[24:25] op_sel_hi:[1,0]
	ds_write2_b32 v140, v10, v11 offset0:11 offset1:12
	v_pk_mul_f32 v[10:11], v[12:13], s[24:25] op_sel_hi:[1,0]
	ds_write2_b32 v140, v10, v11 offset0:13 offset1:14
	v_cvt_f32_f16_sdwa v10, v6 dst_sel:DWORD dst_unused:UNUSED_PAD src0_sel:WORD_1
	v_cvt_f32_f16_e32 v11, v7
	v_cvt_f32_f16_sdwa v6, v7 dst_sel:DWORD dst_unused:UNUSED_PAD src0_sel:WORD_1
	v_cvt_f32_f16_e32 v7, v8
	v_mul_f32_e32 v14, 0x3b800000, v14
	v_pk_mul_f32 v[10:11], v[10:11], s[24:25] op_sel_hi:[1,0]
	ds_write2_b32 v140, v58, v59 offset0:1 offset1:2
	v_pk_mov_b32 v[10:11], v[10:11], v[10:11] op_sel:[1,0]
	ds_write2_b32 v140, v36, v14 offset1:15
	ds_write_b64 v141, v[10:11] offset:32824
	v_cvt_f32_f16_sdwa v10, v8 dst_sel:DWORD dst_unused:UNUSED_PAD src0_sel:WORD_1
	v_cvt_f32_f16_e32 v11, v9
	v_pk_mul_f32 v[6:7], v[6:7], s[24:25] op_sel_hi:[1,0]
	s_nop 0
	v_pk_mov_b32 v[6:7], v[6:7], v[6:7] op_sel:[1,0]
	ds_write_b64 v142, v[6:7] offset:32824
	v_cvt_f32_f16_sdwa v7, v9 dst_sel:DWORD dst_unused:UNUSED_PAD src0_sel:WORD_1
	v_pk_mul_f32 v[8:9], v[10:11], s[24:25] op_sel_hi:[1,0]
	v_cvt_f32_f16_e32 v6, v2
	v_pk_mov_b32 v[8:9], v[8:9], v[8:9] op_sel:[1,0]
	ds_write_b64 v143, v[8:9] offset:32824
	v_cvt_f32_f16_sdwa v8, v2 dst_sel:DWORD dst_unused:UNUSED_PAD src0_sel:WORD_1
	v_cvt_f32_f16_e32 v9, v3
	v_cvt_f32_f16_sdwa v2, v3 dst_sel:DWORD dst_unused:UNUSED_PAD src0_sel:WORD_1
	v_cvt_f32_f16_e32 v3, v4
	v_pk_mul_f32 v[6:7], v[6:7], s[24:25] op_sel_hi:[1,0]
	ds_write_b64 v144, v[6:7] offset:32824
	v_pk_mul_f32 v[6:7], v[8:9], s[24:25] op_sel_hi:[1,0]
	v_pk_mul_f32 v[2:3], v[2:3], s[24:25] op_sel_hi:[1,0]
	v_pk_mov_b32 v[6:7], v[6:7], v[6:7] op_sel:[1,0]
	ds_write_b64 v145, v[6:7] offset:32824
	v_pk_mov_b32 v[2:3], v[2:3], v[2:3] op_sel:[1,0]
	v_cvt_f32_f16_sdwa v6, v4 dst_sel:DWORD dst_unused:UNUSED_PAD src0_sel:WORD_1
	v_cvt_f32_f16_e32 v7, v5
	ds_write_b64 v148, v[2:3] offset:32824
	v_cvt_f32_f16_sdwa v3, v5 dst_sel:DWORD dst_unused:UNUSED_PAD src0_sel:WORD_1
	v_cvt_f32_f16_e32 v2, v39
	v_pk_mul_f32 v[4:5], v[6:7], s[24:25] op_sel_hi:[1,0]
	v_pk_mul_f32 v[2:3], v[2:3], s[24:25] op_sel_hi:[1,0]
	v_pk_mov_b32 v[4:5], v[4:5], v[4:5] op_sel:[1,0]
	ds_write_b64 v149, v[4:5] offset:32824
	ds_write_b64 v150, v[2:3] offset:32824
	v_mov_b32_e32 v2, v130
	s_waitcnt lgkmcnt(0)
	s_barrier
	s_nop 0
	v_and_b32_e32 v3, 0xff, v2
	v_lshlrev_b32_e32 v4, 5, v2
	v_and_or_b32 v3, v4, s29, v3
	v_ashrrev_i32_e32 v4, 5, v3
	v_lshlrev_b32_e32 v3, 3, v3
	v_lshlrev_b32_e32 v6, 3, v4
	v_add3_u32 v36, 0, v3, v6
	ds_read_b64 v[154:155], v36
	ds_read_b64 v[156:157], v36 offset:2112
	ds_read_b64 v[158:159], v36 offset:4224
	ds_read_b64 v[160:161], v36 offset:6336
	ds_read_b64 v[162:163], v36 offset:8448
	ds_read_b64 v[164:165], v36 offset:10560
	ds_read_b64 v[166:167], v36 offset:12672
	ds_read_b64 v[168:169], v36 offset:14784
	ds_read_b64 v[170:171], v36 offset:16896
	ds_read_b64 v[172:173], v36 offset:19008
	ds_read_b64 v[174:175], v36 offset:21120
	ds_read_b64 v[176:177], v36 offset:23232
	ds_read_b64 v[178:179], v36 offset:25344
	ds_read_b64 v[180:181], v36 offset:27456
	ds_read_b64 v[182:183], v36 offset:29568
	ds_read_b64 v[184:185], v36 offset:31680
	ds_read_b64 v[186:187], v36 offset:33792
	ds_read_b64 v[188:189], v36 offset:35904
	ds_read_b64 v[190:191], v36 offset:38016
	ds_read_b64 v[192:193], v36 offset:40128
	ds_read_b64 v[194:195], v36 offset:42240
	ds_read_b64 v[196:197], v36 offset:44352
	ds_read_b64 v[198:199], v36 offset:46464
	ds_read_b64 v[204:205], v36 offset:48576
	ds_read_b64 v[206:207], v36 offset:50688
	ds_read_b64 v[208:209], v36 offset:52800
	ds_read_b64 v[210:211], v36 offset:54912
	ds_read_b64 v[212:213], v36 offset:57024
	ds_read_b64 v[214:215], v36 offset:59136
	ds_read_b64 v[216:217], v36 offset:61248
	ds_read_b64 v[218:219], v36 offset:63360
	ds_read_b64 v[220:221], v36 offset:65472
	s_waitcnt lgkmcnt(14)
	v_pk_add_f32 v[222:223], v[154:155], v[186:187]
	v_pk_add_f32 v[154:155], v[154:155], v[186:187] neg_lo:[0,1] neg_hi:[0,1]
	v_pk_add_f32 v[186:187], v[156:157], v[188:189]
	v_pk_add_f32 v[156:157], v[156:157], v[188:189] neg_lo:[0,1] neg_hi:[0,1]
	v_cvt_f32_ubyte0_e32 v2, v2
	v_pk_mul_f32 v[188:189], v[156:157], s[40:41]
	v_mul_f32_e32 v5, 0x39000000, v2
	v_pk_fma_f32 v[156:157], v[156:157], s[36:37], v[188:189] op_sel:[0,0,1] op_sel_hi:[1,0,0]
	s_waitcnt lgkmcnt(13)
	v_pk_add_f32 v[188:189], v[158:159], v[190:191]
	v_pk_add_f32 v[158:159], v[158:159], v[190:191] neg_lo:[0,1] neg_hi:[0,1]
	v_sin_f32_e32 v2, v5
	v_pk_mul_f32 v[190:191], v[158:159], s[44:45]
	v_cos_f32_e32 v4, v5
	v_pk_fma_f32 v[158:159], v[158:159], s[42:43], v[190:191] op_sel:[0,0,1] op_sel_hi:[1,0,0]
	s_waitcnt lgkmcnt(12)
	v_pk_add_f32 v[190:191], v[160:161], v[192:193]
	v_pk_add_f32 v[160:161], v[160:161], v[192:193] neg_lo:[0,1] neg_hi:[0,1]
	v_xor_b32_e32 v5, 0x80000000, v2
	v_pk_mul_f32 v[192:193], v[160:161], s[62:63]
	v_mov_b32_e32 v3, v5
	v_pk_fma_f32 v[160:161], v[160:161], s[50:51], v[192:193] op_sel:[0,0,1] op_sel_hi:[1,0,0]
	s_waitcnt lgkmcnt(11)
	v_pk_add_f32 v[192:193], v[162:163], v[194:195]
	v_pk_add_f32 v[162:163], v[162:163], v[194:195] neg_lo:[0,1] neg_hi:[0,1]
	v_pk_mul_f32 v[6:7], v[4:5], v[2:3] op_sel:[1,0] op_sel_hi:[0,1]
	v_pk_mul_f32 v[194:195], v[162:163], s[68:69]
	v_pk_fma_f32 v[6:7], v[4:5], v[4:5], v[6:7] op_sel_hi:[1,0,1]
	v_pk_fma_f32 v[162:163], v[162:163], s[64:65], v[194:195] op_sel:[0,0,1] op_sel_hi:[1,0,0]
	s_waitcnt lgkmcnt(10)
	v_pk_add_f32 v[194:195], v[164:165], v[196:197]
	v_pk_add_f32 v[164:165], v[164:165], v[196:197] neg_lo:[0,1] neg_hi:[0,1]
	v_xor_b32_e32 v12, 0x80000000, v7
	v_pk_mul_f32 v[196:197], v[164:165], s[70:71]
	v_mov_b32_e32 v13, v7
	v_pk_fma_f32 v[164:165], v[164:165], s[46:47], v[196:197] op_sel:[0,0,1] op_sel_hi:[1,0,0]
	s_waitcnt lgkmcnt(9)
	v_pk_add_f32 v[196:197], v[166:167], v[198:199]
	v_pk_add_f32 v[166:167], v[166:167], v[198:199] neg_lo:[0,1] neg_hi:[0,1]
	v_pk_mul_f32 v[10:11], v[6:7], v[12:13] op_sel:[1,0] op_sel_hi:[0,1]
	v_pk_mul_f32 v[198:199], v[166:167], s[76:77]
	v_pk_fma_f32 v[10:11], v[6:7], v[6:7], v[10:11] op_sel_hi:[1,0,1]
	v_pk_fma_f32 v[166:167], v[166:167], s[72:73], v[198:199] op_sel:[0,0,1] op_sel_hi:[1,0,0]
	s_waitcnt lgkmcnt(8)
	v_pk_add_f32 v[198:199], v[168:169], v[204:205]
	v_pk_add_f32 v[168:169], v[168:169], v[204:205] neg_lo:[0,1] neg_hi:[0,1]
	v_xor_b32_e32 v14, 0x80000000, v11
	v_pk_mul_f32 v[204:205], v[168:169], s[26:27]
	v_mov_b32_e32 v15, v11
	v_pk_fma_f32 v[168:169], v[168:169], s[38:39], v[204:205] op_sel:[0,0,1] op_sel_hi:[1,0,0]
	s_waitcnt lgkmcnt(7)
	v_pk_add_f32 v[204:205], v[170:171], v[206:207]
	v_pk_add_f32 v[206:207], v[170:171], v[206:207] neg_lo:[0,1] neg_hi:[0,1]
	v_pk_mul_f32 v[26:27], v[10:11], v[14:15] op_sel:[1,0] op_sel_hi:[0,1]
	s_waitcnt lgkmcnt(6)
	v_pk_add_f32 v[170:171], v[172:173], v[208:209]
	v_pk_add_f32 v[172:173], v[172:173], v[208:209] neg_lo:[0,1] neg_hi:[0,1]
	v_pk_fma_f32 v[26:27], v[10:11], v[10:11], v[26:27] op_sel_hi:[1,0,1]
	v_pk_mul_f32 v[208:209], v[172:173], s[26:27]
	v_pk_mul_f32 v[46:47], v[14:15], v[26:27] op_sel:[0,1] op_sel_hi:[1,0]
	v_pk_fma_f32 v[172:173], v[172:173], s[38:39], v[208:209] op_sel:[0,0,1] op_sel_hi:[1,0,0] neg_lo:[1,0,0] neg_hi:[1,0,0]
	s_waitcnt lgkmcnt(5)
	v_pk_add_f32 v[208:209], v[174:175], v[210:211]
	v_pk_add_f32 v[174:175], v[174:175], v[210:211] neg_lo:[0,1] neg_hi:[0,1]
	v_pk_fma_f32 v[46:47], v[10:11], v[26:27], v[46:47] op_sel_hi:[0,1,1]
	v_pk_mul_f32 v[210:211], v[174:175], s[76:77]
	v_pk_mul_f32 v[62:63], v[14:15], v[46:47] op_sel:[0,1] op_sel_hi:[1,0]
	v_pk_fma_f32 v[174:175], v[174:175], s[72:73], v[210:211] op_sel:[0,0,1] op_sel_hi:[1,0,0] neg_lo:[1,0,0] neg_hi:[1,0,0]
	s_waitcnt lgkmcnt(4)
	v_pk_add_f32 v[210:211], v[176:177], v[212:213]
	v_pk_add_f32 v[176:177], v[176:177], v[212:213] neg_lo:[0,1] neg_hi:[0,1]
	v_pk_fma_f32 v[62:63], v[10:11], v[46:47], v[62:63] op_sel_hi:[0,1,1]
	v_pk_mul_f32 v[212:213], v[176:177], s[70:71]
	v_pk_mul_f32 v[78:79], v[14:15], v[62:63] op_sel:[0,1] op_sel_hi:[1,0]
	v_pk_fma_f32 v[176:177], v[176:177], s[46:47], v[212:213] op_sel:[0,0,1] op_sel_hi:[1,0,0] neg_lo:[1,0,0] neg_hi:[1,0,0]
	s_waitcnt lgkmcnt(3)
	v_pk_add_f32 v[212:213], v[178:179], v[214:215]
	v_pk_add_f32 v[178:179], v[178:179], v[214:215] neg_lo:[0,1] neg_hi:[0,1]
	v_pk_fma_f32 v[78:79], v[10:11], v[62:63], v[78:79] op_sel_hi:[0,1,1]
	v_pk_mul_f32 v[214:215], v[178:179], s[68:69]
	v_pk_mul_f32 v[94:95], v[14:15], v[78:79] op_sel:[0,1] op_sel_hi:[1,0]
	v_pk_fma_f32 v[178:179], v[178:179], s[64:65], v[214:215] op_sel:[0,0,1] op_sel_hi:[1,0,0] neg_lo:[1,0,0] neg_hi:[1,0,0]
	s_waitcnt lgkmcnt(2)
	v_pk_add_f32 v[214:215], v[180:181], v[216:217]
	v_pk_add_f32 v[180:181], v[180:181], v[216:217] neg_lo:[0,1] neg_hi:[0,1]
	v_pk_fma_f32 v[94:95], v[10:11], v[78:79], v[94:95] op_sel_hi:[0,1,1]
	v_pk_mul_f32 v[216:217], v[180:181], s[62:63]
	v_pk_mul_f32 v[110:111], v[14:15], v[94:95] op_sel:[0,1] op_sel_hi:[1,0]
	v_pk_fma_f32 v[180:181], v[180:181], s[50:51], v[216:217] op_sel:[0,0,1] op_sel_hi:[1,0,0] neg_lo:[1,0,0] neg_hi:[1,0,0]
	s_waitcnt lgkmcnt(1)
	v_pk_add_f32 v[216:217], v[182:183], v[218:219]
	v_pk_add_f32 v[182:183], v[182:183], v[218:219] neg_lo:[0,1] neg_hi:[0,1]
	v_pk_mul_f32 v[8:9], v[2:3], v[6:7] op_sel:[0,1] op_sel_hi:[1,0]
	v_pk_mul_f32 v[218:219], v[182:183], s[44:45]
	v_pk_fma_f32 v[110:111], v[10:11], v[94:95], v[110:111] op_sel_hi:[0,1,1]
	v_pk_fma_f32 v[182:183], v[182:183], s[42:43], v[218:219] op_sel:[0,0,1] op_sel_hi:[1,0,0] neg_lo:[1,0,0] neg_hi:[1,0,0]
	s_waitcnt lgkmcnt(0)
	v_pk_add_f32 v[218:219], v[184:185], v[220:221]
	v_pk_add_f32 v[184:185], v[184:185], v[220:221] neg_lo:[0,1] neg_hi:[0,1]
	v_pk_fma_f32 v[8:9], v[4:5], v[6:7], v[8:9] op_sel_hi:[0,1,1]
	v_pk_mul_f32 v[220:221], v[184:185], s[40:41]
	v_pk_mul_f32 v[16:17], v[2:3], v[10:11] op_sel:[0,1] op_sel_hi:[1,0]
	v_pk_fma_f32 v[184:185], v[184:185], s[36:37], v[220:221] op_sel:[0,0,1] op_sel_hi:[1,0,0] neg_lo:[1,0,0] neg_hi:[1,0,0]
	v_pk_add_f32 v[220:221], v[222:223], v[204:205]
	v_pk_add_f32 v[204:205], v[222:223], v[204:205] neg_lo:[0,1] neg_hi:[0,1]
	v_pk_add_f32 v[222:223], v[186:187], v[170:171]
	v_pk_add_f32 v[170:171], v[186:187], v[170:171] neg_lo:[0,1] neg_hi:[0,1]
	v_pk_mul_f32 v[30:31], v[2:3], v[26:27] op_sel:[0,1] op_sel_hi:[1,0]
	v_pk_mul_f32 v[186:187], v[170:171], s[44:45]
	v_pk_mul_f32 v[50:51], v[2:3], v[46:47] op_sel:[0,1] op_sel_hi:[1,0]
	v_pk_fma_f32 v[170:171], v[170:171], s[42:43], v[186:187] op_sel:[0,0,1] op_sel_hi:[1,0,0]
	v_pk_add_f32 v[186:187], v[188:189], v[208:209]
	v_pk_add_f32 v[188:189], v[188:189], v[208:209] neg_lo:[0,1] neg_hi:[0,1]
	v_pk_mul_f32 v[66:67], v[2:3], v[62:63] op_sel:[0,1] op_sel_hi:[1,0]
	v_pk_mul_f32 v[208:209], v[188:189], s[68:69]
	v_pk_mul_f32 v[82:83], v[2:3], v[78:79] op_sel:[0,1] op_sel_hi:[1,0]
	v_pk_fma_f32 v[188:189], v[188:189], s[64:65], v[208:209] op_sel:[0,0,1] op_sel_hi:[1,0,0]
	v_pk_add_f32 v[208:209], v[190:191], v[210:211]
	v_pk_add_f32 v[190:191], v[190:191], v[210:211] neg_lo:[0,1] neg_hi:[0,1]
	v_pk_mul_f32 v[98:99], v[2:3], v[94:95] op_sel:[0,1] op_sel_hi:[1,0]
	v_pk_mul_f32 v[210:211], v[190:191], s[76:77]
	v_pk_mul_f32 v[114:115], v[2:3], v[110:111] op_sel:[0,1] op_sel_hi:[1,0]
	v_pk_fma_f32 v[190:191], v[190:191], s[72:73], v[210:211] op_sel:[0,0,1] op_sel_hi:[1,0,0]
	v_pk_add_f32 v[210:211], v[192:193], v[212:213]
	v_pk_add_f32 v[212:213], v[192:193], v[212:213] neg_lo:[0,1] neg_hi:[0,1]
	v_xor_b32_e32 v20, 0x80000000, v9
	v_pk_add_f32 v[192:193], v[194:195], v[214:215]
	v_pk_add_f32 v[194:195], v[194:195], v[214:215] neg_lo:[0,1] neg_hi:[0,1]
	v_mov_b32_e32 v21, v9
	v_pk_mul_f32 v[214:215], v[194:195], s[76:77]
	v_pk_fma_f32 v[16:17], v[4:5], v[10:11], v[16:17] op_sel_hi:[0,1,1]
	v_pk_fma_f32 v[194:195], v[194:195], s[72:73], v[214:215] op_sel:[0,0,1] op_sel_hi:[1,0,0] neg_lo:[1,0,0] neg_hi:[1,0,0]
	v_pk_add_f32 v[214:215], v[196:197], v[216:217]
	v_pk_add_f32 v[196:197], v[196:197], v[216:217] neg_lo:[0,1] neg_hi:[0,1]
	v_pk_mul_f32 v[18:19], v[12:13], v[10:11] op_sel:[0,1] op_sel_hi:[1,0]
	v_pk_mul_f32 v[216:217], v[196:197], s[68:69]
	v_pk_fma_f32 v[30:31], v[4:5], v[26:27], v[30:31] op_sel_hi:[0,1,1]
	v_pk_fma_f32 v[196:197], v[196:197], s[64:65], v[216:217] op_sel:[0,0,1] op_sel_hi:[1,0,0] neg_lo:[1,0,0] neg_hi:[1,0,0]
	v_pk_add_f32 v[216:217], v[198:199], v[218:219]
	v_pk_add_f32 v[198:199], v[198:199], v[218:219] neg_lo:[0,1] neg_hi:[0,1]
	v_pk_mul_f32 v[38:39], v[12:13], v[26:27] op_sel:[0,1] op_sel_hi:[1,0]
	v_pk_mul_f32 v[218:219], v[198:199], s[44:45]
	v_pk_fma_f32 v[50:51], v[4:5], v[46:47], v[50:51] op_sel_hi:[0,1,1]
	v_pk_fma_f32 v[198:199], v[198:199], s[42:43], v[218:219] op_sel:[0,0,1] op_sel_hi:[1,0,0] neg_lo:[1,0,0] neg_hi:[1,0,0]
	v_pk_add_f32 v[218:219], v[154:155], v[206:207] op_sel:[0,1] op_sel_hi:[1,0] neg_hi:[0,1]
	v_pk_add_f32 v[154:155], v[154:155], v[206:207] op_sel:[0,1] op_sel_hi:[1,0] neg_lo:[0,1]
	v_pk_add_f32 v[206:207], v[156:157], v[172:173]
	v_pk_add_f32 v[156:157], v[156:157], v[172:173] neg_lo:[0,1] neg_hi:[0,1]
	v_pk_mul_f32 v[54:55], v[12:13], v[46:47] op_sel:[0,1] op_sel_hi:[1,0]
	v_pk_mul_f32 v[172:173], v[156:157], s[44:45]
	v_pk_fma_f32 v[66:67], v[4:5], v[62:63], v[66:67] op_sel_hi:[0,1,1]
	v_pk_fma_f32 v[156:157], v[156:157], s[42:43], v[172:173] op_sel:[0,0,1] op_sel_hi:[1,0,0]
	v_pk_add_f32 v[172:173], v[158:159], v[174:175]
	v_pk_add_f32 v[158:159], v[158:159], v[174:175] neg_lo:[0,1] neg_hi:[0,1]
	v_pk_mul_f32 v[70:71], v[12:13], v[62:63] op_sel:[0,1] op_sel_hi:[1,0]
	v_pk_mul_f32 v[174:175], v[158:159], s[68:69]
	v_pk_fma_f32 v[82:83], v[4:5], v[78:79], v[82:83] op_sel_hi:[0,1,1]
	v_pk_fma_f32 v[158:159], v[158:159], s[64:65], v[174:175] op_sel:[0,0,1] op_sel_hi:[1,0,0]
	v_pk_add_f32 v[174:175], v[160:161], v[176:177]
	v_pk_add_f32 v[160:161], v[160:161], v[176:177] neg_lo:[0,1] neg_hi:[0,1]
	v_pk_mul_f32 v[86:87], v[12:13], v[78:79] op_sel:[0,1] op_sel_hi:[1,0]
	v_pk_mul_f32 v[176:177], v[160:161], s[76:77]
	v_pk_fma_f32 v[98:99], v[4:5], v[94:95], v[98:99] op_sel_hi:[0,1,1]
	v_pk_fma_f32 v[160:161], v[160:161], s[72:73], v[176:177] op_sel:[0,0,1] op_sel_hi:[1,0,0]
	v_pk_add_f32 v[176:177], v[162:163], v[178:179]
	v_pk_add_f32 v[178:179], v[162:163], v[178:179] neg_lo:[0,1] neg_hi:[0,1]
	v_pk_mul_f32 v[102:103], v[12:13], v[94:95] op_sel:[0,1] op_sel_hi:[1,0]
	v_pk_add_f32 v[162:163], v[164:165], v[180:181]
	v_pk_add_f32 v[164:165], v[164:165], v[180:181] neg_lo:[0,1] neg_hi:[0,1]
	v_pk_fma_f32 v[114:115], v[4:5], v[110:111], v[114:115] op_sel_hi:[0,1,1]
	v_pk_mul_f32 v[180:181], v[164:165], s[76:77]
	v_pk_mul_f32 v[118:119], v[12:13], v[110:111] op_sel:[0,1] op_sel_hi:[1,0]
	v_pk_fma_f32 v[164:165], v[164:165], s[72:73], v[180:181] op_sel:[0,0,1] op_sel_hi:[1,0,0] neg_lo:[1,0,0] neg_hi:[1,0,0]
	v_pk_add_f32 v[180:181], v[166:167], v[182:183]
	v_pk_add_f32 v[166:167], v[166:167], v[182:183] neg_lo:[0,1] neg_hi:[0,1]
	v_pk_fma_f32 v[18:19], v[6:7], v[10:11], v[18:19] op_sel_hi:[0,1,1]
	v_pk_mul_f32 v[182:183], v[166:167], s[68:69]
	v_pk_mul_f32 v[22:23], v[10:11], v[20:21] op_sel:[1,0] op_sel_hi:[0,1]
	v_pk_fma_f32 v[166:167], v[166:167], s[64:65], v[182:183] op_sel:[0,0,1] op_sel_hi:[1,0,0] neg_lo:[1,0,0] neg_hi:[1,0,0]
	v_pk_add_f32 v[182:183], v[168:169], v[184:185]
	v_pk_add_f32 v[168:169], v[168:169], v[184:185] neg_lo:[0,1] neg_hi:[0,1]
	v_pk_fma_f32 v[38:39], v[6:7], v[26:27], v[38:39] op_sel_hi:[0,1,1]
	v_pk_mul_f32 v[184:185], v[168:169], s[44:45]
	v_pk_mul_f32 v[42:43], v[20:21], v[26:27] op_sel:[0,1] op_sel_hi:[1,0]
	v_pk_fma_f32 v[168:169], v[168:169], s[42:43], v[184:185] op_sel:[0,0,1] op_sel_hi:[1,0,0] neg_lo:[1,0,0] neg_hi:[1,0,0]
	v_pk_add_f32 v[184:185], v[220:221], v[210:211]
	v_pk_add_f32 v[210:211], v[220:221], v[210:211] neg_lo:[0,1] neg_hi:[0,1]
	v_pk_add_f32 v[220:221], v[222:223], v[192:193]
	v_pk_add_f32 v[192:193], v[222:223], v[192:193] neg_lo:[0,1] neg_hi:[0,1]
	v_pk_fma_f32 v[54:55], v[6:7], v[46:47], v[54:55] op_sel_hi:[0,1,1]
	v_pk_mul_f32 v[222:223], v[192:193], s[68:69]
	v_pk_mul_f32 v[58:59], v[20:21], v[46:47] op_sel:[0,1] op_sel_hi:[1,0]
	v_pk_fma_f32 v[192:193], v[192:193], s[64:65], v[222:223] op_sel:[0,0,1] op_sel_hi:[1,0,0]
	v_pk_add_f32 v[222:223], v[186:187], v[214:215]
	v_pk_add_f32 v[214:215], v[186:187], v[214:215] neg_lo:[0,1] neg_hi:[0,1]
	v_pk_fma_f32 v[70:71], v[6:7], v[62:63], v[70:71] op_sel_hi:[0,1,1]
	v_pk_add_f32 v[186:187], v[208:209], v[216:217]
	v_pk_add_f32 v[208:209], v[208:209], v[216:217] neg_lo:[0,1] neg_hi:[0,1]
	v_pk_mul_f32 v[74:75], v[20:21], v[62:63] op_sel:[0,1] op_sel_hi:[1,0]
	v_pk_mul_f32 v[216:217], v[208:209], s[68:69]
	v_pk_fma_f32 v[86:87], v[6:7], v[78:79], v[86:87] op_sel_hi:[0,1,1]
	v_pk_fma_f32 v[208:209], v[208:209], s[64:65], v[216:217] op_sel:[0,0,1] op_sel_hi:[1,0,0] neg_lo:[1,0,0] neg_hi:[1,0,0]
	v_pk_add_f32 v[216:217], v[204:205], v[212:213] op_sel:[0,1] op_sel_hi:[1,0] neg_hi:[0,1]
	v_pk_add_f32 v[204:205], v[204:205], v[212:213] op_sel:[0,1] op_sel_hi:[1,0] neg_lo:[0,1]
	v_pk_add_f32 v[212:213], v[170:171], v[194:195]
	v_pk_add_f32 v[170:171], v[170:171], v[194:195] neg_lo:[0,1] neg_hi:[0,1]
	v_pk_mul_f32 v[90:91], v[20:21], v[78:79] op_sel:[0,1] op_sel_hi:[1,0]
	v_pk_mul_f32 v[194:195], v[170:171], s[68:69]
	v_pk_fma_f32 v[102:103], v[6:7], v[94:95], v[102:103] op_sel_hi:[0,1,1]
	v_pk_fma_f32 v[170:171], v[170:171], s[64:65], v[194:195] op_sel:[0,0,1] op_sel_hi:[1,0,0]
	v_pk_add_f32 v[194:195], v[188:189], v[196:197]
	v_pk_add_f32 v[196:197], v[188:189], v[196:197] neg_lo:[0,1] neg_hi:[0,1]
	v_pk_mul_f32 v[106:107], v[20:21], v[94:95] op_sel:[0,1] op_sel_hi:[1,0]
	v_pk_add_f32 v[188:189], v[190:191], v[198:199]
	v_pk_add_f32 v[190:191], v[190:191], v[198:199] neg_lo:[0,1] neg_hi:[0,1]
	v_pk_fma_f32 v[118:119], v[6:7], v[110:111], v[118:119] op_sel_hi:[0,1,1]
	v_pk_mul_f32 v[198:199], v[190:191], s[68:69]
	v_pk_mul_f32 v[122:123], v[20:21], v[110:111] op_sel:[0,1] op_sel_hi:[1,0]
	v_pk_fma_f32 v[190:191], v[190:191], s[64:65], v[198:199] op_sel:[0,0,1] op_sel_hi:[1,0,0] neg_lo:[1,0,0] neg_hi:[1,0,0]
	v_pk_add_f32 v[198:199], v[218:219], v[176:177]
	v_pk_add_f32 v[176:177], v[218:219], v[176:177] neg_lo:[0,1] neg_hi:[0,1]
	v_pk_add_f32 v[218:219], v[206:207], v[162:163]
	v_pk_add_f32 v[162:163], v[206:207], v[162:163] neg_lo:[0,1] neg_hi:[0,1]
	v_xor_b32_e32 v24, 0x80000000, v17
	v_pk_mul_f32 v[206:207], v[162:163], s[68:69]
	v_xor_b32_e32 v28, 0x80000000, v19
	v_pk_fma_f32 v[162:163], v[162:163], s[64:65], v[206:207] op_sel:[0,0,1] op_sel_hi:[1,0,0]
	v_pk_add_f32 v[206:207], v[172:173], v[180:181]
	v_pk_add_f32 v[180:181], v[172:173], v[180:181] neg_lo:[0,1] neg_hi:[0,1]
	v_pk_fma_f32 v[22:23], v[10:11], v[8:9], v[22:23] op_sel_hi:[1,0,1]
	v_pk_add_f32 v[172:173], v[174:175], v[182:183]
	v_pk_add_f32 v[174:175], v[174:175], v[182:183] neg_lo:[0,1] neg_hi:[0,1]
	v_pk_fma_f32 v[42:43], v[8:9], v[26:27], v[42:43] op_sel_hi:[0,1,1]
	v_pk_mul_f32 v[182:183], v[174:175], s[68:69]
	v_pk_fma_f32 v[58:59], v[8:9], v[46:47], v[58:59] op_sel_hi:[0,1,1]
	v_pk_fma_f32 v[174:175], v[174:175], s[64:65], v[182:183] op_sel:[0,0,1] op_sel_hi:[1,0,0] neg_lo:[1,0,0] neg_hi:[1,0,0]
	v_pk_add_f32 v[182:183], v[154:155], v[178:179] op_sel:[0,1] op_sel_hi:[1,0] neg_hi:[0,1]
	v_pk_add_f32 v[154:155], v[154:155], v[178:179] op_sel:[0,1] op_sel_hi:[1,0] neg_lo:[0,1]
	v_pk_add_f32 v[178:179], v[156:157], v[164:165]
	v_pk_add_f32 v[156:157], v[156:157], v[164:165] neg_lo:[0,1] neg_hi:[0,1]
	v_pk_fma_f32 v[74:75], v[8:9], v[62:63], v[74:75] op_sel_hi:[0,1,1]
	v_pk_mul_f32 v[164:165], v[156:157], s[68:69]
	v_pk_fma_f32 v[90:91], v[8:9], v[78:79], v[90:91] op_sel_hi:[0,1,1]
	v_pk_fma_f32 v[156:157], v[156:157], s[64:65], v[164:165] op_sel:[0,0,1] op_sel_hi:[1,0,0]
	v_pk_add_f32 v[164:165], v[158:159], v[166:167]
	v_pk_add_f32 v[166:167], v[158:159], v[166:167] neg_lo:[0,1] neg_hi:[0,1]
	v_pk_fma_f32 v[106:107], v[8:9], v[94:95], v[106:107] op_sel_hi:[0,1,1]
	v_pk_add_f32 v[158:159], v[160:161], v[168:169]
	v_pk_add_f32 v[160:161], v[160:161], v[168:169] neg_lo:[0,1] neg_hi:[0,1]
	v_pk_fma_f32 v[122:123], v[8:9], v[110:111], v[122:123] op_sel_hi:[0,1,1]
	v_pk_mul_f32 v[168:169], v[160:161], s[68:69]
	v_mov_b32_e32 v25, v17
	v_pk_fma_f32 v[160:161], v[160:161], s[64:65], v[168:169] op_sel:[0,0,1] op_sel_hi:[1,0,0] neg_lo:[1,0,0] neg_hi:[1,0,0]
	v_pk_add_f32 v[168:169], v[184:185], v[222:223]
	v_pk_add_f32 v[184:185], v[184:185], v[222:223] neg_lo:[0,1] neg_hi:[0,1]
	v_pk_add_f32 v[222:223], v[220:221], v[186:187]
	v_pk_add_f32 v[220:221], v[220:221], v[186:187] neg_lo:[0,1] neg_hi:[0,1]
	v_mov_b32_e32 v29, v19
	v_pk_add_f32 v[186:187], v[210:211], v[214:215] op_sel:[0,1] op_sel_hi:[1,0] neg_hi:[0,1]
	v_pk_add_f32 v[210:211], v[210:211], v[214:215] op_sel:[0,1] op_sel_hi:[1,0] neg_lo:[0,1]
	v_pk_add_f32 v[214:215], v[192:193], v[208:209]
	v_pk_add_f32 v[208:209], v[192:193], v[208:209] neg_lo:[0,1] neg_hi:[0,1]
	v_xor_b32_e32 v32, 0x80000000, v23
	v_pk_add_f32 v[192:193], v[216:217], v[194:195]
	v_pk_add_f32 v[194:195], v[216:217], v[194:195] neg_lo:[0,1] neg_hi:[0,1]
	v_pk_add_f32 v[216:217], v[212:213], v[188:189]
	v_pk_add_f32 v[212:213], v[212:213], v[188:189] neg_lo:[0,1] neg_hi:[0,1]
	v_xor_b32_e32 v40, 0x80000000, v27
	v_pk_add_f32 v[188:189], v[204:205], v[196:197] op_sel:[0,1] op_sel_hi:[1,0] neg_hi:[0,1]
	v_pk_add_f32 v[196:197], v[204:205], v[196:197] op_sel:[0,1] op_sel_hi:[1,0] neg_lo:[0,1]
	v_pk_add_f32 v[204:205], v[170:171], v[190:191]
	v_pk_add_f32 v[190:191], v[170:171], v[190:191] neg_lo:[0,1] neg_hi:[0,1]
	v_xor_b32_e32 v44, 0x80000000, v31
	v_pk_add_f32 v[170:171], v[198:199], v[206:207]
	v_pk_add_f32 v[198:199], v[198:199], v[206:207] neg_lo:[0,1] neg_hi:[0,1]
	v_pk_add_f32 v[206:207], v[218:219], v[172:173]
	v_pk_add_f32 v[218:219], v[218:219], v[172:173] neg_lo:[0,1] neg_hi:[0,1]
	v_xor_b32_e32 v48, 0x80000000, v39
	v_pk_add_f32 v[172:173], v[176:177], v[180:181] op_sel:[0,1] op_sel_hi:[1,0] neg_hi:[0,1]
	v_pk_add_f32 v[176:177], v[176:177], v[180:181] op_sel:[0,1] op_sel_hi:[1,0] neg_lo:[0,1]
	v_pk_add_f32 v[180:181], v[162:163], v[174:175]
	v_pk_add_f32 v[174:175], v[162:163], v[174:175] neg_lo:[0,1] neg_hi:[0,1]
	v_mov_b32_e32 v33, v23
	v_pk_add_f32 v[162:163], v[182:183], v[164:165]
	v_pk_add_f32 v[164:165], v[182:183], v[164:165] neg_lo:[0,1] neg_hi:[0,1]
	v_pk_add_f32 v[182:183], v[178:179], v[158:159]
	v_pk_add_f32 v[178:179], v[178:179], v[158:159] neg_lo:[0,1] neg_hi:[0,1]
	v_mov_b32_e32 v41, v27
	v_pk_add_f32 v[158:159], v[154:155], v[166:167] op_sel:[0,1] op_sel_hi:[1,0] neg_hi:[0,1]
	v_pk_add_f32 v[154:155], v[154:155], v[166:167] op_sel:[0,1] op_sel_hi:[1,0] neg_lo:[0,1]
	v_pk_add_f32 v[166:167], v[156:157], v[160:161]
	v_pk_add_f32 v[156:157], v[156:157], v[160:161] neg_lo:[0,1] neg_hi:[0,1]
	v_mov_b32_e32 v45, v31
	v_xor_b32_e32 v161, 0x80000000, v156
	v_mov_b32_e32 v160, v157
	v_pk_add_f32 v[156:157], v[168:169], v[222:223]
	v_pk_add_f32 v[168:169], v[168:169], v[222:223] neg_lo:[0,1] neg_hi:[0,1]
	v_pk_add_f32 v[222:223], v[184:185], v[220:221] op_sel:[0,1] op_sel_hi:[1,0] neg_hi:[0,1]
	v_pk_add_f32 v[184:185], v[184:185], v[220:221] op_sel:[0,1] op_sel_hi:[1,0] neg_lo:[0,1]
	v_pk_add_f32 v[220:221], v[186:187], v[214:215]
	v_pk_add_f32 v[186:187], v[186:187], v[214:215] neg_lo:[0,1] neg_hi:[0,1]
	v_pk_add_f32 v[214:215], v[210:211], v[208:209] op_sel:[0,1] op_sel_hi:[1,0] neg_hi:[0,1]
	v_pk_add_f32 v[208:209], v[210:211], v[208:209] op_sel:[0,1] op_sel_hi:[1,0] neg_lo:[0,1]
	v_pk_add_f32 v[210:211], v[192:193], v[216:217]
	v_pk_add_f32 v[192:193], v[192:193], v[216:217] neg_lo:[0,1] neg_hi:[0,1]
	v_pk_add_f32 v[216:217], v[194:195], v[212:213] op_sel:[0,1] op_sel_hi:[1,0] neg_hi:[0,1]
	v_pk_add_f32 v[194:195], v[194:195], v[212:213] op_sel:[0,1] op_sel_hi:[1,0] neg_lo:[0,1]
	v_pk_add_f32 v[212:213], v[188:189], v[204:205]
	v_pk_add_f32 v[188:189], v[188:189], v[204:205] neg_lo:[0,1] neg_hi:[0,1]
	v_pk_add_f32 v[204:205], v[196:197], v[190:191] op_sel:[0,1] op_sel_hi:[1,0] neg_hi:[0,1]
	v_pk_add_f32 v[190:191], v[196:197], v[190:191] op_sel:[0,1] op_sel_hi:[1,0] neg_lo:[0,1]
	v_pk_add_f32 v[196:197], v[170:171], v[206:207]
	v_pk_add_f32 v[170:171], v[170:171], v[206:207] neg_lo:[0,1] neg_hi:[0,1]
	v_pk_mul_f32 v[2:3], v[2:3], v[196:197] op_sel:[0,1] op_sel_hi:[1,0]
	v_pk_add_f32 v[206:207], v[198:199], v[218:219] op_sel:[0,1] op_sel_hi:[1,0] neg_hi:[0,1]
	v_pk_add_f32 v[198:199], v[198:199], v[218:219] op_sel:[0,1] op_sel_hi:[1,0] neg_lo:[0,1]
	v_pk_add_f32 v[218:219], v[172:173], v[180:181]
	v_pk_add_f32 v[172:173], v[172:173], v[180:181] neg_lo:[0,1] neg_hi:[0,1]
	v_pk_add_f32 v[180:181], v[176:177], v[174:175] op_sel:[0,1] op_sel_hi:[1,0] neg_hi:[0,1]
	v_pk_add_f32 v[174:175], v[176:177], v[174:175] op_sel:[0,1] op_sel_hi:[1,0] neg_lo:[0,1]
	v_pk_add_f32 v[176:177], v[162:163], v[182:183]
	v_pk_fma_f32 v[2:3], v[4:5], v[196:197], v[2:3] op_sel_hi:[0,1,1]
	v_pk_mul_f32 v[4:5], v[12:13], v[210:211] op_sel:[0,1] op_sel_hi:[1,0]
	v_mov_b32_e32 v49, v39
	v_pk_fma_f32 v[4:5], v[6:7], v[210:211], v[4:5] op_sel_hi:[0,1,1]
	v_pk_mul_f32 v[6:7], v[20:21], v[176:177] op_sel:[0,1] op_sel_hi:[1,0]
	v_pk_add_f32 v[162:163], v[162:163], v[182:183] neg_lo:[0,1] neg_hi:[0,1]
	v_pk_fma_f32 v[6:7], v[8:9], v[176:177], v[6:7] op_sel_hi:[0,1,1]
	v_pk_mul_f32 v[8:9], v[14:15], v[220:221] op_sel:[0,1] op_sel_hi:[1,0]
	v_pk_add_f32 v[182:183], v[164:165], v[178:179] op_sel:[0,1] op_sel_hi:[1,0] neg_hi:[0,1]
	v_pk_add_f32 v[164:165], v[164:165], v[178:179] op_sel:[0,1] op_sel_hi:[1,0] neg_lo:[0,1]
	v_pk_add_f32 v[178:179], v[158:159], v[166:167]
	v_pk_fma_f32 v[8:9], v[10:11], v[220:221], v[8:9] op_sel_hi:[0,1,1]
	v_pk_mul_f32 v[10:11], v[24:25], v[218:219] op_sel:[0,1] op_sel_hi:[1,0]
	v_pk_mul_f32 v[12:13], v[28:29], v[212:213] op_sel:[0,1] op_sel_hi:[1,0]
	v_xor_b32_e32 v52, 0x80000000, v43
	v_xor_b32_e32 v56, 0x80000000, v47
	v_xor_b32_e32 v60, 0x80000000, v51
	v_xor_b32_e32 v64, 0x80000000, v55
	v_xor_b32_e32 v68, 0x80000000, v59
	v_xor_b32_e32 v72, 0x80000000, v63
	v_xor_b32_e32 v76, 0x80000000, v67
	v_mov_b32_e32 v53, v43
	v_mov_b32_e32 v57, v47
	v_mov_b32_e32 v61, v51
	v_mov_b32_e32 v65, v55
	v_mov_b32_e32 v69, v59
	v_mov_b32_e32 v73, v63
	v_mov_b32_e32 v77, v67
	v_pk_add_f32 v[158:159], v[158:159], v[166:167] neg_lo:[0,1] neg_hi:[0,1]
	v_pk_add_f32 v[166:167], v[154:155], v[160:161]
	v_pk_fma_f32 v[10:11], v[16:17], v[218:219], v[10:11] op_sel_hi:[0,1,1]
	v_pk_fma_f32 v[12:13], v[18:19], v[212:213], v[12:13] op_sel_hi:[0,1,1]
	v_pk_mul_f32 v[14:15], v[32:33], v[178:179] op_sel:[0,1] op_sel_hi:[1,0]
	v_pk_mul_f32 v[16:17], v[40:41], v[222:223] op_sel:[0,1] op_sel_hi:[1,0]
	v_pk_mul_f32 v[18:19], v[44:45], v[206:207] op_sel:[0,1] op_sel_hi:[1,0]
	v_pk_mul_f32 v[20:21], v[48:49], v[216:217] op_sel:[0,1] op_sel_hi:[1,0]
	v_xor_b32_e32 v80, 0x80000000, v71
	v_xor_b32_e32 v84, 0x80000000, v75
	v_xor_b32_e32 v88, 0x80000000, v79
	v_xor_b32_e32 v92, 0x80000000, v83
	v_xor_b32_e32 v96, 0x80000000, v87
	v_xor_b32_e32 v100, 0x80000000, v91
	v_xor_b32_e32 v104, 0x80000000, v95
	v_xor_b32_e32 v108, 0x80000000, v99
	v_xor_b32_e32 v112, 0x80000000, v103
	v_xor_b32_e32 v116, 0x80000000, v107
	v_xor_b32_e32 v120, 0x80000000, v111
	v_xor_b32_e32 v124, 0x80000000, v115
	v_xor_b32_e32 v126, 0x80000000, v119
	v_xor_b32_e32 v128, 0x80000000, v123
	v_mov_b32_e32 v81, v71
	v_mov_b32_e32 v85, v75
	v_mov_b32_e32 v89, v79
	v_mov_b32_e32 v93, v83
	v_mov_b32_e32 v97, v87
	v_mov_b32_e32 v101, v91
	v_mov_b32_e32 v105, v95
	v_mov_b32_e32 v109, v99
	v_mov_b32_e32 v113, v103
	v_mov_b32_e32 v117, v107
	v_mov_b32_e32 v121, v111
	v_mov_b32_e32 v125, v115
	v_mov_b32_e32 v127, v119
	v_mov_b32_e32 v129, v123
	v_pk_add_f32 v[154:155], v[154:155], v[160:161] neg_lo:[0,1] neg_hi:[0,1]
	v_pk_fma_f32 v[14:15], v[22:23], v[178:179], v[14:15] op_sel_hi:[0,1,1]
	v_pk_fma_f32 v[16:17], v[26:27], v[222:223], v[16:17] op_sel_hi:[0,1,1]
	v_pk_fma_f32 v[18:19], v[30:31], v[206:207], v[18:19] op_sel_hi:[0,1,1]
	v_pk_fma_f32 v[20:21], v[38:39], v[216:217], v[20:21] op_sel_hi:[0,1,1]
	v_pk_mul_f32 v[22:23], v[52:53], v[182:183] op_sel:[0,1] op_sel_hi:[1,0]
	v_pk_mul_f32 v[24:25], v[56:57], v[214:215] op_sel:[0,1] op_sel_hi:[1,0]
	v_pk_mul_f32 v[26:27], v[60:61], v[180:181] op_sel:[0,1] op_sel_hi:[1,0]
	v_pk_mul_f32 v[28:29], v[64:65], v[204:205] op_sel:[0,1] op_sel_hi:[1,0]
	v_pk_mul_f32 v[30:31], v[68:69], v[166:167] op_sel:[0,1] op_sel_hi:[1,0]
	v_pk_mul_f32 v[32:33], v[72:73], v[168:169] op_sel:[0,1] op_sel_hi:[1,0]
	v_pk_mul_f32 v[38:39], v[76:77], v[170:171] op_sel:[0,1] op_sel_hi:[1,0]
	v_pk_fma_f32 v[22:23], v[42:43], v[182:183], v[22:23] op_sel_hi:[0,1,1]
	v_pk_fma_f32 v[24:25], v[46:47], v[214:215], v[24:25] op_sel_hi:[0,1,1]
	v_pk_fma_f32 v[26:27], v[50:51], v[180:181], v[26:27] op_sel_hi:[0,1,1]
	v_pk_fma_f32 v[28:29], v[54:55], v[204:205], v[28:29] op_sel_hi:[0,1,1]
	v_pk_fma_f32 v[30:31], v[58:59], v[166:167], v[30:31] op_sel_hi:[0,1,1]
	v_pk_fma_f32 v[32:33], v[62:63], v[168:169], v[32:33] op_sel_hi:[0,1,1]
	v_pk_fma_f32 v[38:39], v[66:67], v[170:171], v[38:39] op_sel_hi:[0,1,1]
	v_pk_mul_f32 v[40:41], v[80:81], v[192:193] op_sel:[0,1] op_sel_hi:[1,0]
	v_pk_mul_f32 v[42:43], v[84:85], v[162:163] op_sel:[0,1] op_sel_hi:[1,0]
	v_pk_mul_f32 v[44:45], v[88:89], v[186:187] op_sel:[0,1] op_sel_hi:[1,0]
	v_pk_mul_f32 v[46:47], v[92:93], v[172:173] op_sel:[0,1] op_sel_hi:[1,0]
	v_pk_mul_f32 v[48:49], v[96:97], v[188:189] op_sel:[0,1] op_sel_hi:[1,0]
	v_pk_mul_f32 v[50:51], v[100:101], v[158:159] op_sel:[0,1] op_sel_hi:[1,0]
	v_pk_mul_f32 v[52:53], v[104:105], v[184:185] op_sel:[0,1] op_sel_hi:[1,0]
	v_pk_mul_f32 v[54:55], v[108:109], v[198:199] op_sel:[0,1] op_sel_hi:[1,0]
	v_pk_mul_f32 v[56:57], v[112:113], v[194:195] op_sel:[0,1] op_sel_hi:[1,0]
	v_pk_mul_f32 v[58:59], v[116:117], v[164:165] op_sel:[0,1] op_sel_hi:[1,0]
	v_pk_mul_f32 v[60:61], v[120:121], v[208:209] op_sel:[0,1] op_sel_hi:[1,0]
	v_pk_mul_f32 v[62:63], v[124:125], v[174:175] op_sel:[0,1] op_sel_hi:[1,0]
	v_pk_mul_f32 v[64:65], v[126:127], v[190:191] op_sel:[0,1] op_sel_hi:[1,0]
	v_pk_mul_f32 v[66:67], v[128:129], v[154:155] op_sel:[0,1] op_sel_hi:[1,0]
	v_pk_fma_f32 v[40:41], v[70:71], v[192:193], v[40:41] op_sel_hi:[0,1,1]
	v_pk_fma_f32 v[42:43], v[74:75], v[162:163], v[42:43] op_sel_hi:[0,1,1]
	v_pk_fma_f32 v[44:45], v[78:79], v[186:187], v[44:45] op_sel_hi:[0,1,1]
	v_pk_fma_f32 v[46:47], v[82:83], v[172:173], v[46:47] op_sel_hi:[0,1,1]
	v_pk_fma_f32 v[48:49], v[86:87], v[188:189], v[48:49] op_sel_hi:[0,1,1]
	v_pk_fma_f32 v[50:51], v[90:91], v[158:159], v[50:51] op_sel_hi:[0,1,1]
	v_pk_fma_f32 v[52:53], v[94:95], v[184:185], v[52:53] op_sel_hi:[0,1,1]
	v_pk_fma_f32 v[54:55], v[98:99], v[198:199], v[54:55] op_sel_hi:[0,1,1]
	v_pk_fma_f32 v[56:57], v[102:103], v[194:195], v[56:57] op_sel_hi:[0,1,1]
	v_pk_fma_f32 v[58:59], v[106:107], v[164:165], v[58:59] op_sel_hi:[0,1,1]
	v_pk_fma_f32 v[60:61], v[110:111], v[208:209], v[60:61] op_sel_hi:[0,1,1]
	v_pk_fma_f32 v[62:63], v[114:115], v[174:175], v[62:63] op_sel_hi:[0,1,1]
	v_pk_fma_f32 v[64:65], v[118:119], v[190:191], v[64:65] op_sel_hi:[0,1,1]
	v_pk_fma_f32 v[66:67], v[122:123], v[154:155], v[66:67] op_sel_hi:[0,1,1]
	ds_write_b64 v36, v[156:157]
	ds_write_b64 v36, v[32:33] offset:2112
	ds_write_b64 v36, v[16:17] offset:4224
	ds_write_b64 v36, v[52:53] offset:6336
	ds_write_b64 v36, v[8:9] offset:8448
	ds_write_b64 v36, v[44:45] offset:10560
	ds_write_b64 v36, v[24:25] offset:12672
	ds_write_b64 v36, v[60:61] offset:14784
	ds_write_b64 v36, v[4:5] offset:16896
	ds_write_b64 v36, v[40:41] offset:19008
	ds_write_b64 v36, v[20:21] offset:21120
	ds_write_b64 v36, v[56:57] offset:23232
	ds_write_b64 v36, v[12:13] offset:25344
	ds_write_b64 v36, v[48:49] offset:27456
	ds_write_b64 v36, v[28:29] offset:29568
	ds_write_b64 v36, v[64:65] offset:31680
	ds_write_b64 v36, v[2:3] offset:33792
	ds_write_b64 v36, v[38:39] offset:35904
	ds_write_b64 v36, v[18:19] offset:38016
	ds_write_b64 v36, v[54:55] offset:40128
	ds_write_b64 v36, v[10:11] offset:42240
	ds_write_b64 v36, v[46:47] offset:44352
	ds_write_b64 v36, v[26:27] offset:46464
	ds_write_b64 v36, v[62:63] offset:48576
	ds_write_b64 v36, v[6:7] offset:50688
	ds_write_b64 v36, v[42:43] offset:52800
	ds_write_b64 v36, v[22:23] offset:54912
	ds_write_b64 v36, v[58:59] offset:57024
	ds_write_b64 v36, v[14:15] offset:59136
	ds_write_b64 v36, v[50:51] offset:61248
	ds_write_b64 v36, v[30:31] offset:63360
	ds_write_b64 v36, v[66:67] offset:65472
	v_mov_b32_e32 v3, v130
	s_waitcnt lgkmcnt(0)
	s_barrier
	s_nop 0
	v_and_b32_e32 v5, 15, v3
	v_cvt_f32_ubyte0_e32 v2, v5
	v_mul_f32_e32 v4, 0x3b800000, v2
	v_sin_f32_e32 v2, v4
	v_cos_f32_e32 v4, v4
	v_lshlrev_b32_e32 v66, 3, v5
	v_lshlrev_b32_e32 v36, 4, v3
	v_xor_b32_e32 v5, 0x80000000, v2
	v_mov_b32_e32 v3, v5
	v_pk_mul_f32 v[6:7], v[4:5], v[2:3] op_sel:[1,0] op_sel_hi:[0,1]
	v_pk_fma_f32 v[6:7], v[4:5], v[4:5], v[6:7] op_sel_hi:[0,1,1]
	v_xor_b32_e32 v12, 0x80000000, v7
	v_mov_b32_e32 v13, v7
	v_pk_mul_f32 v[10:11], v[6:7], v[12:13] op_sel:[1,0] op_sel_hi:[0,1]
	v_pk_fma_f32 v[10:11], v[6:7], v[6:7], v[10:11] op_sel_hi:[1,0,1]
	v_pk_mul_f32 v[8:9], v[2:3], v[6:7] op_sel:[0,1] op_sel_hi:[1,0]
	v_xor_b32_e32 v14, 0x80000000, v11
	v_mov_b32_e32 v15, v11
	v_pk_mul_f32 v[30:31], v[10:11], v[14:15] op_sel:[1,0] op_sel_hi:[0,1]
	v_pk_fma_f32 v[30:31], v[10:11], v[10:11], v[30:31] op_sel_hi:[1,0,1]
	v_pk_mul_f32 v[16:17], v[2:3], v[10:11] op_sel:[0,1] op_sel_hi:[1,0]
	v_pk_mul_f32 v[50:51], v[14:15], v[30:31] op_sel:[0,1] op_sel_hi:[1,0]
	v_pk_mul_f32 v[38:39], v[2:3], v[30:31] op_sel:[0,1] op_sel_hi:[1,0]
	v_pk_fma_f32 v[50:51], v[10:11], v[30:31], v[50:51] op_sel_hi:[0,1,1]
	v_pk_mul_f32 v[54:55], v[2:3], v[50:51] op_sel:[0,1] op_sel_hi:[1,0]
	v_pk_fma_f32 v[8:9], v[4:5], v[6:7], v[8:9] op_sel_hi:[0,1,1]
	v_pk_fma_f32 v[16:17], v[4:5], v[10:11], v[16:17] op_sel_hi:[0,1,1]
	v_pk_fma_f32 v[38:39], v[4:5], v[30:31], v[38:39] op_sel_hi:[0,1,1]
	v_pk_fma_f32 v[54:55], v[4:5], v[50:51], v[54:55] op_sel_hi:[0,1,1]
	v_and_b32_e32 v5, 0xffffff00, v36
	v_lshlrev_b32_e32 v36, 3, v5
	v_add3_u32 v36, 0, v66, v36
	v_ashrrev_i32_e32 v66, 2, v5
	v_add_u32_e32 v108, v36, v66
	ds_read2_b64 v[66:69], v108 offset1:16
	ds_read2_b64 v[70:73], v108 offset0:33 offset1:49
	ds_read2_b64 v[74:77], v108 offset0:66 offset1:82
	ds_read2_b64 v[78:81], v108 offset0:132 offset1:148
	ds_read2_b64 v[82:85], v108 offset0:99 offset1:115
	ds_read2_b64 v[86:89], v108 offset0:165 offset1:181
	ds_read2_b64 v[90:93], v108 offset0:198 offset1:214
	ds_read2_b64 v[94:97], v108 offset0:231 offset1:247
	s_waitcnt lgkmcnt(4)
	v_pk_add_f32 v[98:99], v[66:67], v[78:79]
	v_pk_add_f32 v[66:67], v[66:67], v[78:79] neg_lo:[0,1] neg_hi:[0,1]
	v_pk_add_f32 v[78:79], v[68:69], v[80:81]
	v_pk_add_f32 v[68:69], v[68:69], v[80:81] neg_lo:[0,1] neg_hi:[0,1]
	s_waitcnt lgkmcnt(1)
	v_pk_add_f32 v[100:101], v[76:77], v[92:93]
	v_pk_mul_f32 v[80:81], v[68:69], s[44:45]
	v_pk_add_f32 v[76:77], v[76:77], v[92:93] neg_lo:[0,1] neg_hi:[0,1]
	v_pk_fma_f32 v[68:69], v[68:69], s[42:43], v[80:81] op_sel:[0,0,1] op_sel_hi:[1,0,0]
	v_pk_add_f32 v[80:81], v[70:71], v[86:87]
	v_pk_add_f32 v[70:71], v[70:71], v[86:87] neg_lo:[0,1] neg_hi:[0,1]
	v_pk_mul_f32 v[92:93], v[76:77], s[76:77]
	v_pk_mul_f32 v[86:87], v[70:71], s[68:69]
	v_pk_fma_f32 v[76:77], v[76:77], s[72:73], v[92:93] op_sel:[0,0,1] op_sel_hi:[1,0,0] neg_lo:[1,0,0] neg_hi:[1,0,0]
	v_pk_fma_f32 v[70:71], v[70:71], s[64:65], v[86:87] op_sel:[0,0,1] op_sel_hi:[1,0,0]
	v_pk_add_f32 v[86:87], v[72:73], v[88:89]
	v_pk_add_f32 v[72:73], v[72:73], v[88:89] neg_lo:[0,1] neg_hi:[0,1]
	s_waitcnt lgkmcnt(0)
	v_pk_add_f32 v[92:93], v[82:83], v[94:95]
	v_pk_add_f32 v[82:83], v[82:83], v[94:95] neg_lo:[0,1] neg_hi:[0,1]
	v_pk_mul_f32 v[88:89], v[72:73], s[76:77]
	v_pk_mul_f32 v[94:95], v[82:83], s[68:69]
	v_pk_fma_f32 v[72:73], v[72:73], s[72:73], v[88:89] op_sel:[0,0,1] op_sel_hi:[1,0,0]
	v_pk_add_f32 v[88:89], v[74:75], v[90:91]
	v_pk_add_f32 v[90:91], v[74:75], v[90:91] neg_lo:[0,1] neg_hi:[0,1]
	v_pk_fma_f32 v[82:83], v[82:83], s[64:65], v[94:95] op_sel:[0,0,1] op_sel_hi:[1,0,0] neg_lo:[1,0,0] neg_hi:[1,0,0]
	v_pk_add_f32 v[94:95], v[84:85], v[96:97]
	v_pk_add_f32 v[84:85], v[84:85], v[96:97] op_sel:[1,1] op_sel_hi:[0,0] neg_lo:[0,1] neg_hi:[0,1]
	v_pk_mul_f32 v[96:97], v[84:85], s[44:45] op_sel:[1,0] op_sel_hi:[0,1]
	s_nop 0
	v_pk_fma_f32 v[84:85], v[84:85], s[42:43], v[96:97] op_sel:[1,0,1] op_sel_hi:[0,0,0] neg_lo:[1,0,0] neg_hi:[1,0,0]
	v_pk_add_f32 v[96:97], v[98:99], v[88:89]
	v_pk_add_f32 v[88:89], v[98:99], v[88:89] neg_lo:[0,1] neg_hi:[0,1]
	v_pk_add_f32 v[98:99], v[78:79], v[100:101]
	v_pk_add_f32 v[78:79], v[78:79], v[100:101] neg_lo:[0,1] neg_hi:[0,1]
	v_pk_add_f32 v[102:103], v[86:87], v[94:95]
	v_pk_add_f32 v[86:87], v[86:87], v[94:95] neg_lo:[0,1] neg_hi:[0,1]
	v_pk_add_f32 v[74:75], v[66:67], v[90:91] op_sel:[0,1] op_sel_hi:[1,0] neg_hi:[0,1]
	v_pk_add_f32 v[66:67], v[66:67], v[90:91] op_sel:[0,1] op_sel_hi:[1,0] neg_lo:[0,1]
	v_pk_add_f32 v[90:91], v[68:69], v[76:77]
	v_pk_add_f32 v[68:69], v[68:69], v[76:77] neg_lo:[0,1] neg_hi:[0,1]
	v_pk_mul_f32 v[100:101], v[78:79], s[68:69]
	v_pk_mul_f32 v[94:95], v[86:87], s[68:69]
	v_pk_mul_f32 v[76:77], v[68:69], s[68:69]
	v_pk_fma_f32 v[78:79], v[78:79], s[64:65], v[100:101] op_sel:[0,0,1] op_sel_hi:[1,0,0]
	v_pk_add_f32 v[100:101], v[80:81], v[92:93]
	v_pk_add_f32 v[92:93], v[80:81], v[92:93] neg_lo:[0,1] neg_hi:[0,1]
	v_pk_fma_f32 v[86:87], v[86:87], s[64:65], v[94:95] op_sel:[0,0,1] op_sel_hi:[1,0,0] neg_lo:[1,0,0] neg_hi:[1,0,0]
	v_pk_fma_f32 v[68:69], v[68:69], s[64:65], v[76:77] op_sel:[0,0,1] op_sel_hi:[1,0,0]
	v_pk_add_f32 v[76:77], v[70:71], v[82:83]
	v_pk_add_f32 v[94:95], v[72:73], v[84:85]
	v_pk_add_f32 v[72:73], v[72:73], v[84:85] neg_lo:[0,1] neg_hi:[0,1]
	v_pk_add_f32 v[70:71], v[70:71], v[82:83] neg_lo:[0,1] neg_hi:[0,1]
	v_pk_mul_f32 v[84:85], v[72:73], s[68:69]
	v_pk_add_f32 v[104:105], v[74:75], v[76:77]
	v_pk_add_f32 v[74:75], v[74:75], v[76:77] neg_lo:[0,1] neg_hi:[0,1]
	v_pk_add_f32 v[76:77], v[90:91], v[94:95]
	v_pk_add_f32 v[94:95], v[90:91], v[94:95] neg_lo:[0,1] neg_hi:[0,1]
	v_xor_b32_e32 v18, 0x80000000, v9
	v_mov_b32_e32 v19, v9
	v_pk_mul_f32 v[22:23], v[12:13], v[10:11] op_sel:[0,1] op_sel_hi:[1,0]
	v_xor_b32_e32 v83, 0x80000000, v70
	v_pk_fma_f32 v[72:73], v[72:73], s[64:65], v[84:85] op_sel:[0,0,1] op_sel_hi:[1,0,0] neg_lo:[1,0,0] neg_hi:[1,0,0]
	v_pk_add_f32 v[80:81], v[88:89], v[92:93] op_sel:[0,1] op_sel_hi:[1,0] neg_hi:[0,1]
	v_pk_add_f32 v[88:89], v[88:89], v[92:93] op_sel:[0,1] op_sel_hi:[1,0] neg_lo:[0,1]
	v_pk_add_f32 v[92:93], v[78:79], v[86:87]
	v_pk_add_f32 v[86:87], v[78:79], v[86:87] neg_lo:[0,1] neg_hi:[0,1]
	v_mov_b32_e32 v82, v71
	v_xor_b32_e32 v20, 0x80000000, v17
	v_mov_b32_e32 v21, v17
	v_pk_fma_f32 v[22:23], v[6:7], v[10:11], v[22:23] op_sel_hi:[0,1,1]
	v_pk_mul_f32 v[26:27], v[10:11], v[18:19] op_sel:[1,0] op_sel_hi:[0,1]
	v_pk_add_f32 v[70:71], v[66:67], v[82:83]
	v_pk_add_f32 v[66:67], v[66:67], v[82:83] neg_lo:[0,1] neg_hi:[0,1]
	v_pk_add_f32 v[82:83], v[68:69], v[72:73]
	v_pk_add_f32 v[72:73], v[68:69], v[72:73] neg_lo:[0,1] neg_hi:[0,1]
	v_pk_add_f32 v[90:91], v[74:75], v[94:95] op_sel:[0,1] op_sel_hi:[1,0] neg_hi:[0,1]
	v_xor_b32_e32 v24, 0x80000000, v23
	v_mov_b32_e32 v25, v23
	v_pk_fma_f32 v[26:27], v[10:11], v[8:9], v[26:27] op_sel_hi:[1,0,1]
	v_pk_add_f32 v[78:79], v[88:89], v[86:87] op_sel:[0,1] op_sel_hi:[1,0] neg_hi:[0,1]
	v_pk_add_f32 v[74:75], v[74:75], v[94:95] op_sel:[0,1] op_sel_hi:[1,0] neg_lo:[0,1]
	v_pk_mul_f32 v[94:95], v[20:21], v[90:91] op_sel:[0,1] op_sel_hi:[1,0]
	v_xor_b32_e32 v28, 0x80000000, v27
	v_mov_b32_e32 v29, v27
	v_pk_add_f32 v[84:85], v[96:97], v[100:101]
	v_pk_add_f32 v[96:97], v[96:97], v[100:101] neg_lo:[0,1] neg_hi:[0,1]
	v_pk_add_f32 v[100:101], v[98:99], v[102:103]
	v_pk_add_f32 v[68:69], v[66:67], v[72:73] op_sel:[0,1] op_sel_hi:[1,0] neg_hi:[0,1]
	v_pk_fma_f32 v[90:91], v[16:17], v[90:91], v[94:95] op_sel_hi:[0,1,1]
	v_pk_mul_f32 v[94:95], v[24:25], v[78:79] op_sel:[0,1] op_sel_hi:[1,0]
	v_xor_b32_e32 v32, 0x80000000, v31
	v_mov_b32_e32 v33, v31
	v_pk_mul_f32 v[42:43], v[12:13], v[30:31] op_sel:[0,1] op_sel_hi:[1,0]
	v_pk_add_f32 v[106:107], v[84:85], v[100:101]
	v_pk_add_f32 v[84:85], v[84:85], v[100:101] neg_lo:[0,1] neg_hi:[0,1]
	v_pk_fma_f32 v[78:79], v[22:23], v[78:79], v[94:95] op_sel_hi:[0,1,1]
	v_pk_mul_f32 v[94:95], v[28:29], v[68:69] op_sel:[0,1] op_sel_hi:[1,0]
	v_xor_b32_e32 v40, 0x80000000, v39
	v_mov_b32_e32 v41, v39
	v_pk_fma_f32 v[42:43], v[6:7], v[30:31], v[42:43] op_sel_hi:[0,1,1]
	v_pk_mul_f32 v[46:47], v[18:19], v[30:31] op_sel:[0,1] op_sel_hi:[1,0]
	v_pk_add_f32 v[86:87], v[88:89], v[86:87] op_sel:[0,1] op_sel_hi:[1,0] neg_lo:[0,1]
	v_pk_add_f32 v[88:89], v[104:105], v[76:77]
	v_pk_add_f32 v[76:77], v[104:105], v[76:77] neg_lo:[0,1] neg_hi:[0,1]
	v_pk_fma_f32 v[68:69], v[26:27], v[68:69], v[94:95] op_sel_hi:[0,1,1]
	v_pk_mul_f32 v[94:95], v[32:33], v[84:85] op_sel:[0,1] op_sel_hi:[1,0]
	v_xor_b32_e32 v44, 0x80000000, v43
	v_mov_b32_e32 v45, v43
	v_pk_fma_f32 v[46:47], v[8:9], v[30:31], v[46:47] op_sel_hi:[0,1,1]
	v_pk_add_f32 v[102:103], v[98:99], v[102:103] neg_lo:[0,1] neg_hi:[0,1]
	v_pk_add_f32 v[100:101], v[80:81], v[92:93]
	v_pk_add_f32 v[80:81], v[80:81], v[92:93] neg_lo:[0,1] neg_hi:[0,1]
	v_pk_fma_f32 v[84:85], v[30:31], v[84:85], v[94:95] op_sel_hi:[0,1,1]
	v_pk_mul_f32 v[94:95], v[40:41], v[76:77] op_sel:[0,1] op_sel_hi:[1,0]
	v_xor_b32_e32 v48, 0x80000000, v47
	v_mov_b32_e32 v49, v47
	v_pk_add_f32 v[92:93], v[70:71], v[82:83]
	v_pk_add_f32 v[70:71], v[70:71], v[82:83] neg_lo:[0,1] neg_hi:[0,1]
	v_pk_fma_f32 v[76:77], v[38:39], v[76:77], v[94:95] op_sel_hi:[0,1,1]
	v_pk_mul_f32 v[94:95], v[44:45], v[80:81] op_sel:[0,1] op_sel_hi:[1,0]
	v_xor_b32_e32 v52, 0x80000000, v51
	v_mov_b32_e32 v53, v51
	v_pk_mul_f32 v[58:59], v[12:13], v[50:51] op_sel:[0,1] op_sel_hi:[1,0]
	v_pk_add_f32 v[98:99], v[96:97], v[102:103] op_sel:[0,1] op_sel_hi:[1,0] neg_hi:[0,1]
	v_pk_add_f32 v[96:97], v[96:97], v[102:103] op_sel:[0,1] op_sel_hi:[1,0] neg_lo:[0,1]
	v_pk_fma_f32 v[80:81], v[42:43], v[80:81], v[94:95] op_sel_hi:[0,1,1]
	v_pk_mul_f32 v[94:95], v[48:49], v[70:71] op_sel:[0,1] op_sel_hi:[1,0]
	v_xor_b32_e32 v56, 0x80000000, v55
	v_mov_b32_e32 v57, v55
	v_pk_fma_f32 v[58:59], v[6:7], v[50:51], v[58:59] op_sel_hi:[0,1,1]
	v_pk_mul_f32 v[62:63], v[18:19], v[50:51] op_sel:[0,1] op_sel_hi:[1,0]
	v_pk_fma_f32 v[70:71], v[46:47], v[70:71], v[94:95] op_sel_hi:[0,1,1]
	v_pk_mul_f32 v[94:95], v[52:53], v[96:97] op_sel:[0,1] op_sel_hi:[1,0]
	v_xor_b32_e32 v60, 0x80000000, v59
	v_mov_b32_e32 v61, v59
	v_pk_fma_f32 v[62:63], v[8:9], v[50:51], v[62:63] op_sel_hi:[0,1,1]
	v_pk_add_f32 v[66:67], v[66:67], v[72:73] op_sel:[0,1] op_sel_hi:[1,0] neg_lo:[0,1]
	v_pk_mul_f32 v[72:73], v[2:3], v[88:89] op_sel:[0,1] op_sel_hi:[1,0]
	v_pk_fma_f32 v[94:95], v[50:51], v[96:97], v[94:95] op_sel_hi:[0,1,1]
	v_pk_mul_f32 v[96:97], v[56:57], v[74:75] op_sel:[0,1] op_sel_hi:[1,0]
	v_xor_b32_e32 v64, 0x80000000, v63
	v_mov_b32_e32 v65, v63
	v_pk_fma_f32 v[72:73], v[4:5], v[88:89], v[72:73] op_sel_hi:[0,1,1]
	v_pk_mul_f32 v[88:89], v[18:19], v[92:93] op_sel:[0,1] op_sel_hi:[1,0]
	v_pk_fma_f32 v[74:75], v[54:55], v[74:75], v[96:97] op_sel_hi:[0,1,1]
	v_pk_mul_f32 v[96:97], v[60:61], v[86:87] op_sel:[0,1] op_sel_hi:[1,0]
	v_add_u32_e32 v5, 0x2000, v5
	v_pk_mul_f32 v[82:83], v[12:13], v[100:101] op_sel:[0,1] op_sel_hi:[1,0]
	v_pk_fma_f32 v[88:89], v[8:9], v[92:93], v[88:89] op_sel_hi:[0,1,1]
	v_pk_mul_f32 v[92:93], v[14:15], v[98:99] op_sel:[0,1] op_sel_hi:[1,0]
	v_pk_fma_f32 v[86:87], v[58:59], v[86:87], v[96:97] op_sel_hi:[0,1,1]
	v_pk_mul_f32 v[96:97], v[64:65], v[66:67] op_sel:[0,1] op_sel_hi:[1,0]
	v_ashrrev_i32_e32 v5, 2, v5
	v_pk_fma_f32 v[82:83], v[6:7], v[100:101], v[82:83] op_sel_hi:[0,1,1]
	v_pk_fma_f32 v[92:93], v[10:11], v[98:99], v[92:93] op_sel_hi:[0,1,1]
	v_pk_fma_f32 v[66:67], v[62:63], v[66:67], v[96:97] op_sel_hi:[0,1,1]
	ds_write2_b64 v108, v[106:107], v[84:85] offset1:16
	ds_write2_b64 v108, v[92:93], v[94:95] offset0:33 offset1:49
	ds_write2_b64 v108, v[82:83], v[80:81] offset0:66 offset1:82
	ds_write2_b64 v108, v[78:79], v[86:87] offset0:99 offset1:115
	ds_write2_b64 v108, v[72:73], v[76:77] offset0:132 offset1:148
	ds_write2_b64 v108, v[90:91], v[74:75] offset0:165 offset1:181
	ds_write2_b64 v108, v[88:89], v[70:71] offset0:198 offset1:214
	ds_write2_b64 v108, v[68:69], v[66:67] offset0:231 offset1:247
	v_add3_u32 v36, v36, v5, s30
	ds_read2_b64 v[66:69], v36 offset1:16
	ds_read2_b64 v[70:73], v36 offset0:33 offset1:49
	ds_read2_b64 v[74:77], v36 offset0:66 offset1:82
	ds_read2_b64 v[78:81], v36 offset0:132 offset1:148
	ds_read2_b64 v[82:85], v36 offset0:99 offset1:115
	ds_read2_b64 v[86:89], v36 offset0:165 offset1:181
	ds_read2_b64 v[90:93], v36 offset0:198 offset1:214
	ds_read2_b64 v[94:97], v36 offset0:231 offset1:247
	s_waitcnt lgkmcnt(4)
	v_pk_add_f32 v[98:99], v[66:67], v[78:79]
	v_pk_add_f32 v[66:67], v[66:67], v[78:79] neg_lo:[0,1] neg_hi:[0,1]
	v_pk_add_f32 v[78:79], v[68:69], v[80:81]
	v_pk_add_f32 v[68:69], v[68:69], v[80:81] neg_lo:[0,1] neg_hi:[0,1]
	s_waitcnt lgkmcnt(1)
	v_pk_add_f32 v[100:101], v[76:77], v[92:93]
	v_pk_mul_f32 v[80:81], v[68:69], s[44:45]
	v_pk_add_f32 v[76:77], v[76:77], v[92:93] neg_lo:[0,1] neg_hi:[0,1]
	v_pk_fma_f32 v[68:69], v[68:69], s[42:43], v[80:81] op_sel:[0,0,1] op_sel_hi:[1,0,0]
	v_pk_add_f32 v[80:81], v[70:71], v[86:87]
	v_pk_add_f32 v[70:71], v[70:71], v[86:87] neg_lo:[0,1] neg_hi:[0,1]
	v_pk_mul_f32 v[92:93], v[76:77], s[76:77]
	v_pk_mul_f32 v[86:87], v[70:71], s[68:69]
	v_pk_fma_f32 v[76:77], v[76:77], s[72:73], v[92:93] op_sel:[0,0,1] op_sel_hi:[1,0,0] neg_lo:[1,0,0] neg_hi:[1,0,0]
	s_waitcnt lgkmcnt(0)
	v_pk_add_f32 v[92:93], v[82:83], v[94:95]
	v_pk_add_f32 v[82:83], v[82:83], v[94:95] neg_lo:[0,1] neg_hi:[0,1]
	v_pk_fma_f32 v[70:71], v[70:71], s[64:65], v[86:87] op_sel:[0,0,1] op_sel_hi:[1,0,0]
	v_pk_add_f32 v[86:87], v[72:73], v[88:89]
	v_pk_add_f32 v[72:73], v[72:73], v[88:89] neg_lo:[0,1] neg_hi:[0,1]
	v_pk_mul_f32 v[94:95], v[82:83], s[68:69]
	v_pk_mul_f32 v[88:89], v[72:73], s[76:77]
	v_pk_fma_f32 v[82:83], v[82:83], s[64:65], v[94:95] op_sel:[0,0,1] op_sel_hi:[1,0,0] neg_lo:[1,0,0] neg_hi:[1,0,0]
	v_pk_add_f32 v[94:95], v[84:85], v[96:97]
	v_pk_add_f32 v[84:85], v[84:85], v[96:97] neg_lo:[0,1] neg_hi:[0,1]
	v_pk_fma_f32 v[72:73], v[72:73], s[72:73], v[88:89] op_sel:[0,0,1] op_sel_hi:[1,0,0]
	v_pk_add_f32 v[88:89], v[74:75], v[90:91]
	v_pk_mul_f32 v[96:97], v[84:85], s[44:45]
	v_pk_add_f32 v[90:91], v[74:75], v[90:91] neg_lo:[0,1] neg_hi:[0,1]
	v_pk_fma_f32 v[84:85], v[84:85], s[42:43], v[96:97] op_sel:[0,0,1] op_sel_hi:[1,0,0] neg_lo:[1,0,0] neg_hi:[1,0,0]
	v_pk_add_f32 v[96:97], v[98:99], v[88:89]
	v_pk_add_f32 v[88:89], v[98:99], v[88:89] neg_lo:[0,1] neg_hi:[0,1]
	v_pk_add_f32 v[98:99], v[78:79], v[100:101]
	v_pk_add_f32 v[78:79], v[78:79], v[100:101] neg_lo:[0,1] neg_hi:[0,1]
	v_pk_add_f32 v[102:103], v[86:87], v[94:95]
	v_pk_add_f32 v[86:87], v[86:87], v[94:95] neg_lo:[0,1] neg_hi:[0,1]
	v_pk_mul_f32 v[100:101], v[78:79], s[68:69]
	v_pk_mul_f32 v[94:95], v[86:87], s[68:69]
	v_pk_fma_f32 v[78:79], v[78:79], s[64:65], v[100:101] op_sel:[0,0,1] op_sel_hi:[1,0,0]
	v_pk_add_f32 v[100:101], v[80:81], v[92:93]
	v_pk_add_f32 v[92:93], v[80:81], v[92:93] neg_lo:[0,1] neg_hi:[0,1]
	v_pk_fma_f32 v[86:87], v[86:87], s[64:65], v[94:95] op_sel:[0,0,1] op_sel_hi:[1,0,0] neg_lo:[1,0,0] neg_hi:[1,0,0]
	v_pk_add_f32 v[74:75], v[66:67], v[90:91] op_sel:[0,1] op_sel_hi:[1,0] neg_hi:[0,1]
	v_pk_add_f32 v[66:67], v[66:67], v[90:91] op_sel:[0,1] op_sel_hi:[1,0] neg_lo:[0,1]
	v_pk_add_f32 v[90:91], v[68:69], v[76:77]
	v_pk_add_f32 v[68:69], v[68:69], v[76:77] neg_lo:[0,1] neg_hi:[0,1]
	v_pk_add_f32 v[94:95], v[72:73], v[84:85]
	v_pk_add_f32 v[72:73], v[72:73], v[84:85] neg_lo:[0,1] neg_hi:[0,1]
	v_pk_mul_f32 v[76:77], v[68:69], s[68:69]
	v_pk_mul_f32 v[84:85], v[72:73], s[68:69]
	v_pk_fma_f32 v[68:69], v[68:69], s[64:65], v[76:77] op_sel:[0,0,1] op_sel_hi:[1,0,0]
	v_pk_add_f32 v[76:77], v[70:71], v[82:83]
	v_pk_fma_f32 v[72:73], v[72:73], s[64:65], v[84:85] op_sel:[0,0,1] op_sel_hi:[1,0,0] neg_lo:[1,0,0] neg_hi:[1,0,0]
	v_pk_add_f32 v[80:81], v[88:89], v[92:93] op_sel:[0,1] op_sel_hi:[1,0] neg_hi:[0,1]
	v_pk_add_f32 v[88:89], v[88:89], v[92:93] op_sel:[0,1] op_sel_hi:[1,0] neg_lo:[0,1]
	v_pk_add_f32 v[92:93], v[78:79], v[86:87]
	v_pk_add_f32 v[86:87], v[78:79], v[86:87] neg_lo:[0,1] neg_hi:[0,1]
	s_add_i32 s65, s65, s28
	v_pk_add_f32 v[82:83], v[70:71], v[82:83] neg_lo:[0,1] neg_hi:[0,1]
	s_nop 0
	v_pk_add_f32 v[104:105], v[74:75], v[76:77]
	v_pk_add_f32 v[74:75], v[74:75], v[76:77] neg_lo:[0,1] neg_hi:[0,1]
	v_pk_add_f32 v[76:77], v[90:91], v[94:95]
	s_cmpk_gt_i32 s65, 0x3ff
	s_nop 0
	v_pk_add_f32 v[84:85], v[96:97], v[100:101]
	v_pk_add_f32 v[96:97], v[96:97], v[100:101] neg_lo:[0,1] neg_hi:[0,1]
	v_pk_add_f32 v[100:101], v[98:99], v[102:103]
	s_nop 0
	v_pk_add_f32 v[78:79], v[88:89], v[86:87] op_sel:[0,1] op_sel_hi:[1,0] neg_hi:[0,1]
	v_pk_add_f32 v[86:87], v[88:89], v[86:87] op_sel:[0,1] op_sel_hi:[1,0] neg_lo:[0,1]
	v_pk_add_f32 v[88:89], v[104:105], v[76:77]
	s_cselect_b64 s[80:81], -1, 0
	s_cmpk_lt_i32 s65, 0x400
	v_pk_add_f32 v[98:99], v[98:99], v[102:103] neg_lo:[0,1] neg_hi:[0,1]
	v_pk_add_f32 v[70:71], v[66:67], v[82:83] op_sel:[0,1] op_sel_hi:[1,0] neg_hi:[0,1]
	v_pk_add_f32 v[66:67], v[66:67], v[82:83] op_sel:[0,1] op_sel_hi:[1,0] neg_lo:[0,1]
	v_pk_add_f32 v[82:83], v[68:69], v[72:73]
	v_pk_add_f32 v[106:107], v[84:85], v[100:101]
	v_pk_add_f32 v[84:85], v[84:85], v[100:101] neg_lo:[0,1] neg_hi:[0,1]
	v_pk_add_f32 v[100:101], v[80:81], v[92:93]
	v_pk_mul_f32 v[2:3], v[2:3], v[88:89] op_sel:[0,1] op_sel_hi:[1,0]
	s_cselect_b32 s6, s65, s6
	v_xor_b32_e32 v103, 0x80000000, v98
	v_pk_add_f32 v[90:91], v[90:91], v[94:95] neg_lo:[0,1] neg_hi:[0,1]
	v_mov_b32_e32 v102, v99
	v_pk_add_f32 v[80:81], v[80:81], v[92:93] neg_lo:[0,1] neg_hi:[0,1]
	v_pk_add_f32 v[92:93], v[70:71], v[82:83]
	v_pk_fma_f32 v[2:3], v[4:5], v[88:89], v[2:3] op_sel_hi:[0,1,1]
	v_pk_mul_f32 v[4:5], v[12:13], v[100:101] op_sel:[0,1] op_sel_hi:[1,0]
	s_lshl_b32 s8, s6, 1
	s_lshl_b32 s6, s6, 2
	v_xor_b32_e32 v95, 0x80000000, v90
	v_pk_add_f32 v[68:69], v[68:69], v[72:73] neg_lo:[0,1] neg_hi:[0,1]
	v_pk_add_f32 v[98:99], v[96:97], v[102:103]
	v_mov_b32_e32 v94, v91
	v_pk_fma_f32 v[4:5], v[6:7], v[100:101], v[4:5] op_sel_hi:[0,1,1]
	v_pk_mul_f32 v[6:7], v[18:19], v[92:93] op_sel:[0,1] op_sel_hi:[1,0]
	s_and_b32 s7, s8, 0x3fe
	s_and_b32 s6, s6, 0xfffff800
	v_xor_b32_e32 v73, 0x80000000, v68
	v_pk_add_f32 v[90:91], v[74:75], v[94:95]
	v_mov_b32_e32 v72, v69
	v_pk_fma_f32 v[6:7], v[8:9], v[92:93], v[6:7] op_sel_hi:[0,1,1]
	v_pk_mul_f32 v[8:9], v[14:15], v[98:99] op_sel:[0,1] op_sel_hi:[1,0]
	s_or_b32 s6, s7, s6
	v_pk_add_f32 v[68:69], v[66:67], v[72:73]
	v_pk_fma_f32 v[8:9], v[10:11], v[98:99], v[8:9] op_sel_hi:[0,1,1]
	v_pk_mul_f32 v[10:11], v[20:21], v[90:91] op_sel:[0,1] op_sel_hi:[1,0]
	s_ashr_i32 s7, s6, 31
	v_pk_add_f32 v[96:97], v[96:97], v[102:103] neg_lo:[0,1] neg_hi:[0,1]
	v_pk_add_f32 v[76:77], v[104:105], v[76:77] neg_lo:[0,1] neg_hi:[0,1]
	v_pk_add_f32 v[74:75], v[74:75], v[94:95] neg_lo:[0,1] neg_hi:[0,1]
	v_pk_add_f32 v[70:71], v[70:71], v[82:83] neg_lo:[0,1] neg_hi:[0,1]
	v_pk_add_f32 v[66:67], v[66:67], v[72:73] neg_lo:[0,1] neg_hi:[0,1]
	v_pk_fma_f32 v[10:11], v[16:17], v[90:91], v[10:11] op_sel_hi:[0,1,1]
	v_pk_mul_f32 v[12:13], v[24:25], v[78:79] op_sel:[0,1] op_sel_hi:[1,0]
	v_pk_mul_f32 v[14:15], v[28:29], v[68:69] op_sel:[0,1] op_sel_hi:[1,0]
	v_pk_mul_f32 v[16:17], v[32:33], v[84:85] op_sel:[0,1] op_sel_hi:[1,0]
	s_lshl_b64 s[82:83], s[6:7], 14
	s_bitset1_b32 s6, 10
	v_pk_fma_f32 v[12:13], v[22:23], v[78:79], v[12:13] op_sel_hi:[0,1,1]
	v_pk_fma_f32 v[14:15], v[26:27], v[68:69], v[14:15] op_sel_hi:[0,1,1]
	v_pk_fma_f32 v[16:17], v[30:31], v[84:85], v[16:17] op_sel_hi:[0,1,1]
	v_pk_mul_f32 v[18:19], v[40:41], v[76:77] op_sel:[0,1] op_sel_hi:[1,0]
	v_pk_mul_f32 v[20:21], v[44:45], v[80:81] op_sel:[0,1] op_sel_hi:[1,0]
	v_pk_mul_f32 v[22:23], v[48:49], v[70:71] op_sel:[0,1] op_sel_hi:[1,0]
	v_pk_mul_f32 v[24:25], v[52:53], v[96:97] op_sel:[0,1] op_sel_hi:[1,0]
	v_pk_mul_f32 v[26:27], v[56:57], v[74:75] op_sel:[0,1] op_sel_hi:[1,0]
	v_pk_mul_f32 v[28:29], v[60:61], v[86:87] op_sel:[0,1] op_sel_hi:[1,0]
	v_pk_mul_f32 v[30:31], v[64:65], v[66:67] op_sel:[0,1] op_sel_hi:[1,0]
	s_ashr_i32 s7, s6, 31
	v_pk_fma_f32 v[18:19], v[38:39], v[76:77], v[18:19] op_sel_hi:[0,1,1]
	v_pk_fma_f32 v[20:21], v[42:43], v[80:81], v[20:21] op_sel_hi:[0,1,1]
	v_pk_fma_f32 v[22:23], v[46:47], v[70:71], v[22:23] op_sel_hi:[0,1,1]
	v_pk_fma_f32 v[24:25], v[50:51], v[96:97], v[24:25] op_sel_hi:[0,1,1]
	v_pk_fma_f32 v[26:27], v[54:55], v[74:75], v[26:27] op_sel_hi:[0,1,1]
	v_pk_fma_f32 v[28:29], v[58:59], v[86:87], v[28:29] op_sel_hi:[0,1,1]
	v_pk_fma_f32 v[30:31], v[62:63], v[66:67], v[30:31] op_sel_hi:[0,1,1]
	ds_write2_b64 v36, v[106:107], v[16:17] offset1:16
	ds_write2_b64 v36, v[8:9], v[24:25] offset0:33 offset1:49
	ds_write2_b64 v36, v[4:5], v[20:21] offset0:66 offset1:82
	ds_write2_b64 v36, v[12:13], v[28:29] offset0:99 offset1:115
	ds_write2_b64 v36, v[2:3], v[18:19] offset0:132 offset1:148
	ds_write2_b64 v36, v[10:11], v[26:27] offset0:165 offset1:181
	ds_write2_b64 v36, v[6:7], v[22:23] offset0:198 offset1:214
	ds_write2_b64 v36, v[14:15], v[30:31] offset0:231 offset1:247
	s_lshl_b64 s[6:7], s[6:7], 14
	v_lshl_add_u64 v[2:3], v[34:35], 0, s[82:83]
	s_waitcnt lgkmcnt(0)
	s_barrier
	global_load_dwordx4 v[10:13], v[2:3], off nt
	global_load_dwordx4 v[30:33], v[2:3], off offset:16 nt
	v_lshl_add_u64 v[2:3], v[34:35], 0, s[6:7]
	global_load_dwordx4 v[26:29], v[2:3], off nt
	global_load_dwordx4 v[22:25], v[2:3], off offset:16 nt
	v_mov_b32_e32 v38, 0
	s_and_saveexec_b64 s[6:7], s[0:1]
	s_cbranch_execz .LBB0_430
	global_load_ushort v38, v[2:3], off offset:32

.LBB0_432:
	s_or_b64 exec, exec, s[6:7]
	v_mov_b32_e32 v36, v130
	s_mov_b32 s75, s42
	v_ashrrev_i32_e32 v40, 31, v36
	v_add_u32_sdwa v40, v36, v40 dst_sel:DWORD dst_unused:UNUSED_PAD src0_sel:DWORD src1_sel:BYTE_3
	v_ashrrev_i32_e32 v40, 8, v40
	v_mul_i32_i24_e32 v41, 0x100, v40
	v_sub_u32_e32 v66, v36, v41
	v_lshlrev_b32_e32 v41, 1, v66
	v_bfrev_b32_e32 v41, v41
	v_lshrrev_b32_e32 v41, 23, v41
	v_sub_u32_e32 v41, 0x200, v41
	v_bfrev_b32_e32 v41, v41
	v_lshrrev_b32_e32 v41, 19, v41
	v_and_b32_e32 v41, 0x1ff0, v41
	v_cmp_eq_u32_e64 s[6:7], 0, v66
	v_lshlrev_b32_e32 v40, 13, v40
	v_lshl_add_u32 v42, v66, 5, v40
	v_cndmask_b32_e64 v41, v41, 16, s[6:7]
	v_or_b32_e32 v40, v41, v40
	v_lshlrev_b32_e32 v43, 3, v42
	v_ashrrev_i32_e32 v42, 2, v42
	v_ashrrev_i32_e32 v41, 5, v40
	v_add3_u32 v88, 0, v43, v42
	v_lshlrev_b32_e32 v40, 3, v40
	v_lshlrev_b32_e32 v41, 3, v41
	v_add_u32_e32 v36, 0xffffff00, v36
	v_add3_u32 v40, 0, v40, v41
	ds_read2_b64 v[42:45], v88 offset1:1
	ds_read2_b64 v[46:49], v88 offset0:2 offset1:3
	ds_read2_b64 v[72:75], v40 offset1:1
	ds_read2_b64 v[76:79], v40 offset0:2 offset1:3
	ds_read2_b64 v[50:53], v88 offset0:4 offset1:5
	ds_read2_b64 v[54:57], v88 offset0:6 offset1:7
	ds_read2_b64 v[80:83], v40 offset0:4 offset1:5
	ds_read2_b64 v[84:87], v40 offset0:6 offset1:7
	ds_read2_b64 v[58:61], v88 offset0:8 offset1:9
	ds_read2_b64 v[62:65], v88 offset0:10 offset1:11
	ds_read2_b64 v[96:99], v40 offset0:8 offset1:9
	ds_read2_b64 v[100:103], v40 offset0:10 offset1:11
	ds_read2_b64 v[68:71], v88 offset0:12 offset1:13
	ds_read2_b64 v[88:91], v88 offset0:14 offset1:15
	ds_read2_b64 v[104:107], v40 offset0:12 offset1:13
	ds_read2_b64 v[108:111], v40 offset0:14 offset1:15
	v_mov_b32_e32 v40, s16
	v_cmp_gt_u32_e64 s[8:9], s33, v36
	s_waitcnt lgkmcnt(7)
	v_pk_add_f32 v[92:93], v[42:43], v[58:59]
	v_pk_add_f32 v[42:43], v[42:43], v[58:59] neg_lo:[0,1] neg_hi:[0,1]
	v_pk_add_f32 v[58:59], v[44:45], v[60:61]
	v_pk_add_f32 v[44:45], v[44:45], v[60:61] neg_lo:[0,1] neg_hi:[0,1]
	v_addc_co_u32_e64 v40, s[8:9], 0, v40, s[8:9]
	v_pk_mul_f32 v[60:61], v[44:45], s[44:45]
	s_waitcnt lgkmcnt(3)
	v_pk_add_f32 v[94:95], v[52:53], v[70:71]
	v_pk_add_f32 v[52:53], v[52:53], v[70:71] neg_lo:[0,1] neg_hi:[0,1]
	v_pk_fma_f32 v[44:45], v[44:45], s[42:43], v[60:61] op_sel:[0,0,1] op_sel_hi:[1,0,0]
	v_pk_add_f32 v[60:61], v[46:47], v[62:63]
	v_pk_add_f32 v[46:47], v[46:47], v[62:63] neg_lo:[0,1] neg_hi:[0,1]
	s_mov_b32 s67, s64
	s_mov_b32 s8, s45
	v_pk_mul_f32 v[70:71], v[52:53], s[74:75]
	v_pk_mul_f32 v[62:63], v[46:47], s[66:67]
	v_pk_fma_f32 v[52:53], v[52:53], s[8:9], v[70:71] op_sel:[0,0,1] op_sel_hi:[1,0,0] neg_lo:[1,0,0] neg_hi:[1,0,0]
	s_waitcnt lgkmcnt(2)
	v_pk_add_f32 v[70:71], v[54:55], v[88:89]
	v_pk_add_f32 v[54:55], v[54:55], v[88:89] neg_lo:[0,1] neg_hi:[0,1]
	v_pk_fma_f32 v[46:47], v[46:47], s[64:65], v[62:63] op_sel:[0,0,1] op_sel_hi:[1,0,0]
	v_pk_add_f32 v[62:63], v[48:49], v[64:65]
	v_pk_add_f32 v[48:49], v[48:49], v[64:65] neg_lo:[0,1] neg_hi:[0,1]
	v_pk_mul_f32 v[88:89], v[54:55], s[66:67]
	v_pk_mul_f32 v[64:65], v[48:49], s[74:75]
	v_pk_fma_f32 v[54:55], v[54:55], s[64:65], v[88:89] op_sel:[0,0,1] op_sel_hi:[1,0,0] neg_lo:[1,0,0] neg_hi:[1,0,0]
	v_pk_add_f32 v[88:89], v[56:57], v[90:91]
	v_pk_add_f32 v[56:57], v[56:57], v[90:91] neg_lo:[0,1] neg_hi:[0,1]
	v_pk_fma_f32 v[48:49], v[48:49], s[8:9], v[64:65] op_sel:[0,0,1] op_sel_hi:[1,0,0]
	v_pk_add_f32 v[64:65], v[50:51], v[68:69]
	v_pk_add_f32 v[50:51], v[50:51], v[68:69] neg_lo:[0,1] neg_hi:[0,1]
	v_pk_mul_f32 v[90:91], v[56:57], s[44:45]
	v_pk_add_f32 v[112:113], v[62:63], v[88:89]
	v_pk_add_f32 v[62:63], v[62:63], v[88:89] neg_lo:[0,1] neg_hi:[0,1]
	v_xor_b32_e32 v69, 0x80000000, v50
	v_pk_fma_f32 v[56:57], v[56:57], s[42:43], v[90:91] op_sel:[0,0,1] op_sel_hi:[1,0,0] neg_lo:[1,0,0] neg_hi:[1,0,0]
	v_pk_add_f32 v[90:91], v[92:93], v[64:65]
	v_pk_add_f32 v[64:65], v[92:93], v[64:65] neg_lo:[0,1] neg_hi:[0,1]
	v_pk_add_f32 v[92:93], v[58:59], v[94:95]
	v_pk_add_f32 v[58:59], v[58:59], v[94:95] neg_lo:[0,1] neg_hi:[0,1]
	v_pk_mul_f32 v[88:89], v[62:63], s[66:67]
	v_mov_b32_e32 v68, v51
	v_pk_mul_f32 v[94:95], v[58:59], s[66:67]
	v_pk_fma_f32 v[62:63], v[62:63], s[64:65], v[88:89] op_sel:[0,0,1] op_sel_hi:[1,0,0] neg_lo:[1,0,0] neg_hi:[1,0,0]
	v_pk_add_f32 v[50:51], v[42:43], v[68:69]
	v_pk_add_f32 v[42:43], v[42:43], v[68:69] neg_lo:[0,1] neg_hi:[0,1]
	v_pk_add_f32 v[68:69], v[44:45], v[52:53]
	v_pk_add_f32 v[44:45], v[44:45], v[52:53] neg_lo:[0,1] neg_hi:[0,1]
	v_pk_add_f32 v[88:89], v[48:49], v[56:57]
	v_pk_add_f32 v[48:49], v[48:49], v[56:57] neg_lo:[0,1] neg_hi:[0,1]
	v_pk_fma_f32 v[58:59], v[58:59], s[64:65], v[94:95] op_sel:[0,0,1] op_sel_hi:[1,0,0]
	v_pk_add_f32 v[94:95], v[60:61], v[70:71]
	v_pk_mul_f32 v[52:53], v[44:45], s[66:67]
	v_pk_mul_f32 v[56:57], v[48:49], s[66:67]
	v_pk_fma_f32 v[44:45], v[44:45], s[64:65], v[52:53] op_sel:[0,0,1] op_sel_hi:[1,0,0]
	v_pk_add_f32 v[52:53], v[46:47], v[54:55]
	v_pk_fma_f32 v[48:49], v[48:49], s[64:65], v[56:57] op_sel:[0,0,1] op_sel_hi:[1,0,0] neg_lo:[1,0,0] neg_hi:[1,0,0]
	v_pk_add_f32 v[56:57], v[90:91], v[94:95]
	v_pk_add_f32 v[114:115], v[90:91], v[94:95] neg_lo:[0,1] neg_hi:[0,1]
	v_pk_add_f32 v[90:91], v[92:93], v[112:113]
	v_pk_add_f32 v[112:113], v[92:93], v[112:113] neg_lo:[0,1] neg_hi:[0,1]
	v_pk_add_f32 v[122:123], v[50:51], v[52:53]
	v_pk_add_f32 v[50:51], v[50:51], v[52:53] neg_lo:[0,1] neg_hi:[0,1]
	v_pk_add_f32 v[52:53], v[68:69], v[88:89]
	v_pk_add_f32 v[88:89], v[68:69], v[88:89] neg_lo:[0,1] neg_hi:[0,1]
	v_pk_add_f32 v[92:93], v[74:75], v[98:99]
	v_pk_add_f32 v[74:75], v[74:75], v[98:99] neg_lo:[0,1] neg_hi:[0,1]
	v_xor_b32_e32 v125, 0x80000000, v88
	v_mov_b32_e32 v124, v89
	v_pk_add_f32 v[88:89], v[72:73], v[96:97]
	v_pk_add_f32 v[72:73], v[72:73], v[96:97] neg_lo:[0,1] neg_hi:[0,1]
	v_pk_mul_f32 v[96:97], v[74:75], s[44:45]
	v_bfrev_b32_e32 v36, v66
	v_pk_fma_f32 v[74:75], v[74:75], s[42:43], v[96:97] op_sel:[0,0,1] op_sel_hi:[1,0,0]
	v_pk_add_f32 v[96:97], v[76:77], v[100:101]
	v_pk_add_f32 v[76:77], v[76:77], v[100:101] neg_lo:[0,1] neg_hi:[0,1]
	v_ashrrev_i32_e32 v41, 31, v40
	v_pk_mul_f32 v[98:99], v[76:77], s[66:67]
	v_cvt_f32_ubyte3_e32 v36, v36
	v_pk_fma_f32 v[76:77], v[76:77], s[64:65], v[98:99] op_sel:[0,0,1] op_sel_hi:[1,0,0]
	v_pk_add_f32 v[98:99], v[78:79], v[102:103]
	v_pk_add_f32 v[78:79], v[78:79], v[102:103] neg_lo:[0,1] neg_hi:[0,1]
	v_lshlrev_b64 v[40:41], 15, v[40:41]
	v_pk_mul_f32 v[100:101], v[78:79], s[74:75]
	v_mul_f32_e32 v36, 0x38800000, v36
	v_pk_fma_f32 v[78:79], v[78:79], s[8:9], v[100:101] op_sel:[0,0,1] op_sel_hi:[1,0,0]
	s_waitcnt lgkmcnt(1)
	v_pk_add_f32 v[100:101], v[80:81], v[104:105]
	v_pk_add_f32 v[102:103], v[80:81], v[104:105] neg_lo:[0,1] neg_hi:[0,1]
	v_ashrrev_i32_e32 v67, 31, v66
	v_pk_add_f32 v[80:81], v[82:83], v[106:107]
	v_pk_add_f32 v[82:83], v[82:83], v[106:107] neg_lo:[0,1] neg_hi:[0,1]
	v_lshl_add_u64 v[40:41], s[18:19], 0, v[40:41]
	v_pk_mul_f32 v[104:105], v[82:83], s[74:75]
	v_pk_add_f32 v[60:61], v[60:61], v[70:71] neg_lo:[0,1] neg_hi:[0,1]
	v_pk_fma_f32 v[82:83], v[82:83], s[8:9], v[104:105] op_sel:[0,0,1] op_sel_hi:[1,0,0] neg_lo:[1,0,0] neg_hi:[1,0,0]
	s_waitcnt lgkmcnt(0)
	v_pk_add_f32 v[104:105], v[84:85], v[108:109]
	v_pk_add_f32 v[84:85], v[84:85], v[108:109] neg_lo:[0,1] neg_hi:[0,1]
	v_cndmask_b32_e64 v36, v36, v152, s[6:7]
	v_pk_mul_f32 v[106:107], v[84:85], s[66:67]
	v_lshl_add_u64 v[40:41], v[66:67], 3, v[40:41]
	v_pk_fma_f32 v[84:85], v[84:85], s[64:65], v[106:107] op_sel:[0,0,1] op_sel_hi:[1,0,0] neg_lo:[1,0,0] neg_hi:[1,0,0]
	v_pk_add_f32 v[106:107], v[86:87], v[110:111]
	v_pk_add_f32 v[86:87], v[86:87], v[110:111] neg_lo:[0,1] neg_hi:[0,1]
	v_xor_b32_e32 v71, 0x80000000, v60
	v_pk_mul_f32 v[108:109], v[86:87], s[44:45]
	v_pk_add_f32 v[46:47], v[46:47], v[54:55] neg_lo:[0,1] neg_hi:[0,1]
	v_pk_fma_f32 v[86:87], v[86:87], s[42:43], v[108:109] op_sel:[0,0,1] op_sel_hi:[1,0,0] neg_lo:[1,0,0] neg_hi:[1,0,0]
	v_pk_add_f32 v[108:109], v[88:89], v[100:101]
	v_pk_add_f32 v[88:89], v[88:89], v[100:101] neg_lo:[0,1] neg_hi:[0,1]
	v_pk_add_f32 v[100:101], v[92:93], v[80:81]
	v_pk_add_f32 v[80:81], v[92:93], v[80:81] neg_lo:[0,1] neg_hi:[0,1]
	v_mov_b32_e32 v70, v61
	v_pk_mul_f32 v[92:93], v[80:81], s[66:67]
	v_pk_add_f32 v[118:119], v[58:59], v[62:63]
	v_pk_fma_f32 v[80:81], v[80:81], s[64:65], v[92:93] op_sel:[0,0,1] op_sel_hi:[1,0,0]
	v_pk_add_f32 v[92:93], v[96:97], v[104:105]
	v_pk_add_f32 v[104:105], v[96:97], v[104:105] neg_lo:[0,1] neg_hi:[0,1]
	v_pk_add_f32 v[62:63], v[58:59], v[62:63] neg_lo:[0,1] neg_hi:[0,1]
	v_pk_add_f32 v[96:97], v[98:99], v[106:107]
	v_pk_add_f32 v[98:99], v[98:99], v[106:107] neg_lo:[0,1] neg_hi:[0,1]
	v_cos_f32_e32 v67, v36
	v_pk_mul_f32 v[106:107], v[98:99], s[66:67]
	v_cmp_ne_u32_e32 vcc, 0, v66
	v_pk_fma_f32 v[98:99], v[98:99], s[64:65], v[106:107] op_sel:[0,0,1] op_sel_hi:[1,0,0] neg_lo:[1,0,0] neg_hi:[1,0,0]
	v_pk_add_f32 v[106:107], v[72:73], v[102:103] op_sel:[0,1] op_sel_hi:[1,0] neg_hi:[0,1]
	v_pk_add_f32 v[72:73], v[72:73], v[102:103] op_sel:[0,1] op_sel_hi:[1,0] neg_lo:[0,1]
	v_pk_add_f32 v[102:103], v[74:75], v[82:83]
	v_pk_add_f32 v[74:75], v[74:75], v[82:83] neg_lo:[0,1] neg_hi:[0,1]
	v_xor_b32_e32 v55, 0x80000000, v46
	v_pk_mul_f32 v[82:83], v[74:75], s[66:67]
	v_pk_add_f32 v[116:117], v[64:65], v[70:71] neg_lo:[0,1] neg_hi:[0,1]
	v_pk_fma_f32 v[74:75], v[74:75], s[64:65], v[82:83] op_sel:[0,0,1] op_sel_hi:[1,0,0]
	v_pk_add_f32 v[82:83], v[76:77], v[84:85]
	v_pk_add_f32 v[84:85], v[76:77], v[84:85] neg_lo:[0,1] neg_hi:[0,1]
	v_xor_b32_e32 v121, 0x80000000, v62
	v_pk_add_f32 v[76:77], v[78:79], v[86:87]
	v_pk_add_f32 v[78:79], v[78:79], v[86:87] neg_lo:[0,1] neg_hi:[0,1]
	v_mov_b32_e32 v54, v47
	v_pk_mul_f32 v[86:87], v[78:79], s[66:67]
	v_mov_b32_e32 v120, v63
	v_pk_fma_f32 v[78:79], v[78:79], s[64:65], v[86:87] op_sel:[0,0,1] op_sel_hi:[1,0,0] neg_lo:[1,0,0] neg_hi:[1,0,0]
	v_pk_add_f32 v[86:87], v[108:109], v[92:93]
	v_pk_add_f32 v[92:93], v[108:109], v[92:93] neg_lo:[0,1] neg_hi:[0,1]
	v_pk_add_f32 v[108:109], v[100:101], v[96:97]
	v_pk_add_f32 v[96:97], v[100:101], v[96:97] neg_lo:[0,1] neg_hi:[0,1]
	v_sin_f32_e32 v66, v36
	v_pk_add_f32 v[60:61], v[64:65], v[70:71]
	v_pk_add_f32 v[126:127], v[42:43], v[54:55]
	v_pk_add_f32 v[128:129], v[42:43], v[54:55] neg_lo:[0,1] neg_hi:[0,1]
	v_pk_add_f32 v[42:43], v[44:45], v[48:49]
	v_pk_add_f32 v[48:49], v[44:45], v[48:49] neg_lo:[0,1] neg_hi:[0,1]
	v_pk_add_f32 v[94:95], v[56:57], v[90:91]
	v_pk_add_f32 v[90:91], v[56:57], v[90:91] neg_lo:[0,1] neg_hi:[0,1]
	v_pk_add_f32 v[70:71], v[114:115], v[112:113] op_sel:[0,1] op_sel_hi:[1,0] neg_hi:[0,1]
	v_pk_add_f32 v[64:65], v[114:115], v[112:113] op_sel:[0,1] op_sel_hi:[1,0] neg_lo:[0,1]
	v_pk_add_f32 v[56:57], v[116:117], v[120:121]
	v_pk_add_f32 v[62:63], v[116:117], v[120:121] neg_lo:[0,1] neg_hi:[0,1]
	v_xor_b32_e32 v101, 0x80000000, v96
	v_mov_b32_e32 v100, v97
	v_pk_add_f32 v[96:97], v[88:89], v[104:105] op_sel:[0,1] op_sel_hi:[1,0] neg_hi:[0,1]
	v_pk_add_f32 v[88:89], v[88:89], v[104:105] op_sel:[0,1] op_sel_hi:[1,0] neg_lo:[0,1]
	v_pk_add_f32 v[104:105], v[80:81], v[98:99]
	v_pk_add_f32 v[98:99], v[80:81], v[98:99] neg_lo:[0,1] neg_hi:[0,1]
	v_pk_add_f32 v[112:113], v[102:103], v[76:77]
	v_pk_add_f32 v[102:103], v[102:103], v[76:77] neg_lo:[0,1] neg_hi:[0,1]
	v_pk_add_f32 v[114:115], v[72:73], v[84:85] op_sel:[0,1] op_sel_hi:[1,0] neg_hi:[0,1]
	v_pk_add_f32 v[116:117], v[72:73], v[84:85] op_sel:[0,1] op_sel_hi:[1,0] neg_lo:[0,1]
	v_pk_add_f32 v[72:73], v[74:75], v[78:79] neg_lo:[0,1] neg_hi:[0,1]
	v_xor_b32_e32 v155, 0x80000000, v48
	v_pk_add_f32 v[68:69], v[60:61], v[118:119]
	v_pk_add_f32 v[58:59], v[60:61], v[118:119] neg_lo:[0,1] neg_hi:[0,1]
	v_mov_b32_e32 v154, v49
	v_pk_add_f32 v[110:111], v[106:107], v[82:83]
	v_pk_add_f32 v[106:107], v[106:107], v[82:83] neg_lo:[0,1] neg_hi:[0,1]
	v_pk_add_f32 v[118:119], v[74:75], v[78:79]
	v_xor_b32_e32 v121, 0x80000000, v72
	v_mov_b32_e32 v120, v73
	v_pk_add_f32 v[60:61], v[122:123], v[52:53]
	v_pk_add_f32 v[46:47], v[122:123], v[52:53] neg_lo:[0,1] neg_hi:[0,1]
	v_pk_add_f32 v[52:53], v[50:51], v[124:125]
	v_pk_add_f32 v[54:55], v[50:51], v[124:125] neg_lo:[0,1] neg_hi:[0,1]
	v_pk_add_f32 v[50:51], v[126:127], v[42:43]
	v_pk_add_f32 v[44:45], v[126:127], v[42:43] neg_lo:[0,1] neg_hi:[0,1]
	v_pk_add_f32 v[42:43], v[128:129], v[154:155]
	v_pk_add_f32 v[48:49], v[128:129], v[154:155] neg_lo:[0,1] neg_hi:[0,1]
	v_pk_add_f32 v[84:85], v[86:87], v[108:109]
	v_pk_add_f32 v[86:87], v[86:87], v[108:109] neg_lo:[0,1] neg_hi:[0,1]
	v_pk_add_f32 v[78:79], v[92:93], v[100:101]
	v_pk_add_f32 v[74:75], v[92:93], v[100:101] neg_lo:[0,1] neg_hi:[0,1]
	v_pk_add_f32 v[72:73], v[96:97], v[104:105]
	v_pk_add_f32 v[76:77], v[96:97], v[104:105] neg_lo:[0,1] neg_hi:[0,1]
	v_pk_add_f32 v[82:83], v[88:89], v[98:99] op_sel:[0,1] op_sel_hi:[1,0] neg_hi:[0,1]
	v_pk_add_f32 v[80:81], v[88:89], v[98:99] op_sel:[0,1] op_sel_hi:[1,0] neg_lo:[0,1]
	v_pk_add_f32 v[88:89], v[110:111], v[112:113]
	v_pk_add_f32 v[96:97], v[110:111], v[112:113] neg_lo:[0,1] neg_hi:[0,1]
	v_pk_add_f32 v[98:99], v[106:107], v[102:103] op_sel:[0,1] op_sel_hi:[1,0] neg_hi:[0,1]
	v_pk_add_f32 v[102:103], v[106:107], v[102:103] op_sel:[0,1] op_sel_hi:[1,0] neg_lo:[0,1]
	v_pk_add_f32 v[104:105], v[114:115], v[118:119]
	v_pk_add_f32 v[106:107], v[114:115], v[118:119] neg_lo:[0,1] neg_hi:[0,1]
	v_pk_add_f32 v[108:109], v[116:117], v[120:121]
	v_pk_add_f32 v[114:115], v[116:117], v[120:121] neg_lo:[0,1] neg_hi:[0,1]
	v_mul_f32_e32 v36, 0x3f3504f3, v67
	v_mul_f32_e32 v100, 0xbec3ef15, v67
	v_mul_f32_e32 v92, 0xbf6c835e, v67
	s_and_saveexec_b64 s[6:7], vcc
	s_xor_b64 s[6:7], exec, s[6:7]
	s_cbranch_execz .LBB0_434
	v_pk_add_f32 v[110:111], v[94:95], v[114:115]
	v_pk_add_f32 v[94:95], v[94:95], v[114:115] neg_lo:[0,1] neg_hi:[0,1]
	v_mul_f32_e32 v112, 0.5, v110
	v_pk_fma_f32 v[114:115], v[66:67], 0, v[66:67] op_sel:[0,0,1] op_sel_hi:[1,0,0] neg_lo:[1,0,0]
	v_mov_b32_e32 v110, v94
	v_pk_mul_f32 v[110:111], v[110:111], s[78:79]
	s_mov_b32 s8, s45
	v_pk_mul_f32 v[116:117], v[114:115], v[110:111] op_sel:[0,1] op_sel_hi:[1,0]
	v_pk_mul_f32 v[110:111], v[114:115], v[110:111]
	s_mov_b32 s9, s42
	v_sub_f32_e32 v93, v110, v111
	v_fma_mixlo_f16 v101, v95, s79, v93
	v_fma_f32 v93, v95, 0.5, -v93
	v_cvt_f16_f32_sdwa v93, -v93 dst_sel:WORD_1 dst_unused:UNUSED_PAD src0_sel:DWORD
	v_pk_add_f32 v[94:95], v[116:117], v[116:117] op_sel:[0,1] op_sel_hi:[0,1]
	v_pk_add_f32 v[110:111], v[112:113], v[94:95]
	v_pk_add_f32 v[94:95], v[112:113], v[94:95] op_sel_hi:[0,1] neg_lo:[0,1] neg_hi:[0,1]
	v_cvt_pk_f16_f32 v94, v110, v95
	v_lshlrev_b32_e32 v101, 16, v101
	v_or_b32_sdwa v95, v93, v94 dst_sel:DWORD dst_unused:UNUSED_PAD src0_sel:DWORD src1_sel:WORD_1
	v_or_b32_sdwa v94, v101, v94 dst_sel:DWORD dst_unused:UNUSED_PAD src0_sel:DWORD src1_sel:WORD_0
	global_store_dwordx2 v[40:41], v[94:95], off
	v_pk_add_f32 v[94:95], v[90:91], v[108:109]
	v_pk_add_f32 v[90:91], v[90:91], v[108:109] neg_lo:[0,1] neg_hi:[0,1]
	v_mul_f32_e32 v110, 0.5, v94
	v_mov_b32_e32 v94, v67
	v_mov_b32_e32 v108, v67
	v_mov_b32_e32 v109, v66
	v_pk_fma_f32 v[112:113], v[66:67], 0, v[108:109] op_sel_hi:[1,0,1] neg_lo:[0,0,1] neg_hi:[0,0,1]
	v_pk_fma_f32 v[114:115], v[66:67], 0, v[94:95] op_sel_hi:[1,0,1]
	v_mov_b32_e32 v94, v90
	v_pk_mov_b32 v[112:113], v[112:113], v[114:115] op_sel:[1,0]
	v_pk_mul_f32 v[94:95], v[94:95], s[78:79]
	s_mov_b32 s43, s45
	v_pk_mul_f32 v[114:115], v[112:113], v[94:95] op_sel:[0,1] op_sel_hi:[1,0]
	v_pk_mul_f32 v[94:95], v[112:113], v[94:95]
	v_pk_fma_f32 v[112:113], v[108:109], s[68:69], v[36:37] op_sel_hi:[1,1,0]
	v_sub_f32_e32 v90, v94, v95
	v_fma_mixlo_f16 v93, v91, s79, v90
	v_fma_f32 v90, v91, 0.5, -v90
	v_cvt_f16_f32_sdwa v101, -v90 dst_sel:WORD_1 dst_unused:UNUSED_PAD src0_sel:DWORD
	v_pk_add_f32 v[90:91], v[114:115], v[114:115] op_sel:[0,1] op_sel_hi:[0,1]
	v_pk_add_f32 v[94:95], v[110:111], v[90:91]
	v_pk_add_f32 v[90:91], v[110:111], v[90:91] op_sel_hi:[0,1] neg_lo:[0,1] neg_hi:[0,1]
	v_cvt_pk_f16_f32 v90, v94, v91
	v_lshlrev_b32_e32 v93, 16, v93
	v_or_b32_sdwa v91, v101, v90 dst_sel:DWORD dst_unused:UNUSED_PAD src0_sel:DWORD src1_sel:WORD_1
	v_or_b32_sdwa v90, v93, v90 dst_sel:DWORD dst_unused:UNUSED_PAD src0_sel:DWORD src1_sel:WORD_0
	global_store_dwordx2 v[40:41], v[90:91], off offset:2048
	v_pk_mul_f32 v[90:91], v[108:109], s[68:69]
	v_pk_add_f32 v[94:95], v[70:71], v[106:107]
	v_pk_add_f32 v[70:71], v[70:71], v[106:107] neg_lo:[0,1] neg_hi:[0,1]
	v_mul_f32_e32 v110, 0.5, v94
	v_pk_add_f32 v[106:107], v[36:37], v[90:91] op_sel:[0,1] op_sel_hi:[0,1] neg_lo:[0,1] neg_hi:[0,1]
	v_mov_b32_e32 v94, v70
	v_mov_b32_e32 v107, v113
	v_pk_mul_f32 v[94:95], v[94:95], s[78:79]
	v_mov_b32_e32 v101, v58
	v_pk_mul_f32 v[112:113], v[106:107], v[94:95] op_sel:[0,1] op_sel_hi:[1,0]
	v_pk_mul_f32 v[94:95], v[106:107], v[94:95]
	s_mov_b32 s39, s27
	v_sub_f32_e32 v36, v94, v95
	v_fma_mixlo_f16 v93, v71, s79, v36
	v_fma_f32 v36, v71, 0.5, -v36
	v_pk_add_f32 v[70:71], v[112:113], v[112:113] op_sel:[0,1] op_sel_hi:[0,1]
	v_cvt_f16_f32_sdwa v36, -v36 dst_sel:WORD_1 dst_unused:UNUSED_PAD src0_sel:DWORD
	v_pk_add_f32 v[94:95], v[110:111], v[70:71]
	v_pk_add_f32 v[70:71], v[110:111], v[70:71] op_sel_hi:[0,1] neg_lo:[0,1] neg_hi:[0,1]
	v_cvt_pk_f16_f32 v70, v94, v71
	v_add_co_u32_e32 v94, vcc, s34, v40
	v_lshlrev_b32_e32 v93, 16, v93
	s_nop 0
	v_addc_co_u32_e32 v95, vcc, 0, v41, vcc
	v_add_co_u32_e32 v110, vcc, s3, v40
	v_or_b32_sdwa v71, v36, v70 dst_sel:DWORD dst_unused:UNUSED_PAD src0_sel:DWORD src1_sel:WORD_1
	v_or_b32_sdwa v70, v93, v70 dst_sel:DWORD dst_unused:UNUSED_PAD src0_sel:DWORD src1_sel:WORD_0
	v_addc_co_u32_e32 v111, vcc, 0, v41, vcc
	global_store_dwordx2 v[110:111], v[70:71], off offset:-4096
	v_pk_fma_f32 v[70:71], v[108:109], s[68:69], v[90:91] op_sel:[0,0,1] op_sel_hi:[1,1,0] neg_lo:[0,0,1] neg_hi:[0,0,1]
	v_pk_add_f32 v[90:91], v[64:65], v[104:105]
	v_pk_add_f32 v[64:65], v[64:65], v[104:105] neg_lo:[0,1] neg_hi:[0,1]
	v_mul_f32_e32 v36, 0.5, v90
	v_mov_b32_e32 v90, v64
	v_pk_mul_f32 v[90:91], v[90:91], s[78:79]
	v_mov_b32_e32 v71, v106
	v_mov_b32_e32 v107, v70
	v_pk_mul_f32 v[70:71], v[70:71], v[90:91]
	v_pk_mul_f32 v[104:105], v[106:107], v[90:91]
	v_sub_f32_e32 v64, v70, v71
	v_fma_mixlo_f16 v90, v65, s79, v64
	v_fma_f32 v64, v65, 0.5, -v64
	v_cvt_f16_f32_sdwa v91, -v64 dst_sel:WORD_1 dst_unused:UNUSED_PAD src0_sel:DWORD
	v_pk_add_f32 v[64:65], v[104:105], v[104:105] op_sel:[1,0] op_sel_hi:[1,0]
	s_nop 0
	v_pk_add_f32 v[70:71], v[36:37], v[64:65]
	v_pk_add_f32 v[64:65], v[36:37], v[64:65] op_sel_hi:[0,1] neg_lo:[0,1] neg_hi:[0,1]
	v_cvt_pk_f16_f32 v36, v70, v65
	v_lshlrev_b32_e32 v64, 16, v90
	v_or_b32_sdwa v65, v91, v36 dst_sel:DWORD dst_unused:UNUSED_PAD src0_sel:DWORD src1_sel:WORD_1
	v_or_b32_sdwa v64, v64, v36 dst_sel:DWORD dst_unused:UNUSED_PAD src0_sel:DWORD src1_sel:WORD_0
	global_store_dwordx2 v[94:95], v[64:65], off offset:2048
	v_mov_b32_e32 v64, v67
	v_pk_mul_f32 v[70:71], v[66:67], s[8:9] op_sel_hi:[0,1]
	v_pk_add_f32 v[90:91], v[68:69], v[102:103]
	v_pk_add_f32 v[68:69], v[68:69], v[102:103] neg_lo:[0,1] neg_hi:[0,1]
	v_mul_f32_e32 v36, 0.5, v90
	v_pk_fma_f32 v[94:95], v[64:65], s[42:43], v[70:71] op_sel_hi:[0,1,1] neg_lo:[0,0,1] neg_hi:[0,0,1]
	v_pk_fma_f32 v[102:103], v[64:65], s[42:43], v[70:71] op_sel_hi:[0,1,1]
	v_mov_b32_e32 v90, v68
	v_mov_b32_e32 v104, v94
	v_mov_b32_e32 v105, v103
	v_pk_mul_f32 v[90:91], v[90:91], s[78:79]
	s_mov_b32 s8, s27
	v_pk_mul_f32 v[106:107], v[104:105], v[90:91] op_sel:[0,1] op_sel_hi:[1,0]
	v_pk_mul_f32 v[90:91], v[104:105], v[90:91]
	s_mov_b32 s9, s38
	v_sub_f32_e32 v65, v90, v91
	v_fma_mixlo_f16 v93, v69, s79, v65
	v_fma_f32 v65, v69, 0.5, -v65
	v_cvt_f16_f32_sdwa v65, -v65 dst_sel:WORD_1 dst_unused:UNUSED_PAD src0_sel:DWORD
	v_pk_add_f32 v[68:69], v[106:107], v[106:107] op_sel:[0,1] op_sel_hi:[0,1]
	v_pk_add_f32 v[90:91], v[36:37], v[68:69]
	v_pk_add_f32 v[68:69], v[36:37], v[68:69] op_sel_hi:[0,1] neg_lo:[0,1] neg_hi:[0,1]
	v_cvt_pk_f16_f32 v36, v90, v69
	v_lshlrev_b32_e32 v68, 16, v93
	v_or_b32_sdwa v69, v65, v36 dst_sel:DWORD dst_unused:UNUSED_PAD src0_sel:DWORD src1_sel:WORD_1
	v_or_b32_sdwa v68, v68, v36 dst_sel:DWORD dst_unused:UNUSED_PAD src0_sel:DWORD src1_sel:WORD_0
	global_store_dwordx2 v[110:111], v[68:69], off
	v_pk_add_f32 v[68:69], v[58:59], v[98:99]
	v_sub_f32_e32 v65, v59, v99
	v_pk_mov_b32 v[58:59], v[70:71], v[98:99] op_sel:[1,0]
	v_mul_f32_e32 v36, 0.5, v69
	v_pk_add_f32 v[58:59], v[100:101], v[58:59] neg_lo:[0,1] neg_hi:[0,1]
	v_mul_f32_e32 v90, 0.5, v68
	v_pk_mul_f32 v[98:99], v[58:59], v[36:37]
	v_mov_b32_e32 v93, v62
	v_mul_f32_e32 v58, v58, v99
	v_fma_f32 v36, -v94, v36, v58
	v_fma_mixlo_f16 v69, v65, s79, v36
	v_fma_f32 v36, v65, 0.5, -v36
	v_pk_fma_f32 v[100:101], v[94:95], v[98:99], v[98:99] op_sel:[0,1,0] op_sel_hi:[1,0,1]
	v_cvt_f16_f32_sdwa v36, -v36 dst_sel:WORD_1 dst_unused:UNUSED_PAD src0_sel:DWORD
	v_pk_add_f32 v[58:59], v[90:91], v[100:101]
	v_lshlrev_b32_e32 v65, 16, v69
	v_fma_f32 v59, v68, 0.5, -v100
	v_cvt_pk_f16_f32 v58, v58, v59
	v_or_b32_sdwa v59, v36, v58 dst_sel:DWORD dst_unused:UNUSED_PAD src0_sel:DWORD src1_sel:WORD_1
	v_or_b32_sdwa v58, v65, v58 dst_sel:DWORD dst_unused:UNUSED_PAD src0_sel:DWORD src1_sel:WORD_0
	global_store_dwordx2 v[110:111], v[58:59], off offset:2048
	v_pk_add_f32 v[58:59], v[96:97], v[56:57]
	v_pk_add_f32 v[56:57], v[56:57], v[96:97] neg_lo:[0,1] neg_hi:[0,1]
	v_mul_f32_e32 v36, 0.5, v58
	v_mov_b32_e32 v58, v56
	v_pk_mov_b32 v[68:69], v[94:95], v[102:103] op_sel:[1,0]
	v_pk_mul_f32 v[58:59], v[58:59], s[78:79] op_sel:[1,1] op_sel_hi:[0,0]
	v_pk_mul_f32 v[90:91], v[68:69], v[58:59]
	v_pk_mul_f32 v[58:59], v[58:59], v[68:69] op_sel:[1,0] op_sel_hi:[0,1]
	v_sub_f32_e32 v56, v58, v59
	v_fma_mixlo_f16 v65, v57, s79, v56
	v_fma_f32 v56, v57, 0.5, -v56
	v_cvt_f16_f32_sdwa v71, -v56 dst_sel:WORD_1 dst_unused:UNUSED_PAD src0_sel:DWORD
	v_pk_add_f32 v[56:57], v[90:91], v[90:91] op_sel:[0,1] op_sel_hi:[0,1]
	v_pk_add_f32 v[58:59], v[36:37], v[56:57]
	v_pk_add_f32 v[56:57], v[36:37], v[56:57] op_sel_hi:[0,1] neg_lo:[0,1] neg_hi:[0,1]
	v_cvt_pk_f16_f32 v36, v58, v57
	v_add_co_u32_e32 v58, vcc, s35, v40
	v_lshlrev_b32_e32 v56, 16, v65
	s_nop 0
	v_addc_co_u32_e32 v59, vcc, 0, v41, vcc
	v_add_co_u32_e32 v90, vcc, s37, v40
	v_or_b32_sdwa v57, v71, v36 dst_sel:DWORD dst_unused:UNUSED_PAD src0_sel:DWORD src1_sel:WORD_1
	v_or_b32_sdwa v56, v56, v36 dst_sel:DWORD dst_unused:UNUSED_PAD src0_sel:DWORD src1_sel:WORD_0
	v_addc_co_u32_e32 v91, vcc, 0, v41, vcc
	global_store_dwordx2 v[90:91], v[56:57], off offset:-4096
	v_pk_add_f32 v[56:57], v[88:89], v[62:63]
	v_mov_b32_e32 v71, v88
	v_sub_f32_e32 v65, v63, v89
	v_mul_f32_e32 v36, 0.5, v57
	v_pk_add_f32 v[62:63], v[92:93], v[70:71] neg_lo:[0,1] neg_hi:[0,1]
	v_mul_f32_e32 v94, 0.5, v56
	v_pk_mul_f32 v[70:71], v[62:63], v[36:37]
	s_nop 0
	v_mul_f32_e32 v57, v62, v71
	v_fma_f32 v36, -v95, v36, v57
	v_fma_mixlo_f16 v57, v65, s79, v36
	v_fma_f32 v36, v65, 0.5, -v36
	v_cvt_f16_f32_sdwa v36, -v36 dst_sel:WORD_1 dst_unused:UNUSED_PAD src0_sel:DWORD
	v_pk_fma_f32 v[68:69], v[68:69], v[70:71], v[70:71] op_sel:[0,1,0] op_sel_hi:[1,0,1]
	s_nop 0
	v_pk_add_f32 v[62:63], v[94:95], v[68:69]
	v_fma_f32 v56, v56, 0.5, -v68
	v_cvt_pk_f16_f32 v56, v62, v56
	v_lshlrev_b32_e32 v62, 16, v57
	v_or_b32_sdwa v57, v36, v56 dst_sel:DWORD dst_unused:UNUSED_PAD src0_sel:DWORD src1_sel:WORD_1
	v_or_b32_sdwa v56, v62, v56 dst_sel:DWORD dst_unused:UNUSED_PAD src0_sel:DWORD src1_sel:WORD_0
	global_store_dwordx2 v[58:59], v[56:57], off offset:2048
	v_pk_mul_f32 v[56:57], v[66:67], s[38:39] op_sel_hi:[0,1]
	v_pk_add_f32 v[58:59], v[60:61], v[80:81]
	v_pk_add_f32 v[60:61], v[60:61], v[80:81] neg_lo:[0,1] neg_hi:[0,1]
	v_mul_f32_e32 v36, 0.5, v58
	v_pk_fma_f32 v[62:63], v[64:65], s[8:9], v[56:57] op_sel_hi:[0,1,1] neg_lo:[0,0,1] neg_hi:[0,0,1]
	v_pk_fma_f32 v[68:69], v[64:65], s[8:9], v[56:57] op_sel_hi:[0,1,1]
	v_mov_b32_e32 v58, v60
	v_mov_b32_e32 v70, v62
	v_mov_b32_e32 v71, v69
	v_pk_mul_f32 v[58:59], v[58:59], s[78:79]
	s_mov_b32 s8, s47
	v_pk_mul_f32 v[80:81], v[70:71], v[58:59] op_sel:[0,1] op_sel_hi:[1,0]
	v_pk_mul_f32 v[58:59], v[70:71], v[58:59]
	s_mov_b32 s9, s46
	v_sub_f32_e32 v58, v58, v59
	v_fma_mixlo_f16 v65, v61, s79, v58
	v_fma_f32 v58, v61, 0.5, -v58
	v_cvt_f16_f32_sdwa v70, -v58 dst_sel:WORD_1 dst_unused:UNUSED_PAD src0_sel:DWORD
	v_pk_add_f32 v[58:59], v[80:81], v[80:81] op_sel:[0,1] op_sel_hi:[0,1]
	v_pk_add_f32 v[60:61], v[36:37], v[58:59]
	v_pk_add_f32 v[58:59], v[36:37], v[58:59] op_sel_hi:[0,1] neg_lo:[0,1] neg_hi:[0,1]
	v_cvt_pk_f16_f32 v36, v60, v59
	v_lshlrev_b32_e32 v58, 16, v65
	v_or_b32_sdwa v59, v70, v36 dst_sel:DWORD dst_unused:UNUSED_PAD src0_sel:DWORD src1_sel:WORD_1
	v_or_b32_sdwa v58, v58, v36 dst_sel:DWORD dst_unused:UNUSED_PAD src0_sel:DWORD src1_sel:WORD_0
	global_store_dwordx2 v[90:91], v[58:59], off
	v_mul_f32_e32 v58, 0xbe47c5c2, v67
	v_pk_add_f32 v[60:61], v[46:47], v[82:83]
	v_sub_f32_e32 v65, v47, v83
	v_mov_b32_e32 v59, v46
	v_pk_mov_b32 v[46:47], v[56:57], v[82:83] op_sel:[1,0]
	v_mul_f32_e32 v36, 0.5, v61
	v_pk_add_f32 v[46:47], v[58:59], v[46:47] neg_lo:[0,1] neg_hi:[0,1]
	v_mul_f32_e32 v70, 0.5, v60
	v_pk_mul_f32 v[58:59], v[46:47], v[36:37]
	s_nop 0
	v_mul_f32_e32 v46, v46, v59
	v_fma_f32 v36, -v62, v36, v46
	v_fma_mixlo_f16 v57, v65, s79, v36
	v_fma_f32 v36, v65, 0.5, -v36
	v_pk_fma_f32 v[80:81], v[62:63], v[58:59], v[58:59] op_sel:[0,1,0] op_sel_hi:[1,0,1]
	v_cvt_f16_f32_sdwa v36, -v36 dst_sel:WORD_1 dst_unused:UNUSED_PAD src0_sel:DWORD
	v_pk_add_f32 v[46:47], v[70:71], v[80:81]
	v_lshlrev_b32_e32 v57, 16, v57
	v_fma_f32 v47, v60, 0.5, -v80
	v_cvt_pk_f16_f32 v46, v46, v47
	v_or_b32_sdwa v47, v36, v46 dst_sel:DWORD dst_unused:UNUSED_PAD src0_sel:DWORD src1_sel:WORD_1
	v_or_b32_sdwa v46, v57, v46 dst_sel:DWORD dst_unused:UNUSED_PAD src0_sel:DWORD src1_sel:WORD_0
	global_store_dwordx2 v[90:91], v[46:47], off offset:2048
	v_pk_mul_f32 v[46:47], v[66:67], s[8:9] op_sel_hi:[0,1]
	v_pk_add_f32 v[58:59], v[76:77], v[52:53]
	v_pk_add_f32 v[52:53], v[52:53], v[76:77] neg_lo:[0,1] neg_hi:[0,1]
	v_mul_f32_e32 v36, 0.5, v58
	v_pk_fma_f32 v[60:61], v[64:65], s[46:47], v[46:47] op_sel_hi:[0,1,1] neg_lo:[0,0,1] neg_hi:[0,0,1]
	v_pk_fma_f32 v[64:65], v[64:65], s[46:47], v[46:47] op_sel_hi:[0,1,1]
	v_mov_b32_e32 v58, v52
	v_mov_b32_e32 v70, v60
	v_mov_b32_e32 v71, v65
	v_pk_mul_f32 v[58:59], v[58:59], s[78:79] op_sel:[1,1] op_sel_hi:[0,0]
	v_pk_mul_f32 v[76:77], v[70:71], v[58:59]
	v_pk_mul_f32 v[58:59], v[58:59], v[70:71] op_sel:[1,0] op_sel_hi:[0,1]
	v_sub_f32_e32 v52, v58, v59
	v_fma_mixlo_f16 v57, v53, s79, v52
	v_fma_f32 v52, v53, 0.5, -v52
	v_cvt_f16_f32_sdwa v66, -v52 dst_sel:WORD_1 dst_unused:UNUSED_PAD src0_sel:DWORD
	v_pk_add_f32 v[52:53], v[76:77], v[76:77] op_sel:[0,1] op_sel_hi:[0,1]
	v_pk_add_f32 v[58:59], v[36:37], v[52:53]
	v_pk_add_f32 v[52:53], v[36:37], v[52:53] op_sel_hi:[0,1] neg_lo:[0,1] neg_hi:[0,1]
	v_cvt_pk_f16_f32 v36, v58, v53
	v_add_co_u32_e32 v58, vcc, s51, v40
	v_lshlrev_b32_e32 v52, 16, v57
	s_nop 0
	v_addc_co_u32_e32 v59, vcc, 0, v41, vcc
	v_add_co_u32_e32 v70, vcc, s60, v40
	v_or_b32_sdwa v53, v66, v36 dst_sel:DWORD dst_unused:UNUSED_PAD src0_sel:DWORD src1_sel:WORD_1
	v_or_b32_sdwa v52, v52, v36 dst_sel:DWORD dst_unused:UNUSED_PAD src0_sel:DWORD src1_sel:WORD_0
	v_addc_co_u32_e32 v71, vcc, 0, v41, vcc
	global_store_dwordx2 v[70:71], v[52:53], off offset:-4096
	v_mul_f32_e32 v52, 0xbf54db31, v67
	v_pk_add_f32 v[76:77], v[72:73], v[54:55]
	v_sub_f32_e32 v57, v55, v73
	v_mov_b32_e32 v53, v54
	v_pk_mov_b32 v[54:55], v[46:47], v[72:73] op_sel:[1,0]
	v_mul_f32_e32 v36, 0.5, v77
	v_pk_add_f32 v[52:53], v[52:53], v[54:55] neg_lo:[0,1] neg_hi:[0,1]
	v_mul_f32_e32 v66, 0.5, v76
	v_pk_mul_f32 v[54:55], v[52:53], v[36:37]
	s_nop 0
	v_mul_f32_e32 v47, v52, v55
	v_fma_f32 v36, -v60, v36, v47
	v_fma_mixlo_f16 v47, v57, s79, v36
	v_fma_f32 v36, v57, 0.5, -v36
	v_pk_fma_f32 v[72:73], v[60:61], v[54:55], v[54:55] op_sel:[0,1,0] op_sel_hi:[1,0,1]
	v_cvt_f16_f32_sdwa v36, -v36 dst_sel:WORD_1 dst_unused:UNUSED_PAD src0_sel:DWORD
	v_pk_add_f32 v[52:53], v[66:67], v[72:73]
	v_lshlrev_b32_e32 v47, 16, v47
	v_fma_f32 v53, v76, 0.5, -v72
	v_cvt_pk_f16_f32 v52, v52, v53
	v_or_b32_sdwa v53, v36, v52 dst_sel:DWORD dst_unused:UNUSED_PAD src0_sel:DWORD src1_sel:WORD_1
	v_or_b32_sdwa v52, v47, v52 dst_sel:DWORD dst_unused:UNUSED_PAD src0_sel:DWORD src1_sel:WORD_0
	global_store_dwordx2 v[58:59], v[52:53], off offset:2048
	v_pk_add_f32 v[52:53], v[74:75], v[50:51]
	v_pk_add_f32 v[50:51], v[50:51], v[74:75] neg_lo:[0,1] neg_hi:[0,1]
	v_mul_f32_e32 v36, 0.5, v52
	v_mov_b32_e32 v52, v50
	v_pk_mov_b32 v[54:55], v[60:61], v[64:65] op_sel:[1,0]
	v_pk_mul_f32 v[52:53], v[52:53], s[78:79] op_sel:[1,1] op_sel_hi:[0,0]
	v_pk_mul_f32 v[58:59], v[54:55], v[52:53]
	v_pk_mul_f32 v[52:53], v[52:53], v[54:55] op_sel:[1,0] op_sel_hi:[0,1]
	v_sub_f32_e32 v47, v52, v53
	v_fma_mixlo_f16 v57, v51, s79, v47
	v_fma_f32 v47, v51, 0.5, -v47
	v_cvt_f16_f32_sdwa v47, -v47 dst_sel:WORD_1 dst_unused:UNUSED_PAD src0_sel:DWORD
	v_pk_add_f32 v[50:51], v[58:59], v[58:59] op_sel:[0,1] op_sel_hi:[0,1]
	v_pk_add_f32 v[52:53], v[36:37], v[50:51]
	v_pk_add_f32 v[50:51], v[36:37], v[50:51] op_sel_hi:[0,1] neg_lo:[0,1] neg_hi:[0,1]
	v_cvt_pk_f16_f32 v36, v52, v51
	v_lshlrev_b32_e32 v50, 16, v57
	v_or_b32_sdwa v51, v47, v36 dst_sel:DWORD dst_unused:UNUSED_PAD src0_sel:DWORD src1_sel:WORD_1
	v_or_b32_sdwa v50, v50, v36 dst_sel:DWORD dst_unused:UNUSED_PAD src0_sel:DWORD src1_sel:WORD_0
	global_store_dwordx2 v[70:71], v[50:51], off
	v_mul_f32_e32 v50, 0xbf0e39da, v67
	v_pk_add_f32 v[52:53], v[78:79], v[44:45]
	v_mov_b32_e32 v51, v44
	v_mov_b32_e32 v47, v78
	v_sub_f32_e32 v57, v45, v79
	v_mul_f32_e32 v36, 0.5, v53
	v_pk_add_f32 v[44:45], v[50:51], v[46:47] neg_lo:[0,1] neg_hi:[0,1]
	v_mul_f32_e32 v58, 0.5, v52
	v_pk_mul_f32 v[46:47], v[44:45], v[36:37]
	s_nop 0
	v_mul_f32_e32 v44, v44, v47
	v_fma_f32 v36, -v61, v36, v44
	v_pk_fma_f32 v[50:51], v[54:55], v[46:47], v[46:47] op_sel:[0,1,0] op_sel_hi:[1,0,1]
	v_fma_mixlo_f16 v46, v57, s79, v36
	v_fma_f32 v36, v57, 0.5, -v36
	v_cvt_f16_f32_sdwa v36, -v36 dst_sel:WORD_1 dst_unused:UNUSED_PAD src0_sel:DWORD
	v_pk_add_f32 v[44:45], v[58:59], v[50:51]
	v_lshlrev_b32_e32 v46, 16, v46
	v_fma_f32 v45, v52, 0.5, -v50
	v_cvt_pk_f16_f32 v44, v44, v45
	v_or_b32_sdwa v45, v36, v44 dst_sel:DWORD dst_unused:UNUSED_PAD src0_sel:DWORD src1_sel:WORD_1
	v_or_b32_sdwa v44, v46, v44 dst_sel:DWORD dst_unused:UNUSED_PAD src0_sel:DWORD src1_sel:WORD_0
	global_store_dwordx2 v[70:71], v[44:45], off offset:2048
	v_pk_add_f32 v[44:45], v[86:87], v[42:43]
	v_pk_add_f32 v[42:43], v[42:43], v[86:87] neg_lo:[0,1] neg_hi:[0,1]
	v_mul_f32_e32 v36, 0.5, v44
	v_mov_b32_e32 v44, v42
	v_pk_mov_b32 v[46:47], v[62:63], v[68:69] op_sel:[1,0]
	v_pk_mul_f32 v[44:45], v[44:45], s[78:79] op_sel:[1,1] op_sel_hi:[0,0]
	v_pk_mul_f32 v[50:51], v[46:47], v[44:45]
	v_pk_mul_f32 v[44:45], v[44:45], v[46:47] op_sel:[1,0] op_sel_hi:[0,1]
	v_sub_f32_e32 v42, v44, v45
	v_fma_mixlo_f16 v46, v43, s79, v42
	v_fma_f32 v42, v43, 0.5, -v42
	v_cvt_f16_f32_sdwa v47, -v42 dst_sel:WORD_1 dst_unused:UNUSED_PAD src0_sel:DWORD
	v_pk_add_f32 v[42:43], v[50:51], v[50:51] op_sel:[0,1] op_sel_hi:[0,1]
	v_pk_add_f32 v[44:45], v[36:37], v[42:43]
	v_pk_add_f32 v[42:43], v[36:37], v[42:43] op_sel_hi:[0,1] neg_lo:[0,1] neg_hi:[0,1]
	v_cvt_pk_f16_f32 v36, v44, v43
	v_lshlrev_b32_e32 v42, 16, v46
	v_or_b32_sdwa v43, v47, v36 dst_sel:DWORD dst_unused:UNUSED_PAD src0_sel:DWORD src1_sel:WORD_1
	v_pk_add_f32 v[44:45], v[48:49], v[84:85]
	v_pk_add_f32 v[46:47], v[48:49], v[84:85] neg_lo:[0,1] neg_hi:[0,1]
	v_mov_b32_e32 v48, v44
	v_mov_b32_e32 v49, v47
	v_mov_b32_e32 v47, v45
	v_pk_mul_f32 v[44:45], v[46:47], s[78:79]
	v_or_b32_sdwa v42, v42, v36 dst_sel:DWORD dst_unused:UNUSED_PAD src0_sel:DWORD src1_sel:WORD_0
	v_fma_f32 v36, v67, s26, -v56
	v_pk_mul_f32 v[46:47], v[62:63], v[44:45] op_sel:[1,0]
	s_nop 0
	v_pk_fma_f32 v[50:51], v[36:37], v[44:45], v[46:47] op_sel:[0,1,0] op_sel_hi:[0,0,1] neg_hi:[0,0,1]
	s_nop 0
	v_pk_fma_f32 v[44:45], v[48:49], 0.5, v[50:51] op_sel_hi:[1,0,1]
	v_pk_fma_f32 v[112:113], v[48:49], 0.5, v[50:51] op_sel_hi:[1,0,1] neg_lo:[0,0,1] neg_hi:[0,0,1]
	v_cvt_f16_f32_e32 v36, v44
	v_cvt_f16_f32_sdwa v46, v45 dst_sel:WORD_1 dst_unused:UNUSED_PAD src0_sel:DWORD
	v_add_co_u32_e32 v44, vcc, s61, v40
	v_or_b32_e32 v110, v46, v36
	s_nop 0
	v_addc_co_u32_e32 v45, vcc, 0, v41, vcc
	global_store_dwordx2 v[44:45], v[42:43], off
.LBB0_434:
	s_andn2_saveexec_b64 s[6:7], s[6:7]
	s_cbranch_execz .LBB0_427
	v_pk_add_f32 v[110:111], v[84:85], v[114:115]
	v_pk_add_f32 v[84:85], v[84:85], v[114:115] neg_lo:[0,1] neg_hi:[0,1]
	v_mul_f32_e32 v112, 0.5, v110
	v_pk_fma_f32 v[114:115], v[66:67], 0, v[66:67] op_sel:[0,0,1] op_sel_hi:[1,0,0] neg_lo:[1,0,0]
	v_mov_b32_e32 v110, v84
	v_pk_mul_f32 v[110:111], v[110:111], s[78:79]
	s_mov_b32 s8, s45
	v_pk_mul_f32 v[116:117], v[114:115], v[110:111] op_sel:[0,1] op_sel_hi:[1,0]
	v_pk_mul_f32 v[110:111], v[114:115], v[110:111]
	s_mov_b32 s9, s42
	v_sub_f32_e32 v84, v110, v111
	v_fma_mixlo_f16 v93, v85, s79, v84
	v_fma_f32 v84, v85, 0.5, -v84
	v_cvt_f16_f32_sdwa v101, -v84 dst_sel:WORD_1 dst_unused:UNUSED_PAD src0_sel:DWORD
	v_pk_add_f32 v[84:85], v[116:117], v[116:117] op_sel:[0,1] op_sel_hi:[0,1]
	v_pk_add_f32 v[110:111], v[112:113], v[84:85]
	v_pk_add_f32 v[84:85], v[112:113], v[84:85] op_sel_hi:[0,1] neg_lo:[0,1] neg_hi:[0,1]
	v_cvt_pk_f16_f32 v84, v110, v85
	v_lshlrev_b32_e32 v93, 16, v93
	v_or_b32_sdwa v85, v101, v84 dst_sel:DWORD dst_unused:UNUSED_PAD src0_sel:DWORD src1_sel:WORD_1
	v_or_b32_sdwa v84, v93, v84 dst_sel:DWORD dst_unused:UNUSED_PAD src0_sel:DWORD src1_sel:WORD_0
	global_store_dwordx2 v[40:41], v[84:85], off
	v_pk_add_f32 v[84:85], v[86:87], v[108:109]
	v_pk_add_f32 v[86:87], v[86:87], v[108:109] neg_lo:[0,1] neg_hi:[0,1]
	v_mul_f32_e32 v110, 0.5, v84
	v_mov_b32_e32 v84, v67
	v_mov_b32_e32 v108, v67
	v_mov_b32_e32 v109, v66
	v_pk_fma_f32 v[112:113], v[66:67], 0, v[108:109] op_sel_hi:[1,0,1] neg_lo:[0,0,1] neg_hi:[0,0,1]
	v_pk_fma_f32 v[114:115], v[66:67], 0, v[84:85] op_sel_hi:[1,0,1]
	v_mov_b32_e32 v84, v86
	v_pk_mov_b32 v[112:113], v[112:113], v[114:115] op_sel:[1,0]
	v_pk_mul_f32 v[84:85], v[84:85], s[78:79]
	s_mov_b32 s43, s45
	v_pk_mul_f32 v[114:115], v[112:113], v[84:85] op_sel:[0,1] op_sel_hi:[1,0]
	v_pk_mul_f32 v[84:85], v[112:113], v[84:85]
	v_pk_fma_f32 v[112:113], v[108:109], s[68:69], v[36:37] op_sel_hi:[1,1,0]
	v_sub_f32_e32 v84, v84, v85
	v_fma_mixlo_f16 v93, v87, s79, v84
	v_fma_f32 v84, v87, 0.5, -v84
	v_cvt_f16_f32_sdwa v101, -v84 dst_sel:WORD_1 dst_unused:UNUSED_PAD src0_sel:DWORD
	v_pk_add_f32 v[84:85], v[114:115], v[114:115] op_sel:[0,1] op_sel_hi:[0,1]
	v_pk_add_f32 v[86:87], v[110:111], v[84:85]
	v_pk_add_f32 v[84:85], v[110:111], v[84:85] op_sel_hi:[0,1] neg_lo:[0,1] neg_hi:[0,1]
	v_cvt_pk_f16_f32 v84, v86, v85
	v_lshlrev_b32_e32 v86, 16, v93
	v_or_b32_sdwa v85, v101, v84 dst_sel:DWORD dst_unused:UNUSED_PAD src0_sel:DWORD src1_sel:WORD_1
	v_or_b32_sdwa v84, v86, v84 dst_sel:DWORD dst_unused:UNUSED_PAD src0_sel:DWORD src1_sel:WORD_0
	global_store_dwordx2 v[40:41], v[84:85], off offset:2048
	v_pk_mul_f32 v[84:85], v[108:109], s[68:69]
	v_pk_add_f32 v[86:87], v[78:79], v[106:107]
	v_pk_add_f32 v[78:79], v[78:79], v[106:107] neg_lo:[0,1] neg_hi:[0,1]
	v_mul_f32_e32 v110, 0.5, v86
	v_pk_add_f32 v[106:107], v[36:37], v[84:85] op_sel:[0,1] op_sel_hi:[0,1] neg_lo:[0,1] neg_hi:[0,1]
	v_mov_b32_e32 v86, v78
	v_mov_b32_e32 v107, v113
	v_pk_mul_f32 v[86:87], v[86:87], s[78:79]
	v_mov_b32_e32 v101, v76
	v_pk_mul_f32 v[112:113], v[106:107], v[86:87] op_sel:[0,1] op_sel_hi:[1,0]
	v_pk_mul_f32 v[86:87], v[106:107], v[86:87]
	s_mov_b32 s39, s27
	v_sub_f32_e32 v36, v86, v87
	v_fma_mixlo_f16 v93, v79, s79, v36
	v_fma_f32 v36, v79, 0.5, -v36
	v_cvt_f16_f32_sdwa v36, -v36 dst_sel:WORD_1 dst_unused:UNUSED_PAD src0_sel:DWORD
	v_pk_add_f32 v[78:79], v[112:113], v[112:113] op_sel:[0,1] op_sel_hi:[0,1]
	v_pk_add_f32 v[86:87], v[110:111], v[78:79]
	v_pk_add_f32 v[78:79], v[110:111], v[78:79] op_sel_hi:[0,1] neg_lo:[0,1] neg_hi:[0,1]
	v_cvt_pk_f16_f32 v78, v86, v79
	v_lshlrev_b32_e32 v86, 16, v93
	v_or_b32_sdwa v79, v36, v78 dst_sel:DWORD dst_unused:UNUSED_PAD src0_sel:DWORD src1_sel:WORD_1
	v_or_b32_sdwa v78, v86, v78 dst_sel:DWORD dst_unused:UNUSED_PAD src0_sel:DWORD src1_sel:WORD_0
	v_add_co_u32_e32 v86, vcc, s34, v40
	v_mov_b32_e32 v93, v80
	s_nop 0
	v_addc_co_u32_e32 v87, vcc, 0, v41, vcc
	v_add_co_u32_e32 v110, vcc, s3, v40
	s_mov_b32 s82, s27
	s_nop 0
	v_addc_co_u32_e32 v111, vcc, 0, v41, vcc
	global_store_dwordx2 v[110:111], v[78:79], off offset:-4096
	v_pk_fma_f32 v[78:79], v[108:109], s[68:69], v[84:85] op_sel:[0,0,1] op_sel_hi:[1,1,0] neg_lo:[0,0,1] neg_hi:[0,0,1]
	v_pk_add_f32 v[84:85], v[74:75], v[104:105]
	v_pk_add_f32 v[74:75], v[74:75], v[104:105] neg_lo:[0,1] neg_hi:[0,1]
	v_mul_f32_e32 v36, 0.5, v84
	v_mov_b32_e32 v84, v74
	v_pk_mul_f32 v[84:85], v[84:85], s[78:79]
	v_mov_b32_e32 v79, v106
	v_mov_b32_e32 v107, v78
	v_pk_mul_f32 v[78:79], v[78:79], v[84:85]
	v_pk_mul_f32 v[104:105], v[106:107], v[84:85]
	v_sub_f32_e32 v74, v78, v79
	v_fma_mixlo_f16 v84, v75, s79, v74
	v_fma_f32 v74, v75, 0.5, -v74
	v_cvt_f16_f32_sdwa v85, -v74 dst_sel:WORD_1 dst_unused:UNUSED_PAD src0_sel:DWORD
	v_pk_add_f32 v[74:75], v[104:105], v[104:105] op_sel:[1,0] op_sel_hi:[1,0]
	s_mov_b32 s83, s38
	v_pk_add_f32 v[78:79], v[36:37], v[74:75]
	v_pk_add_f32 v[74:75], v[36:37], v[74:75] op_sel_hi:[0,1] neg_lo:[0,1] neg_hi:[0,1]
	v_cvt_pk_f16_f32 v36, v78, v75
	v_lshlrev_b32_e32 v74, 16, v84
	v_or_b32_sdwa v75, v85, v36 dst_sel:DWORD dst_unused:UNUSED_PAD src0_sel:DWORD src1_sel:WORD_1
	v_or_b32_sdwa v74, v74, v36 dst_sel:DWORD dst_unused:UNUSED_PAD src0_sel:DWORD src1_sel:WORD_0
	global_store_dwordx2 v[86:87], v[74:75], off offset:2048
	v_mov_b32_e32 v36, v67
	v_pk_mul_f32 v[66:67], v[66:67], s[8:9] op_sel_hi:[0,1]
	v_pk_add_f32 v[74:75], v[72:73], v[102:103]
	v_pk_add_f32 v[72:73], v[72:73], v[102:103] neg_lo:[0,1] neg_hi:[0,1]
	v_mul_f32_e32 v78, 0.5, v74
	v_pk_fma_f32 v[84:85], v[36:37], s[42:43], v[66:67] op_sel_hi:[0,1,1] neg_lo:[0,0,1] neg_hi:[0,0,1]
	v_pk_fma_f32 v[86:87], v[36:37], s[42:43], v[66:67] op_sel_hi:[0,1,1]
	v_mov_b32_e32 v74, v72
	v_mov_b32_e32 v102, v84
	v_mov_b32_e32 v103, v87
	v_pk_mul_f32 v[74:75], v[74:75], s[78:79] op_sel:[1,1] op_sel_hi:[0,0]
	v_pk_mul_f32 v[104:105], v[102:103], v[74:75]
	v_pk_mul_f32 v[74:75], v[74:75], v[102:103] op_sel:[1,0] op_sel_hi:[0,1]
	v_sub_f32_e32 v36, v74, v75
	v_fma_mixlo_f16 v79, v73, s79, v36
	v_fma_f32 v36, v73, 0.5, -v36
	v_cvt_f16_f32_sdwa v36, -v36 dst_sel:WORD_1 dst_unused:UNUSED_PAD src0_sel:DWORD
	v_pk_add_f32 v[72:73], v[104:105], v[104:105] op_sel:[0,1] op_sel_hi:[0,1]
	v_pk_add_f32 v[74:75], v[78:79], v[72:73]
	v_pk_add_f32 v[72:73], v[78:79], v[72:73] op_sel_hi:[0,1] neg_lo:[0,1] neg_hi:[0,1]
	v_cvt_pk_f16_f32 v72, v74, v73
	v_lshlrev_b32_e32 v74, 16, v79
	v_or_b32_sdwa v73, v36, v72 dst_sel:DWORD dst_unused:UNUSED_PAD src0_sel:DWORD src1_sel:WORD_1
	v_or_b32_sdwa v72, v74, v72 dst_sel:DWORD dst_unused:UNUSED_PAD src0_sel:DWORD src1_sel:WORD_0
	global_store_dwordx2 v[110:111], v[72:73], off
	v_pk_add_f32 v[72:73], v[76:77], v[98:99]
	v_sub_f32_e32 v75, v77, v99
	v_pk_mov_b32 v[76:77], v[66:67], v[98:99] op_sel:[1,0]
	v_mul_f32_e32 v36, 0.5, v73
	v_pk_add_f32 v[76:77], v[100:101], v[76:77] neg_lo:[0,1] neg_hi:[0,1]
	v_mul_f32_e32 v74, 0.5, v72
	v_pk_mul_f32 v[78:79], v[76:77], v[36:37]
	s_nop 0
	v_mul_f32_e32 v67, v76, v79
	v_fma_f32 v36, -v84, v36, v67
	v_fma_mixlo_f16 v67, v75, s79, v36
	v_fma_f32 v36, v75, 0.5, -v36
	v_cvt_f16_f32_sdwa v36, -v36 dst_sel:WORD_1 dst_unused:UNUSED_PAD src0_sel:DWORD
	v_pk_fma_f32 v[98:99], v[84:85], v[78:79], v[78:79] op_sel:[0,1,0] op_sel_hi:[1,0,1]
	v_lshlrev_b32_e32 v67, 16, v67
	v_pk_add_f32 v[74:75], v[74:75], v[98:99]
	v_fma_f32 v72, v72, 0.5, -v98
	v_cvt_pk_f16_f32 v72, v74, v72
	v_or_b32_sdwa v73, v36, v72 dst_sel:DWORD dst_unused:UNUSED_PAD src0_sel:DWORD src1_sel:WORD_1
	v_or_b32_sdwa v72, v67, v72 dst_sel:DWORD dst_unused:UNUSED_PAD src0_sel:DWORD src1_sel:WORD_0
	global_store_dwordx2 v[110:111], v[72:73], off offset:2048
	v_pk_add_f32 v[72:73], v[96:97], v[82:83]
	v_pk_add_f32 v[74:75], v[82:83], v[96:97] neg_lo:[0,1] neg_hi:[0,1]
	v_mul_f32_e32 v36, 0.5, v72
	v_mov_b32_e32 v72, v74
	v_pk_mov_b32 v[76:77], v[84:85], v[86:87] op_sel:[1,0]
	v_pk_mul_f32 v[72:73], v[72:73], s[78:79]
	v_sub_f32_e32 v83, v81, v89
	v_pk_mul_f32 v[78:79], v[76:77], v[72:73] op_sel:[0,1] op_sel_hi:[1,0]
	v_pk_mul_f32 v[72:73], v[76:77], v[72:73]
	s_nop 0
	v_sub_f32_e32 v67, v72, v73
	v_fma_mixlo_f16 v82, v75, s79, v67
	v_fma_f32 v67, v75, 0.5, -v67
	v_pk_add_f32 v[72:73], v[78:79], v[78:79] op_sel:[0,1] op_sel_hi:[0,1]
	v_cvt_f16_f32_sdwa v67, -v67 dst_sel:WORD_1 dst_unused:UNUSED_PAD src0_sel:DWORD
	v_pk_add_f32 v[74:75], v[36:37], v[72:73]
	v_pk_add_f32 v[72:73], v[36:37], v[72:73] op_sel_hi:[0,1] neg_lo:[0,1] neg_hi:[0,1]
	v_cvt_pk_f16_f32 v36, v74, v73
	v_add_co_u32_e32 v74, vcc, s35, v40
	v_lshlrev_b32_e32 v72, 16, v82
	s_nop 0
	v_addc_co_u32_e32 v75, vcc, 0, v41, vcc
	v_add_co_u32_e32 v78, vcc, s37, v40
	v_or_b32_sdwa v73, v67, v36 dst_sel:DWORD dst_unused:UNUSED_PAD src0_sel:DWORD src1_sel:WORD_1
	v_or_b32_sdwa v72, v72, v36 dst_sel:DWORD dst_unused:UNUSED_PAD src0_sel:DWORD src1_sel:WORD_0
	v_addc_co_u32_e32 v79, vcc, 0, v41, vcc
	global_store_dwordx2 v[78:79], v[72:73], off offset:-4096
	v_pk_add_f32 v[72:73], v[88:89], v[80:81]
	v_mov_b32_e32 v67, v88
	v_mul_f32_e32 v36, 0.5, v73
	v_pk_add_f32 v[66:67], v[92:93], v[66:67] neg_lo:[0,1] neg_hi:[0,1]
	v_mul_f32_e32 v82, 0.5, v72
	v_pk_mul_f32 v[80:81], v[66:67], v[36:37]
	s_nop 0
	v_mul_f32_e32 v66, v66, v81
	v_fma_f32 v36, -v85, v36, v66
	v_fma_mixlo_f16 v73, v83, s79, v36
	v_fma_f32 v36, v83, 0.5, -v36
	v_pk_fma_f32 v[76:77], v[76:77], v[80:81], v[80:81] op_sel:[0,1,0] op_sel_hi:[1,0,1]
	v_cvt_f16_f32_sdwa v36, -v36 dst_sel:WORD_1 dst_unused:UNUSED_PAD src0_sel:DWORD
	v_pk_add_f32 v[66:67], v[82:83], v[76:77]
	s_nop 0
	v_fma_f32 v67, v72, 0.5, -v76
	v_cvt_pk_f16_f32 v66, v66, v67
	v_lshlrev_b32_e32 v72, 16, v73
	v_or_b32_sdwa v67, v36, v66 dst_sel:DWORD dst_unused:UNUSED_PAD src0_sel:DWORD src1_sel:WORD_1
	v_sub_f32_e32 v36, v94, v95
	v_or_b32_sdwa v66, v72, v66 dst_sel:DWORD dst_unused:UNUSED_PAD src0_sel:DWORD src1_sel:WORD_0
	v_cvt_f16_f32_sdwa v72, -v91 dst_sel:WORD_1 dst_unused:UNUSED_PAD src0_sel:DWORD
	v_cvt_f16_f32_sdwa v36, v36 dst_sel:WORD_1 dst_unused:UNUSED_PAD src0_sel:DWORD
	global_store_dwordx2 v[74:75], v[66:67], off offset:2048
	v_pk_add_f32 v[66:67], v[94:95], v[94:95] op_sel:[0,1] op_sel_hi:[1,0]
	s_nop 0
	v_cvt_pk_f16_f32 v66, v66, v90
	v_or_b32_sdwa v67, v72, v66 dst_sel:DWORD dst_unused:UNUSED_PAD src0_sel:DWORD src1_sel:WORD_1
	v_or_b32_sdwa v66, v36, v66 dst_sel:DWORD dst_unused:UNUSED_PAD src0_sel:DWORD src1_sel:WORD_0
	global_store_dwordx2 v[78:79], v[66:67], off
	v_pk_add_f32 v[66:67], v[60:61], v[48:49]
	v_pk_add_f32 v[48:49], v[60:61], v[48:49] neg_lo:[0,1] neg_hi:[0,1]
	v_mul_f32_e32 v36, 0.5, v66
	v_mov_b32_e32 v66, v48
	v_pk_mul_f32 v[60:61], v[66:67], s[78:79] op_sel:[1,1] op_sel_hi:[0,0]
	v_pk_mul_f32 v[66:67], v[60:61], s[38:39] op_sel:[1,0] op_sel_hi:[0,1]
	v_pk_mul_f32 v[60:61], v[60:61], s[82:83] op_sel:[1,0] op_sel_hi:[0,1]
	s_mov_b32 s82, s47
	v_sub_f32_e32 v48, v60, v61
	v_fma_mixlo_f16 v72, v49, s79, v48
	v_fma_f32 v48, v49, 0.5, -v48
	v_cvt_f16_f32_sdwa v73, -v48 dst_sel:WORD_1 dst_unused:UNUSED_PAD src0_sel:DWORD
	v_pk_add_f32 v[48:49], v[66:67], v[66:67] op_sel:[1,0] op_sel_hi:[1,0]
	s_mov_b32 s83, s46
	v_pk_add_f32 v[60:61], v[36:37], v[48:49]
	v_pk_add_f32 v[48:49], v[36:37], v[48:49] op_sel_hi:[0,1] neg_lo:[0,1] neg_hi:[0,1]
	v_cvt_pk_f16_f32 v36, v60, v49
	v_lshlrev_b32_e32 v48, 16, v72
	v_or_b32_sdwa v49, v73, v36 dst_sel:DWORD dst_unused:UNUSED_PAD src0_sel:DWORD src1_sel:WORD_1
	v_or_b32_sdwa v48, v48, v36 dst_sel:DWORD dst_unused:UNUSED_PAD src0_sel:DWORD src1_sel:WORD_0
	global_store_dwordx2 v[78:79], v[48:49], off offset:2048
	v_pk_add_f32 v[48:49], v[68:69], v[62:63]
	v_pk_add_f32 v[60:61], v[68:69], v[62:63] neg_lo:[0,1] neg_hi:[0,1]
	v_mul_f32_e32 v36, 0.5, v48
	v_mov_b32_e32 v48, v60
	v_pk_mul_f32 v[48:49], v[48:49], s[78:79] op_sel:[1,1] op_sel_hi:[0,0]
	v_pk_mul_f32 v[62:63], v[48:49], s[8:9] op_sel:[1,0] op_sel_hi:[0,1]
	v_pk_mul_f32 v[48:49], v[48:49], s[42:43] op_sel:[1,0] op_sel_hi:[0,1]
	s_nop 0
	v_sub_f32_e32 v48, v48, v49
	v_fma_mixlo_f16 v66, v61, s79, v48
	v_fma_f32 v48, v61, 0.5, -v48
	v_cvt_f16_f32_sdwa v67, -v48 dst_sel:WORD_1 dst_unused:UNUSED_PAD src0_sel:DWORD
	v_pk_add_f32 v[48:49], v[62:63], v[62:63] op_sel:[1,0] op_sel_hi:[1,0]
	s_nop 0
	v_pk_add_f32 v[60:61], v[36:37], v[48:49]
	v_pk_add_f32 v[48:49], v[36:37], v[48:49] op_sel_hi:[0,1] neg_lo:[0,1] neg_hi:[0,1]
	v_cvt_pk_f16_f32 v36, v60, v49
	v_add_co_u32_e32 v60, vcc, s51, v40
	v_lshlrev_b32_e32 v48, 16, v66
	s_nop 0
	v_addc_co_u32_e32 v61, vcc, 0, v41, vcc
	v_add_co_u32_e32 v62, vcc, s60, v40
	v_or_b32_sdwa v49, v67, v36 dst_sel:DWORD dst_unused:UNUSED_PAD src0_sel:DWORD src1_sel:WORD_1
	v_or_b32_sdwa v48, v48, v36 dst_sel:DWORD dst_unused:UNUSED_PAD src0_sel:DWORD src1_sel:WORD_0
	v_addc_co_u32_e32 v63, vcc, 0, v41, vcc
	global_store_dwordx2 v[62:63], v[48:49], off offset:-4096
	v_pk_add_f32 v[48:49], v[50:51], v[54:55]
	v_pk_add_f32 v[50:51], v[50:51], v[54:55] neg_lo:[0,1] neg_hi:[0,1]
	v_mul_f32_e32 v36, 0.5, v48
	v_mov_b32_e32 v48, v50
	v_pk_mul_f32 v[48:49], v[48:49], s[78:79] op_sel:[1,1] op_sel_hi:[0,0]
	v_pk_mul_f32 v[54:55], v[48:49], s[46:47] op_sel:[1,0] op_sel_hi:[0,1]
	v_pk_mul_f32 v[48:49], v[48:49], s[82:83] op_sel:[1,0] op_sel_hi:[0,1]
	s_nop 0
	v_sub_f32_e32 v48, v48, v49
	v_fma_mixlo_f16 v66, v51, s79, v48
	v_fma_f32 v48, v51, 0.5, -v48
	v_cvt_f16_f32_sdwa v67, -v48 dst_sel:WORD_1 dst_unused:UNUSED_PAD src0_sel:DWORD
	v_pk_add_f32 v[48:49], v[54:55], v[54:55] op_sel:[1,0] op_sel_hi:[1,0]
	s_nop 0
	v_pk_add_f32 v[50:51], v[36:37], v[48:49]
	v_pk_add_f32 v[48:49], v[36:37], v[48:49] op_sel_hi:[0,1] neg_lo:[0,1] neg_hi:[0,1]
	v_cvt_pk_f16_f32 v36, v50, v49
	v_lshlrev_b32_e32 v48, 16, v66
	v_or_b32_sdwa v49, v67, v36 dst_sel:DWORD dst_unused:UNUSED_PAD src0_sel:DWORD src1_sel:WORD_1
	v_or_b32_sdwa v48, v48, v36 dst_sel:DWORD dst_unused:UNUSED_PAD src0_sel:DWORD src1_sel:WORD_0
	global_store_dwordx2 v[60:61], v[48:49], off offset:2048
	v_pk_add_f32 v[48:49], v[70:71], v[64:65]
	v_pk_add_f32 v[50:51], v[70:71], v[64:65] neg_lo:[0,1] neg_hi:[0,1]
	v_mul_f32_e32 v36, 0.5, v48
	v_mov_b32_e32 v48, v50
	v_pk_mul_f32 v[48:49], v[48:49], s[78:79] op_sel:[1,1] op_sel_hi:[0,0]
	v_pk_mul_f32 v[48:49], s[64:65], v[48:49] op_sel:[0,1] op_sel_hi:[0,0]
	v_sub_f32_e32 v50, v48, v49
	v_fma_mixlo_f16 v54, v51, s79, v50
	v_fma_f32 v50, v51, 0.5, -v50
	v_cvt_f16_f32_sdwa v55, -v50 dst_sel:WORD_1 dst_unused:UNUSED_PAD src0_sel:DWORD
	v_pk_add_f32 v[48:49], v[48:49], v[48:49] op_sel:[1,0] op_sel_hi:[1,0]
	s_nop 0
	v_pk_add_f32 v[50:51], v[36:37], v[48:49]
	v_pk_add_f32 v[48:49], v[36:37], v[48:49] op_sel_hi:[0,1] neg_lo:[0,1] neg_hi:[0,1]
	v_cvt_pk_f16_f32 v36, v50, v49
	v_lshlrev_b32_e32 v48, 16, v54
	v_or_b32_sdwa v49, v55, v36 dst_sel:DWORD dst_unused:UNUSED_PAD src0_sel:DWORD src1_sel:WORD_1
	v_or_b32_sdwa v48, v48, v36 dst_sel:DWORD dst_unused:UNUSED_PAD src0_sel:DWORD src1_sel:WORD_0
	global_store_dwordx2 v[62:63], v[48:49], off
	v_pk_add_f32 v[48:49], v[52:53], v[44:45]
	v_pk_add_f32 v[44:45], v[52:53], v[44:45] neg_lo:[0,1] neg_hi:[0,1]
	v_mul_f32_e32 v36, 0.5, v48
	v_mov_b32_e32 v48, v44
	v_pk_mul_f32 v[48:49], v[48:49], s[78:79] op_sel:[1,1] op_sel_hi:[0,0]
	v_pk_mul_f32 v[50:51], v[48:49], s[82:83] op_sel:[1,0] op_sel_hi:[0,1]
	v_pk_mul_f32 v[48:49], v[48:49], s[46:47] op_sel:[1,0] op_sel_hi:[0,1]
	s_nop 0
	v_sub_f32_e32 v44, v48, v49
	v_fma_mixlo_f16 v52, v45, s79, v44
	v_fma_f32 v44, v45, 0.5, -v44
	v_cvt_f16_f32_sdwa v53, -v44 dst_sel:WORD_1 dst_unused:UNUSED_PAD src0_sel:DWORD
	v_pk_add_f32 v[44:45], v[50:51], v[50:51] op_sel:[1,0] op_sel_hi:[1,0]
	s_nop 0
	v_pk_add_f32 v[48:49], v[36:37], v[44:45]
	v_pk_add_f32 v[44:45], v[36:37], v[44:45] op_sel_hi:[0,1] neg_lo:[0,1] neg_hi:[0,1]
	v_cvt_pk_f16_f32 v36, v48, v45
	v_lshlrev_b32_e32 v44, 16, v52
	v_or_b32_sdwa v45, v53, v36 dst_sel:DWORD dst_unused:UNUSED_PAD src0_sel:DWORD src1_sel:WORD_1
	v_or_b32_sdwa v44, v44, v36 dst_sel:DWORD dst_unused:UNUSED_PAD src0_sel:DWORD src1_sel:WORD_0
	global_store_dwordx2 v[62:63], v[44:45], off offset:2048
	v_pk_add_f32 v[44:45], v[58:59], v[56:57]
	v_pk_add_f32 v[48:49], v[56:57], v[58:59] neg_lo:[0,1] neg_hi:[0,1]
	v_mul_f32_e32 v36, 0.5, v44
	v_mov_b32_e32 v44, v48
	v_pk_mul_f32 v[44:45], v[44:45], s[78:79] op_sel:[1,1] op_sel_hi:[0,0]
	v_pk_mul_f32 v[50:51], v[44:45], s[42:43] op_sel:[1,0] op_sel_hi:[0,1]
	v_pk_mul_f32 v[44:45], v[44:45], s[8:9] op_sel:[1,0] op_sel_hi:[0,1]
	s_mov_b32 s8, s27
	v_sub_f32_e32 v44, v44, v45
	v_fma_mixlo_f16 v52, v49, s79, v44
	v_fma_f32 v44, v49, 0.5, -v44
	v_cvt_f16_f32_sdwa v53, -v44 dst_sel:WORD_1 dst_unused:UNUSED_PAD src0_sel:DWORD
	v_pk_add_f32 v[44:45], v[50:51], v[50:51] op_sel:[1,0] op_sel_hi:[1,0]
	s_nop 0
	v_pk_add_f32 v[48:49], v[36:37], v[44:45]
	v_pk_add_f32 v[44:45], v[36:37], v[44:45] op_sel_hi:[0,1] neg_lo:[0,1] neg_hi:[0,1]
	v_cvt_pk_f16_f32 v36, v48, v45
	v_pk_add_f32 v[48:49], v[42:43], v[46:47]
	v_pk_add_f32 v[42:43], v[42:43], v[46:47] neg_lo:[0,1] neg_hi:[0,1]
	v_mov_b32_e32 v46, v48
	v_mov_b32_e32 v47, v43
	v_mov_b32_e32 v43, v49
	v_pk_mul_f32 v[42:43], v[42:43], s[78:79]
	v_lshlrev_b32_e32 v44, 16, v52
	v_pk_mul_f32 v[48:49], v[42:43], s[38:39] op_sel_hi:[1,0]
	v_or_b32_sdwa v45, v53, v36 dst_sel:DWORD dst_unused:UNUSED_PAD src0_sel:DWORD src1_sel:WORD_1
	v_pk_fma_f32 v[50:51], v[42:43], s[8:9], v[48:49] op_sel:[0,0,1] op_sel_hi:[1,0,0] neg_hi:[1,0,0]
	s_nop 0
	v_or_b32_sdwa v44, v44, v36 dst_sel:DWORD dst_unused:UNUSED_PAD src0_sel:DWORD src1_sel:WORD_0
	s_nop 0
	v_pk_fma_f32 v[42:43], v[46:47], 0.5, v[50:51] op_sel_hi:[1,0,1]
	v_pk_fma_f32 v[112:113], v[46:47], 0.5, v[50:51] op_sel_hi:[1,0,1] neg_lo:[0,0,1] neg_hi:[0,0,1]
	v_cvt_f16_f32_e32 v36, v42
	v_cvt_f16_f32_sdwa v48, v43 dst_sel:WORD_1 dst_unused:UNUSED_PAD src0_sel:DWORD
	v_add_co_u32_e32 v42, vcc, s61, v40
	v_or_b32_e32 v110, v48, v36
	s_nop 0
	v_addc_co_u32_e32 v43, vcc, 0, v41, vcc
	global_store_dwordx2 v[42:43], v[44:45], off
	s_branch .LBB0_427

.LBB0_499:
	v_mov_b32_e32 v2, v210
	s_mov_b32 s43, s8
	v_and_b32_e32 v3, 0x1ff, v2
	v_lshlrev_b32_e32 v2, 5, v2
	v_and_or_b32 v2, v2, s94, v3
	v_ashrrev_i32_e32 v4, 5, v2
	v_lshlrev_b32_e32 v2, 3, v2
	v_lshlrev_b32_e32 v4, 3, v4
	v_add3_u32 v18, 0, v2, v4
	ds_read_b64 v[128:129], v18
	ds_read_b64 v[134:135], v18 offset:4224
	ds_read_b64 v[136:137], v18 offset:8448
	ds_read_b64 v[138:139], v18 offset:12672
	ds_read_b64 v[140:141], v18 offset:16896
	ds_read_b64 v[142:143], v18 offset:21120
	ds_read_b64 v[132:133], v18 offset:25344
	ds_read_b64 v[130:131], v18 offset:29568
	ds_read_b64 v[144:145], v18 offset:33792
	ds_read_b64 v[148:149], v18 offset:38016
	ds_read_b64 v[150:151], v18 offset:42240
	ds_read_b64 v[152:153], v18 offset:46464
	s_waitcnt lgkmcnt(10)
	v_pk_mul_f32 v[162:163], v[134:135], s[10:11]
	s_mov_b32 s74, s11
	v_pk_fma_f32 v[162:163], v[134:135], s[8:9], v[162:163] op_sel:[0,0,1] op_sel_hi:[1,0,0]
	s_waitcnt lgkmcnt(2)
	v_pk_mul_f32 v[178:179], v[148:149], s[42:43]
	v_pk_add_f32 v[194:195], v[134:135], v[148:149]
	v_pk_add_f32 v[134:135], v[134:135], v[148:149] neg_lo:[0,1] neg_hi:[0,1]
	v_pk_mul_f32 v[164:165], v[136:137], s[18:19]
	s_mov_b32 s41, s16
	v_pk_fma_f32 v[178:179], v[148:149], s[74:75], v[178:179] op_sel:[0,0,1] op_sel_hi:[1,0,0] neg_lo:[1,0,0] neg_hi:[1,0,0]
	v_pk_mul_f32 v[148:149], v[134:135], s[18:19]
	v_pk_fma_f32 v[164:165], v[136:137], s[16:17], v[164:165] op_sel:[0,0,1] op_sel_hi:[1,0,0]
	s_mov_b32 s80, s19
	s_waitcnt lgkmcnt(1)
	v_pk_mul_f32 v[180:181], v[150:151], s[40:41]
	v_pk_fma_f32 v[134:135], v[134:135], s[16:17], v[148:149] op_sel:[0,0,1] op_sel_hi:[1,0,0]
	v_pk_add_f32 v[148:149], v[136:137], v[150:151]
	v_pk_add_f32 v[136:137], v[136:137], v[150:151] neg_lo:[0,1] neg_hi:[0,1]
	v_pk_mul_f32 v[166:167], v[138:139], s[26:27]
	s_mov_b32 s78, s37
	s_mov_b32 s39, s24
	v_pk_fma_f32 v[180:181], v[150:151], s[80:81], v[180:181] op_sel:[0,0,1] op_sel_hi:[1,0,0] neg_lo:[1,0,0] neg_hi:[1,0,0]
	v_pk_mul_f32 v[150:151], v[136:137], s[36:37]
	ds_read_b64 v[154:155], v18 offset:50688
	ds_read_b64 v[156:157], v18 offset:54912
	ds_read_b64 v[158:159], v18 offset:59136
	ds_read_b64 v[160:161], v18 offset:63360
	v_pk_fma_f32 v[166:167], v[138:139], s[24:25], v[166:167] op_sel:[0,0,1] op_sel_hi:[1,0,0]
	s_mov_b32 s0, s27
	s_waitcnt lgkmcnt(4)
	v_pk_mul_f32 v[182:183], v[152:153], s[38:39]
	v_pk_fma_f32 v[136:137], v[136:137], s[78:79], v[150:151] op_sel:[0,0,1] op_sel_hi:[1,0,0]
	v_pk_add_f32 v[150:151], v[138:139], v[152:153]
	v_pk_add_f32 v[138:139], v[138:139], v[152:153] neg_lo:[0,1] neg_hi:[0,1]
	v_pk_mul_f32 v[168:169], v[140:141], s[36:37]
	v_pk_fma_f32 v[182:183], v[152:153], s[0:1], v[182:183] op_sel:[0,0,1] op_sel_hi:[1,0,0] neg_lo:[1,0,0] neg_hi:[1,0,0]
	v_pk_mul_f32 v[152:153], v[138:139], s[40:41]
	v_pk_fma_f32 v[168:169], v[140:141], s[78:79], v[168:169] op_sel:[0,0,1] op_sel_hi:[1,0,0]
	v_pk_mul_f32 v[170:171], v[142:143], s[38:39]
	s_waitcnt lgkmcnt(3)
	v_pk_mul_f32 v[184:185], v[154:155], s[36:37]
	v_pk_fma_f32 v[138:139], v[138:139], s[80:81], v[152:153] op_sel:[0,0,1] op_sel_hi:[1,0,0]
	v_pk_add_f32 v[152:153], v[140:141], v[154:155]
	v_pk_add_f32 v[140:141], v[140:141], v[154:155] neg_lo:[0,1] neg_hi:[0,1]
	v_pk_fma_f32 v[170:171], v[142:143], s[0:1], v[170:171] op_sel:[0,0,1] op_sel_hi:[1,0,0]
	v_pk_fma_f32 v[184:185], v[154:155], s[78:79], v[184:185] op_sel:[0,0,1] op_sel_hi:[1,0,0] neg_lo:[1,0,0] neg_hi:[1,0,0]
	s_waitcnt lgkmcnt(2)
	v_pk_mul_f32 v[186:187], v[156:157], s[26:27]
	v_xor_b32_e32 v155, 0x80000000, v140
	v_mov_b32_e32 v154, v141
	v_pk_add_f32 v[140:141], v[142:143], v[156:157]
	v_pk_add_f32 v[142:143], v[142:143], v[156:157] neg_lo:[0,1] neg_hi:[0,1]
	v_pk_mul_f32 v[172:173], v[132:133], s[40:41]
	v_pk_fma_f32 v[186:187], v[156:157], s[24:25], v[186:187] op_sel:[0,0,1] op_sel_hi:[1,0,0] neg_lo:[1,0,0] neg_hi:[1,0,0]
	v_pk_mul_f32 v[156:157], v[142:143], s[40:41]
	v_pk_fma_f32 v[172:173], v[132:133], s[80:81], v[172:173] op_sel:[0,0,1] op_sel_hi:[1,0,0]
	s_waitcnt lgkmcnt(1)
	v_pk_mul_f32 v[188:189], v[158:159], s[18:19]
	v_pk_fma_f32 v[142:143], v[142:143], s[80:81], v[156:157] op_sel:[0,0,1] op_sel_hi:[1,0,0] neg_lo:[1,0,0] neg_hi:[1,0,0]
	v_pk_add_f32 v[156:157], v[132:133], v[158:159]
	v_pk_add_f32 v[132:133], v[132:133], v[158:159] neg_lo:[0,1] neg_hi:[0,1]
	v_pk_mul_f32 v[174:175], v[130:131], s[42:43]
	v_pk_fma_f32 v[188:189], v[158:159], s[16:17], v[188:189] op_sel:[0,0,1] op_sel_hi:[1,0,0] neg_lo:[1,0,0] neg_hi:[1,0,0]
	v_pk_mul_f32 v[158:159], v[132:133], s[36:37]
	v_pk_fma_f32 v[174:175], v[130:131], s[74:75], v[174:175] op_sel:[0,0,1] op_sel_hi:[1,0,0]
	s_waitcnt lgkmcnt(0)
	v_pk_mul_f32 v[190:191], v[160:161], s[10:11]
	v_pk_fma_f32 v[132:133], v[132:133], s[78:79], v[158:159] op_sel:[0,0,1] op_sel_hi:[1,0,0] neg_lo:[1,0,0] neg_hi:[1,0,0]
	v_pk_add_f32 v[158:159], v[130:131], v[160:161]
	v_pk_add_f32 v[130:131], v[130:131], v[160:161] neg_lo:[0,1] neg_hi:[0,1]
	v_xor_b32_e32 v177, 0x80000000, v144
	v_mov_b32_e32 v176, v145
	v_pk_fma_f32 v[190:191], v[160:161], s[8:9], v[190:191] op_sel:[0,0,1] op_sel_hi:[1,0,0] neg_lo:[1,0,0] neg_hi:[1,0,0]
	v_pk_mul_f32 v[160:161], v[130:131], s[18:19]
	v_pk_add_f32 v[192:193], v[128:129], v[144:145]
	v_pk_add_f32 v[144:145], v[128:129], v[144:145] neg_lo:[0,1] neg_hi:[0,1]
	v_pk_fma_f32 v[130:131], v[130:131], s[16:17], v[160:161] op_sel:[0,0,1] op_sel_hi:[1,0,0] neg_lo:[1,0,0] neg_hi:[1,0,0]
	v_pk_add_f32 v[160:161], v[128:129], v[176:177]
	v_pk_add_f32 v[128:129], v[128:129], v[176:177] neg_lo:[0,1] neg_hi:[0,1]
	v_pk_add_f32 v[176:177], v[162:163], v[178:179]
	v_pk_add_f32 v[162:163], v[162:163], v[178:179] neg_lo:[0,1] neg_hi:[0,1]
	v_cvt_f32_u32_e32 v2, v3
	v_pk_mul_f32 v[178:179], v[162:163], s[18:19]
	s_add_i32 s76, s72, s48
	v_pk_fma_f32 v[162:163], v[162:163], s[16:17], v[178:179] op_sel:[0,0,1] op_sel_hi:[1,0,0]
	v_pk_add_f32 v[178:179], v[164:165], v[180:181]
	v_pk_add_f32 v[164:165], v[164:165], v[180:181] neg_lo:[0,1] neg_hi:[0,1]
	v_mul_f32_e32 v2, 0x38800000, v2
	v_pk_mul_f32 v[180:181], v[164:165], s[36:37]
	v_sin_f32_e32 v34, v2
	v_pk_fma_f32 v[164:165], v[164:165], s[78:79], v[180:181] op_sel:[0,0,1] op_sel_hi:[1,0,0]
	v_pk_add_f32 v[180:181], v[166:167], v[182:183]
	v_pk_add_f32 v[166:167], v[166:167], v[182:183] neg_lo:[0,1] neg_hi:[0,1]
	v_cos_f32_e32 v30, v2
	v_pk_mul_f32 v[182:183], v[166:167], s[40:41]
	v_xor_b32_e32 v31, 0x80000000, v34
	v_pk_fma_f32 v[166:167], v[166:167], s[80:81], v[182:183] op_sel:[0,0,1] op_sel_hi:[1,0,0]
	v_pk_add_f32 v[182:183], v[168:169], v[184:185]
	v_pk_add_f32 v[184:185], v[168:169], v[184:185] neg_lo:[0,1] neg_hi:[0,1]
	v_mov_b32_e32 v35, v31
	v_pk_add_f32 v[168:169], v[170:171], v[186:187]
	v_pk_add_f32 v[170:171], v[170:171], v[186:187] neg_lo:[0,1] neg_hi:[0,1]
	v_pk_mul_f32 v[2:3], v[30:31], v[34:35] op_sel:[1,0] op_sel_hi:[0,1]
	v_pk_mul_f32 v[186:187], v[170:171], s[40:41]
	v_pk_fma_f32 v[44:45], v[30:31], v[30:31], v[2:3] op_sel_hi:[1,0,1]
	v_pk_fma_f32 v[170:171], v[170:171], s[80:81], v[186:187] op_sel:[0,0,1] op_sel_hi:[1,0,0] neg_lo:[1,0,0] neg_hi:[1,0,0]
	v_pk_add_f32 v[186:187], v[172:173], v[188:189]
	v_pk_add_f32 v[172:173], v[172:173], v[188:189] neg_lo:[0,1] neg_hi:[0,1]
	v_pk_mul_f32 v[2:3], v[34:35], v[44:45] op_sel:[0,1] op_sel_hi:[1,0]
	v_pk_mul_f32 v[188:189], v[172:173], s[36:37]
	v_xor_b32_e32 v54, 0x80000000, v45
	v_pk_fma_f32 v[172:173], v[172:173], s[78:79], v[188:189] op_sel:[0,0,1] op_sel_hi:[1,0,0] neg_lo:[1,0,0] neg_hi:[1,0,0]
	v_pk_add_f32 v[188:189], v[174:175], v[190:191]
	v_pk_add_f32 v[174:175], v[174:175], v[190:191] neg_lo:[0,1] neg_hi:[0,1]
	v_mov_b32_e32 v55, v45
	v_pk_mul_f32 v[190:191], v[174:175], s[18:19]
	v_pk_fma_f32 v[46:47], v[30:31], v[44:45], v[2:3] op_sel_hi:[0,1,1]
	v_pk_fma_f32 v[174:175], v[174:175], s[16:17], v[190:191] op_sel:[0,0,1] op_sel_hi:[1,0,0] neg_lo:[1,0,0] neg_hi:[1,0,0]
	v_pk_add_f32 v[190:191], v[192:193], v[152:153]
	v_pk_add_f32 v[152:153], v[192:193], v[152:153] neg_lo:[0,1] neg_hi:[0,1]
	v_pk_add_f32 v[192:193], v[194:195], v[140:141]
	v_pk_add_f32 v[140:141], v[194:195], v[140:141] neg_lo:[0,1] neg_hi:[0,1]
	v_pk_mul_f32 v[2:3], v[44:45], v[54:55] op_sel:[1,0] op_sel_hi:[0,1]
	v_pk_mul_f32 v[194:195], v[140:141], s[36:37]
	v_pk_fma_f32 v[52:53], v[44:45], v[44:45], v[2:3] op_sel_hi:[1,0,1]
	v_pk_fma_f32 v[140:141], v[140:141], s[78:79], v[194:195] op_sel:[0,0,1] op_sel_hi:[1,0,0]
	v_pk_add_f32 v[194:195], v[148:149], v[156:157]
	v_pk_add_f32 v[156:157], v[148:149], v[156:157] neg_lo:[0,1] neg_hi:[0,1]
	v_xor_b32_e32 v58, 0x80000000, v53
	v_pk_add_f32 v[148:149], v[150:151], v[158:159]
	v_pk_add_f32 v[150:151], v[150:151], v[158:159] neg_lo:[0,1] neg_hi:[0,1]
	v_mov_b32_e32 v59, v53
	v_pk_mul_f32 v[158:159], v[150:151], s[36:37]
	v_pk_mul_f32 v[2:3], v[52:53], v[58:59] op_sel:[1,0] op_sel_hi:[0,1]
	v_pk_fma_f32 v[150:151], v[150:151], s[78:79], v[158:159] op_sel:[0,0,1] op_sel_hi:[1,0,0] neg_lo:[1,0,0] neg_hi:[1,0,0]
	v_pk_add_f32 v[158:159], v[144:145], v[154:155]
	v_pk_add_f32 v[144:145], v[144:145], v[154:155] neg_lo:[0,1] neg_hi:[0,1]
	v_pk_add_f32 v[154:155], v[134:135], v[142:143]
	v_pk_add_f32 v[134:135], v[134:135], v[142:143] neg_lo:[0,1] neg_hi:[0,1]
	v_pk_fma_f32 v[48:49], v[52:53], v[52:53], v[2:3] op_sel_hi:[1,0,1]
	v_pk_mul_f32 v[142:143], v[134:135], s[36:37]
	v_pk_mul_f32 v[2:3], v[58:59], v[48:49] op_sel:[0,1] op_sel_hi:[1,0]
	v_pk_fma_f32 v[134:135], v[134:135], s[78:79], v[142:143] op_sel:[0,0,1] op_sel_hi:[1,0,0]
	v_pk_add_f32 v[142:143], v[136:137], v[132:133]
	v_pk_add_f32 v[136:137], v[136:137], v[132:133] neg_lo:[0,1] neg_hi:[0,1]
	v_pk_fma_f32 v[36:37], v[52:53], v[48:49], v[2:3] op_sel_hi:[0,1,1]
	v_pk_add_f32 v[132:133], v[138:139], v[130:131]
	v_pk_add_f32 v[130:131], v[138:139], v[130:131] neg_lo:[0,1] neg_hi:[0,1]
	v_pk_mul_f32 v[2:3], v[58:59], v[36:37] op_sel:[0,1] op_sel_hi:[1,0]
	v_pk_mul_f32 v[138:139], v[130:131], s[36:37]
	v_pk_fma_f32 v[26:27], v[52:53], v[36:37], v[2:3] op_sel_hi:[0,1,1]
	v_pk_fma_f32 v[130:131], v[130:131], s[78:79], v[138:139] op_sel:[0,0,1] op_sel_hi:[1,0,0] neg_lo:[1,0,0] neg_hi:[1,0,0]
	v_pk_add_f32 v[138:139], v[160:161], v[182:183]
	v_pk_add_f32 v[160:161], v[160:161], v[182:183] neg_lo:[0,1] neg_hi:[0,1]
	v_pk_add_f32 v[182:183], v[176:177], v[168:169]
	v_pk_add_f32 v[168:169], v[176:177], v[168:169] neg_lo:[0,1] neg_hi:[0,1]
	v_pk_mul_f32 v[2:3], v[58:59], v[26:27] op_sel:[0,1] op_sel_hi:[1,0]
	v_pk_mul_f32 v[176:177], v[168:169], s[36:37]
	v_pk_fma_f32 v[20:21], v[52:53], v[26:27], v[2:3] op_sel_hi:[0,1,1]
	v_pk_fma_f32 v[168:169], v[168:169], s[78:79], v[176:177] op_sel:[0,0,1] op_sel_hi:[1,0,0]
	v_pk_add_f32 v[176:177], v[178:179], v[186:187]
	v_pk_add_f32 v[186:187], v[178:179], v[186:187] neg_lo:[0,1] neg_hi:[0,1]
	v_pk_mul_f32 v[2:3], v[58:59], v[20:21] op_sel:[0,1] op_sel_hi:[1,0]
	v_pk_add_f32 v[178:179], v[180:181], v[188:189]
	v_pk_add_f32 v[180:181], v[180:181], v[188:189] neg_lo:[0,1] neg_hi:[0,1]
	v_pk_fma_f32 v[10:11], v[52:53], v[20:21], v[2:3] op_sel_hi:[0,1,1]
	v_pk_mul_f32 v[188:189], v[180:181], s[36:37]
	v_pk_mul_f32 v[2:3], v[58:59], v[10:11] op_sel:[0,1] op_sel_hi:[1,0]
	v_pk_fma_f32 v[180:181], v[180:181], s[78:79], v[188:189] op_sel:[0,0,1] op_sel_hi:[1,0,0] neg_lo:[1,0,0] neg_hi:[1,0,0]
	v_pk_add_f32 v[188:189], v[128:129], v[184:185] op_sel:[0,1] op_sel_hi:[1,0] neg_hi:[0,1]
	v_pk_add_f32 v[128:129], v[128:129], v[184:185] op_sel:[0,1] op_sel_hi:[1,0] neg_lo:[0,1]
	v_pk_add_f32 v[184:185], v[162:163], v[170:171]
	v_pk_add_f32 v[162:163], v[162:163], v[170:171] neg_lo:[0,1] neg_hi:[0,1]
	v_pk_fma_f32 v[4:5], v[52:53], v[10:11], v[2:3] op_sel_hi:[0,1,1]
	v_pk_mul_f32 v[170:171], v[162:163], s[36:37]
	v_pk_mul_f32 v[8:9], v[54:55], v[4:5] op_sel:[0,1] op_sel_hi:[1,0]
	v_pk_fma_f32 v[162:163], v[162:163], s[78:79], v[170:171] op_sel:[0,0,1] op_sel_hi:[1,0,0]
	v_pk_add_f32 v[170:171], v[164:165], v[172:173]
	v_pk_add_f32 v[172:173], v[164:165], v[172:173] neg_lo:[0,1] neg_hi:[0,1]
	v_pk_mul_f32 v[14:15], v[34:35], v[4:5] op_sel:[0,1] op_sel_hi:[1,0]
	v_pk_add_f32 v[164:165], v[166:167], v[174:175]
	v_pk_add_f32 v[166:167], v[166:167], v[174:175] neg_lo:[0,1] neg_hi:[0,1]
	v_pk_mul_f32 v[32:33], v[54:55], v[10:11] op_sel:[0,1] op_sel_hi:[1,0]
	v_pk_mul_f32 v[174:175], v[166:167], s[36:37]
	v_pk_mul_f32 v[40:41], v[34:35], v[10:11] op_sel:[0,1] op_sel_hi:[1,0]
	v_pk_fma_f32 v[166:167], v[166:167], s[78:79], v[174:175] op_sel:[0,0,1] op_sel_hi:[1,0,0] neg_lo:[1,0,0] neg_hi:[1,0,0]
	v_pk_add_f32 v[174:175], v[190:191], v[194:195]
	v_pk_add_f32 v[190:191], v[190:191], v[194:195] neg_lo:[0,1] neg_hi:[0,1]
	v_pk_add_f32 v[194:195], v[192:193], v[148:149]
	v_pk_add_f32 v[192:193], v[192:193], v[148:149] neg_lo:[0,1] neg_hi:[0,1]
	v_pk_mul_f32 v[62:63], v[54:55], v[20:21] op_sel:[0,1] op_sel_hi:[1,0]
	v_pk_add_f32 v[148:149], v[152:153], v[156:157] op_sel:[0,1] op_sel_hi:[1,0] neg_hi:[0,1]
	v_pk_add_f32 v[152:153], v[152:153], v[156:157] op_sel:[0,1] op_sel_hi:[1,0] neg_lo:[0,1]
	v_pk_add_f32 v[156:157], v[140:141], v[150:151]
	v_pk_add_f32 v[150:151], v[140:141], v[150:151] neg_lo:[0,1] neg_hi:[0,1]
	v_pk_mul_f32 v[66:67], v[34:35], v[20:21] op_sel:[0,1] op_sel_hi:[1,0]
	v_pk_add_f32 v[140:141], v[158:159], v[142:143]
	v_pk_add_f32 v[142:143], v[158:159], v[142:143] neg_lo:[0,1] neg_hi:[0,1]
	v_pk_add_f32 v[158:159], v[154:155], v[132:133]
	v_pk_add_f32 v[154:155], v[154:155], v[132:133] neg_lo:[0,1] neg_hi:[0,1]
	v_pk_mul_f32 v[78:79], v[54:55], v[26:27] op_sel:[0,1] op_sel_hi:[1,0]
	v_pk_add_f32 v[132:133], v[144:145], v[136:137] op_sel:[0,1] op_sel_hi:[1,0] neg_hi:[0,1]
	v_pk_add_f32 v[136:137], v[144:145], v[136:137] op_sel:[0,1] op_sel_hi:[1,0] neg_lo:[0,1]
	v_pk_add_f32 v[144:145], v[134:135], v[130:131]
	v_pk_add_f32 v[134:135], v[134:135], v[130:131] neg_lo:[0,1] neg_hi:[0,1]
	v_pk_mul_f32 v[82:83], v[34:35], v[26:27] op_sel:[0,1] op_sel_hi:[1,0]
	v_pk_add_f32 v[130:131], v[138:139], v[176:177]
	v_pk_add_f32 v[138:139], v[138:139], v[176:177] neg_lo:[0,1] neg_hi:[0,1]
	v_pk_add_f32 v[176:177], v[182:183], v[178:179]
	v_pk_add_f32 v[182:183], v[182:183], v[178:179] neg_lo:[0,1] neg_hi:[0,1]
	v_pk_mul_f32 v[92:93], v[54:55], v[36:37] op_sel:[0,1] op_sel_hi:[1,0]
	v_pk_add_f32 v[178:179], v[160:161], v[186:187] op_sel:[0,1] op_sel_hi:[1,0] neg_hi:[0,1]
	v_pk_add_f32 v[160:161], v[160:161], v[186:187] op_sel:[0,1] op_sel_hi:[1,0] neg_lo:[0,1]
	v_pk_add_f32 v[186:187], v[168:169], v[180:181]
	v_pk_add_f32 v[180:181], v[168:169], v[180:181] neg_lo:[0,1] neg_hi:[0,1]
	v_pk_mul_f32 v[96:97], v[34:35], v[36:37] op_sel:[0,1] op_sel_hi:[1,0]
	v_pk_add_f32 v[168:169], v[188:189], v[170:171]
	v_pk_add_f32 v[170:171], v[188:189], v[170:171] neg_lo:[0,1] neg_hi:[0,1]
	v_pk_add_f32 v[188:189], v[184:185], v[164:165]
	v_pk_add_f32 v[184:185], v[184:185], v[164:165] neg_lo:[0,1] neg_hi:[0,1]
	v_pk_mul_f32 v[106:107], v[54:55], v[48:49] op_sel:[0,1] op_sel_hi:[1,0]
	v_pk_add_f32 v[164:165], v[128:129], v[172:173] op_sel:[0,1] op_sel_hi:[1,0] neg_hi:[0,1]
	v_pk_add_f32 v[128:129], v[128:129], v[172:173] op_sel:[0,1] op_sel_hi:[1,0] neg_lo:[0,1]
	v_pk_add_f32 v[172:173], v[162:163], v[166:167]
	v_pk_add_f32 v[166:167], v[162:163], v[166:167] neg_lo:[0,1] neg_hi:[0,1]
	v_pk_mul_f32 v[110:111], v[34:35], v[48:49] op_sel:[0,1] op_sel_hi:[1,0]
	v_pk_add_f32 v[162:163], v[174:175], v[194:195]
	v_pk_add_f32 v[174:175], v[174:175], v[194:195] neg_lo:[0,1] neg_hi:[0,1]
	v_pk_add_f32 v[194:195], v[190:191], v[192:193] op_sel:[0,1] op_sel_hi:[1,0] neg_hi:[0,1]
	v_pk_add_f32 v[190:191], v[190:191], v[192:193] op_sel:[0,1] op_sel_hi:[1,0] neg_lo:[0,1]
	v_pk_add_f32 v[192:193], v[148:149], v[156:157]
	v_pk_add_f32 v[148:149], v[148:149], v[156:157] neg_lo:[0,1] neg_hi:[0,1]
	v_pk_add_f32 v[156:157], v[152:153], v[150:151] op_sel:[0,1] op_sel_hi:[1,0] neg_hi:[0,1]
	v_pk_add_f32 v[150:151], v[152:153], v[150:151] op_sel:[0,1] op_sel_hi:[1,0] neg_lo:[0,1]
	v_pk_add_f32 v[152:153], v[140:141], v[158:159]
	v_pk_add_f32 v[140:141], v[140:141], v[158:159] neg_lo:[0,1] neg_hi:[0,1]
	v_pk_add_f32 v[158:159], v[142:143], v[154:155] op_sel:[0,1] op_sel_hi:[1,0] neg_hi:[0,1]
	v_pk_add_f32 v[142:143], v[142:143], v[154:155] op_sel:[0,1] op_sel_hi:[1,0] neg_lo:[0,1]
	v_pk_add_f32 v[154:155], v[132:133], v[144:145]
	v_pk_add_f32 v[132:133], v[132:133], v[144:145] neg_lo:[0,1] neg_hi:[0,1]
	v_pk_add_f32 v[144:145], v[136:137], v[134:135] op_sel:[0,1] op_sel_hi:[1,0] neg_hi:[0,1]
	v_pk_add_f32 v[134:135], v[136:137], v[134:135] op_sel:[0,1] op_sel_hi:[1,0] neg_lo:[0,1]
	v_pk_add_f32 v[136:137], v[130:131], v[176:177]
	v_pk_mul_f32 v[120:121], v[54:55], v[52:53] op_sel:[0,1] op_sel_hi:[1,0]
	v_pk_mul_f32 v[124:125], v[34:35], v[52:53] op_sel:[0,1] op_sel_hi:[1,0]
	v_pk_mul_f32 v[34:35], v[34:35], v[136:137] op_sel:[0,1] op_sel_hi:[1,0]
	v_xor_b32_e32 v72, 0x80000000, v47
	v_mov_b32_e32 v73, v47
	v_pk_fma_f32 v[8:9], v[44:45], v[4:5], v[8:9] op_sel_hi:[0,1,1]
	v_pk_fma_f32 v[14:15], v[30:31], v[4:5], v[14:15] op_sel_hi:[0,1,1]
	v_xor_b32_e32 v22, 0x80000000, v5
	v_pk_fma_f32 v[32:33], v[44:45], v[10:11], v[32:33] op_sel_hi:[0,1,1]
	v_pk_fma_f32 v[40:41], v[30:31], v[10:11], v[40:41] op_sel_hi:[0,1,1]
	v_pk_fma_f32 v[62:63], v[44:45], v[20:21], v[62:63] op_sel_hi:[0,1,1]
	v_pk_fma_f32 v[66:67], v[30:31], v[20:21], v[66:67] op_sel_hi:[0,1,1]
	v_pk_fma_f32 v[78:79], v[44:45], v[26:27], v[78:79] op_sel_hi:[0,1,1]
	v_pk_fma_f32 v[82:83], v[30:31], v[26:27], v[82:83] op_sel_hi:[0,1,1]
	v_pk_fma_f32 v[92:93], v[44:45], v[36:37], v[92:93] op_sel_hi:[0,1,1]
	v_pk_fma_f32 v[96:97], v[30:31], v[36:37], v[96:97] op_sel_hi:[0,1,1]
	v_pk_fma_f32 v[106:107], v[44:45], v[48:49], v[106:107] op_sel_hi:[0,1,1]
	v_pk_fma_f32 v[110:111], v[30:31], v[48:49], v[110:111] op_sel_hi:[0,1,1]
	v_pk_fma_f32 v[120:121], v[44:45], v[52:53], v[120:121] op_sel_hi:[0,1,1]
	v_pk_fma_f32 v[124:125], v[30:31], v[52:53], v[124:125] op_sel_hi:[0,1,1]
	v_mov_b32_e32 v23, v5
	v_pk_add_f32 v[130:131], v[130:131], v[176:177] neg_lo:[0,1] neg_hi:[0,1]
	v_pk_add_f32 v[176:177], v[138:139], v[182:183] op_sel:[0,1] op_sel_hi:[1,0] neg_hi:[0,1]
	v_pk_add_f32 v[138:139], v[138:139], v[182:183] op_sel:[0,1] op_sel_hi:[1,0] neg_lo:[0,1]
	v_pk_add_f32 v[182:183], v[178:179], v[186:187]
	v_pk_add_f32 v[178:179], v[178:179], v[186:187] neg_lo:[0,1] neg_hi:[0,1]
	v_pk_add_f32 v[186:187], v[160:161], v[180:181] op_sel:[0,1] op_sel_hi:[1,0] neg_hi:[0,1]
	v_pk_add_f32 v[160:161], v[160:161], v[180:181] op_sel:[0,1] op_sel_hi:[1,0] neg_lo:[0,1]
	v_pk_add_f32 v[180:181], v[168:169], v[188:189]
	v_pk_fma_f32 v[30:31], v[30:31], v[136:137], v[34:35] op_sel_hi:[0,1,1]
	v_pk_mul_f32 v[34:35], v[54:55], v[152:153] op_sel:[0,1] op_sel_hi:[1,0]
	v_pk_mul_f32 v[2:3], v[72:73], v[4:5] op_sel:[0,1] op_sel_hi:[1,0]
	v_xor_b32_e32 v12, 0x80000000, v9
	v_pk_mul_f32 v[24:25], v[72:73], v[10:11] op_sel:[0,1] op_sel_hi:[1,0]
	v_xor_b32_e32 v38, 0x80000000, v33
	v_xor_b32_e32 v50, 0x80000000, v11
	v_pk_mul_f32 v[56:57], v[72:73], v[20:21] op_sel:[0,1] op_sel_hi:[1,0]
	v_xor_b32_e32 v64, 0x80000000, v63
	v_xor_b32_e32 v70, 0x80000000, v21
	v_pk_mul_f32 v[74:75], v[72:73], v[26:27] op_sel:[0,1] op_sel_hi:[1,0]
	v_xor_b32_e32 v80, 0x80000000, v79
	v_xor_b32_e32 v86, 0x80000000, v27
	v_pk_mul_f32 v[88:89], v[72:73], v[36:37] op_sel:[0,1] op_sel_hi:[1,0]
	v_xor_b32_e32 v94, 0x80000000, v93
	v_xor_b32_e32 v100, 0x80000000, v37
	v_pk_mul_f32 v[102:103], v[72:73], v[48:49] op_sel:[0,1] op_sel_hi:[1,0]
	v_xor_b32_e32 v108, 0x80000000, v107
	v_xor_b32_e32 v114, 0x80000000, v49
	v_pk_mul_f32 v[116:117], v[52:53], v[72:73] op_sel:[1,0] op_sel_hi:[0,1]
	v_xor_b32_e32 v122, 0x80000000, v121
	v_mov_b32_e32 v123, v121
	v_mov_b32_e32 v115, v49
	v_mov_b32_e32 v109, v107
	v_mov_b32_e32 v101, v37
	v_mov_b32_e32 v95, v93
	v_mov_b32_e32 v87, v27
	v_mov_b32_e32 v81, v79
	v_mov_b32_e32 v71, v21
	v_mov_b32_e32 v65, v63
	v_mov_b32_e32 v51, v11
	v_mov_b32_e32 v39, v33
	v_mov_b32_e32 v13, v9
	v_pk_fma_f32 v[34:35], v[44:45], v[152:153], v[34:35] op_sel_hi:[0,1,1]
	v_pk_mul_f32 v[44:45], v[72:73], v[180:181] op_sel:[0,1] op_sel_hi:[1,0]
	v_pk_mul_f32 v[22:23], v[150:151], v[22:23] op_sel:[1,0] op_sel_hi:[0,1]
	v_pk_fma_f32 v[2:3], v[46:47], v[4:5], v[2:3] op_sel_hi:[0,1,1]
	v_pk_fma_f32 v[24:25], v[46:47], v[10:11], v[24:25] op_sel_hi:[0,1,1]
	v_pk_fma_f32 v[56:57], v[46:47], v[20:21], v[56:57] op_sel_hi:[0,1,1]
	v_pk_fma_f32 v[74:75], v[46:47], v[26:27], v[74:75] op_sel_hi:[0,1,1]
	v_xor_b32_e32 v84, 0x80000000, v83
	v_pk_fma_f32 v[88:89], v[46:47], v[36:37], v[88:89] op_sel_hi:[0,1,1]
	v_pk_fma_f32 v[102:103], v[46:47], v[48:49], v[102:103] op_sel_hi:[0,1,1]
	v_pk_fma_f32 v[116:117], v[52:53], v[46:47], v[116:117] op_sel_hi:[1,0,1]
	v_mov_b32_e32 v85, v83
	v_pk_fma_f32 v[44:45], v[46:47], v[180:181], v[44:45] op_sel_hi:[0,1,1]
	v_pk_mul_f32 v[46:47], v[58:59], v[192:193] op_sel:[0,1] op_sel_hi:[1,0]
	v_pk_mul_f32 v[54:55], v[122:123], v[154:155] op_sel:[0,1] op_sel_hi:[1,0]
	v_pk_mul_f32 v[72:73], v[114:115], v[194:195] op_sel:[0,1] op_sel_hi:[1,0]
	v_pk_mul_f32 v[108:109], v[108:109], v[158:159] op_sel:[0,1] op_sel_hi:[1,0]
	v_pk_mul_f32 v[100:101], v[100:101], v[156:157] op_sel:[0,1] op_sel_hi:[1,0]
	v_pk_mul_f32 v[94:95], v[94:95], v[144:145] op_sel:[0,1] op_sel_hi:[1,0]
	v_pk_mul_f32 v[86:87], v[174:175], v[86:87] op_sel:[1,0] op_sel_hi:[0,1]
	v_pk_mul_f32 v[80:81], v[140:141], v[80:81] op_sel:[1,0] op_sel_hi:[0,1]
	v_pk_mul_f32 v[70:71], v[148:149], v[70:71] op_sel:[1,0] op_sel_hi:[0,1]
	v_pk_mul_f32 v[64:65], v[132:133], v[64:65] op_sel:[1,0] op_sel_hi:[0,1]
	v_pk_mul_f32 v[50:51], v[190:191], v[50:51] op_sel:[1,0] op_sel_hi:[0,1]
	v_pk_mul_f32 v[38:39], v[142:143], v[38:39] op_sel:[1,0] op_sel_hi:[0,1]
	v_pk_fma_f32 v[4:5], v[150:151], v[4:5], v[22:23] op_sel_hi:[1,0,1]
	v_pk_mul_f32 v[12:13], v[134:135], v[12:13] op_sel:[1,0] op_sel_hi:[0,1]
	v_xor_b32_e32 v112, 0x80000000, v111
	v_mov_b32_e32 v113, v111
	v_pk_fma_f32 v[46:47], v[52:53], v[192:193], v[46:47] op_sel_hi:[0,1,1]
	v_pk_fma_f32 v[54:55], v[120:121], v[154:155], v[54:55] op_sel_hi:[0,1,1]
	v_pk_fma_f32 v[48:49], v[48:49], v[194:195], v[72:73] op_sel_hi:[0,1,1]
	v_pk_fma_f32 v[106:107], v[106:107], v[158:159], v[108:109] op_sel_hi:[0,1,1]
	v_pk_fma_f32 v[36:37], v[36:37], v[156:157], v[100:101] op_sel_hi:[0,1,1]
	v_pk_fma_f32 v[92:93], v[92:93], v[144:145], v[94:95] op_sel_hi:[0,1,1]
	v_pk_fma_f32 v[26:27], v[174:175], v[26:27], v[86:87] op_sel_hi:[1,0,1]
	v_pk_mul_f32 v[84:85], v[130:131], v[84:85] op_sel:[1,0] op_sel_hi:[0,1]
	v_pk_fma_f32 v[78:79], v[140:141], v[78:79], v[80:81] op_sel_hi:[1,0,1]
	v_pk_fma_f32 v[20:21], v[148:149], v[20:21], v[70:71] op_sel_hi:[1,0,1]
	v_pk_fma_f32 v[62:63], v[132:133], v[62:63], v[64:65] op_sel_hi:[1,0,1]
	v_pk_fma_f32 v[10:11], v[190:191], v[10:11], v[50:51] op_sel_hi:[1,0,1]
	v_pk_fma_f32 v[32:33], v[142:143], v[32:33], v[38:39] op_sel_hi:[1,0,1]
	v_pk_fma_f32 v[8:9], v[134:135], v[8:9], v[12:13] op_sel_hi:[1,0,1]
	ds_write_b64 v18, v[162:163]
	ds_write_b64 v18, v[26:27] offset:4224
	ds_write_b64 v18, v[48:49] offset:8448
	ds_write_b64 v18, v[10:11] offset:12672
	ds_write_b64 v18, v[46:47] offset:16896
	ds_write_b64 v18, v[20:21] offset:21120
	ds_write_b64 v18, v[36:37] offset:25344
	ds_write_b64 v18, v[4:5] offset:29568
	ds_write_b64 v18, v[34:35] offset:33792
	ds_write_b64 v18, v[78:79] offset:38016
	ds_write_b64 v18, v[106:107] offset:42240
	ds_write_b64 v18, v[32:33] offset:46464
	ds_write_b64 v18, v[54:55] offset:50688
	ds_write_b64 v18, v[62:63] offset:54912
	ds_write_b64 v18, v[92:93] offset:59136
	ds_write_b64 v18, v[8:9] offset:63360
	v_add_u32_e32 v4, 0x10800, v18
	v_xor_b32_e32 v42, 0x80000000, v41
	v_mov_b32_e32 v43, v41
	v_pk_mul_f32 v[72:73], v[112:113], v[176:177] op_sel:[0,1] op_sel_hi:[1,0]
	v_pk_fma_f32 v[82:83], v[130:131], v[82:83], v[84:85] op_sel_hi:[1,0,1]
	ds_write_b64 v4, v[30:31]
	v_add_u32_e32 v4, 0x11880, v18
	v_xor_b32_e32 v126, 0x80000000, v125
	v_mov_b32_e32 v127, v125
	v_pk_fma_f32 v[72:73], v[110:111], v[176:177], v[72:73] op_sel_hi:[0,1,1]
	v_pk_mul_f32 v[42:43], v[138:139], v[42:43] op_sel:[1,0] op_sel_hi:[0,1]
	ds_write_b64 v4, v[82:83]
	v_add_u32_e32 v4, 0x12900, v18
	v_xor_b32_e32 v68, 0x80000000, v67
	v_mov_b32_e32 v69, v67
	v_pk_mul_f32 v[52:53], v[126:127], v[182:183] op_sel:[0,1] op_sel_hi:[1,0]
	v_pk_fma_f32 v[40:41], v[138:139], v[40:41], v[42:43] op_sel_hi:[1,0,1]
	ds_write_b64 v4, v[72:73]
	v_add_u32_e32 v4, 0x13980, v18
	v_xor_b32_e32 v98, 0x80000000, v97
	v_mov_b32_e32 v99, v97
	v_pk_fma_f32 v[52:53], v[124:125], v[182:183], v[52:53] op_sel_hi:[0,1,1]
	v_pk_mul_f32 v[68:69], v[178:179], v[68:69] op_sel:[1,0] op_sel_hi:[0,1]
	ds_write_b64 v4, v[40:41]
	v_add_u32_e32 v4, 0x14a00, v18
	v_xor_b32_e32 v16, 0x80000000, v15
	v_mov_b32_e32 v17, v15
	v_pk_mul_f32 v[98:99], v[98:99], v[186:187] op_sel:[0,1] op_sel_hi:[1,0]
	v_pk_fma_f32 v[66:67], v[178:179], v[66:67], v[68:69] op_sel_hi:[1,0,1]
	ds_write_b64 v4, v[52:53]
	v_add_u32_e32 v4, 0x15a80, v18
	v_pk_fma_f32 v[96:97], v[96:97], v[186:187], v[98:99] op_sel_hi:[0,1,1]
	v_pk_mul_f32 v[16:17], v[160:161], v[16:17] op_sel:[1,0] op_sel_hi:[0,1]
	ds_write_b64 v4, v[66:67]
	v_add_u32_e32 v4, 0x16b00, v18
	v_xor_b32_e32 v76, 0x80000000, v75
	v_mov_b32_e32 v77, v75
	v_pk_add_f32 v[168:169], v[168:169], v[188:189] neg_lo:[0,1] neg_hi:[0,1]
	v_pk_fma_f32 v[14:15], v[160:161], v[14:15], v[16:17] op_sel_hi:[1,0,1]
	ds_write_b64 v4, v[96:97]
	v_add_u32_e32 v4, 0x17b80, v18
	v_xor_b32_e32 v104, 0x80000000, v103
	v_mov_b32_e32 v105, v103
	v_pk_add_f32 v[188:189], v[170:171], v[184:185] op_sel:[0,1] op_sel_hi:[1,0] neg_hi:[0,1]
	v_pk_mul_f32 v[76:77], v[168:169], v[76:77] op_sel:[1,0] op_sel_hi:[0,1]
	ds_write_b64 v4, v[14:15]
	v_add_u32_e32 v4, 0x18c00, v18
	v_xor_b32_e32 v28, 0x80000000, v25
	v_mov_b32_e32 v29, v25
	v_pk_add_f32 v[170:171], v[170:171], v[184:185] op_sel:[0,1] op_sel_hi:[1,0] neg_lo:[0,1]
	v_pk_mul_f32 v[104:105], v[104:105], v[188:189] op_sel:[0,1] op_sel_hi:[1,0]
	v_pk_fma_f32 v[74:75], v[168:169], v[74:75], v[76:77] op_sel_hi:[1,0,1]
	ds_write_b64 v4, v[44:45]
	v_add_u32_e32 v4, 0x19c80, v18
	v_xor_b32_e32 v118, 0x80000000, v117
	v_mov_b32_e32 v119, v117
	v_pk_add_f32 v[184:185], v[164:165], v[172:173]
	v_pk_fma_f32 v[102:103], v[102:103], v[188:189], v[104:105] op_sel_hi:[0,1,1]
	v_pk_mul_f32 v[28:29], v[170:171], v[28:29] op_sel:[1,0] op_sel_hi:[0,1]
	ds_write_b64 v4, v[74:75]
	v_add_u32_e32 v4, 0x1ad00, v18
	v_xor_b32_e32 v60, 0x80000000, v57
	v_mov_b32_e32 v61, v57
	v_pk_add_f32 v[164:165], v[164:165], v[172:173] neg_lo:[0,1] neg_hi:[0,1]
	v_pk_mul_f32 v[58:59], v[118:119], v[184:185] op_sel:[0,1] op_sel_hi:[1,0]
	v_pk_fma_f32 v[24:25], v[170:171], v[24:25], v[28:29] op_sel_hi:[1,0,1]
	ds_write_b64 v4, v[102:103]
	v_add_u32_e32 v4, 0x1bd80, v18
	v_xor_b32_e32 v90, 0x80000000, v89
	v_mov_b32_e32 v91, v89
	v_pk_add_f32 v[172:173], v[128:129], v[166:167] op_sel:[0,1] op_sel_hi:[1,0] neg_hi:[0,1]
	v_pk_fma_f32 v[58:59], v[116:117], v[184:185], v[58:59] op_sel_hi:[0,1,1]
	v_pk_mul_f32 v[60:61], v[164:165], v[60:61] op_sel:[1,0] op_sel_hi:[0,1]
	ds_write_b64 v4, v[24:25]
	v_add_u32_e32 v4, 0x1ce00, v18
	v_xor_b32_e32 v6, 0x80000000, v3
	v_mov_b32_e32 v7, v3
	v_pk_add_f32 v[128:129], v[128:129], v[166:167] op_sel:[0,1] op_sel_hi:[1,0] neg_lo:[0,1]
	v_pk_mul_f32 v[90:91], v[90:91], v[172:173] op_sel:[0,1] op_sel_hi:[1,0]
	v_pk_fma_f32 v[56:57], v[164:165], v[56:57], v[60:61] op_sel_hi:[1,0,1]
	ds_write_b64 v4, v[58:59]
	v_add_u32_e32 v4, 0x1de80, v18
	v_pk_fma_f32 v[88:89], v[88:89], v[172:173], v[90:91] op_sel_hi:[0,1,1]
	v_pk_mul_f32 v[6:7], v[128:129], v[6:7] op_sel:[1,0] op_sel_hi:[0,1]
	ds_write_b64 v4, v[56:57]
	v_add_u32_e32 v4, 0x1ef00, v18
	v_pk_fma_f32 v[2:3], v[128:129], v[2:3], v[6:7] op_sel_hi:[1,0,1]
	ds_write_b64 v4, v[88:89]
	v_add_u32_e32 v4, 0x1ff80, v18
	ds_write_b64 v4, v[2:3]
	v_mov_b32_e32 v2, v210
	s_waitcnt lgkmcnt(0)
	s_barrier
	s_ashr_i32 s77, s76, 31
	v_and_b32_e32 v3, 15, v2
	v_lshlrev_b32_e32 v2, 5, v2
	v_and_b32_e32 v4, 0xfffffe00, v2
	v_lshl_add_u32 v5, v4, 3, 0
	v_lshlrev_b32_e32 v6, 3, v3
	v_ashrrev_i32_e32 v7, 2, v4
	v_add3_u32 v18, v5, v6, v7
	v_add_u32_e32 v196, 0x800, v18
	ds_read2_b64 v[128:131], v18 offset1:16
	ds_read2_b64 v[132:135], v18 offset0:33 offset1:49
	ds_read2_b64 v[136:139], v18 offset0:66 offset1:82
	ds_read2_b64 v[140:143], v18 offset0:99 offset1:115
	ds_read2_b64 v[148:151], v18 offset0:132 offset1:148
	ds_read2_b64 v[152:155], v18 offset0:165 offset1:181
	ds_read2_b64 v[156:159], v18 offset0:198 offset1:214
	ds_read2_b64 v[160:163], v18 offset0:231 offset1:247
	ds_read2_b64 v[164:167], v196 offset0:8 offset1:24
	ds_read2_b64 v[168:171], v196 offset0:41 offset1:57
	ds_read2_b64 v[172:175], v196 offset0:74 offset1:90
	ds_read2_b64 v[176:179], v196 offset0:107 offset1:123
	ds_read2_b64 v[180:183], v196 offset0:140 offset1:156
	ds_read2_b64 v[184:187], v196 offset0:173 offset1:189
	ds_read2_b64 v[188:191], v196 offset0:206 offset1:222
	ds_read2_b64 v[192:195], v196 offset0:239 offset1:255
	s_waitcnt lgkmcnt(7)
	v_pk_add_f32 v[144:145], v[128:129], v[164:165]
	v_pk_add_f32 v[128:129], v[128:129], v[164:165] neg_lo:[0,1] neg_hi:[0,1]
	v_pk_add_f32 v[164:165], v[130:131], v[166:167]
	v_pk_add_f32 v[130:131], v[130:131], v[166:167] neg_lo:[0,1] neg_hi:[0,1]
	v_cvt_f32_ubyte0_e32 v2, v3
	v_pk_mul_f32 v[166:167], v[130:131], s[10:11]
	v_mul_f32_e32 v3, 0x3b000000, v2
	v_pk_fma_f32 v[130:131], v[130:131], s[8:9], v[166:167] op_sel:[0,0,1] op_sel_hi:[1,0,0]
	s_waitcnt lgkmcnt(6)
	v_pk_add_f32 v[166:167], v[132:133], v[168:169]
	v_pk_add_f32 v[132:133], v[132:133], v[168:169] neg_lo:[0,1] neg_hi:[0,1]
	v_sin_f32_e32 v2, v3
	v_pk_mul_f32 v[168:169], v[132:133], s[18:19]
	v_cos_f32_e32 v4, v3
	v_pk_fma_f32 v[132:133], v[132:133], s[16:17], v[168:169] op_sel:[0,0,1] op_sel_hi:[1,0,0]
	v_pk_add_f32 v[168:169], v[134:135], v[170:171]
	v_pk_add_f32 v[134:135], v[134:135], v[170:171] neg_lo:[0,1] neg_hi:[0,1]
	v_xor_b32_e32 v5, 0x80000000, v2
	v_pk_mul_f32 v[170:171], v[134:135], s[26:27]
	v_mov_b32_e32 v3, v5
	v_pk_fma_f32 v[134:135], v[134:135], s[24:25], v[170:171] op_sel:[0,0,1] op_sel_hi:[1,0,0]
	s_waitcnt lgkmcnt(5)
	v_pk_add_f32 v[170:171], v[136:137], v[172:173]
	v_pk_add_f32 v[136:137], v[136:137], v[172:173] neg_lo:[0,1] neg_hi:[0,1]
	v_pk_mul_f32 v[6:7], v[4:5], v[2:3] op_sel:[1,0] op_sel_hi:[0,1]
	v_pk_mul_f32 v[172:173], v[136:137], s[36:37]
	v_pk_fma_f32 v[6:7], v[4:5], v[4:5], v[6:7] op_sel_hi:[1,0,1]
	v_pk_fma_f32 v[136:137], v[136:137], s[78:79], v[172:173] op_sel:[0,0,1] op_sel_hi:[1,0,0]
	v_pk_add_f32 v[172:173], v[138:139], v[174:175]
	v_pk_add_f32 v[138:139], v[138:139], v[174:175] neg_lo:[0,1] neg_hi:[0,1]
	v_xor_b32_e32 v12, 0x80000000, v7
	v_pk_mul_f32 v[174:175], v[138:139], s[38:39]
	v_mov_b32_e32 v13, v7
	v_pk_fma_f32 v[138:139], v[138:139], s[0:1], v[174:175] op_sel:[0,0,1] op_sel_hi:[1,0,0]
	s_waitcnt lgkmcnt(4)
	v_pk_add_f32 v[174:175], v[140:141], v[176:177]
	v_pk_add_f32 v[140:141], v[140:141], v[176:177] neg_lo:[0,1] neg_hi:[0,1]
	v_pk_mul_f32 v[10:11], v[6:7], v[12:13] op_sel:[1,0] op_sel_hi:[0,1]
	v_pk_mul_f32 v[176:177], v[140:141], s[40:41]
	v_pk_fma_f32 v[10:11], v[6:7], v[6:7], v[10:11] op_sel_hi:[1,0,1]
	v_pk_fma_f32 v[140:141], v[140:141], s[80:81], v[176:177] op_sel:[0,0,1] op_sel_hi:[1,0,0]
	v_pk_add_f32 v[176:177], v[142:143], v[178:179]
	v_pk_add_f32 v[142:143], v[142:143], v[178:179] neg_lo:[0,1] neg_hi:[0,1]
	v_xor_b32_e32 v14, 0x80000000, v11
	v_pk_mul_f32 v[178:179], v[142:143], s[42:43]
	v_mov_b32_e32 v15, v11
	v_pk_fma_f32 v[142:143], v[142:143], s[74:75], v[178:179] op_sel:[0,0,1] op_sel_hi:[1,0,0]
	s_waitcnt lgkmcnt(3)
	v_pk_add_f32 v[178:179], v[148:149], v[180:181]
	v_pk_add_f32 v[180:181], v[148:149], v[180:181] neg_lo:[0,1] neg_hi:[0,1]
	v_pk_mul_f32 v[28:29], v[10:11], v[14:15] op_sel:[1,0] op_sel_hi:[0,1]
	v_pk_add_f32 v[148:149], v[150:151], v[182:183]
	v_pk_add_f32 v[150:151], v[150:151], v[182:183] neg_lo:[0,1] neg_hi:[0,1]
	v_pk_fma_f32 v[28:29], v[10:11], v[10:11], v[28:29] op_sel_hi:[1,0,1]
	v_pk_mul_f32 v[182:183], v[150:151], s[42:43]
	v_pk_mul_f32 v[44:45], v[14:15], v[28:29] op_sel:[0,1] op_sel_hi:[1,0]
	v_pk_fma_f32 v[150:151], v[150:151], s[74:75], v[182:183] op_sel:[0,0,1] op_sel_hi:[1,0,0] neg_lo:[1,0,0] neg_hi:[1,0,0]
	s_waitcnt lgkmcnt(2)
	v_pk_add_f32 v[182:183], v[152:153], v[184:185]
	v_pk_add_f32 v[152:153], v[152:153], v[184:185] neg_lo:[0,1] neg_hi:[0,1]
	v_pk_fma_f32 v[44:45], v[10:11], v[28:29], v[44:45] op_sel_hi:[0,1,1]
	v_pk_mul_f32 v[184:185], v[152:153], s[40:41]
	v_pk_mul_f32 v[60:61], v[14:15], v[44:45] op_sel:[0,1] op_sel_hi:[1,0]
	v_pk_fma_f32 v[152:153], v[152:153], s[80:81], v[184:185] op_sel:[0,0,1] op_sel_hi:[1,0,0] neg_lo:[1,0,0] neg_hi:[1,0,0]
	v_pk_add_f32 v[184:185], v[154:155], v[186:187]
	v_pk_add_f32 v[154:155], v[154:155], v[186:187] neg_lo:[0,1] neg_hi:[0,1]
	v_pk_fma_f32 v[60:61], v[10:11], v[44:45], v[60:61] op_sel_hi:[0,1,1]
	v_pk_mul_f32 v[186:187], v[154:155], s[38:39]
	v_pk_mul_f32 v[76:77], v[14:15], v[60:61] op_sel:[0,1] op_sel_hi:[1,0]
	v_pk_fma_f32 v[154:155], v[154:155], s[0:1], v[186:187] op_sel:[0,0,1] op_sel_hi:[1,0,0] neg_lo:[1,0,0] neg_hi:[1,0,0]
	s_waitcnt lgkmcnt(1)
	v_pk_add_f32 v[186:187], v[156:157], v[188:189]
	v_pk_add_f32 v[156:157], v[156:157], v[188:189] neg_lo:[0,1] neg_hi:[0,1]
	v_pk_fma_f32 v[76:77], v[10:11], v[60:61], v[76:77] op_sel_hi:[0,1,1]
	v_pk_mul_f32 v[188:189], v[156:157], s[36:37]
	v_pk_mul_f32 v[92:93], v[14:15], v[76:77] op_sel:[0,1] op_sel_hi:[1,0]
	v_pk_fma_f32 v[156:157], v[156:157], s[78:79], v[188:189] op_sel:[0,0,1] op_sel_hi:[1,0,0] neg_lo:[1,0,0] neg_hi:[1,0,0]
	v_pk_add_f32 v[188:189], v[158:159], v[190:191]
	v_pk_add_f32 v[158:159], v[158:159], v[190:191] neg_lo:[0,1] neg_hi:[0,1]
	v_pk_fma_f32 v[92:93], v[10:11], v[76:77], v[92:93] op_sel_hi:[0,1,1]
	v_pk_mul_f32 v[190:191], v[158:159], s[26:27]
	v_pk_mul_f32 v[108:109], v[14:15], v[92:93] op_sel:[0,1] op_sel_hi:[1,0]
	v_pk_fma_f32 v[158:159], v[158:159], s[24:25], v[190:191] op_sel:[0,0,1] op_sel_hi:[1,0,0] neg_lo:[1,0,0] neg_hi:[1,0,0]
	s_waitcnt lgkmcnt(0)
	v_pk_add_f32 v[190:191], v[160:161], v[192:193]
	v_pk_add_f32 v[160:161], v[160:161], v[192:193] neg_lo:[0,1] neg_hi:[0,1]
	v_pk_mul_f32 v[8:9], v[2:3], v[6:7] op_sel:[0,1] op_sel_hi:[1,0]
	v_pk_mul_f32 v[192:193], v[160:161], s[18:19]
	v_pk_fma_f32 v[108:109], v[10:11], v[92:93], v[108:109] op_sel_hi:[0,1,1]
	v_pk_fma_f32 v[160:161], v[160:161], s[16:17], v[192:193] op_sel:[0,0,1] op_sel_hi:[1,0,0] neg_lo:[1,0,0] neg_hi:[1,0,0]
	v_pk_add_f32 v[192:193], v[162:163], v[194:195]
	v_pk_add_f32 v[162:163], v[162:163], v[194:195] neg_lo:[0,1] neg_hi:[0,1]
	v_pk_fma_f32 v[8:9], v[4:5], v[6:7], v[8:9] op_sel_hi:[0,1,1]
	v_pk_mul_f32 v[194:195], v[162:163], s[10:11]
	v_pk_mul_f32 v[16:17], v[2:3], v[10:11] op_sel:[0,1] op_sel_hi:[1,0]
	v_pk_fma_f32 v[162:163], v[162:163], s[8:9], v[194:195] op_sel:[0,0,1] op_sel_hi:[1,0,0] neg_lo:[1,0,0] neg_hi:[1,0,0]
	v_pk_add_f32 v[194:195], v[144:145], v[178:179]
	v_pk_add_f32 v[144:145], v[144:145], v[178:179] neg_lo:[0,1] neg_hi:[0,1]
	v_pk_add_f32 v[178:179], v[164:165], v[148:149]
	v_pk_add_f32 v[148:149], v[164:165], v[148:149] neg_lo:[0,1] neg_hi:[0,1]
	v_pk_mul_f32 v[32:33], v[2:3], v[28:29] op_sel:[0,1] op_sel_hi:[1,0]
	v_pk_mul_f32 v[164:165], v[148:149], s[18:19]
	v_pk_mul_f32 v[48:49], v[2:3], v[44:45] op_sel:[0,1] op_sel_hi:[1,0]
	v_pk_fma_f32 v[148:149], v[148:149], s[16:17], v[164:165] op_sel:[0,0,1] op_sel_hi:[1,0,0]
	v_pk_add_f32 v[164:165], v[166:167], v[182:183]
	v_pk_add_f32 v[166:167], v[166:167], v[182:183] neg_lo:[0,1] neg_hi:[0,1]
	v_pk_mul_f32 v[64:65], v[2:3], v[60:61] op_sel:[0,1] op_sel_hi:[1,0]
	v_pk_mul_f32 v[182:183], v[166:167], s[36:37]
	v_pk_mul_f32 v[80:81], v[2:3], v[76:77] op_sel:[0,1] op_sel_hi:[1,0]
	v_pk_fma_f32 v[166:167], v[166:167], s[78:79], v[182:183] op_sel:[0,0,1] op_sel_hi:[1,0,0]
	v_pk_add_f32 v[182:183], v[168:169], v[184:185]
	v_pk_add_f32 v[168:169], v[168:169], v[184:185] neg_lo:[0,1] neg_hi:[0,1]
	v_pk_mul_f32 v[96:97], v[2:3], v[92:93] op_sel:[0,1] op_sel_hi:[1,0]
	v_pk_mul_f32 v[184:185], v[168:169], s[40:41]
	v_pk_mul_f32 v[112:113], v[2:3], v[108:109] op_sel:[0,1] op_sel_hi:[1,0]
	v_pk_fma_f32 v[168:169], v[168:169], s[80:81], v[184:185] op_sel:[0,0,1] op_sel_hi:[1,0,0]
	v_pk_add_f32 v[184:185], v[170:171], v[186:187]
	v_pk_add_f32 v[186:187], v[170:171], v[186:187] neg_lo:[0,1] neg_hi:[0,1]
	v_xor_b32_e32 v22, 0x80000000, v9
	v_pk_add_f32 v[170:171], v[172:173], v[188:189]
	v_pk_add_f32 v[172:173], v[172:173], v[188:189] neg_lo:[0,1] neg_hi:[0,1]
	v_mov_b32_e32 v23, v9
	v_pk_mul_f32 v[188:189], v[172:173], s[40:41]
	v_pk_fma_f32 v[16:17], v[4:5], v[10:11], v[16:17] op_sel_hi:[0,1,1]
	v_pk_fma_f32 v[172:173], v[172:173], s[80:81], v[188:189] op_sel:[0,0,1] op_sel_hi:[1,0,0] neg_lo:[1,0,0] neg_hi:[1,0,0]
	v_pk_add_f32 v[188:189], v[174:175], v[190:191]
	v_pk_add_f32 v[174:175], v[174:175], v[190:191] neg_lo:[0,1] neg_hi:[0,1]
	v_pk_mul_f32 v[20:21], v[12:13], v[10:11] op_sel:[0,1] op_sel_hi:[1,0]
	v_pk_mul_f32 v[190:191], v[174:175], s[36:37]
	v_pk_fma_f32 v[32:33], v[4:5], v[28:29], v[32:33] op_sel_hi:[0,1,1]
	v_pk_fma_f32 v[174:175], v[174:175], s[78:79], v[190:191] op_sel:[0,0,1] op_sel_hi:[1,0,0] neg_lo:[1,0,0] neg_hi:[1,0,0]
	v_pk_add_f32 v[190:191], v[176:177], v[192:193]
	v_pk_add_f32 v[176:177], v[176:177], v[192:193] neg_lo:[0,1] neg_hi:[0,1]
	v_pk_mul_f32 v[36:37], v[12:13], v[28:29] op_sel:[0,1] op_sel_hi:[1,0]
	v_pk_mul_f32 v[192:193], v[176:177], s[18:19]
	v_pk_fma_f32 v[48:49], v[4:5], v[44:45], v[48:49] op_sel_hi:[0,1,1]
	v_pk_fma_f32 v[176:177], v[176:177], s[16:17], v[192:193] op_sel:[0,0,1] op_sel_hi:[1,0,0] neg_lo:[1,0,0] neg_hi:[1,0,0]
	v_pk_add_f32 v[192:193], v[128:129], v[180:181] op_sel:[0,1] op_sel_hi:[1,0] neg_hi:[0,1]
	v_pk_add_f32 v[128:129], v[128:129], v[180:181] op_sel:[0,1] op_sel_hi:[1,0] neg_lo:[0,1]
	v_pk_add_f32 v[180:181], v[130:131], v[150:151]
	v_pk_add_f32 v[130:131], v[130:131], v[150:151] neg_lo:[0,1] neg_hi:[0,1]
	v_pk_mul_f32 v[52:53], v[12:13], v[44:45] op_sel:[0,1] op_sel_hi:[1,0]
	v_pk_mul_f32 v[150:151], v[130:131], s[18:19]
	v_pk_fma_f32 v[64:65], v[4:5], v[60:61], v[64:65] op_sel_hi:[0,1,1]
	v_pk_fma_f32 v[130:131], v[130:131], s[16:17], v[150:151] op_sel:[0,0,1] op_sel_hi:[1,0,0]
	v_pk_add_f32 v[150:151], v[132:133], v[152:153]
	v_pk_add_f32 v[132:133], v[132:133], v[152:153] neg_lo:[0,1] neg_hi:[0,1]
	v_pk_mul_f32 v[68:69], v[12:13], v[60:61] op_sel:[0,1] op_sel_hi:[1,0]
	v_pk_mul_f32 v[152:153], v[132:133], s[36:37]
	v_pk_fma_f32 v[80:81], v[4:5], v[76:77], v[80:81] op_sel_hi:[0,1,1]
	v_pk_fma_f32 v[132:133], v[132:133], s[78:79], v[152:153] op_sel:[0,0,1] op_sel_hi:[1,0,0]
	v_pk_add_f32 v[152:153], v[134:135], v[154:155]
	v_pk_add_f32 v[134:135], v[134:135], v[154:155] neg_lo:[0,1] neg_hi:[0,1]
	v_pk_mul_f32 v[84:85], v[12:13], v[76:77] op_sel:[0,1] op_sel_hi:[1,0]
	v_pk_mul_f32 v[154:155], v[134:135], s[40:41]
	v_pk_fma_f32 v[96:97], v[4:5], v[92:93], v[96:97] op_sel_hi:[0,1,1]
	v_pk_fma_f32 v[134:135], v[134:135], s[80:81], v[154:155] op_sel:[0,0,1] op_sel_hi:[1,0,0]
	v_pk_add_f32 v[154:155], v[136:137], v[156:157]
	v_pk_add_f32 v[156:157], v[136:137], v[156:157] neg_lo:[0,1] neg_hi:[0,1]
	v_pk_mul_f32 v[100:101], v[12:13], v[92:93] op_sel:[0,1] op_sel_hi:[1,0]
	v_pk_add_f32 v[136:137], v[138:139], v[158:159]
	v_pk_add_f32 v[138:139], v[138:139], v[158:159] neg_lo:[0,1] neg_hi:[0,1]
	v_pk_fma_f32 v[112:113], v[4:5], v[108:109], v[112:113] op_sel_hi:[0,1,1]
	v_pk_mul_f32 v[158:159], v[138:139], s[40:41]
	v_pk_mul_f32 v[116:117], v[12:13], v[108:109] op_sel:[0,1] op_sel_hi:[1,0]
	v_pk_fma_f32 v[138:139], v[138:139], s[80:81], v[158:159] op_sel:[0,0,1] op_sel_hi:[1,0,0] neg_lo:[1,0,0] neg_hi:[1,0,0]
	v_pk_add_f32 v[158:159], v[140:141], v[160:161]
	v_pk_add_f32 v[140:141], v[140:141], v[160:161] neg_lo:[0,1] neg_hi:[0,1]
	v_pk_fma_f32 v[20:21], v[6:7], v[10:11], v[20:21] op_sel_hi:[0,1,1]
	v_pk_mul_f32 v[160:161], v[140:141], s[36:37]
	v_pk_mul_f32 v[24:25], v[10:11], v[22:23] op_sel:[1,0] op_sel_hi:[0,1]
	v_pk_fma_f32 v[140:141], v[140:141], s[78:79], v[160:161] op_sel:[0,0,1] op_sel_hi:[1,0,0] neg_lo:[1,0,0] neg_hi:[1,0,0]
	v_pk_add_f32 v[160:161], v[142:143], v[162:163]
	v_pk_add_f32 v[142:143], v[142:143], v[162:163] neg_lo:[0,1] neg_hi:[0,1]
	v_pk_fma_f32 v[36:37], v[6:7], v[28:29], v[36:37] op_sel_hi:[0,1,1]
	v_pk_mul_f32 v[162:163], v[142:143], s[18:19]
	v_pk_mul_f32 v[40:41], v[22:23], v[28:29] op_sel:[0,1] op_sel_hi:[1,0]
	v_pk_fma_f32 v[142:143], v[142:143], s[16:17], v[162:163] op_sel:[0,0,1] op_sel_hi:[1,0,0] neg_lo:[1,0,0] neg_hi:[1,0,0]
	v_pk_add_f32 v[162:163], v[194:195], v[184:185]
	v_pk_add_f32 v[184:185], v[194:195], v[184:185] neg_lo:[0,1] neg_hi:[0,1]
	v_pk_add_f32 v[194:195], v[178:179], v[170:171]
	v_pk_add_f32 v[170:171], v[178:179], v[170:171] neg_lo:[0,1] neg_hi:[0,1]
	v_pk_fma_f32 v[52:53], v[6:7], v[44:45], v[52:53] op_sel_hi:[0,1,1]
	v_pk_mul_f32 v[178:179], v[170:171], s[36:37]
	v_pk_mul_f32 v[56:57], v[22:23], v[44:45] op_sel:[0,1] op_sel_hi:[1,0]
	v_pk_fma_f32 v[170:171], v[170:171], s[78:79], v[178:179] op_sel:[0,0,1] op_sel_hi:[1,0,0]
	v_pk_add_f32 v[178:179], v[164:165], v[188:189]
	v_pk_add_f32 v[188:189], v[164:165], v[188:189] neg_lo:[0,1] neg_hi:[0,1]
	v_pk_fma_f32 v[68:69], v[6:7], v[60:61], v[68:69] op_sel_hi:[0,1,1]
	v_pk_add_f32 v[164:165], v[182:183], v[190:191]
	v_pk_add_f32 v[182:183], v[182:183], v[190:191] neg_lo:[0,1] neg_hi:[0,1]
	v_pk_mul_f32 v[72:73], v[22:23], v[60:61] op_sel:[0,1] op_sel_hi:[1,0]
	v_pk_mul_f32 v[190:191], v[182:183], s[36:37]
	v_pk_fma_f32 v[84:85], v[6:7], v[76:77], v[84:85] op_sel_hi:[0,1,1]
	v_pk_fma_f32 v[182:183], v[182:183], s[78:79], v[190:191] op_sel:[0,0,1] op_sel_hi:[1,0,0] neg_lo:[1,0,0] neg_hi:[1,0,0]
	v_pk_add_f32 v[190:191], v[144:145], v[186:187] op_sel:[0,1] op_sel_hi:[1,0] neg_hi:[0,1]
	v_pk_add_f32 v[144:145], v[144:145], v[186:187] op_sel:[0,1] op_sel_hi:[1,0] neg_lo:[0,1]
	v_pk_add_f32 v[186:187], v[148:149], v[172:173]
	v_pk_add_f32 v[148:149], v[148:149], v[172:173] neg_lo:[0,1] neg_hi:[0,1]
	v_pk_mul_f32 v[88:89], v[22:23], v[76:77] op_sel:[0,1] op_sel_hi:[1,0]
	v_pk_mul_f32 v[172:173], v[148:149], s[36:37]
	v_pk_fma_f32 v[100:101], v[6:7], v[92:93], v[100:101] op_sel_hi:[0,1,1]
	v_pk_fma_f32 v[148:149], v[148:149], s[78:79], v[172:173] op_sel:[0,0,1] op_sel_hi:[1,0,0]
	v_pk_add_f32 v[172:173], v[166:167], v[174:175]
	v_pk_add_f32 v[174:175], v[166:167], v[174:175] neg_lo:[0,1] neg_hi:[0,1]
	v_pk_mul_f32 v[104:105], v[22:23], v[92:93] op_sel:[0,1] op_sel_hi:[1,0]
	v_pk_add_f32 v[166:167], v[168:169], v[176:177]
	v_pk_add_f32 v[168:169], v[168:169], v[176:177] neg_lo:[0,1] neg_hi:[0,1]
	v_pk_fma_f32 v[116:117], v[6:7], v[108:109], v[116:117] op_sel_hi:[0,1,1]
	v_pk_mul_f32 v[176:177], v[168:169], s[36:37]
	v_pk_mul_f32 v[120:121], v[22:23], v[108:109] op_sel:[0,1] op_sel_hi:[1,0]
	v_pk_fma_f32 v[168:169], v[168:169], s[78:79], v[176:177] op_sel:[0,0,1] op_sel_hi:[1,0,0] neg_lo:[1,0,0] neg_hi:[1,0,0]
	v_pk_add_f32 v[176:177], v[192:193], v[154:155]
	v_pk_add_f32 v[154:155], v[192:193], v[154:155] neg_lo:[0,1] neg_hi:[0,1]
	v_pk_add_f32 v[192:193], v[180:181], v[136:137]
	v_pk_add_f32 v[136:137], v[180:181], v[136:137] neg_lo:[0,1] neg_hi:[0,1]
	v_xor_b32_e32 v26, 0x80000000, v17
	v_pk_mul_f32 v[180:181], v[136:137], s[36:37]
	v_xor_b32_e32 v30, 0x80000000, v21
	v_pk_fma_f32 v[136:137], v[136:137], s[78:79], v[180:181] op_sel:[0,0,1] op_sel_hi:[1,0,0]
	v_pk_add_f32 v[180:181], v[150:151], v[158:159]
	v_pk_add_f32 v[158:159], v[150:151], v[158:159] neg_lo:[0,1] neg_hi:[0,1]
	v_pk_fma_f32 v[24:25], v[10:11], v[8:9], v[24:25] op_sel_hi:[1,0,1]
	v_pk_add_f32 v[150:151], v[152:153], v[160:161]
	v_pk_add_f32 v[152:153], v[152:153], v[160:161] neg_lo:[0,1] neg_hi:[0,1]
	v_pk_fma_f32 v[40:41], v[8:9], v[28:29], v[40:41] op_sel_hi:[0,1,1]
	v_pk_mul_f32 v[160:161], v[152:153], s[36:37]
	v_pk_fma_f32 v[56:57], v[8:9], v[44:45], v[56:57] op_sel_hi:[0,1,1]
	v_pk_fma_f32 v[152:153], v[152:153], s[78:79], v[160:161] op_sel:[0,0,1] op_sel_hi:[1,0,0] neg_lo:[1,0,0] neg_hi:[1,0,0]
	v_pk_add_f32 v[160:161], v[128:129], v[156:157] op_sel:[0,1] op_sel_hi:[1,0] neg_hi:[0,1]
	v_pk_add_f32 v[128:129], v[128:129], v[156:157] op_sel:[0,1] op_sel_hi:[1,0] neg_lo:[0,1]
	v_pk_add_f32 v[156:157], v[130:131], v[138:139]
	v_pk_add_f32 v[130:131], v[130:131], v[138:139] neg_lo:[0,1] neg_hi:[0,1]
	v_pk_fma_f32 v[72:73], v[8:9], v[60:61], v[72:73] op_sel_hi:[0,1,1]
	v_pk_mul_f32 v[138:139], v[130:131], s[36:37]
	v_pk_fma_f32 v[88:89], v[8:9], v[76:77], v[88:89] op_sel_hi:[0,1,1]
	v_pk_fma_f32 v[130:131], v[130:131], s[78:79], v[138:139] op_sel:[0,0,1] op_sel_hi:[1,0,0]
	v_pk_add_f32 v[138:139], v[132:133], v[140:141]
	v_pk_add_f32 v[140:141], v[132:133], v[140:141] neg_lo:[0,1] neg_hi:[0,1]
	v_pk_fma_f32 v[104:105], v[8:9], v[92:93], v[104:105] op_sel_hi:[0,1,1]
	v_pk_add_f32 v[132:133], v[134:135], v[142:143]
	v_pk_add_f32 v[134:135], v[134:135], v[142:143] neg_lo:[0,1] neg_hi:[0,1]
	v_pk_fma_f32 v[120:121], v[8:9], v[108:109], v[120:121] op_sel_hi:[0,1,1]
	v_pk_mul_f32 v[142:143], v[134:135], s[36:37]
	v_mov_b32_e32 v27, v17
	v_pk_fma_f32 v[134:135], v[134:135], s[78:79], v[142:143] op_sel:[0,0,1] op_sel_hi:[1,0,0] neg_lo:[1,0,0] neg_hi:[1,0,0]
	v_pk_add_f32 v[142:143], v[162:163], v[178:179]
	v_pk_add_f32 v[162:163], v[162:163], v[178:179] neg_lo:[0,1] neg_hi:[0,1]
	v_pk_add_f32 v[178:179], v[194:195], v[164:165]
	v_pk_add_f32 v[194:195], v[194:195], v[164:165] neg_lo:[0,1] neg_hi:[0,1]
	v_mov_b32_e32 v31, v21
	v_pk_add_f32 v[164:165], v[184:185], v[188:189] op_sel:[0,1] op_sel_hi:[1,0] neg_hi:[0,1]
	v_pk_add_f32 v[184:185], v[184:185], v[188:189] op_sel:[0,1] op_sel_hi:[1,0] neg_lo:[0,1]
	v_pk_add_f32 v[188:189], v[170:171], v[182:183]
	v_pk_add_f32 v[182:183], v[170:171], v[182:183] neg_lo:[0,1] neg_hi:[0,1]
	v_xor_b32_e32 v34, 0x80000000, v25
	v_pk_add_f32 v[170:171], v[190:191], v[172:173]
	v_pk_add_f32 v[172:173], v[190:191], v[172:173] neg_lo:[0,1] neg_hi:[0,1]
	v_pk_add_f32 v[190:191], v[186:187], v[166:167]
	v_pk_add_f32 v[186:187], v[186:187], v[166:167] neg_lo:[0,1] neg_hi:[0,1]
	v_xor_b32_e32 v38, 0x80000000, v29
	v_pk_add_f32 v[166:167], v[144:145], v[174:175] op_sel:[0,1] op_sel_hi:[1,0] neg_hi:[0,1]
	v_pk_add_f32 v[144:145], v[144:145], v[174:175] op_sel:[0,1] op_sel_hi:[1,0] neg_lo:[0,1]
	v_pk_add_f32 v[174:175], v[148:149], v[168:169]
	v_pk_add_f32 v[168:169], v[148:149], v[168:169] neg_lo:[0,1] neg_hi:[0,1]
	v_xor_b32_e32 v42, 0x80000000, v33
	v_pk_add_f32 v[148:149], v[176:177], v[180:181]
	v_pk_add_f32 v[176:177], v[176:177], v[180:181] neg_lo:[0,1] neg_hi:[0,1]
	v_pk_add_f32 v[180:181], v[192:193], v[150:151]
	v_pk_add_f32 v[192:193], v[192:193], v[150:151] neg_lo:[0,1] neg_hi:[0,1]
	v_xor_b32_e32 v46, 0x80000000, v37
	v_pk_add_f32 v[150:151], v[154:155], v[158:159] op_sel:[0,1] op_sel_hi:[1,0] neg_hi:[0,1]
	v_pk_add_f32 v[154:155], v[154:155], v[158:159] op_sel:[0,1] op_sel_hi:[1,0] neg_lo:[0,1]
	v_pk_add_f32 v[158:159], v[136:137], v[152:153]
	v_pk_add_f32 v[152:153], v[136:137], v[152:153] neg_lo:[0,1] neg_hi:[0,1]
	v_mov_b32_e32 v35, v25
	v_pk_add_f32 v[136:137], v[160:161], v[138:139]
	v_pk_add_f32 v[138:139], v[160:161], v[138:139] neg_lo:[0,1] neg_hi:[0,1]
	v_pk_add_f32 v[160:161], v[156:157], v[132:133]
	v_pk_add_f32 v[156:157], v[156:157], v[132:133] neg_lo:[0,1] neg_hi:[0,1]
	v_mov_b32_e32 v39, v29
	v_pk_add_f32 v[132:133], v[128:129], v[140:141] op_sel:[0,1] op_sel_hi:[1,0] neg_hi:[0,1]
	v_pk_add_f32 v[128:129], v[128:129], v[140:141] op_sel:[0,1] op_sel_hi:[1,0] neg_lo:[0,1]
	v_pk_add_f32 v[140:141], v[130:131], v[134:135]
	v_pk_add_f32 v[134:135], v[130:131], v[134:135] neg_lo:[0,1] neg_hi:[0,1]
	v_mov_b32_e32 v43, v33
	v_pk_add_f32 v[130:131], v[142:143], v[178:179]
	v_pk_add_f32 v[142:143], v[142:143], v[178:179] neg_lo:[0,1] neg_hi:[0,1]
	v_pk_add_f32 v[178:179], v[162:163], v[194:195] op_sel:[0,1] op_sel_hi:[1,0] neg_hi:[0,1]
	v_pk_add_f32 v[162:163], v[162:163], v[194:195] op_sel:[0,1] op_sel_hi:[1,0] neg_lo:[0,1]
	v_pk_add_f32 v[194:195], v[164:165], v[188:189]
	v_pk_add_f32 v[164:165], v[164:165], v[188:189] neg_lo:[0,1] neg_hi:[0,1]
	v_pk_add_f32 v[188:189], v[184:185], v[182:183] op_sel:[0,1] op_sel_hi:[1,0] neg_hi:[0,1]
	v_pk_add_f32 v[182:183], v[184:185], v[182:183] op_sel:[0,1] op_sel_hi:[1,0] neg_lo:[0,1]
	v_pk_add_f32 v[184:185], v[170:171], v[190:191]
	v_pk_add_f32 v[170:171], v[170:171], v[190:191] neg_lo:[0,1] neg_hi:[0,1]
	v_pk_add_f32 v[190:191], v[172:173], v[186:187] op_sel:[0,1] op_sel_hi:[1,0] neg_hi:[0,1]
	v_pk_add_f32 v[172:173], v[172:173], v[186:187] op_sel:[0,1] op_sel_hi:[1,0] neg_lo:[0,1]
	v_pk_add_f32 v[186:187], v[166:167], v[174:175]
	v_pk_add_f32 v[166:167], v[166:167], v[174:175] neg_lo:[0,1] neg_hi:[0,1]
	v_pk_add_f32 v[174:175], v[144:145], v[168:169] op_sel:[0,1] op_sel_hi:[1,0] neg_hi:[0,1]
	v_pk_add_f32 v[144:145], v[144:145], v[168:169] op_sel:[0,1] op_sel_hi:[1,0] neg_lo:[0,1]
	v_pk_add_f32 v[168:169], v[148:149], v[180:181]
	v_pk_add_f32 v[148:149], v[148:149], v[180:181] neg_lo:[0,1] neg_hi:[0,1]
	v_pk_mul_f32 v[2:3], v[2:3], v[168:169] op_sel:[0,1] op_sel_hi:[1,0]
	v_pk_add_f32 v[180:181], v[176:177], v[192:193] op_sel:[0,1] op_sel_hi:[1,0] neg_hi:[0,1]
	v_pk_add_f32 v[176:177], v[176:177], v[192:193] op_sel:[0,1] op_sel_hi:[1,0] neg_lo:[0,1]
	v_pk_add_f32 v[192:193], v[150:151], v[158:159]
	v_pk_add_f32 v[150:151], v[150:151], v[158:159] neg_lo:[0,1] neg_hi:[0,1]
	v_pk_add_f32 v[158:159], v[154:155], v[152:153] op_sel:[0,1] op_sel_hi:[1,0] neg_hi:[0,1]
	v_pk_add_f32 v[152:153], v[154:155], v[152:153] op_sel:[0,1] op_sel_hi:[1,0] neg_lo:[0,1]
	v_pk_add_f32 v[154:155], v[136:137], v[160:161]
	v_pk_fma_f32 v[2:3], v[4:5], v[168:169], v[2:3] op_sel_hi:[0,1,1]
	v_pk_mul_f32 v[4:5], v[12:13], v[184:185] op_sel:[0,1] op_sel_hi:[1,0]
	v_mov_b32_e32 v47, v37
	v_pk_fma_f32 v[4:5], v[6:7], v[184:185], v[4:5] op_sel_hi:[0,1,1]
	v_pk_mul_f32 v[6:7], v[22:23], v[154:155] op_sel:[0,1] op_sel_hi:[1,0]
	v_pk_add_f32 v[136:137], v[136:137], v[160:161] neg_lo:[0,1] neg_hi:[0,1]
	v_pk_fma_f32 v[6:7], v[8:9], v[154:155], v[6:7] op_sel_hi:[0,1,1]
	v_pk_mul_f32 v[8:9], v[14:15], v[194:195] op_sel:[0,1] op_sel_hi:[1,0]
	v_pk_add_f32 v[160:161], v[138:139], v[156:157] op_sel:[0,1] op_sel_hi:[1,0] neg_hi:[0,1]
	v_pk_add_f32 v[138:139], v[138:139], v[156:157] op_sel:[0,1] op_sel_hi:[1,0] neg_lo:[0,1]
	v_pk_add_f32 v[156:157], v[132:133], v[140:141]
	v_pk_fma_f32 v[8:9], v[10:11], v[194:195], v[8:9] op_sel_hi:[0,1,1]
	v_pk_mul_f32 v[10:11], v[26:27], v[192:193] op_sel:[0,1] op_sel_hi:[1,0]
	v_pk_mul_f32 v[12:13], v[30:31], v[186:187] op_sel:[0,1] op_sel_hi:[1,0]
	v_xor_b32_e32 v50, 0x80000000, v41
	v_xor_b32_e32 v54, 0x80000000, v45
	v_xor_b32_e32 v58, 0x80000000, v49
	v_xor_b32_e32 v62, 0x80000000, v53
	v_xor_b32_e32 v66, 0x80000000, v57
	v_xor_b32_e32 v70, 0x80000000, v61
	v_xor_b32_e32 v74, 0x80000000, v65
	v_mov_b32_e32 v51, v41
	v_mov_b32_e32 v55, v45
	v_mov_b32_e32 v59, v49
	v_mov_b32_e32 v63, v53
	v_mov_b32_e32 v67, v57
	v_mov_b32_e32 v71, v61
	v_mov_b32_e32 v75, v65
	v_pk_add_f32 v[132:133], v[132:133], v[140:141] neg_lo:[0,1] neg_hi:[0,1]
	v_pk_add_f32 v[140:141], v[128:129], v[134:135] op_sel:[0,1] op_sel_hi:[1,0] neg_hi:[0,1]
	v_pk_fma_f32 v[10:11], v[16:17], v[192:193], v[10:11] op_sel_hi:[0,1,1]
	v_pk_fma_f32 v[12:13], v[20:21], v[186:187], v[12:13] op_sel_hi:[0,1,1]
	v_pk_mul_f32 v[14:15], v[34:35], v[156:157] op_sel:[0,1] op_sel_hi:[1,0]
	v_pk_mul_f32 v[16:17], v[38:39], v[178:179] op_sel:[0,1] op_sel_hi:[1,0]
	v_pk_mul_f32 v[20:21], v[42:43], v[180:181] op_sel:[0,1] op_sel_hi:[1,0]
	v_pk_mul_f32 v[22:23], v[46:47], v[190:191] op_sel:[0,1] op_sel_hi:[1,0]
	v_xor_b32_e32 v78, 0x80000000, v69
	v_xor_b32_e32 v82, 0x80000000, v73
	v_xor_b32_e32 v86, 0x80000000, v77
	v_xor_b32_e32 v90, 0x80000000, v81
	v_xor_b32_e32 v94, 0x80000000, v85
	v_xor_b32_e32 v98, 0x80000000, v89
	v_xor_b32_e32 v102, 0x80000000, v93
	v_xor_b32_e32 v106, 0x80000000, v97
	v_xor_b32_e32 v110, 0x80000000, v101
	v_xor_b32_e32 v114, 0x80000000, v105
	v_xor_b32_e32 v118, 0x80000000, v109
	v_xor_b32_e32 v122, 0x80000000, v113
	v_xor_b32_e32 v124, 0x80000000, v117
	v_xor_b32_e32 v126, 0x80000000, v121
	v_mov_b32_e32 v79, v69
	v_mov_b32_e32 v83, v73
	v_mov_b32_e32 v87, v77
	v_mov_b32_e32 v91, v81
	v_mov_b32_e32 v95, v85
	v_mov_b32_e32 v99, v89
	v_mov_b32_e32 v103, v93
	v_mov_b32_e32 v107, v97
	v_mov_b32_e32 v111, v101
	v_mov_b32_e32 v115, v105
	v_mov_b32_e32 v119, v109
	v_mov_b32_e32 v123, v113
	v_mov_b32_e32 v125, v117
	v_mov_b32_e32 v127, v121
	v_pk_add_f32 v[128:129], v[128:129], v[134:135] op_sel:[0,1] op_sel_hi:[1,0] neg_lo:[0,1]
	v_pk_fma_f32 v[14:15], v[24:25], v[156:157], v[14:15] op_sel_hi:[0,1,1]
	v_pk_fma_f32 v[16:17], v[28:29], v[178:179], v[16:17] op_sel_hi:[0,1,1]
	v_pk_fma_f32 v[20:21], v[32:33], v[180:181], v[20:21] op_sel_hi:[0,1,1]
	v_pk_fma_f32 v[22:23], v[36:37], v[190:191], v[22:23] op_sel_hi:[0,1,1]
	v_pk_mul_f32 v[24:25], v[50:51], v[160:161] op_sel:[0,1] op_sel_hi:[1,0]
	v_pk_mul_f32 v[26:27], v[54:55], v[188:189] op_sel:[0,1] op_sel_hi:[1,0]
	v_pk_mul_f32 v[28:29], v[58:59], v[158:159] op_sel:[0,1] op_sel_hi:[1,0]
	v_pk_mul_f32 v[30:31], v[62:63], v[174:175] op_sel:[0,1] op_sel_hi:[1,0]
	v_pk_mul_f32 v[32:33], v[66:67], v[140:141] op_sel:[0,1] op_sel_hi:[1,0]
	v_pk_mul_f32 v[34:35], v[70:71], v[142:143] op_sel:[0,1] op_sel_hi:[1,0]
	v_pk_mul_f32 v[36:37], v[74:75], v[148:149] op_sel:[0,1] op_sel_hi:[1,0]
	v_pk_fma_f32 v[24:25], v[40:41], v[160:161], v[24:25] op_sel_hi:[0,1,1]
	v_pk_fma_f32 v[26:27], v[44:45], v[188:189], v[26:27] op_sel_hi:[0,1,1]
	v_pk_fma_f32 v[28:29], v[48:49], v[158:159], v[28:29] op_sel_hi:[0,1,1]
	v_pk_fma_f32 v[30:31], v[52:53], v[174:175], v[30:31] op_sel_hi:[0,1,1]
	v_pk_fma_f32 v[32:33], v[56:57], v[140:141], v[32:33] op_sel_hi:[0,1,1]
	v_pk_fma_f32 v[34:35], v[60:61], v[142:143], v[34:35] op_sel_hi:[0,1,1]
	v_pk_fma_f32 v[36:37], v[64:65], v[148:149], v[36:37] op_sel_hi:[0,1,1]
	v_pk_mul_f32 v[38:39], v[78:79], v[170:171] op_sel:[0,1] op_sel_hi:[1,0]
	v_pk_mul_f32 v[40:41], v[82:83], v[136:137] op_sel:[0,1] op_sel_hi:[1,0]
	v_pk_mul_f32 v[42:43], v[86:87], v[164:165] op_sel:[0,1] op_sel_hi:[1,0]
	v_pk_mul_f32 v[44:45], v[90:91], v[150:151] op_sel:[0,1] op_sel_hi:[1,0]
	v_pk_mul_f32 v[46:47], v[94:95], v[166:167] op_sel:[0,1] op_sel_hi:[1,0]
	v_pk_mul_f32 v[48:49], v[98:99], v[132:133] op_sel:[0,1] op_sel_hi:[1,0]
	v_pk_mul_f32 v[50:51], v[102:103], v[162:163] op_sel:[0,1] op_sel_hi:[1,0]
	v_pk_mul_f32 v[52:53], v[106:107], v[176:177] op_sel:[0,1] op_sel_hi:[1,0]
	v_pk_mul_f32 v[54:55], v[110:111], v[172:173] op_sel:[0,1] op_sel_hi:[1,0]
	v_pk_mul_f32 v[56:57], v[114:115], v[138:139] op_sel:[0,1] op_sel_hi:[1,0]
	v_pk_mul_f32 v[58:59], v[118:119], v[182:183] op_sel:[0,1] op_sel_hi:[1,0]
	v_pk_mul_f32 v[60:61], v[122:123], v[152:153] op_sel:[0,1] op_sel_hi:[1,0]
	v_pk_mul_f32 v[62:63], v[124:125], v[144:145] op_sel:[0,1] op_sel_hi:[1,0]
	v_pk_mul_f32 v[64:65], v[126:127], v[128:129] op_sel:[0,1] op_sel_hi:[1,0]
	v_pk_fma_f32 v[38:39], v[68:69], v[170:171], v[38:39] op_sel_hi:[0,1,1]
	v_pk_fma_f32 v[40:41], v[72:73], v[136:137], v[40:41] op_sel_hi:[0,1,1]
	v_pk_fma_f32 v[42:43], v[76:77], v[164:165], v[42:43] op_sel_hi:[0,1,1]
	v_pk_fma_f32 v[44:45], v[80:81], v[150:151], v[44:45] op_sel_hi:[0,1,1]
	v_pk_fma_f32 v[46:47], v[84:85], v[166:167], v[46:47] op_sel_hi:[0,1,1]
	v_pk_fma_f32 v[48:49], v[88:89], v[132:133], v[48:49] op_sel_hi:[0,1,1]
	v_pk_fma_f32 v[50:51], v[92:93], v[162:163], v[50:51] op_sel_hi:[0,1,1]
	v_pk_fma_f32 v[52:53], v[96:97], v[176:177], v[52:53] op_sel_hi:[0,1,1]
	v_pk_fma_f32 v[54:55], v[100:101], v[172:173], v[54:55] op_sel_hi:[0,1,1]
	v_pk_fma_f32 v[56:57], v[104:105], v[138:139], v[56:57] op_sel_hi:[0,1,1]
	v_pk_fma_f32 v[58:59], v[108:109], v[182:183], v[58:59] op_sel_hi:[0,1,1]
	v_pk_fma_f32 v[60:61], v[112:113], v[152:153], v[60:61] op_sel_hi:[0,1,1]
	v_pk_fma_f32 v[62:63], v[116:117], v[144:145], v[62:63] op_sel_hi:[0,1,1]
	v_pk_fma_f32 v[64:65], v[120:121], v[128:129], v[64:65] op_sel_hi:[0,1,1]
	ds_write2_b64 v18, v[130:131], v[34:35] offset1:16
	ds_write2_b64 v18, v[16:17], v[50:51] offset0:33 offset1:49
	ds_write2_b64 v18, v[8:9], v[42:43] offset0:66 offset1:82
	ds_write2_b64 v18, v[26:27], v[58:59] offset0:99 offset1:115
	ds_write2_b64 v18, v[4:5], v[38:39] offset0:132 offset1:148
	ds_write2_b64 v18, v[22:23], v[54:55] offset0:165 offset1:181
	ds_write2_b64 v18, v[12:13], v[46:47] offset0:198 offset1:214
	ds_write2_b64 v18, v[30:31], v[62:63] offset0:231 offset1:247
	ds_write2_b64 v196, v[2:3], v[36:37] offset0:8 offset1:24
	ds_write2_b64 v196, v[20:21], v[52:53] offset0:41 offset1:57
	ds_write2_b64 v196, v[10:11], v[44:45] offset0:74 offset1:90
	ds_write2_b64 v196, v[28:29], v[60:61] offset0:107 offset1:123
	ds_write2_b64 v196, v[6:7], v[40:41] offset0:140 offset1:156
	ds_write2_b64 v196, v[24:25], v[56:57] offset0:173 offset1:189
	ds_write2_b64 v196, v[14:15], v[48:49] offset0:206 offset1:222
	ds_write2_b64 v196, v[32:33], v[64:65] offset0:239 offset1:255
	v_ashrrev_i32_e32 v2, 31, v210
	v_lshrrev_b32_e32 v2, 23, v2
	v_add_u32_e32 v2, v210, v2
	s_lshl_b64 s[74:75], s[76:77], 16
	v_and_b32_e32 v2, 0xfffffe00, v2
	s_add_u32 s0, s54, s74
	v_sub_u32_e32 v2, v210, v2
	s_addc_u32 s1, s55, s75
	v_ashrrev_i32_e32 v3, 31, v2
	v_lshl_add_u64 v[14:15], v[2:3], 3, s[0:1]
	v_add_co_u32_e32 v2, vcc, s92, v14
	s_mov_b32 s0, 0x8000
	s_nop 0
	v_addc_co_u32_e32 v3, vcc, 0, v15, vcc
	v_add_co_u32_e32 v4, vcc, s95, v14
	s_waitcnt lgkmcnt(0)
	s_nop 0
	v_addc_co_u32_e32 v5, vcc, 0, v15, vcc
	v_add_co_u32_e32 v8, vcc, s96, v14
	s_barrier
	s_nop 0
	v_addc_co_u32_e32 v9, vcc, 0, v15, vcc
	global_load_dwordx2 v[24:25], v[4:5], off offset:-4096 nt
	global_load_dwordx2 v[12:13], v[4:5], off nt
	global_load_dwordx2 v[6:7], v[8:9], off offset:-4096 nt
	s_nop 0
	global_load_dwordx2 v[4:5], v[8:9], off nt
	v_add_co_u32_e32 v8, vcc, s0, v14
	s_waitcnt vmcnt(3)
	v_cvt_f32_f16_sdwa v174, v24 dst_sel:DWORD dst_unused:UNUSED_PAD src0_sel:WORD_1
	v_addc_co_u32_e32 v9, vcc, 0, v15, vcc
	v_add_co_u32_e32 v10, vcc, s34, v14
	v_cvt_f32_f16_e32 v175, v25
	s_nop 0
	v_addc_co_u32_e32 v11, vcc, 0, v15, vcc
	global_load_dwordx2 v[16:17], v[8:9], off offset:-4096 nt
	global_load_dwordx2 v[122:123], v[8:9], off nt
	global_load_dwordx2 v[46:47], v[10:11], off offset:-4096 nt
	global_load_dwordx2 v[36:37], v[10:11], off nt
	v_add_co_u32_e32 v8, vcc, s35, v14
	v_cvt_f32_f16_sdwa v177, v25 dst_sel:DWORD dst_unused:UNUSED_PAD src0_sel:WORD_1
	s_nop 0
	v_addc_co_u32_e32 v9, vcc, 0, v15, vcc
	v_add_co_u32_e32 v22, vcc, s30, v14
	v_cvt_f32_f16_e32 v176, v24
	s_nop 0
	v_addc_co_u32_e32 v23, vcc, 0, v15, vcc
	global_load_dwordx2 v[26:27], v[8:9], off offset:-4096 nt
	global_load_dwordx2 v[20:21], v[8:9], off nt
	global_load_dwordx2 v[10:11], v[22:23], off offset:-4096 nt
	s_nop 0
	global_load_dwordx2 v[8:9], v[22:23], off nt
	v_add_co_u32_e32 v22, vcc, s31, v14
	s_waitcnt vmcnt(10)
	v_cvt_f32_f16_sdwa v164, v12 dst_sel:DWORD dst_unused:UNUSED_PAD src0_sel:WORD_1
	v_addc_co_u32_e32 v23, vcc, 0, v15, vcc
	global_load_dwordx2 v[30:31], v[2:3], off offset:-4096 nt
	global_load_dwordx2 v[28:29], v[2:3], off nt
	s_nop 0
	global_load_dwordx2 v[2:3], v[22:23], off nt
	global_load_dwordx2 v[32:33], v[14:15], off nt
	v_mov_b32_e32 v14, v210
	v_cvt_f32_f16_e32 v165, v13
	v_ashrrev_i32_e32 v15, 31, v14
	v_lshrrev_b32_e32 v15, 23, v15
	v_add_u32_e32 v15, v14, v15
	v_ashrrev_i32_e32 v15, 9, v15
	v_mul_i32_i24_e32 v18, 0x200, v15
	v_sub_u32_e32 v18, v14, v18
	v_lshlrev_b32_e32 v14, 14, v15
	v_lshlrev_b32_e32 v15, 1, v18
	v_bfrev_b32_e32 v15, v15
	v_lshrrev_b32_e32 v15, 22, v15
	v_sub_u32_e32 v15, 0x400, v15
	v_bfrev_b32_e32 v15, v15
	v_lshrrev_b32_e32 v15, 18, v15
	v_and_b32_e32 v15, 0x3ff0, v15
	v_cmp_eq_u32_e64 s[0:1], 0, v18
	v_lshl_add_u32 v22, v18, 5, v14
	v_lshl_add_u32 v23, v22, 3, 0
	v_cndmask_b32_e64 v15, v15, 16, s[0:1]
	v_or_b32_e32 v14, v15, v14
	v_ashrrev_i32_e32 v22, 2, v22
	v_ashrrev_i32_e32 v15, 5, v14
	v_add_u32_e32 v211, v23, v22
	v_lshlrev_b32_e32 v14, 3, v14
	v_lshlrev_b32_e32 v15, 3, v15
	v_add3_u32 v212, 0, v14, v15
	ds_read2_b64 v[38:41], v211 offset1:1
	ds_read2_b64 v[42:45], v211 offset0:2 offset1:3
	ds_read2_b64 v[48:51], v212 offset1:1
	ds_read2_b64 v[52:55], v212 offset0:2 offset1:3
	ds_read2_b64 v[56:59], v211 offset0:4 offset1:5
	ds_read2_b64 v[60:63], v211 offset0:6 offset1:7
	ds_read2_b64 v[68:71], v212 offset0:4 offset1:5
	ds_read2_b64 v[72:75], v212 offset0:6 offset1:7
	ds_read2_b64 v[64:67], v211 offset0:8 offset1:9
	ds_read2_b64 v[76:79], v211 offset0:10 offset1:11
	ds_read2_b64 v[80:83], v212 offset0:8 offset1:9
	ds_read2_b64 v[98:101], v212 offset0:10 offset1:11
	ds_read2_b64 v[84:87], v211 offset0:12 offset1:13
	ds_read2_b64 v[88:91], v211 offset0:14 offset1:15
	ds_read2_b64 v[102:105], v212 offset0:12 offset1:13
	ds_read2_b64 v[106:109], v212 offset0:14 offset1:15
	s_waitcnt lgkmcnt(7)
	v_pk_add_f32 v[14:15], v[38:39], v[64:65]
	v_pk_add_f32 v[22:23], v[38:39], v[64:65] neg_lo:[0,1] neg_hi:[0,1]
	v_pk_add_f32 v[38:39], v[40:41], v[66:67] neg_lo:[0,1] neg_hi:[0,1]
	v_pk_add_f32 v[34:35], v[40:41], v[66:67]
	v_pk_mul_f32 v[40:41], v[38:39], s[18:19]
	v_cmp_ne_u32_e32 vcc, 0, v18
	v_pk_fma_f32 v[38:39], v[38:39], s[16:17], v[40:41] op_sel:[0,0,1] op_sel_hi:[1,0,0]
	s_waitcnt lgkmcnt(6)
	v_pk_add_f32 v[40:41], v[42:43], v[76:77]
	v_pk_add_f32 v[42:43], v[42:43], v[76:77] neg_lo:[0,1] neg_hi:[0,1]
	v_bfrev_b32_e32 v18, v18
	v_pk_mul_f32 v[64:65], v[42:43], s[36:37]
	v_lshrrev_b32_e32 v18, 23, v18
	v_pk_fma_f32 v[42:43], v[42:43], s[78:79], v[64:65] op_sel:[0,0,1] op_sel_hi:[1,0,0]
	v_pk_add_f32 v[64:65], v[44:45], v[78:79]
	v_pk_add_f32 v[44:45], v[44:45], v[78:79] neg_lo:[0,1] neg_hi:[0,1]
	s_waitcnt lgkmcnt(3)
	v_pk_add_f32 v[78:79], v[58:59], v[86:87]
	v_pk_mul_f32 v[66:67], v[44:45], s[40:41]
	v_pk_add_f32 v[58:59], v[58:59], v[86:87] neg_lo:[0,1] neg_hi:[0,1]
	v_pk_fma_f32 v[44:45], v[44:45], s[80:81], v[66:67] op_sel:[0,0,1] op_sel_hi:[1,0,0]
	v_pk_add_f32 v[66:67], v[56:57], v[84:85]
	v_pk_add_f32 v[76:77], v[56:57], v[84:85] neg_lo:[0,1] neg_hi:[0,1]
	v_pk_mul_f32 v[84:85], v[58:59], s[40:41] op_sel:[1,1] op_sel_hi:[0,0]
	v_pk_fma_f32 v[58:59], v[58:59], s[80:81], v[84:85] op_sel_hi:[1,0,1] neg_lo:[1,0,0] neg_hi:[1,0,0]
	s_waitcnt lgkmcnt(2)
	v_pk_add_f32 v[84:85], v[60:61], v[88:89]
	v_pk_add_f32 v[60:61], v[60:61], v[88:89] op_sel:[1,1] op_sel_hi:[0,0] neg_lo:[0,1] neg_hi:[0,1]
	v_pk_mul_f32 v[86:87], v[60:61], s[36:37] op_sel:[1,0] op_sel_hi:[0,1]
	v_pk_add_f32 v[56:57], v[22:23], v[76:77] op_sel:[0,1] op_sel_hi:[1,0] neg_hi:[0,1]
	v_pk_fma_f32 v[60:61], v[60:61], s[78:79], v[86:87] op_sel:[1,0,1] op_sel_hi:[0,0,0] neg_lo:[1,0,0] neg_hi:[1,0,0]
	v_pk_add_f32 v[86:87], v[62:63], v[90:91]
	v_pk_add_f32 v[62:63], v[62:63], v[90:91] neg_lo:[0,1] neg_hi:[0,1]
	v_pk_add_f32 v[90:91], v[64:65], v[86:87]
	v_pk_mul_f32 v[88:89], v[62:63], s[18:19]
	v_pk_add_f32 v[64:65], v[64:65], v[86:87] neg_lo:[0,1] neg_hi:[0,1]
	v_pk_fma_f32 v[62:63], v[62:63], s[16:17], v[88:89] op_sel:[0,0,1] op_sel_hi:[1,0,0] neg_lo:[1,0,0] neg_hi:[1,0,0]
	v_pk_add_f32 v[88:89], v[14:15], v[66:67]
	v_pk_add_f32 v[14:15], v[14:15], v[66:67] neg_lo:[0,1] neg_hi:[0,1]
	v_pk_add_f32 v[66:67], v[34:35], v[78:79]
	v_pk_add_f32 v[34:35], v[34:35], v[78:79] neg_lo:[0,1] neg_hi:[0,1]
	v_pk_add_f32 v[22:23], v[22:23], v[76:77] op_sel:[0,1] op_sel_hi:[1,0] neg_lo:[0,1]
	v_pk_mul_f32 v[78:79], v[34:35], s[36:37]
	v_pk_add_f32 v[76:77], v[38:39], v[58:59]
	v_pk_add_f32 v[38:39], v[38:39], v[58:59] neg_lo:[0,1] neg_hi:[0,1]
	v_pk_fma_f32 v[34:35], v[34:35], s[78:79], v[78:79] op_sel:[0,0,1] op_sel_hi:[1,0,0]
	v_pk_add_f32 v[78:79], v[40:41], v[84:85]
	v_pk_add_f32 v[84:85], v[40:41], v[84:85] neg_lo:[0,1] neg_hi:[0,1]
	v_pk_mul_f32 v[86:87], v[64:65], s[36:37]
	v_pk_mul_f32 v[58:59], v[38:39], s[36:37]
	v_pk_fma_f32 v[64:65], v[64:65], s[78:79], v[86:87] op_sel:[0,0,1] op_sel_hi:[1,0,0] neg_lo:[1,0,0] neg_hi:[1,0,0]
	v_pk_fma_f32 v[38:39], v[38:39], s[78:79], v[58:59] op_sel:[0,0,1] op_sel_hi:[1,0,0]
	v_pk_add_f32 v[58:59], v[42:43], v[60:61]
	v_pk_add_f32 v[86:87], v[44:45], v[62:63]
	v_pk_add_f32 v[44:45], v[44:45], v[62:63] op_sel:[1,1] op_sel_hi:[0,0] neg_lo:[0,1] neg_hi:[0,1]
	v_pk_mul_f32 v[62:63], v[44:45], s[36:37] op_sel:[1,0] op_sel_hi:[0,1]
	v_pk_add_f32 v[40:41], v[14:15], v[84:85] op_sel:[0,1] op_sel_hi:[1,0] neg_hi:[0,1]
	v_pk_add_f32 v[14:15], v[14:15], v[84:85] op_sel:[0,1] op_sel_hi:[1,0] neg_lo:[0,1]
	v_pk_add_f32 v[84:85], v[34:35], v[64:65]
	v_pk_add_f32 v[64:65], v[34:35], v[64:65] neg_lo:[0,1] neg_hi:[0,1]
	v_pk_add_f32 v[94:95], v[56:57], v[58:59]
	v_pk_add_f32 v[56:57], v[56:57], v[58:59] neg_lo:[0,1] neg_hi:[0,1]
	v_pk_add_f32 v[58:59], v[76:77], v[86:87]
	v_pk_fma_f32 v[44:45], v[44:45], s[78:79], v[62:63] op_sel:[1,0,1] op_sel_hi:[0,0,0] neg_lo:[1,0,0] neg_hi:[1,0,0]
	v_pk_add_f32 v[62:63], v[88:89], v[78:79]
	v_pk_add_f32 v[78:79], v[88:89], v[78:79] neg_lo:[0,1] neg_hi:[0,1]
	v_pk_add_f32 v[88:89], v[66:67], v[90:91]
	v_pk_add_f32 v[110:111], v[76:77], v[86:87] neg_lo:[0,1] neg_hi:[0,1]
	v_pk_add_f32 v[86:87], v[94:95], v[58:59]
	v_pk_add_f32 v[34:35], v[94:95], v[58:59] neg_lo:[0,1] neg_hi:[0,1]
	v_pk_add_f32 v[58:59], v[50:51], v[82:83]
	v_pk_add_f32 v[50:51], v[50:51], v[82:83] neg_lo:[0,1] neg_hi:[0,1]
	v_pk_add_f32 v[60:61], v[42:43], v[60:61] neg_lo:[0,1] neg_hi:[0,1]
	v_pk_add_f32 v[148:149], v[62:63], v[88:89]
	v_pk_add_f32 v[138:139], v[62:63], v[88:89] neg_lo:[0,1] neg_hi:[0,1]
	v_pk_mul_f32 v[62:63], v[50:51], s[18:19]
	v_pk_add_f32 v[90:91], v[66:67], v[90:91] neg_lo:[0,1] neg_hi:[0,1]
	v_pk_fma_f32 v[50:51], v[50:51], s[16:17], v[62:63] op_sel:[0,0,1] op_sel_hi:[1,0,0]
	v_pk_add_f32 v[62:63], v[52:53], v[98:99]
	v_pk_add_f32 v[52:53], v[52:53], v[98:99] neg_lo:[0,1] neg_hi:[0,1]
	v_pk_add_f32 v[112:113], v[22:23], v[60:61] op_sel:[0,1] op_sel_hi:[1,0] neg_hi:[0,1]
	v_pk_add_f32 v[114:115], v[22:23], v[60:61] op_sel:[0,1] op_sel_hi:[1,0] neg_lo:[0,1]
	v_pk_add_f32 v[96:97], v[40:41], v[84:85]
	v_pk_add_f32 v[66:67], v[40:41], v[84:85] neg_lo:[0,1] neg_hi:[0,1]
	v_pk_add_f32 v[60:61], v[14:15], v[64:65] op_sel:[0,1] op_sel_hi:[1,0] neg_hi:[0,1]
	v_pk_add_f32 v[84:85], v[14:15], v[64:65] op_sel:[0,1] op_sel_hi:[1,0] neg_lo:[0,1]
	v_pk_mul_f32 v[64:65], v[52:53], s[36:37] op_sel:[1,1] op_sel_hi:[0,0]
	v_pk_fma_f32 v[52:53], v[52:53], s[78:79], v[64:65] op_sel_hi:[1,0,1]
	v_pk_add_f32 v[64:65], v[54:55], v[100:101]
	v_pk_add_f32 v[54:55], v[54:55], v[100:101] op_sel:[1,1] op_sel_hi:[0,0] neg_lo:[0,1] neg_hi:[0,1]
	v_pk_mul_f32 v[76:77], v[54:55], s[40:41] op_sel:[1,0] op_sel_hi:[0,1]
	v_pk_add_f32 v[92:93], v[78:79], v[90:91] op_sel:[0,1] op_sel_hi:[1,0] neg_hi:[0,1]
	v_pk_fma_f32 v[54:55], v[54:55], s[80:81], v[76:77] op_sel:[1,0,1] op_sel_hi:[0,0,0]
	s_waitcnt lgkmcnt(1)
	v_pk_add_f32 v[76:77], v[68:69], v[102:103]
	v_pk_add_f32 v[68:69], v[68:69], v[102:103] neg_lo:[0,1] neg_hi:[0,1]
	v_pk_add_f32 v[88:89], v[78:79], v[90:91] op_sel:[0,1] op_sel_hi:[1,0] neg_lo:[0,1]
	v_xor_b32_e32 v79, 0x80000000, v68
	v_mov_b32_e32 v78, v69
	v_pk_add_f32 v[68:69], v[70:71], v[104:105]
	v_pk_add_f32 v[70:71], v[70:71], v[104:105] neg_lo:[0,1] neg_hi:[0,1]
	v_pk_add_f32 v[22:23], v[38:39], v[44:45]
	v_pk_add_f32 v[116:117], v[38:39], v[44:45] neg_lo:[0,1] neg_hi:[0,1]
	v_pk_add_f32 v[40:41], v[56:57], v[110:111] op_sel:[0,1] op_sel_hi:[1,0] neg_hi:[0,1]
	v_pk_add_f32 v[44:45], v[56:57], v[110:111] op_sel:[0,1] op_sel_hi:[1,0] neg_lo:[0,1]
	v_pk_add_f32 v[56:57], v[48:49], v[80:81]
	v_pk_add_f32 v[48:49], v[48:49], v[80:81] neg_lo:[0,1] neg_hi:[0,1]
	v_pk_mul_f32 v[80:81], v[70:71], s[40:41]
	v_cvt_f32_u32_e32 v18, v18
	v_pk_fma_f32 v[70:71], v[70:71], s[80:81], v[80:81] op_sel:[0,0,1] op_sel_hi:[1,0,0] neg_lo:[1,0,0] neg_hi:[1,0,0]
	s_waitcnt lgkmcnt(0)
	v_pk_add_f32 v[80:81], v[72:73], v[106:107]
	v_pk_add_f32 v[72:73], v[72:73], v[106:107] neg_lo:[0,1] neg_hi:[0,1]
	v_mul_f32_e32 v18, 0x38000000, v18
	v_pk_mul_f32 v[82:83], v[72:73], s[36:37]
	v_cndmask_b32_e64 v18, v18, v208, s[0:1]
	v_pk_fma_f32 v[72:73], v[72:73], s[78:79], v[82:83] op_sel:[0,0,1] op_sel_hi:[1,0,0] neg_lo:[1,0,0] neg_hi:[1,0,0]
	v_pk_add_f32 v[82:83], v[74:75], v[108:109]
	v_pk_add_f32 v[74:75], v[74:75], v[108:109] neg_lo:[0,1] neg_hi:[0,1]
	s_nop 0
	v_pk_mul_f32 v[90:91], v[74:75], s[18:19] op_sel:[1,1] op_sel_hi:[0,0]
	v_pk_fma_f32 v[74:75], v[74:75], s[16:17], v[90:91] op_sel_hi:[1,0,1] neg_lo:[1,0,0] neg_hi:[1,0,0]
	v_pk_add_f32 v[90:91], v[56:57], v[76:77]
	v_pk_add_f32 v[56:57], v[56:57], v[76:77] neg_lo:[0,1] neg_hi:[0,1]
	v_pk_add_f32 v[76:77], v[58:59], v[68:69]
	v_pk_add_f32 v[58:59], v[58:59], v[68:69] neg_lo:[0,1] neg_hi:[0,1]
	v_pk_add_f32 v[14:15], v[114:115], v[116:117] op_sel:[0,1] op_sel_hi:[1,0] neg_hi:[0,1]
	v_pk_mul_f32 v[68:69], v[58:59], s[36:37]
	v_pk_add_f32 v[38:39], v[114:115], v[116:117] op_sel:[0,1] op_sel_hi:[1,0] neg_lo:[0,1]
	v_pk_fma_f32 v[58:59], v[58:59], s[78:79], v[68:69] op_sel:[0,0,1] op_sel_hi:[1,0,0]
	v_pk_add_f32 v[68:69], v[62:63], v[80:81]
	v_pk_add_f32 v[80:81], v[62:63], v[80:81] neg_lo:[0,1] neg_hi:[0,1]
	s_waitcnt vmcnt(0)
	v_cvt_f32_f16_e32 v193, v33
	s_nop 0
	s_nop 0
	v_pk_add_f32 v[62:63], v[64:65], v[82:83]
	v_pk_add_f32 v[64:65], v[64:65], v[82:83] neg_lo:[0,1] neg_hi:[0,1]
	v_cvt_f32_f16_sdwa v192, v32 dst_sel:DWORD dst_unused:UNUSED_PAD src0_sel:WORD_1
	v_pk_mul_f32 v[82:83], v[64:65], s[36:37]
	v_cvt_f32_f16_e32 v194, v32
	v_pk_fma_f32 v[64:65], v[64:65], s[78:79], v[82:83] op_sel:[0,0,1] op_sel_hi:[1,0,0] neg_lo:[1,0,0] neg_hi:[1,0,0]
	v_pk_add_f32 v[82:83], v[48:49], v[78:79]
	v_pk_add_f32 v[48:49], v[48:49], v[78:79] neg_lo:[0,1] neg_hi:[0,1]
	v_pk_add_f32 v[78:79], v[50:51], v[70:71]
	v_pk_add_f32 v[50:51], v[50:51], v[70:71] neg_lo:[0,1] neg_hi:[0,1]
	v_cvt_f32_f16_sdwa v195, v33 dst_sel:DWORD dst_unused:UNUSED_PAD src0_sel:WORD_1
	v_pk_mul_f32 v[70:71], v[50:51], s[36:37]
	v_cvt_f32_f16_sdwa v170, v30 dst_sel:DWORD dst_unused:UNUSED_PAD src0_sel:WORD_1
	v_pk_fma_f32 v[50:51], v[50:51], s[78:79], v[70:71] op_sel:[0,0,1] op_sel_hi:[1,0,0]
	v_pk_add_f32 v[70:71], v[52:53], v[72:73]
	v_pk_add_f32 v[72:73], v[52:53], v[72:73] neg_lo:[0,1] neg_hi:[0,1]
	v_cvt_f32_f16_e32 v171, v31
	s_nop 0
	s_nop 0
	v_pk_add_f32 v[52:53], v[54:55], v[74:75]
	v_pk_add_f32 v[54:55], v[54:55], v[74:75] neg_lo:[0,1] neg_hi:[0,1]
	v_cvt_f32_f16_sdwa v185, v31 dst_sel:DWORD dst_unused:UNUSED_PAD src0_sel:WORD_1
	v_pk_mul_f32 v[74:75], v[54:55], s[36:37]
	v_cvt_f32_f16_e32 v184, v30
	v_pk_fma_f32 v[54:55], v[54:55], s[78:79], v[74:75] op_sel:[0,0,1] op_sel_hi:[1,0,0] neg_lo:[1,0,0] neg_hi:[1,0,0]
	v_pk_add_f32 v[74:75], v[90:91], v[68:69]
	v_pk_add_f32 v[68:69], v[90:91], v[68:69] neg_lo:[0,1] neg_hi:[0,1]
	v_pk_add_f32 v[90:91], v[76:77], v[62:63]
	v_pk_add_f32 v[62:63], v[76:77], v[62:63] neg_lo:[0,1] neg_hi:[0,1]
	v_cvt_f32_f16_sdwa v172, v28 dst_sel:DWORD dst_unused:UNUSED_PAD src0_sel:WORD_1
	v_xor_b32_e32 v77, 0x80000000, v62
	v_mov_b32_e32 v76, v63
	v_pk_add_f32 v[62:63], v[56:57], v[80:81] op_sel:[0,1] op_sel_hi:[1,0] neg_hi:[0,1]
	v_pk_add_f32 v[56:57], v[56:57], v[80:81] op_sel:[0,1] op_sel_hi:[1,0] neg_lo:[0,1]
	v_pk_add_f32 v[80:81], v[58:59], v[64:65]
	v_pk_add_f32 v[58:59], v[58:59], v[64:65] neg_lo:[0,1] neg_hi:[0,1]
	v_cvt_f32_f16_e32 v173, v29
	v_xor_b32_e32 v65, 0x80000000, v58
	v_mov_b32_e32 v64, v59
	v_pk_add_f32 v[58:59], v[82:83], v[70:71]
	v_pk_add_f32 v[70:71], v[82:83], v[70:71] neg_lo:[0,1] neg_hi:[0,1]
	v_pk_add_f32 v[82:83], v[78:79], v[52:53]
	v_pk_add_f32 v[52:53], v[78:79], v[52:53] neg_lo:[0,1] neg_hi:[0,1]
	v_pk_add_f32 v[118:119], v[58:59], v[82:83]
	v_pk_add_f32 v[134:135], v[58:59], v[82:83] neg_lo:[0,1] neg_hi:[0,1]
	v_cos_f32_e32 v83, v18
	v_sin_f32_e32 v82, v18
	v_cvt_f32_f16_sdwa v181, v29 dst_sel:DWORD dst_unused:UNUSED_PAD src0_sel:WORD_1
	v_cvt_f32_f16_e32 v180, v28
	v_cvt_f32_f16_sdwa v167, v13 dst_sel:DWORD dst_unused:UNUSED_PAD src0_sel:WORD_1
	v_cvt_f32_f16_e32 v166, v12
	v_cvt_f32_f16_e32 v154, v6
	v_cvt_f32_f16_e32 v155, v7
	v_cvt_f32_f16_sdwa v157, v7 dst_sel:DWORD dst_unused:UNUSED_PAD src0_sel:WORD_1
	v_cvt_f32_f16_sdwa v156, v6 dst_sel:DWORD dst_unused:UNUSED_PAD src0_sel:WORD_1
	v_cvt_f32_f16_sdwa v140, v4 dst_sel:DWORD dst_unused:UNUSED_PAD src0_sel:WORD_1
	v_cvt_f32_f16_e32 v141, v5
	v_cvt_f32_f16_sdwa v143, v5 dst_sel:DWORD dst_unused:UNUSED_PAD src0_sel:WORD_1
	v_cvt_f32_f16_e32 v142, v4
	v_cvt_f32_f16_e32 v124, v16
	v_cvt_f32_f16_e32 v125, v17
	v_cvt_f32_f16_sdwa v127, v17 dst_sel:DWORD dst_unused:UNUSED_PAD src0_sel:WORD_1
	v_cvt_f32_f16_sdwa v126, v16 dst_sel:DWORD dst_unused:UNUSED_PAD src0_sel:WORD_1
	v_cvt_f32_f16_sdwa v114, v122 dst_sel:DWORD dst_unused:UNUSED_PAD src0_sel:WORD_1
	v_cvt_f32_f16_e32 v115, v123
	v_cvt_f32_f16_sdwa v117, v123 dst_sel:DWORD dst_unused:UNUSED_PAD src0_sel:WORD_1
	v_cvt_f32_f16_e32 v116, v122
	v_xor_b32_e32 v79, 0x80000000, v52
	v_mov_b32_e32 v78, v53
	v_pk_add_f32 v[52:53], v[48:49], v[72:73] op_sel:[0,1] op_sel_hi:[1,0] neg_hi:[0,1]
	v_pk_add_f32 v[48:49], v[48:49], v[72:73] op_sel:[0,1] op_sel_hi:[1,0] neg_lo:[0,1]
	v_pk_add_f32 v[72:73], v[50:51], v[54:55]
	v_pk_add_f32 v[50:51], v[50:51], v[54:55] neg_lo:[0,1] neg_hi:[0,1]
	v_pk_fma_f32 v[160:161], v[82:83], 0, v[82:83] op_sel:[0,0,1] op_sel_hi:[1,0,0] neg_lo:[1,0,0] neg_hi:[1,0,0]
	v_xor_b32_e32 v55, 0x80000000, v50
	v_mov_b32_e32 v54, v51
	v_pk_fma_f32 v[198:199], v[82:83], 0, v[82:83] op_sel:[0,0,1] op_sel_hi:[1,0,0]
	v_pk_add_f32 v[42:43], v[112:113], v[22:23]
	v_pk_add_f32 v[22:23], v[112:113], v[22:23] neg_lo:[0,1] neg_hi:[0,1]
	v_pk_add_f32 v[98:99], v[74:75], v[90:91]
	v_pk_add_f32 v[100:101], v[74:75], v[90:91] neg_lo:[0,1] neg_hi:[0,1]
	v_pk_add_f32 v[102:103], v[68:69], v[76:77]
	v_pk_add_f32 v[106:107], v[68:69], v[76:77] neg_lo:[0,1] neg_hi:[0,1]
	v_pk_add_f32 v[104:105], v[62:63], v[80:81]
	v_pk_add_f32 v[108:109], v[62:63], v[80:81] neg_lo:[0,1] neg_hi:[0,1]
	v_pk_add_f32 v[110:111], v[56:57], v[64:65]
	v_pk_add_f32 v[112:113], v[56:57], v[64:65] neg_lo:[0,1] neg_hi:[0,1]
	v_pk_add_f32 v[152:153], v[70:71], v[78:79]
	v_pk_add_f32 v[162:163], v[70:71], v[78:79] neg_lo:[0,1] neg_hi:[0,1]
	v_pk_add_f32 v[178:179], v[52:53], v[72:73]
	v_pk_add_f32 v[182:183], v[52:53], v[72:73] neg_lo:[0,1] neg_hi:[0,1]
	v_pk_add_f32 v[188:189], v[48:49], v[54:55]
	v_pk_add_f32 v[196:197], v[48:49], v[54:55] neg_lo:[0,1] neg_hi:[0,1]
	v_pk_mul_f32 v[186:187], v[82:83], 0 op_sel_hi:[1,0]
	v_mov_b32_e32 v190, v160
	v_mov_b32_e32 v191, v199
	v_mul_f32_e32 v18, 0x3f3504f3, v83
	v_mul_f32_e32 v158, 0xbec3ef15, v83
	v_mul_f32_e32 v132, 0xbf6c835e, v83
	s_and_saveexec_b64 s[0:1], vcc
	s_xor_b64 s[0:1], exec, s[0:1]
	s_cbranch_execz .LBB0_501
	v_pk_add_f32 v[4:5], v[148:149], v[196:197]
	v_pk_add_f32 v[6:7], v[148:149], v[196:197] neg_lo:[0,1] neg_hi:[0,1]
	v_mul_f32_e32 v4, 0.5, v4
	v_mul_f32_e32 v12, 0.5, v7
	v_mov_b32_e32 v7, v5
	v_pk_mul_f32 v[6:7], v[6:7], s[44:45]
	v_pk_mov_b32 v[16:17], v[198:199], v[160:161] op_sel:[1,0]
	v_pk_mul_f32 v[24:25], v[190:191], v[6:7] op_sel:[0,1] op_sel_hi:[1,0]
	v_pk_mul_f32 v[6:7], v[190:191], v[6:7]
	v_pk_add_f32 v[24:25], v[24:25], v[24:25] op_sel:[0,1] op_sel_hi:[0,1]
	v_pk_add_f32 v[28:29], v[4:5], v[24:25] op_sel_hi:[0,1] neg_hi:[0,1]
	v_pk_add_f32 v[4:5], v[6:7], v[6:7] op_sel:[0,1] op_sel_hi:[0,1] neg_lo:[0,1] neg_hi:[0,1]
	v_pk_add_f32 v[6:7], v[12:13], v[4:5] op_sel_hi:[0,1] neg_hi:[0,1]
	v_pk_mul_f32 v[4:5], v[6:7], v[194:195]
	v_pk_mul_f32 v[6:7], v[6:7], v[192:193]
	v_pk_fma_f32 v[4:5], v[28:29], v[192:193], v[4:5]
	v_pk_fma_f32 v[6:7], v[28:29], v[194:195], v[6:7] neg_lo:[0,0,1] neg_hi:[0,0,1]
	s_mov_b32 s78, s19
	v_pk_add_f32 v[12:13], v[6:7], v[4:5] op_sel:[0,1] op_sel_hi:[1,0] neg_lo:[0,1]
	v_pk_add_f32 v[28:29], v[6:7], v[4:5] op_sel:[0,1] op_sel_hi:[1,0]
	v_pk_add_f32 v[4:5], v[4:5], v[6:7] op_sel:[1,0] op_sel_hi:[0,1] neg_lo:[0,1] neg_hi:[0,1]
	s_nop 0
	v_pk_mul_f32 v[12:13], v[12:13], 0.5 op_sel_hi:[1,0]
	v_mov_b32_e32 v29, v5
	v_mul_f32_e32 v24, v190, v12
	v_pk_fma_f32 v[30:31], v[190:191], v[12:13], v[24:25] op_sel_hi:[1,1,0] neg_lo:[1,0,0] neg_hi:[1,0,0]
	v_mul_f32_e32 v24, v160, v13
	v_pk_fma_f32 v[12:13], v[16:17], v[12:13], v[24:25] op_sel_hi:[1,1,0]
	v_mov_b32_e32 v16, v83
	v_mov_b32_e32 v30, v12
	v_pk_fma_f32 v[4:5], v[28:29], 0.5, v[12:13] op_sel_hi:[1,0,1] neg_lo:[0,0,1] neg_hi:[0,0,1]
	v_pk_fma_f32 v[122:123], v[28:29], 0.5, v[30:31] op_sel_hi:[1,0,1]
	v_pk_fma_f32 v[6:7], v[28:29], 0.5, v[30:31] op_sel_hi:[1,0,1] neg_lo:[1,0,0] neg_hi:[1,0,0]
	v_mov_b32_e32 v5, v123
	v_pk_mul_f32 v[24:25], v[4:5], s[6:7] op_sel_hi:[1,0]
	v_pk_add_f32 v[4:5], v[138:139], v[188:189]
	v_pk_add_f32 v[12:13], v[138:139], v[188:189] neg_lo:[0,1] neg_hi:[0,1]
	v_mov_b32_e32 v17, v82
	v_mul_f32_e32 v6, 0.5, v13
	v_pk_add_f32 v[28:29], v[186:187], v[16:17] neg_lo:[0,1] neg_hi:[0,1]
	v_pk_add_f32 v[30:31], v[186:187], v[16:17]
	v_mov_b32_e32 v13, v5
	v_pk_mov_b32 v[32:33], v[28:29], v[30:31] op_sel:[1,0]
	v_pk_mul_f32 v[12:13], v[12:13], s[44:45]
	v_mul_f32_e32 v4, 0.5, v4
	v_pk_mul_f32 v[48:49], v[32:33], v[12:13] op_sel:[0,1] op_sel_hi:[1,0]
	v_pk_mul_f32 v[12:13], v[32:33], v[12:13]
	v_pk_add_f32 v[48:49], v[48:49], v[48:49] op_sel:[0,1] op_sel_hi:[0,1]
	v_pk_add_f32 v[50:51], v[4:5], v[48:49] op_sel_hi:[0,1] neg_hi:[0,1]
	v_pk_add_f32 v[4:5], v[12:13], v[12:13] op_sel:[0,1] op_sel_hi:[0,1] neg_lo:[0,1] neg_hi:[0,1]
	v_pk_add_f32 v[12:13], v[6:7], v[4:5] op_sel_hi:[0,1] neg_hi:[0,1]
	v_pk_mul_f32 v[4:5], v[12:13], v[184:185]
	v_pk_mul_f32 v[12:13], v[12:13], v[170:171]
	v_pk_fma_f32 v[4:5], v[50:51], v[170:171], v[4:5]
	v_pk_fma_f32 v[12:13], v[50:51], v[184:185], v[12:13] neg_lo:[0,0,1] neg_hi:[0,0,1]
	v_mov_b32_e32 v31, v29
	v_pk_add_f32 v[48:49], v[12:13], v[4:5] op_sel:[0,1] op_sel_hi:[1,0] neg_lo:[0,1]
	v_pk_add_f32 v[50:51], v[12:13], v[4:5] op_sel:[0,1] op_sel_hi:[1,0]
	v_pk_add_f32 v[4:5], v[4:5], v[12:13] op_sel:[1,0] op_sel_hi:[0,1] neg_lo:[0,1] neg_hi:[0,1]
	v_pk_mul_f32 v[48:49], v[48:49], 0.5 op_sel_hi:[1,0]
	v_mov_b32_e32 v51, v5
	v_mul_f32_e32 v6, v29, v48
	v_pk_fma_f32 v[32:33], v[32:33], v[48:49], v[6:7] op_sel_hi:[1,1,0] neg_lo:[1,0,0] neg_hi:[1,0,0]
	v_mul_f32_e32 v6, v29, v49
	v_pk_fma_f32 v[28:29], v[30:31], v[48:49], v[6:7] op_sel_hi:[1,1,0]
	v_pk_mul_f32 v[12:13], v[16:17], s[36:37]
	v_mov_b32_e32 v32, v28
	v_pk_fma_f32 v[4:5], v[50:51], 0.5, v[28:29] op_sel_hi:[1,0,1] neg_lo:[0,0,1] neg_hi:[0,0,1]
	v_pk_fma_f32 v[138:139], v[50:51], 0.5, v[32:33] op_sel_hi:[1,0,1]
	v_pk_add_f32 v[16:17], v[92:93], v[182:183]
	v_mov_b32_e32 v5, v139
	v_pk_add_f32 v[28:29], v[92:93], v[182:183] neg_lo:[0,1] neg_hi:[0,1]
	v_pk_mul_f32 v[30:31], v[4:5], s[6:7] op_sel_hi:[1,0]
	v_pk_fma_f32 v[4:5], v[50:51], 0.5, v[32:33] op_sel_hi:[1,0,1] neg_lo:[1,0,0] neg_hi:[1,0,0]
	v_mul_f32_e32 v6, 0.5, v29
	v_pk_add_f32 v[32:33], v[18:19], v[12:13] op_sel:[0,1] op_sel_hi:[0,1] neg_lo:[0,1] neg_hi:[0,1]
	v_pk_add_f32 v[48:49], v[18:19], v[12:13] op_sel:[0,1] op_sel_hi:[0,1]
	v_mov_b32_e32 v29, v17
	v_mul_f32_e32 v4, 0.5, v16
	v_mov_b32_e32 v50, v32
	v_mov_b32_e32 v51, v49
	v_pk_mul_f32 v[16:17], v[28:29], s[44:45]
	v_pk_mov_b32 v[48:49], v[48:49], v[32:33] op_sel:[1,0]
	v_pk_mul_f32 v[28:29], v[50:51], v[16:17] op_sel:[0,1] op_sel_hi:[1,0]
	v_pk_mul_f32 v[16:17], v[50:51], v[16:17]
	v_pk_add_f32 v[28:29], v[28:29], v[28:29] op_sel:[0,1] op_sel_hi:[0,1]
	v_pk_add_f32 v[52:53], v[4:5], v[28:29] op_sel_hi:[0,1] neg_hi:[0,1]
	v_pk_add_f32 v[16:17], v[16:17], v[16:17] op_sel:[0,1] op_sel_hi:[0,1] neg_lo:[0,1] neg_hi:[0,1]
	v_pk_add_f32 v[28:29], v[6:7], v[16:17] op_sel_hi:[0,1] neg_hi:[0,1]
	v_pk_mul_f32 v[16:17], v[28:29], v[180:181]
	v_pk_mul_f32 v[28:29], v[28:29], v[172:173]
	v_pk_fma_f32 v[16:17], v[52:53], v[172:173], v[16:17]
	v_pk_fma_f32 v[28:29], v[52:53], v[180:181], v[28:29] neg_lo:[0,0,1] neg_hi:[0,0,1]
	v_sub_f32_e32 v6, v89, v179
	v_pk_add_f32 v[52:53], v[28:29], v[16:17] op_sel:[0,1] op_sel_hi:[1,0] neg_lo:[0,1]
	v_pk_add_f32 v[54:55], v[28:29], v[16:17] op_sel:[0,1] op_sel_hi:[1,0]
	v_pk_add_f32 v[16:17], v[16:17], v[28:29] op_sel:[1,0] op_sel_hi:[0,1] neg_lo:[0,1] neg_hi:[0,1]
	v_pk_mul_f32 v[52:53], v[52:53], 0.5 op_sel_hi:[1,0]
	v_mov_b32_e32 v55, v17
	v_mul_f32_e32 v4, v32, v52
	v_pk_fma_f32 v[56:57], v[50:51], v[52:53], v[4:5] op_sel_hi:[1,1,0] neg_lo:[1,0,0] neg_hi:[1,0,0]
	v_mul_f32_e32 v4, v32, v53
	v_pk_fma_f32 v[48:49], v[48:49], v[52:53], v[4:5] op_sel_hi:[1,1,0]
	v_pk_add_f32 v[28:29], v[88:89], v[178:179]
	v_mov_b32_e32 v56, v48
	v_pk_fma_f32 v[16:17], v[54:55], 0.5, v[48:49] op_sel_hi:[1,0,1] neg_lo:[0,0,1] neg_hi:[0,0,1]
	v_mov_b32_e32 v48, v12
	v_mov_b32_e32 v49, v88
	v_pk_mov_b32 v[12:13], v[12:13], v[178:179] op_sel:[1,0]
	v_mul_f32_e32 v18, 0.5, v29
	v_pk_add_f32 v[12:13], v[48:49], v[12:13] neg_lo:[0,1] neg_hi:[0,1]
	v_mul_f32_e32 v4, 0.5, v28
	v_pk_mul_f32 v[48:49], v[12:13], v[18:19]
	v_mov_b32_e32 v13, v32
	v_pk_fma_f32 v[50:51], v[50:51], v[48:49], v[48:49] op_sel:[0,1,0] op_sel_hi:[1,0,1]
	v_mov_b32_e32 v48, v49
	v_mov_b32_e32 v49, v18
	v_pk_mul_f32 v[48:49], v[12:13], v[48:49]
	v_pk_add_f32 v[52:53], v[4:5], v[50:51]
	v_mul_f32_e32 v6, 0.5, v6
	v_fma_f32 v53, v28, 0.5, -v50
	v_pk_add_f32 v[28:29], v[48:49], v[48:49] op_sel:[0,1] op_sel_hi:[0,1] neg_lo:[0,1] neg_hi:[0,1]
	v_pk_add_f32 v[48:49], v[6:7], v[28:29] op_sel_hi:[0,1] neg_hi:[0,1]
	v_pk_mul_f32 v[28:29], v[48:49], v[176:177]
	v_pk_mul_f32 v[48:49], v[48:49], v[174:175]
	v_pk_fma_f32 v[28:29], v[52:53], v[174:175], v[28:29]
	v_pk_fma_f32 v[48:49], v[52:53], v[176:177], v[48:49] neg_lo:[0,0,1] neg_hi:[0,0,1]
	v_pk_fma_f32 v[92:93], v[54:55], 0.5, v[56:57] op_sel_hi:[1,0,1]
	v_pk_add_f32 v[50:51], v[48:49], v[28:29] op_sel:[0,1] op_sel_hi:[1,0] neg_lo:[0,1]
	v_pk_add_f32 v[52:53], v[48:49], v[28:29] op_sel:[0,1] op_sel_hi:[1,0]
	v_mov_b32_e32 v17, v93
	v_pk_mul_f32 v[50:51], v[50:51], 0.5 op_sel_hi:[1,0]
	v_pk_mul_f32 v[64:65], v[16:17], s[6:7] op_sel_hi:[1,0]
	v_mul_f32_e32 v4, v12, v50
	v_pk_fma_f32 v[16:17], v[54:55], 0.5, v[56:57] op_sel_hi:[1,0,1] neg_lo:[1,0,0] neg_hi:[1,0,0]
	v_pk_fma_f32 v[54:55], v[12:13], v[50:51], v[4:5] op_sel_hi:[1,1,0] neg_lo:[1,0,0] neg_hi:[1,0,0]
	v_mov_b32_e32 v33, v12
	v_mul_f32_e32 v4, v12, v51
	v_pk_fma_f32 v[12:13], v[32:33], v[50:51], v[4:5] op_sel_hi:[1,1,0]
	v_pk_add_f32 v[28:29], v[28:29], v[48:49] op_sel:[1,0] op_sel_hi:[0,1] neg_lo:[0,1] neg_hi:[0,1]
	v_mov_b32_e32 v53, v29
	v_mov_b32_e32 v54, v12
	v_pk_fma_f32 v[12:13], v[52:53], 0.5, v[12:13] op_sel_hi:[1,0,1] neg_lo:[0,0,1] neg_hi:[0,0,1]
	v_pk_fma_f32 v[88:89], v[52:53], 0.5, v[54:55] op_sel_hi:[1,0,1]
	s_mov_b32 s79, s16
	v_mov_b32_e32 v13, v89
	v_pk_mul_f32 v[68:69], v[12:13], s[6:7] op_sel_hi:[1,0]
	v_pk_fma_f32 v[12:13], v[52:53], 0.5, v[54:55] op_sel_hi:[1,0,1] neg_lo:[1,0,0] neg_hi:[1,0,0]
	v_mov_b32_e32 v4, v83
	s_mov_b32 s17, s19
	v_pk_mul_f32 v[48:49], v[82:83], s[78:79] op_sel_hi:[0,1]
	v_pk_add_f32 v[28:29], v[96:97], v[162:163]
	v_pk_add_f32 v[32:33], v[96:97], v[162:163] neg_lo:[0,1] neg_hi:[0,1]
	v_pk_fma_f32 v[52:53], v[4:5], s[16:17], v[48:49] op_sel_hi:[0,1,1] neg_lo:[0,0,1] neg_hi:[0,0,1]
	v_mul_f32_e32 v12, 0.5, v33
	v_pk_fma_f32 v[50:51], v[4:5], s[16:17], v[48:49] op_sel_hi:[0,1,1]
	v_mov_b32_e32 v33, v29
	v_mul_f32_e32 v6, 0.5, v28
	v_mov_b32_e32 v54, v52
	v_mov_b32_e32 v55, v51
	v_pk_mul_f32 v[28:29], v[32:33], s[44:45]
	v_pk_mov_b32 v[56:57], v[50:51], v[52:53] op_sel:[1,0]
	v_pk_mul_f32 v[32:33], v[54:55], v[28:29] op_sel:[0,1] op_sel_hi:[1,0]
	v_pk_mul_f32 v[28:29], v[54:55], v[28:29]
	v_pk_add_f32 v[32:33], v[32:33], v[32:33] op_sel:[0,1] op_sel_hi:[0,1]
	v_pk_add_f32 v[58:59], v[6:7], v[32:33] op_sel_hi:[0,1] neg_hi:[0,1]
	v_pk_add_f32 v[28:29], v[28:29], v[28:29] op_sel:[0,1] op_sel_hi:[0,1] neg_lo:[0,1] neg_hi:[0,1]
	v_pk_add_f32 v[32:33], v[12:13], v[28:29] op_sel_hi:[0,1] neg_hi:[0,1]
	v_pk_mul_f32 v[28:29], v[32:33], v[166:167]
	v_pk_mul_f32 v[32:33], v[32:33], v[164:165]
	v_pk_fma_f32 v[28:29], v[58:59], v[164:165], v[28:29]
	v_pk_fma_f32 v[32:33], v[58:59], v[166:167], v[32:33] neg_lo:[0,0,1] neg_hi:[0,0,1]
	v_mov_b32_e32 v159, v66
	v_pk_add_f32 v[58:59], v[32:33], v[28:29] op_sel:[0,1] op_sel_hi:[1,0] neg_lo:[0,1]
	v_pk_add_f32 v[70:71], v[32:33], v[28:29] op_sel:[0,1] op_sel_hi:[1,0]
	v_pk_add_f32 v[28:29], v[28:29], v[32:33] op_sel:[1,0] op_sel_hi:[0,1] neg_lo:[0,1] neg_hi:[0,1]
	v_pk_mul_f32 v[58:59], v[58:59], 0.5 op_sel_hi:[1,0]
	v_mov_b32_e32 v71, v29
	v_mul_f32_e32 v6, v52, v58
	v_pk_fma_f32 v[72:73], v[54:55], v[58:59], v[6:7] op_sel_hi:[1,1,0] neg_lo:[1,0,0] neg_hi:[1,0,0]
	v_mul_f32_e32 v6, v52, v59
	v_pk_fma_f32 v[56:57], v[56:57], v[58:59], v[6:7] op_sel_hi:[1,1,0]
	v_sub_f32_e32 v12, v67, v153
	v_mov_b32_e32 v72, v56
	v_pk_fma_f32 v[28:29], v[70:71], 0.5, v[56:57] op_sel_hi:[1,0,1] neg_lo:[0,0,1] neg_hi:[0,0,1]
	v_pk_fma_f32 v[96:97], v[70:71], 0.5, v[72:73] op_sel_hi:[1,0,1]
	v_pk_mov_b32 v[56:57], v[48:49], v[152:153] op_sel:[1,0]
	v_mov_b32_e32 v29, v97
	v_pk_mul_f32 v[62:63], v[28:29], s[6:7] op_sel_hi:[1,0]
	v_pk_add_f32 v[28:29], v[66:67], v[152:153]
	v_pk_add_f32 v[56:57], v[158:159], v[56:57] neg_lo:[0,1] neg_hi:[0,1]
	v_mul_f32_e32 v18, 0.5, v29
	v_pk_mul_f32 v[58:59], v[56:57], v[18:19]
	v_mul_f32_e32 v6, 0.5, v28
	v_pk_fma_f32 v[54:55], v[54:55], v[58:59], v[58:59] op_sel:[0,1,0] op_sel_hi:[1,0,1]
	v_mov_b32_e32 v66, v56
	v_mov_b32_e32 v67, v52
	v_mov_b32_e32 v58, v59
	v_mov_b32_e32 v59, v18
	v_pk_mul_f32 v[58:59], v[66:67], v[58:59]
	v_pk_add_f32 v[66:67], v[6:7], v[54:55]
	v_mul_f32_e32 v12, 0.5, v12
	v_fma_f32 v67, v28, 0.5, -v54
	v_pk_add_f32 v[28:29], v[58:59], v[58:59] op_sel:[0,1] op_sel_hi:[0,1] neg_lo:[0,1] neg_hi:[0,1]
	v_pk_add_f32 v[54:55], v[12:13], v[28:29] op_sel_hi:[0,1] neg_hi:[0,1]
	v_pk_mul_f32 v[28:29], v[54:55], v[156:157]
	v_pk_mul_f32 v[54:55], v[54:55], v[154:155]
	v_pk_fma_f32 v[32:33], v[70:71], 0.5, v[72:73] op_sel_hi:[1,0,1] neg_lo:[1,0,0] neg_hi:[1,0,0]
	v_pk_fma_f32 v[58:59], v[66:67], v[154:155], v[28:29] neg_lo:[0,0,1] neg_hi:[0,0,1]
	v_pk_fma_f32 v[28:29], v[66:67], v[154:155], v[28:29]
	v_pk_fma_f32 v[70:71], v[66:67], v[156:157], v[54:55]
	v_pk_fma_f32 v[54:55], v[66:67], v[156:157], v[54:55] neg_lo:[0,0,1] neg_hi:[0,0,1]
	v_pk_add_f32 v[72:73], v[58:59], v[28:29] op_sel:[0,1] op_sel_hi:[1,0]
	v_pk_add_f32 v[66:67], v[70:71], v[54:55] op_sel_hi:[0,1] neg_lo:[0,1] neg_hi:[0,1]
	v_pk_add_f32 v[28:29], v[58:59], v[28:29] op_sel_hi:[0,1] neg_lo:[0,1] neg_hi:[0,1]
	v_pk_add_f32 v[54:55], v[70:71], v[54:55] op_sel:[0,1] op_sel_hi:[1,0]
	v_mov_b32_e32 v73, v67
	v_mov_b32_e32 v55, v29
	v_pk_mul_f32 v[28:29], v[54:55], 0.5 op_sel_hi:[1,0]
	v_mov_b32_e32 v133, v84
	v_pk_mul_f32 v[54:55], v[52:53], v[28:29] op_sel:[0,1] op_sel_hi:[0,0]
	v_pk_fma_f32 v[58:59], v[56:57], v[28:29], v[54:55] op_sel_hi:[0,1,1]
	v_pk_fma_f32 v[28:29], v[56:57], v[28:29], v[54:55] op_sel_hi:[0,1,1] neg_hi:[0,0,1]
	v_pk_fma_f32 v[54:55], v[72:73], 0.5, v[58:59] op_sel_hi:[1,0,1] neg_lo:[0,0,1] neg_hi:[0,0,1]
	v_pk_fma_f32 v[66:67], v[72:73], 0.5, v[28:29] op_sel_hi:[1,0,1]
	v_pk_add_f32 v[56:57], v[60:61], v[134:135] neg_lo:[0,1] neg_hi:[0,1]
	v_mov_b32_e32 v55, v67
	v_pk_mul_f32 v[90:91], v[54:55], s[6:7] op_sel_hi:[1,0]
	v_pk_add_f32 v[54:55], v[134:135], v[60:61]
	v_mul_f32_e32 v12, 0.5, v57
	v_mov_b32_e32 v57, v55
	v_mul_f32_e32 v6, 0.5, v54
	v_pk_mov_b32 v[58:59], v[52:53], v[50:51] op_sel:[1,0]
	v_pk_mul_f32 v[54:55], v[56:57], s[44:45]
	v_pk_fma_f32 v[28:29], v[72:73], 0.5, v[28:29] op_sel_hi:[1,0,1] neg_lo:[1,0,0] neg_hi:[1,0,0]
	v_pk_mul_f32 v[56:57], v[58:59], v[54:55] op_sel:[0,1] op_sel_hi:[1,0]
	v_pk_mul_f32 v[54:55], v[58:59], v[54:55]
	v_pk_add_f32 v[56:57], v[56:57], v[56:57] op_sel:[0,1] op_sel_hi:[0,1]
	v_pk_add_f32 v[60:61], v[6:7], v[56:57] op_sel_hi:[0,1] neg_hi:[0,1]
	v_pk_add_f32 v[54:55], v[54:55], v[54:55] op_sel:[0,1] op_sel_hi:[0,1] neg_lo:[0,1] neg_hi:[0,1]
	v_pk_add_f32 v[56:57], v[12:13], v[54:55] op_sel_hi:[0,1] neg_hi:[0,1]
	v_pk_mul_f32 v[54:55], v[56:57], v[142:143]
	v_pk_mul_f32 v[56:57], v[56:57], v[140:141]
	v_pk_fma_f32 v[54:55], v[60:61], v[140:141], v[54:55]
	v_pk_fma_f32 v[56:57], v[60:61], v[142:143], v[56:57] neg_lo:[0,0,1] neg_hi:[0,0,1]
	v_mov_b32_e32 v51, v53
	v_pk_add_f32 v[60:61], v[56:57], v[54:55] op_sel:[0,1] op_sel_hi:[1,0] neg_lo:[0,1]
	v_pk_add_f32 v[70:71], v[56:57], v[54:55] op_sel:[0,1] op_sel_hi:[1,0]
	v_pk_add_f32 v[54:55], v[54:55], v[56:57] op_sel:[1,0] op_sel_hi:[0,1] neg_lo:[0,1] neg_hi:[0,1]
	v_pk_mul_f32 v[60:61], v[60:61], 0.5 op_sel_hi:[1,0]
	v_mov_b32_e32 v71, v55
	v_mul_f32_e32 v6, v53, v60
	v_pk_fma_f32 v[72:73], v[58:59], v[60:61], v[6:7] op_sel_hi:[1,1,0] neg_lo:[1,0,0] neg_hi:[1,0,0]
	v_mul_f32_e32 v6, v53, v61
	v_pk_fma_f32 v[50:51], v[50:51], v[60:61], v[6:7] op_sel_hi:[1,1,0]
	v_pk_add_f32 v[54:55], v[118:119], v[84:85]
	v_mov_b32_e32 v72, v50
	v_mov_b32_e32 v49, v118
	v_pk_fma_f32 v[50:51], v[70:71], 0.5, v[50:51] op_sel_hi:[1,0,1] neg_lo:[0,0,1] neg_hi:[0,0,1]
	v_pk_fma_f32 v[60:61], v[70:71], 0.5, v[72:73] op_sel_hi:[1,0,1]
	v_mul_f32_e32 v18, 0.5, v55
	v_pk_add_f32 v[48:49], v[132:133], v[48:49] neg_lo:[0,1] neg_hi:[0,1]
	v_mov_b32_e32 v51, v61
	v_pk_mul_f32 v[56:57], v[48:49], v[18:19]
	v_pk_mul_f32 v[94:95], v[50:51], s[6:7] op_sel_hi:[1,0]
	v_pk_fma_f32 v[50:51], v[70:71], 0.5, v[72:73] op_sel_hi:[1,0,1] neg_lo:[1,0,0] neg_hi:[1,0,0]
	v_mul_f32_e32 v6, 0.5, v54
	v_pk_fma_f32 v[58:59], v[58:59], v[56:57], v[56:57] op_sel:[0,1,0] op_sel_hi:[1,0,1]
	v_mov_b32_e32 v70, v48
	v_mov_b32_e32 v71, v53
	v_mov_b32_e32 v56, v57
	v_mov_b32_e32 v57, v18
	v_sub_f32_e32 v12, v85, v119
	v_pk_mul_f32 v[56:57], v[70:71], v[56:57]
	v_pk_add_f32 v[70:71], v[6:7], v[58:59]
	v_mul_f32_e32 v12, 0.5, v12
	v_fma_f32 v71, v54, 0.5, -v58
	v_pk_add_f32 v[54:55], v[56:57], v[56:57] op_sel:[0,1] op_sel_hi:[0,1] neg_lo:[0,1] neg_hi:[0,1]
	v_pk_add_f32 v[56:57], v[12:13], v[54:55] op_sel_hi:[0,1] neg_hi:[0,1]
	v_pk_mul_f32 v[54:55], v[56:57], v[126:127]
	v_pk_mul_f32 v[56:57], v[56:57], v[124:125]
	v_pk_fma_f32 v[58:59], v[70:71], v[124:125], v[54:55] neg_lo:[0,0,1] neg_hi:[0,0,1]
	v_pk_fma_f32 v[54:55], v[70:71], v[124:125], v[54:55]
	v_pk_fma_f32 v[72:73], v[70:71], v[126:127], v[56:57]
	v_pk_fma_f32 v[56:57], v[70:71], v[126:127], v[56:57] neg_lo:[0,0,1] neg_hi:[0,0,1]
	v_pk_add_f32 v[70:71], v[58:59], v[54:55] op_sel:[0,1] op_sel_hi:[1,0]
	v_pk_add_f32 v[74:75], v[72:73], v[56:57] op_sel_hi:[0,1] neg_lo:[0,1] neg_hi:[0,1]
	v_pk_add_f32 v[54:55], v[58:59], v[54:55] op_sel_hi:[0,1] neg_lo:[0,1] neg_hi:[0,1]
	v_pk_add_f32 v[56:57], v[72:73], v[56:57] op_sel:[0,1] op_sel_hi:[1,0]
	v_mov_b32_e32 v71, v75
	v_mov_b32_e32 v57, v55
	v_pk_mul_f32 v[54:55], v[56:57], 0.5 op_sel_hi:[1,0]
	s_mov_b32 s78, s11
	v_pk_mul_f32 v[52:53], v[52:53], v[54:55] op_sel:[1,1] op_sel_hi:[1,0]
	s_mov_b32 s79, s8
	v_pk_fma_f32 v[56:57], v[48:49], v[54:55], v[52:53] op_sel_hi:[0,1,1]
	v_pk_fma_f32 v[48:49], v[48:49], v[54:55], v[52:53] op_sel_hi:[0,1,1] neg_hi:[0,0,1]
	s_nop 0
	v_pk_fma_f32 v[52:53], v[70:71], 0.5, v[56:57] op_sel_hi:[1,0,1] neg_lo:[0,0,1] neg_hi:[0,0,1]
	v_pk_fma_f32 v[84:85], v[70:71], 0.5, v[48:49] op_sel_hi:[1,0,1]
	s_mov_b32 s9, s11
	v_mov_b32_e32 v53, v85
	v_pk_mul_f32 v[80:81], v[52:53], s[6:7] op_sel_hi:[1,0]
	v_pk_mul_f32 v[118:119], v[82:83], s[78:79] op_sel_hi:[0,1]
	v_pk_add_f32 v[52:53], v[86:87], v[112:113]
	v_pk_add_f32 v[54:55], v[86:87], v[112:113] neg_lo:[0,1] neg_hi:[0,1]
	v_pk_fma_f32 v[58:59], v[4:5], s[8:9], v[118:119] op_sel_hi:[0,1,1] neg_lo:[0,0,1] neg_hi:[0,0,1]
	v_mul_f32_e32 v12, 0.5, v55
	v_pk_fma_f32 v[72:73], v[4:5], s[8:9], v[118:119] op_sel_hi:[0,1,1]
	v_mov_b32_e32 v55, v53
	v_mul_f32_e32 v6, 0.5, v52
	v_mov_b32_e32 v56, v58
	v_mov_b32_e32 v57, v73
	v_pk_mul_f32 v[52:53], v[54:55], s[44:45]
	v_pk_fma_f32 v[48:49], v[70:71], 0.5, v[48:49] op_sel_hi:[1,0,1] neg_lo:[1,0,0] neg_hi:[1,0,0]
	v_pk_mul_f32 v[54:55], v[56:57], v[52:53] op_sel:[0,1] op_sel_hi:[1,0]
	v_pk_mul_f32 v[52:53], v[56:57], v[52:53]
	v_pk_add_f32 v[54:55], v[54:55], v[54:55] op_sel:[0,1] op_sel_hi:[0,1]
	v_pk_add_f32 v[74:75], v[6:7], v[54:55] op_sel_hi:[0,1] neg_hi:[0,1]
	v_pk_add_f32 v[52:53], v[52:53], v[52:53] op_sel:[0,1] op_sel_hi:[0,1] neg_lo:[0,1] neg_hi:[0,1]
	v_pk_add_f32 v[54:55], v[12:13], v[52:53] op_sel_hi:[0,1] neg_hi:[0,1]
	v_pk_mul_f32 v[52:53], v[54:55], v[116:117]
	v_pk_mul_f32 v[54:55], v[54:55], v[114:115]
	v_pk_fma_f32 v[52:53], v[74:75], v[114:115], v[52:53]
	v_pk_fma_f32 v[54:55], v[74:75], v[116:117], v[54:55] neg_lo:[0,0,1] neg_hi:[0,0,1]
	v_pk_mov_b32 v[70:71], v[72:73], v[58:59] op_sel:[1,0]
	v_pk_add_f32 v[74:75], v[54:55], v[52:53] op_sel:[0,1] op_sel_hi:[1,0] neg_lo:[0,1]
	v_pk_add_f32 v[76:77], v[54:55], v[52:53] op_sel:[0,1] op_sel_hi:[1,0]
	v_pk_add_f32 v[52:53], v[52:53], v[54:55] op_sel:[1,0] op_sel_hi:[0,1] neg_lo:[0,1] neg_hi:[0,1]
	v_pk_mul_f32 v[74:75], v[74:75], 0.5 op_sel_hi:[1,0]
	v_mov_b32_e32 v77, v53
	v_mul_f32_e32 v6, v58, v74
	v_pk_fma_f32 v[112:113], v[56:57], v[74:75], v[6:7] op_sel_hi:[1,1,0] neg_lo:[1,0,0] neg_hi:[1,0,0]
	v_mul_f32_e32 v6, v58, v75
	v_pk_fma_f32 v[70:71], v[70:71], v[74:75], v[6:7] op_sel_hi:[1,1,0]
	v_pk_add_f32 v[54:55], v[34:35], v[110:111]
	v_mov_b32_e32 v112, v70
	v_pk_fma_f32 v[52:53], v[76:77], 0.5, v[70:71] op_sel_hi:[1,0,1] neg_lo:[0,0,1] neg_hi:[0,0,1]
	v_pk_fma_f32 v[86:87], v[76:77], 0.5, v[112:113] op_sel_hi:[1,0,1]
	v_sub_f32_e32 v12, v35, v111
	v_mov_b32_e32 v53, v87
	v_pk_mul_f32 v[78:79], v[52:53], s[6:7] op_sel_hi:[1,0]
	v_mul_f32_e32 v52, 0xbe47c5c2, v83
	v_mov_b32_e32 v53, v34
	v_pk_mov_b32 v[34:35], v[118:119], v[110:111] op_sel:[1,0]
	v_mul_f32_e32 v18, 0.5, v55
	v_pk_add_f32 v[34:35], v[52:53], v[34:35] neg_lo:[0,1] neg_hi:[0,1]
	v_mov_b32_e32 v71, v58
	v_pk_mul_f32 v[52:53], v[34:35], v[18:19]
	v_mov_b32_e32 v70, v34
	v_pk_fma_f32 v[56:57], v[56:57], v[52:53], v[52:53] op_sel:[0,1,0] op_sel_hi:[1,0,1]
	v_mov_b32_e32 v52, v53
	v_mov_b32_e32 v53, v18
	v_mul_f32_e32 v6, 0.5, v54
	v_pk_mul_f32 v[52:53], v[70:71], v[52:53]
	v_cvt_f32_f16_e32 v70, v46
	v_cvt_f32_f16_e32 v71, v47
	v_cvt_f32_f16_sdwa v47, v47 dst_sel:DWORD dst_unused:UNUSED_PAD src0_sel:WORD_1
	v_cvt_f32_f16_sdwa v46, v46 dst_sel:DWORD dst_unused:UNUSED_PAD src0_sel:WORD_1
	v_pk_fma_f32 v[74:75], v[76:77], 0.5, v[112:113] op_sel_hi:[1,0,1] neg_lo:[1,0,0] neg_hi:[1,0,0]
	v_mul_f32_e32 v12, 0.5, v12
	v_pk_add_f32 v[76:77], v[6:7], v[56:57]
	v_pk_add_f32 v[52:53], v[52:53], v[52:53] op_sel:[0,1] op_sel_hi:[0,1] neg_lo:[0,1] neg_hi:[0,1]
	v_fma_f32 v77, v54, 0.5, -v56
	v_pk_add_f32 v[54:55], v[12:13], v[52:53] op_sel_hi:[0,1] neg_hi:[0,1]
	v_pk_mul_f32 v[52:53], v[54:55], v[46:47]
	v_pk_mul_f32 v[54:55], v[54:55], v[70:71]
	v_pk_fma_f32 v[56:57], v[76:77], v[70:71], v[52:53] neg_lo:[0,0,1] neg_hi:[0,0,1]
	v_pk_fma_f32 v[52:53], v[76:77], v[70:71], v[52:53]
	v_pk_fma_f32 v[70:71], v[76:77], v[46:47], v[54:55]
	v_pk_fma_f32 v[46:47], v[76:77], v[46:47], v[54:55] neg_lo:[0,0,1] neg_hi:[0,0,1]
	v_pk_add_f32 v[54:55], v[56:57], v[52:53] op_sel:[0,1] op_sel_hi:[1,0]
	v_pk_add_f32 v[76:77], v[70:71], v[46:47] op_sel_hi:[0,1] neg_lo:[0,1] neg_hi:[0,1]
	v_pk_add_f32 v[52:53], v[56:57], v[52:53] op_sel_hi:[0,1] neg_lo:[0,1] neg_hi:[0,1]
	v_pk_add_f32 v[46:47], v[70:71], v[46:47] op_sel:[0,1] op_sel_hi:[1,0]
	v_mov_b32_e32 v55, v77
	v_mov_b32_e32 v47, v53
	v_pk_mul_f32 v[46:47], v[46:47], 0.5 op_sel_hi:[1,0]
	s_mov_b32 s25, s27
	v_pk_mul_f32 v[52:53], v[58:59], v[46:47] op_sel:[0,1] op_sel_hi:[0,0]
	v_pk_fma_f32 v[56:57], v[34:35], v[46:47], v[52:53] op_sel_hi:[0,1,1]
	v_pk_fma_f32 v[46:47], v[34:35], v[46:47], v[52:53] op_sel_hi:[0,1,1] neg_hi:[0,0,1]
	s_nop 0
	v_pk_fma_f32 v[52:53], v[54:55], 0.5, v[56:57] op_sel_hi:[1,0,1] neg_lo:[0,0,1] neg_hi:[0,0,1]
	v_pk_fma_f32 v[34:35], v[54:55], 0.5, v[46:47] op_sel_hi:[1,0,1]
	s_mov_b32 s78, s27
	v_mov_b32_e32 v53, v35
	v_pk_mul_f32 v[136:137], v[52:53], s[6:7] op_sel_hi:[1,0]
	v_pk_fma_f32 v[52:53], v[54:55], 0.5, v[46:47] op_sel_hi:[1,0,1] neg_lo:[1,0,0] neg_hi:[1,0,0]
	s_mov_b32 s79, s24
	v_pk_mul_f32 v[46:47], v[82:83], s[24:25] op_sel_hi:[0,1]
	v_pk_add_f32 v[54:55], v[108:109], v[40:41]
	v_pk_add_f32 v[40:41], v[40:41], v[108:109] neg_lo:[0,1] neg_hi:[0,1]
	v_pk_fma_f32 v[108:109], v[4:5], s[78:79], v[46:47] op_sel_hi:[0,1,1] neg_lo:[0,0,1] neg_hi:[0,0,1]
	v_mul_f32_e32 v12, 0.5, v41
	v_pk_fma_f32 v[70:71], v[4:5], s[78:79], v[46:47] op_sel_hi:[0,1,1]
	v_mov_b32_e32 v41, v55
	v_mov_b32_e32 v56, v108
	v_mov_b32_e32 v57, v71
	v_pk_mul_f32 v[40:41], v[40:41], s[44:45]
	v_mul_f32_e32 v6, 0.5, v54
	v_pk_mul_f32 v[54:55], v[56:57], v[40:41] op_sel:[0,1] op_sel_hi:[1,0]
	v_cvt_f32_f16_sdwa v76, v36 dst_sel:DWORD dst_unused:UNUSED_PAD src0_sel:WORD_1
	v_cvt_f32_f16_e32 v77, v37
	v_cvt_f32_f16_sdwa v37, v37 dst_sel:DWORD dst_unused:UNUSED_PAD src0_sel:WORD_1
	v_cvt_f32_f16_e32 v36, v36
	v_pk_mul_f32 v[40:41], v[56:57], v[40:41]
	v_pk_add_f32 v[54:55], v[54:55], v[54:55] op_sel:[0,1] op_sel_hi:[0,1]
	v_pk_add_f32 v[112:113], v[6:7], v[54:55] op_sel_hi:[0,1] neg_hi:[0,1]
	s_nop 0
	v_pk_add_f32 v[40:41], v[40:41], v[40:41] op_sel:[0,1] op_sel_hi:[0,1] neg_lo:[0,1] neg_hi:[0,1]
	v_pk_add_f32 v[54:55], v[12:13], v[40:41] op_sel_hi:[0,1] neg_hi:[0,1]
	v_pk_mul_f32 v[40:41], v[54:55], v[36:37]
	v_pk_mul_f32 v[54:55], v[54:55], v[76:77]
	v_pk_fma_f32 v[40:41], v[112:113], v[76:77], v[40:41]
	v_pk_fma_f32 v[36:37], v[112:113], v[36:37], v[54:55] neg_lo:[0,0,1] neg_hi:[0,0,1]
	v_pk_mov_b32 v[110:111], v[70:71], v[108:109] op_sel:[1,0]
	v_pk_add_f32 v[54:55], v[36:37], v[40:41] op_sel:[0,1] op_sel_hi:[1,0] neg_lo:[0,1]
	v_pk_add_f32 v[76:77], v[36:37], v[40:41] op_sel:[0,1] op_sel_hi:[1,0]
	v_pk_add_f32 v[36:37], v[40:41], v[36:37] op_sel:[1,0] op_sel_hi:[0,1] neg_lo:[0,1] neg_hi:[0,1]
	v_pk_mul_f32 v[54:55], v[54:55], 0.5 op_sel_hi:[1,0]
	v_mov_b32_e32 v77, v37
	v_mul_f32_e32 v4, v108, v54
	v_pk_fma_f32 v[112:113], v[56:57], v[54:55], v[4:5] op_sel_hi:[1,1,0] neg_lo:[1,0,0] neg_hi:[1,0,0]
	v_mul_f32_e32 v4, v108, v55
	v_pk_fma_f32 v[54:55], v[110:111], v[54:55], v[4:5] op_sel_hi:[1,1,0]
	v_sub_f32_e32 v6, v45, v105
	v_mov_b32_e32 v112, v54
	v_pk_fma_f32 v[40:41], v[76:77], 0.5, v[54:55] op_sel_hi:[1,0,1] neg_lo:[0,0,1] neg_hi:[0,0,1]
	v_pk_fma_f32 v[36:37], v[76:77], 0.5, v[112:113] op_sel_hi:[1,0,1]
	v_pk_add_f32 v[54:55], v[104:105], v[44:45]
	v_mov_b32_e32 v41, v37
	v_pk_mul_f32 v[130:131], v[40:41], s[6:7] op_sel_hi:[1,0]
	v_mul_f32_e32 v40, 0xbf54db31, v83
	v_mov_b32_e32 v41, v44
	v_pk_mov_b32 v[44:45], v[46:47], v[104:105] op_sel:[1,0]
	v_mul_f32_e32 v18, 0.5, v55
	v_pk_add_f32 v[40:41], v[40:41], v[44:45] neg_lo:[0,1] neg_hi:[0,1]
	v_mov_b32_e32 v105, v108
	v_pk_mul_f32 v[44:45], v[40:41], v[18:19]
	v_mov_b32_e32 v104, v40
	v_pk_fma_f32 v[56:57], v[56:57], v[44:45], v[44:45] op_sel:[0,1,0] op_sel_hi:[1,0,1]
	v_mov_b32_e32 v44, v45
	v_mov_b32_e32 v45, v18
	v_mul_f32_e32 v4, 0.5, v54
	v_pk_mul_f32 v[44:45], v[104:105], v[44:45]
	v_cvt_f32_f16_e32 v104, v26
	v_cvt_f32_f16_e32 v105, v27
	v_cvt_f32_f16_sdwa v27, v27 dst_sel:DWORD dst_unused:UNUSED_PAD src0_sel:WORD_1
	v_cvt_f32_f16_sdwa v26, v26 dst_sel:DWORD dst_unused:UNUSED_PAD src0_sel:WORD_1
	v_mul_f32_e32 v6, 0.5, v6
	v_pk_add_f32 v[110:111], v[4:5], v[56:57]
	v_pk_add_f32 v[44:45], v[44:45], v[44:45] op_sel:[0,1] op_sel_hi:[0,1] neg_lo:[0,1] neg_hi:[0,1]
	v_fma_f32 v111, v54, 0.5, -v56
	v_pk_add_f32 v[54:55], v[6:7], v[44:45] op_sel_hi:[0,1] neg_hi:[0,1]
	v_pk_mul_f32 v[44:45], v[54:55], v[26:27]
	v_pk_mul_f32 v[54:55], v[54:55], v[104:105]
	v_pk_fma_f32 v[56:57], v[110:111], v[104:105], v[44:45] neg_lo:[0,0,1] neg_hi:[0,0,1]
	v_pk_fma_f32 v[44:45], v[110:111], v[104:105], v[44:45]
	v_pk_fma_f32 v[104:105], v[110:111], v[26:27], v[54:55]
	v_pk_fma_f32 v[26:27], v[110:111], v[26:27], v[54:55] neg_lo:[0,0,1] neg_hi:[0,0,1]
	v_pk_add_f32 v[54:55], v[56:57], v[44:45] op_sel:[0,1] op_sel_hi:[1,0]
	v_pk_add_f32 v[110:111], v[104:105], v[26:27] op_sel_hi:[0,1] neg_lo:[0,1] neg_hi:[0,1]
	v_pk_add_f32 v[44:45], v[56:57], v[44:45] op_sel_hi:[0,1] neg_lo:[0,1] neg_hi:[0,1]
	v_pk_add_f32 v[26:27], v[104:105], v[26:27] op_sel:[0,1] op_sel_hi:[1,0]
	v_mov_b32_e32 v55, v111
	v_mov_b32_e32 v27, v45
	v_pk_mul_f32 v[26:27], v[26:27], 0.5 op_sel_hi:[1,0]
	v_mov_b32_e32 v47, v102
	v_pk_mul_f32 v[44:45], v[108:109], v[26:27] op_sel:[0,1] op_sel_hi:[0,0]
	v_pk_fma_f32 v[56:57], v[40:41], v[26:27], v[44:45] op_sel_hi:[0,1,1]
	v_pk_fma_f32 v[40:41], v[40:41], v[26:27], v[44:45] op_sel_hi:[0,1,1] neg_hi:[0,0,1]
	v_pk_fma_f32 v[44:45], v[54:55], 0.5, v[56:57] op_sel_hi:[1,0,1] neg_lo:[0,0,1] neg_hi:[0,0,1]
	v_pk_fma_f32 v[26:27], v[54:55], 0.5, v[40:41] op_sel_hi:[1,0,1]
	v_pk_fma_f32 v[56:57], v[54:55], 0.5, v[40:41] op_sel_hi:[1,0,1] neg_lo:[1,0,0] neg_hi:[1,0,0]
	v_pk_add_f32 v[40:41], v[106:107], v[42:43]
	v_pk_add_f32 v[42:43], v[42:43], v[106:107] neg_lo:[0,1] neg_hi:[0,1]
	v_mov_b32_e32 v45, v27
	v_mul_f32_e32 v6, 0.5, v43
	v_mov_b32_e32 v43, v41
	v_pk_mul_f32 v[120:121], v[44:45], s[6:7] op_sel_hi:[1,0]
	v_mul_f32_e32 v4, 0.5, v40
	v_pk_mov_b32 v[44:45], v[108:109], v[70:71] op_sel:[1,0]
	v_pk_mul_f32 v[40:41], v[42:43], s[44:45]
	v_cvt_f32_f16_sdwa v54, v20 dst_sel:DWORD dst_unused:UNUSED_PAD src0_sel:WORD_1
	v_pk_mul_f32 v[42:43], v[44:45], v[40:41] op_sel:[0,1] op_sel_hi:[1,0]
	v_cvt_f32_f16_e32 v55, v21
	v_cvt_f32_f16_sdwa v21, v21 dst_sel:DWORD dst_unused:UNUSED_PAD src0_sel:WORD_1
	v_cvt_f32_f16_e32 v20, v20
	v_pk_mul_f32 v[40:41], v[44:45], v[40:41]
	v_pk_add_f32 v[42:43], v[42:43], v[42:43] op_sel:[0,1] op_sel_hi:[0,1]
	v_pk_add_f32 v[104:105], v[4:5], v[42:43] op_sel_hi:[0,1] neg_hi:[0,1]
	s_nop 0
	v_pk_add_f32 v[40:41], v[40:41], v[40:41] op_sel:[0,1] op_sel_hi:[0,1] neg_lo:[0,1] neg_hi:[0,1]
	v_pk_add_f32 v[42:43], v[6:7], v[40:41] op_sel_hi:[0,1] neg_hi:[0,1]
	v_pk_mul_f32 v[40:41], v[42:43], v[20:21]
	v_pk_mul_f32 v[42:43], v[42:43], v[54:55]
	v_pk_fma_f32 v[40:41], v[104:105], v[54:55], v[40:41]
	v_pk_fma_f32 v[20:21], v[104:105], v[20:21], v[42:43] neg_lo:[0,0,1] neg_hi:[0,0,1]
	v_mov_b32_e32 v71, v109
	v_pk_add_f32 v[42:43], v[20:21], v[40:41] op_sel:[0,1] op_sel_hi:[1,0] neg_lo:[0,1]
	v_pk_add_f32 v[54:55], v[20:21], v[40:41] op_sel:[0,1] op_sel_hi:[1,0]
	v_pk_add_f32 v[20:21], v[40:41], v[20:21] op_sel:[1,0] op_sel_hi:[0,1] neg_lo:[0,1] neg_hi:[0,1]
	v_pk_mul_f32 v[42:43], v[42:43], 0.5 op_sel_hi:[1,0]
	v_mov_b32_e32 v55, v21
	v_mul_f32_e32 v4, v109, v42
	v_pk_fma_f32 v[104:105], v[44:45], v[42:43], v[4:5] op_sel_hi:[1,1,0] neg_lo:[1,0,0] neg_hi:[1,0,0]
	v_mul_f32_e32 v4, v109, v43
	v_pk_fma_f32 v[42:43], v[70:71], v[42:43], v[4:5] op_sel_hi:[1,1,0]
	v_sub_f32_e32 v6, v23, v103
	v_mov_b32_e32 v104, v42
	v_pk_fma_f32 v[40:41], v[54:55], 0.5, v[42:43] op_sel_hi:[1,0,1] neg_lo:[0,0,1] neg_hi:[0,0,1]
	v_pk_fma_f32 v[20:21], v[54:55], 0.5, v[104:105] op_sel_hi:[1,0,1]
	v_pk_add_f32 v[42:43], v[102:103], v[22:23]
	v_mov_b32_e32 v41, v21
	v_pk_mul_f32 v[128:129], v[40:41], s[6:7] op_sel_hi:[1,0]
	v_mul_f32_e32 v40, 0xbf0e39da, v83
	v_mov_b32_e32 v41, v22
	v_mul_f32_e32 v18, 0.5, v43
	v_pk_add_f32 v[22:23], v[40:41], v[46:47] neg_lo:[0,1] neg_hi:[0,1]
	v_mov_b32_e32 v47, v109
	v_pk_mul_f32 v[40:41], v[22:23], v[18:19]
	v_mov_b32_e32 v46, v22
	v_pk_fma_f32 v[44:45], v[44:45], v[40:41], v[40:41] op_sel:[0,1,0] op_sel_hi:[1,0,1]
	v_mov_b32_e32 v40, v41
	v_mov_b32_e32 v41, v18
	v_mul_f32_e32 v4, 0.5, v42
	v_pk_mul_f32 v[40:41], v[46:47], v[40:41]
	v_cvt_f32_f16_e32 v46, v10
	v_cvt_f32_f16_e32 v47, v11
	v_cvt_f32_f16_sdwa v11, v11 dst_sel:DWORD dst_unused:UNUSED_PAD src0_sel:WORD_1
	v_cvt_f32_f16_sdwa v10, v10 dst_sel:DWORD dst_unused:UNUSED_PAD src0_sel:WORD_1
	v_pk_fma_f32 v[70:71], v[54:55], 0.5, v[104:105] op_sel_hi:[1,0,1] neg_lo:[1,0,0] neg_hi:[1,0,0]
	v_mul_f32_e32 v6, 0.5, v6
	v_pk_add_f32 v[54:55], v[4:5], v[44:45]
	v_pk_add_f32 v[40:41], v[40:41], v[40:41] op_sel:[0,1] op_sel_hi:[0,1] neg_lo:[0,1] neg_hi:[0,1]
	v_fma_f32 v55, v42, 0.5, -v44
	v_pk_add_f32 v[42:43], v[6:7], v[40:41] op_sel_hi:[0,1] neg_hi:[0,1]
	v_pk_mul_f32 v[40:41], v[42:43], v[10:11]
	v_pk_mul_f32 v[42:43], v[42:43], v[46:47]
	v_pk_fma_f32 v[44:45], v[54:55], v[46:47], v[40:41] neg_lo:[0,0,1] neg_hi:[0,0,1]
	v_pk_fma_f32 v[40:41], v[54:55], v[46:47], v[40:41]
	v_pk_fma_f32 v[46:47], v[54:55], v[10:11], v[42:43]
	v_pk_fma_f32 v[10:11], v[54:55], v[10:11], v[42:43] neg_lo:[0,0,1] neg_hi:[0,0,1]
	v_pk_add_f32 v[42:43], v[44:45], v[40:41] op_sel:[0,1] op_sel_hi:[1,0]
	v_pk_add_f32 v[54:55], v[46:47], v[10:11] op_sel_hi:[0,1] neg_lo:[0,1] neg_hi:[0,1]
	v_pk_add_f32 v[40:41], v[44:45], v[40:41] op_sel_hi:[0,1] neg_lo:[0,1] neg_hi:[0,1]
	v_pk_add_f32 v[10:11], v[46:47], v[10:11] op_sel:[0,1] op_sel_hi:[1,0]
	v_mov_b32_e32 v43, v55
	v_mov_b32_e32 v11, v41
	v_pk_mul_f32 v[10:11], v[10:11], 0.5 op_sel_hi:[1,0]
	v_mov_b32_e32 v119, v98
	v_pk_mul_f32 v[40:41], v[108:109], v[10:11] op_sel:[1,1] op_sel_hi:[1,0]
	v_pk_fma_f32 v[76:77], v[76:77], 0.5, v[112:113] op_sel_hi:[1,0,1] neg_lo:[1,0,0] neg_hi:[1,0,0]
	v_pk_fma_f32 v[44:45], v[22:23], v[10:11], v[40:41] op_sel_hi:[0,1,1]
	v_pk_fma_f32 v[10:11], v[22:23], v[10:11], v[40:41] op_sel_hi:[0,1,1] neg_hi:[0,0,1]
	v_pk_fma_f32 v[22:23], v[42:43], 0.5, v[44:45] op_sel_hi:[1,0,1] neg_lo:[0,0,1] neg_hi:[0,0,1]
	v_pk_fma_f32 v[40:41], v[42:43], 0.5, v[10:11] op_sel_hi:[1,0,1]
	v_pk_fma_f32 v[54:55], v[42:43], 0.5, v[10:11] op_sel_hi:[1,0,1] neg_lo:[1,0,0] neg_hi:[1,0,0]
	v_pk_add_f32 v[10:11], v[100:101], v[14:15]
	v_pk_add_f32 v[14:15], v[14:15], v[100:101] neg_lo:[0,1] neg_hi:[0,1]
	v_mov_b32_e32 v23, v41
	v_mul_f32_e32 v6, 0.5, v15
	v_mov_b32_e32 v15, v11
	v_pk_mul_f32 v[150:151], v[22:23], s[6:7] op_sel_hi:[1,0]
	v_mul_f32_e32 v4, 0.5, v10
	v_pk_mov_b32 v[22:23], v[58:59], v[72:73] op_sel:[1,0]
	v_pk_mul_f32 v[10:11], v[14:15], s[44:45]
	v_cvt_f32_f16_sdwa v42, v8 dst_sel:DWORD dst_unused:UNUSED_PAD src0_sel:WORD_1
	v_pk_mul_f32 v[14:15], v[22:23], v[10:11] op_sel:[0,1] op_sel_hi:[1,0]
	v_cvt_f32_f16_e32 v43, v9
	v_cvt_f32_f16_sdwa v9, v9 dst_sel:DWORD dst_unused:UNUSED_PAD src0_sel:WORD_1
	v_cvt_f32_f16_e32 v8, v8
	v_pk_mul_f32 v[10:11], v[22:23], v[10:11]
	v_pk_add_f32 v[14:15], v[14:15], v[14:15] op_sel:[0,1] op_sel_hi:[0,1]
	v_pk_add_f32 v[44:45], v[4:5], v[14:15] op_sel_hi:[0,1] neg_hi:[0,1]
	s_nop 0
	v_pk_add_f32 v[10:11], v[10:11], v[10:11] op_sel:[0,1] op_sel_hi:[0,1] neg_lo:[0,1] neg_hi:[0,1]
	v_pk_add_f32 v[14:15], v[6:7], v[10:11] op_sel_hi:[0,1] neg_hi:[0,1]
	v_pk_mul_f32 v[10:11], v[14:15], v[8:9]
	v_pk_mul_f32 v[14:15], v[14:15], v[42:43]
	v_pk_fma_f32 v[10:11], v[44:45], v[42:43], v[10:11]
	v_pk_fma_f32 v[8:9], v[44:45], v[8:9], v[14:15] neg_lo:[0,0,1] neg_hi:[0,0,1]
	v_mov_b32_e32 v73, v59
	v_pk_add_f32 v[14:15], v[8:9], v[10:11] op_sel:[0,1] op_sel_hi:[1,0] neg_lo:[0,1]
	v_pk_add_f32 v[42:43], v[8:9], v[10:11] op_sel:[0,1] op_sel_hi:[1,0]
	v_pk_add_f32 v[8:9], v[10:11], v[8:9] op_sel:[1,0] op_sel_hi:[0,1] neg_lo:[0,1] neg_hi:[0,1]
	v_pk_mul_f32 v[14:15], v[14:15], 0.5 op_sel_hi:[1,0]
	v_mov_b32_e32 v43, v9
	v_mul_f32_e32 v4, v59, v14
	v_pk_fma_f32 v[44:45], v[22:23], v[14:15], v[4:5] op_sel_hi:[1,1,0] neg_lo:[1,0,0] neg_hi:[1,0,0]
	v_mul_f32_e32 v4, v59, v15
	v_pk_fma_f32 v[14:15], v[72:73], v[14:15], v[4:5] op_sel_hi:[1,1,0]
	v_sub_f32_e32 v6, v39, v99
	v_mov_b32_e32 v44, v14
	v_pk_fma_f32 v[8:9], v[42:43], 0.5, v[14:15] op_sel_hi:[1,0,1] neg_lo:[0,0,1] neg_hi:[0,0,1]
	v_pk_fma_f32 v[10:11], v[42:43], 0.5, v[44:45] op_sel_hi:[1,0,1]
	v_pk_add_f32 v[14:15], v[98:99], v[38:39]
	v_mov_b32_e32 v9, v11
	v_pk_mul_f32 v[168:169], v[8:9], s[6:7] op_sel_hi:[1,0]
	v_mul_f32_e32 v8, 0xbf7b14be, v83
	v_mov_b32_e32 v9, v38
	v_mul_f32_e32 v18, 0.5, v15
	v_pk_add_f32 v[8:9], v[8:9], v[118:119] neg_lo:[0,1] neg_hi:[0,1]
	v_pk_fma_f32 v[72:73], v[42:43], 0.5, v[44:45] op_sel_hi:[1,0,1] neg_lo:[1,0,0] neg_hi:[1,0,0]
	v_pk_mul_f32 v[38:39], v[8:9], v[18:19]
	v_mov_b32_e32 v42, v8
	v_pk_fma_f32 v[22:23], v[22:23], v[38:39], v[38:39] op_sel:[0,1,0] op_sel_hi:[1,0,1]
	v_mov_b32_e32 v43, v59
	v_mov_b32_e32 v38, v39
	v_mov_b32_e32 v39, v18
	v_mul_f32_e32 v4, 0.5, v14
	v_pk_mul_f32 v[38:39], v[42:43], v[38:39]
	v_cvt_f32_f16_e32 v44, v2
	v_cvt_f32_f16_e32 v45, v3
	v_cvt_f32_f16_sdwa v3, v3 dst_sel:DWORD dst_unused:UNUSED_PAD src0_sel:WORD_1
	v_cvt_f32_f16_sdwa v2, v2 dst_sel:DWORD dst_unused:UNUSED_PAD src0_sel:WORD_1
	v_mul_f32_e32 v6, 0.5, v6
	v_pk_add_f32 v[46:47], v[4:5], v[22:23]
	v_fma_f32 v4, v14, 0.5, -v22
	v_pk_add_f32 v[22:23], v[38:39], v[38:39] op_sel:[0,1] op_sel_hi:[0,1] neg_lo:[0,1] neg_hi:[0,1]
	v_pk_add_f32 v[38:39], v[6:7], v[22:23] op_sel_hi:[0,1] neg_hi:[0,1]
	v_mov_b32_e32 v14, v46
	v_mov_b32_e32 v15, v4
	v_pk_mul_f32 v[22:23], v[4:5], v[44:45] op_sel_hi:[0,1]
	v_pk_mul_f32 v[82:83], v[38:39], v[2:3]
	v_pk_mul_f32 v[46:47], v[46:47], v[2:3]
	v_pk_mul_f32 v[38:39], v[38:39], v[44:45]
	v_pk_fma_f32 v[98:99], v[14:15], v[44:45], v[82:83] neg_lo:[0,0,1] neg_hi:[0,0,1]
	v_pk_fma_f32 v[2:3], v[14:15], v[2:3], v[38:39] neg_lo:[0,0,1] neg_hi:[0,0,1]
	v_add_f32_e32 v4, v23, v83
	v_add_f32_e32 v6, v46, v38
	v_pk_add_f32 v[22:23], v[6:7], v[2:3] op_sel_hi:[0,1] neg_lo:[0,1] neg_hi:[0,1]
	v_pk_add_f32 v[38:39], v[98:99], v[4:5] op_sel_hi:[1,0] neg_lo:[0,1] neg_hi:[0,1]
	v_pk_add_f32 v[2:3], v[6:7], v[2:3] op_sel_hi:[0,1]
	v_mov_b32_e32 v39, v3
	v_pk_mul_f32 v[2:3], v[38:39], 0.5 op_sel_hi:[1,0]
	v_pk_add_f32 v[14:15], v[98:99], v[4:5] op_sel_hi:[1,0]
	v_mul_f32_e32 v4, v59, v3
	v_pk_fma_f32 v[38:39], v[42:43], v[2:3], v[4:5] op_sel_hi:[1,1,0] neg_lo:[0,0,1] neg_hi:[0,0,1]
	v_pk_mov_b32 v[42:43], v[58:59], v[8:9] op_sel:[1,0]
	v_mul_f32_e32 v4, v8, v3
	v_pk_fma_f32 v[2:3], v[42:43], v[2:3], v[4:5] op_sel_hi:[1,1,0]
	v_mov_b32_e32 v15, v23
	v_pk_fma_f32 v[8:9], v[14:15], 0.5, v[2:3] op_sel_hi:[1,0,1] neg_lo:[0,0,1] neg_hi:[0,0,1]
	v_pk_fma_f32 v[42:43], v[14:15], 0.5, v[38:39] op_sel_hi:[1,0,0]
	v_pk_fma_f32 v[2:3], v[14:15], 0.5, v[2:3] op_sel_hi:[1,0,1]
	v_mov_b32_e32 v9, v43
	v_pk_fma_f32 v[58:59], v[22:23], 0.5, v[38:39] op_sel_hi:[1,0,0] neg_lo:[1,0,0] neg_hi:[1,0,0]
	v_pk_mul_f32 v[144:145], v[8:9], s[6:7] op_sel_hi:[1,0]
	v_mov_b32_e32 v58, v2
	v_mov_b32_e32 v72, v10
	v_mov_b32_e32 v54, v40
	v_mov_b32_e32 v70, v20
	v_mov_b32_e32 v56, v26
	v_mov_b32_e32 v76, v36
	v_mov_b32_e32 v52, v34
	v_mov_b32_e32 v74, v86
	v_mov_b32_e32 v48, v84
	v_mov_b32_e32 v50, v60
	v_mov_b32_e32 v28, v66
	v_mov_b32_e32 v32, v96
	v_mov_b32_e32 v12, v88
	v_mov_b32_e32 v16, v92
	v_mov_b32_e32 v4, v138
	v_mov_b32_e32 v6, v122

.LBB0_503:
	s_or_b64 exec, exec, s[0:1]
	v_pk_mul_f32 v[22:23], v[32:33], s[6:7] op_sel_hi:[1,0]
	v_pk_add_f32 v[26:27], v[24:25], v[30:31]
	v_pk_add_f32 v[24:25], v[24:25], v[30:31] neg_lo:[0,1] neg_hi:[0,1]
	v_pk_add_f32 v[30:31], v[64:65], v[68:69]
	v_pk_add_f32 v[32:33], v[64:65], v[68:69] neg_lo:[0,1] neg_hi:[0,1]
	v_pk_add_f32 v[34:35], v[62:63], v[90:91]
	v_pk_add_f32 v[38:39], v[94:95], v[80:81]
	v_pk_add_f32 v[40:41], v[94:95], v[80:81] neg_lo:[0,1] neg_hi:[0,1]
	v_pk_add_f32 v[68:69], v[26:27], v[30:31]
	v_pk_add_f32 v[26:27], v[26:27], v[30:31] neg_lo:[0,1] neg_hi:[0,1]
	v_xor_b32_e32 v30, 0x80000000, v33
	v_mov_b32_e32 v31, v32
	v_pk_mul_f32 v[20:21], v[50:51], s[6:7] op_sel_hi:[1,0]
	v_pk_add_f32 v[36:37], v[62:63], v[90:91] neg_lo:[0,1] neg_hi:[0,1]
	v_pk_add_f32 v[42:43], v[78:79], v[136:137]
	v_pk_add_f32 v[46:47], v[130:131], v[120:121]
	v_pk_add_f32 v[50:51], v[130:131], v[120:121] neg_lo:[0,1] neg_hi:[0,1]
	v_pk_add_f32 v[32:33], v[24:25], v[30:31]
	v_pk_add_f32 v[24:25], v[24:25], v[30:31] neg_lo:[0,1] neg_hi:[0,1]
	v_pk_add_f32 v[30:31], v[34:35], v[38:39]
	v_pk_add_f32 v[34:35], v[34:35], v[38:39] neg_lo:[0,1] neg_hi:[0,1]
	v_xor_b32_e32 v38, 0x80000000, v41
	v_mov_b32_e32 v39, v40
	v_pk_add_f32 v[44:45], v[78:79], v[136:137] neg_lo:[0,1] neg_hi:[0,1]
	v_pk_add_f32 v[60:61], v[128:129], v[150:151]
	v_pk_add_f32 v[64:65], v[168:169], v[144:145]
	v_pk_add_f32 v[66:67], v[168:169], v[144:145] neg_lo:[0,1] neg_hi:[0,1]
	v_pk_add_f32 v[40:41], v[36:37], v[38:39]
	v_pk_add_f32 v[36:37], v[36:37], v[38:39] neg_lo:[0,1] neg_hi:[0,1]
	v_pk_add_f32 v[38:39], v[42:43], v[46:47]
	v_pk_add_f32 v[42:43], v[42:43], v[46:47] neg_lo:[0,1] neg_hi:[0,1]
	v_xor_b32_e32 v46, 0x80000000, v51
	v_mov_b32_e32 v47, v50
	v_pk_add_f32 v[62:63], v[128:129], v[150:151] neg_lo:[0,1] neg_hi:[0,1]
	v_pk_add_f32 v[50:51], v[44:45], v[46:47]
	v_pk_add_f32 v[44:45], v[44:45], v[46:47] neg_lo:[0,1] neg_hi:[0,1]
	v_pk_add_f32 v[46:47], v[60:61], v[64:65]
	v_pk_add_f32 v[60:61], v[60:61], v[64:65] neg_lo:[0,1] neg_hi:[0,1]
	v_xor_b32_e32 v64, 0x80000000, v67
	v_mov_b32_e32 v65, v66
	s_mov_b32 s78, s37
	s_mov_b32 s79, s36
	v_pk_add_f32 v[66:67], v[62:63], v[64:65]
	v_pk_add_f32 v[62:63], v[62:63], v[64:65] neg_lo:[0,1] neg_hi:[0,1]
	v_pk_add_f32 v[64:65], v[68:69], v[30:31]
	v_pk_add_f32 v[30:31], v[68:69], v[30:31] neg_lo:[0,1] neg_hi:[0,1]
	s_mov_b32 s0, s37
	v_pk_mul_f32 v[68:69], v[40:41], s[78:79]
	s_mov_b32 s80, s19
	v_pk_fma_f32 v[40:41], v[40:41], s[0:1], v[68:69] op_sel:[0,0,1] op_sel_hi:[1,0,0]
	s_mov_b32 s81, s18
	v_pk_add_f32 v[68:69], v[32:33], v[40:41]
	v_pk_add_f32 v[32:33], v[32:33], v[40:41] neg_lo:[0,1] neg_hi:[0,1]
	v_xor_b32_e32 v40, 0x80000000, v35
	v_mov_b32_e32 v41, v34
	v_pk_add_f32 v[34:35], v[26:27], v[40:41]
	v_pk_add_f32 v[26:27], v[26:27], v[40:41] neg_lo:[0,1] neg_hi:[0,1]
	v_pk_mul_f32 v[40:41], v[36:37], s[78:79]
	s_mov_b32 s82, s19
	v_pk_fma_f32 v[36:37], v[36:37], s[0:1], v[40:41] op_sel:[0,0,1] op_sel_hi:[1,0,0] neg_lo:[1,0,0] neg_hi:[1,0,0]
	v_pk_mul_f32 v[2:3], v[72:73], s[6:7] op_sel_hi:[1,0]
	v_pk_add_f32 v[40:41], v[24:25], v[36:37]
	v_pk_add_f32 v[24:25], v[24:25], v[36:37] neg_lo:[0,1] neg_hi:[0,1]
	v_pk_add_f32 v[36:37], v[38:39], v[46:47]
	v_pk_add_f32 v[38:39], v[38:39], v[46:47] neg_lo:[0,1] neg_hi:[0,1]
	v_pk_mul_f32 v[46:47], v[66:67], s[78:79]
	v_pk_mul_f32 v[8:9], v[70:71], s[6:7] op_sel_hi:[1,0]
	v_pk_fma_f32 v[46:47], v[66:67], s[0:1], v[46:47] op_sel:[0,0,1] op_sel_hi:[1,0,0]
	v_pk_mul_f32 v[10:11], v[76:77], s[6:7] op_sel_hi:[1,0]
	v_pk_add_f32 v[66:67], v[50:51], v[46:47]
	v_pk_add_f32 v[46:47], v[50:51], v[46:47] neg_lo:[0,1] neg_hi:[0,1]
	v_xor_b32_e32 v50, 0x80000000, v61
	v_mov_b32_e32 v51, v60
	v_pk_add_f32 v[60:61], v[42:43], v[50:51]
	v_pk_add_f32 v[42:43], v[42:43], v[50:51] neg_lo:[0,1] neg_hi:[0,1]
	v_pk_mul_f32 v[50:51], v[62:63], s[78:79]
	v_pk_mul_f32 v[14:15], v[74:75], s[6:7] op_sel_hi:[1,0]
	v_pk_fma_f32 v[50:51], v[62:63], s[0:1], v[50:51] op_sel:[0,0,1] op_sel_hi:[1,0,0] neg_lo:[1,0,0] neg_hi:[1,0,0]
	v_pk_mul_f32 v[16:17], v[16:17], s[6:7] op_sel_hi:[1,0]
	v_pk_add_f32 v[62:63], v[44:45], v[50:51]
	v_pk_add_f32 v[44:45], v[44:45], v[50:51] neg_lo:[0,1] neg_hi:[0,1]
	v_pk_add_f32 v[50:51], v[64:65], v[36:37]
	v_pk_add_f32 v[36:37], v[64:65], v[36:37] neg_lo:[0,1] neg_hi:[0,1]
	v_pk_mul_f32 v[64:65], v[66:67], s[80:81]
	v_pk_mul_f32 v[6:7], v[6:7], s[6:7] op_sel_hi:[1,0]
	v_pk_fma_f32 v[64:65], v[66:67], s[16:17], v[64:65] op_sel:[0,0,1] op_sel_hi:[1,0,0]
	s_mov_b32 s17, s40
	v_pk_add_f32 v[66:67], v[68:69], v[64:65]
	v_pk_add_f32 v[64:65], v[68:69], v[64:65] neg_lo:[0,1] neg_hi:[0,1]
	v_pk_mul_f32 v[68:69], v[60:61], s[78:79]
	s_mov_b32 s88, s11
	v_pk_fma_f32 v[60:61], v[60:61], s[0:1], v[68:69] op_sel:[0,0,1] op_sel_hi:[1,0,0]
	s_mov_b32 s89, s10
	v_pk_add_f32 v[68:69], v[34:35], v[60:61]
	v_pk_add_f32 v[34:35], v[34:35], v[60:61] neg_lo:[0,1] neg_hi:[0,1]
	v_pk_mul_f32 v[60:61], v[62:63], s[16:17]
	s_mov_b32 s62, s27
	v_pk_fma_f32 v[60:61], v[62:63], s[82:83], v[60:61] op_sel:[0,0,1] op_sel_hi:[1,0,0]
	s_mov_b32 s63, s26
	v_pk_add_f32 v[62:63], v[40:41], v[60:61]
	v_pk_add_f32 v[40:41], v[40:41], v[60:61] neg_lo:[0,1] neg_hi:[0,1]
	v_xor_b32_e32 v60, 0x80000000, v39
	v_mov_b32_e32 v61, v38
	v_pk_add_f32 v[38:39], v[30:31], v[60:61]
	v_pk_add_f32 v[30:31], v[30:31], v[60:61] neg_lo:[0,1] neg_hi:[0,1]
	v_pk_mul_f32 v[60:61], v[46:47], s[16:17]
	s_mov_b32 s84, s27
	v_pk_fma_f32 v[46:47], v[46:47], s[82:83], v[60:61] op_sel:[0,0,1] op_sel_hi:[1,0,0] neg_lo:[1,0,0] neg_hi:[1,0,0]
	s_mov_b32 s86, s11
	v_pk_add_f32 v[60:61], v[32:33], v[46:47]
	v_pk_add_f32 v[32:33], v[32:33], v[46:47] neg_lo:[0,1] neg_hi:[0,1]
	v_pk_mul_f32 v[46:47], v[42:43], s[78:79]
	s_ashr_i32 s73, s72, 31
	v_pk_fma_f32 v[42:43], s[0:1], v[42:43], v[46:47] op_sel:[0,0,1] op_sel_hi:[0,1,0] neg_lo:[0,1,0] neg_hi:[0,1,0]
	v_pk_add_f32 v[46:47], v[26:27], v[42:43]
	v_pk_add_f32 v[26:27], v[26:27], v[42:43] neg_lo:[0,1] neg_hi:[0,1]
	v_pk_mul_f32 v[42:43], v[44:45], s[80:81] op_sel:[1,1] op_sel_hi:[0,0]
	v_pk_fma_f32 v[42:43], s[16:17], v[44:45], v[42:43] op_sel_hi:[0,1,1] neg_lo:[0,1,0] neg_hi:[0,1,0]
	v_pk_add_f32 v[44:45], v[24:25], v[42:43]
	v_pk_add_f32 v[24:25], v[24:25], v[42:43] neg_lo:[0,1] neg_hi:[0,1]
	v_pk_fma_f32 v[42:43], v[58:59], s[6:7], v[2:3] op_sel_hi:[1,0,1]
	v_pk_fma_f32 v[2:3], v[58:59], s[6:7], v[2:3] op_sel_hi:[1,0,1] neg_lo:[0,0,1] neg_hi:[0,0,1]
	v_pk_fma_f32 v[58:59], v[54:55], s[6:7], v[8:9] op_sel_hi:[1,0,1]
	v_pk_fma_f32 v[8:9], v[54:55], s[6:7], v[8:9] op_sel_hi:[1,0,1] neg_lo:[0,0,1] neg_hi:[0,0,1]
	v_pk_fma_f32 v[54:55], v[56:57], s[6:7], v[10:11] op_sel_hi:[1,0,1]
	v_pk_fma_f32 v[10:11], v[56:57], s[6:7], v[10:11] op_sel_hi:[1,0,1] neg_lo:[0,0,1] neg_hi:[0,0,1]
	v_pk_fma_f32 v[56:57], v[52:53], s[6:7], v[14:15] op_sel_hi:[1,0,1]
	v_pk_fma_f32 v[14:15], v[52:53], s[6:7], v[14:15] op_sel_hi:[1,0,1] neg_lo:[0,0,1] neg_hi:[0,0,1]
	v_pk_fma_f32 v[52:53], v[48:49], s[6:7], v[20:21] op_sel_hi:[1,0,1]
	v_pk_fma_f32 v[20:21], v[48:49], s[6:7], v[20:21] op_sel_hi:[1,0,1] neg_lo:[0,0,1] neg_hi:[0,0,1]
	v_pk_fma_f32 v[48:49], v[28:29], s[6:7], v[22:23] op_sel_hi:[1,0,1]
	v_pk_fma_f32 v[22:23], v[28:29], s[6:7], v[22:23] op_sel_hi:[1,0,1] neg_lo:[0,0,1] neg_hi:[0,0,1]
	v_pk_fma_f32 v[28:29], v[12:13], s[6:7], v[16:17] op_sel_hi:[1,0,1]
	v_pk_fma_f32 v[12:13], v[12:13], s[6:7], v[16:17] op_sel_hi:[1,0,1] neg_lo:[0,0,1] neg_hi:[0,0,1]
	v_pk_fma_f32 v[16:17], v[4:5], s[6:7], v[6:7] op_sel_hi:[1,0,1]
	v_pk_fma_f32 v[4:5], v[4:5], s[6:7], v[6:7] op_sel_hi:[1,0,1] neg_lo:[0,0,1] neg_hi:[0,0,1]
	v_pk_add_f32 v[6:7], v[58:59], v[42:43]
	v_pk_add_f32 v[42:43], v[42:43], v[58:59] neg_lo:[0,1] neg_hi:[0,1]
	v_xor_b32_e32 v58, 0x80000000, v9
	v_mov_b32_e32 v59, v8
	v_pk_add_f32 v[8:9], v[2:3], v[58:59]
	v_pk_add_f32 v[2:3], v[2:3], v[58:59] neg_lo:[0,1] neg_hi:[0,1]
	v_pk_add_f32 v[58:59], v[56:57], v[54:55]
	v_pk_add_f32 v[54:55], v[54:55], v[56:57] neg_lo:[0,1] neg_hi:[0,1]
	v_xor_b32_e32 v56, 0x80000000, v15
	v_mov_b32_e32 v57, v14
	v_pk_add_f32 v[14:15], v[10:11], v[56:57]
	v_pk_add_f32 v[10:11], v[10:11], v[56:57] neg_lo:[0,1] neg_hi:[0,1]
	v_pk_add_f32 v[56:57], v[48:49], v[52:53]
	v_pk_add_f32 v[48:49], v[52:53], v[48:49] neg_lo:[0,1] neg_hi:[0,1]
	v_xor_b32_e32 v52, 0x80000000, v23
	v_mov_b32_e32 v53, v22
	v_pk_add_f32 v[22:23], v[20:21], v[52:53]
	v_pk_add_f32 v[20:21], v[20:21], v[52:53] neg_lo:[0,1] neg_hi:[0,1]
	v_pk_add_f32 v[52:53], v[16:17], v[28:29]
	v_pk_add_f32 v[16:17], v[28:29], v[16:17] neg_lo:[0,1] neg_hi:[0,1]
	v_xor_b32_e32 v28, 0x80000000, v5
	v_mov_b32_e32 v29, v4
	v_pk_add_f32 v[4:5], v[12:13], v[28:29]
	v_pk_add_f32 v[12:13], v[12:13], v[28:29] neg_lo:[0,1] neg_hi:[0,1]
	v_pk_add_f32 v[28:29], v[58:59], v[6:7]
	v_pk_add_f32 v[6:7], v[6:7], v[58:59] neg_lo:[0,1] neg_hi:[0,1]
	v_pk_mul_f32 v[58:59], v[14:15], s[78:79] op_sel:[1,1] op_sel_hi:[0,0]
	v_pk_fma_f32 v[14:15], s[0:1], v[14:15], v[58:59] op_sel_hi:[0,1,1]
	v_pk_add_f32 v[58:59], v[14:15], v[8:9]
	v_pk_add_f32 v[8:9], v[8:9], v[14:15] neg_lo:[0,1] neg_hi:[0,1]
	v_xor_b32_e32 v14, 0x80000000, v55
	v_mov_b32_e32 v15, v54
	v_pk_add_f32 v[54:55], v[14:15], v[42:43]
	v_pk_add_f32 v[14:15], v[42:43], v[14:15] neg_lo:[0,1] neg_hi:[0,1]
	v_pk_mul_f32 v[42:43], v[10:11], s[78:79] op_sel:[1,1] op_sel_hi:[0,0]
	v_pk_fma_f32 v[10:11], s[0:1], v[10:11], v[42:43] op_sel_hi:[0,1,1] neg_lo:[0,1,0] neg_hi:[0,1,0]
	v_pk_add_f32 v[42:43], v[10:11], v[2:3]
	v_pk_add_f32 v[2:3], v[2:3], v[10:11] neg_lo:[0,1] neg_hi:[0,1]
	v_pk_add_f32 v[10:11], v[52:53], v[56:57]
	v_pk_add_f32 v[52:53], v[56:57], v[52:53] neg_lo:[0,1] neg_hi:[0,1]
	v_pk_mul_f32 v[56:57], v[4:5], s[78:79] op_sel:[1,1] op_sel_hi:[0,0]
	v_pk_fma_f32 v[4:5], s[0:1], v[4:5], v[56:57] op_sel_hi:[0,1,1]
	v_pk_add_f32 v[56:57], v[4:5], v[22:23]
	v_pk_add_f32 v[4:5], v[22:23], v[4:5] neg_lo:[0,1] neg_hi:[0,1]
	v_xor_b32_e32 v22, 0x80000000, v17
	v_mov_b32_e32 v23, v16
	v_pk_add_f32 v[16:17], v[22:23], v[48:49]
	v_pk_add_f32 v[22:23], v[48:49], v[22:23] neg_lo:[0,1] neg_hi:[0,1]
	v_pk_mul_f32 v[48:49], v[12:13], s[78:79] op_sel:[1,1] op_sel_hi:[0,0]
	v_pk_fma_f32 v[12:13], s[0:1], v[12:13], v[48:49] op_sel_hi:[0,1,1] neg_lo:[0,1,0] neg_hi:[0,1,0]
	v_pk_add_f32 v[48:49], v[12:13], v[20:21]
	v_pk_add_f32 v[12:13], v[20:21], v[12:13] neg_lo:[0,1] neg_hi:[0,1]
	v_pk_add_f32 v[20:21], v[10:11], v[28:29]
	v_pk_add_f32 v[10:11], v[28:29], v[10:11] neg_lo:[0,1] neg_hi:[0,1]
	v_pk_mul_f32 v[28:29], v[56:57], s[80:81] op_sel:[1,1] op_sel_hi:[0,0]
	v_pk_fma_f32 v[28:29], s[16:17], v[56:57], v[28:29] op_sel_hi:[0,1,1]
	v_pk_add_f32 v[56:57], v[28:29], v[58:59]
	v_pk_add_f32 v[28:29], v[58:59], v[28:29] neg_lo:[0,1] neg_hi:[0,1]
	v_pk_mul_f32 v[58:59], v[16:17], s[78:79] op_sel:[1,1] op_sel_hi:[0,0]
	v_pk_fma_f32 v[16:17], s[0:1], v[16:17], v[58:59] op_sel_hi:[0,1,1]
	v_pk_add_f32 v[58:59], v[16:17], v[54:55]
	v_pk_add_f32 v[16:17], v[54:55], v[16:17] neg_lo:[0,1] neg_hi:[0,1]
	v_pk_mul_f32 v[54:55], v[48:49], s[16:17] op_sel:[1,1] op_sel_hi:[0,0]
	v_pk_fma_f32 v[48:49], s[82:83], v[48:49], v[54:55] op_sel_hi:[0,1,1]
	v_pk_add_f32 v[54:55], v[48:49], v[42:43]
	v_pk_add_f32 v[42:43], v[42:43], v[48:49] neg_lo:[0,1] neg_hi:[0,1]
	v_xor_b32_e32 v48, 0x80000000, v53
	v_mov_b32_e32 v49, v52
	v_pk_add_f32 v[52:53], v[48:49], v[6:7]
	v_pk_add_f32 v[6:7], v[6:7], v[48:49] neg_lo:[0,1] neg_hi:[0,1]
	v_pk_mul_f32 v[48:49], v[4:5], s[16:17] op_sel:[1,1] op_sel_hi:[0,0]
	v_pk_fma_f32 v[4:5], s[82:83], v[4:5], v[48:49] op_sel_hi:[0,1,1] neg_lo:[0,1,0] neg_hi:[0,1,0]
	v_pk_add_f32 v[48:49], v[4:5], v[8:9]
	v_pk_add_f32 v[4:5], v[8:9], v[4:5] neg_lo:[0,1] neg_hi:[0,1]
	v_pk_mul_f32 v[8:9], v[22:23], s[78:79] op_sel:[1,1] op_sel_hi:[0,0]
	v_pk_fma_f32 v[8:9], s[0:1], v[22:23], v[8:9] op_sel_hi:[0,1,1] neg_lo:[0,1,0] neg_hi:[0,1,0]
	v_pk_add_f32 v[22:23], v[8:9], v[14:15]
	v_pk_add_f32 v[8:9], v[14:15], v[8:9] neg_lo:[0,1] neg_hi:[0,1]
	v_pk_mul_f32 v[14:15], v[12:13], s[80:81] op_sel:[1,1] op_sel_hi:[0,0]
	v_pk_fma_f32 v[12:13], s[16:17], v[12:13], v[14:15] op_sel_hi:[0,1,1] neg_lo:[0,1,0] neg_hi:[0,1,0]
	v_pk_add_f32 v[14:15], v[12:13], v[2:3]
	v_pk_add_f32 v[2:3], v[2:3], v[12:13] neg_lo:[0,1] neg_hi:[0,1]
	ds_write_b64 v211, v[50:51]
	ds_write_b64 v212, v[20:21]
	ds_write_b64 v211, v[66:67] offset:8
	ds_write_b64 v212, v[56:57] offset:8
	ds_write_b64 v211, v[68:69] offset:16
	ds_write_b64 v212, v[58:59] offset:16
	ds_write_b64 v211, v[62:63] offset:24
	ds_write_b64 v212, v[54:55] offset:24
	ds_write_b64 v211, v[38:39] offset:32
	ds_write_b64 v212, v[52:53] offset:32
	ds_write_b64 v211, v[60:61] offset:40
	ds_write_b64 v212, v[48:49] offset:40
	ds_write_b64 v211, v[46:47] offset:48
	ds_write_b64 v212, v[22:23] offset:48
	ds_write_b64 v211, v[44:45] offset:56
	ds_write_b64 v212, v[14:15] offset:56
	ds_write_b64 v211, v[36:37] offset:64
	ds_write_b64 v212, v[10:11] offset:64
	ds_write_b64 v211, v[64:65] offset:72
	ds_write_b64 v212, v[28:29] offset:72
	ds_write_b64 v211, v[34:35] offset:80
	ds_write_b64 v212, v[16:17] offset:80
	ds_write_b64 v211, v[40:41] offset:88
	ds_write_b64 v212, v[42:43] offset:88
	ds_write_b64 v211, v[30:31] offset:96
	ds_write_b64 v212, v[6:7] offset:96
	ds_write_b64 v211, v[32:33] offset:104
	ds_write_b64 v212, v[4:5] offset:104
	ds_write_b64 v211, v[26:27] offset:112
	ds_write_b64 v212, v[8:9] offset:112
	ds_write_b64 v211, v[24:25] offset:120
	ds_write_b64 v212, v[2:3] offset:120
	v_mov_b32_e32 v2, v210
	s_waitcnt lgkmcnt(0)
	s_barrier
	s_nop 0
	v_and_b32_e32 v3, 15, v2
	v_lshlrev_b32_e32 v5, 3, v3
	v_cvt_f32_ubyte0_e32 v3, v3
	v_mul_f32_e32 v3, 0x3b000000, v3
	v_sin_f32_e32 v17, v3
	v_cos_f32_e32 v16, v3
	v_lshlrev_b32_e32 v2, 5, v2
	v_and_b32_e32 v2, 0xfffffe00, v2
	v_lshl_add_u32 v4, v2, 3, 0
	v_ashrrev_i32_e32 v2, 2, v2
	v_xor_b32_e32 v72, 0x80000000, v17
	v_mov_b32_e32 v73, v17
	v_add3_u32 v2, v4, v5, v2
	v_pk_mul_f32 v[4:5], v[16:17], v[72:73] op_sel:[1,0] op_sel_hi:[0,1]
	v_pk_fma_f32 v[74:75], v[16:17], v[16:17], v[4:5] op_sel_hi:[1,0,1]
	v_add_u32_e32 v3, 0x800, v2
	v_pk_mul_f32 v[4:5], v[72:73], v[74:75] op_sel:[0,1] op_sel_hi:[1,0]
	v_xor_b32_e32 v78, 0x80000000, v75
	v_mov_b32_e32 v79, v75
	v_pk_fma_f32 v[76:77], v[16:17], v[74:75], v[4:5] op_sel_hi:[0,1,1]
	v_pk_mul_f32 v[4:5], v[74:75], v[78:79] op_sel:[1,0] op_sel_hi:[0,1]
	v_pk_fma_f32 v[80:81], v[74:75], v[74:75], v[4:5] op_sel_hi:[1,0,1]
	v_xor_b32_e32 v84, 0x80000000, v77
	v_pk_mul_f32 v[4:5], v[72:73], v[80:81] op_sel:[0,1] op_sel_hi:[1,0]
	v_mov_b32_e32 v85, v77
	v_pk_fma_f32 v[86:87], v[16:17], v[80:81], v[4:5] op_sel_hi:[0,1,1]
	v_pk_mul_f32 v[4:5], v[78:79], v[80:81] op_sel:[0,1] op_sel_hi:[1,0]
	v_xor_b32_e32 v82, 0x80000000, v81
	v_mov_b32_e32 v83, v81
	v_pk_fma_f32 v[90:91], v[74:75], v[80:81], v[4:5] op_sel_hi:[0,1,1]
	v_pk_mul_f32 v[4:5], v[80:81], v[84:85] op_sel:[1,0] op_sel_hi:[0,1]
	v_pk_fma_f32 v[94:95], v[80:81], v[76:77], v[4:5] op_sel_hi:[1,0,1]
	v_pk_mul_f32 v[4:5], v[80:81], v[82:83] op_sel:[1,0] op_sel_hi:[0,1]
	v_pk_fma_f32 v[98:99], v[80:81], v[80:81], v[4:5] op_sel_hi:[1,0,1]
	v_xor_b32_e32 v88, 0x80000000, v87
	v_pk_mul_f32 v[4:5], v[72:73], v[98:99] op_sel:[0,1] op_sel_hi:[1,0]
	v_mov_b32_e32 v89, v87
	v_pk_fma_f32 v[102:103], v[16:17], v[98:99], v[4:5] op_sel_hi:[0,1,1]
	v_pk_mul_f32 v[4:5], v[78:79], v[98:99] op_sel:[0,1] op_sel_hi:[1,0]
	v_xor_b32_e32 v92, 0x80000000, v91
	v_pk_fma_f32 v[106:107], v[74:75], v[98:99], v[4:5] op_sel_hi:[0,1,1]
	v_pk_mul_f32 v[4:5], v[84:85], v[98:99] op_sel:[0,1] op_sel_hi:[1,0]
	v_mov_b32_e32 v93, v91
	v_pk_fma_f32 v[110:111], v[76:77], v[98:99], v[4:5] op_sel_hi:[0,1,1]
	v_pk_mul_f32 v[4:5], v[82:83], v[98:99] op_sel:[0,1] op_sel_hi:[1,0]
	v_xor_b32_e32 v96, 0x80000000, v95
	v_pk_fma_f32 v[114:115], v[80:81], v[98:99], v[4:5] op_sel_hi:[0,1,1]
	v_pk_mul_f32 v[4:5], v[72:73], v[114:115] op_sel:[0,1] op_sel_hi:[1,0]
	v_mov_b32_e32 v97, v95
	v_pk_fma_f32 v[118:119], v[16:17], v[114:115], v[4:5] op_sel_hi:[0,1,1]
	v_pk_mul_f32 v[4:5], v[78:79], v[114:115] op_sel:[0,1] op_sel_hi:[1,0]
	v_xor_b32_e32 v100, 0x80000000, v99
	v_pk_fma_f32 v[122:123], v[74:75], v[114:115], v[4:5] op_sel_hi:[0,1,1]
	v_pk_mul_f32 v[4:5], v[84:85], v[114:115] op_sel:[0,1] op_sel_hi:[1,0]
	v_mov_b32_e32 v101, v99
	v_pk_fma_f32 v[126:127], v[76:77], v[114:115], v[4:5] op_sel_hi:[0,1,1]
	v_pk_mul_f32 v[4:5], v[82:83], v[114:115] op_sel:[0,1] op_sel_hi:[1,0]
	v_xor_b32_e32 v104, 0x80000000, v103
	v_pk_fma_f32 v[130:131], v[80:81], v[114:115], v[4:5] op_sel_hi:[0,1,1]
	v_pk_mul_f32 v[4:5], v[72:73], v[130:131] op_sel:[0,1] op_sel_hi:[1,0]
	v_mov_b32_e32 v105, v103
	v_pk_fma_f32 v[134:135], v[16:17], v[130:131], v[4:5] op_sel_hi:[0,1,1]
	v_pk_mul_f32 v[4:5], v[78:79], v[130:131] op_sel:[0,1] op_sel_hi:[1,0]
	v_xor_b32_e32 v108, 0x80000000, v107
	v_pk_fma_f32 v[138:139], v[74:75], v[130:131], v[4:5] op_sel_hi:[0,1,1]
	v_pk_mul_f32 v[4:5], v[84:85], v[130:131] op_sel:[0,1] op_sel_hi:[1,0]
	v_mov_b32_e32 v109, v107
	v_pk_fma_f32 v[142:143], v[76:77], v[130:131], v[4:5] op_sel_hi:[0,1,1]
	v_pk_mul_f32 v[4:5], v[82:83], v[130:131] op_sel:[0,1] op_sel_hi:[1,0]
	v_xor_b32_e32 v112, 0x80000000, v111
	v_pk_fma_f32 v[148:149], v[80:81], v[130:131], v[4:5] op_sel_hi:[0,1,1]
	v_pk_mul_f32 v[4:5], v[72:73], v[148:149] op_sel:[0,1] op_sel_hi:[1,0]
	v_mov_b32_e32 v113, v111
	v_pk_fma_f32 v[152:153], v[16:17], v[148:149], v[4:5] op_sel_hi:[0,1,1]
	v_pk_mul_f32 v[4:5], v[78:79], v[148:149] op_sel:[0,1] op_sel_hi:[1,0]
	v_xor_b32_e32 v116, 0x80000000, v115
	v_pk_fma_f32 v[156:157], v[74:75], v[148:149], v[4:5] op_sel_hi:[0,1,1]
	v_pk_mul_f32 v[4:5], v[84:85], v[148:149] op_sel:[0,1] op_sel_hi:[1,0]
	v_mov_b32_e32 v117, v115
	v_pk_fma_f32 v[160:161], v[76:77], v[148:149], v[4:5] op_sel_hi:[0,1,1]
	v_pk_mul_f32 v[4:5], v[82:83], v[148:149] op_sel:[0,1] op_sel_hi:[1,0]
	v_xor_b32_e32 v120, 0x80000000, v119
	v_pk_fma_f32 v[164:165], v[80:81], v[148:149], v[4:5] op_sel_hi:[0,1,1]
	v_pk_mul_f32 v[4:5], v[72:73], v[164:165] op_sel:[0,1] op_sel_hi:[1,0]
	v_mov_b32_e32 v121, v119
	v_pk_fma_f32 v[168:169], v[16:17], v[164:165], v[4:5] op_sel_hi:[0,1,1]
	v_pk_mul_f32 v[4:5], v[78:79], v[164:165] op_sel:[0,1] op_sel_hi:[1,0]
	v_xor_b32_e32 v124, 0x80000000, v123
	v_pk_fma_f32 v[172:173], v[74:75], v[164:165], v[4:5] op_sel_hi:[0,1,1]
	v_pk_mul_f32 v[4:5], v[84:85], v[164:165] op_sel:[0,1] op_sel_hi:[1,0]
	v_mov_b32_e32 v125, v123
	v_pk_fma_f32 v[176:177], v[76:77], v[164:165], v[4:5] op_sel_hi:[0,1,1]
	v_pk_mul_f32 v[4:5], v[82:83], v[164:165] op_sel:[0,1] op_sel_hi:[1,0]
	v_xor_b32_e32 v128, 0x80000000, v127
	v_pk_fma_f32 v[180:181], v[80:81], v[164:165], v[4:5] op_sel_hi:[0,1,1]
	v_pk_mul_f32 v[4:5], v[72:73], v[180:181] op_sel:[0,1] op_sel_hi:[1,0]
	v_mov_b32_e32 v129, v127
	v_pk_fma_f32 v[184:185], v[16:17], v[180:181], v[4:5] op_sel_hi:[0,1,1]
	v_pk_mul_f32 v[4:5], v[78:79], v[180:181] op_sel:[0,1] op_sel_hi:[1,0]
	v_xor_b32_e32 v132, 0x80000000, v131
	v_pk_fma_f32 v[188:189], v[74:75], v[180:181], v[4:5] op_sel_hi:[0,1,1]
	v_pk_mul_f32 v[4:5], v[84:85], v[180:181] op_sel:[0,1] op_sel_hi:[1,0]
	v_mov_b32_e32 v133, v131
	v_pk_fma_f32 v[192:193], v[76:77], v[180:181], v[4:5] op_sel_hi:[0,1,1]
	ds_read2_b64 v[4:7], v2 offset1:16
	ds_read2_b64 v[8:11], v2 offset0:33 offset1:49
	ds_read2_b64 v[12:15], v2 offset0:66 offset1:82
	ds_read2_b64 v[20:23], v2 offset0:99 offset1:115
	ds_read2_b64 v[24:27], v2 offset0:132 offset1:148
	ds_read2_b64 v[28:31], v2 offset0:165 offset1:181
	ds_read2_b64 v[32:35], v2 offset0:198 offset1:214
	ds_read2_b64 v[36:39], v2 offset0:231 offset1:247
	ds_read2_b64 v[40:43], v3 offset0:8 offset1:24
	ds_read2_b64 v[44:47], v3 offset0:41 offset1:57
	ds_read2_b64 v[48:51], v3 offset0:74 offset1:90
	ds_read2_b64 v[52:55], v3 offset0:107 offset1:123
	ds_read2_b64 v[56:59], v3 offset0:140 offset1:156
	ds_read2_b64 v[60:63], v3 offset0:173 offset1:189
	ds_read2_b64 v[64:67], v3 offset0:206 offset1:222
	ds_read2_b64 v[68:71], v3 offset0:239 offset1:255
	s_waitcnt lgkmcnt(7)
	v_pk_mul_f32 v[72:73], v[72:73], v[40:41] op_sel:[0,1] op_sel_hi:[1,0]
	v_xor_b32_e32 v136, 0x80000000, v135
	v_pk_fma_f32 v[16:17], v[16:17], v[40:41], v[72:73] op_sel_hi:[0,1,1]
	v_pk_mul_f32 v[40:41], v[24:25], v[78:79] op_sel:[1,0] op_sel_hi:[0,1]
	v_pk_fma_f32 v[24:25], v[24:25], v[74:75], v[40:41] op_sel_hi:[1,0,1]
	s_waitcnt lgkmcnt(3)
	v_pk_mul_f32 v[40:41], v[84:85], v[56:57] op_sel:[0,1] op_sel_hi:[1,0]
	v_mov_b32_e32 v137, v135
	v_pk_fma_f32 v[40:41], v[76:77], v[56:57], v[40:41] op_sel_hi:[0,1,1]
	v_pk_mul_f32 v[56:57], v[12:13], v[82:83] op_sel:[1,0] op_sel_hi:[0,1]
	v_pk_fma_f32 v[12:13], v[12:13], v[80:81], v[56:57] op_sel_hi:[1,0,1]
	v_pk_mul_f32 v[56:57], v[88:89], v[48:49] op_sel:[0,1] op_sel_hi:[1,0]
	v_xor_b32_e32 v140, 0x80000000, v139
	v_pk_fma_f32 v[48:49], v[86:87], v[48:49], v[56:57] op_sel_hi:[0,1,1]
	v_pk_mul_f32 v[56:57], v[32:33], v[92:93] op_sel:[1,0] op_sel_hi:[0,1]
	v_pk_fma_f32 v[32:33], v[32:33], v[90:91], v[56:57] op_sel_hi:[1,0,1]
	s_waitcnt lgkmcnt(1)
	v_pk_mul_f32 v[56:57], v[96:97], v[64:65] op_sel:[0,1] op_sel_hi:[1,0]
	v_mov_b32_e32 v141, v139
	v_pk_fma_f32 v[56:57], v[94:95], v[64:65], v[56:57] op_sel_hi:[0,1,1]
	v_pk_mul_f32 v[64:65], v[8:9], v[100:101] op_sel:[1,0] op_sel_hi:[0,1]
	v_pk_fma_f32 v[8:9], v[8:9], v[98:99], v[64:65] op_sel_hi:[1,0,1]
	v_pk_mul_f32 v[64:65], v[44:45], v[104:105] op_sel:[1,0] op_sel_hi:[0,1]
	v_pk_fma_f32 v[44:45], v[44:45], v[102:103], v[64:65] op_sel_hi:[1,0,1]
	v_pk_mul_f32 v[64:65], v[28:29], v[108:109] op_sel:[1,0] op_sel_hi:[0,1]
	v_pk_fma_f32 v[28:29], v[28:29], v[106:107], v[64:65] op_sel_hi:[1,0,1]
	v_pk_mul_f32 v[64:65], v[112:113], v[60:61] op_sel:[0,1] op_sel_hi:[1,0]
	v_xor_b32_e32 v144, 0x80000000, v143
	v_pk_fma_f32 v[60:61], v[110:111], v[60:61], v[64:65] op_sel_hi:[0,1,1]
	v_pk_mul_f32 v[64:65], v[20:21], v[116:117] op_sel:[1,0] op_sel_hi:[0,1]
	v_pk_fma_f32 v[20:21], v[20:21], v[114:115], v[64:65] op_sel_hi:[1,0,1]
	v_pk_mul_f32 v[64:65], v[52:53], v[120:121] op_sel:[1,0] op_sel_hi:[0,1]
	v_pk_fma_f32 v[52:53], v[52:53], v[118:119], v[64:65] op_sel_hi:[1,0,1]
	v_pk_mul_f32 v[64:65], v[36:37], v[124:125] op_sel:[1,0] op_sel_hi:[0,1]
	v_pk_fma_f32 v[36:37], v[36:37], v[122:123], v[64:65] op_sel_hi:[1,0,1]
	s_waitcnt lgkmcnt(0)
	v_pk_mul_f32 v[64:65], v[128:129], v[68:69] op_sel:[0,1] op_sel_hi:[1,0]
	v_mov_b32_e32 v145, v143
	v_pk_fma_f32 v[64:65], v[126:127], v[68:69], v[64:65] op_sel_hi:[0,1,1]
	v_pk_mul_f32 v[68:69], v[6:7], v[132:133] op_sel:[1,0] op_sel_hi:[0,1]
	v_pk_fma_f32 v[6:7], v[6:7], v[130:131], v[68:69] op_sel_hi:[1,0,1]
	v_pk_mul_f32 v[68:69], v[42:43], v[136:137] op_sel:[1,0] op_sel_hi:[0,1]
	v_pk_fma_f32 v[42:43], v[42:43], v[134:135], v[68:69] op_sel_hi:[1,0,1]
	v_pk_mul_f32 v[68:69], v[26:27], v[140:141] op_sel:[1,0] op_sel_hi:[0,1]
	v_xor_b32_e32 v150, 0x80000000, v149
	v_mov_b32_e32 v151, v149
	v_pk_fma_f32 v[26:27], v[26:27], v[138:139], v[68:69] op_sel_hi:[1,0,1]
	v_pk_mul_f32 v[68:69], v[58:59], v[144:145] op_sel:[1,0] op_sel_hi:[0,1]
	v_xor_b32_e32 v154, 0x80000000, v153
	v_mov_b32_e32 v155, v153
	v_pk_fma_f32 v[58:59], v[58:59], v[142:143], v[68:69] op_sel_hi:[1,0,1]
	v_pk_mul_f32 v[68:69], v[14:15], v[150:151] op_sel:[1,0] op_sel_hi:[0,1]
	v_xor_b32_e32 v158, 0x80000000, v157
	v_mov_b32_e32 v159, v157
	v_pk_fma_f32 v[14:15], v[14:15], v[148:149], v[68:69] op_sel_hi:[1,0,1]
	v_pk_mul_f32 v[68:69], v[50:51], v[154:155] op_sel:[1,0] op_sel_hi:[0,1]
	v_xor_b32_e32 v162, 0x80000000, v161
	v_mov_b32_e32 v163, v161
	v_pk_fma_f32 v[50:51], v[50:51], v[152:153], v[68:69] op_sel_hi:[1,0,1]
	v_pk_mul_f32 v[68:69], v[34:35], v[158:159] op_sel:[1,0] op_sel_hi:[0,1]
	v_xor_b32_e32 v166, 0x80000000, v165
	v_mov_b32_e32 v167, v165
	v_pk_fma_f32 v[34:35], v[34:35], v[156:157], v[68:69] op_sel_hi:[1,0,1]
	v_pk_mul_f32 v[68:69], v[162:163], v[66:67] op_sel:[0,1] op_sel_hi:[1,0]
	v_xor_b32_e32 v170, 0x80000000, v169
	v_mov_b32_e32 v171, v169
	v_pk_fma_f32 v[66:67], v[160:161], v[66:67], v[68:69] op_sel_hi:[0,1,1]
	v_pk_mul_f32 v[68:69], v[10:11], v[166:167] op_sel:[1,0] op_sel_hi:[0,1]
	v_xor_b32_e32 v174, 0x80000000, v173
	v_mov_b32_e32 v175, v173
	v_pk_fma_f32 v[10:11], v[10:11], v[164:165], v[68:69] op_sel_hi:[1,0,1]
	v_pk_mul_f32 v[68:69], v[46:47], v[170:171] op_sel:[1,0] op_sel_hi:[0,1]
	v_xor_b32_e32 v178, 0x80000000, v177
	v_mov_b32_e32 v179, v177
	v_pk_fma_f32 v[46:47], v[46:47], v[168:169], v[68:69] op_sel_hi:[1,0,1]
	v_pk_mul_f32 v[68:69], v[30:31], v[174:175] op_sel:[1,0] op_sel_hi:[0,1]
	v_xor_b32_e32 v182, 0x80000000, v181
	v_mov_b32_e32 v183, v181
	v_pk_fma_f32 v[30:31], v[30:31], v[172:173], v[68:69] op_sel_hi:[1,0,1]
	v_pk_mul_f32 v[68:69], v[62:63], v[178:179] op_sel:[1,0] op_sel_hi:[0,1]
	v_xor_b32_e32 v186, 0x80000000, v185
	v_mov_b32_e32 v187, v185
	v_pk_fma_f32 v[62:63], v[62:63], v[176:177], v[68:69] op_sel_hi:[1,0,1]
	v_pk_mul_f32 v[68:69], v[22:23], v[182:183] op_sel:[1,0] op_sel_hi:[0,1]
	v_xor_b32_e32 v190, 0x80000000, v189
	v_mov_b32_e32 v191, v189
	v_pk_fma_f32 v[22:23], v[22:23], v[180:181], v[68:69] op_sel_hi:[1,0,1]
	v_pk_mul_f32 v[68:69], v[54:55], v[186:187] op_sel:[1,0] op_sel_hi:[0,1]
	v_xor_b32_e32 v194, 0x80000000, v193
	v_mov_b32_e32 v195, v193
	v_pk_fma_f32 v[54:55], v[54:55], v[184:185], v[68:69] op_sel_hi:[1,0,1]
	v_pk_mul_f32 v[68:69], v[38:39], v[190:191] op_sel:[1,0] op_sel_hi:[0,1]
	v_pk_fma_f32 v[38:39], v[38:39], v[188:189], v[68:69] op_sel_hi:[1,0,1]
	v_pk_mul_f32 v[68:69], v[70:71], v[194:195] op_sel:[1,0] op_sel_hi:[0,1]
	v_pk_fma_f32 v[68:69], v[70:71], v[192:193], v[68:69] op_sel_hi:[1,0,1]
	v_pk_add_f32 v[70:71], v[4:5], v[6:7]
	v_pk_add_f32 v[4:5], v[4:5], v[6:7] neg_lo:[0,1] neg_hi:[0,1]
	v_pk_add_f32 v[6:7], v[8:9], v[10:11]
	v_pk_add_f32 v[8:9], v[8:9], v[10:11] neg_lo:[0,1] neg_hi:[0,1]
	v_pk_add_f32 v[10:11], v[12:13], v[14:15]
	v_pk_add_f32 v[12:13], v[12:13], v[14:15] neg_lo:[0,1] neg_hi:[0,1]
	v_pk_add_f32 v[14:15], v[20:21], v[22:23]
	v_pk_add_f32 v[20:21], v[20:21], v[22:23] neg_lo:[0,1] neg_hi:[0,1]
	v_pk_add_f32 v[22:23], v[24:25], v[26:27]
	v_pk_add_f32 v[24:25], v[24:25], v[26:27] neg_lo:[0,1] neg_hi:[0,1]
	v_pk_add_f32 v[26:27], v[28:29], v[30:31]
	v_pk_add_f32 v[28:29], v[28:29], v[30:31] neg_lo:[0,1] neg_hi:[0,1]
	v_pk_add_f32 v[30:31], v[32:33], v[34:35]
	v_pk_add_f32 v[32:33], v[32:33], v[34:35] neg_lo:[0,1] neg_hi:[0,1]
	v_pk_add_f32 v[34:35], v[36:37], v[38:39]
	v_pk_add_f32 v[36:37], v[36:37], v[38:39] neg_lo:[0,1] neg_hi:[0,1]
	v_pk_add_f32 v[38:39], v[16:17], v[42:43]
	v_pk_add_f32 v[16:17], v[16:17], v[42:43] neg_lo:[0,1] neg_hi:[0,1]
	v_pk_add_f32 v[42:43], v[44:45], v[46:47]
	v_pk_add_f32 v[44:45], v[44:45], v[46:47] neg_lo:[0,1] neg_hi:[0,1]
	v_pk_add_f32 v[46:47], v[48:49], v[50:51]
	v_pk_add_f32 v[48:49], v[48:49], v[50:51] neg_lo:[0,1] neg_hi:[0,1]
	v_pk_add_f32 v[50:51], v[52:53], v[54:55]
	v_pk_add_f32 v[52:53], v[52:53], v[54:55] neg_lo:[0,1] neg_hi:[0,1]
	v_pk_add_f32 v[54:55], v[40:41], v[58:59]
	v_pk_add_f32 v[40:41], v[40:41], v[58:59] neg_lo:[0,1] neg_hi:[0,1]
	v_pk_add_f32 v[58:59], v[60:61], v[62:63]
	v_pk_add_f32 v[60:61], v[60:61], v[62:63] neg_lo:[0,1] neg_hi:[0,1]
	v_pk_add_f32 v[62:63], v[56:57], v[66:67]
	v_pk_add_f32 v[56:57], v[56:57], v[66:67] neg_lo:[0,1] neg_hi:[0,1]
	v_pk_add_f32 v[66:67], v[64:65], v[68:69]
	v_pk_add_f32 v[64:65], v[64:65], v[68:69] neg_lo:[0,1] neg_hi:[0,1]
	v_pk_add_f32 v[68:69], v[70:71], v[6:7]
	v_pk_add_f32 v[6:7], v[70:71], v[6:7] neg_lo:[0,1] neg_hi:[0,1]
	v_xor_b32_e32 v70, 0x80000000, v9
	v_mov_b32_e32 v71, v8
	v_pk_add_f32 v[8:9], v[4:5], v[70:71]
	v_pk_add_f32 v[4:5], v[4:5], v[70:71] neg_lo:[0,1] neg_hi:[0,1]
	v_pk_add_f32 v[70:71], v[10:11], v[14:15]
	v_pk_add_f32 v[10:11], v[10:11], v[14:15] neg_lo:[0,1] neg_hi:[0,1]
	v_xor_b32_e32 v14, 0x80000000, v21
	v_mov_b32_e32 v15, v20
	v_pk_add_f32 v[20:21], v[12:13], v[14:15]
	v_pk_add_f32 v[12:13], v[12:13], v[14:15] neg_lo:[0,1] neg_hi:[0,1]
	v_pk_add_f32 v[14:15], v[22:23], v[26:27]
	v_pk_add_f32 v[22:23], v[22:23], v[26:27] neg_lo:[0,1] neg_hi:[0,1]
	v_xor_b32_e32 v26, 0x80000000, v29
	v_mov_b32_e32 v27, v28
	v_pk_add_f32 v[28:29], v[24:25], v[26:27]
	v_pk_add_f32 v[24:25], v[24:25], v[26:27] neg_lo:[0,1] neg_hi:[0,1]
	v_pk_add_f32 v[26:27], v[30:31], v[34:35]
	v_pk_add_f32 v[30:31], v[30:31], v[34:35] neg_lo:[0,1] neg_hi:[0,1]
	v_xor_b32_e32 v34, 0x80000000, v37
	v_mov_b32_e32 v35, v36
	v_pk_add_f32 v[36:37], v[32:33], v[34:35]
	v_pk_add_f32 v[32:33], v[32:33], v[34:35] neg_lo:[0,1] neg_hi:[0,1]
	v_pk_add_f32 v[34:35], v[38:39], v[42:43]
	v_pk_add_f32 v[38:39], v[38:39], v[42:43] neg_lo:[0,1] neg_hi:[0,1]
	v_xor_b32_e32 v42, 0x80000000, v45
	v_mov_b32_e32 v43, v44
	v_pk_add_f32 v[44:45], v[16:17], v[42:43]
	v_pk_add_f32 v[16:17], v[16:17], v[42:43] neg_lo:[0,1] neg_hi:[0,1]
	v_pk_add_f32 v[42:43], v[46:47], v[50:51]
	v_pk_add_f32 v[46:47], v[46:47], v[50:51] neg_lo:[0,1] neg_hi:[0,1]
	v_xor_b32_e32 v50, 0x80000000, v53
	v_mov_b32_e32 v51, v52
	v_pk_add_f32 v[52:53], v[48:49], v[50:51]
	v_pk_add_f32 v[48:49], v[48:49], v[50:51] neg_lo:[0,1] neg_hi:[0,1]
	v_pk_add_f32 v[50:51], v[54:55], v[58:59]
	v_pk_add_f32 v[54:55], v[54:55], v[58:59] neg_lo:[0,1] neg_hi:[0,1]
	v_xor_b32_e32 v58, 0x80000000, v61
	v_mov_b32_e32 v59, v60
	v_pk_add_f32 v[60:61], v[40:41], v[58:59]
	v_pk_add_f32 v[40:41], v[40:41], v[58:59] neg_lo:[0,1] neg_hi:[0,1]
	v_pk_add_f32 v[58:59], v[62:63], v[66:67]
	v_pk_add_f32 v[62:63], v[62:63], v[66:67] neg_lo:[0,1] neg_hi:[0,1]
	v_xor_b32_e32 v66, 0x80000000, v65
	v_mov_b32_e32 v67, v64
	v_pk_add_f32 v[64:65], v[56:57], v[66:67]
	v_pk_add_f32 v[56:57], v[56:57], v[66:67] neg_lo:[0,1] neg_hi:[0,1]
	v_pk_add_f32 v[66:67], v[68:69], v[70:71]
	v_pk_add_f32 v[68:69], v[68:69], v[70:71] neg_lo:[0,1] neg_hi:[0,1]
	v_pk_mul_f32 v[70:71], v[20:21], s[78:79] op_sel:[1,1] op_sel_hi:[0,0]
	v_pk_fma_f32 v[20:21], s[0:1], v[20:21], v[70:71] op_sel_hi:[0,1,1]
	v_pk_add_f32 v[70:71], v[8:9], v[20:21]
	v_pk_add_f32 v[8:9], v[8:9], v[20:21] neg_lo:[0,1] neg_hi:[0,1]
	v_xor_b32_e32 v20, 0x80000000, v11
	v_mov_b32_e32 v21, v10
	v_pk_add_f32 v[10:11], v[6:7], v[20:21]
	v_pk_add_f32 v[6:7], v[6:7], v[20:21] neg_lo:[0,1] neg_hi:[0,1]
	v_pk_mul_f32 v[20:21], v[12:13], s[78:79] op_sel:[1,1] op_sel_hi:[0,0]
	v_pk_fma_f32 v[12:13], s[0:1], v[12:13], v[20:21] op_sel_hi:[0,1,1] neg_lo:[0,1,0] neg_hi:[0,1,0]
	v_pk_add_f32 v[20:21], v[4:5], v[12:13]
	v_pk_add_f32 v[4:5], v[4:5], v[12:13] neg_lo:[0,1] neg_hi:[0,1]
	v_pk_add_f32 v[12:13], v[14:15], v[26:27]
	v_pk_add_f32 v[14:15], v[14:15], v[26:27] neg_lo:[0,1] neg_hi:[0,1]
	v_pk_mul_f32 v[26:27], v[36:37], s[78:79] op_sel:[1,1] op_sel_hi:[0,0]
	v_pk_fma_f32 v[26:27], s[0:1], v[36:37], v[26:27] op_sel_hi:[0,1,1]
	v_pk_add_f32 v[36:37], v[28:29], v[26:27]
	v_pk_add_f32 v[26:27], v[28:29], v[26:27] neg_lo:[0,1] neg_hi:[0,1]
	v_xor_b32_e32 v28, 0x80000000, v31
	v_mov_b32_e32 v29, v30
	v_pk_add_f32 v[30:31], v[22:23], v[28:29]
	v_pk_add_f32 v[22:23], v[22:23], v[28:29] neg_lo:[0,1] neg_hi:[0,1]
	v_pk_mul_f32 v[28:29], v[32:33], s[78:79] op_sel:[1,1] op_sel_hi:[0,0]
	v_pk_fma_f32 v[28:29], s[0:1], v[32:33], v[28:29] op_sel_hi:[0,1,1] neg_lo:[0,1,0] neg_hi:[0,1,0]
	v_pk_add_f32 v[32:33], v[24:25], v[28:29]
	v_pk_add_f32 v[24:25], v[24:25], v[28:29] neg_lo:[0,1] neg_hi:[0,1]
	v_pk_add_f32 v[28:29], v[34:35], v[42:43]
	v_pk_add_f32 v[34:35], v[34:35], v[42:43] neg_lo:[0,1] neg_hi:[0,1]
	v_pk_mul_f32 v[42:43], v[52:53], s[78:79] op_sel:[1,1] op_sel_hi:[0,0]
	v_pk_fma_f32 v[42:43], s[0:1], v[52:53], v[42:43] op_sel_hi:[0,1,1]
	v_pk_add_f32 v[52:53], v[44:45], v[42:43]
	v_pk_add_f32 v[42:43], v[44:45], v[42:43] neg_lo:[0,1] neg_hi:[0,1]
	v_xor_b32_e32 v44, 0x80000000, v47
	v_mov_b32_e32 v45, v46
	v_pk_add_f32 v[46:47], v[38:39], v[44:45]
	v_pk_add_f32 v[38:39], v[38:39], v[44:45] neg_lo:[0,1] neg_hi:[0,1]
	v_pk_mul_f32 v[44:45], v[48:49], s[78:79] op_sel:[1,1] op_sel_hi:[0,0]
	v_pk_fma_f32 v[44:45], s[0:1], v[48:49], v[44:45] op_sel_hi:[0,1,1] neg_lo:[0,1,0] neg_hi:[0,1,0]
	v_pk_add_f32 v[48:49], v[16:17], v[44:45]
	v_pk_add_f32 v[16:17], v[16:17], v[44:45] neg_lo:[0,1] neg_hi:[0,1]
	v_pk_add_f32 v[44:45], v[50:51], v[58:59]
	v_pk_add_f32 v[50:51], v[50:51], v[58:59] neg_lo:[0,1] neg_hi:[0,1]
	v_pk_mul_f32 v[58:59], v[64:65], s[78:79] op_sel:[1,1] op_sel_hi:[0,0]
	v_pk_fma_f32 v[58:59], s[0:1], v[64:65], v[58:59] op_sel_hi:[0,1,1]
	v_pk_add_f32 v[64:65], v[60:61], v[58:59]
	v_pk_add_f32 v[58:59], v[60:61], v[58:59] neg_lo:[0,1] neg_hi:[0,1]
	v_xor_b32_e32 v60, 0x80000000, v63
	v_mov_b32_e32 v61, v62
	v_pk_add_f32 v[62:63], v[54:55], v[60:61]
	v_pk_add_f32 v[54:55], v[54:55], v[60:61] neg_lo:[0,1] neg_hi:[0,1]
	v_pk_mul_f32 v[60:61], v[56:57], s[78:79] op_sel:[1,1] op_sel_hi:[0,0]
	v_pk_fma_f32 v[56:57], s[0:1], v[56:57], v[60:61] op_sel_hi:[0,1,1] neg_lo:[0,1,0] neg_hi:[0,1,0]
	v_pk_add_f32 v[60:61], v[40:41], v[56:57]
	v_pk_add_f32 v[40:41], v[40:41], v[56:57] neg_lo:[0,1] neg_hi:[0,1]
	v_pk_add_f32 v[56:57], v[66:67], v[12:13]
	v_pk_add_f32 v[12:13], v[66:67], v[12:13] neg_lo:[0,1] neg_hi:[0,1]
	v_pk_mul_f32 v[66:67], v[36:37], s[80:81] op_sel:[1,1] op_sel_hi:[0,0]
	v_pk_fma_f32 v[36:37], s[16:17], v[36:37], v[66:67] op_sel_hi:[0,1,1]
	v_pk_add_f32 v[66:67], v[70:71], v[36:37]
	v_pk_add_f32 v[36:37], v[70:71], v[36:37] neg_lo:[0,1] neg_hi:[0,1]
	v_pk_mul_f32 v[70:71], v[30:31], s[78:79] op_sel:[1,1] op_sel_hi:[0,0]
	v_pk_fma_f32 v[30:31], s[0:1], v[30:31], v[70:71] op_sel_hi:[0,1,1]
	v_pk_add_f32 v[70:71], v[10:11], v[30:31]
	v_pk_add_f32 v[10:11], v[10:11], v[30:31] neg_lo:[0,1] neg_hi:[0,1]
	v_pk_mul_f32 v[30:31], v[32:33], s[16:17] op_sel:[1,1] op_sel_hi:[0,0]
	v_pk_fma_f32 v[30:31], s[82:83], v[32:33], v[30:31] op_sel_hi:[0,1,1]
	v_pk_add_f32 v[32:33], v[20:21], v[30:31]
	v_pk_add_f32 v[20:21], v[20:21], v[30:31] neg_lo:[0,1] neg_hi:[0,1]
	v_xor_b32_e32 v30, 0x80000000, v15
	v_mov_b32_e32 v31, v14
	v_pk_add_f32 v[14:15], v[68:69], v[30:31]
	v_pk_add_f32 v[30:31], v[68:69], v[30:31] neg_lo:[0,1] neg_hi:[0,1]
	v_pk_mul_f32 v[68:69], v[26:27], s[16:17] op_sel:[1,1] op_sel_hi:[0,0]
	v_pk_fma_f32 v[26:27], s[82:83], v[26:27], v[68:69] op_sel_hi:[0,1,1] neg_lo:[0,1,0] neg_hi:[0,1,0]
	v_pk_add_f32 v[68:69], v[8:9], v[26:27]
	v_pk_add_f32 v[8:9], v[8:9], v[26:27] neg_lo:[0,1] neg_hi:[0,1]
	v_pk_mul_f32 v[26:27], v[22:23], s[78:79] op_sel:[1,1] op_sel_hi:[0,0]
	v_pk_fma_f32 v[22:23], s[0:1], v[22:23], v[26:27] op_sel_hi:[0,1,1] neg_lo:[0,1,0] neg_hi:[0,1,0]
	v_pk_add_f32 v[26:27], v[6:7], v[22:23]
	v_pk_add_f32 v[6:7], v[6:7], v[22:23] neg_lo:[0,1] neg_hi:[0,1]
	v_pk_mul_f32 v[22:23], v[24:25], s[80:81] op_sel:[1,1] op_sel_hi:[0,0]
	v_pk_fma_f32 v[22:23], s[16:17], v[24:25], v[22:23] op_sel_hi:[0,1,1] neg_lo:[0,1,0] neg_hi:[0,1,0]
	v_pk_add_f32 v[24:25], v[4:5], v[22:23]
	v_pk_add_f32 v[4:5], v[4:5], v[22:23] neg_lo:[0,1] neg_hi:[0,1]
	v_pk_add_f32 v[22:23], v[28:29], v[44:45]
	v_pk_add_f32 v[28:29], v[28:29], v[44:45] neg_lo:[0,1] neg_hi:[0,1]
	v_pk_mul_f32 v[44:45], v[64:65], s[80:81] op_sel:[1,1] op_sel_hi:[0,0]
	v_pk_fma_f32 v[44:45], s[16:17], v[64:65], v[44:45] op_sel_hi:[0,1,1]
	v_pk_add_f32 v[64:65], v[52:53], v[44:45]
	v_pk_add_f32 v[44:45], v[52:53], v[44:45] neg_lo:[0,1] neg_hi:[0,1]
	v_pk_mul_f32 v[52:53], v[62:63], s[78:79] op_sel:[1,1] op_sel_hi:[0,0]
	v_pk_fma_f32 v[52:53], s[0:1], v[62:63], v[52:53] op_sel_hi:[0,1,1]
	v_pk_add_f32 v[62:63], v[46:47], v[52:53]
	v_pk_add_f32 v[46:47], v[46:47], v[52:53] neg_lo:[0,1] neg_hi:[0,1]
	v_pk_mul_f32 v[52:53], v[60:61], s[16:17] op_sel:[1,1] op_sel_hi:[0,0]
	v_pk_fma_f32 v[52:53], s[82:83], v[60:61], v[52:53] op_sel_hi:[0,1,1]
	v_pk_add_f32 v[60:61], v[48:49], v[52:53]
	v_pk_add_f32 v[48:49], v[48:49], v[52:53] neg_lo:[0,1] neg_hi:[0,1]
	v_xor_b32_e32 v52, 0x80000000, v51
	v_mov_b32_e32 v53, v50
	v_pk_add_f32 v[50:51], v[34:35], v[52:53]
	v_pk_add_f32 v[34:35], v[34:35], v[52:53] neg_lo:[0,1] neg_hi:[0,1]
	v_pk_mul_f32 v[52:53], v[58:59], s[16:17] op_sel:[1,1] op_sel_hi:[0,0]
	v_pk_fma_f32 v[52:53], s[82:83], v[58:59], v[52:53] op_sel_hi:[0,1,1] neg_lo:[0,1,0] neg_hi:[0,1,0]
	v_pk_add_f32 v[58:59], v[42:43], v[52:53]
	v_pk_add_f32 v[42:43], v[42:43], v[52:53] neg_lo:[0,1] neg_hi:[0,1]
	v_pk_mul_f32 v[52:53], v[54:55], s[78:79] op_sel:[1,1] op_sel_hi:[0,0]
	v_pk_fma_f32 v[52:53], s[0:1], v[54:55], v[52:53] op_sel_hi:[0,1,1] neg_lo:[0,1,0] neg_hi:[0,1,0]
	v_pk_add_f32 v[54:55], v[38:39], v[52:53]
	v_pk_add_f32 v[38:39], v[38:39], v[52:53] neg_lo:[0,1] neg_hi:[0,1]
	v_pk_mul_f32 v[52:53], v[40:41], s[80:81] op_sel:[1,1] op_sel_hi:[0,0]
	v_pk_fma_f32 v[40:41], s[16:17], v[40:41], v[52:53] op_sel_hi:[0,1,1] neg_lo:[0,1,0] neg_hi:[0,1,0]
	v_pk_add_f32 v[52:53], v[16:17], v[40:41]
	v_pk_add_f32 v[16:17], v[16:17], v[40:41] neg_lo:[0,1] neg_hi:[0,1]
	v_pk_add_f32 v[40:41], v[56:57], v[22:23]
	v_pk_add_f32 v[22:23], v[56:57], v[22:23] neg_lo:[0,1] neg_hi:[0,1]
	v_pk_mul_f32 v[56:57], v[64:65], s[88:89] op_sel:[1,1] op_sel_hi:[0,0]
	v_pk_fma_f32 v[56:57], v[64:65], s[8:9], v[56:57] op_sel_hi:[1,0,1]
	s_mov_b32 s9, s42
	v_pk_add_f32 v[64:65], v[66:67], v[56:57]
	v_pk_add_f32 v[56:57], v[66:67], v[56:57] neg_lo:[0,1] neg_hi:[0,1]
	v_pk_mul_f32 v[66:67], v[62:63], s[80:81] op_sel:[1,1] op_sel_hi:[0,0]
	v_pk_fma_f32 v[62:63], s[16:17], v[62:63], v[66:67] op_sel_hi:[0,1,1]
	v_pk_add_f32 v[66:67], v[70:71], v[62:63]
	v_pk_add_f32 v[62:63], v[70:71], v[62:63] neg_lo:[0,1] neg_hi:[0,1]
	v_pk_mul_f32 v[70:71], v[60:61], s[62:63] op_sel:[1,1] op_sel_hi:[0,0]
	v_pk_fma_f32 v[60:61], v[60:61], s[24:25], v[70:71] op_sel_hi:[1,0,1]
	s_mov_b32 s25, s38
	v_pk_add_f32 v[70:71], v[32:33], v[60:61]
	v_pk_add_f32 v[32:33], v[32:33], v[60:61] neg_lo:[0,1] neg_hi:[0,1]
	v_pk_mul_f32 v[60:61], v[50:51], s[78:79] op_sel:[1,1] op_sel_hi:[0,0]
	v_pk_fma_f32 v[50:51], s[0:1], v[50:51], v[60:61] op_sel_hi:[0,1,1]
	v_pk_add_f32 v[60:61], v[14:15], v[50:51]
	v_pk_add_f32 v[14:15], v[14:15], v[50:51] neg_lo:[0,1] neg_hi:[0,1]
	v_pk_mul_f32 v[50:51], v[58:59], s[24:25] op_sel:[1,1] op_sel_hi:[0,0]
	v_pk_fma_f32 v[50:51], s[84:85], v[58:59], v[50:51] op_sel_hi:[0,1,1]
	v_pk_add_f32 v[58:59], v[68:69], v[50:51]
	v_pk_add_f32 v[50:51], v[68:69], v[50:51] neg_lo:[0,1] neg_hi:[0,1]
	v_pk_mul_f32 v[68:69], v[54:55], s[16:17] op_sel:[1,1] op_sel_hi:[0,0]
	v_pk_fma_f32 v[54:55], s[82:83], v[54:55], v[68:69] op_sel_hi:[0,1,1]
	v_pk_add_f32 v[68:69], v[26:27], v[54:55]
	v_pk_add_f32 v[26:27], v[26:27], v[54:55] neg_lo:[0,1] neg_hi:[0,1]
	v_pk_mul_f32 v[54:55], v[52:53], s[8:9] op_sel:[1,1] op_sel_hi:[0,0]
	v_pk_fma_f32 v[52:53], s[86:87], v[52:53], v[54:55] op_sel_hi:[0,1,1]
	v_pk_add_f32 v[54:55], v[24:25], v[52:53]
	v_pk_add_f32 v[24:25], v[24:25], v[52:53] neg_lo:[0,1] neg_hi:[0,1]
	v_xor_b32_e32 v52, 0x80000000, v29
	v_mov_b32_e32 v53, v28
	v_pk_add_f32 v[28:29], v[12:13], v[52:53]
	v_pk_add_f32 v[12:13], v[12:13], v[52:53] neg_lo:[0,1] neg_hi:[0,1]
	v_pk_mul_f32 v[52:53], v[44:45], s[8:9] op_sel:[1,1] op_sel_hi:[0,0]
	v_pk_fma_f32 v[44:45], s[86:87], v[44:45], v[52:53] op_sel_hi:[0,1,1] neg_lo:[0,1,0] neg_hi:[0,1,0]
	v_pk_add_f32 v[52:53], v[36:37], v[44:45]
	v_pk_add_f32 v[36:37], v[36:37], v[44:45] neg_lo:[0,1] neg_hi:[0,1]
	v_pk_mul_f32 v[44:45], v[46:47], s[16:17] op_sel:[1,1] op_sel_hi:[0,0]
	v_pk_fma_f32 v[44:45], s[82:83], v[46:47], v[44:45] op_sel_hi:[0,1,1] neg_lo:[0,1,0] neg_hi:[0,1,0]
	v_pk_add_f32 v[46:47], v[10:11], v[44:45]
	v_pk_add_f32 v[10:11], v[10:11], v[44:45] neg_lo:[0,1] neg_hi:[0,1]
	v_pk_mul_f32 v[44:45], v[48:49], s[24:25] op_sel:[1,1] op_sel_hi:[0,0]
	v_pk_fma_f32 v[44:45], s[84:85], v[48:49], v[44:45] op_sel_hi:[0,1,1] neg_lo:[0,1,0] neg_hi:[0,1,0]
	v_pk_add_f32 v[48:49], v[20:21], v[44:45]
	v_pk_add_f32 v[20:21], v[20:21], v[44:45] neg_lo:[0,1] neg_hi:[0,1]
	v_pk_mul_f32 v[44:45], v[34:35], s[78:79] op_sel:[1,1] op_sel_hi:[0,0]
	v_pk_fma_f32 v[34:35], v[34:35], s[0:1], v[44:45] op_sel_hi:[1,0,1] neg_lo:[1,0,0] neg_hi:[1,0,0]
	s_lshl_b64 s[0:1], s[72:73], 2
	v_pk_add_f32 v[44:45], v[30:31], v[34:35]
	v_pk_add_f32 v[30:31], v[30:31], v[34:35] neg_lo:[0,1] neg_hi:[0,1]
	v_pk_mul_f32 v[34:35], v[42:43], s[62:63]
	s_add_u32 s0, s49, s0
	v_pk_fma_f32 v[34:35], v[42:43], s[24:25], v[34:35] op_sel:[0,0,1] op_sel_hi:[1,0,0] neg_lo:[1,0,0] neg_hi:[1,0,0]
	s_addc_u32 s1, s60, s1
	v_pk_add_f32 v[42:43], v[8:9], v[34:35]
	v_pk_add_f32 v[8:9], v[8:9], v[34:35] neg_lo:[0,1] neg_hi:[0,1]
	v_pk_mul_f32 v[34:35], v[38:39], s[80:81]
	s_lshl_b64 s[62:63], s[76:77], 2
	v_pk_fma_f32 v[34:35], v[38:39], s[16:17], v[34:35] op_sel:[0,0,1] op_sel_hi:[1,0,0] neg_lo:[1,0,0] neg_hi:[1,0,0]
	s_add_u32 s62, s22, s62
	v_pk_add_f32 v[38:39], v[6:7], v[34:35]
	v_pk_add_f32 v[6:7], v[6:7], v[34:35] neg_lo:[0,1] neg_hi:[0,1]
	v_pk_mul_f32 v[34:35], v[16:17], s[88:89]
	s_addc_u32 s63, s23, s63
	v_pk_fma_f32 v[16:17], s[8:9], v[16:17], v[34:35] op_sel:[0,0,1] op_sel_hi:[0,1,0] neg_lo:[0,1,0] neg_hi:[0,1,0]
	v_pk_add_f32 v[34:35], v[4:5], v[16:17]
	v_pk_add_f32 v[4:5], v[4:5], v[16:17] neg_lo:[0,1] neg_hi:[0,1]
	ds_write2_b64 v2, v[40:41], v[64:65] offset1:16
	ds_write2_b64 v2, v[66:67], v[70:71] offset0:33 offset1:49
	ds_write2_b64 v2, v[60:61], v[58:59] offset0:66 offset1:82
	ds_write2_b64 v2, v[68:69], v[54:55] offset0:99 offset1:115
	ds_write2_b64 v2, v[28:29], v[52:53] offset0:132 offset1:148
	ds_write2_b64 v2, v[46:47], v[48:49] offset0:165 offset1:181
	ds_write2_b64 v2, v[44:45], v[42:43] offset0:198 offset1:214
	ds_write2_b64 v2, v[38:39], v[34:35] offset0:231 offset1:247
	ds_write2_b64 v3, v[22:23], v[56:57] offset0:8 offset1:24
	ds_write2_b64 v3, v[62:63], v[32:33] offset0:41 offset1:57
	ds_write2_b64 v3, v[14:15], v[50:51] offset0:74 offset1:90
	ds_write2_b64 v3, v[26:27], v[24:25] offset0:107 offset1:123
	ds_write2_b64 v3, v[12:13], v[36:37] offset0:140 offset1:156
	ds_write2_b64 v3, v[10:11], v[20:21] offset0:173 offset1:189
	ds_write2_b64 v3, v[30:31], v[8:9] offset0:206 offset1:222
	ds_write2_b64 v3, v[6:7], v[4:5] offset0:239 offset1:255
	s_waitcnt lgkmcnt(0)
	s_barrier
	global_load_dword v30, v206, s[0:1]
	global_load_dword v20, v207, s[0:1]
	v_ashrrev_i32_e32 v2, 31, v210
	v_lshrrev_b32_e32 v2, 22, v2
	v_add_u32_e32 v2, v210, v2
	v_ashrrev_i32_e32 v2, 10, v2
	v_mul_i32_i24_e32 v3, 0x400, v2
	global_load_dword v31, v205, s[0:1]
	global_load_dword v24, v205, s[62:63]
	s_add_u32 s0, s87, s74
	v_sub_u32_e32 v21, v210, v3
	v_lshlrev_b32_e32 v36, 14, v2
	s_addc_u32 s1, s90, s75
	v_ashrrev_i32_e32 v37, 31, v36
	v_lshlrev_b32_e32 v32, 4, v21
	v_lshl_add_u64 v[2:3], v[36:37], 1, s[0:1]
	v_ashrrev_i32_e32 v33, 31, v32
	v_lshl_add_u64 v[2:3], v[32:33], 1, v[2:3]
	global_load_dwordx4 v[10:13], v[2:3], off offset:16 nt
	global_load_dwordx4 v[14:17], v[2:3], off nt
	v_cmp_lt_i32_e32 vcc, 0, v21
	v_mov_b32_e32 v39, 0
	v_mov_b32_e32 v41, 0
	s_and_saveexec_b64 s[72:73], vcc
	s_cbranch_execz .LBB0_505
	global_load_ushort v41, v[2:3], off offset:-2

.LBB0_515:
	v_lshl_add_u32 v10, v18, 3, v26
	v_ashrrev_i32_e32 v11, 5, v10
	v_lshlrev_b32_e32 v10, 3, v10
	v_lshlrev_b32_e32 v11, 3, v11
	v_add3_u32 v18, 0, v10, v11
	s_waitcnt vmcnt(0)
	v_and_b32_e32 v32, 0xffff0000, v6
	v_mov_b32_e32 v34, v32
	ds_read2_b64 v[10:13], v18 offset1:1
	v_lshlrev_b32_e32 v14, 16, v6
	v_pk_mul_f32 v[16:17], v[30:31], v[34:35]
	v_mov_b32_e32 v21, v20
	v_lshlrev_b32_e32 v33, 16, v7
	v_pk_fma_f32 v[14:15], v[30:31], v[14:15], v[16:17] op_sel:[0,0,1] op_sel_hi:[1,0,0]
	v_mov_b32_e32 v25, v24
	v_pk_fma_f32 v[14:15], v[20:21], v[32:33], v[14:15]
	v_mov_b32_e32 v36, v30
	v_mov_b32_e32 v37, v30
	v_mov_b32_e32 v38, v31
	v_mov_b32_e32 v39, v31
	v_pk_add_f32 v[30:31], v[24:25], v[14:15]
	ds_read2_b64 v[14:17], v18 offset0:2 offset1:3
	s_waitcnt lgkmcnt(1)
	v_pk_mul_f32 v[10:11], v[30:31], v[10:11]
	v_and_b32_e32 v31, 16, v8
	v_and_b32_e32 v30, 0xffff0000, v7
	v_pk_mov_b32 v[6:7], v[32:33], v[30:31] op_sel:[1,0]
	v_lshlrev_b32_e32 v35, 16, v8
	v_pk_mul_f32 v[6:7], v[36:37], v[6:7]
	v_mov_b32_e32 v34, v30
	v_pk_fma_f32 v[6:7], v[38:39], v[32:33], v[6:7]
	v_lshlrev_b32_e32 v31, 16, v9
	v_pk_fma_f32 v[6:7], v[20:21], v[34:35], v[6:7]
	v_lshlrev_b32_e32 v33, 16, v2
	v_pk_add_f32 v[6:7], v[24:25], v[6:7]
	v_lshlrev_b32_e32 v43, 16, v4
	v_pk_mul_f32 v[6:7], v[6:7], v[12:13]
	v_and_b32_e32 v13, 16, v9
	v_and_b32_e32 v12, 0xffff0000, v8
	v_mov_b32_e32 v30, v12
	v_pk_mov_b32 v[12:13], v[34:35], v[12:13] op_sel:[1,0]
	v_pk_mov_b32 v[8:9], v[8:9], v[2:3] op_sel:[1,0]
	v_pk_mul_f32 v[12:13], v[36:37], v[12:13]
	v_and_b32_e32 v9, 16, v9
	v_and_b32_e32 v8, 0xffff0000, v8
	v_pk_fma_f32 v[12:13], v[38:39], v[34:35], v[12:13]
	v_mov_b32_e32 v32, v8
	v_pk_mov_b32 v[8:9], v[30:31], v[8:9] op_sel:[1,0]
	v_pk_fma_f32 v[12:13], v[20:21], v[30:31], v[12:13]
	v_pk_mul_f32 v[8:9], v[36:37], v[8:9]
	v_pk_add_f32 v[12:13], v[24:25], v[12:13]
	v_pk_fma_f32 v[8:9], v[38:39], v[30:31], v[8:9]
	s_waitcnt lgkmcnt(0)
	v_pk_mul_f32 v[12:13], v[12:13], v[14:15]
	v_pk_fma_f32 v[8:9], v[20:21], v[32:33], v[8:9]
	v_and_b32_e32 v15, 16, v3
	v_and_b32_e32 v14, 0xffff0000, v2
	v_pk_add_f32 v[8:9], v[24:25], v[8:9]
	v_mov_b32_e32 v34, v14
	v_pk_mov_b32 v[14:15], v[32:33], v[14:15] op_sel:[1,0]
	v_pk_mul_f32 v[8:9], v[8:9], v[16:17]
	v_pk_mul_f32 v[30:31], v[36:37], v[14:15]
	ds_read2_b64 v[14:17], v18 offset0:4 offset1:5
	v_lshlrev_b32_e32 v35, 16, v3
	v_pk_fma_f32 v[30:31], v[38:39], v[32:33], v[30:31]
	v_and_b32_e32 v28, 0xffff0000, v5
	v_pk_fma_f32 v[30:31], v[20:21], v[34:35], v[30:31]
	s_andn2_b64 vcc, exec, s[70:71]
	v_pk_add_f32 v[40:41], v[24:25], v[30:31]
	ds_read2_b64 v[30:33], v18 offset0:6 offset1:7
	s_waitcnt lgkmcnt(1)
	v_pk_mul_f32 v[14:15], v[40:41], v[14:15]
	v_and_b32_e32 v41, 16, v4
	v_and_b32_e32 v40, 0xffff0000, v3
	v_pk_mov_b32 v[2:3], v[34:35], v[40:41] op_sel:[1,0]
	v_mov_b32_e32 v42, v40
	v_pk_mul_f32 v[2:3], v[36:37], v[2:3] op_sel:[1,1] op_sel_hi:[0,0]
	v_pk_fma_f32 v[2:3], v[38:39], v[34:35], v[2:3] op_sel:[0,0,1] op_sel_hi:[1,1,0]
	v_lshlrev_b32_e32 v35, 16, v5
	v_pk_fma_f32 v[2:3], v[20:21], v[42:43], v[2:3] op_sel:[1,1,1] op_sel_hi:[0,0,0]
	v_pk_add_f32 v[2:3], v[24:25], v[2:3] op_sel:[1,0] op_sel_hi:[0,1]
	v_pk_mul_f32 v[2:3], v[2:3], v[16:17] op_sel:[1,0] op_sel_hi:[0,1]
	v_and_b32_e32 v17, 16, v5
	v_and_b32_e32 v16, 0xffff0000, v4
	v_mov_b32_e32 v34, v16
	v_pk_mov_b32 v[4:5], v[42:43], v[16:17] op_sel:[1,0]
	v_mov_b32_e32 v16, v35
	v_mov_b32_e32 v17, v28
	v_pk_mul_f32 v[4:5], v[36:37], v[4:5]
	v_pk_mul_f32 v[16:17], v[36:37], v[16:17]
	v_pk_fma_f32 v[4:5], v[38:39], v[42:43], v[4:5]
	v_pk_fma_f32 v[16:17], v[38:39], v[34:35], v[16:17]
	v_pk_fma_f32 v[4:5], v[20:21], v[34:35], v[4:5]
	v_pk_fma_f32 v[16:17], v[20:21], v[28:29], v[16:17]
	v_pk_add_f32 v[4:5], v[24:25], v[4:5]
	v_pk_add_f32 v[16:17], v[24:25], v[16:17]
	v_cndmask_b32_e64 v20, 0, 1, s[70:71]
	s_waitcnt lgkmcnt(0)
	v_pk_mul_f32 v[4:5], v[4:5], v[30:31]
	v_pk_mul_f32 v[16:17], v[16:17], v[32:33]
	v_cmp_ne_u32_e64 s[0:1], 1, v20
	s_mov_b64 s[70:71], -1
	s_cbranch_vccnz .LBB0_517
	v_lshl_add_u64 v[20:21], v[26:27], 1, s[50:51]
	v_bfe_u32 v26, v9, 16, 1
	v_bfe_u32 v27, v7, 16, 1
	v_add3_u32 v28, v7, v27, s4
	v_add3_u32 v27, v9, v26, s4
	v_bfe_u32 v26, v6, 16, 1
	v_bfe_u32 v30, v10, 16, 1
	v_bfe_u32 v31, v12, 16, 1
	v_bfe_u32 v24, v13, 16, 1
	v_bfe_u32 v25, v11, 16, 1
	v_add3_u32 v31, v12, v31, s4
	v_add3_u32 v30, v10, v30, s4
	v_add3_u32 v26, v6, v26, s4
	v_add3_u32 v25, v11, v25, s4
	v_add3_u32 v24, v13, v24, s4
	v_bfe_u32 v29, v8, 16, 1
	v_lshrrev_b32_e32 v32, 16, v26
	v_lshrrev_b32_e32 v30, 16, v30
	v_lshrrev_b32_e32 v26, 16, v31
	v_add3_u32 v29, v8, v29, s4
	v_and_or_b32 v26, v24, s91, v26
	v_and_or_b32 v24, v25, s91, v30
	v_bfe_u32 v30, v17, 16, 1
	v_bfe_u32 v31, v3, 16, 1
	v_lshrrev_b32_e32 v29, 16, v29
	v_and_or_b32 v25, v28, s91, v32
	v_add3_u32 v32, v3, v31, s4
	v_add3_u32 v31, v17, v30, s4
	v_bfe_u32 v30, v2, 16, 1
	v_bfe_u32 v33, v16, 16, 1
	v_bfe_u32 v34, v14, 16, 1
	v_bfe_u32 v35, v4, 16, 1
	v_and_or_b32 v27, v27, s91, v29
	v_bfe_u32 v28, v5, 16, 1
	v_bfe_u32 v29, v15, 16, 1
	v_add3_u32 v35, v4, v35, s4
	v_add3_u32 v34, v14, v34, s4
	v_add3_u32 v33, v16, v33, s4
	v_add3_u32 v30, v2, v30, s4
	v_add3_u32 v29, v15, v29, s4
	v_add3_u32 v28, v5, v28, s4
	v_lshrrev_b32_e32 v36, 16, v30
	v_lshrrev_b32_e32 v33, 16, v33
	v_lshrrev_b32_e32 v34, 16, v34
	v_lshrrev_b32_e32 v30, 16, v35
	v_lshl_add_u64 v[20:21], v[22:23], 1, v[20:21]
	s_mov_b64 s[70:71], 0
	v_and_or_b32 v30, v28, s91, v30
	v_and_or_b32 v28, v29, s91, v34
	v_and_or_b32 v31, v31, s91, v33
	v_and_or_b32 v29, v32, s91, v36
	global_store_dwordx4 v[20:21], v[24:27], off
	global_store_dwordx4 v[20:21], v[28:31], off offset:16

.LBB0_534:
	v_mov_b32_e32 v2, v210
	s_mov_b32 s43, s8
	v_and_b32_e32 v3, 0xff, v2
	v_lshlrev_b32_e32 v4, 5, v2
	v_and_or_b32 v3, v4, s33, v3
	v_ashrrev_i32_e32 v4, 5, v3
	v_lshlrev_b32_e32 v3, 3, v3
	v_lshlrev_b32_e32 v4, 3, v4
	v_add3_u32 v18, 0, v3, v4
	ds_read_b64 v[128:129], v18
	ds_read_b64 v[132:133], v18 offset:2112
	ds_read_b64 v[134:135], v18 offset:4224
	ds_read_b64 v[136:137], v18 offset:6336
	ds_read_b64 v[138:139], v18 offset:8448
	ds_read_b64 v[140:141], v18 offset:10560
	ds_read_b64 v[142:143], v18 offset:12672
	ds_read_b64 v[130:131], v18 offset:14784
	ds_read_b64 v[144:145], v18 offset:16896
	ds_read_b64 v[148:149], v18 offset:19008
	ds_read_b64 v[150:151], v18 offset:21120
	ds_read_b64 v[152:153], v18 offset:23232
	s_waitcnt lgkmcnt(10)
	v_pk_mul_f32 v[162:163], v[132:133], s[10:11]
	s_mov_b32 s64, s11
	v_pk_fma_f32 v[162:163], v[132:133], s[8:9], v[162:163] op_sel:[0,0,1] op_sel_hi:[1,0,0]
	s_waitcnt lgkmcnt(2)
	v_pk_mul_f32 v[178:179], v[148:149], s[42:43]
	v_pk_add_f32 v[194:195], v[132:133], v[148:149]
	v_pk_add_f32 v[132:133], v[132:133], v[148:149] neg_lo:[0,1] neg_hi:[0,1]
	v_pk_mul_f32 v[164:165], v[134:135], s[18:19]
	s_mov_b32 s41, s16
	v_pk_fma_f32 v[178:179], v[148:149], s[64:65], v[178:179] op_sel:[0,0,1] op_sel_hi:[1,0,0] neg_lo:[1,0,0] neg_hi:[1,0,0]
	v_pk_mul_f32 v[148:149], v[132:133], s[18:19]
	v_pk_fma_f32 v[164:165], v[134:135], s[16:17], v[164:165] op_sel:[0,0,1] op_sel_hi:[1,0,0]
	s_mov_b32 s68, s19
	s_waitcnt lgkmcnt(1)
	v_pk_mul_f32 v[180:181], v[150:151], s[40:41]
	v_pk_fma_f32 v[132:133], v[132:133], s[16:17], v[148:149] op_sel:[0,0,1] op_sel_hi:[1,0,0]
	v_pk_add_f32 v[148:149], v[134:135], v[150:151]
	v_pk_add_f32 v[134:135], v[134:135], v[150:151] neg_lo:[0,1] neg_hi:[0,1]
	v_pk_mul_f32 v[166:167], v[136:137], s[26:27]
	s_mov_b32 s66, s37
	s_mov_b32 s39, s24
	v_pk_fma_f32 v[180:181], v[150:151], s[68:69], v[180:181] op_sel:[0,0,1] op_sel_hi:[1,0,0] neg_lo:[1,0,0] neg_hi:[1,0,0]
	v_pk_mul_f32 v[150:151], v[134:135], s[36:37]
	ds_read_b64 v[154:155], v18 offset:25344
	ds_read_b64 v[156:157], v18 offset:27456
	ds_read_b64 v[158:159], v18 offset:29568
	ds_read_b64 v[160:161], v18 offset:31680
	v_pk_fma_f32 v[166:167], v[136:137], s[24:25], v[166:167] op_sel:[0,0,1] op_sel_hi:[1,0,0]
	s_mov_b32 s0, s27
	s_waitcnt lgkmcnt(4)
	v_pk_mul_f32 v[182:183], v[152:153], s[38:39]
	v_pk_fma_f32 v[134:135], v[134:135], s[66:67], v[150:151] op_sel:[0,0,1] op_sel_hi:[1,0,0]
	v_pk_add_f32 v[150:151], v[136:137], v[152:153]
	v_pk_add_f32 v[136:137], v[136:137], v[152:153] neg_lo:[0,1] neg_hi:[0,1]
	v_pk_mul_f32 v[168:169], v[138:139], s[36:37]
	v_pk_fma_f32 v[182:183], v[152:153], s[0:1], v[182:183] op_sel:[0,0,1] op_sel_hi:[1,0,0] neg_lo:[1,0,0] neg_hi:[1,0,0]
	v_pk_mul_f32 v[152:153], v[136:137], s[40:41]
	v_pk_fma_f32 v[168:169], v[138:139], s[66:67], v[168:169] op_sel:[0,0,1] op_sel_hi:[1,0,0]
	v_pk_mul_f32 v[170:171], v[140:141], s[38:39]
	s_waitcnt lgkmcnt(3)
	v_pk_mul_f32 v[184:185], v[154:155], s[36:37]
	v_pk_fma_f32 v[136:137], v[136:137], s[68:69], v[152:153] op_sel:[0,0,1] op_sel_hi:[1,0,0]
	v_pk_add_f32 v[152:153], v[138:139], v[154:155]
	v_pk_add_f32 v[138:139], v[138:139], v[154:155] neg_lo:[0,1] neg_hi:[0,1]
	v_pk_fma_f32 v[170:171], v[140:141], s[0:1], v[170:171] op_sel:[0,0,1] op_sel_hi:[1,0,0]
	v_pk_fma_f32 v[184:185], v[154:155], s[66:67], v[184:185] op_sel:[0,0,1] op_sel_hi:[1,0,0] neg_lo:[1,0,0] neg_hi:[1,0,0]
	s_waitcnt lgkmcnt(2)
	v_pk_mul_f32 v[186:187], v[156:157], s[26:27]
	v_xor_b32_e32 v155, 0x80000000, v138
	v_mov_b32_e32 v154, v139
	v_pk_add_f32 v[138:139], v[140:141], v[156:157]
	v_pk_add_f32 v[140:141], v[140:141], v[156:157] neg_lo:[0,1] neg_hi:[0,1]
	v_pk_mul_f32 v[172:173], v[142:143], s[40:41]
	v_pk_fma_f32 v[186:187], v[156:157], s[24:25], v[186:187] op_sel:[0,0,1] op_sel_hi:[1,0,0] neg_lo:[1,0,0] neg_hi:[1,0,0]
	v_pk_mul_f32 v[156:157], v[140:141], s[40:41]
	v_pk_fma_f32 v[172:173], v[142:143], s[68:69], v[172:173] op_sel:[0,0,1] op_sel_hi:[1,0,0]
	s_waitcnt lgkmcnt(1)
	v_pk_mul_f32 v[188:189], v[158:159], s[18:19]
	v_pk_fma_f32 v[140:141], v[140:141], s[68:69], v[156:157] op_sel:[0,0,1] op_sel_hi:[1,0,0] neg_lo:[1,0,0] neg_hi:[1,0,0]
	v_pk_add_f32 v[156:157], v[142:143], v[158:159]
	v_pk_add_f32 v[142:143], v[142:143], v[158:159] neg_lo:[0,1] neg_hi:[0,1]
	v_pk_mul_f32 v[174:175], v[130:131], s[42:43]
	v_pk_fma_f32 v[188:189], v[158:159], s[16:17], v[188:189] op_sel:[0,0,1] op_sel_hi:[1,0,0] neg_lo:[1,0,0] neg_hi:[1,0,0]
	v_pk_mul_f32 v[158:159], v[142:143], s[36:37]
	v_pk_fma_f32 v[174:175], v[130:131], s[64:65], v[174:175] op_sel:[0,0,1] op_sel_hi:[1,0,0]
	s_waitcnt lgkmcnt(0)
	v_pk_mul_f32 v[190:191], v[160:161], s[10:11]
	v_pk_fma_f32 v[142:143], v[142:143], s[66:67], v[158:159] op_sel:[0,0,1] op_sel_hi:[1,0,0] neg_lo:[1,0,0] neg_hi:[1,0,0]
	v_pk_add_f32 v[158:159], v[130:131], v[160:161]
	v_pk_add_f32 v[130:131], v[130:131], v[160:161] neg_lo:[0,1] neg_hi:[0,1]
	v_xor_b32_e32 v177, 0x80000000, v144
	v_mov_b32_e32 v176, v145
	v_pk_fma_f32 v[190:191], v[160:161], s[8:9], v[190:191] op_sel:[0,0,1] op_sel_hi:[1,0,0] neg_lo:[1,0,0] neg_hi:[1,0,0]
	v_pk_mul_f32 v[160:161], v[130:131], s[18:19]
	v_pk_add_f32 v[192:193], v[128:129], v[144:145]
	v_pk_add_f32 v[144:145], v[128:129], v[144:145] neg_lo:[0,1] neg_hi:[0,1]
	v_pk_fma_f32 v[130:131], v[130:131], s[16:17], v[160:161] op_sel:[0,0,1] op_sel_hi:[1,0,0] neg_lo:[1,0,0] neg_hi:[1,0,0]
	v_pk_add_f32 v[160:161], v[128:129], v[176:177]
	v_pk_add_f32 v[128:129], v[128:129], v[176:177] neg_lo:[0,1] neg_hi:[0,1]
	v_pk_add_f32 v[176:177], v[162:163], v[178:179]
	v_pk_add_f32 v[162:163], v[162:163], v[178:179] neg_lo:[0,1] neg_hi:[0,1]
	v_cvt_f32_ubyte0_e32 v2, v2
	v_pk_mul_f32 v[178:179], v[162:163], s[18:19]
	v_mul_f32_e32 v2, 0x39000000, v2
	v_pk_fma_f32 v[162:163], v[162:163], s[16:17], v[178:179] op_sel:[0,0,1] op_sel_hi:[1,0,0]
	v_pk_add_f32 v[178:179], v[164:165], v[180:181]
	v_pk_add_f32 v[164:165], v[164:165], v[180:181] neg_lo:[0,1] neg_hi:[0,1]
	v_sin_f32_e32 v34, v2
	v_pk_mul_f32 v[180:181], v[164:165], s[36:37]
	v_cos_f32_e32 v30, v2
	v_pk_fma_f32 v[164:165], v[164:165], s[66:67], v[180:181] op_sel:[0,0,1] op_sel_hi:[1,0,0]
	v_pk_add_f32 v[180:181], v[166:167], v[182:183]
	v_pk_add_f32 v[166:167], v[166:167], v[182:183] neg_lo:[0,1] neg_hi:[0,1]
	v_xor_b32_e32 v31, 0x80000000, v34
	v_pk_mul_f32 v[182:183], v[166:167], s[40:41]
	v_mov_b32_e32 v35, v31
	v_pk_fma_f32 v[166:167], v[166:167], s[68:69], v[182:183] op_sel:[0,0,1] op_sel_hi:[1,0,0]
	v_pk_add_f32 v[182:183], v[168:169], v[184:185]
	v_pk_add_f32 v[184:185], v[168:169], v[184:185] neg_lo:[0,1] neg_hi:[0,1]
	v_pk_mul_f32 v[2:3], v[30:31], v[34:35] op_sel:[1,0] op_sel_hi:[0,1]
	v_pk_add_f32 v[168:169], v[170:171], v[186:187]
	v_pk_add_f32 v[170:171], v[170:171], v[186:187] neg_lo:[0,1] neg_hi:[0,1]
	v_pk_fma_f32 v[44:45], v[30:31], v[30:31], v[2:3] op_sel_hi:[1,0,1]
	v_pk_mul_f32 v[186:187], v[170:171], s[40:41]
	v_pk_mul_f32 v[2:3], v[34:35], v[44:45] op_sel:[0,1] op_sel_hi:[1,0]
	v_pk_fma_f32 v[170:171], v[170:171], s[68:69], v[186:187] op_sel:[0,0,1] op_sel_hi:[1,0,0] neg_lo:[1,0,0] neg_hi:[1,0,0]
	v_pk_add_f32 v[186:187], v[172:173], v[188:189]
	v_pk_add_f32 v[172:173], v[172:173], v[188:189] neg_lo:[0,1] neg_hi:[0,1]
	v_xor_b32_e32 v54, 0x80000000, v45
	v_pk_mul_f32 v[188:189], v[172:173], s[36:37]
	v_mov_b32_e32 v55, v45
	v_pk_fma_f32 v[172:173], v[172:173], s[66:67], v[188:189] op_sel:[0,0,1] op_sel_hi:[1,0,0] neg_lo:[1,0,0] neg_hi:[1,0,0]
	v_pk_add_f32 v[188:189], v[174:175], v[190:191]
	v_pk_add_f32 v[174:175], v[174:175], v[190:191] neg_lo:[0,1] neg_hi:[0,1]
	v_pk_fma_f32 v[46:47], v[30:31], v[44:45], v[2:3] op_sel_hi:[0,1,1]
	v_pk_mul_f32 v[190:191], v[174:175], s[18:19]
	v_pk_mul_f32 v[2:3], v[44:45], v[54:55] op_sel:[1,0] op_sel_hi:[0,1]
	v_pk_fma_f32 v[174:175], v[174:175], s[16:17], v[190:191] op_sel:[0,0,1] op_sel_hi:[1,0,0] neg_lo:[1,0,0] neg_hi:[1,0,0]
	v_pk_add_f32 v[190:191], v[192:193], v[152:153]
	v_pk_add_f32 v[152:153], v[192:193], v[152:153] neg_lo:[0,1] neg_hi:[0,1]
	v_pk_add_f32 v[192:193], v[194:195], v[138:139]
	v_pk_add_f32 v[138:139], v[194:195], v[138:139] neg_lo:[0,1] neg_hi:[0,1]
	v_pk_fma_f32 v[52:53], v[44:45], v[44:45], v[2:3] op_sel_hi:[1,0,1]
	v_pk_mul_f32 v[194:195], v[138:139], s[36:37]
	v_xor_b32_e32 v58, 0x80000000, v53
	v_pk_fma_f32 v[138:139], v[138:139], s[66:67], v[194:195] op_sel:[0,0,1] op_sel_hi:[1,0,0]
	v_pk_add_f32 v[194:195], v[148:149], v[156:157]
	v_pk_add_f32 v[156:157], v[148:149], v[156:157] neg_lo:[0,1] neg_hi:[0,1]
	v_mov_b32_e32 v59, v53
	v_pk_add_f32 v[148:149], v[150:151], v[158:159]
	v_pk_add_f32 v[150:151], v[150:151], v[158:159] neg_lo:[0,1] neg_hi:[0,1]
	v_pk_mul_f32 v[2:3], v[52:53], v[58:59] op_sel:[1,0] op_sel_hi:[0,1]
	v_pk_mul_f32 v[158:159], v[150:151], s[36:37]
	v_pk_fma_f32 v[48:49], v[52:53], v[52:53], v[2:3] op_sel_hi:[1,0,1]
	v_pk_fma_f32 v[150:151], v[150:151], s[66:67], v[158:159] op_sel:[0,0,1] op_sel_hi:[1,0,0] neg_lo:[1,0,0] neg_hi:[1,0,0]
	v_pk_add_f32 v[158:159], v[144:145], v[154:155]
	v_pk_add_f32 v[144:145], v[144:145], v[154:155] neg_lo:[0,1] neg_hi:[0,1]
	v_pk_add_f32 v[154:155], v[132:133], v[140:141]
	v_pk_add_f32 v[132:133], v[132:133], v[140:141] neg_lo:[0,1] neg_hi:[0,1]
	v_pk_mul_f32 v[2:3], v[58:59], v[48:49] op_sel:[0,1] op_sel_hi:[1,0]
	v_pk_mul_f32 v[140:141], v[132:133], s[36:37]
	v_pk_fma_f32 v[36:37], v[52:53], v[48:49], v[2:3] op_sel_hi:[0,1,1]
	v_pk_fma_f32 v[132:133], v[132:133], s[66:67], v[140:141] op_sel:[0,0,1] op_sel_hi:[1,0,0]
	v_pk_add_f32 v[140:141], v[134:135], v[142:143]
	v_pk_add_f32 v[142:143], v[134:135], v[142:143] neg_lo:[0,1] neg_hi:[0,1]
	v_pk_mul_f32 v[2:3], v[58:59], v[36:37] op_sel:[0,1] op_sel_hi:[1,0]
	v_pk_add_f32 v[134:135], v[136:137], v[130:131]
	v_pk_add_f32 v[130:131], v[136:137], v[130:131] neg_lo:[0,1] neg_hi:[0,1]
	v_pk_fma_f32 v[26:27], v[52:53], v[36:37], v[2:3] op_sel_hi:[0,1,1]
	v_pk_mul_f32 v[136:137], v[130:131], s[36:37]
	v_pk_mul_f32 v[2:3], v[58:59], v[26:27] op_sel:[0,1] op_sel_hi:[1,0]
	v_pk_fma_f32 v[130:131], v[130:131], s[66:67], v[136:137] op_sel:[0,0,1] op_sel_hi:[1,0,0] neg_lo:[1,0,0] neg_hi:[1,0,0]
	v_pk_add_f32 v[136:137], v[160:161], v[182:183]
	v_pk_add_f32 v[160:161], v[160:161], v[182:183] neg_lo:[0,1] neg_hi:[0,1]
	v_pk_add_f32 v[182:183], v[176:177], v[168:169]
	v_pk_add_f32 v[168:169], v[176:177], v[168:169] neg_lo:[0,1] neg_hi:[0,1]
	v_pk_fma_f32 v[20:21], v[52:53], v[26:27], v[2:3] op_sel_hi:[0,1,1]
	v_pk_mul_f32 v[176:177], v[168:169], s[36:37]
	v_pk_mul_f32 v[2:3], v[58:59], v[20:21] op_sel:[0,1] op_sel_hi:[1,0]
	v_pk_fma_f32 v[168:169], v[168:169], s[66:67], v[176:177] op_sel:[0,0,1] op_sel_hi:[1,0,0]
	v_pk_add_f32 v[176:177], v[178:179], v[186:187]
	v_pk_add_f32 v[186:187], v[178:179], v[186:187] neg_lo:[0,1] neg_hi:[0,1]
	v_pk_fma_f32 v[10:11], v[52:53], v[20:21], v[2:3] op_sel_hi:[0,1,1]
	v_pk_add_f32 v[178:179], v[180:181], v[188:189]
	v_pk_add_f32 v[180:181], v[180:181], v[188:189] neg_lo:[0,1] neg_hi:[0,1]
	v_pk_mul_f32 v[2:3], v[58:59], v[10:11] op_sel:[0,1] op_sel_hi:[1,0]
	v_pk_mul_f32 v[188:189], v[180:181], s[36:37]
	v_pk_fma_f32 v[4:5], v[52:53], v[10:11], v[2:3] op_sel_hi:[0,1,1]
	v_pk_fma_f32 v[180:181], v[180:181], s[66:67], v[188:189] op_sel:[0,0,1] op_sel_hi:[1,0,0] neg_lo:[1,0,0] neg_hi:[1,0,0]
	v_pk_add_f32 v[188:189], v[128:129], v[184:185] op_sel:[0,1] op_sel_hi:[1,0] neg_hi:[0,1]
	v_pk_add_f32 v[128:129], v[128:129], v[184:185] op_sel:[0,1] op_sel_hi:[1,0] neg_lo:[0,1]
	v_pk_add_f32 v[184:185], v[162:163], v[170:171]
	v_pk_add_f32 v[162:163], v[162:163], v[170:171] neg_lo:[0,1] neg_hi:[0,1]
	v_xor_b32_e32 v72, 0x80000000, v47
	v_pk_mul_f32 v[170:171], v[162:163], s[36:37]
	v_mov_b32_e32 v73, v47
	v_pk_fma_f32 v[162:163], v[162:163], s[66:67], v[170:171] op_sel:[0,0,1] op_sel_hi:[1,0,0]
	v_pk_add_f32 v[170:171], v[164:165], v[172:173]
	v_pk_add_f32 v[172:173], v[164:165], v[172:173] neg_lo:[0,1] neg_hi:[0,1]
	v_pk_mul_f32 v[2:3], v[72:73], v[4:5] op_sel:[0,1] op_sel_hi:[1,0]
	v_pk_add_f32 v[164:165], v[166:167], v[174:175]
	v_pk_add_f32 v[166:167], v[166:167], v[174:175] neg_lo:[0,1] neg_hi:[0,1]
	v_pk_mul_f32 v[14:15], v[34:35], v[4:5] op_sel:[0,1] op_sel_hi:[1,0]
	v_pk_mul_f32 v[174:175], v[166:167], s[36:37]
	v_pk_mul_f32 v[40:41], v[34:35], v[10:11] op_sel:[0,1] op_sel_hi:[1,0]
	v_pk_fma_f32 v[166:167], v[166:167], s[66:67], v[174:175] op_sel:[0,0,1] op_sel_hi:[1,0,0] neg_lo:[1,0,0] neg_hi:[1,0,0]
	v_pk_add_f32 v[174:175], v[190:191], v[194:195]
	v_pk_add_f32 v[190:191], v[190:191], v[194:195] neg_lo:[0,1] neg_hi:[0,1]
	v_pk_add_f32 v[194:195], v[192:193], v[148:149]
	v_pk_add_f32 v[192:193], v[192:193], v[148:149] neg_lo:[0,1] neg_hi:[0,1]
	v_pk_mul_f32 v[66:67], v[34:35], v[20:21] op_sel:[0,1] op_sel_hi:[1,0]
	v_pk_add_f32 v[148:149], v[152:153], v[156:157] op_sel:[0,1] op_sel_hi:[1,0] neg_hi:[0,1]
	v_pk_add_f32 v[152:153], v[152:153], v[156:157] op_sel:[0,1] op_sel_hi:[1,0] neg_lo:[0,1]
	v_pk_add_f32 v[156:157], v[138:139], v[150:151]
	v_pk_add_f32 v[150:151], v[138:139], v[150:151] neg_lo:[0,1] neg_hi:[0,1]
	v_pk_mul_f32 v[82:83], v[34:35], v[26:27] op_sel:[0,1] op_sel_hi:[1,0]
	v_pk_add_f32 v[138:139], v[158:159], v[140:141]
	v_pk_add_f32 v[140:141], v[158:159], v[140:141] neg_lo:[0,1] neg_hi:[0,1]
	v_pk_add_f32 v[158:159], v[154:155], v[134:135]
	v_pk_add_f32 v[154:155], v[154:155], v[134:135] neg_lo:[0,1] neg_hi:[0,1]
	v_pk_mul_f32 v[96:97], v[34:35], v[36:37] op_sel:[0,1] op_sel_hi:[1,0]
	v_pk_add_f32 v[134:135], v[144:145], v[142:143] op_sel:[0,1] op_sel_hi:[1,0] neg_hi:[0,1]
	v_pk_add_f32 v[142:143], v[144:145], v[142:143] op_sel:[0,1] op_sel_hi:[1,0] neg_lo:[0,1]
	v_pk_add_f32 v[144:145], v[132:133], v[130:131]
	v_pk_add_f32 v[132:133], v[132:133], v[130:131] neg_lo:[0,1] neg_hi:[0,1]
	v_pk_mul_f32 v[110:111], v[34:35], v[48:49] op_sel:[0,1] op_sel_hi:[1,0]
	v_pk_add_f32 v[130:131], v[136:137], v[176:177]
	v_pk_add_f32 v[136:137], v[136:137], v[176:177] neg_lo:[0,1] neg_hi:[0,1]
	v_pk_add_f32 v[176:177], v[182:183], v[178:179]
	v_pk_add_f32 v[182:183], v[182:183], v[178:179] neg_lo:[0,1] neg_hi:[0,1]
	v_pk_mul_f32 v[124:125], v[34:35], v[52:53] op_sel:[0,1] op_sel_hi:[1,0]
	v_pk_add_f32 v[178:179], v[160:161], v[186:187] op_sel:[0,1] op_sel_hi:[1,0] neg_hi:[0,1]
	v_pk_add_f32 v[160:161], v[160:161], v[186:187] op_sel:[0,1] op_sel_hi:[1,0] neg_lo:[0,1]
	v_pk_add_f32 v[186:187], v[168:169], v[180:181]
	v_pk_add_f32 v[180:181], v[168:169], v[180:181] neg_lo:[0,1] neg_hi:[0,1]
	v_pk_fma_f32 v[2:3], v[46:47], v[4:5], v[2:3] op_sel_hi:[0,1,1]
	v_pk_add_f32 v[168:169], v[188:189], v[170:171]
	v_pk_add_f32 v[170:171], v[188:189], v[170:171] neg_lo:[0,1] neg_hi:[0,1]
	v_pk_add_f32 v[188:189], v[184:185], v[164:165]
	v_pk_add_f32 v[184:185], v[184:185], v[164:165] neg_lo:[0,1] neg_hi:[0,1]
	v_pk_mul_f32 v[8:9], v[54:55], v[4:5] op_sel:[0,1] op_sel_hi:[1,0]
	v_pk_add_f32 v[164:165], v[128:129], v[172:173] op_sel:[0,1] op_sel_hi:[1,0] neg_hi:[0,1]
	v_pk_add_f32 v[128:129], v[128:129], v[172:173] op_sel:[0,1] op_sel_hi:[1,0] neg_lo:[0,1]
	v_pk_add_f32 v[172:173], v[162:163], v[166:167]
	v_pk_add_f32 v[166:167], v[162:163], v[166:167] neg_lo:[0,1] neg_hi:[0,1]
	v_pk_fma_f32 v[14:15], v[30:31], v[4:5], v[14:15] op_sel_hi:[0,1,1]
	v_pk_add_f32 v[162:163], v[174:175], v[194:195]
	v_pk_add_f32 v[174:175], v[174:175], v[194:195] neg_lo:[0,1] neg_hi:[0,1]
	v_pk_add_f32 v[194:195], v[190:191], v[192:193] op_sel:[0,1] op_sel_hi:[1,0] neg_hi:[0,1]
	v_pk_add_f32 v[190:191], v[190:191], v[192:193] op_sel:[0,1] op_sel_hi:[1,0] neg_lo:[0,1]
	v_pk_add_f32 v[192:193], v[148:149], v[156:157]
	v_pk_add_f32 v[148:149], v[148:149], v[156:157] neg_lo:[0,1] neg_hi:[0,1]
	v_pk_add_f32 v[156:157], v[152:153], v[150:151] op_sel:[0,1] op_sel_hi:[1,0] neg_hi:[0,1]
	v_pk_add_f32 v[150:151], v[152:153], v[150:151] op_sel:[0,1] op_sel_hi:[1,0] neg_lo:[0,1]
	v_pk_add_f32 v[152:153], v[138:139], v[158:159]
	v_pk_add_f32 v[138:139], v[138:139], v[158:159] neg_lo:[0,1] neg_hi:[0,1]
	v_pk_add_f32 v[158:159], v[140:141], v[154:155] op_sel:[0,1] op_sel_hi:[1,0] neg_hi:[0,1]
	v_pk_add_f32 v[140:141], v[140:141], v[154:155] op_sel:[0,1] op_sel_hi:[1,0] neg_lo:[0,1]
	v_pk_add_f32 v[154:155], v[134:135], v[144:145]
	v_pk_add_f32 v[134:135], v[134:135], v[144:145] neg_lo:[0,1] neg_hi:[0,1]
	v_pk_add_f32 v[144:145], v[142:143], v[132:133] op_sel:[0,1] op_sel_hi:[1,0] neg_hi:[0,1]
	v_pk_add_f32 v[132:133], v[142:143], v[132:133] op_sel:[0,1] op_sel_hi:[1,0] neg_lo:[0,1]
	v_pk_add_f32 v[142:143], v[130:131], v[176:177]
	v_pk_mul_f32 v[24:25], v[72:73], v[10:11] op_sel:[0,1] op_sel_hi:[1,0]
	v_pk_mul_f32 v[34:35], v[34:35], v[142:143] op_sel:[0,1] op_sel_hi:[1,0]
	v_pk_mul_f32 v[32:33], v[54:55], v[10:11] op_sel:[0,1] op_sel_hi:[1,0]
	v_pk_fma_f32 v[40:41], v[30:31], v[10:11], v[40:41] op_sel_hi:[0,1,1]
	v_pk_mul_f32 v[56:57], v[72:73], v[20:21] op_sel:[0,1] op_sel_hi:[1,0]
	v_pk_mul_f32 v[62:63], v[54:55], v[20:21] op_sel:[0,1] op_sel_hi:[1,0]
	v_pk_fma_f32 v[66:67], v[30:31], v[20:21], v[66:67] op_sel_hi:[0,1,1]
	v_pk_mul_f32 v[74:75], v[72:73], v[26:27] op_sel:[0,1] op_sel_hi:[1,0]
	v_pk_mul_f32 v[78:79], v[54:55], v[26:27] op_sel:[0,1] op_sel_hi:[1,0]
	v_pk_fma_f32 v[82:83], v[30:31], v[26:27], v[82:83] op_sel_hi:[0,1,1]
	v_pk_mul_f32 v[88:89], v[72:73], v[36:37] op_sel:[0,1] op_sel_hi:[1,0]
	v_pk_mul_f32 v[92:93], v[54:55], v[36:37] op_sel:[0,1] op_sel_hi:[1,0]
	v_pk_fma_f32 v[96:97], v[30:31], v[36:37], v[96:97] op_sel_hi:[0,1,1]
	v_pk_mul_f32 v[102:103], v[72:73], v[48:49] op_sel:[0,1] op_sel_hi:[1,0]
	v_pk_mul_f32 v[106:107], v[54:55], v[48:49] op_sel:[0,1] op_sel_hi:[1,0]
	v_pk_fma_f32 v[110:111], v[30:31], v[48:49], v[110:111] op_sel_hi:[0,1,1]
	v_pk_mul_f32 v[116:117], v[52:53], v[72:73] op_sel:[1,0] op_sel_hi:[0,1]
	v_pk_mul_f32 v[120:121], v[54:55], v[52:53] op_sel:[0,1] op_sel_hi:[1,0]
	v_pk_fma_f32 v[124:125], v[30:31], v[52:53], v[124:125] op_sel_hi:[0,1,1]
	v_pk_add_f32 v[130:131], v[130:131], v[176:177] neg_lo:[0,1] neg_hi:[0,1]
	v_pk_add_f32 v[176:177], v[136:137], v[182:183] op_sel:[0,1] op_sel_hi:[1,0] neg_hi:[0,1]
	v_pk_add_f32 v[136:137], v[136:137], v[182:183] op_sel:[0,1] op_sel_hi:[1,0] neg_lo:[0,1]
	v_pk_add_f32 v[182:183], v[178:179], v[186:187]
	v_pk_add_f32 v[178:179], v[178:179], v[186:187] neg_lo:[0,1] neg_hi:[0,1]
	v_pk_add_f32 v[186:187], v[160:161], v[180:181] op_sel:[0,1] op_sel_hi:[1,0] neg_hi:[0,1]
	v_pk_add_f32 v[160:161], v[160:161], v[180:181] op_sel:[0,1] op_sel_hi:[1,0] neg_lo:[0,1]
	v_pk_add_f32 v[180:181], v[168:169], v[188:189]
	v_pk_fma_f32 v[30:31], v[30:31], v[142:143], v[34:35] op_sel_hi:[0,1,1]
	v_pk_mul_f32 v[34:35], v[54:55], v[152:153] op_sel:[0,1] op_sel_hi:[1,0]
	v_xor_b32_e32 v6, 0x80000000, v3
	v_pk_fma_f32 v[8:9], v[44:45], v[4:5], v[8:9] op_sel_hi:[0,1,1]
	v_pk_fma_f32 v[24:25], v[46:47], v[10:11], v[24:25] op_sel_hi:[0,1,1]
	v_pk_fma_f32 v[32:33], v[44:45], v[10:11], v[32:33] op_sel_hi:[0,1,1]
	v_pk_fma_f32 v[56:57], v[46:47], v[20:21], v[56:57] op_sel_hi:[0,1,1]
	v_pk_fma_f32 v[62:63], v[44:45], v[20:21], v[62:63] op_sel_hi:[0,1,1]
	v_pk_fma_f32 v[74:75], v[46:47], v[26:27], v[74:75] op_sel_hi:[0,1,1]
	v_pk_fma_f32 v[78:79], v[44:45], v[26:27], v[78:79] op_sel_hi:[0,1,1]
	v_pk_fma_f32 v[88:89], v[46:47], v[36:37], v[88:89] op_sel_hi:[0,1,1]
	v_pk_fma_f32 v[92:93], v[44:45], v[36:37], v[92:93] op_sel_hi:[0,1,1]
	v_pk_fma_f32 v[102:103], v[46:47], v[48:49], v[102:103] op_sel_hi:[0,1,1]
	v_pk_fma_f32 v[106:107], v[44:45], v[48:49], v[106:107] op_sel_hi:[0,1,1]
	v_xor_b32_e32 v114, 0x80000000, v49
	v_pk_fma_f32 v[116:117], v[52:53], v[46:47], v[116:117] op_sel_hi:[1,0,1]
	v_pk_fma_f32 v[120:121], v[44:45], v[52:53], v[120:121] op_sel_hi:[0,1,1]
	v_mov_b32_e32 v115, v49
	v_mov_b32_e32 v7, v3
	v_pk_add_f32 v[168:169], v[168:169], v[188:189] neg_lo:[0,1] neg_hi:[0,1]
	v_pk_add_f32 v[188:189], v[170:171], v[184:185] op_sel:[0,1] op_sel_hi:[1,0] neg_hi:[0,1]
	v_pk_add_f32 v[170:171], v[170:171], v[184:185] op_sel:[0,1] op_sel_hi:[1,0] neg_lo:[0,1]
	v_pk_add_f32 v[184:185], v[164:165], v[172:173]
	v_pk_add_f32 v[164:165], v[164:165], v[172:173] neg_lo:[0,1] neg_hi:[0,1]
	v_pk_add_f32 v[172:173], v[128:129], v[166:167] op_sel:[0,1] op_sel_hi:[1,0] neg_hi:[0,1]
	v_pk_add_f32 v[128:129], v[128:129], v[166:167] op_sel:[0,1] op_sel_hi:[1,0] neg_lo:[0,1]
	v_pk_fma_f32 v[34:35], v[44:45], v[152:153], v[34:35] op_sel_hi:[0,1,1]
	v_pk_mul_f32 v[44:45], v[72:73], v[180:181] op_sel:[0,1] op_sel_hi:[1,0]
	v_xor_b32_e32 v12, 0x80000000, v9
	v_xor_b32_e32 v16, 0x80000000, v15
	v_xor_b32_e32 v22, 0x80000000, v5
	v_xor_b32_e32 v28, 0x80000000, v25
	v_xor_b32_e32 v38, 0x80000000, v33
	v_xor_b32_e32 v42, 0x80000000, v41
	v_xor_b32_e32 v50, 0x80000000, v11
	v_xor_b32_e32 v60, 0x80000000, v57
	v_xor_b32_e32 v64, 0x80000000, v63
	v_xor_b32_e32 v68, 0x80000000, v67
	v_xor_b32_e32 v70, 0x80000000, v21
	v_xor_b32_e32 v76, 0x80000000, v75
	v_xor_b32_e32 v80, 0x80000000, v79
	v_xor_b32_e32 v84, 0x80000000, v83
	v_xor_b32_e32 v86, 0x80000000, v27
	v_xor_b32_e32 v90, 0x80000000, v89
	v_xor_b32_e32 v94, 0x80000000, v93
	v_xor_b32_e32 v98, 0x80000000, v97
	v_xor_b32_e32 v100, 0x80000000, v37
	v_xor_b32_e32 v104, 0x80000000, v103
	v_xor_b32_e32 v108, 0x80000000, v107
	v_xor_b32_e32 v112, 0x80000000, v111
	v_xor_b32_e32 v118, 0x80000000, v117
	v_xor_b32_e32 v122, 0x80000000, v121
	v_xor_b32_e32 v126, 0x80000000, v125
	v_mov_b32_e32 v127, v125
	v_mov_b32_e32 v123, v121
	v_mov_b32_e32 v119, v117
	v_mov_b32_e32 v113, v111
	v_mov_b32_e32 v109, v107
	v_mov_b32_e32 v105, v103
	v_mov_b32_e32 v101, v37
	v_mov_b32_e32 v99, v97
	v_mov_b32_e32 v95, v93
	v_mov_b32_e32 v91, v89
	v_mov_b32_e32 v87, v27
	v_mov_b32_e32 v85, v83
	v_mov_b32_e32 v81, v79
	v_mov_b32_e32 v77, v75
	v_mov_b32_e32 v71, v21
	v_mov_b32_e32 v69, v67
	v_mov_b32_e32 v65, v63
	v_mov_b32_e32 v61, v57
	v_mov_b32_e32 v51, v11
	v_mov_b32_e32 v43, v41
	v_mov_b32_e32 v39, v33
	v_mov_b32_e32 v29, v25
	v_mov_b32_e32 v23, v5
	v_mov_b32_e32 v17, v15
	v_mov_b32_e32 v13, v9
	v_pk_fma_f32 v[44:45], v[46:47], v[180:181], v[44:45] op_sel_hi:[0,1,1]
	v_pk_mul_f32 v[46:47], v[58:59], v[192:193] op_sel:[0,1] op_sel_hi:[1,0]
	v_pk_mul_f32 v[72:73], v[114:115], v[194:195] op_sel:[0,1] op_sel_hi:[1,0]
	v_pk_mul_f32 v[6:7], v[128:129], v[6:7] op_sel:[1,0] op_sel_hi:[0,1]
	v_pk_fma_f32 v[46:47], v[52:53], v[192:193], v[46:47] op_sel_hi:[0,1,1]
	v_pk_mul_f32 v[52:53], v[126:127], v[182:183] op_sel:[0,1] op_sel_hi:[1,0]
	v_pk_mul_f32 v[54:55], v[122:123], v[154:155] op_sel:[0,1] op_sel_hi:[1,0]
	v_pk_mul_f32 v[58:59], v[118:119], v[184:185] op_sel:[0,1] op_sel_hi:[1,0]
	v_pk_fma_f32 v[48:49], v[48:49], v[194:195], v[72:73] op_sel_hi:[0,1,1]
	v_pk_mul_f32 v[72:73], v[112:113], v[176:177] op_sel:[0,1] op_sel_hi:[1,0]
	v_pk_mul_f32 v[108:109], v[108:109], v[158:159] op_sel:[0,1] op_sel_hi:[1,0]
	v_pk_mul_f32 v[104:105], v[104:105], v[188:189] op_sel:[0,1] op_sel_hi:[1,0]
	v_pk_mul_f32 v[100:101], v[100:101], v[156:157] op_sel:[0,1] op_sel_hi:[1,0]
	v_pk_mul_f32 v[98:99], v[98:99], v[186:187] op_sel:[0,1] op_sel_hi:[1,0]
	v_pk_mul_f32 v[94:95], v[94:95], v[144:145] op_sel:[0,1] op_sel_hi:[1,0]
	v_pk_mul_f32 v[90:91], v[90:91], v[172:173] op_sel:[0,1] op_sel_hi:[1,0]
	v_pk_mul_f32 v[86:87], v[174:175], v[86:87] op_sel:[1,0] op_sel_hi:[0,1]
	v_pk_mul_f32 v[84:85], v[130:131], v[84:85] op_sel:[1,0] op_sel_hi:[0,1]
	v_pk_mul_f32 v[80:81], v[138:139], v[80:81] op_sel:[1,0] op_sel_hi:[0,1]
	v_pk_mul_f32 v[76:77], v[168:169], v[76:77] op_sel:[1,0] op_sel_hi:[0,1]
	v_pk_mul_f32 v[70:71], v[148:149], v[70:71] op_sel:[1,0] op_sel_hi:[0,1]
	v_pk_mul_f32 v[68:69], v[178:179], v[68:69] op_sel:[1,0] op_sel_hi:[0,1]
	v_pk_mul_f32 v[64:65], v[134:135], v[64:65] op_sel:[1,0] op_sel_hi:[0,1]
	v_pk_mul_f32 v[60:61], v[164:165], v[60:61] op_sel:[1,0] op_sel_hi:[0,1]
	v_pk_mul_f32 v[50:51], v[190:191], v[50:51] op_sel:[1,0] op_sel_hi:[0,1]
	v_pk_mul_f32 v[42:43], v[136:137], v[42:43] op_sel:[1,0] op_sel_hi:[0,1]
	v_pk_mul_f32 v[38:39], v[140:141], v[38:39] op_sel:[1,0] op_sel_hi:[0,1]
	v_pk_mul_f32 v[28:29], v[170:171], v[28:29] op_sel:[1,0] op_sel_hi:[0,1]
	v_pk_mul_f32 v[22:23], v[150:151], v[22:23] op_sel:[1,0] op_sel_hi:[0,1]
	v_pk_mul_f32 v[16:17], v[160:161], v[16:17] op_sel:[1,0] op_sel_hi:[0,1]
	v_pk_mul_f32 v[12:13], v[132:133], v[12:13] op_sel:[1,0] op_sel_hi:[0,1]
	v_pk_fma_f32 v[2:3], v[128:129], v[2:3], v[6:7] op_sel_hi:[1,0,1]
	v_pk_fma_f32 v[52:53], v[124:125], v[182:183], v[52:53] op_sel_hi:[0,1,1]
	v_pk_fma_f32 v[54:55], v[120:121], v[154:155], v[54:55] op_sel_hi:[0,1,1]
	v_pk_fma_f32 v[58:59], v[116:117], v[184:185], v[58:59] op_sel_hi:[0,1,1]
	v_pk_fma_f32 v[72:73], v[110:111], v[176:177], v[72:73] op_sel_hi:[0,1,1]
	v_pk_fma_f32 v[106:107], v[106:107], v[158:159], v[108:109] op_sel_hi:[0,1,1]
	v_pk_fma_f32 v[102:103], v[102:103], v[188:189], v[104:105] op_sel_hi:[0,1,1]
	v_pk_fma_f32 v[36:37], v[36:37], v[156:157], v[100:101] op_sel_hi:[0,1,1]
	v_pk_fma_f32 v[96:97], v[96:97], v[186:187], v[98:99] op_sel_hi:[0,1,1]
	v_pk_fma_f32 v[92:93], v[92:93], v[144:145], v[94:95] op_sel_hi:[0,1,1]
	v_pk_fma_f32 v[88:89], v[88:89], v[172:173], v[90:91] op_sel_hi:[0,1,1]
	v_pk_fma_f32 v[26:27], v[174:175], v[26:27], v[86:87] op_sel_hi:[1,0,1]
	v_pk_fma_f32 v[82:83], v[130:131], v[82:83], v[84:85] op_sel_hi:[1,0,1]
	v_pk_fma_f32 v[78:79], v[138:139], v[78:79], v[80:81] op_sel_hi:[1,0,1]
	v_pk_fma_f32 v[74:75], v[168:169], v[74:75], v[76:77] op_sel_hi:[1,0,1]
	v_pk_fma_f32 v[20:21], v[148:149], v[20:21], v[70:71] op_sel_hi:[1,0,1]
	v_pk_fma_f32 v[66:67], v[178:179], v[66:67], v[68:69] op_sel_hi:[1,0,1]
	v_pk_fma_f32 v[62:63], v[134:135], v[62:63], v[64:65] op_sel_hi:[1,0,1]
	v_pk_fma_f32 v[56:57], v[164:165], v[56:57], v[60:61] op_sel_hi:[1,0,1]
	v_pk_fma_f32 v[10:11], v[190:191], v[10:11], v[50:51] op_sel_hi:[1,0,1]
	v_pk_fma_f32 v[40:41], v[136:137], v[40:41], v[42:43] op_sel_hi:[1,0,1]
	v_pk_fma_f32 v[32:33], v[140:141], v[32:33], v[38:39] op_sel_hi:[1,0,1]
	v_pk_fma_f32 v[24:25], v[170:171], v[24:25], v[28:29] op_sel_hi:[1,0,1]
	v_pk_fma_f32 v[4:5], v[150:151], v[4:5], v[22:23] op_sel_hi:[1,0,1]
	v_pk_fma_f32 v[14:15], v[160:161], v[14:15], v[16:17] op_sel_hi:[1,0,1]
	v_pk_fma_f32 v[8:9], v[132:133], v[8:9], v[12:13] op_sel_hi:[1,0,1]
	ds_write_b64 v18, v[162:163]
	ds_write_b64 v18, v[26:27] offset:2112
	ds_write_b64 v18, v[48:49] offset:4224
	ds_write_b64 v18, v[10:11] offset:6336
	ds_write_b64 v18, v[46:47] offset:8448
	ds_write_b64 v18, v[20:21] offset:10560
	ds_write_b64 v18, v[36:37] offset:12672
	ds_write_b64 v18, v[4:5] offset:14784
	ds_write_b64 v18, v[34:35] offset:16896
	ds_write_b64 v18, v[78:79] offset:19008
	ds_write_b64 v18, v[106:107] offset:21120
	ds_write_b64 v18, v[32:33] offset:23232
	ds_write_b64 v18, v[54:55] offset:25344
	ds_write_b64 v18, v[62:63] offset:27456
	ds_write_b64 v18, v[92:93] offset:29568
	ds_write_b64 v18, v[8:9] offset:31680
	ds_write_b64 v18, v[30:31] offset:33792
	ds_write_b64 v18, v[82:83] offset:35904
	ds_write_b64 v18, v[72:73] offset:38016
	ds_write_b64 v18, v[40:41] offset:40128
	ds_write_b64 v18, v[52:53] offset:42240
	ds_write_b64 v18, v[66:67] offset:44352
	ds_write_b64 v18, v[96:97] offset:46464
	ds_write_b64 v18, v[14:15] offset:48576
	ds_write_b64 v18, v[44:45] offset:50688
	ds_write_b64 v18, v[74:75] offset:52800
	ds_write_b64 v18, v[102:103] offset:54912
	ds_write_b64 v18, v[24:25] offset:57024
	ds_write_b64 v18, v[58:59] offset:59136
	ds_write_b64 v18, v[56:57] offset:61248
	ds_write_b64 v18, v[88:89] offset:63360
	ds_write_b64 v18, v[2:3] offset:65472
	v_mov_b32_e32 v3, v210
	s_waitcnt lgkmcnt(0)
	s_barrier
	s_add_i32 s64, s62, s48
	v_and_b32_e32 v5, 15, v3
	v_cvt_f32_ubyte0_e32 v2, v5
	v_mul_f32_e32 v4, 0x3b800000, v2
	v_sin_f32_e32 v2, v4
	v_cos_f32_e32 v4, v4
	v_lshlrev_b32_e32 v64, 3, v5
	v_lshlrev_b32_e32 v18, 4, v3
	v_xor_b32_e32 v5, 0x80000000, v2
	v_mov_b32_e32 v3, v5
	v_pk_mul_f32 v[6:7], v[4:5], v[2:3] op_sel:[1,0] op_sel_hi:[0,1]
	v_pk_fma_f32 v[6:7], v[4:5], v[4:5], v[6:7] op_sel_hi:[1,0,1]
	s_ashr_i32 s65, s64, 31
	v_xor_b32_e32 v12, 0x80000000, v7
	v_mov_b32_e32 v13, v7
	v_pk_mul_f32 v[10:11], v[6:7], v[12:13] op_sel:[1,0] op_sel_hi:[0,1]
	v_pk_fma_f32 v[10:11], v[6:7], v[6:7], v[10:11] op_sel_hi:[1,0,1]
	v_pk_mul_f32 v[8:9], v[2:3], v[6:7] op_sel:[0,1] op_sel_hi:[1,0]
	v_xor_b32_e32 v14, 0x80000000, v11
	v_mov_b32_e32 v15, v11
	v_pk_mul_f32 v[32:33], v[10:11], v[14:15] op_sel:[1,0] op_sel_hi:[0,1]
	v_pk_fma_f32 v[32:33], v[10:11], v[10:11], v[32:33] op_sel_hi:[1,0,1]
	v_pk_mul_f32 v[16:17], v[2:3], v[10:11] op_sel:[0,1] op_sel_hi:[1,0]
	v_pk_mul_f32 v[48:49], v[14:15], v[32:33] op_sel:[0,1] op_sel_hi:[1,0]
	v_pk_mul_f32 v[36:37], v[2:3], v[32:33] op_sel:[0,1] op_sel_hi:[1,0]
	v_pk_fma_f32 v[48:49], v[10:11], v[32:33], v[48:49] op_sel_hi:[0,1,1]
	v_pk_mul_f32 v[52:53], v[2:3], v[48:49] op_sel:[0,1] op_sel_hi:[1,0]
	v_pk_fma_f32 v[8:9], v[4:5], v[6:7], v[8:9] op_sel_hi:[0,1,1]
	v_pk_fma_f32 v[16:17], v[4:5], v[10:11], v[16:17] op_sel_hi:[0,1,1]
	v_pk_fma_f32 v[36:37], v[4:5], v[32:33], v[36:37] op_sel_hi:[0,1,1]
	v_pk_fma_f32 v[52:53], v[4:5], v[48:49], v[52:53] op_sel_hi:[0,1,1]
	v_and_b32_e32 v5, 0xffffff00, v18
	v_lshlrev_b32_e32 v18, 3, v5
	v_add3_u32 v18, 0, v64, v18
	v_ashrrev_i32_e32 v64, 2, v5
	v_add_u32_e32 v106, v18, v64
	ds_read2_b64 v[64:67], v106 offset1:16
	ds_read2_b64 v[68:71], v106 offset0:33 offset1:49
	ds_read2_b64 v[72:75], v106 offset0:66 offset1:82
	ds_read2_b64 v[76:79], v106 offset0:132 offset1:148
	ds_read2_b64 v[80:83], v106 offset0:99 offset1:115
	ds_read2_b64 v[84:87], v106 offset0:165 offset1:181
	ds_read2_b64 v[88:91], v106 offset0:198 offset1:214
	ds_read2_b64 v[92:95], v106 offset0:231 offset1:247
	s_waitcnt lgkmcnt(4)
	v_pk_add_f32 v[96:97], v[64:65], v[76:77]
	v_pk_add_f32 v[64:65], v[64:65], v[76:77] neg_lo:[0,1] neg_hi:[0,1]
	v_pk_add_f32 v[76:77], v[66:67], v[78:79]
	v_pk_add_f32 v[66:67], v[66:67], v[78:79] neg_lo:[0,1] neg_hi:[0,1]
	s_waitcnt lgkmcnt(1)
	v_pk_add_f32 v[98:99], v[74:75], v[90:91]
	v_pk_mul_f32 v[78:79], v[66:67], s[18:19]
	v_pk_add_f32 v[74:75], v[74:75], v[90:91] neg_lo:[0,1] neg_hi:[0,1]
	v_pk_fma_f32 v[66:67], v[66:67], s[16:17], v[78:79] op_sel:[0,0,1] op_sel_hi:[1,0,0]
	v_pk_add_f32 v[78:79], v[68:69], v[84:85]
	v_pk_add_f32 v[68:69], v[68:69], v[84:85] neg_lo:[0,1] neg_hi:[0,1]
	v_pk_mul_f32 v[90:91], v[74:75], s[40:41]
	v_pk_mul_f32 v[84:85], v[68:69], s[36:37]
	v_pk_fma_f32 v[74:75], v[74:75], s[68:69], v[90:91] op_sel:[0,0,1] op_sel_hi:[1,0,0] neg_lo:[1,0,0] neg_hi:[1,0,0]
	v_pk_fma_f32 v[68:69], v[68:69], s[66:67], v[84:85] op_sel:[0,0,1] op_sel_hi:[1,0,0]
	v_pk_add_f32 v[84:85], v[70:71], v[86:87]
	v_pk_add_f32 v[70:71], v[70:71], v[86:87] neg_lo:[0,1] neg_hi:[0,1]
	s_waitcnt lgkmcnt(0)
	v_pk_add_f32 v[90:91], v[80:81], v[92:93]
	v_pk_add_f32 v[80:81], v[80:81], v[92:93] neg_lo:[0,1] neg_hi:[0,1]
	v_pk_mul_f32 v[86:87], v[70:71], s[40:41]
	v_pk_mul_f32 v[92:93], v[80:81], s[36:37]
	v_pk_fma_f32 v[70:71], v[70:71], s[68:69], v[86:87] op_sel:[0,0,1] op_sel_hi:[1,0,0]
	v_pk_add_f32 v[86:87], v[72:73], v[88:89]
	v_pk_add_f32 v[88:89], v[72:73], v[88:89] neg_lo:[0,1] neg_hi:[0,1]
	v_pk_fma_f32 v[80:81], v[80:81], s[66:67], v[92:93] op_sel:[0,0,1] op_sel_hi:[1,0,0] neg_lo:[1,0,0] neg_hi:[1,0,0]
	v_pk_add_f32 v[92:93], v[82:83], v[94:95]
	v_pk_add_f32 v[82:83], v[82:83], v[94:95] op_sel:[1,1] op_sel_hi:[0,0] neg_lo:[0,1] neg_hi:[0,1]
	v_pk_mul_f32 v[94:95], v[82:83], s[18:19] op_sel:[1,0] op_sel_hi:[0,1]
	s_nop 0
	v_pk_fma_f32 v[82:83], v[82:83], s[16:17], v[94:95] op_sel:[1,0,1] op_sel_hi:[0,0,0] neg_lo:[1,0,0] neg_hi:[1,0,0]
	v_pk_add_f32 v[94:95], v[96:97], v[86:87]
	v_pk_add_f32 v[86:87], v[96:97], v[86:87] neg_lo:[0,1] neg_hi:[0,1]
	v_pk_add_f32 v[96:97], v[76:77], v[98:99]
	v_pk_add_f32 v[76:77], v[76:77], v[98:99] neg_lo:[0,1] neg_hi:[0,1]
	v_pk_add_f32 v[100:101], v[84:85], v[92:93]
	v_pk_add_f32 v[84:85], v[84:85], v[92:93] neg_lo:[0,1] neg_hi:[0,1]
	v_pk_add_f32 v[72:73], v[64:65], v[88:89] op_sel:[0,1] op_sel_hi:[1,0] neg_hi:[0,1]
	v_pk_add_f32 v[64:65], v[64:65], v[88:89] op_sel:[0,1] op_sel_hi:[1,0] neg_lo:[0,1]
	v_pk_add_f32 v[88:89], v[66:67], v[74:75]
	v_pk_add_f32 v[66:67], v[66:67], v[74:75] neg_lo:[0,1] neg_hi:[0,1]
	v_pk_mul_f32 v[98:99], v[76:77], s[36:37]
	v_pk_mul_f32 v[92:93], v[84:85], s[36:37]
	v_pk_mul_f32 v[74:75], v[66:67], s[36:37]
	v_pk_fma_f32 v[76:77], v[76:77], s[66:67], v[98:99] op_sel:[0,0,1] op_sel_hi:[1,0,0]
	v_pk_add_f32 v[98:99], v[78:79], v[90:91]
	v_pk_add_f32 v[90:91], v[78:79], v[90:91] neg_lo:[0,1] neg_hi:[0,1]
	v_pk_fma_f32 v[84:85], v[84:85], s[66:67], v[92:93] op_sel:[0,0,1] op_sel_hi:[1,0,0] neg_lo:[1,0,0] neg_hi:[1,0,0]
	v_pk_fma_f32 v[66:67], v[66:67], s[66:67], v[74:75] op_sel:[0,0,1] op_sel_hi:[1,0,0]
	v_pk_add_f32 v[74:75], v[68:69], v[80:81]
	v_pk_add_f32 v[92:93], v[70:71], v[82:83]
	v_pk_add_f32 v[70:71], v[70:71], v[82:83] neg_lo:[0,1] neg_hi:[0,1]
	v_pk_add_f32 v[68:69], v[68:69], v[80:81] neg_lo:[0,1] neg_hi:[0,1]
	v_pk_mul_f32 v[82:83], v[70:71], s[36:37]
	v_pk_add_f32 v[102:103], v[72:73], v[74:75]
	v_pk_add_f32 v[72:73], v[72:73], v[74:75] neg_lo:[0,1] neg_hi:[0,1]
	v_pk_add_f32 v[74:75], v[88:89], v[92:93]
	v_pk_add_f32 v[92:93], v[88:89], v[92:93] neg_lo:[0,1] neg_hi:[0,1]
	v_xor_b32_e32 v20, 0x80000000, v9
	v_mov_b32_e32 v21, v9
	v_pk_mul_f32 v[24:25], v[12:13], v[10:11] op_sel:[0,1] op_sel_hi:[1,0]
	v_xor_b32_e32 v81, 0x80000000, v68
	v_pk_fma_f32 v[70:71], v[70:71], s[66:67], v[82:83] op_sel:[0,0,1] op_sel_hi:[1,0,0] neg_lo:[1,0,0] neg_hi:[1,0,0]
	v_pk_add_f32 v[78:79], v[86:87], v[90:91] op_sel:[0,1] op_sel_hi:[1,0] neg_hi:[0,1]
	v_pk_add_f32 v[86:87], v[86:87], v[90:91] op_sel:[0,1] op_sel_hi:[1,0] neg_lo:[0,1]
	v_pk_add_f32 v[90:91], v[76:77], v[84:85]
	v_pk_add_f32 v[84:85], v[76:77], v[84:85] neg_lo:[0,1] neg_hi:[0,1]
	v_mov_b32_e32 v80, v69
	v_xor_b32_e32 v22, 0x80000000, v17
	v_mov_b32_e32 v23, v17
	v_pk_fma_f32 v[24:25], v[6:7], v[10:11], v[24:25] op_sel_hi:[0,1,1]
	v_pk_mul_f32 v[28:29], v[10:11], v[20:21] op_sel:[1,0] op_sel_hi:[0,1]
	v_pk_add_f32 v[68:69], v[64:65], v[80:81]
	v_pk_add_f32 v[64:65], v[64:65], v[80:81] neg_lo:[0,1] neg_hi:[0,1]
	v_pk_add_f32 v[80:81], v[66:67], v[70:71]
	v_pk_add_f32 v[70:71], v[66:67], v[70:71] neg_lo:[0,1] neg_hi:[0,1]
	v_pk_add_f32 v[88:89], v[72:73], v[92:93] op_sel:[0,1] op_sel_hi:[1,0] neg_hi:[0,1]
	v_xor_b32_e32 v26, 0x80000000, v25
	v_mov_b32_e32 v27, v25
	v_pk_fma_f32 v[28:29], v[10:11], v[8:9], v[28:29] op_sel_hi:[1,0,1]
	v_pk_add_f32 v[76:77], v[86:87], v[84:85] op_sel:[0,1] op_sel_hi:[1,0] neg_hi:[0,1]
	v_pk_add_f32 v[72:73], v[72:73], v[92:93] op_sel:[0,1] op_sel_hi:[1,0] neg_lo:[0,1]
	v_pk_mul_f32 v[92:93], v[22:23], v[88:89] op_sel:[0,1] op_sel_hi:[1,0]
	v_xor_b32_e32 v30, 0x80000000, v29
	v_mov_b32_e32 v31, v29
	v_pk_add_f32 v[82:83], v[94:95], v[98:99]
	v_pk_add_f32 v[94:95], v[94:95], v[98:99] neg_lo:[0,1] neg_hi:[0,1]
	v_pk_add_f32 v[98:99], v[96:97], v[100:101]
	v_pk_add_f32 v[66:67], v[64:65], v[70:71] op_sel:[0,1] op_sel_hi:[1,0] neg_hi:[0,1]
	v_pk_fma_f32 v[88:89], v[16:17], v[88:89], v[92:93] op_sel_hi:[0,1,1]
	v_pk_mul_f32 v[92:93], v[26:27], v[76:77] op_sel:[0,1] op_sel_hi:[1,0]
	v_xor_b32_e32 v34, 0x80000000, v33
	v_mov_b32_e32 v35, v33
	v_pk_mul_f32 v[40:41], v[12:13], v[32:33] op_sel:[0,1] op_sel_hi:[1,0]
	v_pk_add_f32 v[104:105], v[82:83], v[98:99]
	v_pk_add_f32 v[82:83], v[82:83], v[98:99] neg_lo:[0,1] neg_hi:[0,1]
	v_pk_fma_f32 v[76:77], v[24:25], v[76:77], v[92:93] op_sel_hi:[0,1,1]
	v_pk_mul_f32 v[92:93], v[30:31], v[66:67] op_sel:[0,1] op_sel_hi:[1,0]
	v_xor_b32_e32 v38, 0x80000000, v37
	v_mov_b32_e32 v39, v37
	v_pk_fma_f32 v[40:41], v[6:7], v[32:33], v[40:41] op_sel_hi:[0,1,1]
	v_pk_mul_f32 v[44:45], v[20:21], v[32:33] op_sel:[0,1] op_sel_hi:[1,0]
	v_pk_add_f32 v[84:85], v[86:87], v[84:85] op_sel:[0,1] op_sel_hi:[1,0] neg_lo:[0,1]
	v_pk_add_f32 v[86:87], v[102:103], v[74:75]
	v_pk_add_f32 v[74:75], v[102:103], v[74:75] neg_lo:[0,1] neg_hi:[0,1]
	v_pk_fma_f32 v[66:67], v[28:29], v[66:67], v[92:93] op_sel_hi:[0,1,1]
	v_pk_mul_f32 v[92:93], v[34:35], v[82:83] op_sel:[0,1] op_sel_hi:[1,0]
	v_xor_b32_e32 v42, 0x80000000, v41
	v_mov_b32_e32 v43, v41
	v_pk_fma_f32 v[44:45], v[8:9], v[32:33], v[44:45] op_sel_hi:[0,1,1]
	v_pk_add_f32 v[100:101], v[96:97], v[100:101] neg_lo:[0,1] neg_hi:[0,1]
	v_pk_add_f32 v[98:99], v[78:79], v[90:91]
	v_pk_add_f32 v[78:79], v[78:79], v[90:91] neg_lo:[0,1] neg_hi:[0,1]
	v_pk_fma_f32 v[82:83], v[32:33], v[82:83], v[92:93] op_sel_hi:[0,1,1]
	v_pk_mul_f32 v[92:93], v[38:39], v[74:75] op_sel:[0,1] op_sel_hi:[1,0]
	v_xor_b32_e32 v46, 0x80000000, v45
	v_mov_b32_e32 v47, v45
	v_pk_add_f32 v[90:91], v[68:69], v[80:81]
	v_pk_add_f32 v[68:69], v[68:69], v[80:81] neg_lo:[0,1] neg_hi:[0,1]
	v_pk_fma_f32 v[74:75], v[36:37], v[74:75], v[92:93] op_sel_hi:[0,1,1]
	v_pk_mul_f32 v[92:93], v[42:43], v[78:79] op_sel:[0,1] op_sel_hi:[1,0]
	v_xor_b32_e32 v50, 0x80000000, v49
	v_mov_b32_e32 v51, v49
	v_pk_mul_f32 v[56:57], v[12:13], v[48:49] op_sel:[0,1] op_sel_hi:[1,0]
	v_pk_add_f32 v[96:97], v[94:95], v[100:101] op_sel:[0,1] op_sel_hi:[1,0] neg_hi:[0,1]
	v_pk_add_f32 v[94:95], v[94:95], v[100:101] op_sel:[0,1] op_sel_hi:[1,0] neg_lo:[0,1]
	v_pk_fma_f32 v[78:79], v[40:41], v[78:79], v[92:93] op_sel_hi:[0,1,1]
	v_pk_mul_f32 v[92:93], v[46:47], v[68:69] op_sel:[0,1] op_sel_hi:[1,0]
	v_xor_b32_e32 v54, 0x80000000, v53
	v_mov_b32_e32 v55, v53
	v_pk_fma_f32 v[56:57], v[6:7], v[48:49], v[56:57] op_sel_hi:[0,1,1]
	v_pk_mul_f32 v[60:61], v[20:21], v[48:49] op_sel:[0,1] op_sel_hi:[1,0]
	v_pk_fma_f32 v[68:69], v[44:45], v[68:69], v[92:93] op_sel_hi:[0,1,1]
	v_pk_mul_f32 v[92:93], v[50:51], v[94:95] op_sel:[0,1] op_sel_hi:[1,0]
	v_xor_b32_e32 v58, 0x80000000, v57
	v_mov_b32_e32 v59, v57
	v_pk_fma_f32 v[60:61], v[8:9], v[48:49], v[60:61] op_sel_hi:[0,1,1]
	v_pk_add_f32 v[64:65], v[64:65], v[70:71] op_sel:[0,1] op_sel_hi:[1,0] neg_lo:[0,1]
	v_pk_mul_f32 v[70:71], v[2:3], v[86:87] op_sel:[0,1] op_sel_hi:[1,0]
	v_pk_fma_f32 v[92:93], v[48:49], v[94:95], v[92:93] op_sel_hi:[0,1,1]
	v_pk_mul_f32 v[94:95], v[54:55], v[72:73] op_sel:[0,1] op_sel_hi:[1,0]
	v_xor_b32_e32 v62, 0x80000000, v61
	v_mov_b32_e32 v63, v61
	v_pk_fma_f32 v[70:71], v[4:5], v[86:87], v[70:71] op_sel_hi:[0,1,1]
	v_pk_mul_f32 v[86:87], v[20:21], v[90:91] op_sel:[0,1] op_sel_hi:[1,0]
	v_pk_fma_f32 v[72:73], v[52:53], v[72:73], v[94:95] op_sel_hi:[0,1,1]
	v_pk_mul_f32 v[94:95], v[58:59], v[84:85] op_sel:[0,1] op_sel_hi:[1,0]
	v_add_u32_e32 v5, 0x2000, v5
	v_pk_mul_f32 v[80:81], v[12:13], v[98:99] op_sel:[0,1] op_sel_hi:[1,0]
	v_pk_fma_f32 v[86:87], v[8:9], v[90:91], v[86:87] op_sel_hi:[0,1,1]
	v_pk_mul_f32 v[90:91], v[14:15], v[96:97] op_sel:[0,1] op_sel_hi:[1,0]
	v_pk_fma_f32 v[84:85], v[56:57], v[84:85], v[94:95] op_sel_hi:[0,1,1]
	v_pk_mul_f32 v[94:95], v[62:63], v[64:65] op_sel:[0,1] op_sel_hi:[1,0]
	v_ashrrev_i32_e32 v5, 2, v5
	v_pk_fma_f32 v[80:81], v[6:7], v[98:99], v[80:81] op_sel_hi:[0,1,1]
	v_pk_fma_f32 v[90:91], v[10:11], v[96:97], v[90:91] op_sel_hi:[0,1,1]
	v_pk_fma_f32 v[64:65], v[60:61], v[64:65], v[94:95] op_sel_hi:[0,1,1]
	ds_write2_b64 v106, v[104:105], v[82:83] offset1:16
	ds_write2_b64 v106, v[90:91], v[92:93] offset0:33 offset1:49
	ds_write2_b64 v106, v[80:81], v[78:79] offset0:66 offset1:82
	ds_write2_b64 v106, v[76:77], v[84:85] offset0:99 offset1:115
	ds_write2_b64 v106, v[70:71], v[74:75] offset0:132 offset1:148
	ds_write2_b64 v106, v[88:89], v[72:73] offset0:165 offset1:181
	ds_write2_b64 v106, v[86:87], v[68:69] offset0:198 offset1:214
	ds_write2_b64 v106, v[66:67], v[64:65] offset0:231 offset1:247
	v_add3_u32 v18, v18, v5, s5
	ds_read2_b64 v[64:67], v18 offset1:16
	ds_read2_b64 v[68:71], v18 offset0:33 offset1:49
	ds_read2_b64 v[72:75], v18 offset0:66 offset1:82
	ds_read2_b64 v[76:79], v18 offset0:132 offset1:148
	ds_read2_b64 v[80:83], v18 offset0:99 offset1:115
	ds_read2_b64 v[84:87], v18 offset0:165 offset1:181
	ds_read2_b64 v[88:91], v18 offset0:198 offset1:214
	ds_read2_b64 v[92:95], v18 offset0:231 offset1:247
	s_waitcnt lgkmcnt(4)
	v_pk_add_f32 v[96:97], v[64:65], v[76:77]
	v_pk_add_f32 v[64:65], v[64:65], v[76:77] neg_lo:[0,1] neg_hi:[0,1]
	v_pk_add_f32 v[76:77], v[66:67], v[78:79]
	v_pk_add_f32 v[66:67], v[66:67], v[78:79] neg_lo:[0,1] neg_hi:[0,1]
	s_waitcnt lgkmcnt(1)
	v_pk_add_f32 v[98:99], v[74:75], v[90:91]
	v_pk_mul_f32 v[78:79], v[66:67], s[18:19]
	v_pk_add_f32 v[74:75], v[74:75], v[90:91] neg_lo:[0,1] neg_hi:[0,1]
	v_pk_fma_f32 v[66:67], v[66:67], s[16:17], v[78:79] op_sel:[0,0,1] op_sel_hi:[1,0,0]
	v_pk_add_f32 v[78:79], v[68:69], v[84:85]
	v_pk_add_f32 v[68:69], v[68:69], v[84:85] neg_lo:[0,1] neg_hi:[0,1]
	v_pk_mul_f32 v[90:91], v[74:75], s[40:41]
	v_pk_mul_f32 v[84:85], v[68:69], s[36:37]
	v_pk_fma_f32 v[74:75], v[74:75], s[68:69], v[90:91] op_sel:[0,0,1] op_sel_hi:[1,0,0] neg_lo:[1,0,0] neg_hi:[1,0,0]
	s_waitcnt lgkmcnt(0)
	v_pk_add_f32 v[90:91], v[80:81], v[92:93]
	v_pk_add_f32 v[80:81], v[80:81], v[92:93] neg_lo:[0,1] neg_hi:[0,1]
	v_pk_fma_f32 v[68:69], v[68:69], s[66:67], v[84:85] op_sel:[0,0,1] op_sel_hi:[1,0,0]
	v_pk_add_f32 v[84:85], v[70:71], v[86:87]
	v_pk_add_f32 v[70:71], v[70:71], v[86:87] neg_lo:[0,1] neg_hi:[0,1]
	v_pk_mul_f32 v[92:93], v[80:81], s[36:37]
	v_pk_mul_f32 v[86:87], v[70:71], s[40:41]
	v_pk_fma_f32 v[80:81], v[80:81], s[66:67], v[92:93] op_sel:[0,0,1] op_sel_hi:[1,0,0] neg_lo:[1,0,0] neg_hi:[1,0,0]
	v_pk_add_f32 v[92:93], v[82:83], v[94:95]
	v_pk_add_f32 v[82:83], v[82:83], v[94:95] neg_lo:[0,1] neg_hi:[0,1]
	v_pk_fma_f32 v[70:71], v[70:71], s[68:69], v[86:87] op_sel:[0,0,1] op_sel_hi:[1,0,0]
	v_pk_add_f32 v[86:87], v[72:73], v[88:89]
	v_pk_mul_f32 v[94:95], v[82:83], s[18:19]
	v_pk_add_f32 v[88:89], v[72:73], v[88:89] neg_lo:[0,1] neg_hi:[0,1]
	v_pk_fma_f32 v[82:83], v[82:83], s[16:17], v[94:95] op_sel:[0,0,1] op_sel_hi:[1,0,0] neg_lo:[1,0,0] neg_hi:[1,0,0]
	v_pk_add_f32 v[94:95], v[96:97], v[86:87]
	v_pk_add_f32 v[86:87], v[96:97], v[86:87] neg_lo:[0,1] neg_hi:[0,1]
	v_pk_add_f32 v[96:97], v[76:77], v[98:99]
	v_pk_add_f32 v[76:77], v[76:77], v[98:99] op_sel:[1,1] op_sel_hi:[0,0] neg_lo:[0,1] neg_hi:[0,1]
	v_pk_mul_f32 v[98:99], v[76:77], s[36:37] op_sel:[1,0] op_sel_hi:[0,1]
	v_pk_add_f32 v[100:101], v[84:85], v[92:93]
	v_pk_add_f32 v[84:85], v[84:85], v[92:93] neg_lo:[0,1] neg_hi:[0,1]
	v_pk_fma_f32 v[76:77], v[76:77], s[66:67], v[98:99] op_sel:[1,0,1] op_sel_hi:[0,0,0]
	v_pk_add_f32 v[98:99], v[78:79], v[90:91]
	v_pk_add_f32 v[90:91], v[78:79], v[90:91] neg_lo:[0,1] neg_hi:[0,1]
	v_pk_mul_f32 v[92:93], v[84:85], s[36:37]
	v_pk_add_f32 v[72:73], v[64:65], v[88:89] op_sel:[0,1] op_sel_hi:[1,0] neg_hi:[0,1]
	v_pk_add_f32 v[64:65], v[64:65], v[88:89] op_sel:[0,1] op_sel_hi:[1,0] neg_lo:[0,1]
	v_pk_add_f32 v[88:89], v[66:67], v[74:75]
	v_pk_add_f32 v[66:67], v[66:67], v[74:75] neg_lo:[0,1] neg_hi:[0,1]
	v_pk_fma_f32 v[84:85], v[84:85], s[66:67], v[92:93] op_sel:[0,0,1] op_sel_hi:[1,0,0] neg_lo:[1,0,0] neg_hi:[1,0,0]
	v_pk_mul_f32 v[74:75], v[66:67], s[36:37] op_sel:[1,1] op_sel_hi:[0,0]
	v_pk_fma_f32 v[66:67], v[66:67], s[66:67], v[74:75] op_sel_hi:[1,0,1]
	v_pk_add_f32 v[74:75], v[68:69], v[80:81]
	v_pk_add_f32 v[92:93], v[70:71], v[82:83]
	v_pk_add_f32 v[70:71], v[70:71], v[82:83] neg_lo:[0,1] neg_hi:[0,1]
	v_pk_add_f32 v[78:79], v[86:87], v[90:91] op_sel:[0,1] op_sel_hi:[1,0] neg_hi:[0,1]
	v_pk_add_f32 v[86:87], v[86:87], v[90:91] op_sel:[0,1] op_sel_hi:[1,0] neg_lo:[0,1]
	v_pk_add_f32 v[90:91], v[76:77], v[84:85]
	v_pk_add_f32 v[84:85], v[76:77], v[84:85] neg_lo:[0,1] neg_hi:[0,1]
	v_pk_add_f32 v[80:81], v[68:69], v[80:81] neg_lo:[0,1] neg_hi:[0,1]
	v_pk_mul_f32 v[82:83], v[70:71], s[36:37]
	v_pk_add_f32 v[102:103], v[72:73], v[74:75]
	v_pk_add_f32 v[72:73], v[72:73], v[74:75] neg_lo:[0,1] neg_hi:[0,1]
	v_pk_add_f32 v[74:75], v[88:89], v[92:93]
	v_pk_fma_f32 v[70:71], v[70:71], s[66:67], v[82:83] op_sel:[0,0,1] op_sel_hi:[1,0,0] neg_lo:[1,0,0] neg_hi:[1,0,0]
	v_pk_add_f32 v[82:83], v[94:95], v[98:99]
	v_pk_add_f32 v[94:95], v[94:95], v[98:99] neg_lo:[0,1] neg_hi:[0,1]
	v_pk_add_f32 v[98:99], v[96:97], v[100:101]
	v_pk_add_f32 v[76:77], v[86:87], v[84:85] op_sel:[0,1] op_sel_hi:[1,0] neg_hi:[0,1]
	v_pk_add_f32 v[84:85], v[86:87], v[84:85] op_sel:[0,1] op_sel_hi:[1,0] neg_lo:[0,1]
	v_pk_add_f32 v[86:87], v[102:103], v[74:75]
	v_pk_add_f32 v[100:101], v[96:97], v[100:101] neg_lo:[0,1] neg_hi:[0,1]
	v_pk_add_f32 v[68:69], v[64:65], v[80:81] op_sel:[0,1] op_sel_hi:[1,0] neg_hi:[0,1]
	v_pk_add_f32 v[64:65], v[64:65], v[80:81] op_sel:[0,1] op_sel_hi:[1,0] neg_lo:[0,1]
	v_pk_add_f32 v[80:81], v[66:67], v[70:71]
	v_pk_add_f32 v[104:105], v[82:83], v[98:99]
	v_pk_add_f32 v[82:83], v[82:83], v[98:99] neg_lo:[0,1] neg_hi:[0,1]
	v_pk_add_f32 v[98:99], v[78:79], v[90:91]
	v_pk_mul_f32 v[2:3], v[2:3], v[86:87] op_sel:[0,1] op_sel_hi:[1,0]
	v_pk_add_f32 v[92:93], v[88:89], v[92:93] neg_lo:[0,1] neg_hi:[0,1]
	v_pk_add_f32 v[78:79], v[78:79], v[90:91] neg_lo:[0,1] neg_hi:[0,1]
	v_pk_add_f32 v[90:91], v[68:69], v[80:81]
	v_pk_fma_f32 v[2:3], v[4:5], v[86:87], v[2:3] op_sel_hi:[0,1,1]
	v_pk_mul_f32 v[4:5], v[12:13], v[98:99] op_sel:[0,1] op_sel_hi:[1,0]
	v_pk_add_f32 v[70:71], v[66:67], v[70:71] neg_lo:[0,1] neg_hi:[0,1]
	v_pk_add_f32 v[96:97], v[94:95], v[100:101] op_sel:[0,1] op_sel_hi:[1,0] neg_hi:[0,1]
	v_pk_fma_f32 v[4:5], v[6:7], v[98:99], v[4:5] op_sel_hi:[0,1,1]
	v_pk_mul_f32 v[6:7], v[20:21], v[90:91] op_sel:[0,1] op_sel_hi:[1,0]
	v_pk_add_f32 v[88:89], v[72:73], v[92:93] op_sel:[0,1] op_sel_hi:[1,0] neg_hi:[0,1]
	v_pk_fma_f32 v[6:7], v[8:9], v[90:91], v[6:7] op_sel_hi:[0,1,1]
	v_pk_mul_f32 v[8:9], v[14:15], v[96:97] op_sel:[0,1] op_sel_hi:[1,0]
	v_pk_add_f32 v[66:67], v[64:65], v[70:71] op_sel:[0,1] op_sel_hi:[1,0] neg_hi:[0,1]
	v_pk_fma_f32 v[8:9], v[10:11], v[96:97], v[8:9] op_sel_hi:[0,1,1]
	v_pk_mul_f32 v[10:11], v[22:23], v[88:89] op_sel:[0,1] op_sel_hi:[1,0]
	v_pk_add_f32 v[94:95], v[94:95], v[100:101] op_sel:[0,1] op_sel_hi:[1,0] neg_lo:[0,1]
	v_pk_add_f32 v[74:75], v[102:103], v[74:75] neg_lo:[0,1] neg_hi:[0,1]
	v_pk_add_f32 v[72:73], v[72:73], v[92:93] op_sel:[0,1] op_sel_hi:[1,0] neg_lo:[0,1]
	v_pk_add_f32 v[68:69], v[68:69], v[80:81] neg_lo:[0,1] neg_hi:[0,1]
	v_pk_add_f32 v[64:65], v[64:65], v[70:71] op_sel:[0,1] op_sel_hi:[1,0] neg_lo:[0,1]
	v_pk_fma_f32 v[10:11], v[16:17], v[88:89], v[10:11] op_sel_hi:[0,1,1]
	v_pk_mul_f32 v[12:13], v[26:27], v[76:77] op_sel:[0,1] op_sel_hi:[1,0]
	v_pk_mul_f32 v[14:15], v[30:31], v[66:67] op_sel:[0,1] op_sel_hi:[1,0]
	v_pk_mul_f32 v[16:17], v[34:35], v[82:83] op_sel:[0,1] op_sel_hi:[1,0]
	v_pk_fma_f32 v[12:13], v[24:25], v[76:77], v[12:13] op_sel_hi:[0,1,1]
	v_pk_fma_f32 v[14:15], v[28:29], v[66:67], v[14:15] op_sel_hi:[0,1,1]
	v_pk_fma_f32 v[16:17], v[32:33], v[82:83], v[16:17] op_sel_hi:[0,1,1]
	v_pk_mul_f32 v[20:21], v[38:39], v[74:75] op_sel:[0,1] op_sel_hi:[1,0]
	v_pk_mul_f32 v[22:23], v[42:43], v[78:79] op_sel:[0,1] op_sel_hi:[1,0]
	v_pk_mul_f32 v[24:25], v[46:47], v[68:69] op_sel:[0,1] op_sel_hi:[1,0]
	v_pk_mul_f32 v[26:27], v[50:51], v[94:95] op_sel:[0,1] op_sel_hi:[1,0]
	v_pk_mul_f32 v[28:29], v[54:55], v[72:73] op_sel:[0,1] op_sel_hi:[1,0]
	v_pk_mul_f32 v[30:31], v[58:59], v[84:85] op_sel:[0,1] op_sel_hi:[1,0]
	v_pk_mul_f32 v[32:33], v[62:63], v[64:65] op_sel:[0,1] op_sel_hi:[1,0]
	v_pk_fma_f32 v[20:21], v[36:37], v[74:75], v[20:21] op_sel_hi:[0,1,1]
	v_pk_fma_f32 v[22:23], v[40:41], v[78:79], v[22:23] op_sel_hi:[0,1,1]
	v_pk_fma_f32 v[24:25], v[44:45], v[68:69], v[24:25] op_sel_hi:[0,1,1]
	v_pk_fma_f32 v[26:27], v[48:49], v[94:95], v[26:27] op_sel_hi:[0,1,1]
	v_pk_fma_f32 v[28:29], v[52:53], v[72:73], v[28:29] op_sel_hi:[0,1,1]
	v_pk_fma_f32 v[30:31], v[56:57], v[84:85], v[30:31] op_sel_hi:[0,1,1]
	v_pk_fma_f32 v[32:33], v[60:61], v[64:65], v[32:33] op_sel_hi:[0,1,1]
	ds_write2_b64 v18, v[104:105], v[16:17] offset1:16
	ds_write2_b64 v18, v[8:9], v[26:27] offset0:33 offset1:49
	ds_write2_b64 v18, v[4:5], v[22:23] offset0:66 offset1:82
	ds_write2_b64 v18, v[12:13], v[30:31] offset0:99 offset1:115
	ds_write2_b64 v18, v[2:3], v[20:21] offset0:132 offset1:148
	ds_write2_b64 v18, v[10:11], v[28:29] offset0:165 offset1:181
	ds_write2_b64 v18, v[6:7], v[24:25] offset0:198 offset1:214
	ds_write2_b64 v18, v[14:15], v[32:33] offset0:231 offset1:247
	v_ashrrev_i32_e32 v2, 31, v210
	v_add_u32_sdwa v2, v210, v2 dst_sel:DWORD dst_unused:UNUSED_PAD src0_sel:DWORD src1_sel:BYTE_3
	s_lshl_b64 s[0:1], s[64:65], 15
	v_and_b32_e32 v2, 0xffffff00, v2
	s_add_u32 s0, s29, s0
	v_sub_u32_e32 v2, v210, v2
	s_addc_u32 s1, s85, s1
	v_ashrrev_i32_e32 v3, 31, v2
	v_lshl_add_u64 v[14:15], v[2:3], 3, s[0:1]
	s_movk_i32 s0, 0x1000
	v_add_co_u32_e32 v16, vcc, s0, v14
	s_movk_i32 s0, 0x3000
	s_nop 0
	v_addc_co_u32_e32 v17, vcc, 0, v15, vcc
	v_add_co_u32_e32 v2, vcc, s92, v14
	s_waitcnt lgkmcnt(0)
	s_nop 0
	v_addc_co_u32_e32 v3, vcc, 0, v15, vcc
	v_add_co_u32_e32 v22, vcc, s0, v14
	s_movk_i32 s0, 0x5000
	s_nop 0
	v_addc_co_u32_e32 v23, vcc, 0, v15, vcc
	v_add_co_u32_e32 v8, vcc, s95, v14
	s_barrier
	s_nop 0
	v_addc_co_u32_e32 v9, vcc, 0, v15, vcc
	v_add_co_u32_e32 v26, vcc, s0, v14
	s_nop 1
	v_addc_co_u32_e32 v27, vcc, 0, v15, vcc
	v_add_co_u32_e32 v10, vcc, s96, v14
	global_load_dwordx2 v[12:13], v[2:3], off nt
	global_load_dwordx2 v[6:7], v[2:3], off offset:2048 nt
	global_load_dwordx2 v[4:5], v[8:9], off offset:-4096 nt
	global_load_dwordx2 v[122:123], v[8:9], off nt
	v_addc_co_u32_e32 v11, vcc, 0, v15, vcc
	v_add_co_u32_e32 v28, vcc, s97, v14
	global_load_dwordx2 v[46:47], v[8:9], off offset:2048 nt
	global_load_dwordx2 v[38:39], v[10:11], off offset:-4096 nt
	global_load_dwordx2 v[20:21], v[10:11], off nt
	s_nop 0
	global_load_dwordx2 v[10:11], v[10:11], off offset:2048 nt
	v_addc_co_u32_e32 v29, vcc, 0, v15, vcc
	global_load_dwordx2 v[24:25], v[2:3], off offset:-4096 nt
	s_nop 0
	global_load_dwordx2 v[26:27], v[26:27], off offset:2048 nt
	s_nop 0
	global_load_dwordx2 v[8:9], v[28:29], off nt
	global_load_dwordx2 v[2:3], v[28:29], off offset:2048 nt
	global_load_dwordx2 v[30:31], v[14:15], off offset:2048 nt
	s_nop 0
	global_load_dwordx2 v[28:29], v[16:17], off offset:2048 nt
	s_nop 0
	global_load_dwordx2 v[16:17], v[22:23], off offset:2048 nt
	global_load_dwordx2 v[32:33], v[14:15], off nt
	v_mov_b32_e32 v14, v210
	s_waitcnt vmcnt(15)
	v_cvt_f32_f16_sdwa v164, v12 dst_sel:DWORD dst_unused:UNUSED_PAD src0_sel:WORD_1
	v_ashrrev_i32_e32 v15, 31, v14
	v_add_u32_sdwa v15, v14, v15 dst_sel:DWORD dst_unused:UNUSED_PAD src0_sel:DWORD src1_sel:BYTE_3
	v_ashrrev_i32_e32 v15, 8, v15
	v_mul_i32_i24_e32 v18, 0x100, v15
	v_sub_u32_e32 v18, v14, v18
	v_lshlrev_b32_e32 v14, 13, v15
	v_lshlrev_b32_e32 v15, 1, v18
	v_bfrev_b32_e32 v15, v15
	v_lshrrev_b32_e32 v15, 23, v15
	v_sub_u32_e32 v15, 0x200, v15
	v_bfrev_b32_e32 v15, v15
	v_lshrrev_b32_e32 v15, 19, v15
	v_and_b32_e32 v15, 0x1ff0, v15
	v_cmp_eq_u32_e64 s[0:1], 0, v18
	v_lshl_add_u32 v22, v18, 5, v14
	v_lshl_add_u32 v23, v22, 3, 0
	v_cndmask_b32_e64 v15, v15, 16, s[0:1]
	v_or_b32_e32 v14, v15, v14
	v_ashrrev_i32_e32 v22, 2, v22
	v_ashrrev_i32_e32 v15, 5, v14
	v_add_u32_e32 v211, v23, v22
	v_lshlrev_b32_e32 v14, 3, v14
	v_lshlrev_b32_e32 v15, 3, v15
	v_add3_u32 v212, 0, v14, v15
	ds_read2_b64 v[34:37], v211 offset1:1
	ds_read2_b64 v[40:43], v211 offset0:2 offset1:3
	ds_read2_b64 v[48:51], v212 offset1:1
	ds_read2_b64 v[52:55], v212 offset0:2 offset1:3
	ds_read2_b64 v[56:59], v211 offset0:4 offset1:5
	ds_read2_b64 v[60:63], v211 offset0:6 offset1:7
	ds_read2_b64 v[68:71], v212 offset0:4 offset1:5
	ds_read2_b64 v[72:75], v212 offset0:6 offset1:7
	ds_read2_b64 v[64:67], v211 offset0:8 offset1:9
	ds_read2_b64 v[76:79], v211 offset0:10 offset1:11
	ds_read2_b64 v[80:83], v212 offset0:8 offset1:9
	ds_read2_b64 v[98:101], v212 offset0:10 offset1:11
	ds_read2_b64 v[84:87], v211 offset0:12 offset1:13
	ds_read2_b64 v[88:91], v211 offset0:14 offset1:15
	ds_read2_b64 v[102:105], v212 offset0:12 offset1:13
	ds_read2_b64 v[106:109], v212 offset0:14 offset1:15
	s_waitcnt lgkmcnt(7)
	v_pk_add_f32 v[14:15], v[34:35], v[64:65]
	v_pk_add_f32 v[22:23], v[34:35], v[64:65] neg_lo:[0,1] neg_hi:[0,1]
	v_pk_add_f32 v[34:35], v[36:37], v[66:67]
	v_pk_add_f32 v[36:37], v[36:37], v[66:67] neg_lo:[0,1] neg_hi:[0,1]
	v_cmp_ne_u32_e32 vcc, 0, v18
	v_pk_mul_f32 v[44:45], v[36:37], s[18:19]
	v_bfrev_b32_e32 v18, v18
	v_pk_fma_f32 v[36:37], v[36:37], s[16:17], v[44:45] op_sel:[0,0,1] op_sel_hi:[1,0,0]
	s_waitcnt lgkmcnt(6)
	v_pk_add_f32 v[44:45], v[40:41], v[76:77]
	v_pk_add_f32 v[40:41], v[40:41], v[76:77] neg_lo:[0,1] neg_hi:[0,1]
	v_cvt_f32_ubyte3_e32 v18, v18
	v_pk_mul_f32 v[64:65], v[40:41], s[36:37]
	v_mul_f32_e32 v18, 0x38800000, v18
	v_pk_fma_f32 v[40:41], v[40:41], s[66:67], v[64:65] op_sel:[0,0,1] op_sel_hi:[1,0,0]
	v_pk_add_f32 v[64:65], v[42:43], v[78:79]
	v_pk_add_f32 v[42:43], v[42:43], v[78:79] neg_lo:[0,1] neg_hi:[0,1]
	s_waitcnt lgkmcnt(3)
	v_pk_add_f32 v[78:79], v[58:59], v[86:87]
	v_pk_mul_f32 v[66:67], v[42:43], s[40:41]
	v_pk_add_f32 v[58:59], v[58:59], v[86:87] neg_lo:[0,1] neg_hi:[0,1]
	v_pk_fma_f32 v[42:43], v[42:43], s[68:69], v[66:67] op_sel:[0,0,1] op_sel_hi:[1,0,0]
	v_pk_add_f32 v[66:67], v[56:57], v[84:85]
	v_pk_add_f32 v[76:77], v[56:57], v[84:85] neg_lo:[0,1] neg_hi:[0,1]
	v_pk_mul_f32 v[84:85], v[58:59], s[40:41] op_sel:[1,1] op_sel_hi:[0,0]
	v_pk_fma_f32 v[58:59], v[58:59], s[68:69], v[84:85] op_sel_hi:[1,0,1] neg_lo:[1,0,0] neg_hi:[1,0,0]
	s_waitcnt lgkmcnt(2)
	v_pk_add_f32 v[84:85], v[60:61], v[88:89]
	v_pk_add_f32 v[60:61], v[60:61], v[88:89] op_sel:[1,1] op_sel_hi:[0,0] neg_lo:[0,1] neg_hi:[0,1]
	v_pk_mul_f32 v[86:87], v[60:61], s[36:37] op_sel:[1,0] op_sel_hi:[0,1]
	v_pk_add_f32 v[56:57], v[22:23], v[76:77] op_sel:[0,1] op_sel_hi:[1,0] neg_hi:[0,1]
	v_pk_fma_f32 v[60:61], v[60:61], s[66:67], v[86:87] op_sel:[1,0,1] op_sel_hi:[0,0,0] neg_lo:[1,0,0] neg_hi:[1,0,0]
	v_pk_add_f32 v[86:87], v[62:63], v[90:91]
	v_pk_add_f32 v[62:63], v[62:63], v[90:91] neg_lo:[0,1] neg_hi:[0,1]
	v_pk_add_f32 v[90:91], v[64:65], v[86:87]
	v_pk_mul_f32 v[88:89], v[62:63], s[18:19]
	v_pk_add_f32 v[64:65], v[64:65], v[86:87] neg_lo:[0,1] neg_hi:[0,1]
	v_pk_fma_f32 v[62:63], v[62:63], s[16:17], v[88:89] op_sel:[0,0,1] op_sel_hi:[1,0,0] neg_lo:[1,0,0] neg_hi:[1,0,0]
	v_pk_add_f32 v[88:89], v[14:15], v[66:67]
	v_pk_add_f32 v[14:15], v[14:15], v[66:67] neg_lo:[0,1] neg_hi:[0,1]
	v_pk_add_f32 v[66:67], v[34:35], v[78:79]
	v_pk_add_f32 v[34:35], v[34:35], v[78:79] neg_lo:[0,1] neg_hi:[0,1]
	v_pk_add_f32 v[22:23], v[22:23], v[76:77] op_sel:[0,1] op_sel_hi:[1,0] neg_lo:[0,1]
	v_pk_mul_f32 v[78:79], v[34:35], s[36:37]
	v_pk_add_f32 v[76:77], v[36:37], v[58:59]
	v_pk_add_f32 v[36:37], v[36:37], v[58:59] neg_lo:[0,1] neg_hi:[0,1]
	v_pk_fma_f32 v[34:35], v[34:35], s[66:67], v[78:79] op_sel:[0,0,1] op_sel_hi:[1,0,0]
	v_pk_add_f32 v[78:79], v[44:45], v[84:85]
	v_pk_add_f32 v[84:85], v[44:45], v[84:85] neg_lo:[0,1] neg_hi:[0,1]
	v_pk_mul_f32 v[86:87], v[64:65], s[36:37]
	v_pk_mul_f32 v[58:59], v[36:37], s[36:37]
	v_pk_fma_f32 v[64:65], v[64:65], s[66:67], v[86:87] op_sel:[0,0,1] op_sel_hi:[1,0,0] neg_lo:[1,0,0] neg_hi:[1,0,0]
	v_pk_fma_f32 v[36:37], v[36:37], s[66:67], v[58:59] op_sel:[0,0,1] op_sel_hi:[1,0,0]
	v_pk_add_f32 v[58:59], v[40:41], v[60:61]
	v_pk_add_f32 v[86:87], v[42:43], v[62:63]
	v_pk_add_f32 v[42:43], v[42:43], v[62:63] op_sel:[1,1] op_sel_hi:[0,0] neg_lo:[0,1] neg_hi:[0,1]
	v_pk_mul_f32 v[62:63], v[42:43], s[36:37] op_sel:[1,0] op_sel_hi:[0,1]
	v_pk_add_f32 v[44:45], v[14:15], v[84:85] op_sel:[0,1] op_sel_hi:[1,0] neg_hi:[0,1]
	v_pk_add_f32 v[14:15], v[14:15], v[84:85] op_sel:[0,1] op_sel_hi:[1,0] neg_lo:[0,1]
	v_pk_add_f32 v[84:85], v[34:35], v[64:65]
	v_pk_add_f32 v[64:65], v[34:35], v[64:65] neg_lo:[0,1] neg_hi:[0,1]
	v_pk_add_f32 v[94:95], v[56:57], v[58:59]
	v_pk_add_f32 v[56:57], v[56:57], v[58:59] neg_lo:[0,1] neg_hi:[0,1]
	v_pk_add_f32 v[58:59], v[76:77], v[86:87]
	v_pk_fma_f32 v[42:43], v[42:43], s[66:67], v[62:63] op_sel:[1,0,1] op_sel_hi:[0,0,0] neg_lo:[1,0,0] neg_hi:[1,0,0]
	v_pk_add_f32 v[62:63], v[88:89], v[78:79]
	v_pk_add_f32 v[78:79], v[88:89], v[78:79] neg_lo:[0,1] neg_hi:[0,1]
	v_pk_add_f32 v[88:89], v[66:67], v[90:91]
	v_pk_add_f32 v[110:111], v[76:77], v[86:87] neg_lo:[0,1] neg_hi:[0,1]
	v_pk_add_f32 v[86:87], v[94:95], v[58:59]
	v_pk_add_f32 v[34:35], v[94:95], v[58:59] neg_lo:[0,1] neg_hi:[0,1]
	v_pk_add_f32 v[58:59], v[50:51], v[82:83]
	v_pk_add_f32 v[50:51], v[50:51], v[82:83] neg_lo:[0,1] neg_hi:[0,1]
	v_pk_add_f32 v[60:61], v[40:41], v[60:61] neg_lo:[0,1] neg_hi:[0,1]
	v_pk_add_f32 v[148:149], v[62:63], v[88:89]
	v_pk_add_f32 v[138:139], v[62:63], v[88:89] neg_lo:[0,1] neg_hi:[0,1]
	v_pk_mul_f32 v[62:63], v[50:51], s[18:19]
	v_pk_add_f32 v[90:91], v[66:67], v[90:91] neg_lo:[0,1] neg_hi:[0,1]
	v_pk_fma_f32 v[50:51], v[50:51], s[16:17], v[62:63] op_sel:[0,0,1] op_sel_hi:[1,0,0]
	v_pk_add_f32 v[62:63], v[52:53], v[98:99]
	v_pk_add_f32 v[52:53], v[52:53], v[98:99] neg_lo:[0,1] neg_hi:[0,1]
	v_pk_add_f32 v[112:113], v[22:23], v[60:61] op_sel:[0,1] op_sel_hi:[1,0] neg_hi:[0,1]
	v_pk_add_f32 v[114:115], v[22:23], v[60:61] op_sel:[0,1] op_sel_hi:[1,0] neg_lo:[0,1]
	v_pk_add_f32 v[96:97], v[44:45], v[84:85]
	v_pk_add_f32 v[66:67], v[44:45], v[84:85] neg_lo:[0,1] neg_hi:[0,1]
	v_pk_add_f32 v[60:61], v[14:15], v[64:65] op_sel:[0,1] op_sel_hi:[1,0] neg_hi:[0,1]
	v_pk_add_f32 v[84:85], v[14:15], v[64:65] op_sel:[0,1] op_sel_hi:[1,0] neg_lo:[0,1]
	v_pk_mul_f32 v[64:65], v[52:53], s[36:37] op_sel:[1,1] op_sel_hi:[0,0]
	v_pk_fma_f32 v[52:53], v[52:53], s[66:67], v[64:65] op_sel_hi:[1,0,1]
	v_pk_add_f32 v[64:65], v[54:55], v[100:101]
	v_pk_add_f32 v[54:55], v[54:55], v[100:101] op_sel:[1,1] op_sel_hi:[0,0] neg_lo:[0,1] neg_hi:[0,1]
	v_pk_mul_f32 v[76:77], v[54:55], s[40:41] op_sel:[1,0] op_sel_hi:[0,1]
	v_pk_add_f32 v[92:93], v[78:79], v[90:91] op_sel:[0,1] op_sel_hi:[1,0] neg_hi:[0,1]
	v_pk_fma_f32 v[54:55], v[54:55], s[68:69], v[76:77] op_sel:[1,0,1] op_sel_hi:[0,0,0]
	s_waitcnt lgkmcnt(1)
	v_pk_add_f32 v[76:77], v[68:69], v[102:103]
	v_pk_add_f32 v[68:69], v[68:69], v[102:103] neg_lo:[0,1] neg_hi:[0,1]
	v_pk_add_f32 v[88:89], v[78:79], v[90:91] op_sel:[0,1] op_sel_hi:[1,0] neg_lo:[0,1]
	v_xor_b32_e32 v79, 0x80000000, v68
	v_mov_b32_e32 v78, v69
	v_pk_add_f32 v[68:69], v[70:71], v[104:105]
	v_pk_add_f32 v[70:71], v[70:71], v[104:105] neg_lo:[0,1] neg_hi:[0,1]
	v_pk_add_f32 v[40:41], v[56:57], v[110:111] op_sel:[0,1] op_sel_hi:[1,0] neg_hi:[0,1]
	v_pk_add_f32 v[44:45], v[56:57], v[110:111] op_sel:[0,1] op_sel_hi:[1,0] neg_lo:[0,1]
	v_pk_add_f32 v[56:57], v[48:49], v[80:81]
	v_pk_add_f32 v[48:49], v[48:49], v[80:81] neg_lo:[0,1] neg_hi:[0,1]
	v_pk_mul_f32 v[80:81], v[70:71], s[40:41]
	v_cndmask_b32_e64 v18, v18, v208, s[0:1]
	v_pk_fma_f32 v[70:71], v[70:71], s[68:69], v[80:81] op_sel:[0,0,1] op_sel_hi:[1,0,0] neg_lo:[1,0,0] neg_hi:[1,0,0]
	s_waitcnt lgkmcnt(0)
	v_pk_add_f32 v[80:81], v[72:73], v[106:107]
	v_pk_add_f32 v[72:73], v[72:73], v[106:107] neg_lo:[0,1] neg_hi:[0,1]
	v_pk_add_f32 v[22:23], v[36:37], v[42:43]
	v_pk_mul_f32 v[82:83], v[72:73], s[36:37]
	v_pk_add_f32 v[116:117], v[36:37], v[42:43] neg_lo:[0,1] neg_hi:[0,1]
	v_pk_fma_f32 v[72:73], v[72:73], s[66:67], v[82:83] op_sel:[0,0,1] op_sel_hi:[1,0,0] neg_lo:[1,0,0] neg_hi:[1,0,0]
	v_pk_add_f32 v[82:83], v[74:75], v[108:109]
	v_pk_add_f32 v[74:75], v[74:75], v[108:109] op_sel:[1,1] op_sel_hi:[0,0] neg_lo:[0,1] neg_hi:[0,1]
	v_pk_mul_f32 v[90:91], v[74:75], s[18:19] op_sel:[1,0] op_sel_hi:[0,1]
	s_nop 0
	v_pk_fma_f32 v[74:75], v[74:75], s[16:17], v[90:91] op_sel:[1,0,1] op_sel_hi:[0,0,0] neg_lo:[1,0,0] neg_hi:[1,0,0]
	v_pk_add_f32 v[90:91], v[56:57], v[76:77]
	v_pk_add_f32 v[56:57], v[56:57], v[76:77] neg_lo:[0,1] neg_hi:[0,1]
	v_pk_add_f32 v[76:77], v[58:59], v[68:69]
	v_pk_add_f32 v[58:59], v[58:59], v[68:69] neg_lo:[0,1] neg_hi:[0,1]
	v_pk_add_f32 v[14:15], v[114:115], v[116:117] op_sel:[0,1] op_sel_hi:[1,0] neg_hi:[0,1]
	v_pk_mul_f32 v[68:69], v[58:59], s[36:37]
	v_pk_add_f32 v[36:37], v[114:115], v[116:117] op_sel:[0,1] op_sel_hi:[1,0] neg_lo:[0,1]
	v_pk_fma_f32 v[58:59], v[58:59], s[66:67], v[68:69] op_sel:[0,0,1] op_sel_hi:[1,0,0]
	v_pk_add_f32 v[68:69], v[62:63], v[80:81]
	v_pk_add_f32 v[80:81], v[62:63], v[80:81] neg_lo:[0,1] neg_hi:[0,1]
	s_waitcnt vmcnt(0)
	v_cvt_f32_f16_e32 v193, v33
	s_nop 0
	s_nop 0
	v_pk_add_f32 v[62:63], v[64:65], v[82:83]
	v_pk_add_f32 v[64:65], v[64:65], v[82:83] neg_lo:[0,1] neg_hi:[0,1]
	v_cvt_f32_f16_sdwa v192, v32 dst_sel:DWORD dst_unused:UNUSED_PAD src0_sel:WORD_1
	v_pk_mul_f32 v[82:83], v[64:65], s[36:37]
	v_cvt_f32_f16_e32 v194, v32
	v_pk_fma_f32 v[64:65], v[64:65], s[66:67], v[82:83] op_sel:[0,0,1] op_sel_hi:[1,0,0] neg_lo:[1,0,0] neg_hi:[1,0,0]
	v_pk_add_f32 v[82:83], v[48:49], v[78:79]
	v_pk_add_f32 v[48:49], v[48:49], v[78:79] neg_lo:[0,1] neg_hi:[0,1]
	v_pk_add_f32 v[78:79], v[50:51], v[70:71]
	v_pk_add_f32 v[50:51], v[50:51], v[70:71] neg_lo:[0,1] neg_hi:[0,1]
	v_cvt_f32_f16_sdwa v195, v33 dst_sel:DWORD dst_unused:UNUSED_PAD src0_sel:WORD_1
	v_pk_mul_f32 v[70:71], v[50:51], s[36:37]
	v_cvt_f32_f16_sdwa v170, v30 dst_sel:DWORD dst_unused:UNUSED_PAD src0_sel:WORD_1
	v_pk_fma_f32 v[50:51], v[50:51], s[66:67], v[70:71] op_sel:[0,0,1] op_sel_hi:[1,0,0]
	v_pk_add_f32 v[70:71], v[52:53], v[72:73]
	v_pk_add_f32 v[72:73], v[52:53], v[72:73] neg_lo:[0,1] neg_hi:[0,1]
	v_cvt_f32_f16_e32 v171, v31
	s_nop 0
	s_nop 0
	v_pk_add_f32 v[52:53], v[54:55], v[74:75]
	v_pk_add_f32 v[54:55], v[54:55], v[74:75] neg_lo:[0,1] neg_hi:[0,1]
	v_cvt_f32_f16_sdwa v185, v31 dst_sel:DWORD dst_unused:UNUSED_PAD src0_sel:WORD_1
	v_pk_mul_f32 v[74:75], v[54:55], s[36:37]
	v_cvt_f32_f16_e32 v184, v30
	v_pk_fma_f32 v[54:55], v[54:55], s[66:67], v[74:75] op_sel:[0,0,1] op_sel_hi:[1,0,0] neg_lo:[1,0,0] neg_hi:[1,0,0]
	v_pk_add_f32 v[74:75], v[90:91], v[68:69]
	v_pk_add_f32 v[68:69], v[90:91], v[68:69] neg_lo:[0,1] neg_hi:[0,1]
	v_pk_add_f32 v[90:91], v[76:77], v[62:63]
	v_pk_add_f32 v[62:63], v[76:77], v[62:63] neg_lo:[0,1] neg_hi:[0,1]
	v_cvt_f32_f16_sdwa v172, v24 dst_sel:DWORD dst_unused:UNUSED_PAD src0_sel:WORD_1
	v_xor_b32_e32 v77, 0x80000000, v62
	v_mov_b32_e32 v76, v63
	v_pk_add_f32 v[62:63], v[56:57], v[80:81] op_sel:[0,1] op_sel_hi:[1,0] neg_hi:[0,1]
	v_pk_add_f32 v[56:57], v[56:57], v[80:81] op_sel:[0,1] op_sel_hi:[1,0] neg_lo:[0,1]
	v_pk_add_f32 v[80:81], v[58:59], v[64:65]
	v_pk_add_f32 v[58:59], v[58:59], v[64:65] neg_lo:[0,1] neg_hi:[0,1]
	v_cvt_f32_f16_e32 v173, v25
	v_xor_b32_e32 v65, 0x80000000, v58
	v_mov_b32_e32 v64, v59
	v_pk_add_f32 v[58:59], v[82:83], v[70:71]
	v_pk_add_f32 v[70:71], v[82:83], v[70:71] neg_lo:[0,1] neg_hi:[0,1]
	v_pk_add_f32 v[82:83], v[78:79], v[52:53]
	v_pk_add_f32 v[52:53], v[78:79], v[52:53] neg_lo:[0,1] neg_hi:[0,1]
	v_pk_add_f32 v[118:119], v[58:59], v[82:83]
	v_pk_add_f32 v[134:135], v[58:59], v[82:83] neg_lo:[0,1] neg_hi:[0,1]
	v_cos_f32_e32 v83, v18
	v_sin_f32_e32 v82, v18
	v_cvt_f32_f16_sdwa v181, v25 dst_sel:DWORD dst_unused:UNUSED_PAD src0_sel:WORD_1
	v_cvt_f32_f16_e32 v180, v24
	v_cvt_f32_f16_sdwa v174, v28 dst_sel:DWORD dst_unused:UNUSED_PAD src0_sel:WORD_1
	v_cvt_f32_f16_e32 v175, v29
	v_cvt_f32_f16_sdwa v179, v29 dst_sel:DWORD dst_unused:UNUSED_PAD src0_sel:WORD_1
	v_cvt_f32_f16_e32 v178, v28
	v_cvt_f32_f16_e32 v165, v13
	v_cvt_f32_f16_sdwa v167, v13 dst_sel:DWORD dst_unused:UNUSED_PAD src0_sel:WORD_1
	v_cvt_f32_f16_e32 v166, v12
	v_cvt_f32_f16_e32 v154, v6
	v_cvt_f32_f16_e32 v155, v7
	v_cvt_f32_f16_sdwa v157, v7 dst_sel:DWORD dst_unused:UNUSED_PAD src0_sel:WORD_1
	v_cvt_f32_f16_sdwa v156, v6 dst_sel:DWORD dst_unused:UNUSED_PAD src0_sel:WORD_1
	v_cvt_f32_f16_sdwa v140, v4 dst_sel:DWORD dst_unused:UNUSED_PAD src0_sel:WORD_1
	v_cvt_f32_f16_e32 v141, v5
	v_cvt_f32_f16_sdwa v143, v5 dst_sel:DWORD dst_unused:UNUSED_PAD src0_sel:WORD_1
	v_cvt_f32_f16_e32 v142, v4
	v_cvt_f32_f16_e32 v124, v16
	v_cvt_f32_f16_e32 v125, v17
	v_cvt_f32_f16_sdwa v127, v17 dst_sel:DWORD dst_unused:UNUSED_PAD src0_sel:WORD_1
	v_cvt_f32_f16_sdwa v126, v16 dst_sel:DWORD dst_unused:UNUSED_PAD src0_sel:WORD_1
	v_cvt_f32_f16_sdwa v114, v122 dst_sel:DWORD dst_unused:UNUSED_PAD src0_sel:WORD_1
	v_cvt_f32_f16_e32 v115, v123
	v_cvt_f32_f16_sdwa v117, v123 dst_sel:DWORD dst_unused:UNUSED_PAD src0_sel:WORD_1
	v_cvt_f32_f16_e32 v116, v122
	v_xor_b32_e32 v79, 0x80000000, v52
	v_mov_b32_e32 v78, v53
	v_pk_add_f32 v[52:53], v[48:49], v[72:73] op_sel:[0,1] op_sel_hi:[1,0] neg_hi:[0,1]
	v_pk_add_f32 v[48:49], v[48:49], v[72:73] op_sel:[0,1] op_sel_hi:[1,0] neg_lo:[0,1]
	v_pk_add_f32 v[72:73], v[50:51], v[54:55]
	v_pk_add_f32 v[50:51], v[50:51], v[54:55] neg_lo:[0,1] neg_hi:[0,1]
	v_pk_fma_f32 v[160:161], v[82:83], 0, v[82:83] op_sel:[0,0,1] op_sel_hi:[1,0,0] neg_lo:[1,0,0] neg_hi:[1,0,0]
	v_xor_b32_e32 v55, 0x80000000, v50
	v_mov_b32_e32 v54, v51
	v_pk_fma_f32 v[198:199], v[82:83], 0, v[82:83] op_sel:[0,0,1] op_sel_hi:[1,0,0]
	v_pk_add_f32 v[42:43], v[112:113], v[22:23]
	v_pk_add_f32 v[22:23], v[112:113], v[22:23] neg_lo:[0,1] neg_hi:[0,1]
	v_pk_add_f32 v[98:99], v[74:75], v[90:91]
	v_pk_add_f32 v[100:101], v[74:75], v[90:91] neg_lo:[0,1] neg_hi:[0,1]
	v_pk_add_f32 v[102:103], v[68:69], v[76:77]
	v_pk_add_f32 v[106:107], v[68:69], v[76:77] neg_lo:[0,1] neg_hi:[0,1]
	v_pk_add_f32 v[104:105], v[62:63], v[80:81]
	v_pk_add_f32 v[108:109], v[62:63], v[80:81] neg_lo:[0,1] neg_hi:[0,1]
	v_pk_add_f32 v[110:111], v[56:57], v[64:65]
	v_pk_add_f32 v[112:113], v[56:57], v[64:65] neg_lo:[0,1] neg_hi:[0,1]
	v_pk_add_f32 v[152:153], v[70:71], v[78:79]
	v_pk_add_f32 v[162:163], v[70:71], v[78:79] neg_lo:[0,1] neg_hi:[0,1]
	v_pk_add_f32 v[176:177], v[52:53], v[72:73]
	v_pk_add_f32 v[182:183], v[52:53], v[72:73] neg_lo:[0,1] neg_hi:[0,1]
	v_pk_add_f32 v[188:189], v[48:49], v[54:55]
	v_pk_add_f32 v[196:197], v[48:49], v[54:55] neg_lo:[0,1] neg_hi:[0,1]
	v_pk_mul_f32 v[186:187], v[82:83], 0 op_sel_hi:[1,0]
	v_mov_b32_e32 v190, v160
	v_mov_b32_e32 v191, v199
	v_mul_f32_e32 v18, 0x3f3504f3, v83
	v_mul_f32_e32 v158, 0xbec3ef15, v83
	v_mul_f32_e32 v132, 0xbf6c835e, v83
	s_and_saveexec_b64 s[0:1], vcc
	s_xor_b64 s[0:1], exec, s[0:1]
	s_cbranch_execz .LBB0_536
	v_pk_add_f32 v[4:5], v[148:149], v[196:197]
	v_pk_add_f32 v[6:7], v[148:149], v[196:197] neg_lo:[0,1] neg_hi:[0,1]
	v_mul_f32_e32 v4, 0.5, v4
	v_mul_f32_e32 v12, 0.5, v7
	v_mov_b32_e32 v7, v5
	v_pk_mul_f32 v[6:7], v[6:7], s[44:45]
	v_pk_mov_b32 v[16:17], v[198:199], v[160:161] op_sel:[1,0]
	v_pk_mul_f32 v[24:25], v[190:191], v[6:7] op_sel:[0,1] op_sel_hi:[1,0]
	v_pk_mul_f32 v[6:7], v[190:191], v[6:7]
	v_pk_add_f32 v[24:25], v[24:25], v[24:25] op_sel:[0,1] op_sel_hi:[0,1]
	v_pk_add_f32 v[28:29], v[4:5], v[24:25] op_sel_hi:[0,1] neg_hi:[0,1]
	v_pk_add_f32 v[4:5], v[6:7], v[6:7] op_sel:[0,1] op_sel_hi:[0,1] neg_lo:[0,1] neg_hi:[0,1]
	v_pk_add_f32 v[6:7], v[12:13], v[4:5] op_sel_hi:[0,1] neg_hi:[0,1]
	v_pk_mul_f32 v[4:5], v[6:7], v[194:195]
	v_pk_mul_f32 v[6:7], v[6:7], v[192:193]
	v_pk_fma_f32 v[4:5], v[28:29], v[192:193], v[4:5]
	v_pk_fma_f32 v[6:7], v[28:29], v[194:195], v[6:7] neg_lo:[0,0,1] neg_hi:[0,0,1]
	s_mov_b32 s66, s19
	v_pk_add_f32 v[12:13], v[6:7], v[4:5] op_sel:[0,1] op_sel_hi:[1,0] neg_lo:[0,1]
	v_pk_add_f32 v[28:29], v[6:7], v[4:5] op_sel:[0,1] op_sel_hi:[1,0]
	v_pk_add_f32 v[4:5], v[4:5], v[6:7] op_sel:[1,0] op_sel_hi:[0,1] neg_lo:[0,1] neg_hi:[0,1]
	s_nop 0
	v_pk_mul_f32 v[12:13], v[12:13], 0.5 op_sel_hi:[1,0]
	v_mov_b32_e32 v29, v5
	v_mul_f32_e32 v24, v190, v12
	v_pk_fma_f32 v[30:31], v[190:191], v[12:13], v[24:25] op_sel_hi:[1,1,0] neg_lo:[1,0,0] neg_hi:[1,0,0]
	v_mul_f32_e32 v24, v160, v13
	v_pk_fma_f32 v[12:13], v[16:17], v[12:13], v[24:25] op_sel_hi:[1,1,0]
	v_mov_b32_e32 v16, v83
	v_mov_b32_e32 v30, v12
	v_pk_fma_f32 v[4:5], v[28:29], 0.5, v[12:13] op_sel_hi:[1,0,1] neg_lo:[0,0,1] neg_hi:[0,0,1]
	v_pk_fma_f32 v[122:123], v[28:29], 0.5, v[30:31] op_sel_hi:[1,0,1]
	v_pk_fma_f32 v[6:7], v[28:29], 0.5, v[30:31] op_sel_hi:[1,0,1] neg_lo:[1,0,0] neg_hi:[1,0,0]
	v_mov_b32_e32 v5, v123
	v_pk_mul_f32 v[24:25], v[4:5], s[46:47] op_sel_hi:[1,0]
	v_pk_add_f32 v[4:5], v[138:139], v[188:189]
	v_pk_add_f32 v[12:13], v[138:139], v[188:189] neg_lo:[0,1] neg_hi:[0,1]
	v_mov_b32_e32 v17, v82
	v_mul_f32_e32 v6, 0.5, v13
	v_pk_add_f32 v[28:29], v[186:187], v[16:17] neg_lo:[0,1] neg_hi:[0,1]
	v_pk_add_f32 v[30:31], v[186:187], v[16:17]
	v_mov_b32_e32 v13, v5
	v_pk_mov_b32 v[32:33], v[28:29], v[30:31] op_sel:[1,0]
	v_pk_mul_f32 v[12:13], v[12:13], s[44:45]
	v_mul_f32_e32 v4, 0.5, v4
	v_pk_mul_f32 v[48:49], v[32:33], v[12:13] op_sel:[0,1] op_sel_hi:[1,0]
	v_pk_mul_f32 v[12:13], v[32:33], v[12:13]
	v_pk_add_f32 v[48:49], v[48:49], v[48:49] op_sel:[0,1] op_sel_hi:[0,1]
	v_pk_add_f32 v[50:51], v[4:5], v[48:49] op_sel_hi:[0,1] neg_hi:[0,1]
	v_pk_add_f32 v[4:5], v[12:13], v[12:13] op_sel:[0,1] op_sel_hi:[0,1] neg_lo:[0,1] neg_hi:[0,1]
	v_pk_add_f32 v[12:13], v[6:7], v[4:5] op_sel_hi:[0,1] neg_hi:[0,1]
	v_pk_mul_f32 v[4:5], v[12:13], v[184:185]
	v_pk_mul_f32 v[12:13], v[12:13], v[170:171]
	v_pk_fma_f32 v[4:5], v[50:51], v[170:171], v[4:5]
	v_pk_fma_f32 v[12:13], v[50:51], v[184:185], v[12:13] neg_lo:[0,0,1] neg_hi:[0,0,1]
	v_mov_b32_e32 v31, v29
	v_pk_add_f32 v[48:49], v[12:13], v[4:5] op_sel:[0,1] op_sel_hi:[1,0] neg_lo:[0,1]
	v_pk_add_f32 v[50:51], v[12:13], v[4:5] op_sel:[0,1] op_sel_hi:[1,0]
	v_pk_add_f32 v[4:5], v[4:5], v[12:13] op_sel:[1,0] op_sel_hi:[0,1] neg_lo:[0,1] neg_hi:[0,1]
	v_pk_mul_f32 v[48:49], v[48:49], 0.5 op_sel_hi:[1,0]
	v_mov_b32_e32 v51, v5
	v_mul_f32_e32 v6, v29, v48
	v_pk_fma_f32 v[32:33], v[32:33], v[48:49], v[6:7] op_sel_hi:[1,1,0] neg_lo:[1,0,0] neg_hi:[1,0,0]
	v_mul_f32_e32 v6, v29, v49
	v_pk_fma_f32 v[28:29], v[30:31], v[48:49], v[6:7] op_sel_hi:[1,1,0]
	v_pk_mul_f32 v[12:13], v[16:17], s[36:37]
	v_mov_b32_e32 v32, v28
	v_pk_fma_f32 v[4:5], v[50:51], 0.5, v[28:29] op_sel_hi:[1,0,1] neg_lo:[0,0,1] neg_hi:[0,0,1]
	v_pk_fma_f32 v[138:139], v[50:51], 0.5, v[32:33] op_sel_hi:[1,0,1]
	v_pk_add_f32 v[16:17], v[92:93], v[182:183]
	v_mov_b32_e32 v5, v139
	v_pk_add_f32 v[28:29], v[92:93], v[182:183] neg_lo:[0,1] neg_hi:[0,1]
	v_pk_mul_f32 v[30:31], v[4:5], s[46:47] op_sel_hi:[1,0]
	v_pk_fma_f32 v[4:5], v[50:51], 0.5, v[32:33] op_sel_hi:[1,0,1] neg_lo:[1,0,0] neg_hi:[1,0,0]
	v_mul_f32_e32 v6, 0.5, v29
	v_pk_add_f32 v[32:33], v[18:19], v[12:13] op_sel:[0,1] op_sel_hi:[0,1] neg_lo:[0,1] neg_hi:[0,1]
	v_pk_add_f32 v[48:49], v[18:19], v[12:13] op_sel:[0,1] op_sel_hi:[0,1]
	v_mov_b32_e32 v29, v17
	v_mul_f32_e32 v4, 0.5, v16
	v_mov_b32_e32 v50, v32
	v_mov_b32_e32 v51, v49
	v_pk_mul_f32 v[16:17], v[28:29], s[44:45]
	v_pk_mov_b32 v[48:49], v[48:49], v[32:33] op_sel:[1,0]
	v_pk_mul_f32 v[28:29], v[50:51], v[16:17] op_sel:[0,1] op_sel_hi:[1,0]
	v_pk_mul_f32 v[16:17], v[50:51], v[16:17]
	v_pk_add_f32 v[28:29], v[28:29], v[28:29] op_sel:[0,1] op_sel_hi:[0,1]
	v_pk_add_f32 v[52:53], v[4:5], v[28:29] op_sel_hi:[0,1] neg_hi:[0,1]
	v_pk_add_f32 v[16:17], v[16:17], v[16:17] op_sel:[0,1] op_sel_hi:[0,1] neg_lo:[0,1] neg_hi:[0,1]
	v_pk_add_f32 v[28:29], v[6:7], v[16:17] op_sel_hi:[0,1] neg_hi:[0,1]
	v_pk_mul_f32 v[16:17], v[28:29], v[180:181]
	v_pk_mul_f32 v[28:29], v[28:29], v[172:173]
	v_pk_fma_f32 v[16:17], v[52:53], v[172:173], v[16:17]
	v_pk_fma_f32 v[28:29], v[52:53], v[180:181], v[28:29] neg_lo:[0,0,1] neg_hi:[0,0,1]
	v_sub_f32_e32 v6, v89, v177
	v_pk_add_f32 v[52:53], v[28:29], v[16:17] op_sel:[0,1] op_sel_hi:[1,0] neg_lo:[0,1]
	v_pk_add_f32 v[54:55], v[28:29], v[16:17] op_sel:[0,1] op_sel_hi:[1,0]
	v_pk_add_f32 v[16:17], v[16:17], v[28:29] op_sel:[1,0] op_sel_hi:[0,1] neg_lo:[0,1] neg_hi:[0,1]
	v_pk_mul_f32 v[52:53], v[52:53], 0.5 op_sel_hi:[1,0]
	v_mov_b32_e32 v55, v17
	v_mul_f32_e32 v4, v32, v52
	v_pk_fma_f32 v[56:57], v[50:51], v[52:53], v[4:5] op_sel_hi:[1,1,0] neg_lo:[1,0,0] neg_hi:[1,0,0]
	v_mul_f32_e32 v4, v32, v53
	v_pk_fma_f32 v[48:49], v[48:49], v[52:53], v[4:5] op_sel_hi:[1,1,0]
	v_pk_add_f32 v[28:29], v[88:89], v[176:177]
	v_mov_b32_e32 v56, v48
	v_pk_fma_f32 v[16:17], v[54:55], 0.5, v[48:49] op_sel_hi:[1,0,1] neg_lo:[0,0,1] neg_hi:[0,0,1]
	v_mov_b32_e32 v48, v12
	v_mov_b32_e32 v49, v88
	v_pk_mov_b32 v[12:13], v[12:13], v[176:177] op_sel:[1,0]
	v_mul_f32_e32 v18, 0.5, v29
	v_pk_add_f32 v[12:13], v[48:49], v[12:13] neg_lo:[0,1] neg_hi:[0,1]
	v_mul_f32_e32 v4, 0.5, v28
	v_pk_mul_f32 v[48:49], v[12:13], v[18:19]
	v_mov_b32_e32 v13, v32
	v_pk_fma_f32 v[50:51], v[50:51], v[48:49], v[48:49] op_sel:[0,1,0] op_sel_hi:[1,0,1]
	v_mov_b32_e32 v48, v49
	v_mov_b32_e32 v49, v18
	v_pk_mul_f32 v[48:49], v[12:13], v[48:49]
	v_pk_add_f32 v[52:53], v[4:5], v[50:51]
	v_mul_f32_e32 v6, 0.5, v6
	v_fma_f32 v53, v28, 0.5, -v50
	v_pk_add_f32 v[28:29], v[48:49], v[48:49] op_sel:[0,1] op_sel_hi:[0,1] neg_lo:[0,1] neg_hi:[0,1]
	v_pk_add_f32 v[48:49], v[6:7], v[28:29] op_sel_hi:[0,1] neg_hi:[0,1]
	v_pk_mul_f32 v[28:29], v[48:49], v[178:179]
	v_pk_mul_f32 v[48:49], v[48:49], v[174:175]
	v_pk_fma_f32 v[28:29], v[52:53], v[174:175], v[28:29]
	v_pk_fma_f32 v[48:49], v[52:53], v[178:179], v[48:49] neg_lo:[0,0,1] neg_hi:[0,0,1]
	v_pk_fma_f32 v[92:93], v[54:55], 0.5, v[56:57] op_sel_hi:[1,0,1]
	v_pk_add_f32 v[50:51], v[48:49], v[28:29] op_sel:[0,1] op_sel_hi:[1,0] neg_lo:[0,1]
	v_pk_add_f32 v[52:53], v[48:49], v[28:29] op_sel:[0,1] op_sel_hi:[1,0]
	v_mov_b32_e32 v17, v93
	v_pk_mul_f32 v[50:51], v[50:51], 0.5 op_sel_hi:[1,0]
	v_pk_mul_f32 v[64:65], v[16:17], s[46:47] op_sel_hi:[1,0]
	v_mul_f32_e32 v4, v12, v50
	v_pk_fma_f32 v[16:17], v[54:55], 0.5, v[56:57] op_sel_hi:[1,0,1] neg_lo:[1,0,0] neg_hi:[1,0,0]
	v_pk_fma_f32 v[54:55], v[12:13], v[50:51], v[4:5] op_sel_hi:[1,1,0] neg_lo:[1,0,0] neg_hi:[1,0,0]
	v_mov_b32_e32 v33, v12
	v_mul_f32_e32 v4, v12, v51
	v_pk_fma_f32 v[12:13], v[32:33], v[50:51], v[4:5] op_sel_hi:[1,1,0]
	v_pk_add_f32 v[28:29], v[28:29], v[48:49] op_sel:[1,0] op_sel_hi:[0,1] neg_lo:[0,1] neg_hi:[0,1]
	v_mov_b32_e32 v53, v29
	v_mov_b32_e32 v54, v12
	v_pk_fma_f32 v[12:13], v[52:53], 0.5, v[12:13] op_sel_hi:[1,0,1] neg_lo:[0,0,1] neg_hi:[0,0,1]
	v_pk_fma_f32 v[88:89], v[52:53], 0.5, v[54:55] op_sel_hi:[1,0,1]
	s_mov_b32 s67, s16
	v_mov_b32_e32 v13, v89
	v_pk_mul_f32 v[68:69], v[12:13], s[46:47] op_sel_hi:[1,0]
	v_pk_fma_f32 v[12:13], v[52:53], 0.5, v[54:55] op_sel_hi:[1,0,1] neg_lo:[1,0,0] neg_hi:[1,0,0]
	v_mov_b32_e32 v4, v83
	s_mov_b32 s17, s19
	v_pk_mul_f32 v[48:49], v[82:83], s[66:67] op_sel_hi:[0,1]
	v_pk_add_f32 v[28:29], v[96:97], v[162:163]
	v_pk_add_f32 v[32:33], v[96:97], v[162:163] neg_lo:[0,1] neg_hi:[0,1]
	v_pk_fma_f32 v[52:53], v[4:5], s[16:17], v[48:49] op_sel_hi:[0,1,1] neg_lo:[0,0,1] neg_hi:[0,0,1]
	v_mul_f32_e32 v12, 0.5, v33
	v_pk_fma_f32 v[50:51], v[4:5], s[16:17], v[48:49] op_sel_hi:[0,1,1]
	v_mov_b32_e32 v33, v29
	v_mul_f32_e32 v6, 0.5, v28
	v_mov_b32_e32 v54, v52
	v_mov_b32_e32 v55, v51
	v_pk_mul_f32 v[28:29], v[32:33], s[44:45]
	v_pk_mov_b32 v[56:57], v[50:51], v[52:53] op_sel:[1,0]
	v_pk_mul_f32 v[32:33], v[54:55], v[28:29] op_sel:[0,1] op_sel_hi:[1,0]
	v_pk_mul_f32 v[28:29], v[54:55], v[28:29]
	v_pk_add_f32 v[32:33], v[32:33], v[32:33] op_sel:[0,1] op_sel_hi:[0,1]
	v_pk_add_f32 v[58:59], v[6:7], v[32:33] op_sel_hi:[0,1] neg_hi:[0,1]
	v_pk_add_f32 v[28:29], v[28:29], v[28:29] op_sel:[0,1] op_sel_hi:[0,1] neg_lo:[0,1] neg_hi:[0,1]
	v_pk_add_f32 v[32:33], v[12:13], v[28:29] op_sel_hi:[0,1] neg_hi:[0,1]
	v_pk_mul_f32 v[28:29], v[32:33], v[166:167]
	v_pk_mul_f32 v[32:33], v[32:33], v[164:165]
	v_pk_fma_f32 v[28:29], v[58:59], v[164:165], v[28:29]
	v_pk_fma_f32 v[32:33], v[58:59], v[166:167], v[32:33] neg_lo:[0,0,1] neg_hi:[0,0,1]
	v_mov_b32_e32 v159, v66
	v_pk_add_f32 v[58:59], v[32:33], v[28:29] op_sel:[0,1] op_sel_hi:[1,0] neg_lo:[0,1]
	v_pk_add_f32 v[70:71], v[32:33], v[28:29] op_sel:[0,1] op_sel_hi:[1,0]
	v_pk_add_f32 v[28:29], v[28:29], v[32:33] op_sel:[1,0] op_sel_hi:[0,1] neg_lo:[0,1] neg_hi:[0,1]
	v_pk_mul_f32 v[58:59], v[58:59], 0.5 op_sel_hi:[1,0]
	v_mov_b32_e32 v71, v29
	v_mul_f32_e32 v6, v52, v58
	v_pk_fma_f32 v[72:73], v[54:55], v[58:59], v[6:7] op_sel_hi:[1,1,0] neg_lo:[1,0,0] neg_hi:[1,0,0]
	v_mul_f32_e32 v6, v52, v59
	v_pk_fma_f32 v[56:57], v[56:57], v[58:59], v[6:7] op_sel_hi:[1,1,0]
	v_sub_f32_e32 v12, v67, v153
	v_mov_b32_e32 v72, v56
	v_pk_fma_f32 v[28:29], v[70:71], 0.5, v[56:57] op_sel_hi:[1,0,1] neg_lo:[0,0,1] neg_hi:[0,0,1]
	v_pk_fma_f32 v[96:97], v[70:71], 0.5, v[72:73] op_sel_hi:[1,0,1]
	v_pk_mov_b32 v[56:57], v[48:49], v[152:153] op_sel:[1,0]
	v_mov_b32_e32 v29, v97
	v_pk_mul_f32 v[62:63], v[28:29], s[46:47] op_sel_hi:[1,0]
	v_pk_add_f32 v[28:29], v[66:67], v[152:153]
	v_pk_add_f32 v[56:57], v[158:159], v[56:57] neg_lo:[0,1] neg_hi:[0,1]
	v_mul_f32_e32 v18, 0.5, v29
	v_pk_mul_f32 v[58:59], v[56:57], v[18:19]
	v_mul_f32_e32 v6, 0.5, v28
	v_pk_fma_f32 v[54:55], v[54:55], v[58:59], v[58:59] op_sel:[0,1,0] op_sel_hi:[1,0,1]
	v_mov_b32_e32 v66, v56
	v_mov_b32_e32 v67, v52
	v_mov_b32_e32 v58, v59
	v_mov_b32_e32 v59, v18
	v_pk_mul_f32 v[58:59], v[66:67], v[58:59]
	v_pk_add_f32 v[66:67], v[6:7], v[54:55]
	v_mul_f32_e32 v12, 0.5, v12
	v_fma_f32 v67, v28, 0.5, -v54
	v_pk_add_f32 v[28:29], v[58:59], v[58:59] op_sel:[0,1] op_sel_hi:[0,1] neg_lo:[0,1] neg_hi:[0,1]
	v_pk_add_f32 v[54:55], v[12:13], v[28:29] op_sel_hi:[0,1] neg_hi:[0,1]
	v_pk_mul_f32 v[28:29], v[54:55], v[156:157]
	v_pk_mul_f32 v[54:55], v[54:55], v[154:155]
	v_pk_fma_f32 v[32:33], v[70:71], 0.5, v[72:73] op_sel_hi:[1,0,1] neg_lo:[1,0,0] neg_hi:[1,0,0]
	v_pk_fma_f32 v[58:59], v[66:67], v[154:155], v[28:29] neg_lo:[0,0,1] neg_hi:[0,0,1]
	v_pk_fma_f32 v[28:29], v[66:67], v[154:155], v[28:29]
	v_pk_fma_f32 v[70:71], v[66:67], v[156:157], v[54:55]
	v_pk_fma_f32 v[54:55], v[66:67], v[156:157], v[54:55] neg_lo:[0,0,1] neg_hi:[0,0,1]
	v_pk_add_f32 v[72:73], v[58:59], v[28:29] op_sel:[0,1] op_sel_hi:[1,0]
	v_pk_add_f32 v[66:67], v[70:71], v[54:55] op_sel_hi:[0,1] neg_lo:[0,1] neg_hi:[0,1]
	v_pk_add_f32 v[28:29], v[58:59], v[28:29] op_sel_hi:[0,1] neg_lo:[0,1] neg_hi:[0,1]
	v_pk_add_f32 v[54:55], v[70:71], v[54:55] op_sel:[0,1] op_sel_hi:[1,0]
	v_mov_b32_e32 v73, v67
	v_mov_b32_e32 v55, v29
	v_pk_mul_f32 v[28:29], v[54:55], 0.5 op_sel_hi:[1,0]
	v_mov_b32_e32 v133, v84
	v_pk_mul_f32 v[54:55], v[52:53], v[28:29] op_sel:[0,1] op_sel_hi:[0,0]
	v_pk_fma_f32 v[58:59], v[56:57], v[28:29], v[54:55] op_sel_hi:[0,1,1]
	v_pk_fma_f32 v[28:29], v[56:57], v[28:29], v[54:55] op_sel_hi:[0,1,1] neg_hi:[0,0,1]
	v_pk_fma_f32 v[54:55], v[72:73], 0.5, v[58:59] op_sel_hi:[1,0,1] neg_lo:[0,0,1] neg_hi:[0,0,1]
	v_pk_fma_f32 v[66:67], v[72:73], 0.5, v[28:29] op_sel_hi:[1,0,1]
	v_pk_add_f32 v[56:57], v[60:61], v[134:135] neg_lo:[0,1] neg_hi:[0,1]
	v_mov_b32_e32 v55, v67
	v_pk_mul_f32 v[90:91], v[54:55], s[46:47] op_sel_hi:[1,0]
	v_pk_add_f32 v[54:55], v[134:135], v[60:61]
	v_mul_f32_e32 v12, 0.5, v57
	v_mov_b32_e32 v57, v55
	v_mul_f32_e32 v6, 0.5, v54
	v_pk_mov_b32 v[58:59], v[52:53], v[50:51] op_sel:[1,0]
	v_pk_mul_f32 v[54:55], v[56:57], s[44:45]
	v_pk_fma_f32 v[28:29], v[72:73], 0.5, v[28:29] op_sel_hi:[1,0,1] neg_lo:[1,0,0] neg_hi:[1,0,0]
	v_pk_mul_f32 v[56:57], v[58:59], v[54:55] op_sel:[0,1] op_sel_hi:[1,0]
	v_pk_mul_f32 v[54:55], v[58:59], v[54:55]
	v_pk_add_f32 v[56:57], v[56:57], v[56:57] op_sel:[0,1] op_sel_hi:[0,1]
	v_pk_add_f32 v[60:61], v[6:7], v[56:57] op_sel_hi:[0,1] neg_hi:[0,1]
	v_pk_add_f32 v[54:55], v[54:55], v[54:55] op_sel:[0,1] op_sel_hi:[0,1] neg_lo:[0,1] neg_hi:[0,1]
	v_pk_add_f32 v[56:57], v[12:13], v[54:55] op_sel_hi:[0,1] neg_hi:[0,1]
	v_pk_mul_f32 v[54:55], v[56:57], v[142:143]
	v_pk_mul_f32 v[56:57], v[56:57], v[140:141]
	v_pk_fma_f32 v[54:55], v[60:61], v[140:141], v[54:55]
	v_pk_fma_f32 v[56:57], v[60:61], v[142:143], v[56:57] neg_lo:[0,0,1] neg_hi:[0,0,1]
	v_mov_b32_e32 v51, v53
	v_pk_add_f32 v[60:61], v[56:57], v[54:55] op_sel:[0,1] op_sel_hi:[1,0] neg_lo:[0,1]
	v_pk_add_f32 v[70:71], v[56:57], v[54:55] op_sel:[0,1] op_sel_hi:[1,0]
	v_pk_add_f32 v[54:55], v[54:55], v[56:57] op_sel:[1,0] op_sel_hi:[0,1] neg_lo:[0,1] neg_hi:[0,1]
	v_pk_mul_f32 v[60:61], v[60:61], 0.5 op_sel_hi:[1,0]
	v_mov_b32_e32 v71, v55
	v_mul_f32_e32 v6, v53, v60
	v_pk_fma_f32 v[72:73], v[58:59], v[60:61], v[6:7] op_sel_hi:[1,1,0] neg_lo:[1,0,0] neg_hi:[1,0,0]
	v_mul_f32_e32 v6, v53, v61
	v_pk_fma_f32 v[50:51], v[50:51], v[60:61], v[6:7] op_sel_hi:[1,1,0]
	v_pk_add_f32 v[54:55], v[118:119], v[84:85]
	v_mov_b32_e32 v72, v50
	v_mov_b32_e32 v49, v118
	v_pk_fma_f32 v[50:51], v[70:71], 0.5, v[50:51] op_sel_hi:[1,0,1] neg_lo:[0,0,1] neg_hi:[0,0,1]
	v_pk_fma_f32 v[60:61], v[70:71], 0.5, v[72:73] op_sel_hi:[1,0,1]
	v_mul_f32_e32 v18, 0.5, v55
	v_pk_add_f32 v[48:49], v[132:133], v[48:49] neg_lo:[0,1] neg_hi:[0,1]
	v_mov_b32_e32 v51, v61
	v_pk_mul_f32 v[56:57], v[48:49], v[18:19]
	v_pk_mul_f32 v[94:95], v[50:51], s[46:47] op_sel_hi:[1,0]
	v_pk_fma_f32 v[50:51], v[70:71], 0.5, v[72:73] op_sel_hi:[1,0,1] neg_lo:[1,0,0] neg_hi:[1,0,0]
	v_mul_f32_e32 v6, 0.5, v54
	v_pk_fma_f32 v[58:59], v[58:59], v[56:57], v[56:57] op_sel:[0,1,0] op_sel_hi:[1,0,1]
	v_mov_b32_e32 v70, v48
	v_mov_b32_e32 v71, v53
	v_mov_b32_e32 v56, v57
	v_mov_b32_e32 v57, v18
	v_sub_f32_e32 v12, v85, v119
	v_pk_mul_f32 v[56:57], v[70:71], v[56:57]
	v_pk_add_f32 v[70:71], v[6:7], v[58:59]
	v_mul_f32_e32 v12, 0.5, v12
	v_fma_f32 v71, v54, 0.5, -v58
	v_pk_add_f32 v[54:55], v[56:57], v[56:57] op_sel:[0,1] op_sel_hi:[0,1] neg_lo:[0,1] neg_hi:[0,1]
	v_pk_add_f32 v[56:57], v[12:13], v[54:55] op_sel_hi:[0,1] neg_hi:[0,1]
	v_pk_mul_f32 v[54:55], v[56:57], v[126:127]
	v_pk_mul_f32 v[56:57], v[56:57], v[124:125]
	v_pk_fma_f32 v[58:59], v[70:71], v[124:125], v[54:55] neg_lo:[0,0,1] neg_hi:[0,0,1]
	v_pk_fma_f32 v[54:55], v[70:71], v[124:125], v[54:55]
	v_pk_fma_f32 v[72:73], v[70:71], v[126:127], v[56:57]
	v_pk_fma_f32 v[56:57], v[70:71], v[126:127], v[56:57] neg_lo:[0,0,1] neg_hi:[0,0,1]
	v_pk_add_f32 v[70:71], v[58:59], v[54:55] op_sel:[0,1] op_sel_hi:[1,0]
	v_pk_add_f32 v[74:75], v[72:73], v[56:57] op_sel_hi:[0,1] neg_lo:[0,1] neg_hi:[0,1]
	v_pk_add_f32 v[54:55], v[58:59], v[54:55] op_sel_hi:[0,1] neg_lo:[0,1] neg_hi:[0,1]
	v_pk_add_f32 v[56:57], v[72:73], v[56:57] op_sel:[0,1] op_sel_hi:[1,0]
	v_mov_b32_e32 v71, v75
	v_mov_b32_e32 v57, v55
	v_pk_mul_f32 v[54:55], v[56:57], 0.5 op_sel_hi:[1,0]
	s_mov_b32 s66, s11
	v_pk_mul_f32 v[52:53], v[52:53], v[54:55] op_sel:[1,1] op_sel_hi:[1,0]
	s_mov_b32 s67, s8
	v_pk_fma_f32 v[56:57], v[48:49], v[54:55], v[52:53] op_sel_hi:[0,1,1]
	v_pk_fma_f32 v[48:49], v[48:49], v[54:55], v[52:53] op_sel_hi:[0,1,1] neg_hi:[0,0,1]
	s_nop 0
	v_pk_fma_f32 v[52:53], v[70:71], 0.5, v[56:57] op_sel_hi:[1,0,1] neg_lo:[0,0,1] neg_hi:[0,0,1]
	v_pk_fma_f32 v[84:85], v[70:71], 0.5, v[48:49] op_sel_hi:[1,0,1]
	s_mov_b32 s9, s11
	v_mov_b32_e32 v53, v85
	v_pk_mul_f32 v[80:81], v[52:53], s[46:47] op_sel_hi:[1,0]
	v_pk_mul_f32 v[118:119], v[82:83], s[66:67] op_sel_hi:[0,1]
	v_pk_add_f32 v[52:53], v[86:87], v[112:113]
	v_pk_add_f32 v[54:55], v[86:87], v[112:113] neg_lo:[0,1] neg_hi:[0,1]
	v_pk_fma_f32 v[58:59], v[4:5], s[8:9], v[118:119] op_sel_hi:[0,1,1] neg_lo:[0,0,1] neg_hi:[0,0,1]
	v_mul_f32_e32 v12, 0.5, v55
	v_pk_fma_f32 v[72:73], v[4:5], s[8:9], v[118:119] op_sel_hi:[0,1,1]
	v_mov_b32_e32 v55, v53
	v_mul_f32_e32 v6, 0.5, v52
	v_mov_b32_e32 v56, v58
	v_mov_b32_e32 v57, v73
	v_pk_mul_f32 v[52:53], v[54:55], s[44:45]
	v_pk_fma_f32 v[48:49], v[70:71], 0.5, v[48:49] op_sel_hi:[1,0,1] neg_lo:[1,0,0] neg_hi:[1,0,0]
	v_pk_mul_f32 v[54:55], v[56:57], v[52:53] op_sel:[0,1] op_sel_hi:[1,0]
	v_pk_mul_f32 v[52:53], v[56:57], v[52:53]
	v_pk_add_f32 v[54:55], v[54:55], v[54:55] op_sel:[0,1] op_sel_hi:[0,1]
	v_pk_add_f32 v[74:75], v[6:7], v[54:55] op_sel_hi:[0,1] neg_hi:[0,1]
	v_pk_add_f32 v[52:53], v[52:53], v[52:53] op_sel:[0,1] op_sel_hi:[0,1] neg_lo:[0,1] neg_hi:[0,1]
	v_pk_add_f32 v[54:55], v[12:13], v[52:53] op_sel_hi:[0,1] neg_hi:[0,1]
	v_pk_mul_f32 v[52:53], v[54:55], v[116:117]
	v_pk_mul_f32 v[54:55], v[54:55], v[114:115]
	v_pk_fma_f32 v[52:53], v[74:75], v[114:115], v[52:53]
	v_pk_fma_f32 v[54:55], v[74:75], v[116:117], v[54:55] neg_lo:[0,0,1] neg_hi:[0,0,1]
	v_pk_mov_b32 v[70:71], v[72:73], v[58:59] op_sel:[1,0]
	v_pk_add_f32 v[74:75], v[54:55], v[52:53] op_sel:[0,1] op_sel_hi:[1,0] neg_lo:[0,1]
	v_pk_add_f32 v[76:77], v[54:55], v[52:53] op_sel:[0,1] op_sel_hi:[1,0]
	v_pk_add_f32 v[52:53], v[52:53], v[54:55] op_sel:[1,0] op_sel_hi:[0,1] neg_lo:[0,1] neg_hi:[0,1]
	v_pk_mul_f32 v[74:75], v[74:75], 0.5 op_sel_hi:[1,0]
	v_mov_b32_e32 v77, v53
	v_mul_f32_e32 v6, v58, v74
	v_pk_fma_f32 v[112:113], v[56:57], v[74:75], v[6:7] op_sel_hi:[1,1,0] neg_lo:[1,0,0] neg_hi:[1,0,0]
	v_mul_f32_e32 v6, v58, v75
	v_pk_fma_f32 v[70:71], v[70:71], v[74:75], v[6:7] op_sel_hi:[1,1,0]
	v_pk_add_f32 v[54:55], v[34:35], v[110:111]
	v_mov_b32_e32 v112, v70
	v_pk_fma_f32 v[52:53], v[76:77], 0.5, v[70:71] op_sel_hi:[1,0,1] neg_lo:[0,0,1] neg_hi:[0,0,1]
	v_pk_fma_f32 v[86:87], v[76:77], 0.5, v[112:113] op_sel_hi:[1,0,1]
	v_sub_f32_e32 v12, v35, v111
	v_mov_b32_e32 v53, v87
	v_pk_mul_f32 v[78:79], v[52:53], s[46:47] op_sel_hi:[1,0]
	v_mul_f32_e32 v52, 0xbe47c5c2, v83
	v_mov_b32_e32 v53, v34
	v_pk_mov_b32 v[34:35], v[118:119], v[110:111] op_sel:[1,0]
	v_mul_f32_e32 v18, 0.5, v55
	v_pk_add_f32 v[34:35], v[52:53], v[34:35] neg_lo:[0,1] neg_hi:[0,1]
	v_mov_b32_e32 v71, v58
	v_pk_mul_f32 v[52:53], v[34:35], v[18:19]
	v_mov_b32_e32 v70, v34
	v_pk_fma_f32 v[56:57], v[56:57], v[52:53], v[52:53] op_sel:[0,1,0] op_sel_hi:[1,0,1]
	v_mov_b32_e32 v52, v53
	v_mov_b32_e32 v53, v18
	v_mul_f32_e32 v6, 0.5, v54
	v_pk_mul_f32 v[52:53], v[70:71], v[52:53]
	v_cvt_f32_f16_e32 v70, v46
	v_cvt_f32_f16_e32 v71, v47
	v_cvt_f32_f16_sdwa v47, v47 dst_sel:DWORD dst_unused:UNUSED_PAD src0_sel:WORD_1
	v_cvt_f32_f16_sdwa v46, v46 dst_sel:DWORD dst_unused:UNUSED_PAD src0_sel:WORD_1
	v_pk_fma_f32 v[74:75], v[76:77], 0.5, v[112:113] op_sel_hi:[1,0,1] neg_lo:[1,0,0] neg_hi:[1,0,0]
	v_mul_f32_e32 v12, 0.5, v12
	v_pk_add_f32 v[76:77], v[6:7], v[56:57]
	v_pk_add_f32 v[52:53], v[52:53], v[52:53] op_sel:[0,1] op_sel_hi:[0,1] neg_lo:[0,1] neg_hi:[0,1]
	v_fma_f32 v77, v54, 0.5, -v56
	v_pk_add_f32 v[54:55], v[12:13], v[52:53] op_sel_hi:[0,1] neg_hi:[0,1]
	v_pk_mul_f32 v[52:53], v[54:55], v[46:47]
	v_pk_mul_f32 v[54:55], v[54:55], v[70:71]
	v_pk_fma_f32 v[56:57], v[76:77], v[70:71], v[52:53] neg_lo:[0,0,1] neg_hi:[0,0,1]
	v_pk_fma_f32 v[52:53], v[76:77], v[70:71], v[52:53]
	v_pk_fma_f32 v[70:71], v[76:77], v[46:47], v[54:55]
	v_pk_fma_f32 v[46:47], v[76:77], v[46:47], v[54:55] neg_lo:[0,0,1] neg_hi:[0,0,1]
	v_pk_add_f32 v[54:55], v[56:57], v[52:53] op_sel:[0,1] op_sel_hi:[1,0]
	v_pk_add_f32 v[76:77], v[70:71], v[46:47] op_sel_hi:[0,1] neg_lo:[0,1] neg_hi:[0,1]
	v_pk_add_f32 v[52:53], v[56:57], v[52:53] op_sel_hi:[0,1] neg_lo:[0,1] neg_hi:[0,1]
	v_pk_add_f32 v[46:47], v[70:71], v[46:47] op_sel:[0,1] op_sel_hi:[1,0]
	v_mov_b32_e32 v55, v77
	v_mov_b32_e32 v47, v53
	v_pk_mul_f32 v[46:47], v[46:47], 0.5 op_sel_hi:[1,0]
	s_mov_b32 s25, s27
	v_pk_mul_f32 v[52:53], v[58:59], v[46:47] op_sel:[0,1] op_sel_hi:[0,0]
	v_pk_fma_f32 v[56:57], v[34:35], v[46:47], v[52:53] op_sel_hi:[0,1,1]
	v_pk_fma_f32 v[46:47], v[34:35], v[46:47], v[52:53] op_sel_hi:[0,1,1] neg_hi:[0,0,1]
	s_nop 0
	v_pk_fma_f32 v[52:53], v[54:55], 0.5, v[56:57] op_sel_hi:[1,0,1] neg_lo:[0,0,1] neg_hi:[0,0,1]
	v_pk_fma_f32 v[34:35], v[54:55], 0.5, v[46:47] op_sel_hi:[1,0,1]
	s_mov_b32 s66, s27
	v_mov_b32_e32 v53, v35
	v_pk_mul_f32 v[136:137], v[52:53], s[46:47] op_sel_hi:[1,0]
	v_pk_fma_f32 v[52:53], v[54:55], 0.5, v[46:47] op_sel_hi:[1,0,1] neg_lo:[1,0,0] neg_hi:[1,0,0]
	s_mov_b32 s67, s24
	v_pk_mul_f32 v[46:47], v[82:83], s[24:25] op_sel_hi:[0,1]
	v_pk_add_f32 v[54:55], v[108:109], v[40:41]
	v_pk_add_f32 v[40:41], v[40:41], v[108:109] neg_lo:[0,1] neg_hi:[0,1]
	v_pk_fma_f32 v[108:109], v[4:5], s[66:67], v[46:47] op_sel_hi:[0,1,1] neg_lo:[0,0,1] neg_hi:[0,0,1]
	v_mul_f32_e32 v12, 0.5, v41
	v_pk_fma_f32 v[70:71], v[4:5], s[66:67], v[46:47] op_sel_hi:[0,1,1]
	v_mov_b32_e32 v41, v55
	v_mov_b32_e32 v56, v108
	v_mov_b32_e32 v57, v71
	v_pk_mul_f32 v[40:41], v[40:41], s[44:45]
	v_mul_f32_e32 v6, 0.5, v54
	v_pk_mul_f32 v[54:55], v[56:57], v[40:41] op_sel:[0,1] op_sel_hi:[1,0]
	v_cvt_f32_f16_sdwa v76, v38 dst_sel:DWORD dst_unused:UNUSED_PAD src0_sel:WORD_1
	v_cvt_f32_f16_e32 v77, v39
	v_cvt_f32_f16_sdwa v39, v39 dst_sel:DWORD dst_unused:UNUSED_PAD src0_sel:WORD_1
	v_cvt_f32_f16_e32 v38, v38
	v_pk_mul_f32 v[40:41], v[56:57], v[40:41]
	v_pk_add_f32 v[54:55], v[54:55], v[54:55] op_sel:[0,1] op_sel_hi:[0,1]
	v_pk_add_f32 v[112:113], v[6:7], v[54:55] op_sel_hi:[0,1] neg_hi:[0,1]
	s_nop 0
	v_pk_add_f32 v[40:41], v[40:41], v[40:41] op_sel:[0,1] op_sel_hi:[0,1] neg_lo:[0,1] neg_hi:[0,1]
	v_pk_add_f32 v[54:55], v[12:13], v[40:41] op_sel_hi:[0,1] neg_hi:[0,1]
	v_pk_mul_f32 v[40:41], v[54:55], v[38:39]
	v_pk_mul_f32 v[54:55], v[54:55], v[76:77]
	v_pk_fma_f32 v[40:41], v[112:113], v[76:77], v[40:41]
	v_pk_fma_f32 v[38:39], v[112:113], v[38:39], v[54:55] neg_lo:[0,0,1] neg_hi:[0,0,1]
	v_pk_mov_b32 v[110:111], v[70:71], v[108:109] op_sel:[1,0]
	v_pk_add_f32 v[54:55], v[38:39], v[40:41] op_sel:[0,1] op_sel_hi:[1,0] neg_lo:[0,1]
	v_pk_add_f32 v[76:77], v[38:39], v[40:41] op_sel:[0,1] op_sel_hi:[1,0]
	v_pk_add_f32 v[38:39], v[40:41], v[38:39] op_sel:[1,0] op_sel_hi:[0,1] neg_lo:[0,1] neg_hi:[0,1]
	v_pk_mul_f32 v[54:55], v[54:55], 0.5 op_sel_hi:[1,0]
	v_mov_b32_e32 v77, v39
	v_mul_f32_e32 v4, v108, v54
	v_pk_fma_f32 v[112:113], v[56:57], v[54:55], v[4:5] op_sel_hi:[1,1,0] neg_lo:[1,0,0] neg_hi:[1,0,0]
	v_mul_f32_e32 v4, v108, v55
	v_pk_fma_f32 v[54:55], v[110:111], v[54:55], v[4:5] op_sel_hi:[1,1,0]
	v_sub_f32_e32 v6, v45, v105
	v_mov_b32_e32 v112, v54
	v_pk_fma_f32 v[40:41], v[76:77], 0.5, v[54:55] op_sel_hi:[1,0,1] neg_lo:[0,0,1] neg_hi:[0,0,1]
	v_pk_fma_f32 v[38:39], v[76:77], 0.5, v[112:113] op_sel_hi:[1,0,1]
	v_pk_add_f32 v[54:55], v[104:105], v[44:45]
	v_mov_b32_e32 v41, v39
	v_pk_mul_f32 v[130:131], v[40:41], s[46:47] op_sel_hi:[1,0]
	v_mul_f32_e32 v40, 0xbf54db31, v83
	v_mov_b32_e32 v41, v44
	v_pk_mov_b32 v[44:45], v[46:47], v[104:105] op_sel:[1,0]
	v_mul_f32_e32 v18, 0.5, v55
	v_pk_add_f32 v[40:41], v[40:41], v[44:45] neg_lo:[0,1] neg_hi:[0,1]
	v_mov_b32_e32 v105, v108
	v_pk_mul_f32 v[44:45], v[40:41], v[18:19]
	v_mov_b32_e32 v104, v40
	v_pk_fma_f32 v[56:57], v[56:57], v[44:45], v[44:45] op_sel:[0,1,0] op_sel_hi:[1,0,1]
	v_mov_b32_e32 v44, v45
	v_mov_b32_e32 v45, v18
	v_mul_f32_e32 v4, 0.5, v54
	v_pk_mul_f32 v[44:45], v[104:105], v[44:45]
	v_cvt_f32_f16_e32 v104, v26
	v_cvt_f32_f16_e32 v105, v27
	v_cvt_f32_f16_sdwa v27, v27 dst_sel:DWORD dst_unused:UNUSED_PAD src0_sel:WORD_1
	v_cvt_f32_f16_sdwa v26, v26 dst_sel:DWORD dst_unused:UNUSED_PAD src0_sel:WORD_1
	v_mul_f32_e32 v6, 0.5, v6
	v_pk_add_f32 v[110:111], v[4:5], v[56:57]
	v_pk_add_f32 v[44:45], v[44:45], v[44:45] op_sel:[0,1] op_sel_hi:[0,1] neg_lo:[0,1] neg_hi:[0,1]
	v_fma_f32 v111, v54, 0.5, -v56
	v_pk_add_f32 v[54:55], v[6:7], v[44:45] op_sel_hi:[0,1] neg_hi:[0,1]
	v_pk_mul_f32 v[44:45], v[54:55], v[26:27]
	v_pk_mul_f32 v[54:55], v[54:55], v[104:105]
	v_pk_fma_f32 v[56:57], v[110:111], v[104:105], v[44:45] neg_lo:[0,0,1] neg_hi:[0,0,1]
	v_pk_fma_f32 v[44:45], v[110:111], v[104:105], v[44:45]
	v_pk_fma_f32 v[104:105], v[110:111], v[26:27], v[54:55]
	v_pk_fma_f32 v[26:27], v[110:111], v[26:27], v[54:55] neg_lo:[0,0,1] neg_hi:[0,0,1]
	v_pk_add_f32 v[54:55], v[56:57], v[44:45] op_sel:[0,1] op_sel_hi:[1,0]
	v_pk_add_f32 v[110:111], v[104:105], v[26:27] op_sel_hi:[0,1] neg_lo:[0,1] neg_hi:[0,1]
	v_pk_add_f32 v[44:45], v[56:57], v[44:45] op_sel_hi:[0,1] neg_lo:[0,1] neg_hi:[0,1]
	v_pk_add_f32 v[26:27], v[104:105], v[26:27] op_sel:[0,1] op_sel_hi:[1,0]
	v_mov_b32_e32 v55, v111
	v_mov_b32_e32 v27, v45
	v_pk_mul_f32 v[26:27], v[26:27], 0.5 op_sel_hi:[1,0]
	v_mov_b32_e32 v47, v102
	v_pk_mul_f32 v[44:45], v[108:109], v[26:27] op_sel:[0,1] op_sel_hi:[0,0]
	v_pk_fma_f32 v[56:57], v[40:41], v[26:27], v[44:45] op_sel_hi:[0,1,1]
	v_pk_fma_f32 v[40:41], v[40:41], v[26:27], v[44:45] op_sel_hi:[0,1,1] neg_hi:[0,0,1]
	v_pk_fma_f32 v[44:45], v[54:55], 0.5, v[56:57] op_sel_hi:[1,0,1] neg_lo:[0,0,1] neg_hi:[0,0,1]
	v_pk_fma_f32 v[26:27], v[54:55], 0.5, v[40:41] op_sel_hi:[1,0,1]
	v_pk_fma_f32 v[56:57], v[54:55], 0.5, v[40:41] op_sel_hi:[1,0,1] neg_lo:[1,0,0] neg_hi:[1,0,0]
	v_pk_add_f32 v[40:41], v[106:107], v[42:43]
	v_pk_add_f32 v[42:43], v[42:43], v[106:107] neg_lo:[0,1] neg_hi:[0,1]
	v_mov_b32_e32 v45, v27
	v_mul_f32_e32 v6, 0.5, v43
	v_mov_b32_e32 v43, v41
	v_pk_mul_f32 v[120:121], v[44:45], s[46:47] op_sel_hi:[1,0]
	v_mul_f32_e32 v4, 0.5, v40
	v_pk_mov_b32 v[44:45], v[108:109], v[70:71] op_sel:[1,0]
	v_pk_mul_f32 v[40:41], v[42:43], s[44:45]
	v_cvt_f32_f16_sdwa v54, v20 dst_sel:DWORD dst_unused:UNUSED_PAD src0_sel:WORD_1
	v_pk_mul_f32 v[42:43], v[44:45], v[40:41] op_sel:[0,1] op_sel_hi:[1,0]
	v_cvt_f32_f16_e32 v55, v21
	v_cvt_f32_f16_sdwa v21, v21 dst_sel:DWORD dst_unused:UNUSED_PAD src0_sel:WORD_1
	v_cvt_f32_f16_e32 v20, v20
	v_pk_mul_f32 v[40:41], v[44:45], v[40:41]
	v_pk_add_f32 v[42:43], v[42:43], v[42:43] op_sel:[0,1] op_sel_hi:[0,1]
	v_pk_add_f32 v[104:105], v[4:5], v[42:43] op_sel_hi:[0,1] neg_hi:[0,1]
	s_nop 0
	v_pk_add_f32 v[40:41], v[40:41], v[40:41] op_sel:[0,1] op_sel_hi:[0,1] neg_lo:[0,1] neg_hi:[0,1]
	v_pk_add_f32 v[42:43], v[6:7], v[40:41] op_sel_hi:[0,1] neg_hi:[0,1]
	v_pk_mul_f32 v[40:41], v[42:43], v[20:21]
	v_pk_mul_f32 v[42:43], v[42:43], v[54:55]
	v_pk_fma_f32 v[40:41], v[104:105], v[54:55], v[40:41]
	v_pk_fma_f32 v[20:21], v[104:105], v[20:21], v[42:43] neg_lo:[0,0,1] neg_hi:[0,0,1]
	v_mov_b32_e32 v71, v109
	v_pk_add_f32 v[42:43], v[20:21], v[40:41] op_sel:[0,1] op_sel_hi:[1,0] neg_lo:[0,1]
	v_pk_add_f32 v[54:55], v[20:21], v[40:41] op_sel:[0,1] op_sel_hi:[1,0]
	v_pk_add_f32 v[20:21], v[40:41], v[20:21] op_sel:[1,0] op_sel_hi:[0,1] neg_lo:[0,1] neg_hi:[0,1]
	v_pk_mul_f32 v[42:43], v[42:43], 0.5 op_sel_hi:[1,0]
	v_mov_b32_e32 v55, v21
	v_mul_f32_e32 v4, v109, v42
	v_pk_fma_f32 v[104:105], v[44:45], v[42:43], v[4:5] op_sel_hi:[1,1,0] neg_lo:[1,0,0] neg_hi:[1,0,0]
	v_mul_f32_e32 v4, v109, v43
	v_pk_fma_f32 v[42:43], v[70:71], v[42:43], v[4:5] op_sel_hi:[1,1,0]
	v_sub_f32_e32 v6, v23, v103
	v_mov_b32_e32 v104, v42
	v_pk_fma_f32 v[40:41], v[54:55], 0.5, v[42:43] op_sel_hi:[1,0,1] neg_lo:[0,0,1] neg_hi:[0,0,1]
	v_pk_fma_f32 v[20:21], v[54:55], 0.5, v[104:105] op_sel_hi:[1,0,1]
	v_pk_add_f32 v[42:43], v[102:103], v[22:23]
	v_mov_b32_e32 v41, v21
	v_pk_mul_f32 v[128:129], v[40:41], s[46:47] op_sel_hi:[1,0]
	v_mul_f32_e32 v40, 0xbf0e39da, v83
	v_mov_b32_e32 v41, v22
	v_mul_f32_e32 v18, 0.5, v43
	v_pk_add_f32 v[22:23], v[40:41], v[46:47] neg_lo:[0,1] neg_hi:[0,1]
	v_mov_b32_e32 v47, v109
	v_pk_mul_f32 v[40:41], v[22:23], v[18:19]
	v_mov_b32_e32 v46, v22
	v_pk_fma_f32 v[44:45], v[44:45], v[40:41], v[40:41] op_sel:[0,1,0] op_sel_hi:[1,0,1]
	v_mov_b32_e32 v40, v41
	v_mov_b32_e32 v41, v18
	v_mul_f32_e32 v4, 0.5, v42
	v_pk_mul_f32 v[40:41], v[46:47], v[40:41]
	v_cvt_f32_f16_e32 v46, v10
	v_cvt_f32_f16_e32 v47, v11
	v_cvt_f32_f16_sdwa v11, v11 dst_sel:DWORD dst_unused:UNUSED_PAD src0_sel:WORD_1
	v_cvt_f32_f16_sdwa v10, v10 dst_sel:DWORD dst_unused:UNUSED_PAD src0_sel:WORD_1
	v_pk_fma_f32 v[70:71], v[54:55], 0.5, v[104:105] op_sel_hi:[1,0,1] neg_lo:[1,0,0] neg_hi:[1,0,0]
	v_mul_f32_e32 v6, 0.5, v6
	v_pk_add_f32 v[54:55], v[4:5], v[44:45]
	v_pk_add_f32 v[40:41], v[40:41], v[40:41] op_sel:[0,1] op_sel_hi:[0,1] neg_lo:[0,1] neg_hi:[0,1]
	v_fma_f32 v55, v42, 0.5, -v44
	v_pk_add_f32 v[42:43], v[6:7], v[40:41] op_sel_hi:[0,1] neg_hi:[0,1]
	v_pk_mul_f32 v[40:41], v[42:43], v[10:11]
	v_pk_mul_f32 v[42:43], v[42:43], v[46:47]
	v_pk_fma_f32 v[44:45], v[54:55], v[46:47], v[40:41] neg_lo:[0,0,1] neg_hi:[0,0,1]
	v_pk_fma_f32 v[40:41], v[54:55], v[46:47], v[40:41]
	v_pk_fma_f32 v[46:47], v[54:55], v[10:11], v[42:43]
	v_pk_fma_f32 v[10:11], v[54:55], v[10:11], v[42:43] neg_lo:[0,0,1] neg_hi:[0,0,1]
	v_pk_add_f32 v[42:43], v[44:45], v[40:41] op_sel:[0,1] op_sel_hi:[1,0]
	v_pk_add_f32 v[54:55], v[46:47], v[10:11] op_sel_hi:[0,1] neg_lo:[0,1] neg_hi:[0,1]
	v_pk_add_f32 v[40:41], v[44:45], v[40:41] op_sel_hi:[0,1] neg_lo:[0,1] neg_hi:[0,1]
	v_pk_add_f32 v[10:11], v[46:47], v[10:11] op_sel:[0,1] op_sel_hi:[1,0]
	v_mov_b32_e32 v43, v55
	v_mov_b32_e32 v11, v41
	v_pk_mul_f32 v[10:11], v[10:11], 0.5 op_sel_hi:[1,0]
	v_mov_b32_e32 v119, v98
	v_pk_mul_f32 v[40:41], v[108:109], v[10:11] op_sel:[1,1] op_sel_hi:[1,0]
	v_pk_fma_f32 v[76:77], v[76:77], 0.5, v[112:113] op_sel_hi:[1,0,1] neg_lo:[1,0,0] neg_hi:[1,0,0]
	v_pk_fma_f32 v[44:45], v[22:23], v[10:11], v[40:41] op_sel_hi:[0,1,1]
	v_pk_fma_f32 v[10:11], v[22:23], v[10:11], v[40:41] op_sel_hi:[0,1,1] neg_hi:[0,0,1]
	v_pk_fma_f32 v[22:23], v[42:43], 0.5, v[44:45] op_sel_hi:[1,0,1] neg_lo:[0,0,1] neg_hi:[0,0,1]
	v_pk_fma_f32 v[40:41], v[42:43], 0.5, v[10:11] op_sel_hi:[1,0,1]
	v_pk_fma_f32 v[54:55], v[42:43], 0.5, v[10:11] op_sel_hi:[1,0,1] neg_lo:[1,0,0] neg_hi:[1,0,0]
	v_pk_add_f32 v[10:11], v[100:101], v[14:15]
	v_pk_add_f32 v[14:15], v[14:15], v[100:101] neg_lo:[0,1] neg_hi:[0,1]
	v_mov_b32_e32 v23, v41
	v_mul_f32_e32 v6, 0.5, v15
	v_mov_b32_e32 v15, v11
	v_pk_mul_f32 v[150:151], v[22:23], s[46:47] op_sel_hi:[1,0]
	v_mul_f32_e32 v4, 0.5, v10
	v_pk_mov_b32 v[22:23], v[58:59], v[72:73] op_sel:[1,0]
	v_pk_mul_f32 v[10:11], v[14:15], s[44:45]
	v_cvt_f32_f16_sdwa v42, v8 dst_sel:DWORD dst_unused:UNUSED_PAD src0_sel:WORD_1
	v_pk_mul_f32 v[14:15], v[22:23], v[10:11] op_sel:[0,1] op_sel_hi:[1,0]
	v_cvt_f32_f16_e32 v43, v9
	v_cvt_f32_f16_sdwa v9, v9 dst_sel:DWORD dst_unused:UNUSED_PAD src0_sel:WORD_1
	v_cvt_f32_f16_e32 v8, v8
	v_pk_mul_f32 v[10:11], v[22:23], v[10:11]
	v_pk_add_f32 v[14:15], v[14:15], v[14:15] op_sel:[0,1] op_sel_hi:[0,1]
	v_pk_add_f32 v[44:45], v[4:5], v[14:15] op_sel_hi:[0,1] neg_hi:[0,1]
	s_nop 0
	v_pk_add_f32 v[10:11], v[10:11], v[10:11] op_sel:[0,1] op_sel_hi:[0,1] neg_lo:[0,1] neg_hi:[0,1]
	v_pk_add_f32 v[14:15], v[6:7], v[10:11] op_sel_hi:[0,1] neg_hi:[0,1]
	v_pk_mul_f32 v[10:11], v[14:15], v[8:9]
	v_pk_mul_f32 v[14:15], v[14:15], v[42:43]
	v_pk_fma_f32 v[10:11], v[44:45], v[42:43], v[10:11]
	v_pk_fma_f32 v[8:9], v[44:45], v[8:9], v[14:15] neg_lo:[0,0,1] neg_hi:[0,0,1]
	v_mov_b32_e32 v73, v59
	v_pk_add_f32 v[14:15], v[8:9], v[10:11] op_sel:[0,1] op_sel_hi:[1,0] neg_lo:[0,1]
	v_pk_add_f32 v[42:43], v[8:9], v[10:11] op_sel:[0,1] op_sel_hi:[1,0]
	v_pk_add_f32 v[8:9], v[10:11], v[8:9] op_sel:[1,0] op_sel_hi:[0,1] neg_lo:[0,1] neg_hi:[0,1]
	v_pk_mul_f32 v[14:15], v[14:15], 0.5 op_sel_hi:[1,0]
	v_mov_b32_e32 v43, v9
	v_mul_f32_e32 v4, v59, v14
	v_pk_fma_f32 v[44:45], v[22:23], v[14:15], v[4:5] op_sel_hi:[1,1,0] neg_lo:[1,0,0] neg_hi:[1,0,0]
	v_mul_f32_e32 v4, v59, v15
	v_pk_fma_f32 v[14:15], v[72:73], v[14:15], v[4:5] op_sel_hi:[1,1,0]
	v_sub_f32_e32 v6, v37, v99
	v_mov_b32_e32 v44, v14
	v_pk_fma_f32 v[8:9], v[42:43], 0.5, v[14:15] op_sel_hi:[1,0,1] neg_lo:[0,0,1] neg_hi:[0,0,1]
	v_pk_fma_f32 v[10:11], v[42:43], 0.5, v[44:45] op_sel_hi:[1,0,1]
	v_pk_add_f32 v[14:15], v[98:99], v[36:37]
	v_mov_b32_e32 v9, v11
	v_pk_mul_f32 v[168:169], v[8:9], s[46:47] op_sel_hi:[1,0]
	v_mul_f32_e32 v8, 0xbf7b14be, v83
	v_mov_b32_e32 v9, v36
	v_mul_f32_e32 v18, 0.5, v15
	v_pk_add_f32 v[8:9], v[8:9], v[118:119] neg_lo:[0,1] neg_hi:[0,1]
	v_pk_fma_f32 v[72:73], v[42:43], 0.5, v[44:45] op_sel_hi:[1,0,1] neg_lo:[1,0,0] neg_hi:[1,0,0]
	v_pk_mul_f32 v[36:37], v[8:9], v[18:19]
	v_mov_b32_e32 v42, v8
	v_pk_fma_f32 v[22:23], v[22:23], v[36:37], v[36:37] op_sel:[0,1,0] op_sel_hi:[1,0,1]
	v_mov_b32_e32 v43, v59
	v_mov_b32_e32 v36, v37
	v_mov_b32_e32 v37, v18
	v_mul_f32_e32 v4, 0.5, v14
	v_pk_mul_f32 v[36:37], v[42:43], v[36:37]
	v_cvt_f32_f16_e32 v44, v2
	v_cvt_f32_f16_e32 v45, v3
	v_cvt_f32_f16_sdwa v3, v3 dst_sel:DWORD dst_unused:UNUSED_PAD src0_sel:WORD_1
	v_cvt_f32_f16_sdwa v2, v2 dst_sel:DWORD dst_unused:UNUSED_PAD src0_sel:WORD_1
	v_mul_f32_e32 v6, 0.5, v6
	v_pk_add_f32 v[46:47], v[4:5], v[22:23]
	v_fma_f32 v4, v14, 0.5, -v22
	v_pk_add_f32 v[22:23], v[36:37], v[36:37] op_sel:[0,1] op_sel_hi:[0,1] neg_lo:[0,1] neg_hi:[0,1]
	v_pk_add_f32 v[36:37], v[6:7], v[22:23] op_sel_hi:[0,1] neg_hi:[0,1]
	v_mov_b32_e32 v14, v46
	v_mov_b32_e32 v15, v4
	v_pk_mul_f32 v[22:23], v[4:5], v[44:45] op_sel_hi:[0,1]
	v_pk_mul_f32 v[82:83], v[36:37], v[2:3]
	v_pk_mul_f32 v[46:47], v[46:47], v[2:3]
	v_pk_mul_f32 v[36:37], v[36:37], v[44:45]
	v_pk_fma_f32 v[98:99], v[14:15], v[44:45], v[82:83] neg_lo:[0,0,1] neg_hi:[0,0,1]
	v_pk_fma_f32 v[2:3], v[14:15], v[2:3], v[36:37] neg_lo:[0,0,1] neg_hi:[0,0,1]
	v_add_f32_e32 v4, v23, v83
	v_add_f32_e32 v6, v46, v36
	v_pk_add_f32 v[22:23], v[6:7], v[2:3] op_sel_hi:[0,1] neg_lo:[0,1] neg_hi:[0,1]
	v_pk_add_f32 v[36:37], v[98:99], v[4:5] op_sel_hi:[1,0] neg_lo:[0,1] neg_hi:[0,1]
	v_pk_add_f32 v[2:3], v[6:7], v[2:3] op_sel_hi:[0,1]
	v_mov_b32_e32 v37, v3
	v_pk_mul_f32 v[2:3], v[36:37], 0.5 op_sel_hi:[1,0]
	v_pk_add_f32 v[14:15], v[98:99], v[4:5] op_sel_hi:[1,0]
	v_mul_f32_e32 v4, v59, v3
	v_pk_fma_f32 v[36:37], v[42:43], v[2:3], v[4:5] op_sel_hi:[1,1,0] neg_lo:[0,0,1] neg_hi:[0,0,1]
	v_pk_mov_b32 v[42:43], v[58:59], v[8:9] op_sel:[1,0]
	v_mul_f32_e32 v4, v8, v3
	v_pk_fma_f32 v[2:3], v[42:43], v[2:3], v[4:5] op_sel_hi:[1,1,0]
	v_mov_b32_e32 v15, v23
	v_pk_fma_f32 v[8:9], v[14:15], 0.5, v[2:3] op_sel_hi:[1,0,1] neg_lo:[0,0,1] neg_hi:[0,0,1]
	v_pk_fma_f32 v[42:43], v[14:15], 0.5, v[36:37] op_sel_hi:[1,0,0]
	v_pk_fma_f32 v[2:3], v[14:15], 0.5, v[2:3] op_sel_hi:[1,0,1]
	v_mov_b32_e32 v9, v43
	v_pk_fma_f32 v[58:59], v[22:23], 0.5, v[36:37] op_sel_hi:[1,0,0] neg_lo:[1,0,0] neg_hi:[1,0,0]
	v_pk_mul_f32 v[144:145], v[8:9], s[46:47] op_sel_hi:[1,0]
	v_mov_b32_e32 v58, v2
	v_mov_b32_e32 v72, v10
	v_mov_b32_e32 v54, v40
	v_mov_b32_e32 v70, v20
	v_mov_b32_e32 v56, v26
	v_mov_b32_e32 v76, v38
	v_mov_b32_e32 v52, v34
	v_mov_b32_e32 v74, v86
	v_mov_b32_e32 v48, v84
	v_mov_b32_e32 v50, v60
	v_mov_b32_e32 v28, v66
	v_mov_b32_e32 v32, v96
	v_mov_b32_e32 v12, v88
	v_mov_b32_e32 v16, v92
	v_mov_b32_e32 v4, v138
	v_mov_b32_e32 v6, v122

.LBB0_538:
	s_or_b64 exec, exec, s[0:1]
	v_pk_mul_f32 v[22:23], v[32:33], s[46:47] op_sel_hi:[1,0]
	v_pk_add_f32 v[26:27], v[24:25], v[30:31]
	v_pk_add_f32 v[24:25], v[24:25], v[30:31] neg_lo:[0,1] neg_hi:[0,1]
	v_pk_add_f32 v[30:31], v[64:65], v[68:69]
	v_pk_add_f32 v[32:33], v[64:65], v[68:69] neg_lo:[0,1] neg_hi:[0,1]
	v_pk_add_f32 v[34:35], v[62:63], v[90:91]
	v_pk_add_f32 v[38:39], v[94:95], v[80:81]
	v_pk_add_f32 v[40:41], v[94:95], v[80:81] neg_lo:[0,1] neg_hi:[0,1]
	v_pk_add_f32 v[68:69], v[26:27], v[30:31]
	v_pk_add_f32 v[26:27], v[26:27], v[30:31] neg_lo:[0,1] neg_hi:[0,1]
	v_xor_b32_e32 v30, 0x80000000, v33
	v_mov_b32_e32 v31, v32
	v_pk_mul_f32 v[20:21], v[50:51], s[46:47] op_sel_hi:[1,0]
	v_pk_add_f32 v[36:37], v[62:63], v[90:91] neg_lo:[0,1] neg_hi:[0,1]
	v_pk_add_f32 v[42:43], v[78:79], v[136:137]
	v_pk_add_f32 v[46:47], v[130:131], v[120:121]
	v_pk_add_f32 v[50:51], v[130:131], v[120:121] neg_lo:[0,1] neg_hi:[0,1]
	v_pk_add_f32 v[32:33], v[24:25], v[30:31]
	v_pk_add_f32 v[24:25], v[24:25], v[30:31] neg_lo:[0,1] neg_hi:[0,1]
	v_pk_add_f32 v[30:31], v[34:35], v[38:39]
	v_pk_add_f32 v[34:35], v[34:35], v[38:39] neg_lo:[0,1] neg_hi:[0,1]
	v_xor_b32_e32 v38, 0x80000000, v41
	v_mov_b32_e32 v39, v40
	v_pk_add_f32 v[44:45], v[78:79], v[136:137] neg_lo:[0,1] neg_hi:[0,1]
	v_pk_add_f32 v[60:61], v[128:129], v[150:151]
	v_pk_add_f32 v[64:65], v[168:169], v[144:145]
	v_pk_add_f32 v[66:67], v[168:169], v[144:145] neg_lo:[0,1] neg_hi:[0,1]
	v_pk_add_f32 v[40:41], v[36:37], v[38:39]
	v_pk_add_f32 v[36:37], v[36:37], v[38:39] neg_lo:[0,1] neg_hi:[0,1]
	v_pk_add_f32 v[38:39], v[42:43], v[46:47]
	v_pk_add_f32 v[42:43], v[42:43], v[46:47] neg_lo:[0,1] neg_hi:[0,1]
	v_xor_b32_e32 v46, 0x80000000, v51
	v_mov_b32_e32 v47, v50
	v_pk_add_f32 v[62:63], v[128:129], v[150:151] neg_lo:[0,1] neg_hi:[0,1]
	v_pk_add_f32 v[50:51], v[44:45], v[46:47]
	v_pk_add_f32 v[44:45], v[44:45], v[46:47] neg_lo:[0,1] neg_hi:[0,1]
	v_pk_add_f32 v[46:47], v[60:61], v[64:65]
	v_pk_add_f32 v[60:61], v[60:61], v[64:65] neg_lo:[0,1] neg_hi:[0,1]
	v_xor_b32_e32 v64, 0x80000000, v67
	v_mov_b32_e32 v65, v66
	s_mov_b32 s66, s37
	s_mov_b32 s67, s36
	v_pk_add_f32 v[66:67], v[62:63], v[64:65]
	v_pk_add_f32 v[62:63], v[62:63], v[64:65] neg_lo:[0,1] neg_hi:[0,1]
	v_pk_add_f32 v[64:65], v[68:69], v[30:31]
	v_pk_add_f32 v[30:31], v[68:69], v[30:31] neg_lo:[0,1] neg_hi:[0,1]
	s_mov_b32 s0, s37
	v_pk_mul_f32 v[68:69], v[40:41], s[66:67]
	s_mov_b32 s68, s19
	v_pk_fma_f32 v[40:41], v[40:41], s[0:1], v[68:69] op_sel:[0,0,1] op_sel_hi:[1,0,0]
	s_mov_b32 s69, s18
	v_pk_add_f32 v[68:69], v[32:33], v[40:41]
	v_pk_add_f32 v[32:33], v[32:33], v[40:41] neg_lo:[0,1] neg_hi:[0,1]
	v_xor_b32_e32 v40, 0x80000000, v35
	v_mov_b32_e32 v41, v34
	v_pk_add_f32 v[34:35], v[26:27], v[40:41]
	v_pk_add_f32 v[26:27], v[26:27], v[40:41] neg_lo:[0,1] neg_hi:[0,1]
	v_pk_mul_f32 v[40:41], v[36:37], s[66:67]
	s_mov_b32 s72, s19
	v_pk_fma_f32 v[36:37], v[36:37], s[0:1], v[40:41] op_sel:[0,0,1] op_sel_hi:[1,0,0] neg_lo:[1,0,0] neg_hi:[1,0,0]
	v_pk_mul_f32 v[2:3], v[72:73], s[46:47] op_sel_hi:[1,0]
	v_pk_add_f32 v[40:41], v[24:25], v[36:37]
	v_pk_add_f32 v[24:25], v[24:25], v[36:37] neg_lo:[0,1] neg_hi:[0,1]
	v_pk_add_f32 v[36:37], v[38:39], v[46:47]
	v_pk_add_f32 v[38:39], v[38:39], v[46:47] neg_lo:[0,1] neg_hi:[0,1]
	v_pk_mul_f32 v[46:47], v[66:67], s[66:67]
	v_pk_mul_f32 v[8:9], v[70:71], s[46:47] op_sel_hi:[1,0]
	v_pk_fma_f32 v[46:47], v[66:67], s[0:1], v[46:47] op_sel:[0,0,1] op_sel_hi:[1,0,0]
	v_pk_mul_f32 v[10:11], v[76:77], s[46:47] op_sel_hi:[1,0]
	v_pk_add_f32 v[66:67], v[50:51], v[46:47]
	v_pk_add_f32 v[46:47], v[50:51], v[46:47] neg_lo:[0,1] neg_hi:[0,1]
	v_xor_b32_e32 v50, 0x80000000, v61
	v_mov_b32_e32 v51, v60
	v_pk_add_f32 v[60:61], v[42:43], v[50:51]
	v_pk_add_f32 v[42:43], v[42:43], v[50:51] neg_lo:[0,1] neg_hi:[0,1]
	v_pk_mul_f32 v[50:51], v[62:63], s[66:67]
	v_pk_mul_f32 v[14:15], v[74:75], s[46:47] op_sel_hi:[1,0]
	v_pk_fma_f32 v[50:51], v[62:63], s[0:1], v[50:51] op_sel:[0,0,1] op_sel_hi:[1,0,0] neg_lo:[1,0,0] neg_hi:[1,0,0]
	v_pk_mul_f32 v[16:17], v[16:17], s[46:47] op_sel_hi:[1,0]
	v_pk_add_f32 v[62:63], v[44:45], v[50:51]
	v_pk_add_f32 v[44:45], v[44:45], v[50:51] neg_lo:[0,1] neg_hi:[0,1]
	v_pk_add_f32 v[50:51], v[64:65], v[36:37]
	v_pk_add_f32 v[36:37], v[64:65], v[36:37] neg_lo:[0,1] neg_hi:[0,1]
	v_pk_mul_f32 v[64:65], v[66:67], s[68:69]
	v_pk_mul_f32 v[6:7], v[6:7], s[46:47] op_sel_hi:[1,0]
	v_pk_fma_f32 v[64:65], v[66:67], s[16:17], v[64:65] op_sel:[0,0,1] op_sel_hi:[1,0,0]
	s_mov_b32 s17, s40
	v_pk_add_f32 v[66:67], v[68:69], v[64:65]
	v_pk_add_f32 v[64:65], v[68:69], v[64:65] neg_lo:[0,1] neg_hi:[0,1]
	v_pk_mul_f32 v[68:69], v[60:61], s[66:67]
	s_ashr_i32 s63, s62, 31
	v_pk_fma_f32 v[60:61], s[0:1], v[60:61], v[68:69] op_sel:[0,0,1] op_sel_hi:[0,1,0]
	v_pk_add_f32 v[68:69], v[34:35], v[60:61]
	v_pk_add_f32 v[34:35], v[34:35], v[60:61] neg_lo:[0,1] neg_hi:[0,1]
	v_pk_mul_f32 v[60:61], v[62:63], s[16:17] op_sel:[1,1] op_sel_hi:[0,0]
	v_pk_fma_f32 v[60:61], s[72:73], v[62:63], v[60:61] op_sel_hi:[0,1,1]
	v_pk_add_f32 v[62:63], v[40:41], v[60:61]
	v_pk_add_f32 v[40:41], v[40:41], v[60:61] neg_lo:[0,1] neg_hi:[0,1]
	v_xor_b32_e32 v60, 0x80000000, v39
	v_mov_b32_e32 v61, v38
	v_pk_add_f32 v[38:39], v[30:31], v[60:61]
	v_pk_add_f32 v[30:31], v[30:31], v[60:61] neg_lo:[0,1] neg_hi:[0,1]
	v_pk_mul_f32 v[60:61], v[46:47], s[16:17] op_sel:[1,1] op_sel_hi:[0,0]
	v_pk_fma_f32 v[46:47], s[72:73], v[46:47], v[60:61] op_sel_hi:[0,1,1] neg_lo:[0,1,0] neg_hi:[0,1,0]
	v_pk_add_f32 v[60:61], v[32:33], v[46:47]
	v_pk_add_f32 v[32:33], v[32:33], v[46:47] neg_lo:[0,1] neg_hi:[0,1]
	v_pk_mul_f32 v[46:47], v[42:43], s[66:67] op_sel:[1,1] op_sel_hi:[0,0]
	v_pk_fma_f32 v[42:43], s[0:1], v[42:43], v[46:47] op_sel_hi:[0,1,1] neg_lo:[0,1,0] neg_hi:[0,1,0]
	v_pk_add_f32 v[46:47], v[26:27], v[42:43]
	v_pk_add_f32 v[26:27], v[26:27], v[42:43] neg_lo:[0,1] neg_hi:[0,1]
	v_pk_mul_f32 v[42:43], v[44:45], s[68:69] op_sel:[1,1] op_sel_hi:[0,0]
	v_pk_fma_f32 v[42:43], s[16:17], v[44:45], v[42:43] op_sel_hi:[0,1,1] neg_lo:[0,1,0] neg_hi:[0,1,0]
	v_pk_add_f32 v[44:45], v[24:25], v[42:43]
	v_pk_add_f32 v[24:25], v[24:25], v[42:43] neg_lo:[0,1] neg_hi:[0,1]
	v_pk_fma_f32 v[42:43], v[58:59], s[46:47], v[2:3] op_sel_hi:[1,0,1]
	v_pk_fma_f32 v[2:3], v[58:59], s[46:47], v[2:3] op_sel_hi:[1,0,1] neg_lo:[0,0,1] neg_hi:[0,0,1]
	v_pk_fma_f32 v[58:59], v[54:55], s[46:47], v[8:9] op_sel_hi:[1,0,1]
	v_pk_fma_f32 v[8:9], v[54:55], s[46:47], v[8:9] op_sel_hi:[1,0,1] neg_lo:[0,0,1] neg_hi:[0,0,1]
	v_pk_fma_f32 v[54:55], v[56:57], s[46:47], v[10:11] op_sel_hi:[1,0,1]
	v_pk_fma_f32 v[10:11], v[56:57], s[46:47], v[10:11] op_sel_hi:[1,0,1] neg_lo:[0,0,1] neg_hi:[0,0,1]
	v_pk_fma_f32 v[56:57], v[52:53], s[46:47], v[14:15] op_sel_hi:[1,0,1]
	v_pk_fma_f32 v[14:15], v[52:53], s[46:47], v[14:15] op_sel_hi:[1,0,1] neg_lo:[0,0,1] neg_hi:[0,0,1]
	v_pk_fma_f32 v[52:53], v[48:49], s[46:47], v[20:21] op_sel_hi:[1,0,1]
	v_pk_fma_f32 v[20:21], v[48:49], s[46:47], v[20:21] op_sel_hi:[1,0,1] neg_lo:[0,0,1] neg_hi:[0,0,1]
	v_pk_fma_f32 v[48:49], v[28:29], s[46:47], v[22:23] op_sel_hi:[1,0,1]
	v_pk_fma_f32 v[22:23], v[28:29], s[46:47], v[22:23] op_sel_hi:[1,0,1] neg_lo:[0,0,1] neg_hi:[0,0,1]
	v_pk_fma_f32 v[28:29], v[12:13], s[46:47], v[16:17] op_sel_hi:[1,0,1]
	v_pk_fma_f32 v[12:13], v[12:13], s[46:47], v[16:17] op_sel_hi:[1,0,1] neg_lo:[0,0,1] neg_hi:[0,0,1]
	v_pk_fma_f32 v[16:17], v[4:5], s[46:47], v[6:7] op_sel_hi:[1,0,1]
	v_pk_fma_f32 v[4:5], v[4:5], s[46:47], v[6:7] op_sel_hi:[1,0,1] neg_lo:[0,0,1] neg_hi:[0,0,1]
	v_pk_add_f32 v[6:7], v[58:59], v[42:43]
	v_pk_add_f32 v[42:43], v[42:43], v[58:59] neg_lo:[0,1] neg_hi:[0,1]
	v_xor_b32_e32 v58, 0x80000000, v9
	v_mov_b32_e32 v59, v8
	v_pk_add_f32 v[8:9], v[2:3], v[58:59]
	v_pk_add_f32 v[2:3], v[2:3], v[58:59] neg_lo:[0,1] neg_hi:[0,1]
	v_pk_add_f32 v[58:59], v[56:57], v[54:55]
	v_pk_add_f32 v[54:55], v[54:55], v[56:57] neg_lo:[0,1] neg_hi:[0,1]
	v_xor_b32_e32 v56, 0x80000000, v15
	v_mov_b32_e32 v57, v14
	v_pk_add_f32 v[14:15], v[10:11], v[56:57]
	v_pk_add_f32 v[10:11], v[10:11], v[56:57] neg_lo:[0,1] neg_hi:[0,1]
	v_pk_add_f32 v[56:57], v[48:49], v[52:53]
	v_pk_add_f32 v[48:49], v[52:53], v[48:49] neg_lo:[0,1] neg_hi:[0,1]
	v_xor_b32_e32 v52, 0x80000000, v23
	v_mov_b32_e32 v53, v22
	v_pk_add_f32 v[22:23], v[20:21], v[52:53]
	v_pk_add_f32 v[20:21], v[20:21], v[52:53] neg_lo:[0,1] neg_hi:[0,1]
	v_pk_add_f32 v[52:53], v[16:17], v[28:29]
	v_pk_add_f32 v[16:17], v[28:29], v[16:17] neg_lo:[0,1] neg_hi:[0,1]
	v_xor_b32_e32 v28, 0x80000000, v5
	v_mov_b32_e32 v29, v4
	v_pk_add_f32 v[4:5], v[12:13], v[28:29]
	v_pk_add_f32 v[12:13], v[12:13], v[28:29] neg_lo:[0,1] neg_hi:[0,1]
	v_pk_add_f32 v[28:29], v[58:59], v[6:7]
	v_pk_add_f32 v[6:7], v[6:7], v[58:59] neg_lo:[0,1] neg_hi:[0,1]
	v_pk_mul_f32 v[58:59], v[14:15], s[66:67] op_sel:[1,1] op_sel_hi:[0,0]
	v_pk_fma_f32 v[14:15], s[0:1], v[14:15], v[58:59] op_sel_hi:[0,1,1]
	v_pk_add_f32 v[58:59], v[14:15], v[8:9]
	v_pk_add_f32 v[8:9], v[8:9], v[14:15] neg_lo:[0,1] neg_hi:[0,1]
	v_xor_b32_e32 v14, 0x80000000, v55
	v_mov_b32_e32 v15, v54
	v_pk_add_f32 v[54:55], v[14:15], v[42:43]
	v_pk_add_f32 v[14:15], v[42:43], v[14:15] neg_lo:[0,1] neg_hi:[0,1]
	v_pk_mul_f32 v[42:43], v[10:11], s[66:67] op_sel:[1,1] op_sel_hi:[0,0]
	v_pk_fma_f32 v[10:11], s[0:1], v[10:11], v[42:43] op_sel_hi:[0,1,1] neg_lo:[0,1,0] neg_hi:[0,1,0]
	v_pk_add_f32 v[42:43], v[10:11], v[2:3]
	v_pk_add_f32 v[2:3], v[2:3], v[10:11] neg_lo:[0,1] neg_hi:[0,1]
	v_pk_add_f32 v[10:11], v[52:53], v[56:57]
	v_pk_add_f32 v[52:53], v[56:57], v[52:53] neg_lo:[0,1] neg_hi:[0,1]
	v_pk_mul_f32 v[56:57], v[4:5], s[66:67] op_sel:[1,1] op_sel_hi:[0,0]
	v_pk_fma_f32 v[4:5], s[0:1], v[4:5], v[56:57] op_sel_hi:[0,1,1]
	v_pk_add_f32 v[56:57], v[4:5], v[22:23]
	v_pk_add_f32 v[4:5], v[22:23], v[4:5] neg_lo:[0,1] neg_hi:[0,1]
	v_xor_b32_e32 v22, 0x80000000, v17
	v_mov_b32_e32 v23, v16
	v_pk_add_f32 v[16:17], v[22:23], v[48:49]
	v_pk_add_f32 v[22:23], v[48:49], v[22:23] neg_lo:[0,1] neg_hi:[0,1]
	v_pk_mul_f32 v[48:49], v[12:13], s[66:67] op_sel:[1,1] op_sel_hi:[0,0]
	v_pk_fma_f32 v[12:13], s[0:1], v[12:13], v[48:49] op_sel_hi:[0,1,1] neg_lo:[0,1,0] neg_hi:[0,1,0]
	v_pk_add_f32 v[48:49], v[12:13], v[20:21]
	v_pk_add_f32 v[12:13], v[20:21], v[12:13] neg_lo:[0,1] neg_hi:[0,1]
	v_pk_add_f32 v[20:21], v[10:11], v[28:29]
	v_pk_add_f32 v[10:11], v[28:29], v[10:11] neg_lo:[0,1] neg_hi:[0,1]
	v_pk_mul_f32 v[28:29], v[56:57], s[68:69] op_sel:[1,1] op_sel_hi:[0,0]
	v_pk_fma_f32 v[28:29], s[16:17], v[56:57], v[28:29] op_sel_hi:[0,1,1]
	v_pk_add_f32 v[56:57], v[28:29], v[58:59]
	v_pk_add_f32 v[28:29], v[58:59], v[28:29] neg_lo:[0,1] neg_hi:[0,1]
	v_pk_mul_f32 v[58:59], v[16:17], s[66:67] op_sel:[1,1] op_sel_hi:[0,0]
	v_pk_fma_f32 v[16:17], s[0:1], v[16:17], v[58:59] op_sel_hi:[0,1,1]
	v_pk_add_f32 v[58:59], v[16:17], v[54:55]
	v_pk_add_f32 v[16:17], v[54:55], v[16:17] neg_lo:[0,1] neg_hi:[0,1]
	v_pk_mul_f32 v[54:55], v[48:49], s[16:17] op_sel:[1,1] op_sel_hi:[0,0]
	v_pk_fma_f32 v[48:49], s[72:73], v[48:49], v[54:55] op_sel_hi:[0,1,1]
	v_pk_add_f32 v[54:55], v[48:49], v[42:43]
	v_pk_add_f32 v[42:43], v[42:43], v[48:49] neg_lo:[0,1] neg_hi:[0,1]
	v_xor_b32_e32 v48, 0x80000000, v53
	v_mov_b32_e32 v49, v52
	v_pk_add_f32 v[52:53], v[48:49], v[6:7]
	v_pk_add_f32 v[6:7], v[6:7], v[48:49] neg_lo:[0,1] neg_hi:[0,1]
	v_pk_mul_f32 v[48:49], v[4:5], s[16:17] op_sel:[1,1] op_sel_hi:[0,0]
	v_pk_fma_f32 v[4:5], s[72:73], v[4:5], v[48:49] op_sel_hi:[0,1,1] neg_lo:[0,1,0] neg_hi:[0,1,0]
	v_pk_add_f32 v[48:49], v[4:5], v[8:9]
	v_pk_add_f32 v[4:5], v[8:9], v[4:5] neg_lo:[0,1] neg_hi:[0,1]
	v_pk_mul_f32 v[8:9], v[22:23], s[66:67] op_sel:[1,1] op_sel_hi:[0,0]
	v_pk_fma_f32 v[8:9], s[0:1], v[22:23], v[8:9] op_sel_hi:[0,1,1] neg_lo:[0,1,0] neg_hi:[0,1,0]
	v_pk_add_f32 v[22:23], v[8:9], v[14:15]
	v_pk_add_f32 v[8:9], v[14:15], v[8:9] neg_lo:[0,1] neg_hi:[0,1]
	v_pk_mul_f32 v[14:15], v[12:13], s[68:69] op_sel:[1,1] op_sel_hi:[0,0]
	v_pk_fma_f32 v[12:13], s[16:17], v[12:13], v[14:15] op_sel_hi:[0,1,1] neg_lo:[0,1,0] neg_hi:[0,1,0]
	v_pk_add_f32 v[14:15], v[12:13], v[2:3]
	v_pk_add_f32 v[2:3], v[2:3], v[12:13] neg_lo:[0,1] neg_hi:[0,1]
	ds_write_b64 v211, v[50:51]
	ds_write_b64 v212, v[20:21]
	ds_write_b64 v211, v[66:67] offset:8
	ds_write_b64 v212, v[56:57] offset:8
	ds_write_b64 v211, v[68:69] offset:16
	ds_write_b64 v212, v[58:59] offset:16
	ds_write_b64 v211, v[62:63] offset:24
	ds_write_b64 v212, v[54:55] offset:24
	ds_write_b64 v211, v[38:39] offset:32
	ds_write_b64 v212, v[52:53] offset:32
	ds_write_b64 v211, v[60:61] offset:40
	ds_write_b64 v212, v[48:49] offset:40
	ds_write_b64 v211, v[46:47] offset:48
	ds_write_b64 v212, v[22:23] offset:48
	ds_write_b64 v211, v[44:45] offset:56
	ds_write_b64 v212, v[14:15] offset:56
	ds_write_b64 v211, v[36:37] offset:64
	ds_write_b64 v212, v[10:11] offset:64
	ds_write_b64 v211, v[64:65] offset:72
	ds_write_b64 v212, v[28:29] offset:72
	ds_write_b64 v211, v[34:35] offset:80
	ds_write_b64 v212, v[16:17] offset:80
	ds_write_b64 v211, v[40:41] offset:88
	ds_write_b64 v212, v[42:43] offset:88
	ds_write_b64 v211, v[30:31] offset:96
	ds_write_b64 v212, v[6:7] offset:96
	ds_write_b64 v211, v[32:33] offset:104
	ds_write_b64 v212, v[4:5] offset:104
	ds_write_b64 v211, v[26:27] offset:112
	ds_write_b64 v212, v[8:9] offset:112
	ds_write_b64 v211, v[24:25] offset:120
	ds_write_b64 v212, v[2:3] offset:120
	v_mov_b32_e32 v2, v210
	s_waitcnt lgkmcnt(0)
	s_barrier
	s_nop 0
	v_and_b32_e32 v4, 15, v2
	v_cvt_f32_ubyte0_e32 v3, v4
	v_mul_f32_e32 v5, 0x3b800000, v3
	v_sin_f32_e32 v3, v5
	v_lshlrev_b32_e32 v6, 4, v2
	v_cos_f32_e32 v2, v5
	v_lshlrev_b32_e32 v7, 3, v4
	v_xor_b32_e32 v16, 0x80000000, v3
	v_mov_b32_e32 v17, v3
	v_pk_mul_f32 v[4:5], v[2:3], v[16:17] op_sel:[1,0] op_sel_hi:[0,1]
	v_pk_fma_f32 v[40:41], v[2:3], v[2:3], v[4:5] op_sel_hi:[0,1,1]
	v_pk_mul_f32 v[4:5], v[16:17], v[40:41] op_sel:[0,1] op_sel_hi:[1,0]
	v_xor_b32_e32 v44, 0x80000000, v41
	v_mov_b32_e32 v45, v41
	v_pk_fma_f32 v[42:43], v[2:3], v[40:41], v[4:5] op_sel_hi:[0,1,1]
	v_pk_mul_f32 v[4:5], v[40:41], v[44:45] op_sel:[1,0] op_sel_hi:[0,1]
	v_pk_fma_f32 v[46:47], v[40:41], v[40:41], v[4:5] op_sel_hi:[1,0,1]
	v_xor_b32_e32 v50, 0x80000000, v43
	v_pk_mul_f32 v[4:5], v[16:17], v[46:47] op_sel:[0,1] op_sel_hi:[1,0]
	v_mov_b32_e32 v51, v43
	v_pk_fma_f32 v[52:53], v[2:3], v[46:47], v[4:5] op_sel_hi:[0,1,1]
	v_pk_mul_f32 v[4:5], v[44:45], v[46:47] op_sel:[0,1] op_sel_hi:[1,0]
	v_xor_b32_e32 v48, 0x80000000, v47
	v_mov_b32_e32 v49, v47
	v_pk_fma_f32 v[56:57], v[40:41], v[46:47], v[4:5] op_sel_hi:[0,1,1]
	v_pk_mul_f32 v[4:5], v[46:47], v[50:51] op_sel:[1,0] op_sel_hi:[0,1]
	v_pk_fma_f32 v[60:61], v[46:47], v[42:43], v[4:5] op_sel_hi:[1,0,1]
	v_pk_mul_f32 v[4:5], v[46:47], v[48:49] op_sel:[1,0] op_sel_hi:[0,1]
	v_pk_fma_f32 v[64:65], v[46:47], v[46:47], v[4:5] op_sel_hi:[1,0,1]
	v_xor_b32_e32 v54, 0x80000000, v53
	v_pk_mul_f32 v[4:5], v[16:17], v[64:65] op_sel:[0,1] op_sel_hi:[1,0]
	v_mov_b32_e32 v55, v53
	v_pk_fma_f32 v[68:69], v[2:3], v[64:65], v[4:5] op_sel_hi:[0,1,1]
	v_pk_mul_f32 v[4:5], v[44:45], v[64:65] op_sel:[0,1] op_sel_hi:[1,0]
	v_xor_b32_e32 v58, 0x80000000, v57
	v_pk_fma_f32 v[72:73], v[40:41], v[64:65], v[4:5] op_sel_hi:[0,1,1]
	v_pk_mul_f32 v[4:5], v[50:51], v[64:65] op_sel:[0,1] op_sel_hi:[1,0]
	v_mov_b32_e32 v59, v57
	v_pk_fma_f32 v[76:77], v[42:43], v[64:65], v[4:5] op_sel_hi:[0,1,1]
	v_pk_mul_f32 v[4:5], v[48:49], v[64:65] op_sel:[0,1] op_sel_hi:[1,0]
	v_xor_b32_e32 v62, 0x80000000, v61
	v_pk_fma_f32 v[80:81], v[46:47], v[64:65], v[4:5] op_sel_hi:[0,1,1]
	v_pk_mul_f32 v[4:5], v[16:17], v[80:81] op_sel:[0,1] op_sel_hi:[1,0]
	v_mov_b32_e32 v63, v61
	v_pk_fma_f32 v[84:85], v[2:3], v[80:81], v[4:5] op_sel_hi:[0,1,1]
	v_pk_mul_f32 v[4:5], v[44:45], v[80:81] op_sel:[0,1] op_sel_hi:[1,0]
	v_and_b32_e32 v3, 0xffffff00, v6
	v_pk_fma_f32 v[88:89], v[40:41], v[80:81], v[4:5] op_sel_hi:[0,1,1]
	v_pk_mul_f32 v[4:5], v[50:51], v[80:81] op_sel:[0,1] op_sel_hi:[1,0]
	v_xor_b32_e32 v66, 0x80000000, v65
	v_pk_fma_f32 v[92:93], v[42:43], v[80:81], v[4:5] op_sel_hi:[0,1,1]
	v_lshlrev_b32_e32 v4, 3, v3
	v_add3_u32 v18, 0, v7, v4
	v_ashrrev_i32_e32 v4, 2, v3
	v_add_u32_e32 v98, v18, v4
	ds_read2_b64 v[4:7], v98 offset1:16
	ds_read2_b64 v[8:11], v98 offset0:33 offset1:49
	ds_read2_b64 v[12:15], v98 offset0:66 offset1:82
	ds_read2_b64 v[20:23], v98 offset0:132 offset1:148
	ds_read2_b64 v[24:27], v98 offset0:99 offset1:115
	ds_read2_b64 v[28:31], v98 offset0:165 offset1:181
	ds_read2_b64 v[32:35], v98 offset0:198 offset1:214
	ds_read2_b64 v[36:39], v98 offset0:231 offset1:247
	s_waitcnt lgkmcnt(4)
	v_pk_mul_f32 v[96:97], v[16:17], v[20:21] op_sel:[0,1] op_sel_hi:[1,0]
	v_mov_b32_e32 v67, v65
	v_pk_fma_f32 v[20:21], v[2:3], v[20:21], v[96:97] op_sel_hi:[0,1,1]
	v_pk_mul_f32 v[96:97], v[12:13], v[44:45] op_sel:[1,0] op_sel_hi:[0,1]
	v_pk_fma_f32 v[12:13], v[12:13], v[40:41], v[96:97] op_sel_hi:[1,0,1]
	s_waitcnt lgkmcnt(1)
	v_pk_mul_f32 v[96:97], v[50:51], v[32:33] op_sel:[0,1] op_sel_hi:[1,0]
	v_xor_b32_e32 v70, 0x80000000, v69
	v_pk_fma_f32 v[32:33], v[42:43], v[32:33], v[96:97] op_sel_hi:[0,1,1]
	v_pk_mul_f32 v[96:97], v[8:9], v[48:49] op_sel:[1,0] op_sel_hi:[0,1]
	v_pk_fma_f32 v[8:9], v[8:9], v[46:47], v[96:97] op_sel_hi:[1,0,1]
	v_pk_mul_f32 v[96:97], v[28:29], v[54:55] op_sel:[1,0] op_sel_hi:[0,1]
	v_pk_fma_f32 v[28:29], v[28:29], v[52:53], v[96:97] op_sel_hi:[1,0,1]
	v_pk_mul_f32 v[96:97], v[24:25], v[58:59] op_sel:[1,0] op_sel_hi:[0,1]
	v_pk_fma_f32 v[24:25], v[24:25], v[56:57], v[96:97] op_sel_hi:[1,0,1]
	s_waitcnt lgkmcnt(0)
	v_pk_mul_f32 v[96:97], v[36:37], v[62:63] op_sel:[1,0] op_sel_hi:[0,1]
	v_mov_b32_e32 v71, v69
	v_pk_fma_f32 v[36:37], v[36:37], v[60:61], v[96:97] op_sel_hi:[1,0,1]
	v_pk_mul_f32 v[96:97], v[6:7], v[66:67] op_sel:[1,0] op_sel_hi:[0,1]
	v_xor_b32_e32 v74, 0x80000000, v73
	v_mov_b32_e32 v75, v73
	v_pk_fma_f32 v[6:7], v[6:7], v[64:65], v[96:97] op_sel_hi:[1,0,1]
	v_pk_mul_f32 v[96:97], v[22:23], v[70:71] op_sel:[1,0] op_sel_hi:[0,1]
	v_xor_b32_e32 v78, 0x80000000, v77
	v_mov_b32_e32 v79, v77
	v_pk_fma_f32 v[22:23], v[22:23], v[68:69], v[96:97] op_sel_hi:[1,0,1]
	v_pk_mul_f32 v[96:97], v[14:15], v[74:75] op_sel:[1,0] op_sel_hi:[0,1]
	v_xor_b32_e32 v82, 0x80000000, v81
	v_mov_b32_e32 v83, v81
	v_pk_fma_f32 v[14:15], v[14:15], v[72:73], v[96:97] op_sel_hi:[1,0,1]
	v_pk_mul_f32 v[96:97], v[34:35], v[78:79] op_sel:[1,0] op_sel_hi:[0,1]
	v_xor_b32_e32 v86, 0x80000000, v85
	v_mov_b32_e32 v87, v85
	v_pk_fma_f32 v[34:35], v[34:35], v[76:77], v[96:97] op_sel_hi:[1,0,1]
	v_pk_mul_f32 v[96:97], v[10:11], v[82:83] op_sel:[1,0] op_sel_hi:[0,1]
	v_xor_b32_e32 v90, 0x80000000, v89
	v_mov_b32_e32 v91, v89
	v_pk_fma_f32 v[10:11], v[10:11], v[80:81], v[96:97] op_sel_hi:[1,0,1]
	v_pk_mul_f32 v[96:97], v[30:31], v[86:87] op_sel:[1,0] op_sel_hi:[0,1]
	v_xor_b32_e32 v94, 0x80000000, v93
	v_mov_b32_e32 v95, v93
	v_pk_fma_f32 v[30:31], v[30:31], v[84:85], v[96:97] op_sel_hi:[1,0,1]
	v_pk_mul_f32 v[96:97], v[26:27], v[90:91] op_sel:[1,0] op_sel_hi:[0,1]
	v_pk_fma_f32 v[26:27], v[26:27], v[88:89], v[96:97] op_sel_hi:[1,0,1]
	v_pk_mul_f32 v[96:97], v[38:39], v[94:95] op_sel:[1,0] op_sel_hi:[0,1]
	v_pk_fma_f32 v[38:39], v[38:39], v[92:93], v[96:97] op_sel_hi:[1,0,1]
	v_pk_add_f32 v[96:97], v[4:5], v[6:7]
	v_pk_add_f32 v[4:5], v[4:5], v[6:7] neg_lo:[0,1] neg_hi:[0,1]
	v_pk_add_f32 v[6:7], v[8:9], v[10:11]
	v_pk_add_f32 v[8:9], v[8:9], v[10:11] neg_lo:[0,1] neg_hi:[0,1]
	v_pk_add_f32 v[10:11], v[12:13], v[14:15]
	v_pk_add_f32 v[12:13], v[12:13], v[14:15] neg_lo:[0,1] neg_hi:[0,1]
	v_pk_add_f32 v[14:15], v[24:25], v[26:27]
	v_pk_add_f32 v[24:25], v[24:25], v[26:27] neg_lo:[0,1] neg_hi:[0,1]
	v_pk_add_f32 v[26:27], v[20:21], v[22:23]
	v_pk_add_f32 v[20:21], v[20:21], v[22:23] neg_lo:[0,1] neg_hi:[0,1]
	v_pk_add_f32 v[22:23], v[28:29], v[30:31]
	v_pk_add_f32 v[28:29], v[28:29], v[30:31] neg_lo:[0,1] neg_hi:[0,1]
	v_pk_add_f32 v[30:31], v[32:33], v[34:35]
	v_pk_add_f32 v[32:33], v[32:33], v[34:35] neg_lo:[0,1] neg_hi:[0,1]
	v_pk_add_f32 v[34:35], v[36:37], v[38:39]
	v_pk_add_f32 v[36:37], v[36:37], v[38:39] neg_lo:[0,1] neg_hi:[0,1]
	v_pk_add_f32 v[38:39], v[96:97], v[6:7]
	v_pk_add_f32 v[6:7], v[96:97], v[6:7] neg_lo:[0,1] neg_hi:[0,1]
	v_xor_b32_e32 v96, 0x80000000, v9
	v_mov_b32_e32 v97, v8
	v_pk_add_f32 v[8:9], v[4:5], v[96:97]
	v_pk_add_f32 v[4:5], v[4:5], v[96:97] neg_lo:[0,1] neg_hi:[0,1]
	v_pk_add_f32 v[96:97], v[10:11], v[14:15]
	v_pk_add_f32 v[10:11], v[10:11], v[14:15] neg_lo:[0,1] neg_hi:[0,1]
	v_xor_b32_e32 v14, 0x80000000, v25
	v_mov_b32_e32 v15, v24
	v_pk_add_f32 v[24:25], v[12:13], v[14:15]
	v_pk_add_f32 v[12:13], v[12:13], v[14:15] neg_lo:[0,1] neg_hi:[0,1]
	v_pk_add_f32 v[14:15], v[26:27], v[22:23]
	v_pk_add_f32 v[22:23], v[26:27], v[22:23] neg_lo:[0,1] neg_hi:[0,1]
	v_xor_b32_e32 v26, 0x80000000, v29
	v_mov_b32_e32 v27, v28
	v_pk_add_f32 v[28:29], v[20:21], v[26:27]
	v_pk_add_f32 v[20:21], v[20:21], v[26:27] neg_lo:[0,1] neg_hi:[0,1]
	v_pk_add_f32 v[26:27], v[30:31], v[34:35]
	v_pk_add_f32 v[30:31], v[30:31], v[34:35] neg_lo:[0,1] neg_hi:[0,1]
	v_xor_b32_e32 v34, 0x80000000, v37
	v_mov_b32_e32 v35, v36
	v_pk_add_f32 v[36:37], v[32:33], v[34:35]
	v_pk_add_f32 v[32:33], v[32:33], v[34:35] neg_lo:[0,1] neg_hi:[0,1]
	v_pk_add_f32 v[34:35], v[38:39], v[96:97]
	v_pk_add_f32 v[38:39], v[38:39], v[96:97] neg_lo:[0,1] neg_hi:[0,1]
	v_pk_mul_f32 v[96:97], v[24:25], s[66:67]
	v_add_u32_e32 v3, 0x2000, v3
	v_pk_fma_f32 v[24:25], v[24:25], s[0:1], v[96:97] op_sel:[0,0,1] op_sel_hi:[1,0,0]
	v_ashrrev_i32_e32 v3, 2, v3
	v_pk_add_f32 v[96:97], v[8:9], v[24:25]
	v_pk_add_f32 v[8:9], v[8:9], v[24:25] neg_lo:[0,1] neg_hi:[0,1]
	v_xor_b32_e32 v24, 0x80000000, v11
	v_mov_b32_e32 v25, v10
	v_pk_add_f32 v[10:11], v[6:7], v[24:25]
	v_pk_add_f32 v[6:7], v[6:7], v[24:25] neg_lo:[0,1] neg_hi:[0,1]
	v_pk_mul_f32 v[24:25], v[12:13], s[66:67]
	v_add3_u32 v18, v18, v3, s5
	v_pk_fma_f32 v[12:13], s[0:1], v[12:13], v[24:25] op_sel:[0,0,1] op_sel_hi:[0,1,0] neg_lo:[0,1,0] neg_hi:[0,1,0]
	v_pk_add_f32 v[24:25], v[4:5], v[12:13]
	v_pk_add_f32 v[4:5], v[4:5], v[12:13] neg_lo:[0,1] neg_hi:[0,1]
	v_pk_add_f32 v[12:13], v[14:15], v[26:27]
	v_pk_add_f32 v[14:15], v[14:15], v[26:27] neg_lo:[0,1] neg_hi:[0,1]
	v_pk_mul_f32 v[26:27], v[36:37], s[66:67] op_sel:[1,1] op_sel_hi:[0,0]
	v_pk_fma_f32 v[26:27], s[0:1], v[36:37], v[26:27] op_sel_hi:[0,1,1]
	v_pk_add_f32 v[36:37], v[28:29], v[26:27]
	v_pk_add_f32 v[26:27], v[28:29], v[26:27] neg_lo:[0,1] neg_hi:[0,1]
	v_xor_b32_e32 v28, 0x80000000, v31
	v_mov_b32_e32 v29, v30
	v_pk_add_f32 v[30:31], v[22:23], v[28:29]
	v_pk_add_f32 v[22:23], v[22:23], v[28:29] neg_lo:[0,1] neg_hi:[0,1]
	v_pk_mul_f32 v[28:29], v[32:33], s[66:67] op_sel:[1,1] op_sel_hi:[0,0]
	v_pk_fma_f32 v[28:29], s[0:1], v[32:33], v[28:29] op_sel_hi:[0,1,1] neg_lo:[0,1,0] neg_hi:[0,1,0]
	v_pk_add_f32 v[32:33], v[20:21], v[28:29]
	v_pk_add_f32 v[20:21], v[20:21], v[28:29] neg_lo:[0,1] neg_hi:[0,1]
	v_pk_add_f32 v[28:29], v[34:35], v[12:13]
	v_pk_add_f32 v[12:13], v[34:35], v[12:13] neg_lo:[0,1] neg_hi:[0,1]
	v_pk_mul_f32 v[34:35], v[36:37], s[68:69] op_sel:[1,1] op_sel_hi:[0,0]
	v_pk_fma_f32 v[34:35], s[16:17], v[36:37], v[34:35] op_sel_hi:[0,1,1]
	v_pk_add_f32 v[36:37], v[96:97], v[34:35]
	v_pk_add_f32 v[34:35], v[96:97], v[34:35] neg_lo:[0,1] neg_hi:[0,1]
	v_pk_mul_f32 v[96:97], v[30:31], s[66:67] op_sel:[1,1] op_sel_hi:[0,0]
	v_pk_fma_f32 v[30:31], s[0:1], v[30:31], v[96:97] op_sel_hi:[0,1,1]
	v_pk_add_f32 v[96:97], v[10:11], v[30:31]
	v_pk_add_f32 v[10:11], v[10:11], v[30:31] neg_lo:[0,1] neg_hi:[0,1]
	v_pk_mul_f32 v[30:31], v[32:33], s[16:17] op_sel:[1,1] op_sel_hi:[0,0]
	v_pk_fma_f32 v[30:31], s[72:73], v[32:33], v[30:31] op_sel_hi:[0,1,1]
	v_pk_add_f32 v[32:33], v[24:25], v[30:31]
	v_pk_add_f32 v[24:25], v[24:25], v[30:31] neg_lo:[0,1] neg_hi:[0,1]
	v_xor_b32_e32 v30, 0x80000000, v15
	v_mov_b32_e32 v31, v14
	v_pk_add_f32 v[14:15], v[38:39], v[30:31]
	v_pk_add_f32 v[30:31], v[38:39], v[30:31] neg_lo:[0,1] neg_hi:[0,1]
	v_pk_mul_f32 v[38:39], v[26:27], s[16:17] op_sel:[1,1] op_sel_hi:[0,0]
	v_pk_fma_f32 v[26:27], s[72:73], v[26:27], v[38:39] op_sel_hi:[0,1,1] neg_lo:[0,1,0] neg_hi:[0,1,0]
	v_pk_add_f32 v[38:39], v[8:9], v[26:27]
	v_pk_add_f32 v[8:9], v[8:9], v[26:27] neg_lo:[0,1] neg_hi:[0,1]
	v_pk_mul_f32 v[26:27], v[22:23], s[66:67] op_sel:[1,1] op_sel_hi:[0,0]
	v_pk_fma_f32 v[22:23], s[0:1], v[22:23], v[26:27] op_sel_hi:[0,1,1] neg_lo:[0,1,0] neg_hi:[0,1,0]
	v_pk_add_f32 v[26:27], v[6:7], v[22:23]
	v_pk_add_f32 v[6:7], v[6:7], v[22:23] neg_lo:[0,1] neg_hi:[0,1]
	v_pk_mul_f32 v[22:23], v[20:21], s[68:69] op_sel:[1,1] op_sel_hi:[0,0]
	v_pk_fma_f32 v[20:21], s[16:17], v[20:21], v[22:23] op_sel_hi:[0,1,1] neg_lo:[0,1,0] neg_hi:[0,1,0]
	v_pk_add_f32 v[22:23], v[4:5], v[20:21]
	v_pk_add_f32 v[4:5], v[4:5], v[20:21] neg_lo:[0,1] neg_hi:[0,1]
	ds_write2_b64 v98, v[28:29], v[36:37] offset1:16
	ds_write2_b64 v98, v[96:97], v[32:33] offset0:33 offset1:49
	ds_write2_b64 v98, v[14:15], v[38:39] offset0:66 offset1:82
	ds_write2_b64 v98, v[26:27], v[22:23] offset0:99 offset1:115
	ds_write2_b64 v98, v[12:13], v[34:35] offset0:132 offset1:148
	ds_write2_b64 v98, v[10:11], v[24:25] offset0:165 offset1:181
	ds_write2_b64 v98, v[30:31], v[8:9] offset0:198 offset1:214
	ds_write2_b64 v98, v[6:7], v[4:5] offset0:231 offset1:247
	ds_read2_b64 v[4:7], v18 offset1:16
	ds_read2_b64 v[8:11], v18 offset0:33 offset1:49
	ds_read2_b64 v[12:15], v18 offset0:66 offset1:82
	ds_read2_b64 v[20:23], v18 offset0:132 offset1:148
	ds_read2_b64 v[24:27], v18 offset0:99 offset1:115
	ds_read2_b64 v[28:31], v18 offset0:165 offset1:181
	ds_read2_b64 v[32:35], v18 offset0:198 offset1:214
	ds_read2_b64 v[36:39], v18 offset0:231 offset1:247
	s_waitcnt lgkmcnt(4)
	v_pk_mul_f32 v[16:17], v[20:21], v[16:17] op_sel:[1,0] op_sel_hi:[0,1]
	v_pk_fma_f32 v[2:3], v[2:3], v[20:21], v[16:17] op_sel_hi:[0,1,1]
	v_pk_mul_f32 v[16:17], v[44:45], v[12:13] op_sel:[0,1] op_sel_hi:[1,0]
	v_pk_mul_f32 v[20:21], v[48:49], v[8:9] op_sel:[0,1] op_sel_hi:[1,0]
	v_pk_fma_f32 v[12:13], v[40:41], v[12:13], v[16:17] op_sel_hi:[0,1,1]
	s_waitcnt lgkmcnt(1)
	v_pk_mul_f32 v[16:17], v[50:51], v[32:33] op_sel:[0,1] op_sel_hi:[1,0]
	v_pk_fma_f32 v[8:9], v[46:47], v[8:9], v[20:21] op_sel_hi:[0,1,1]
	v_pk_fma_f32 v[16:17], v[42:43], v[32:33], v[16:17] op_sel_hi:[0,1,1]
	v_pk_mul_f32 v[32:33], v[66:67], v[6:7] op_sel:[0,1] op_sel_hi:[1,0]
	v_pk_mul_f32 v[20:21], v[54:55], v[28:29] op_sel:[0,1] op_sel_hi:[1,0]
	v_pk_fma_f32 v[6:7], v[64:65], v[6:7], v[32:33] op_sel_hi:[0,1,1]
	v_pk_mul_f32 v[32:33], v[70:71], v[22:23] op_sel:[0,1] op_sel_hi:[1,0]
	v_pk_fma_f32 v[20:21], v[52:53], v[28:29], v[20:21] op_sel_hi:[0,1,1]
	v_pk_fma_f32 v[22:23], v[68:69], v[22:23], v[32:33] op_sel_hi:[0,1,1]
	v_pk_mul_f32 v[32:33], v[74:75], v[14:15] op_sel:[0,1] op_sel_hi:[1,0]
	v_pk_mul_f32 v[28:29], v[58:59], v[24:25] op_sel:[0,1] op_sel_hi:[1,0]
	v_pk_fma_f32 v[14:15], v[72:73], v[14:15], v[32:33] op_sel_hi:[0,1,1]
	v_pk_mul_f32 v[32:33], v[78:79], v[34:35] op_sel:[0,1] op_sel_hi:[1,0]
	v_pk_fma_f32 v[24:25], v[56:57], v[24:25], v[28:29] op_sel_hi:[0,1,1]
	v_pk_fma_f32 v[32:33], v[76:77], v[34:35], v[32:33] op_sel_hi:[0,1,1]
	v_pk_mul_f32 v[34:35], v[82:83], v[10:11] op_sel:[0,1] op_sel_hi:[1,0]
	s_waitcnt lgkmcnt(0)
	v_pk_mul_f32 v[28:29], v[62:63], v[36:37] op_sel:[0,1] op_sel_hi:[1,0]
	v_pk_fma_f32 v[10:11], v[80:81], v[10:11], v[34:35] op_sel_hi:[0,1,1]
	v_pk_mul_f32 v[34:35], v[86:87], v[30:31] op_sel:[0,1] op_sel_hi:[1,0]
	v_pk_fma_f32 v[28:29], v[60:61], v[36:37], v[28:29] op_sel_hi:[0,1,1]
	v_pk_fma_f32 v[30:31], v[84:85], v[30:31], v[34:35] op_sel_hi:[0,1,1]
	v_pk_mul_f32 v[34:35], v[90:91], v[26:27] op_sel:[0,1] op_sel_hi:[1,0]
	v_pk_add_f32 v[36:37], v[4:5], v[6:7]
	v_pk_fma_f32 v[26:27], v[88:89], v[26:27], v[34:35] op_sel_hi:[0,1,1]
	v_pk_mul_f32 v[34:35], v[94:95], v[38:39] op_sel:[0,1] op_sel_hi:[1,0]
	v_pk_add_f32 v[4:5], v[4:5], v[6:7] neg_lo:[0,1] neg_hi:[0,1]
	v_pk_fma_f32 v[34:35], v[92:93], v[38:39], v[34:35] op_sel_hi:[0,1,1]
	v_pk_add_f32 v[6:7], v[8:9], v[10:11]
	v_pk_add_f32 v[8:9], v[8:9], v[10:11] neg_lo:[0,1] neg_hi:[0,1]
	v_pk_add_f32 v[10:11], v[12:13], v[14:15]
	v_pk_add_f32 v[12:13], v[12:13], v[14:15] neg_lo:[0,1] neg_hi:[0,1]
	v_pk_add_f32 v[14:15], v[24:25], v[26:27]
	v_pk_add_f32 v[24:25], v[24:25], v[26:27] neg_lo:[0,1] neg_hi:[0,1]
	v_pk_add_f32 v[26:27], v[2:3], v[22:23]
	v_pk_add_f32 v[2:3], v[2:3], v[22:23] neg_lo:[0,1] neg_hi:[0,1]
	v_pk_add_f32 v[22:23], v[20:21], v[30:31]
	v_pk_add_f32 v[20:21], v[20:21], v[30:31] neg_lo:[0,1] neg_hi:[0,1]
	v_pk_add_f32 v[30:31], v[16:17], v[32:33]
	v_pk_add_f32 v[16:17], v[16:17], v[32:33] neg_lo:[0,1] neg_hi:[0,1]
	v_pk_add_f32 v[32:33], v[28:29], v[34:35]
	v_pk_add_f32 v[28:29], v[28:29], v[34:35] neg_lo:[0,1] neg_hi:[0,1]
	v_pk_add_f32 v[34:35], v[36:37], v[6:7]
	v_pk_add_f32 v[6:7], v[36:37], v[6:7] neg_lo:[0,1] neg_hi:[0,1]
	v_xor_b32_e32 v36, 0x80000000, v9
	v_mov_b32_e32 v37, v8
	v_pk_add_f32 v[8:9], v[4:5], v[36:37]
	v_pk_add_f32 v[4:5], v[4:5], v[36:37] neg_lo:[0,1] neg_hi:[0,1]
	v_pk_add_f32 v[36:37], v[10:11], v[14:15]
	v_pk_add_f32 v[10:11], v[10:11], v[14:15] neg_lo:[0,1] neg_hi:[0,1]
	v_xor_b32_e32 v14, 0x80000000, v25
	v_mov_b32_e32 v15, v24
	v_pk_add_f32 v[24:25], v[12:13], v[14:15]
	v_pk_add_f32 v[12:13], v[12:13], v[14:15] neg_lo:[0,1] neg_hi:[0,1]
	v_pk_add_f32 v[14:15], v[26:27], v[22:23]
	v_pk_add_f32 v[22:23], v[26:27], v[22:23] neg_lo:[0,1] neg_hi:[0,1]
	v_xor_b32_e32 v26, 0x80000000, v21
	v_mov_b32_e32 v27, v20
	v_pk_add_f32 v[20:21], v[2:3], v[26:27]
	v_pk_add_f32 v[2:3], v[2:3], v[26:27] neg_lo:[0,1] neg_hi:[0,1]
	v_pk_add_f32 v[26:27], v[30:31], v[32:33]
	v_pk_add_f32 v[30:31], v[30:31], v[32:33] neg_lo:[0,1] neg_hi:[0,1]
	v_xor_b32_e32 v32, 0x80000000, v29
	v_mov_b32_e32 v33, v28
	v_pk_add_f32 v[28:29], v[16:17], v[32:33]
	v_pk_add_f32 v[16:17], v[16:17], v[32:33] neg_lo:[0,1] neg_hi:[0,1]
	v_pk_add_f32 v[32:33], v[34:35], v[36:37]
	v_pk_add_f32 v[34:35], v[34:35], v[36:37] neg_lo:[0,1] neg_hi:[0,1]
	v_pk_mul_f32 v[36:37], v[24:25], s[66:67]
	v_mov_b32_e32 v39, 0
	v_pk_fma_f32 v[24:25], v[24:25], s[0:1], v[36:37] op_sel:[0,0,1] op_sel_hi:[1,0,0]
	v_mov_b32_e32 v41, 0
	v_pk_add_f32 v[36:37], v[8:9], v[24:25]
	v_pk_add_f32 v[8:9], v[8:9], v[24:25] neg_lo:[0,1] neg_hi:[0,1]
	v_xor_b32_e32 v24, 0x80000000, v11
	v_mov_b32_e32 v25, v10
	v_pk_add_f32 v[10:11], v[6:7], v[24:25]
	v_pk_add_f32 v[6:7], v[6:7], v[24:25] neg_lo:[0,1] neg_hi:[0,1]
	v_pk_mul_f32 v[24:25], v[12:13], s[66:67] op_sel:[1,1] op_sel_hi:[0,0]
	v_pk_fma_f32 v[12:13], s[0:1], v[12:13], v[24:25] op_sel_hi:[0,1,1] neg_lo:[0,1,0] neg_hi:[0,1,0]
	v_pk_add_f32 v[24:25], v[4:5], v[12:13]
	v_pk_add_f32 v[4:5], v[4:5], v[12:13] neg_lo:[0,1] neg_hi:[0,1]
	v_pk_add_f32 v[12:13], v[14:15], v[26:27]
	v_pk_add_f32 v[14:15], v[14:15], v[26:27] neg_lo:[0,1] neg_hi:[0,1]
	v_pk_mul_f32 v[26:27], v[28:29], s[66:67] op_sel:[1,1] op_sel_hi:[0,0]
	v_pk_fma_f32 v[26:27], s[0:1], v[28:29], v[26:27] op_sel_hi:[0,1,1]
	v_pk_add_f32 v[28:29], v[20:21], v[26:27]
	v_pk_add_f32 v[20:21], v[20:21], v[26:27] neg_lo:[0,1] neg_hi:[0,1]
	v_xor_b32_e32 v26, 0x80000000, v31
	v_mov_b32_e32 v27, v30
	v_pk_add_f32 v[30:31], v[22:23], v[26:27]
	v_pk_add_f32 v[22:23], v[22:23], v[26:27] neg_lo:[0,1] neg_hi:[0,1]
	v_pk_mul_f32 v[26:27], v[16:17], s[66:67] op_sel:[1,1] op_sel_hi:[0,0]
	v_pk_fma_f32 v[16:17], s[0:1], v[16:17], v[26:27] op_sel_hi:[0,1,1] neg_lo:[0,1,0] neg_hi:[0,1,0]
	v_pk_add_f32 v[26:27], v[2:3], v[16:17]
	v_pk_add_f32 v[2:3], v[2:3], v[16:17] neg_lo:[0,1] neg_hi:[0,1]
	v_pk_add_f32 v[16:17], v[32:33], v[12:13]
	v_pk_add_f32 v[12:13], v[32:33], v[12:13] neg_lo:[0,1] neg_hi:[0,1]
	v_pk_mul_f32 v[32:33], v[28:29], s[68:69] op_sel:[1,1] op_sel_hi:[0,0]
	v_pk_fma_f32 v[28:29], s[16:17], v[28:29], v[32:33] op_sel_hi:[0,1,1]
	v_pk_add_f32 v[32:33], v[36:37], v[28:29]
	v_pk_add_f32 v[28:29], v[36:37], v[28:29] neg_lo:[0,1] neg_hi:[0,1]
	v_pk_mul_f32 v[36:37], v[30:31], s[66:67] op_sel:[1,1] op_sel_hi:[0,0]
	v_pk_fma_f32 v[30:31], s[0:1], v[30:31], v[36:37] op_sel_hi:[0,1,1]
	v_pk_add_f32 v[36:37], v[10:11], v[30:31]
	v_pk_add_f32 v[10:11], v[10:11], v[30:31] neg_lo:[0,1] neg_hi:[0,1]
	v_pk_mul_f32 v[30:31], v[26:27], s[16:17] op_sel:[1,1] op_sel_hi:[0,0]
	v_pk_fma_f32 v[26:27], s[72:73], v[26:27], v[30:31] op_sel_hi:[0,1,1]
	v_pk_add_f32 v[30:31], v[24:25], v[26:27]
	v_pk_add_f32 v[24:25], v[24:25], v[26:27] neg_lo:[0,1] neg_hi:[0,1]
	v_xor_b32_e32 v26, 0x80000000, v15
	v_mov_b32_e32 v27, v14
	v_pk_add_f32 v[14:15], v[34:35], v[26:27]
	v_pk_add_f32 v[26:27], v[34:35], v[26:27] neg_lo:[0,1] neg_hi:[0,1]
	v_pk_mul_f32 v[34:35], v[20:21], s[16:17] op_sel:[1,1] op_sel_hi:[0,0]
	v_pk_fma_f32 v[20:21], s[72:73], v[20:21], v[34:35] op_sel_hi:[0,1,1] neg_lo:[0,1,0] neg_hi:[0,1,0]
	v_pk_add_f32 v[34:35], v[8:9], v[20:21]
	v_pk_add_f32 v[8:9], v[8:9], v[20:21] neg_lo:[0,1] neg_hi:[0,1]
	v_pk_mul_f32 v[20:21], v[22:23], s[66:67] op_sel:[1,1] op_sel_hi:[0,0]
	v_pk_fma_f32 v[20:21], v[22:23], s[0:1], v[20:21] op_sel_hi:[1,0,1] neg_lo:[1,0,0] neg_hi:[1,0,0]
	s_lshl_b64 s[0:1], s[62:63], 2
	v_pk_add_f32 v[22:23], v[6:7], v[20:21]
	v_pk_add_f32 v[6:7], v[6:7], v[20:21] neg_lo:[0,1] neg_hi:[0,1]
	v_pk_mul_f32 v[20:21], v[2:3], s[68:69]
	s_add_u32 s0, s49, s0
	v_pk_fma_f32 v[2:3], v[2:3], s[16:17], v[20:21] op_sel:[0,0,1] op_sel_hi:[1,0,0] neg_lo:[1,0,0] neg_hi:[1,0,0]
	s_addc_u32 s1, s60, s1
	v_pk_add_f32 v[20:21], v[4:5], v[2:3]
	v_pk_add_f32 v[2:3], v[4:5], v[2:3] neg_lo:[0,1] neg_hi:[0,1]
	ds_write2_b64 v18, v[16:17], v[32:33] offset1:16
	ds_write2_b64 v18, v[36:37], v[30:31] offset0:33 offset1:49
	ds_write2_b64 v18, v[14:15], v[34:35] offset0:66 offset1:82
	ds_write2_b64 v18, v[22:23], v[20:21] offset0:99 offset1:115
	ds_write2_b64 v18, v[12:13], v[28:29] offset0:132 offset1:148
	ds_write2_b64 v18, v[10:11], v[24:25] offset0:165 offset1:181
	ds_write2_b64 v18, v[26:27], v[8:9] offset0:198 offset1:214
	ds_write2_b64 v18, v[6:7], v[2:3] offset0:231 offset1:247
	s_waitcnt lgkmcnt(0)
	s_barrier
	s_lshl_b64 s[62:63], s[64:65], 2
	v_ashrrev_i32_e32 v2, 31, v210
	s_add_u32 s62, s22, s62
	v_lshrrev_b32_e32 v2, 23, v2
	global_load_dword v30, v206, s[0:1]
	global_load_dword v20, v207, s[0:1]
	s_addc_u32 s63, s23, s63
	global_load_dword v31, v205, s[0:1]
	global_load_dword v24, v205, s[62:63]
	s_lshl_b64 s[0:1], s[64:65], 16
	v_add_u32_e32 v2, v210, v2
	s_add_u32 s0, s87, s0
	v_ashrrev_i32_e32 v2, 9, v2
	s_addc_u32 s1, s90, s1
	v_mul_i32_i24_e32 v3, 0x200, v2
	s_add_u32 s0, s0, 0x8000
	v_sub_u32_e32 v21, v210, v3
	v_lshlrev_b32_e32 v36, 13, v2
	s_addc_u32 s1, s1, 0
	v_ashrrev_i32_e32 v37, 31, v36
	v_lshlrev_b32_e32 v32, 4, v21
	v_lshl_add_u64 v[2:3], v[36:37], 1, s[0:1]
	v_ashrrev_i32_e32 v33, 31, v32
	v_lshl_add_u64 v[2:3], v[32:33], 1, v[2:3]
	global_load_dwordx4 v[10:13], v[2:3], off offset:16 nt
	global_load_dwordx4 v[14:17], v[2:3], off nt
	v_cmp_lt_i32_e32 vcc, 0, v21
	s_and_saveexec_b64 s[62:63], vcc
	s_cbranch_execz .LBB0_540
	global_load_ushort v41, v[2:3], off offset:-2

.LBB0_550:
	v_lshl_add_u32 v10, v18, 3, v26
	v_ashrrev_i32_e32 v11, 5, v10
	v_lshlrev_b32_e32 v10, 3, v10
	v_lshlrev_b32_e32 v11, 3, v11
	v_add3_u32 v18, 0, v10, v11
	s_waitcnt vmcnt(0)
	v_and_b32_e32 v32, 0xffff0000, v6
	v_mov_b32_e32 v34, v32
	ds_read2_b64 v[10:13], v18 offset1:1
	v_lshlrev_b32_e32 v14, 16, v6
	v_pk_mul_f32 v[16:17], v[30:31], v[34:35]
	v_mov_b32_e32 v21, v20
	v_lshlrev_b32_e32 v33, 16, v7
	v_pk_fma_f32 v[14:15], v[30:31], v[14:15], v[16:17] op_sel:[0,0,1] op_sel_hi:[1,0,0]
	v_mov_b32_e32 v25, v24
	v_pk_fma_f32 v[14:15], v[20:21], v[32:33], v[14:15]
	v_mov_b32_e32 v36, v30
	v_mov_b32_e32 v37, v30
	v_mov_b32_e32 v38, v31
	v_mov_b32_e32 v39, v31
	v_pk_add_f32 v[30:31], v[24:25], v[14:15]
	ds_read2_b64 v[14:17], v18 offset0:2 offset1:3
	s_waitcnt lgkmcnt(1)
	v_pk_mul_f32 v[10:11], v[30:31], v[10:11]
	v_and_b32_e32 v31, 16, v8
	v_and_b32_e32 v30, 0xffff0000, v7
	v_pk_mov_b32 v[6:7], v[32:33], v[30:31] op_sel:[1,0]
	v_lshlrev_b32_e32 v35, 16, v8
	v_pk_mul_f32 v[6:7], v[36:37], v[6:7]
	v_mov_b32_e32 v34, v30
	v_pk_fma_f32 v[6:7], v[38:39], v[32:33], v[6:7]
	v_lshlrev_b32_e32 v31, 16, v9
	v_pk_fma_f32 v[6:7], v[20:21], v[34:35], v[6:7]
	v_lshlrev_b32_e32 v33, 16, v2
	v_pk_add_f32 v[6:7], v[24:25], v[6:7]
	v_lshlrev_b32_e32 v43, 16, v4
	v_pk_mul_f32 v[6:7], v[6:7], v[12:13]
	v_and_b32_e32 v13, 16, v9
	v_and_b32_e32 v12, 0xffff0000, v8
	v_mov_b32_e32 v30, v12
	v_pk_mov_b32 v[12:13], v[34:35], v[12:13] op_sel:[1,0]
	v_pk_mov_b32 v[8:9], v[8:9], v[2:3] op_sel:[1,0]
	v_pk_mul_f32 v[12:13], v[36:37], v[12:13]
	v_and_b32_e32 v9, 16, v9
	v_and_b32_e32 v8, 0xffff0000, v8
	v_pk_fma_f32 v[12:13], v[38:39], v[34:35], v[12:13]
	v_mov_b32_e32 v32, v8
	v_pk_mov_b32 v[8:9], v[30:31], v[8:9] op_sel:[1,0]
	v_pk_fma_f32 v[12:13], v[20:21], v[30:31], v[12:13]
	v_pk_mul_f32 v[8:9], v[36:37], v[8:9]
	v_pk_add_f32 v[12:13], v[24:25], v[12:13]
	v_pk_fma_f32 v[8:9], v[38:39], v[30:31], v[8:9]
	s_waitcnt lgkmcnt(0)
	v_pk_mul_f32 v[12:13], v[12:13], v[14:15]
	v_pk_fma_f32 v[8:9], v[20:21], v[32:33], v[8:9]
	v_and_b32_e32 v15, 16, v3
	v_and_b32_e32 v14, 0xffff0000, v2
	v_pk_add_f32 v[8:9], v[24:25], v[8:9]
	v_mov_b32_e32 v34, v14
	v_pk_mov_b32 v[14:15], v[32:33], v[14:15] op_sel:[1,0]
	v_pk_mul_f32 v[8:9], v[8:9], v[16:17]
	v_pk_mul_f32 v[30:31], v[36:37], v[14:15]
	ds_read2_b64 v[14:17], v18 offset0:4 offset1:5
	v_lshlrev_b32_e32 v35, 16, v3
	v_pk_fma_f32 v[30:31], v[38:39], v[32:33], v[30:31]
	v_and_b32_e32 v28, 0xffff0000, v5
	v_pk_fma_f32 v[30:31], v[20:21], v[34:35], v[30:31]
	s_andn2_b64 vcc, exec, s[50:51]
	v_pk_add_f32 v[40:41], v[24:25], v[30:31]
	ds_read2_b64 v[30:33], v18 offset0:6 offset1:7
	s_waitcnt lgkmcnt(1)
	v_pk_mul_f32 v[14:15], v[40:41], v[14:15]
	v_and_b32_e32 v41, 16, v4
	v_and_b32_e32 v40, 0xffff0000, v3
	v_pk_mov_b32 v[2:3], v[34:35], v[40:41] op_sel:[1,0]
	v_mov_b32_e32 v42, v40
	v_pk_mul_f32 v[2:3], v[36:37], v[2:3] op_sel:[1,1] op_sel_hi:[0,0]
	v_pk_fma_f32 v[2:3], v[38:39], v[34:35], v[2:3] op_sel:[0,0,1] op_sel_hi:[1,1,0]
	v_lshlrev_b32_e32 v35, 16, v5
	v_pk_fma_f32 v[2:3], v[20:21], v[42:43], v[2:3] op_sel:[1,1,1] op_sel_hi:[0,0,0]
	v_pk_add_f32 v[2:3], v[24:25], v[2:3] op_sel:[1,0] op_sel_hi:[0,1]
	v_pk_mul_f32 v[2:3], v[2:3], v[16:17] op_sel:[1,0] op_sel_hi:[0,1]
	v_and_b32_e32 v17, 16, v5
	v_and_b32_e32 v16, 0xffff0000, v4
	v_mov_b32_e32 v34, v16
	v_pk_mov_b32 v[4:5], v[42:43], v[16:17] op_sel:[1,0]
	v_mov_b32_e32 v16, v35
	v_mov_b32_e32 v17, v28
	v_pk_mul_f32 v[4:5], v[36:37], v[4:5]
	v_pk_mul_f32 v[16:17], v[36:37], v[16:17]
	v_pk_fma_f32 v[4:5], v[38:39], v[42:43], v[4:5]
	v_pk_fma_f32 v[16:17], v[38:39], v[34:35], v[16:17]
	v_pk_fma_f32 v[4:5], v[20:21], v[34:35], v[4:5]
	v_pk_fma_f32 v[16:17], v[20:21], v[28:29], v[16:17]
	v_pk_add_f32 v[4:5], v[24:25], v[4:5]
	v_pk_add_f32 v[16:17], v[24:25], v[16:17]
	v_cndmask_b32_e64 v20, 0, 1, s[50:51]
	s_waitcnt lgkmcnt(0)
	v_pk_mul_f32 v[4:5], v[4:5], v[30:31]
	v_pk_mul_f32 v[16:17], v[16:17], v[32:33]
	v_cmp_ne_u32_e64 s[0:1], 1, v20
	s_mov_b64 s[50:51], -1
	s_cbranch_vccnz .LBB0_552
	v_lshl_add_u64 v[20:21], v[26:27], 1, s[70:71]
	v_bfe_u32 v26, v9, 16, 1
	v_bfe_u32 v27, v7, 16, 1
	v_add3_u32 v28, v7, v27, s4
	v_add3_u32 v27, v9, v26, s4
	v_bfe_u32 v26, v6, 16, 1
	v_bfe_u32 v30, v10, 16, 1
	v_bfe_u32 v31, v12, 16, 1
	v_bfe_u32 v24, v13, 16, 1
	v_bfe_u32 v25, v11, 16, 1
	v_add3_u32 v31, v12, v31, s4
	v_add3_u32 v30, v10, v30, s4
	v_add3_u32 v26, v6, v26, s4
	v_add3_u32 v25, v11, v25, s4
	v_add3_u32 v24, v13, v24, s4
	v_bfe_u32 v29, v8, 16, 1
	v_lshrrev_b32_e32 v32, 16, v26
	v_lshrrev_b32_e32 v30, 16, v30
	v_lshrrev_b32_e32 v26, 16, v31
	v_add3_u32 v29, v8, v29, s4
	v_and_or_b32 v26, v24, s91, v26
	v_and_or_b32 v24, v25, s91, v30
	v_bfe_u32 v30, v17, 16, 1
	v_bfe_u32 v31, v3, 16, 1
	v_lshrrev_b32_e32 v29, 16, v29
	v_and_or_b32 v25, v28, s91, v32
	v_add3_u32 v32, v3, v31, s4
	v_add3_u32 v31, v17, v30, s4
	v_bfe_u32 v30, v2, 16, 1
	v_bfe_u32 v33, v16, 16, 1
	v_bfe_u32 v34, v14, 16, 1
	v_bfe_u32 v35, v4, 16, 1
	v_and_or_b32 v27, v27, s91, v29
	v_bfe_u32 v28, v5, 16, 1
	v_bfe_u32 v29, v15, 16, 1
	v_add3_u32 v35, v4, v35, s4
	v_add3_u32 v34, v14, v34, s4
	v_add3_u32 v33, v16, v33, s4
	v_add3_u32 v30, v2, v30, s4
	v_add3_u32 v29, v15, v29, s4
	v_add3_u32 v28, v5, v28, s4
	v_lshrrev_b32_e32 v36, 16, v30
	v_lshrrev_b32_e32 v33, 16, v33
	v_lshrrev_b32_e32 v34, 16, v34
	v_lshrrev_b32_e32 v30, 16, v35
	v_lshl_add_u64 v[20:21], v[22:23], 1, v[20:21]
	s_mov_b64 s[50:51], 0
	v_and_or_b32 v30, v28, s91, v30
	v_and_or_b32 v28, v29, s91, v34
	v_and_or_b32 v31, v31, s91, v33
	v_and_or_b32 v29, v32, s91, v36
	global_store_dwordx4 v[20:21], v[24:27], off
	global_store_dwordx4 v[20:21], v[28:31], off offset:16

.LBB0_560:
	s_or_b64 exec, exec, s[0:1]
	v_mov_b32_e32 v2, v142
	s_waitcnt lgkmcnt(0)
	s_barrier
	s_mov_b32 s41, s38
	v_and_b32_e32 v4, 0x1ff, v2
	v_lshlrev_b32_e32 v2, 5, v2
	v_and_or_b32 v2, v2, s34, v4
	v_ashrrev_i32_e32 v6, 5, v2
	v_lshlrev_b32_e32 v2, 3, v2
	v_lshlrev_b32_e32 v7, 3, v6
	v_add3_u32 v2, 0, v2, v7
	v_add_u32_e32 v143, 0x10800, v2
	ds_read_b64 v[128:129], v2
	ds_read_b64 v[130:131], v2 offset:4224
	ds_read_b64 v[144:145], v2 offset:8448
	ds_read_b64 v[148:149], v2 offset:12672
	ds_read_b64 v[150:151], v2 offset:16896
	ds_read_b64 v[152:153], v2 offset:21120
	ds_read_b64 v[154:155], v2 offset:25344
	ds_read_b64 v[156:157], v2 offset:29568
	ds_read_b64 v[158:159], v2 offset:33792
	ds_read_b64 v[160:161], v2 offset:38016
	ds_read_b64 v[162:163], v2 offset:42240
	ds_read_b64 v[164:165], v2 offset:46464
	ds_read_b64 v[166:167], v2 offset:50688
	ds_read_b64 v[168:169], v2 offset:54912
	ds_read_b64 v[170:171], v2 offset:59136
	ds_read_b64 v[172:173], v2 offset:63360
	v_add_u32_e32 v212, 0x11880, v2
	v_add_u32_e32 v213, 0x12900, v2
	v_add_u32_e32 v214, 0x13980, v2
	ds_read_b64 v[174:175], v143
	ds_read_b64 v[176:177], v212
	ds_read_b64 v[178:179], v213
	ds_read_b64 v[180:181], v214
	v_add_u32_e32 v215, 0x14a00, v2
	s_waitcnt lgkmcnt(3)
	v_pk_add_f32 v[210:211], v[128:129], v[174:175]
	v_pk_add_f32 v[128:129], v[128:129], v[174:175] neg_lo:[0,1] neg_hi:[0,1]
	s_waitcnt lgkmcnt(2)
	v_pk_add_f32 v[174:175], v[130:131], v[176:177]
	v_pk_add_f32 v[130:131], v[130:131], v[176:177] neg_lo:[0,1] neg_hi:[0,1]
	v_add_u32_e32 v216, 0x15a80, v2
	v_pk_mul_f32 v[176:177], v[130:131], s[20:21]
	v_add_u32_e32 v217, 0x16b00, v2
	v_pk_fma_f32 v[130:131], v[130:131], s[10:11], v[176:177] op_sel:[0,0,1] op_sel_hi:[1,0,0]
	s_waitcnt lgkmcnt(1)
	v_pk_add_f32 v[176:177], v[144:145], v[178:179]
	v_pk_add_f32 v[144:145], v[144:145], v[178:179] neg_lo:[0,1] neg_hi:[0,1]
	v_add_u32_e32 v218, 0x17b80, v2
	v_pk_mul_f32 v[178:179], v[144:145], s[24:25]
	ds_read_b64 v[182:183], v215
	ds_read_b64 v[184:185], v216
	ds_read_b64 v[186:187], v217
	ds_read_b64 v[188:189], v218
	v_pk_fma_f32 v[144:145], v[144:145], s[22:23], v[178:179] op_sel:[0,0,1] op_sel_hi:[1,0,0]
	s_waitcnt lgkmcnt(4)
	v_pk_add_f32 v[178:179], v[148:149], v[180:181]
	v_pk_add_f32 v[148:149], v[148:149], v[180:181] neg_lo:[0,1] neg_hi:[0,1]
	s_mov_b32 s43, s26
	v_pk_mul_f32 v[180:181], v[148:149], s[36:37]
	s_mov_b32 s0, s37
	v_pk_fma_f32 v[148:149], v[148:149], s[26:27], v[180:181] op_sel:[0,0,1] op_sel_hi:[1,0,0]
	s_waitcnt lgkmcnt(3)
	v_pk_add_f32 v[180:181], v[150:151], v[182:183]
	v_pk_add_f32 v[150:151], v[150:151], v[182:183] neg_lo:[0,1] neg_hi:[0,1]
	s_mov_b32 s45, s22
	v_pk_mul_f32 v[182:183], v[150:151], s[40:41]
	v_add_u32_e32 v219, 0x18c00, v2
	v_pk_fma_f32 v[150:151], v[150:151], s[38:39], v[182:183] op_sel:[0,0,1] op_sel_hi:[1,0,0]
	s_waitcnt lgkmcnt(2)
	v_pk_add_f32 v[182:183], v[152:153], v[184:185]
	v_pk_add_f32 v[152:153], v[152:153], v[184:185] neg_lo:[0,1] neg_hi:[0,1]
	s_mov_b32 s50, s25
	v_pk_mul_f32 v[184:185], v[152:153], s[42:43]
	v_add_u32_e32 v220, 0x19c80, v2
	v_pk_fma_f32 v[152:153], v[152:153], s[0:1], v[184:185] op_sel:[0,0,1] op_sel_hi:[1,0,0]
	s_waitcnt lgkmcnt(1)
	v_pk_add_f32 v[184:185], v[154:155], v[186:187]
	v_pk_add_f32 v[154:155], v[154:155], v[186:187] neg_lo:[0,1] neg_hi:[0,1]
	v_add_u32_e32 v221, 0x1ad00, v2
	v_pk_mul_f32 v[186:187], v[154:155], s[44:45]
	v_add_u32_e32 v222, 0x1bd80, v2
	ds_read_b64 v[190:191], v219
	ds_read_b64 v[192:193], v220
	ds_read_b64 v[194:195], v221
	ds_read_b64 v[196:197], v222
	v_pk_fma_f32 v[154:155], v[154:155], s[50:51], v[186:187] op_sel:[0,0,1] op_sel_hi:[1,0,0]
	s_waitcnt lgkmcnt(4)
	v_pk_add_f32 v[186:187], v[156:157], v[188:189]
	v_pk_add_f32 v[156:157], v[156:157], v[188:189] neg_lo:[0,1] neg_hi:[0,1]
	v_add_u32_e32 v223, 0x1ce00, v2
	v_pk_mul_f32 v[188:189], v[156:157], s[8:9]
	v_add_u32_e32 v224, 0x1de80, v2
	v_pk_fma_f32 v[156:157], v[156:157], s[16:17], v[188:189] op_sel:[0,0,1] op_sel_hi:[1,0,0]
	s_waitcnt lgkmcnt(3)
	v_pk_add_f32 v[188:189], v[158:159], v[190:191]
	v_pk_add_f32 v[190:191], v[158:159], v[190:191] neg_lo:[0,1] neg_hi:[0,1]
	v_add_u32_e32 v225, 0x1ef00, v2
	s_waitcnt lgkmcnt(2)
	v_pk_add_f32 v[158:159], v[160:161], v[192:193]
	v_pk_add_f32 v[160:161], v[160:161], v[192:193] neg_lo:[0,1] neg_hi:[0,1]
	v_add_u32_e32 v226, 0x1ff80, v2
	v_pk_mul_f32 v[192:193], v[160:161], s[8:9]
	ds_read_b64 v[198:199], v223
	ds_read_b64 v[204:205], v224
	ds_read_b64 v[206:207], v225
	ds_read_b64 v[208:209], v226
	v_pk_fma_f32 v[160:161], v[160:161], s[16:17], v[192:193] op_sel:[0,0,1] op_sel_hi:[1,0,0] neg_lo:[1,0,0] neg_hi:[1,0,0]
	s_waitcnt lgkmcnt(5)
	v_pk_add_f32 v[192:193], v[162:163], v[194:195]
	v_pk_add_f32 v[162:163], v[162:163], v[194:195] neg_lo:[0,1] neg_hi:[0,1]
	v_cvt_f32_u32_e32 v5, v4
	v_pk_mul_f32 v[194:195], v[162:163], s[44:45]
	v_mul_f32_e32 v5, 0x38800000, v5
	v_pk_fma_f32 v[162:163], v[162:163], s[50:51], v[194:195] op_sel:[0,0,1] op_sel_hi:[1,0,0] neg_lo:[1,0,0] neg_hi:[1,0,0]
	s_waitcnt lgkmcnt(4)
	v_pk_add_f32 v[194:195], v[164:165], v[196:197]
	v_pk_add_f32 v[164:165], v[164:165], v[196:197] neg_lo:[0,1] neg_hi:[0,1]
	v_sin_f32_e32 v4, v5
	v_pk_mul_f32 v[196:197], v[164:165], s[42:43]
	v_cos_f32_e32 v6, v5
	v_pk_fma_f32 v[164:165], v[164:165], s[0:1], v[196:197] op_sel:[0,0,1] op_sel_hi:[1,0,0] neg_lo:[1,0,0] neg_hi:[1,0,0]
	s_waitcnt lgkmcnt(3)
	v_pk_add_f32 v[196:197], v[166:167], v[198:199]
	v_pk_add_f32 v[166:167], v[166:167], v[198:199] neg_lo:[0,1] neg_hi:[0,1]
	v_xor_b32_e32 v7, 0x80000000, v4
	v_pk_mul_f32 v[198:199], v[166:167], s[40:41]
	v_mov_b32_e32 v5, v7
	v_pk_fma_f32 v[166:167], v[166:167], s[38:39], v[198:199] op_sel:[0,0,1] op_sel_hi:[1,0,0] neg_lo:[1,0,0] neg_hi:[1,0,0]
	s_waitcnt lgkmcnt(2)
	v_pk_add_f32 v[198:199], v[168:169], v[204:205]
	v_pk_add_f32 v[168:169], v[168:169], v[204:205] neg_lo:[0,1] neg_hi:[0,1]
	v_pk_mul_f32 v[8:9], v[6:7], v[4:5] op_sel:[1,0] op_sel_hi:[0,1]
	v_pk_mul_f32 v[204:205], v[168:169], s[36:37]
	v_pk_fma_f32 v[8:9], v[6:7], v[6:7], v[8:9] op_sel_hi:[1,0,1]
	v_pk_fma_f32 v[168:169], v[168:169], s[26:27], v[204:205] op_sel:[0,0,1] op_sel_hi:[1,0,0] neg_lo:[1,0,0] neg_hi:[1,0,0]
	s_waitcnt lgkmcnt(1)
	v_pk_add_f32 v[204:205], v[170:171], v[206:207]
	v_pk_add_f32 v[170:171], v[170:171], v[206:207] neg_lo:[0,1] neg_hi:[0,1]
	v_xor_b32_e32 v14, 0x80000000, v9
	v_pk_mul_f32 v[206:207], v[170:171], s[24:25]
	v_mov_b32_e32 v15, v9
	v_pk_fma_f32 v[170:171], v[170:171], s[22:23], v[206:207] op_sel:[0,0,1] op_sel_hi:[1,0,0] neg_lo:[1,0,0] neg_hi:[1,0,0]
	s_waitcnt lgkmcnt(0)
	v_pk_add_f32 v[206:207], v[172:173], v[208:209]
	v_pk_add_f32 v[172:173], v[172:173], v[208:209] neg_lo:[0,1] neg_hi:[0,1]
	v_pk_mul_f32 v[12:13], v[8:9], v[14:15] op_sel:[1,0] op_sel_hi:[0,1]
	v_pk_mul_f32 v[208:209], v[172:173], s[20:21]
	v_pk_fma_f32 v[12:13], v[8:9], v[8:9], v[12:13] op_sel_hi:[1,0,1]
	v_pk_fma_f32 v[172:173], v[172:173], s[10:11], v[208:209] op_sel:[0,0,1] op_sel_hi:[1,0,0] neg_lo:[1,0,0] neg_hi:[1,0,0]
	v_pk_add_f32 v[208:209], v[210:211], v[188:189]
	v_pk_add_f32 v[188:189], v[210:211], v[188:189] neg_lo:[0,1] neg_hi:[0,1]
	v_pk_add_f32 v[210:211], v[174:175], v[158:159]
	v_pk_add_f32 v[158:159], v[174:175], v[158:159] neg_lo:[0,1] neg_hi:[0,1]
	v_xor_b32_e32 v16, 0x80000000, v13
	v_pk_mul_f32 v[174:175], v[158:159], s[24:25]
	v_mov_b32_e32 v17, v13
	v_pk_fma_f32 v[158:159], v[158:159], s[22:23], v[174:175] op_sel:[0,0,1] op_sel_hi:[1,0,0]
	v_pk_add_f32 v[174:175], v[176:177], v[192:193]
	v_pk_add_f32 v[176:177], v[176:177], v[192:193] neg_lo:[0,1] neg_hi:[0,1]
	v_pk_mul_f32 v[28:29], v[12:13], v[16:17] op_sel:[1,0] op_sel_hi:[0,1]
	v_pk_mul_f32 v[192:193], v[176:177], s[40:41]
	v_pk_fma_f32 v[28:29], v[12:13], v[12:13], v[28:29] op_sel_hi:[1,0,1]
	v_pk_fma_f32 v[176:177], v[176:177], s[38:39], v[192:193] op_sel:[0,0,1] op_sel_hi:[1,0,0]
	v_pk_add_f32 v[192:193], v[178:179], v[194:195]
	v_pk_add_f32 v[178:179], v[178:179], v[194:195] neg_lo:[0,1] neg_hi:[0,1]
	v_pk_mul_f32 v[44:45], v[16:17], v[28:29] op_sel:[0,1] op_sel_hi:[1,0]
	v_pk_mul_f32 v[194:195], v[178:179], s[44:45]
	v_pk_fma_f32 v[44:45], v[12:13], v[28:29], v[44:45] op_sel_hi:[0,1,1]
	v_pk_fma_f32 v[178:179], v[178:179], s[50:51], v[194:195] op_sel:[0,0,1] op_sel_hi:[1,0,0]
	v_pk_add_f32 v[194:195], v[180:181], v[196:197]
	v_pk_add_f32 v[196:197], v[180:181], v[196:197] neg_lo:[0,1] neg_hi:[0,1]
	v_pk_mul_f32 v[60:61], v[16:17], v[44:45] op_sel:[0,1] op_sel_hi:[1,0]
	v_pk_add_f32 v[180:181], v[182:183], v[198:199]
	v_pk_add_f32 v[182:183], v[182:183], v[198:199] neg_lo:[0,1] neg_hi:[0,1]
	v_pk_fma_f32 v[60:61], v[12:13], v[44:45], v[60:61] op_sel_hi:[0,1,1]
	v_pk_mul_f32 v[198:199], v[182:183], s[44:45]
	v_pk_mul_f32 v[76:77], v[16:17], v[60:61] op_sel:[0,1] op_sel_hi:[1,0]
	v_pk_fma_f32 v[182:183], v[182:183], s[50:51], v[198:199] op_sel:[0,0,1] op_sel_hi:[1,0,0] neg_lo:[1,0,0] neg_hi:[1,0,0]
	v_pk_add_f32 v[198:199], v[184:185], v[204:205]
	v_pk_add_f32 v[184:185], v[184:185], v[204:205] neg_lo:[0,1] neg_hi:[0,1]
	v_pk_fma_f32 v[76:77], v[12:13], v[60:61], v[76:77] op_sel_hi:[0,1,1]
	v_pk_mul_f32 v[204:205], v[184:185], s[40:41]
	v_pk_mul_f32 v[92:93], v[16:17], v[76:77] op_sel:[0,1] op_sel_hi:[1,0]
	v_pk_fma_f32 v[184:185], v[184:185], s[38:39], v[204:205] op_sel:[0,0,1] op_sel_hi:[1,0,0] neg_lo:[1,0,0] neg_hi:[1,0,0]
	v_pk_add_f32 v[204:205], v[186:187], v[206:207]
	v_pk_add_f32 v[186:187], v[186:187], v[206:207] neg_lo:[0,1] neg_hi:[0,1]
	v_pk_fma_f32 v[92:93], v[12:13], v[76:77], v[92:93] op_sel_hi:[0,1,1]
	v_pk_mul_f32 v[206:207], v[186:187], s[24:25]
	v_pk_mul_f32 v[108:109], v[16:17], v[92:93] op_sel:[0,1] op_sel_hi:[1,0]
	v_pk_fma_f32 v[186:187], v[186:187], s[22:23], v[206:207] op_sel:[0,0,1] op_sel_hi:[1,0,0] neg_lo:[1,0,0] neg_hi:[1,0,0]
	v_pk_add_f32 v[206:207], v[128:129], v[190:191] op_sel:[0,1] op_sel_hi:[1,0] neg_hi:[0,1]
	v_pk_add_f32 v[128:129], v[128:129], v[190:191] op_sel:[0,1] op_sel_hi:[1,0] neg_lo:[0,1]
	v_pk_add_f32 v[190:191], v[130:131], v[160:161]
	v_pk_add_f32 v[130:131], v[130:131], v[160:161] neg_lo:[0,1] neg_hi:[0,1]
	v_pk_mul_f32 v[10:11], v[4:5], v[8:9] op_sel:[0,1] op_sel_hi:[1,0]
	v_pk_mul_f32 v[160:161], v[130:131], s[24:25]
	v_pk_fma_f32 v[108:109], v[12:13], v[92:93], v[108:109] op_sel_hi:[0,1,1]
	v_pk_fma_f32 v[130:131], v[130:131], s[22:23], v[160:161] op_sel:[0,0,1] op_sel_hi:[1,0,0]
	v_pk_add_f32 v[160:161], v[144:145], v[162:163]
	v_pk_add_f32 v[144:145], v[144:145], v[162:163] neg_lo:[0,1] neg_hi:[0,1]
	v_pk_fma_f32 v[10:11], v[6:7], v[8:9], v[10:11] op_sel_hi:[0,1,1]
	v_pk_mul_f32 v[162:163], v[144:145], s[40:41]
	v_pk_mul_f32 v[18:19], v[4:5], v[12:13] op_sel:[0,1] op_sel_hi:[1,0]
	v_pk_fma_f32 v[144:145], v[144:145], s[38:39], v[162:163] op_sel:[0,0,1] op_sel_hi:[1,0,0]
	v_pk_add_f32 v[162:163], v[148:149], v[164:165]
	v_pk_add_f32 v[148:149], v[148:149], v[164:165] neg_lo:[0,1] neg_hi:[0,1]
	v_pk_mul_f32 v[32:33], v[4:5], v[28:29] op_sel:[0,1] op_sel_hi:[1,0]
	v_pk_mul_f32 v[164:165], v[148:149], s[44:45]
	v_pk_mul_f32 v[48:49], v[4:5], v[44:45] op_sel:[0,1] op_sel_hi:[1,0]
	v_pk_fma_f32 v[148:149], v[148:149], s[50:51], v[164:165] op_sel:[0,0,1] op_sel_hi:[1,0,0]
	v_pk_add_f32 v[164:165], v[150:151], v[166:167]
	v_pk_add_f32 v[166:167], v[150:151], v[166:167] neg_lo:[0,1] neg_hi:[0,1]
	v_pk_mul_f32 v[64:65], v[4:5], v[60:61] op_sel:[0,1] op_sel_hi:[1,0]
	v_pk_add_f32 v[150:151], v[152:153], v[168:169]
	v_pk_add_f32 v[152:153], v[152:153], v[168:169] neg_lo:[0,1] neg_hi:[0,1]
	v_pk_mul_f32 v[80:81], v[4:5], v[76:77] op_sel:[0,1] op_sel_hi:[1,0]
	v_pk_mul_f32 v[168:169], v[152:153], s[44:45]
	v_pk_mul_f32 v[96:97], v[4:5], v[92:93] op_sel:[0,1] op_sel_hi:[1,0]
	v_pk_fma_f32 v[152:153], v[152:153], s[50:51], v[168:169] op_sel:[0,0,1] op_sel_hi:[1,0,0] neg_lo:[1,0,0] neg_hi:[1,0,0]
	v_pk_add_f32 v[168:169], v[154:155], v[170:171]
	v_pk_add_f32 v[154:155], v[154:155], v[170:171] neg_lo:[0,1] neg_hi:[0,1]
	v_pk_mul_f32 v[112:113], v[4:5], v[108:109] op_sel:[0,1] op_sel_hi:[1,0]
	v_pk_mul_f32 v[170:171], v[154:155], s[40:41]
	v_xor_b32_e32 v22, 0x80000000, v11
	v_pk_fma_f32 v[154:155], v[154:155], s[38:39], v[170:171] op_sel:[0,0,1] op_sel_hi:[1,0,0] neg_lo:[1,0,0] neg_hi:[1,0,0]
	v_pk_add_f32 v[170:171], v[156:157], v[172:173]
	v_pk_add_f32 v[156:157], v[156:157], v[172:173] neg_lo:[0,1] neg_hi:[0,1]
	v_mov_b32_e32 v23, v11
	v_pk_mul_f32 v[172:173], v[156:157], s[24:25]
	v_pk_fma_f32 v[18:19], v[6:7], v[12:13], v[18:19] op_sel_hi:[0,1,1]
	v_pk_fma_f32 v[156:157], v[156:157], s[22:23], v[172:173] op_sel:[0,0,1] op_sel_hi:[1,0,0] neg_lo:[1,0,0] neg_hi:[1,0,0]
	v_pk_add_f32 v[172:173], v[208:209], v[194:195]
	v_pk_add_f32 v[194:195], v[208:209], v[194:195] neg_lo:[0,1] neg_hi:[0,1]
	v_pk_add_f32 v[208:209], v[210:211], v[180:181]
	v_pk_add_f32 v[180:181], v[210:211], v[180:181] neg_lo:[0,1] neg_hi:[0,1]
	v_pk_mul_f32 v[20:21], v[14:15], v[12:13] op_sel:[0,1] op_sel_hi:[1,0]
	v_pk_mul_f32 v[210:211], v[180:181], s[40:41]
	v_pk_fma_f32 v[32:33], v[6:7], v[28:29], v[32:33] op_sel_hi:[0,1,1]
	v_pk_fma_f32 v[180:181], v[180:181], s[38:39], v[210:211] op_sel:[0,0,1] op_sel_hi:[1,0,0]
	v_pk_add_f32 v[210:211], v[174:175], v[198:199]
	v_pk_add_f32 v[198:199], v[174:175], v[198:199] neg_lo:[0,1] neg_hi:[0,1]
	v_pk_mul_f32 v[36:37], v[14:15], v[28:29] op_sel:[0,1] op_sel_hi:[1,0]
	v_pk_add_f32 v[174:175], v[192:193], v[204:205]
	v_pk_add_f32 v[192:193], v[192:193], v[204:205] neg_lo:[0,1] neg_hi:[0,1]
	v_pk_fma_f32 v[48:49], v[6:7], v[44:45], v[48:49] op_sel_hi:[0,1,1]
	v_pk_mul_f32 v[204:205], v[192:193], s[40:41]
	v_pk_mul_f32 v[52:53], v[14:15], v[44:45] op_sel:[0,1] op_sel_hi:[1,0]
	v_pk_fma_f32 v[192:193], v[192:193], s[38:39], v[204:205] op_sel:[0,0,1] op_sel_hi:[1,0,0] neg_lo:[1,0,0] neg_hi:[1,0,0]
	v_pk_add_f32 v[204:205], v[188:189], v[196:197] op_sel:[0,1] op_sel_hi:[1,0] neg_hi:[0,1]
	v_pk_add_f32 v[188:189], v[188:189], v[196:197] op_sel:[0,1] op_sel_hi:[1,0] neg_lo:[0,1]
	v_pk_add_f32 v[196:197], v[158:159], v[182:183]
	v_pk_add_f32 v[158:159], v[158:159], v[182:183] neg_lo:[0,1] neg_hi:[0,1]
	v_pk_fma_f32 v[64:65], v[6:7], v[60:61], v[64:65] op_sel_hi:[0,1,1]
	v_pk_mul_f32 v[182:183], v[158:159], s[40:41]
	v_pk_mul_f32 v[68:69], v[14:15], v[60:61] op_sel:[0,1] op_sel_hi:[1,0]
	v_pk_fma_f32 v[158:159], v[158:159], s[38:39], v[182:183] op_sel:[0,0,1] op_sel_hi:[1,0,0]
	v_pk_add_f32 v[182:183], v[176:177], v[184:185]
	v_pk_add_f32 v[184:185], v[176:177], v[184:185] neg_lo:[0,1] neg_hi:[0,1]
	v_pk_fma_f32 v[80:81], v[6:7], v[76:77], v[80:81] op_sel_hi:[0,1,1]
	v_pk_add_f32 v[176:177], v[178:179], v[186:187]
	v_pk_add_f32 v[178:179], v[178:179], v[186:187] neg_lo:[0,1] neg_hi:[0,1]
	v_pk_mul_f32 v[84:85], v[14:15], v[76:77] op_sel:[0,1] op_sel_hi:[1,0]
	v_pk_mul_f32 v[186:187], v[178:179], s[40:41]
	v_pk_fma_f32 v[96:97], v[6:7], v[92:93], v[96:97] op_sel_hi:[0,1,1]
	v_pk_fma_f32 v[178:179], v[178:179], s[38:39], v[186:187] op_sel:[0,0,1] op_sel_hi:[1,0,0] neg_lo:[1,0,0] neg_hi:[1,0,0]
	v_pk_add_f32 v[186:187], v[206:207], v[164:165]
	v_pk_add_f32 v[164:165], v[206:207], v[164:165] neg_lo:[0,1] neg_hi:[0,1]
	v_pk_add_f32 v[206:207], v[190:191], v[150:151]
	v_pk_add_f32 v[150:151], v[190:191], v[150:151] neg_lo:[0,1] neg_hi:[0,1]
	v_pk_mul_f32 v[100:101], v[14:15], v[92:93] op_sel:[0,1] op_sel_hi:[1,0]
	v_pk_mul_f32 v[190:191], v[150:151], s[40:41]
	v_pk_fma_f32 v[112:113], v[6:7], v[108:109], v[112:113] op_sel_hi:[0,1,1]
	v_pk_fma_f32 v[150:151], v[150:151], s[38:39], v[190:191] op_sel:[0,0,1] op_sel_hi:[1,0,0]
	v_pk_add_f32 v[190:191], v[160:161], v[168:169]
	v_pk_add_f32 v[168:169], v[160:161], v[168:169] neg_lo:[0,1] neg_hi:[0,1]
	v_pk_mul_f32 v[116:117], v[14:15], v[108:109] op_sel:[0,1] op_sel_hi:[1,0]
	v_pk_add_f32 v[160:161], v[162:163], v[170:171]
	v_pk_add_f32 v[162:163], v[162:163], v[170:171] neg_lo:[0,1] neg_hi:[0,1]
	v_pk_fma_f32 v[20:21], v[8:9], v[12:13], v[20:21] op_sel_hi:[0,1,1]
	v_pk_mul_f32 v[170:171], v[162:163], s[40:41]
	v_pk_mul_f32 v[24:25], v[12:13], v[22:23] op_sel:[1,0] op_sel_hi:[0,1]
	v_pk_fma_f32 v[162:163], v[162:163], s[38:39], v[170:171] op_sel:[0,0,1] op_sel_hi:[1,0,0] neg_lo:[1,0,0] neg_hi:[1,0,0]
	v_pk_add_f32 v[170:171], v[128:129], v[166:167] op_sel:[0,1] op_sel_hi:[1,0] neg_hi:[0,1]
	v_pk_add_f32 v[128:129], v[128:129], v[166:167] op_sel:[0,1] op_sel_hi:[1,0] neg_lo:[0,1]
	v_pk_add_f32 v[166:167], v[130:131], v[152:153]
	v_pk_add_f32 v[130:131], v[130:131], v[152:153] neg_lo:[0,1] neg_hi:[0,1]
	v_pk_fma_f32 v[36:37], v[8:9], v[28:29], v[36:37] op_sel_hi:[0,1,1]
	v_pk_mul_f32 v[152:153], v[130:131], s[40:41]
	v_pk_mul_f32 v[40:41], v[22:23], v[28:29] op_sel:[0,1] op_sel_hi:[1,0]
	v_pk_fma_f32 v[130:131], v[130:131], s[38:39], v[152:153] op_sel:[0,0,1] op_sel_hi:[1,0,0]
	v_pk_add_f32 v[152:153], v[144:145], v[154:155]
	v_pk_add_f32 v[154:155], v[144:145], v[154:155] neg_lo:[0,1] neg_hi:[0,1]
	v_pk_fma_f32 v[52:53], v[8:9], v[44:45], v[52:53] op_sel_hi:[0,1,1]
	v_pk_add_f32 v[144:145], v[148:149], v[156:157]
	v_pk_add_f32 v[148:149], v[148:149], v[156:157] neg_lo:[0,1] neg_hi:[0,1]
	v_pk_mul_f32 v[56:57], v[22:23], v[44:45] op_sel:[0,1] op_sel_hi:[1,0]
	v_pk_mul_f32 v[156:157], v[148:149], s[40:41]
	v_pk_fma_f32 v[68:69], v[8:9], v[60:61], v[68:69] op_sel_hi:[0,1,1]
	v_pk_fma_f32 v[148:149], v[148:149], s[38:39], v[156:157] op_sel:[0,0,1] op_sel_hi:[1,0,0] neg_lo:[1,0,0] neg_hi:[1,0,0]
	v_pk_add_f32 v[156:157], v[172:173], v[210:211]
	v_pk_add_f32 v[172:173], v[172:173], v[210:211] neg_lo:[0,1] neg_hi:[0,1]
	v_pk_add_f32 v[210:211], v[208:209], v[174:175]
	v_pk_add_f32 v[208:209], v[208:209], v[174:175] neg_lo:[0,1] neg_hi:[0,1]
	v_pk_mul_f32 v[72:73], v[22:23], v[60:61] op_sel:[0,1] op_sel_hi:[1,0]
	v_pk_add_f32 v[174:175], v[194:195], v[198:199] op_sel:[0,1] op_sel_hi:[1,0] neg_hi:[0,1]
	v_pk_add_f32 v[194:195], v[194:195], v[198:199] op_sel:[0,1] op_sel_hi:[1,0] neg_lo:[0,1]
	v_pk_add_f32 v[198:199], v[180:181], v[192:193]
	v_pk_add_f32 v[192:193], v[180:181], v[192:193] neg_lo:[0,1] neg_hi:[0,1]
	v_pk_fma_f32 v[84:85], v[8:9], v[76:77], v[84:85] op_sel_hi:[0,1,1]
	v_pk_add_f32 v[180:181], v[204:205], v[182:183]
	v_pk_add_f32 v[182:183], v[204:205], v[182:183] neg_lo:[0,1] neg_hi:[0,1]
	v_pk_add_f32 v[204:205], v[196:197], v[176:177]
	v_pk_add_f32 v[196:197], v[196:197], v[176:177] neg_lo:[0,1] neg_hi:[0,1]
	v_pk_mul_f32 v[88:89], v[22:23], v[76:77] op_sel:[0,1] op_sel_hi:[1,0]
	v_pk_add_f32 v[176:177], v[188:189], v[184:185] op_sel:[0,1] op_sel_hi:[1,0] neg_hi:[0,1]
	v_pk_add_f32 v[184:185], v[188:189], v[184:185] op_sel:[0,1] op_sel_hi:[1,0] neg_lo:[0,1]
	v_pk_add_f32 v[188:189], v[158:159], v[178:179]
	v_pk_add_f32 v[178:179], v[158:159], v[178:179] neg_lo:[0,1] neg_hi:[0,1]
	v_pk_fma_f32 v[100:101], v[8:9], v[92:93], v[100:101] op_sel_hi:[0,1,1]
	v_pk_add_f32 v[158:159], v[186:187], v[190:191]
	v_pk_add_f32 v[186:187], v[186:187], v[190:191] neg_lo:[0,1] neg_hi:[0,1]
	v_pk_add_f32 v[190:191], v[206:207], v[160:161]
	v_pk_add_f32 v[206:207], v[206:207], v[160:161] neg_lo:[0,1] neg_hi:[0,1]
	v_pk_mul_f32 v[104:105], v[22:23], v[92:93] op_sel:[0,1] op_sel_hi:[1,0]
	v_pk_add_f32 v[160:161], v[164:165], v[168:169] op_sel:[0,1] op_sel_hi:[1,0] neg_hi:[0,1]
	v_pk_add_f32 v[164:165], v[164:165], v[168:169] op_sel:[0,1] op_sel_hi:[1,0] neg_lo:[0,1]
	v_pk_add_f32 v[168:169], v[150:151], v[162:163]
	v_pk_add_f32 v[162:163], v[150:151], v[162:163] neg_lo:[0,1] neg_hi:[0,1]
	v_pk_fma_f32 v[116:117], v[8:9], v[108:109], v[116:117] op_sel_hi:[0,1,1]
	v_pk_add_f32 v[150:151], v[170:171], v[152:153]
	v_pk_add_f32 v[152:153], v[170:171], v[152:153] neg_lo:[0,1] neg_hi:[0,1]
	v_pk_add_f32 v[170:171], v[166:167], v[144:145]
	v_pk_add_f32 v[166:167], v[166:167], v[144:145] neg_lo:[0,1] neg_hi:[0,1]
	v_pk_mul_f32 v[120:121], v[22:23], v[108:109] op_sel:[0,1] op_sel_hi:[1,0]
	v_pk_add_f32 v[144:145], v[128:129], v[154:155] op_sel:[0,1] op_sel_hi:[1,0] neg_hi:[0,1]
	v_pk_add_f32 v[128:129], v[128:129], v[154:155] op_sel:[0,1] op_sel_hi:[1,0] neg_lo:[0,1]
	v_pk_add_f32 v[154:155], v[130:131], v[148:149]
	v_pk_add_f32 v[148:149], v[130:131], v[148:149] neg_lo:[0,1] neg_hi:[0,1]
	v_xor_b32_e32 v26, 0x80000000, v19
	v_pk_add_f32 v[130:131], v[156:157], v[210:211]
	v_pk_add_f32 v[156:157], v[156:157], v[210:211] neg_lo:[0,1] neg_hi:[0,1]
	v_pk_add_f32 v[210:211], v[172:173], v[208:209] op_sel:[0,1] op_sel_hi:[1,0] neg_hi:[0,1]
	v_pk_add_f32 v[172:173], v[172:173], v[208:209] op_sel:[0,1] op_sel_hi:[1,0] neg_lo:[0,1]
	v_pk_add_f32 v[208:209], v[174:175], v[198:199]
	v_pk_add_f32 v[174:175], v[174:175], v[198:199] neg_lo:[0,1] neg_hi:[0,1]
	v_pk_add_f32 v[198:199], v[194:195], v[192:193] op_sel:[0,1] op_sel_hi:[1,0] neg_hi:[0,1]
	v_pk_add_f32 v[192:193], v[194:195], v[192:193] op_sel:[0,1] op_sel_hi:[1,0] neg_lo:[0,1]
	v_pk_add_f32 v[194:195], v[180:181], v[204:205]
	v_pk_add_f32 v[180:181], v[180:181], v[204:205] neg_lo:[0,1] neg_hi:[0,1]
	v_pk_add_f32 v[204:205], v[182:183], v[196:197] op_sel:[0,1] op_sel_hi:[1,0] neg_hi:[0,1]
	v_pk_add_f32 v[182:183], v[182:183], v[196:197] op_sel:[0,1] op_sel_hi:[1,0] neg_lo:[0,1]
	v_pk_add_f32 v[196:197], v[176:177], v[188:189]
	v_pk_add_f32 v[176:177], v[176:177], v[188:189] neg_lo:[0,1] neg_hi:[0,1]
	v_pk_add_f32 v[188:189], v[184:185], v[178:179] op_sel:[0,1] op_sel_hi:[1,0] neg_hi:[0,1]
	v_pk_add_f32 v[178:179], v[184:185], v[178:179] op_sel:[0,1] op_sel_hi:[1,0] neg_lo:[0,1]
	v_pk_add_f32 v[184:185], v[158:159], v[190:191]
	v_pk_add_f32 v[158:159], v[158:159], v[190:191] neg_lo:[0,1] neg_hi:[0,1]
	v_pk_mul_f32 v[4:5], v[4:5], v[184:185] op_sel:[0,1] op_sel_hi:[1,0]
	v_pk_add_f32 v[190:191], v[186:187], v[206:207] op_sel:[0,1] op_sel_hi:[1,0] neg_hi:[0,1]
	v_pk_add_f32 v[186:187], v[186:187], v[206:207] op_sel:[0,1] op_sel_hi:[1,0] neg_lo:[0,1]
	v_pk_add_f32 v[206:207], v[160:161], v[168:169]
	v_pk_add_f32 v[160:161], v[160:161], v[168:169] neg_lo:[0,1] neg_hi:[0,1]
	v_pk_add_f32 v[168:169], v[164:165], v[162:163] op_sel:[0,1] op_sel_hi:[1,0] neg_hi:[0,1]
	v_pk_add_f32 v[162:163], v[164:165], v[162:163] op_sel:[0,1] op_sel_hi:[1,0] neg_lo:[0,1]
	v_pk_add_f32 v[164:165], v[150:151], v[170:171]
	v_pk_fma_f32 v[4:5], v[6:7], v[184:185], v[4:5] op_sel_hi:[0,1,1]
	v_pk_mul_f32 v[6:7], v[14:15], v[194:195] op_sel:[0,1] op_sel_hi:[1,0]
	v_xor_b32_e32 v30, 0x80000000, v21
	v_pk_fma_f32 v[6:7], v[8:9], v[194:195], v[6:7] op_sel_hi:[0,1,1]
	v_pk_mul_f32 v[8:9], v[22:23], v[164:165] op_sel:[0,1] op_sel_hi:[1,0]
	v_pk_fma_f32 v[24:25], v[12:13], v[10:11], v[24:25] op_sel_hi:[1,0,1]
	v_pk_fma_f32 v[40:41], v[10:11], v[28:29], v[40:41] op_sel_hi:[0,1,1]
	v_pk_fma_f32 v[56:57], v[10:11], v[44:45], v[56:57] op_sel_hi:[0,1,1]
	v_pk_fma_f32 v[72:73], v[10:11], v[60:61], v[72:73] op_sel_hi:[0,1,1]
	v_pk_fma_f32 v[88:89], v[10:11], v[76:77], v[88:89] op_sel_hi:[0,1,1]
	v_pk_fma_f32 v[104:105], v[10:11], v[92:93], v[104:105] op_sel_hi:[0,1,1]
	v_pk_fma_f32 v[120:121], v[10:11], v[108:109], v[120:121] op_sel_hi:[0,1,1]
	v_mov_b32_e32 v27, v19
	v_mov_b32_e32 v31, v21
	v_pk_fma_f32 v[8:9], v[10:11], v[164:165], v[8:9] op_sel_hi:[0,1,1]
	v_pk_mul_f32 v[10:11], v[16:17], v[208:209] op_sel:[0,1] op_sel_hi:[1,0]
	v_xor_b32_e32 v34, 0x80000000, v25
	v_xor_b32_e32 v38, 0x80000000, v29
	v_xor_b32_e32 v42, 0x80000000, v33
	v_xor_b32_e32 v46, 0x80000000, v37
	v_mov_b32_e32 v35, v25
	v_mov_b32_e32 v39, v29
	v_mov_b32_e32 v43, v33
	v_mov_b32_e32 v47, v37
	v_pk_add_f32 v[150:151], v[150:151], v[170:171] neg_lo:[0,1] neg_hi:[0,1]
	v_pk_add_f32 v[170:171], v[152:153], v[166:167] op_sel:[0,1] op_sel_hi:[1,0] neg_hi:[0,1]
	v_pk_add_f32 v[152:153], v[152:153], v[166:167] op_sel:[0,1] op_sel_hi:[1,0] neg_lo:[0,1]
	v_pk_add_f32 v[166:167], v[144:145], v[154:155]
	v_pk_fma_f32 v[10:11], v[12:13], v[208:209], v[10:11] op_sel_hi:[0,1,1]
	v_pk_mul_f32 v[12:13], v[26:27], v[206:207] op_sel:[0,1] op_sel_hi:[1,0]
	v_pk_mul_f32 v[14:15], v[30:31], v[196:197] op_sel:[0,1] op_sel_hi:[1,0]
	v_xor_b32_e32 v50, 0x80000000, v41
	v_xor_b32_e32 v54, 0x80000000, v45
	v_xor_b32_e32 v58, 0x80000000, v49
	v_xor_b32_e32 v62, 0x80000000, v53
	v_xor_b32_e32 v66, 0x80000000, v57
	v_xor_b32_e32 v70, 0x80000000, v61
	v_xor_b32_e32 v74, 0x80000000, v65
	v_mov_b32_e32 v51, v41
	v_mov_b32_e32 v55, v45
	v_mov_b32_e32 v59, v49
	v_mov_b32_e32 v63, v53
	v_mov_b32_e32 v67, v57
	v_mov_b32_e32 v71, v61
	v_mov_b32_e32 v75, v65
	v_pk_add_f32 v[144:145], v[144:145], v[154:155] neg_lo:[0,1] neg_hi:[0,1]
	v_pk_add_f32 v[154:155], v[128:129], v[148:149] op_sel:[0,1] op_sel_hi:[1,0] neg_hi:[0,1]
	v_pk_fma_f32 v[12:13], v[18:19], v[206:207], v[12:13] op_sel_hi:[0,1,1]
	v_pk_fma_f32 v[14:15], v[20:21], v[196:197], v[14:15] op_sel_hi:[0,1,1]
	v_pk_mul_f32 v[16:17], v[34:35], v[166:167] op_sel:[0,1] op_sel_hi:[1,0]
	v_pk_mul_f32 v[18:19], v[38:39], v[210:211] op_sel:[0,1] op_sel_hi:[1,0]
	v_pk_mul_f32 v[20:21], v[42:43], v[190:191] op_sel:[0,1] op_sel_hi:[1,0]
	v_pk_mul_f32 v[22:23], v[46:47], v[204:205] op_sel:[0,1] op_sel_hi:[1,0]
	v_xor_b32_e32 v78, 0x80000000, v69
	v_xor_b32_e32 v82, 0x80000000, v73
	v_xor_b32_e32 v86, 0x80000000, v77
	v_xor_b32_e32 v90, 0x80000000, v81
	v_xor_b32_e32 v94, 0x80000000, v85
	v_xor_b32_e32 v98, 0x80000000, v89
	v_xor_b32_e32 v102, 0x80000000, v93
	v_xor_b32_e32 v106, 0x80000000, v97
	v_xor_b32_e32 v110, 0x80000000, v101
	v_xor_b32_e32 v114, 0x80000000, v105
	v_xor_b32_e32 v118, 0x80000000, v109
	v_xor_b32_e32 v122, 0x80000000, v113
	v_xor_b32_e32 v124, 0x80000000, v117
	v_xor_b32_e32 v126, 0x80000000, v121
	v_mov_b32_e32 v79, v69
	v_mov_b32_e32 v83, v73
	v_mov_b32_e32 v87, v77
	v_mov_b32_e32 v91, v81
	v_mov_b32_e32 v95, v85
	v_mov_b32_e32 v99, v89
	v_mov_b32_e32 v103, v93
	v_mov_b32_e32 v107, v97
	v_mov_b32_e32 v111, v101
	v_mov_b32_e32 v115, v105
	v_mov_b32_e32 v119, v109
	v_mov_b32_e32 v123, v113
	v_mov_b32_e32 v125, v117
	v_mov_b32_e32 v127, v121
	v_pk_add_f32 v[128:129], v[128:129], v[148:149] op_sel:[0,1] op_sel_hi:[1,0] neg_lo:[0,1]
	v_pk_fma_f32 v[16:17], v[24:25], v[166:167], v[16:17] op_sel_hi:[0,1,1]
	v_pk_fma_f32 v[18:19], v[28:29], v[210:211], v[18:19] op_sel_hi:[0,1,1]
	v_pk_fma_f32 v[20:21], v[32:33], v[190:191], v[20:21] op_sel_hi:[0,1,1]
	v_pk_fma_f32 v[22:23], v[36:37], v[204:205], v[22:23] op_sel_hi:[0,1,1]
	v_pk_mul_f32 v[24:25], v[50:51], v[170:171] op_sel:[0,1] op_sel_hi:[1,0]
	v_pk_mul_f32 v[26:27], v[54:55], v[198:199] op_sel:[0,1] op_sel_hi:[1,0]
	v_pk_mul_f32 v[28:29], v[58:59], v[168:169] op_sel:[0,1] op_sel_hi:[1,0]
	v_pk_mul_f32 v[30:31], v[62:63], v[188:189] op_sel:[0,1] op_sel_hi:[1,0]
	v_pk_mul_f32 v[32:33], v[66:67], v[154:155] op_sel:[0,1] op_sel_hi:[1,0]
	v_pk_mul_f32 v[34:35], v[70:71], v[156:157] op_sel:[0,1] op_sel_hi:[1,0]
	v_pk_mul_f32 v[36:37], v[74:75], v[158:159] op_sel:[0,1] op_sel_hi:[1,0]
	v_pk_fma_f32 v[24:25], v[40:41], v[170:171], v[24:25] op_sel_hi:[0,1,1]
	v_pk_fma_f32 v[26:27], v[44:45], v[198:199], v[26:27] op_sel_hi:[0,1,1]
	v_pk_fma_f32 v[28:29], v[48:49], v[168:169], v[28:29] op_sel_hi:[0,1,1]
	v_pk_fma_f32 v[30:31], v[52:53], v[188:189], v[30:31] op_sel_hi:[0,1,1]
	v_pk_fma_f32 v[32:33], v[56:57], v[154:155], v[32:33] op_sel_hi:[0,1,1]
	v_pk_fma_f32 v[34:35], v[60:61], v[156:157], v[34:35] op_sel_hi:[0,1,1]
	v_pk_fma_f32 v[36:37], v[64:65], v[158:159], v[36:37] op_sel_hi:[0,1,1]
	v_pk_mul_f32 v[38:39], v[78:79], v[180:181] op_sel:[0,1] op_sel_hi:[1,0]
	v_pk_mul_f32 v[40:41], v[82:83], v[150:151] op_sel:[0,1] op_sel_hi:[1,0]
	v_pk_mul_f32 v[42:43], v[86:87], v[174:175] op_sel:[0,1] op_sel_hi:[1,0]
	v_pk_mul_f32 v[44:45], v[90:91], v[160:161] op_sel:[0,1] op_sel_hi:[1,0]
	v_pk_mul_f32 v[46:47], v[94:95], v[176:177] op_sel:[0,1] op_sel_hi:[1,0]
	v_pk_mul_f32 v[48:49], v[98:99], v[144:145] op_sel:[0,1] op_sel_hi:[1,0]
	v_pk_mul_f32 v[50:51], v[102:103], v[172:173] op_sel:[0,1] op_sel_hi:[1,0]
	v_pk_mul_f32 v[52:53], v[106:107], v[186:187] op_sel:[0,1] op_sel_hi:[1,0]
	v_pk_mul_f32 v[54:55], v[110:111], v[182:183] op_sel:[0,1] op_sel_hi:[1,0]
	v_pk_mul_f32 v[56:57], v[114:115], v[152:153] op_sel:[0,1] op_sel_hi:[1,0]
	v_pk_mul_f32 v[58:59], v[118:119], v[192:193] op_sel:[0,1] op_sel_hi:[1,0]
	v_pk_mul_f32 v[60:61], v[122:123], v[162:163] op_sel:[0,1] op_sel_hi:[1,0]
	v_pk_mul_f32 v[62:63], v[124:125], v[178:179] op_sel:[0,1] op_sel_hi:[1,0]
	v_pk_mul_f32 v[64:65], v[126:127], v[128:129] op_sel:[0,1] op_sel_hi:[1,0]
	v_pk_fma_f32 v[38:39], v[68:69], v[180:181], v[38:39] op_sel_hi:[0,1,1]
	v_pk_fma_f32 v[40:41], v[72:73], v[150:151], v[40:41] op_sel_hi:[0,1,1]
	v_pk_fma_f32 v[42:43], v[76:77], v[174:175], v[42:43] op_sel_hi:[0,1,1]
	v_pk_fma_f32 v[44:45], v[80:81], v[160:161], v[44:45] op_sel_hi:[0,1,1]
	v_pk_fma_f32 v[46:47], v[84:85], v[176:177], v[46:47] op_sel_hi:[0,1,1]
	v_pk_fma_f32 v[48:49], v[88:89], v[144:145], v[48:49] op_sel_hi:[0,1,1]
	v_pk_fma_f32 v[50:51], v[92:93], v[172:173], v[50:51] op_sel_hi:[0,1,1]
	v_pk_fma_f32 v[52:53], v[96:97], v[186:187], v[52:53] op_sel_hi:[0,1,1]
	v_pk_fma_f32 v[54:55], v[100:101], v[182:183], v[54:55] op_sel_hi:[0,1,1]
	v_pk_fma_f32 v[56:57], v[104:105], v[152:153], v[56:57] op_sel_hi:[0,1,1]
	v_pk_fma_f32 v[58:59], v[108:109], v[192:193], v[58:59] op_sel_hi:[0,1,1]
	v_pk_fma_f32 v[60:61], v[112:113], v[162:163], v[60:61] op_sel_hi:[0,1,1]
	v_pk_fma_f32 v[62:63], v[116:117], v[178:179], v[62:63] op_sel_hi:[0,1,1]
	v_pk_fma_f32 v[64:65], v[120:121], v[128:129], v[64:65] op_sel_hi:[0,1,1]
	ds_write_b64 v2, v[130:131]
	ds_write_b64 v2, v[34:35] offset:4224
	ds_write_b64 v2, v[18:19] offset:8448
	ds_write_b64 v2, v[50:51] offset:12672
	ds_write_b64 v2, v[10:11] offset:16896
	ds_write_b64 v2, v[42:43] offset:21120
	ds_write_b64 v2, v[26:27] offset:25344
	ds_write_b64 v2, v[58:59] offset:29568
	ds_write_b64 v2, v[6:7] offset:33792
	ds_write_b64 v2, v[38:39] offset:38016
	ds_write_b64 v2, v[22:23] offset:42240
	ds_write_b64 v2, v[54:55] offset:46464
	ds_write_b64 v2, v[14:15] offset:50688
	ds_write_b64 v2, v[46:47] offset:54912
	ds_write_b64 v2, v[30:31] offset:59136
	ds_write_b64 v2, v[62:63] offset:63360
	ds_write_b64 v143, v[4:5]
	ds_write_b64 v212, v[36:37]
	ds_write_b64 v213, v[20:21]
	ds_write_b64 v214, v[52:53]
	ds_write_b64 v215, v[12:13]
	ds_write_b64 v216, v[44:45]
	ds_write_b64 v217, v[28:29]
	ds_write_b64 v218, v[60:61]
	ds_write_b64 v219, v[8:9]
	ds_write_b64 v220, v[40:41]
	ds_write_b64 v221, v[24:25]
	ds_write_b64 v222, v[56:57]
	ds_write_b64 v223, v[16:17]
	ds_write_b64 v224, v[48:49]
	ds_write_b64 v225, v[32:33]
	ds_write_b64 v226, v[64:65]
	v_mov_b32_e32 v2, v142
	s_waitcnt lgkmcnt(0)
	s_barrier
	s_nop 0
	v_and_b32_e32 v4, 15, v2
	v_lshlrev_b32_e32 v2, 5, v2
	v_and_b32_e32 v2, 0xfffffe00, v2
	v_lshl_add_u32 v5, v2, 3, 0
	v_lshlrev_b32_e32 v7, 3, v4
	v_ashrrev_i32_e32 v2, 2, v2
	v_add3_u32 v2, v5, v7, v2
	v_add_u32_e32 v143, 0x800, v2
	ds_read2_b64 v[128:131], v2 offset1:16
	ds_read2_b64 v[148:151], v2 offset0:33 offset1:49
	ds_read2_b64 v[152:155], v2 offset0:66 offset1:82
	ds_read2_b64 v[156:159], v2 offset0:99 offset1:115
	ds_read2_b64 v[160:163], v2 offset0:132 offset1:148
	ds_read2_b64 v[164:167], v2 offset0:165 offset1:181
	ds_read2_b64 v[168:171], v2 offset0:198 offset1:214
	ds_read2_b64 v[172:175], v2 offset0:231 offset1:247
	ds_read2_b64 v[176:179], v143 offset0:8 offset1:24
	ds_read2_b64 v[180:183], v143 offset0:41 offset1:57
	ds_read2_b64 v[184:187], v143 offset0:74 offset1:90
	ds_read2_b64 v[188:191], v143 offset0:107 offset1:123
	ds_read2_b64 v[192:195], v143 offset0:140 offset1:156
	ds_read2_b64 v[196:199], v143 offset0:173 offset1:189
	ds_read2_b64 v[204:207], v143 offset0:206 offset1:222
	ds_read2_b64 v[208:211], v143 offset0:239 offset1:255
	s_waitcnt lgkmcnt(7)
	v_pk_add_f32 v[144:145], v[128:129], v[176:177]
	v_pk_add_f32 v[128:129], v[128:129], v[176:177] neg_lo:[0,1] neg_hi:[0,1]
	v_pk_add_f32 v[176:177], v[130:131], v[178:179]
	v_pk_add_f32 v[130:131], v[130:131], v[178:179] neg_lo:[0,1] neg_hi:[0,1]
	v_cvt_f32_ubyte0_e32 v4, v4
	v_pk_mul_f32 v[178:179], v[130:131], s[20:21]
	v_mul_f32_e32 v6, 0x3b000000, v4
	v_pk_fma_f32 v[130:131], v[130:131], s[10:11], v[178:179] op_sel:[0,0,1] op_sel_hi:[1,0,0]
	s_waitcnt lgkmcnt(6)
	v_pk_add_f32 v[178:179], v[148:149], v[180:181]
	v_pk_add_f32 v[148:149], v[148:149], v[180:181] neg_lo:[0,1] neg_hi:[0,1]
	v_sin_f32_e32 v4, v6
	v_pk_mul_f32 v[180:181], v[148:149], s[24:25]
	v_cos_f32_e32 v6, v6
	v_pk_fma_f32 v[148:149], v[148:149], s[22:23], v[180:181] op_sel:[0,0,1] op_sel_hi:[1,0,0]
	v_pk_add_f32 v[180:181], v[150:151], v[182:183]
	v_pk_add_f32 v[150:151], v[150:151], v[182:183] neg_lo:[0,1] neg_hi:[0,1]
	v_xor_b32_e32 v7, 0x80000000, v4
	v_pk_mul_f32 v[182:183], v[150:151], s[36:37]
	v_mov_b32_e32 v5, v7
	v_pk_fma_f32 v[150:151], v[150:151], s[26:27], v[182:183] op_sel:[0,0,1] op_sel_hi:[1,0,0]
	s_waitcnt lgkmcnt(5)
	v_pk_add_f32 v[182:183], v[152:153], v[184:185]
	v_pk_add_f32 v[152:153], v[152:153], v[184:185] neg_lo:[0,1] neg_hi:[0,1]
	v_pk_mul_f32 v[8:9], v[6:7], v[4:5] op_sel:[1,0] op_sel_hi:[0,1]
	v_pk_mul_f32 v[184:185], v[152:153], s[40:41]
	v_pk_fma_f32 v[8:9], v[6:7], v[6:7], v[8:9] op_sel_hi:[1,0,1]
	v_pk_fma_f32 v[152:153], v[152:153], s[38:39], v[184:185] op_sel:[0,0,1] op_sel_hi:[1,0,0]
	v_pk_add_f32 v[184:185], v[154:155], v[186:187]
	v_pk_add_f32 v[154:155], v[154:155], v[186:187] neg_lo:[0,1] neg_hi:[0,1]
	v_xor_b32_e32 v14, 0x80000000, v9
	v_pk_mul_f32 v[186:187], v[154:155], s[42:43]
	v_mov_b32_e32 v15, v9
	v_pk_fma_f32 v[154:155], v[154:155], s[0:1], v[186:187] op_sel:[0,0,1] op_sel_hi:[1,0,0]
	s_waitcnt lgkmcnt(4)
	v_pk_add_f32 v[186:187], v[156:157], v[188:189]
	v_pk_add_f32 v[156:157], v[156:157], v[188:189] neg_lo:[0,1] neg_hi:[0,1]
	v_pk_mul_f32 v[12:13], v[8:9], v[14:15] op_sel:[1,0] op_sel_hi:[0,1]
	v_pk_mul_f32 v[188:189], v[156:157], s[44:45]
	v_pk_fma_f32 v[12:13], v[8:9], v[8:9], v[12:13] op_sel_hi:[1,0,1]
	v_pk_fma_f32 v[156:157], v[156:157], s[50:51], v[188:189] op_sel:[0,0,1] op_sel_hi:[1,0,0]
	v_pk_add_f32 v[188:189], v[158:159], v[190:191]
	v_pk_add_f32 v[158:159], v[158:159], v[190:191] neg_lo:[0,1] neg_hi:[0,1]
	v_xor_b32_e32 v16, 0x80000000, v13
	v_pk_mul_f32 v[190:191], v[158:159], s[8:9]
	v_mov_b32_e32 v17, v13
	v_pk_fma_f32 v[158:159], v[158:159], s[16:17], v[190:191] op_sel:[0,0,1] op_sel_hi:[1,0,0]
	s_waitcnt lgkmcnt(3)
	v_pk_add_f32 v[190:191], v[160:161], v[192:193]
	v_pk_add_f32 v[192:193], v[160:161], v[192:193] neg_lo:[0,1] neg_hi:[0,1]
	v_pk_mul_f32 v[28:29], v[12:13], v[16:17] op_sel:[1,0] op_sel_hi:[0,1]
	v_pk_add_f32 v[160:161], v[162:163], v[194:195]
	v_pk_add_f32 v[162:163], v[162:163], v[194:195] neg_lo:[0,1] neg_hi:[0,1]
	v_pk_fma_f32 v[28:29], v[12:13], v[12:13], v[28:29] op_sel_hi:[1,0,1]
	v_pk_mul_f32 v[194:195], v[162:163], s[8:9]
	v_pk_mul_f32 v[44:45], v[16:17], v[28:29] op_sel:[0,1] op_sel_hi:[1,0]
	v_pk_fma_f32 v[162:163], v[162:163], s[16:17], v[194:195] op_sel:[0,0,1] op_sel_hi:[1,0,0] neg_lo:[1,0,0] neg_hi:[1,0,0]
	s_waitcnt lgkmcnt(2)
	v_pk_add_f32 v[194:195], v[164:165], v[196:197]
	v_pk_add_f32 v[164:165], v[164:165], v[196:197] neg_lo:[0,1] neg_hi:[0,1]
	v_pk_fma_f32 v[44:45], v[12:13], v[28:29], v[44:45] op_sel_hi:[0,1,1]
	v_pk_mul_f32 v[196:197], v[164:165], s[44:45]
	v_pk_mul_f32 v[60:61], v[16:17], v[44:45] op_sel:[0,1] op_sel_hi:[1,0]
	v_pk_fma_f32 v[164:165], v[164:165], s[50:51], v[196:197] op_sel:[0,0,1] op_sel_hi:[1,0,0] neg_lo:[1,0,0] neg_hi:[1,0,0]
	v_pk_add_f32 v[196:197], v[166:167], v[198:199]
	v_pk_add_f32 v[166:167], v[166:167], v[198:199] neg_lo:[0,1] neg_hi:[0,1]
	v_pk_fma_f32 v[60:61], v[12:13], v[44:45], v[60:61] op_sel_hi:[0,1,1]
	v_pk_mul_f32 v[198:199], v[166:167], s[42:43]
	v_pk_mul_f32 v[76:77], v[16:17], v[60:61] op_sel:[0,1] op_sel_hi:[1,0]
	v_pk_fma_f32 v[166:167], v[166:167], s[0:1], v[198:199] op_sel:[0,0,1] op_sel_hi:[1,0,0] neg_lo:[1,0,0] neg_hi:[1,0,0]
	s_waitcnt lgkmcnt(1)
	v_pk_add_f32 v[198:199], v[168:169], v[204:205]
	v_pk_add_f32 v[168:169], v[168:169], v[204:205] neg_lo:[0,1] neg_hi:[0,1]
	v_pk_fma_f32 v[76:77], v[12:13], v[60:61], v[76:77] op_sel_hi:[0,1,1]
	v_pk_mul_f32 v[204:205], v[168:169], s[40:41]
	v_pk_mul_f32 v[92:93], v[16:17], v[76:77] op_sel:[0,1] op_sel_hi:[1,0]
	v_pk_fma_f32 v[168:169], v[168:169], s[38:39], v[204:205] op_sel:[0,0,1] op_sel_hi:[1,0,0] neg_lo:[1,0,0] neg_hi:[1,0,0]
	v_pk_add_f32 v[204:205], v[170:171], v[206:207]
	v_pk_add_f32 v[170:171], v[170:171], v[206:207] neg_lo:[0,1] neg_hi:[0,1]
	v_pk_fma_f32 v[92:93], v[12:13], v[76:77], v[92:93] op_sel_hi:[0,1,1]
	v_pk_mul_f32 v[206:207], v[170:171], s[36:37]
	v_pk_mul_f32 v[108:109], v[16:17], v[92:93] op_sel:[0,1] op_sel_hi:[1,0]
	v_pk_fma_f32 v[170:171], v[170:171], s[26:27], v[206:207] op_sel:[0,0,1] op_sel_hi:[1,0,0] neg_lo:[1,0,0] neg_hi:[1,0,0]
	s_waitcnt lgkmcnt(0)
	v_pk_add_f32 v[206:207], v[172:173], v[208:209]
	v_pk_add_f32 v[172:173], v[172:173], v[208:209] neg_lo:[0,1] neg_hi:[0,1]
	v_pk_mul_f32 v[10:11], v[4:5], v[8:9] op_sel:[0,1] op_sel_hi:[1,0]
	v_pk_mul_f32 v[208:209], v[172:173], s[24:25]
	v_pk_fma_f32 v[108:109], v[12:13], v[92:93], v[108:109] op_sel_hi:[0,1,1]
	v_pk_fma_f32 v[172:173], v[172:173], s[22:23], v[208:209] op_sel:[0,0,1] op_sel_hi:[1,0,0] neg_lo:[1,0,0] neg_hi:[1,0,0]
	v_pk_add_f32 v[208:209], v[174:175], v[210:211]
	v_pk_add_f32 v[174:175], v[174:175], v[210:211] neg_lo:[0,1] neg_hi:[0,1]
	v_pk_fma_f32 v[10:11], v[6:7], v[8:9], v[10:11] op_sel_hi:[0,1,1]
	v_pk_mul_f32 v[210:211], v[174:175], s[20:21]
	v_pk_mul_f32 v[18:19], v[4:5], v[12:13] op_sel:[0,1] op_sel_hi:[1,0]
	v_pk_fma_f32 v[174:175], v[174:175], s[10:11], v[210:211] op_sel:[0,0,1] op_sel_hi:[1,0,0] neg_lo:[1,0,0] neg_hi:[1,0,0]
	v_pk_add_f32 v[210:211], v[144:145], v[190:191]
	v_pk_add_f32 v[144:145], v[144:145], v[190:191] neg_lo:[0,1] neg_hi:[0,1]
	v_pk_add_f32 v[190:191], v[176:177], v[160:161]
	v_pk_add_f32 v[160:161], v[176:177], v[160:161] neg_lo:[0,1] neg_hi:[0,1]
	v_pk_mul_f32 v[32:33], v[4:5], v[28:29] op_sel:[0,1] op_sel_hi:[1,0]
	v_pk_mul_f32 v[176:177], v[160:161], s[24:25]
	v_pk_mul_f32 v[48:49], v[4:5], v[44:45] op_sel:[0,1] op_sel_hi:[1,0]
	v_pk_fma_f32 v[160:161], v[160:161], s[22:23], v[176:177] op_sel:[0,0,1] op_sel_hi:[1,0,0]
	v_pk_add_f32 v[176:177], v[178:179], v[194:195]
	v_pk_add_f32 v[178:179], v[178:179], v[194:195] neg_lo:[0,1] neg_hi:[0,1]
	v_pk_mul_f32 v[64:65], v[4:5], v[60:61] op_sel:[0,1] op_sel_hi:[1,0]
	v_pk_mul_f32 v[194:195], v[178:179], s[40:41]
	v_pk_mul_f32 v[80:81], v[4:5], v[76:77] op_sel:[0,1] op_sel_hi:[1,0]
	v_pk_fma_f32 v[178:179], v[178:179], s[38:39], v[194:195] op_sel:[0,0,1] op_sel_hi:[1,0,0]
	v_pk_add_f32 v[194:195], v[180:181], v[196:197]
	v_pk_add_f32 v[180:181], v[180:181], v[196:197] neg_lo:[0,1] neg_hi:[0,1]
	v_pk_mul_f32 v[96:97], v[4:5], v[92:93] op_sel:[0,1] op_sel_hi:[1,0]
	v_pk_mul_f32 v[196:197], v[180:181], s[44:45]
	v_pk_mul_f32 v[112:113], v[4:5], v[108:109] op_sel:[0,1] op_sel_hi:[1,0]
	v_pk_fma_f32 v[180:181], v[180:181], s[50:51], v[196:197] op_sel:[0,0,1] op_sel_hi:[1,0,0]
	v_pk_add_f32 v[196:197], v[182:183], v[198:199]
	v_pk_add_f32 v[198:199], v[182:183], v[198:199] neg_lo:[0,1] neg_hi:[0,1]
	v_xor_b32_e32 v22, 0x80000000, v11
	v_pk_add_f32 v[182:183], v[184:185], v[204:205]
	v_pk_add_f32 v[184:185], v[184:185], v[204:205] neg_lo:[0,1] neg_hi:[0,1]
	v_mov_b32_e32 v23, v11
	v_pk_mul_f32 v[204:205], v[184:185], s[44:45]
	v_pk_fma_f32 v[18:19], v[6:7], v[12:13], v[18:19] op_sel_hi:[0,1,1]
	v_pk_fma_f32 v[184:185], v[184:185], s[50:51], v[204:205] op_sel:[0,0,1] op_sel_hi:[1,0,0] neg_lo:[1,0,0] neg_hi:[1,0,0]
	v_pk_add_f32 v[204:205], v[186:187], v[206:207]
	v_pk_add_f32 v[186:187], v[186:187], v[206:207] neg_lo:[0,1] neg_hi:[0,1]
	v_pk_mul_f32 v[20:21], v[14:15], v[12:13] op_sel:[0,1] op_sel_hi:[1,0]
	v_pk_mul_f32 v[206:207], v[186:187], s[40:41]
	v_pk_fma_f32 v[32:33], v[6:7], v[28:29], v[32:33] op_sel_hi:[0,1,1]
	v_pk_fma_f32 v[186:187], v[186:187], s[38:39], v[206:207] op_sel:[0,0,1] op_sel_hi:[1,0,0] neg_lo:[1,0,0] neg_hi:[1,0,0]
	v_pk_add_f32 v[206:207], v[188:189], v[208:209]
	v_pk_add_f32 v[188:189], v[188:189], v[208:209] neg_lo:[0,1] neg_hi:[0,1]
	v_pk_mul_f32 v[36:37], v[14:15], v[28:29] op_sel:[0,1] op_sel_hi:[1,0]
	v_pk_mul_f32 v[208:209], v[188:189], s[24:25]
	v_pk_fma_f32 v[48:49], v[6:7], v[44:45], v[48:49] op_sel_hi:[0,1,1]
	v_pk_fma_f32 v[188:189], v[188:189], s[22:23], v[208:209] op_sel:[0,0,1] op_sel_hi:[1,0,0] neg_lo:[1,0,0] neg_hi:[1,0,0]
	v_pk_add_f32 v[208:209], v[128:129], v[192:193] op_sel:[0,1] op_sel_hi:[1,0] neg_hi:[0,1]
	v_pk_add_f32 v[128:129], v[128:129], v[192:193] op_sel:[0,1] op_sel_hi:[1,0] neg_lo:[0,1]
	v_pk_add_f32 v[192:193], v[130:131], v[162:163]
	v_pk_add_f32 v[130:131], v[130:131], v[162:163] neg_lo:[0,1] neg_hi:[0,1]
	v_pk_mul_f32 v[52:53], v[14:15], v[44:45] op_sel:[0,1] op_sel_hi:[1,0]
	v_pk_mul_f32 v[162:163], v[130:131], s[24:25]
	v_pk_fma_f32 v[64:65], v[6:7], v[60:61], v[64:65] op_sel_hi:[0,1,1]
	v_pk_fma_f32 v[130:131], v[130:131], s[22:23], v[162:163] op_sel:[0,0,1] op_sel_hi:[1,0,0]
	v_pk_add_f32 v[162:163], v[148:149], v[164:165]
	v_pk_add_f32 v[148:149], v[148:149], v[164:165] neg_lo:[0,1] neg_hi:[0,1]
	v_pk_mul_f32 v[68:69], v[14:15], v[60:61] op_sel:[0,1] op_sel_hi:[1,0]
	v_pk_mul_f32 v[164:165], v[148:149], s[40:41]
	v_pk_fma_f32 v[80:81], v[6:7], v[76:77], v[80:81] op_sel_hi:[0,1,1]
	v_pk_fma_f32 v[148:149], v[148:149], s[38:39], v[164:165] op_sel:[0,0,1] op_sel_hi:[1,0,0]
	v_pk_add_f32 v[164:165], v[150:151], v[166:167]
	v_pk_add_f32 v[150:151], v[150:151], v[166:167] neg_lo:[0,1] neg_hi:[0,1]
	v_pk_mul_f32 v[84:85], v[14:15], v[76:77] op_sel:[0,1] op_sel_hi:[1,0]
	v_pk_mul_f32 v[166:167], v[150:151], s[44:45]
	v_pk_fma_f32 v[96:97], v[6:7], v[92:93], v[96:97] op_sel_hi:[0,1,1]
	v_pk_fma_f32 v[150:151], v[150:151], s[50:51], v[166:167] op_sel:[0,0,1] op_sel_hi:[1,0,0]
	v_pk_add_f32 v[166:167], v[152:153], v[168:169]
	v_pk_add_f32 v[168:169], v[152:153], v[168:169] neg_lo:[0,1] neg_hi:[0,1]
	v_pk_mul_f32 v[100:101], v[14:15], v[92:93] op_sel:[0,1] op_sel_hi:[1,0]
	v_pk_add_f32 v[152:153], v[154:155], v[170:171]
	v_pk_add_f32 v[154:155], v[154:155], v[170:171] neg_lo:[0,1] neg_hi:[0,1]
	v_pk_fma_f32 v[112:113], v[6:7], v[108:109], v[112:113] op_sel_hi:[0,1,1]
	v_pk_mul_f32 v[170:171], v[154:155], s[44:45]
	v_pk_mul_f32 v[116:117], v[14:15], v[108:109] op_sel:[0,1] op_sel_hi:[1,0]
	v_pk_fma_f32 v[154:155], v[154:155], s[50:51], v[170:171] op_sel:[0,0,1] op_sel_hi:[1,0,0] neg_lo:[1,0,0] neg_hi:[1,0,0]
	v_pk_add_f32 v[170:171], v[156:157], v[172:173]
	v_pk_add_f32 v[156:157], v[156:157], v[172:173] neg_lo:[0,1] neg_hi:[0,1]
	v_pk_fma_f32 v[20:21], v[8:9], v[12:13], v[20:21] op_sel_hi:[0,1,1]
	v_pk_mul_f32 v[172:173], v[156:157], s[40:41]
	v_pk_mul_f32 v[24:25], v[12:13], v[22:23] op_sel:[1,0] op_sel_hi:[0,1]
	v_pk_fma_f32 v[156:157], v[156:157], s[38:39], v[172:173] op_sel:[0,0,1] op_sel_hi:[1,0,0] neg_lo:[1,0,0] neg_hi:[1,0,0]
	v_pk_add_f32 v[172:173], v[158:159], v[174:175]
	v_pk_add_f32 v[158:159], v[158:159], v[174:175] neg_lo:[0,1] neg_hi:[0,1]
	v_pk_fma_f32 v[36:37], v[8:9], v[28:29], v[36:37] op_sel_hi:[0,1,1]
	v_pk_mul_f32 v[174:175], v[158:159], s[24:25]
	v_pk_mul_f32 v[40:41], v[22:23], v[28:29] op_sel:[0,1] op_sel_hi:[1,0]
	v_pk_fma_f32 v[158:159], v[158:159], s[22:23], v[174:175] op_sel:[0,0,1] op_sel_hi:[1,0,0] neg_lo:[1,0,0] neg_hi:[1,0,0]
	v_pk_add_f32 v[174:175], v[210:211], v[196:197]
	v_pk_add_f32 v[196:197], v[210:211], v[196:197] neg_lo:[0,1] neg_hi:[0,1]
	v_pk_add_f32 v[210:211], v[190:191], v[182:183]
	v_pk_add_f32 v[182:183], v[190:191], v[182:183] neg_lo:[0,1] neg_hi:[0,1]
	v_pk_fma_f32 v[52:53], v[8:9], v[44:45], v[52:53] op_sel_hi:[0,1,1]
	v_pk_mul_f32 v[190:191], v[182:183], s[40:41]
	v_pk_mul_f32 v[56:57], v[22:23], v[44:45] op_sel:[0,1] op_sel_hi:[1,0]
	v_pk_fma_f32 v[182:183], v[182:183], s[38:39], v[190:191] op_sel:[0,0,1] op_sel_hi:[1,0,0]
	v_pk_add_f32 v[190:191], v[176:177], v[204:205]
	v_pk_add_f32 v[204:205], v[176:177], v[204:205] neg_lo:[0,1] neg_hi:[0,1]
	v_pk_fma_f32 v[68:69], v[8:9], v[60:61], v[68:69] op_sel_hi:[0,1,1]
	v_pk_add_f32 v[176:177], v[194:195], v[206:207]
	v_pk_add_f32 v[194:195], v[194:195], v[206:207] neg_lo:[0,1] neg_hi:[0,1]
	v_pk_mul_f32 v[72:73], v[22:23], v[60:61] op_sel:[0,1] op_sel_hi:[1,0]
	v_pk_mul_f32 v[206:207], v[194:195], s[40:41]
	v_pk_fma_f32 v[84:85], v[8:9], v[76:77], v[84:85] op_sel_hi:[0,1,1]
	v_pk_fma_f32 v[194:195], v[194:195], s[38:39], v[206:207] op_sel:[0,0,1] op_sel_hi:[1,0,0] neg_lo:[1,0,0] neg_hi:[1,0,0]
	v_pk_add_f32 v[206:207], v[144:145], v[198:199] op_sel:[0,1] op_sel_hi:[1,0] neg_hi:[0,1]
	v_pk_add_f32 v[144:145], v[144:145], v[198:199] op_sel:[0,1] op_sel_hi:[1,0] neg_lo:[0,1]
	v_pk_add_f32 v[198:199], v[160:161], v[184:185]
	v_pk_add_f32 v[160:161], v[160:161], v[184:185] neg_lo:[0,1] neg_hi:[0,1]
	v_pk_mul_f32 v[88:89], v[22:23], v[76:77] op_sel:[0,1] op_sel_hi:[1,0]
	v_pk_mul_f32 v[184:185], v[160:161], s[40:41]
	v_pk_fma_f32 v[100:101], v[8:9], v[92:93], v[100:101] op_sel_hi:[0,1,1]
	v_pk_fma_f32 v[160:161], v[160:161], s[38:39], v[184:185] op_sel:[0,0,1] op_sel_hi:[1,0,0]
	v_pk_add_f32 v[184:185], v[178:179], v[186:187]
	v_pk_add_f32 v[186:187], v[178:179], v[186:187] neg_lo:[0,1] neg_hi:[0,1]
	v_pk_mul_f32 v[104:105], v[22:23], v[92:93] op_sel:[0,1] op_sel_hi:[1,0]
	v_pk_add_f32 v[178:179], v[180:181], v[188:189]
	v_pk_add_f32 v[180:181], v[180:181], v[188:189] neg_lo:[0,1] neg_hi:[0,1]
	v_pk_fma_f32 v[116:117], v[8:9], v[108:109], v[116:117] op_sel_hi:[0,1,1]
	v_pk_mul_f32 v[188:189], v[180:181], s[40:41]
	v_pk_mul_f32 v[120:121], v[22:23], v[108:109] op_sel:[0,1] op_sel_hi:[1,0]
	v_pk_fma_f32 v[180:181], v[180:181], s[38:39], v[188:189] op_sel:[0,0,1] op_sel_hi:[1,0,0] neg_lo:[1,0,0] neg_hi:[1,0,0]
	v_pk_add_f32 v[188:189], v[208:209], v[166:167]
	v_pk_add_f32 v[166:167], v[208:209], v[166:167] neg_lo:[0,1] neg_hi:[0,1]
	v_pk_add_f32 v[208:209], v[192:193], v[152:153]
	v_pk_add_f32 v[152:153], v[192:193], v[152:153] neg_lo:[0,1] neg_hi:[0,1]
	v_xor_b32_e32 v26, 0x80000000, v19
	v_pk_mul_f32 v[192:193], v[152:153], s[40:41]
	v_xor_b32_e32 v30, 0x80000000, v21
	v_pk_fma_f32 v[152:153], v[152:153], s[38:39], v[192:193] op_sel:[0,0,1] op_sel_hi:[1,0,0]
	v_pk_add_f32 v[192:193], v[162:163], v[170:171]
	v_pk_add_f32 v[170:171], v[162:163], v[170:171] neg_lo:[0,1] neg_hi:[0,1]
	v_pk_fma_f32 v[24:25], v[12:13], v[10:11], v[24:25] op_sel_hi:[1,0,1]
	v_pk_add_f32 v[162:163], v[164:165], v[172:173]
	v_pk_add_f32 v[164:165], v[164:165], v[172:173] neg_lo:[0,1] neg_hi:[0,1]
	v_pk_fma_f32 v[40:41], v[10:11], v[28:29], v[40:41] op_sel_hi:[0,1,1]
	v_pk_mul_f32 v[172:173], v[164:165], s[40:41]
	v_pk_fma_f32 v[56:57], v[10:11], v[44:45], v[56:57] op_sel_hi:[0,1,1]
	v_pk_fma_f32 v[164:165], v[164:165], s[38:39], v[172:173] op_sel:[0,0,1] op_sel_hi:[1,0,0] neg_lo:[1,0,0] neg_hi:[1,0,0]
	v_pk_add_f32 v[172:173], v[128:129], v[168:169] op_sel:[0,1] op_sel_hi:[1,0] neg_hi:[0,1]
	v_pk_add_f32 v[128:129], v[128:129], v[168:169] op_sel:[0,1] op_sel_hi:[1,0] neg_lo:[0,1]
	v_pk_add_f32 v[168:169], v[130:131], v[154:155]
	v_pk_add_f32 v[130:131], v[130:131], v[154:155] neg_lo:[0,1] neg_hi:[0,1]
	v_pk_fma_f32 v[72:73], v[10:11], v[60:61], v[72:73] op_sel_hi:[0,1,1]
	v_pk_mul_f32 v[154:155], v[130:131], s[40:41]
	v_pk_fma_f32 v[88:89], v[10:11], v[76:77], v[88:89] op_sel_hi:[0,1,1]
	v_pk_fma_f32 v[130:131], v[130:131], s[38:39], v[154:155] op_sel:[0,0,1] op_sel_hi:[1,0,0]
	v_pk_add_f32 v[154:155], v[148:149], v[156:157]
	v_pk_add_f32 v[156:157], v[148:149], v[156:157] neg_lo:[0,1] neg_hi:[0,1]
	v_pk_fma_f32 v[104:105], v[10:11], v[92:93], v[104:105] op_sel_hi:[0,1,1]
	v_pk_add_f32 v[148:149], v[150:151], v[158:159]
	v_pk_add_f32 v[150:151], v[150:151], v[158:159] neg_lo:[0,1] neg_hi:[0,1]
	v_pk_fma_f32 v[120:121], v[10:11], v[108:109], v[120:121] op_sel_hi:[0,1,1]
	v_pk_mul_f32 v[158:159], v[150:151], s[40:41]
	v_mov_b32_e32 v27, v19
	v_pk_fma_f32 v[150:151], v[150:151], s[38:39], v[158:159] op_sel:[0,0,1] op_sel_hi:[1,0,0] neg_lo:[1,0,0] neg_hi:[1,0,0]
	v_pk_add_f32 v[158:159], v[174:175], v[190:191]
	v_pk_add_f32 v[174:175], v[174:175], v[190:191] neg_lo:[0,1] neg_hi:[0,1]
	v_pk_add_f32 v[190:191], v[210:211], v[176:177]
	v_pk_add_f32 v[210:211], v[210:211], v[176:177] neg_lo:[0,1] neg_hi:[0,1]
	v_mov_b32_e32 v31, v21
	v_pk_add_f32 v[176:177], v[196:197], v[204:205] op_sel:[0,1] op_sel_hi:[1,0] neg_hi:[0,1]
	v_pk_add_f32 v[196:197], v[196:197], v[204:205] op_sel:[0,1] op_sel_hi:[1,0] neg_lo:[0,1]
	v_pk_add_f32 v[204:205], v[182:183], v[194:195]
	v_pk_add_f32 v[194:195], v[182:183], v[194:195] neg_lo:[0,1] neg_hi:[0,1]
	v_xor_b32_e32 v34, 0x80000000, v25
	v_pk_add_f32 v[182:183], v[206:207], v[184:185]
	v_pk_add_f32 v[184:185], v[206:207], v[184:185] neg_lo:[0,1] neg_hi:[0,1]
	v_pk_add_f32 v[206:207], v[198:199], v[178:179]
	v_pk_add_f32 v[198:199], v[198:199], v[178:179] neg_lo:[0,1] neg_hi:[0,1]
	v_xor_b32_e32 v38, 0x80000000, v29
	v_pk_add_f32 v[178:179], v[144:145], v[186:187] op_sel:[0,1] op_sel_hi:[1,0] neg_hi:[0,1]
	v_pk_add_f32 v[144:145], v[144:145], v[186:187] op_sel:[0,1] op_sel_hi:[1,0] neg_lo:[0,1]
	v_pk_add_f32 v[186:187], v[160:161], v[180:181]
	v_pk_add_f32 v[180:181], v[160:161], v[180:181] neg_lo:[0,1] neg_hi:[0,1]
	v_xor_b32_e32 v42, 0x80000000, v33
	v_pk_add_f32 v[160:161], v[188:189], v[192:193]
	v_pk_add_f32 v[188:189], v[188:189], v[192:193] neg_lo:[0,1] neg_hi:[0,1]
	v_pk_add_f32 v[192:193], v[208:209], v[162:163]
	v_pk_add_f32 v[208:209], v[208:209], v[162:163] neg_lo:[0,1] neg_hi:[0,1]
	v_xor_b32_e32 v46, 0x80000000, v37
	v_pk_add_f32 v[162:163], v[166:167], v[170:171] op_sel:[0,1] op_sel_hi:[1,0] neg_hi:[0,1]
	v_pk_add_f32 v[166:167], v[166:167], v[170:171] op_sel:[0,1] op_sel_hi:[1,0] neg_lo:[0,1]
	v_pk_add_f32 v[170:171], v[152:153], v[164:165]
	v_pk_add_f32 v[164:165], v[152:153], v[164:165] neg_lo:[0,1] neg_hi:[0,1]
	v_mov_b32_e32 v35, v25
	v_pk_add_f32 v[152:153], v[172:173], v[154:155]
	v_pk_add_f32 v[154:155], v[172:173], v[154:155] neg_lo:[0,1] neg_hi:[0,1]
	v_pk_add_f32 v[172:173], v[168:169], v[148:149]
	v_pk_add_f32 v[168:169], v[168:169], v[148:149] neg_lo:[0,1] neg_hi:[0,1]
	v_mov_b32_e32 v39, v29
	v_pk_add_f32 v[148:149], v[128:129], v[156:157] op_sel:[0,1] op_sel_hi:[1,0] neg_hi:[0,1]
	v_pk_add_f32 v[128:129], v[128:129], v[156:157] op_sel:[0,1] op_sel_hi:[1,0] neg_lo:[0,1]
	v_pk_add_f32 v[156:157], v[130:131], v[150:151]
	v_pk_add_f32 v[130:131], v[130:131], v[150:151] neg_lo:[0,1] neg_hi:[0,1]
	v_mov_b32_e32 v43, v33
	v_xor_b32_e32 v151, 0x80000000, v130
	v_mov_b32_e32 v150, v131
	v_pk_add_f32 v[130:131], v[158:159], v[190:191]
	v_pk_add_f32 v[158:159], v[158:159], v[190:191] neg_lo:[0,1] neg_hi:[0,1]
	v_pk_add_f32 v[190:191], v[174:175], v[210:211] op_sel:[0,1] op_sel_hi:[1,0] neg_hi:[0,1]
	v_pk_add_f32 v[174:175], v[174:175], v[210:211] op_sel:[0,1] op_sel_hi:[1,0] neg_lo:[0,1]
	v_pk_add_f32 v[210:211], v[176:177], v[204:205]
	v_pk_add_f32 v[176:177], v[176:177], v[204:205] neg_lo:[0,1] neg_hi:[0,1]
	v_pk_add_f32 v[204:205], v[196:197], v[194:195] op_sel:[0,1] op_sel_hi:[1,0] neg_hi:[0,1]
	v_pk_add_f32 v[194:195], v[196:197], v[194:195] op_sel:[0,1] op_sel_hi:[1,0] neg_lo:[0,1]
	v_pk_add_f32 v[196:197], v[182:183], v[206:207]
	v_pk_add_f32 v[182:183], v[182:183], v[206:207] neg_lo:[0,1] neg_hi:[0,1]
	v_pk_add_f32 v[206:207], v[184:185], v[198:199] op_sel:[0,1] op_sel_hi:[1,0] neg_hi:[0,1]
	v_pk_add_f32 v[184:185], v[184:185], v[198:199] op_sel:[0,1] op_sel_hi:[1,0] neg_lo:[0,1]
	v_pk_add_f32 v[198:199], v[178:179], v[186:187]
	v_pk_add_f32 v[178:179], v[178:179], v[186:187] neg_lo:[0,1] neg_hi:[0,1]
	v_pk_add_f32 v[186:187], v[144:145], v[180:181] op_sel:[0,1] op_sel_hi:[1,0] neg_hi:[0,1]
	v_pk_add_f32 v[144:145], v[144:145], v[180:181] op_sel:[0,1] op_sel_hi:[1,0] neg_lo:[0,1]
	v_pk_add_f32 v[180:181], v[160:161], v[192:193]
	v_pk_add_f32 v[160:161], v[160:161], v[192:193] neg_lo:[0,1] neg_hi:[0,1]
	v_pk_mul_f32 v[4:5], v[4:5], v[180:181] op_sel:[0,1] op_sel_hi:[1,0]
	v_pk_add_f32 v[192:193], v[188:189], v[208:209] op_sel:[0,1] op_sel_hi:[1,0] neg_hi:[0,1]
	v_pk_add_f32 v[188:189], v[188:189], v[208:209] op_sel:[0,1] op_sel_hi:[1,0] neg_lo:[0,1]
	v_pk_add_f32 v[208:209], v[162:163], v[170:171]
	v_pk_add_f32 v[162:163], v[162:163], v[170:171] neg_lo:[0,1] neg_hi:[0,1]
	v_pk_add_f32 v[170:171], v[166:167], v[164:165] op_sel:[0,1] op_sel_hi:[1,0] neg_hi:[0,1]
	v_pk_add_f32 v[164:165], v[166:167], v[164:165] op_sel:[0,1] op_sel_hi:[1,0] neg_lo:[0,1]
	v_pk_add_f32 v[166:167], v[152:153], v[172:173]
	v_pk_fma_f32 v[4:5], v[6:7], v[180:181], v[4:5] op_sel_hi:[0,1,1]
	v_pk_mul_f32 v[6:7], v[14:15], v[196:197] op_sel:[0,1] op_sel_hi:[1,0]
	v_mov_b32_e32 v47, v37
	v_pk_fma_f32 v[6:7], v[8:9], v[196:197], v[6:7] op_sel_hi:[0,1,1]
	v_pk_mul_f32 v[8:9], v[22:23], v[166:167] op_sel:[0,1] op_sel_hi:[1,0]
	v_pk_add_f32 v[152:153], v[152:153], v[172:173] neg_lo:[0,1] neg_hi:[0,1]
	v_pk_fma_f32 v[8:9], v[10:11], v[166:167], v[8:9] op_sel_hi:[0,1,1]
	v_pk_mul_f32 v[10:11], v[16:17], v[210:211] op_sel:[0,1] op_sel_hi:[1,0]
	v_pk_add_f32 v[172:173], v[154:155], v[168:169] op_sel:[0,1] op_sel_hi:[1,0] neg_hi:[0,1]
	v_pk_add_f32 v[154:155], v[154:155], v[168:169] op_sel:[0,1] op_sel_hi:[1,0] neg_lo:[0,1]
	v_pk_add_f32 v[168:169], v[148:149], v[156:157]
	v_pk_fma_f32 v[10:11], v[12:13], v[210:211], v[10:11] op_sel_hi:[0,1,1]
	v_pk_mul_f32 v[12:13], v[26:27], v[208:209] op_sel:[0,1] op_sel_hi:[1,0]
	v_pk_mul_f32 v[14:15], v[30:31], v[198:199] op_sel:[0,1] op_sel_hi:[1,0]
	v_xor_b32_e32 v50, 0x80000000, v41
	v_xor_b32_e32 v54, 0x80000000, v45
	v_xor_b32_e32 v58, 0x80000000, v49
	v_xor_b32_e32 v62, 0x80000000, v53
	v_xor_b32_e32 v66, 0x80000000, v57
	v_xor_b32_e32 v70, 0x80000000, v61
	v_xor_b32_e32 v74, 0x80000000, v65
	v_mov_b32_e32 v51, v41
	v_mov_b32_e32 v55, v45
	v_mov_b32_e32 v59, v49
	v_mov_b32_e32 v63, v53
	v_mov_b32_e32 v67, v57
	v_mov_b32_e32 v71, v61
	v_mov_b32_e32 v75, v65
	v_pk_add_f32 v[148:149], v[148:149], v[156:157] neg_lo:[0,1] neg_hi:[0,1]
	v_pk_add_f32 v[156:157], v[128:129], v[150:151]
	v_pk_fma_f32 v[12:13], v[18:19], v[208:209], v[12:13] op_sel_hi:[0,1,1]
	v_pk_fma_f32 v[14:15], v[20:21], v[198:199], v[14:15] op_sel_hi:[0,1,1]
	v_pk_mul_f32 v[16:17], v[34:35], v[168:169] op_sel:[0,1] op_sel_hi:[1,0]
	v_pk_mul_f32 v[18:19], v[38:39], v[190:191] op_sel:[0,1] op_sel_hi:[1,0]
	v_pk_mul_f32 v[20:21], v[42:43], v[192:193] op_sel:[0,1] op_sel_hi:[1,0]
	v_pk_mul_f32 v[22:23], v[46:47], v[206:207] op_sel:[0,1] op_sel_hi:[1,0]
	v_xor_b32_e32 v78, 0x80000000, v69
	v_xor_b32_e32 v82, 0x80000000, v73
	v_xor_b32_e32 v86, 0x80000000, v77
	v_xor_b32_e32 v90, 0x80000000, v81
	v_xor_b32_e32 v94, 0x80000000, v85
	v_xor_b32_e32 v98, 0x80000000, v89
	v_xor_b32_e32 v102, 0x80000000, v93
	v_xor_b32_e32 v106, 0x80000000, v97
	v_xor_b32_e32 v110, 0x80000000, v101
	v_xor_b32_e32 v114, 0x80000000, v105
	v_xor_b32_e32 v118, 0x80000000, v109
	v_xor_b32_e32 v122, 0x80000000, v113
	v_xor_b32_e32 v124, 0x80000000, v117
	v_xor_b32_e32 v126, 0x80000000, v121
	v_mov_b32_e32 v79, v69
	v_mov_b32_e32 v83, v73
	v_mov_b32_e32 v87, v77
	v_mov_b32_e32 v91, v81
	v_mov_b32_e32 v95, v85
	v_mov_b32_e32 v99, v89
	v_mov_b32_e32 v103, v93
	v_mov_b32_e32 v107, v97
	v_mov_b32_e32 v111, v101
	v_mov_b32_e32 v115, v105
	v_mov_b32_e32 v119, v109
	v_mov_b32_e32 v123, v113
	v_mov_b32_e32 v125, v117
	v_mov_b32_e32 v127, v121
	v_pk_add_f32 v[128:129], v[128:129], v[150:151] neg_lo:[0,1] neg_hi:[0,1]
	v_pk_fma_f32 v[16:17], v[24:25], v[168:169], v[16:17] op_sel_hi:[0,1,1]
	v_pk_fma_f32 v[18:19], v[28:29], v[190:191], v[18:19] op_sel_hi:[0,1,1]
	v_pk_fma_f32 v[20:21], v[32:33], v[192:193], v[20:21] op_sel_hi:[0,1,1]
	v_pk_fma_f32 v[22:23], v[36:37], v[206:207], v[22:23] op_sel_hi:[0,1,1]
	v_pk_mul_f32 v[24:25], v[50:51], v[172:173] op_sel:[0,1] op_sel_hi:[1,0]
	v_pk_mul_f32 v[26:27], v[54:55], v[204:205] op_sel:[0,1] op_sel_hi:[1,0]
	v_pk_mul_f32 v[28:29], v[58:59], v[170:171] op_sel:[0,1] op_sel_hi:[1,0]
	v_pk_mul_f32 v[30:31], v[62:63], v[186:187] op_sel:[0,1] op_sel_hi:[1,0]
	v_pk_mul_f32 v[32:33], v[66:67], v[156:157] op_sel:[0,1] op_sel_hi:[1,0]
	v_pk_mul_f32 v[34:35], v[70:71], v[158:159] op_sel:[0,1] op_sel_hi:[1,0]
	v_pk_mul_f32 v[36:37], v[74:75], v[160:161] op_sel:[0,1] op_sel_hi:[1,0]
	v_pk_fma_f32 v[24:25], v[40:41], v[172:173], v[24:25] op_sel_hi:[0,1,1]
	v_pk_fma_f32 v[26:27], v[44:45], v[204:205], v[26:27] op_sel_hi:[0,1,1]
	v_pk_fma_f32 v[28:29], v[48:49], v[170:171], v[28:29] op_sel_hi:[0,1,1]
	v_pk_fma_f32 v[30:31], v[52:53], v[186:187], v[30:31] op_sel_hi:[0,1,1]
	v_pk_fma_f32 v[32:33], v[56:57], v[156:157], v[32:33] op_sel_hi:[0,1,1]
	v_pk_fma_f32 v[34:35], v[60:61], v[158:159], v[34:35] op_sel_hi:[0,1,1]
	v_pk_fma_f32 v[36:37], v[64:65], v[160:161], v[36:37] op_sel_hi:[0,1,1]
	v_pk_mul_f32 v[38:39], v[78:79], v[182:183] op_sel:[0,1] op_sel_hi:[1,0]
	v_pk_mul_f32 v[40:41], v[82:83], v[152:153] op_sel:[0,1] op_sel_hi:[1,0]
	v_pk_mul_f32 v[42:43], v[86:87], v[176:177] op_sel:[0,1] op_sel_hi:[1,0]
	v_pk_mul_f32 v[44:45], v[90:91], v[162:163] op_sel:[0,1] op_sel_hi:[1,0]
	v_pk_mul_f32 v[46:47], v[94:95], v[178:179] op_sel:[0,1] op_sel_hi:[1,0]
	v_pk_mul_f32 v[48:49], v[98:99], v[148:149] op_sel:[0,1] op_sel_hi:[1,0]
	v_pk_mul_f32 v[50:51], v[102:103], v[174:175] op_sel:[0,1] op_sel_hi:[1,0]
	v_pk_mul_f32 v[52:53], v[106:107], v[188:189] op_sel:[0,1] op_sel_hi:[1,0]
	v_pk_mul_f32 v[54:55], v[110:111], v[184:185] op_sel:[0,1] op_sel_hi:[1,0]
	v_pk_mul_f32 v[56:57], v[114:115], v[154:155] op_sel:[0,1] op_sel_hi:[1,0]
	v_pk_mul_f32 v[58:59], v[118:119], v[194:195] op_sel:[0,1] op_sel_hi:[1,0]
	v_pk_mul_f32 v[60:61], v[122:123], v[164:165] op_sel:[0,1] op_sel_hi:[1,0]
	v_pk_mul_f32 v[62:63], v[124:125], v[144:145] op_sel:[0,1] op_sel_hi:[1,0]
	v_pk_mul_f32 v[64:65], v[126:127], v[128:129] op_sel:[0,1] op_sel_hi:[1,0]
	v_pk_fma_f32 v[38:39], v[68:69], v[182:183], v[38:39] op_sel_hi:[0,1,1]
	v_pk_fma_f32 v[40:41], v[72:73], v[152:153], v[40:41] op_sel_hi:[0,1,1]
	v_pk_fma_f32 v[42:43], v[76:77], v[176:177], v[42:43] op_sel_hi:[0,1,1]
	v_pk_fma_f32 v[44:45], v[80:81], v[162:163], v[44:45] op_sel_hi:[0,1,1]
	v_pk_fma_f32 v[46:47], v[84:85], v[178:179], v[46:47] op_sel_hi:[0,1,1]
	v_pk_fma_f32 v[48:49], v[88:89], v[148:149], v[48:49] op_sel_hi:[0,1,1]
	v_pk_fma_f32 v[50:51], v[92:93], v[174:175], v[50:51] op_sel_hi:[0,1,1]
	v_pk_fma_f32 v[52:53], v[96:97], v[188:189], v[52:53] op_sel_hi:[0,1,1]
	v_pk_fma_f32 v[54:55], v[100:101], v[184:185], v[54:55] op_sel_hi:[0,1,1]
	v_pk_fma_f32 v[56:57], v[104:105], v[154:155], v[56:57] op_sel_hi:[0,1,1]
	v_pk_fma_f32 v[58:59], v[108:109], v[194:195], v[58:59] op_sel_hi:[0,1,1]
	v_pk_fma_f32 v[60:61], v[112:113], v[164:165], v[60:61] op_sel_hi:[0,1,1]
	v_pk_fma_f32 v[62:63], v[116:117], v[144:145], v[62:63] op_sel_hi:[0,1,1]
	v_pk_fma_f32 v[64:65], v[120:121], v[128:129], v[64:65] op_sel_hi:[0,1,1]
	ds_write2_b64 v2, v[130:131], v[34:35] offset1:16
	ds_write2_b64 v2, v[18:19], v[50:51] offset0:33 offset1:49
	ds_write2_b64 v2, v[10:11], v[42:43] offset0:66 offset1:82
	ds_write2_b64 v2, v[26:27], v[58:59] offset0:99 offset1:115
	ds_write2_b64 v2, v[6:7], v[38:39] offset0:132 offset1:148
	ds_write2_b64 v2, v[22:23], v[54:55] offset0:165 offset1:181
	ds_write2_b64 v2, v[14:15], v[46:47] offset0:198 offset1:214
	ds_write2_b64 v2, v[30:31], v[62:63] offset0:231 offset1:247
	ds_write2_b64 v143, v[4:5], v[36:37] offset0:8 offset1:24
	ds_write2_b64 v143, v[20:21], v[52:53] offset0:41 offset1:57
	ds_write2_b64 v143, v[12:13], v[44:45] offset0:74 offset1:90
	ds_write2_b64 v143, v[28:29], v[60:61] offset0:107 offset1:123
	ds_write2_b64 v143, v[8:9], v[40:41] offset0:140 offset1:156
	ds_write2_b64 v143, v[24:25], v[56:57] offset0:173 offset1:189
	ds_write2_b64 v143, v[16:17], v[48:49] offset0:206 offset1:222
	ds_write2_b64 v143, v[32:33], v[64:65] offset0:239 offset1:255
	s_waitcnt lgkmcnt(0)
	s_barrier
	s_nop 0
	v_ashrrev_i32_e32 v2, 31, v142
	v_lshrrev_b32_e32 v2, 23, v2
	v_add_u32_e32 v2, v142, v2
	v_ashrrev_i32_e32 v2, 9, v2
	v_mul_i32_i24_e32 v4, 0x200, v2
	v_sub_u32_e32 v144, v142, v4
	v_lshlrev_b32_e32 v143, 14, v2
	v_lshlrev_b32_e32 v2, 1, v144
	v_bfrev_b32_e32 v2, v2
	v_lshrrev_b32_e32 v2, 22, v2
	v_sub_u32_e32 v2, 0x400, v2
	v_bfrev_b32_e32 v2, v2
	v_lshrrev_b32_e32 v2, 18, v2
	v_and_b32_e32 v2, 0x3ff0, v2
	v_cmp_eq_u32_e32 vcc, 0, v144
	v_lshl_add_u32 v4, v144, 5, v143
	v_lshlrev_b32_e32 v5, 3, v4
	v_cndmask_b32_e64 v2, v2, 16, vcc
	v_ashrrev_i32_e32 v4, 2, v4
	v_or_b32_e32 v2, v2, v143
	v_add3_u32 v56, 0, v5, v4
	v_ashrrev_i32_e32 v4, 5, v2
	v_lshlrev_b32_e32 v2, 3, v2
	v_lshlrev_b32_e32 v4, 3, v4
	v_add3_u32 v2, 0, v2, v4
	ds_read2_b64 v[4:7], v56 offset1:1
	ds_read2_b64 v[8:11], v56 offset0:2 offset1:3
	ds_read2_b64 v[12:15], v2 offset1:1
	ds_read2_b64 v[16:19], v2 offset0:2 offset1:3
	ds_read2_b64 v[20:23], v56 offset0:4 offset1:5
	ds_read2_b64 v[24:27], v56 offset0:6 offset1:7
	ds_read2_b64 v[28:31], v2 offset0:4 offset1:5
	ds_read2_b64 v[32:35], v2 offset0:6 offset1:7
	ds_read2_b64 v[36:39], v56 offset0:8 offset1:9
	ds_read2_b64 v[40:43], v56 offset0:10 offset1:11
	ds_read2_b64 v[48:51], v2 offset0:8 offset1:9
	ds_read2_b64 v[52:55], v2 offset0:10 offset1:11
	ds_read2_b64 v[44:47], v56 offset0:12 offset1:13
	ds_read2_b64 v[56:59], v56 offset0:14 offset1:15
	ds_read2_b64 v[70:73], v2 offset0:12 offset1:13
	ds_read2_b64 v[98:101], v2 offset0:14 offset1:15
	s_waitcnt lgkmcnt(7)
	v_pk_add_f32 v[60:61], v[4:5], v[36:37]
	v_pk_add_f32 v[4:5], v[4:5], v[36:37] neg_lo:[0,1] neg_hi:[0,1]
	v_pk_add_f32 v[36:37], v[6:7], v[38:39]
	v_pk_add_f32 v[6:7], v[6:7], v[38:39] neg_lo:[0,1] neg_hi:[0,1]
	s_waitcnt lgkmcnt(3)
	v_pk_add_f32 v[62:63], v[22:23], v[46:47]
	v_pk_mul_f32 v[38:39], v[6:7], s[24:25]
	v_pk_add_f32 v[22:23], v[22:23], v[46:47] neg_lo:[0,1] neg_hi:[0,1]
	v_pk_fma_f32 v[6:7], v[6:7], s[22:23], v[38:39] op_sel:[0,0,1] op_sel_hi:[1,0,0]
	v_pk_add_f32 v[38:39], v[8:9], v[40:41]
	v_pk_add_f32 v[8:9], v[8:9], v[40:41] neg_lo:[0,1] neg_hi:[0,1]
	v_pk_mul_f32 v[46:47], v[22:23], s[44:45]
	v_pk_mul_f32 v[40:41], v[8:9], s[40:41]
	v_pk_fma_f32 v[22:23], v[22:23], s[50:51], v[46:47] op_sel:[0,0,1] op_sel_hi:[1,0,0] neg_lo:[1,0,0] neg_hi:[1,0,0]
	v_pk_fma_f32 v[8:9], v[8:9], s[38:39], v[40:41] op_sel:[0,0,1] op_sel_hi:[1,0,0]
	v_pk_add_f32 v[40:41], v[10:11], v[42:43]
	v_pk_add_f32 v[10:11], v[10:11], v[42:43] neg_lo:[0,1] neg_hi:[0,1]
	s_waitcnt lgkmcnt(2)
	v_pk_add_f32 v[46:47], v[24:25], v[56:57]
	v_pk_add_f32 v[24:25], v[24:25], v[56:57] neg_lo:[0,1] neg_hi:[0,1]
	v_pk_mul_f32 v[42:43], v[10:11], s[44:45]
	v_pk_mul_f32 v[56:57], v[24:25], s[40:41]
	v_pk_fma_f32 v[10:11], v[10:11], s[50:51], v[42:43] op_sel:[0,0,1] op_sel_hi:[1,0,0]
	v_pk_add_f32 v[42:43], v[20:21], v[44:45]
	v_pk_add_f32 v[44:45], v[20:21], v[44:45] neg_lo:[0,1] neg_hi:[0,1]
	v_pk_fma_f32 v[24:25], v[24:25], s[38:39], v[56:57] op_sel:[0,0,1] op_sel_hi:[1,0,0] neg_lo:[1,0,0] neg_hi:[1,0,0]
	v_pk_add_f32 v[56:57], v[26:27], v[58:59]
	v_pk_add_f32 v[26:27], v[26:27], v[58:59] op_sel:[1,1] op_sel_hi:[0,0] neg_lo:[0,1] neg_hi:[0,1]
	v_pk_mul_f32 v[58:59], v[26:27], s[24:25] op_sel:[1,0] op_sel_hi:[0,1]
	v_pk_add_f32 v[64:65], v[40:41], v[56:57]
	v_pk_add_f32 v[40:41], v[40:41], v[56:57] neg_lo:[0,1] neg_hi:[0,1]
	v_pk_fma_f32 v[26:27], v[26:27], s[22:23], v[58:59] op_sel:[1,0,1] op_sel_hi:[0,0,0] neg_lo:[1,0,0] neg_hi:[1,0,0]
	v_pk_mul_f32 v[56:57], v[40:41], s[40:41]
	v_pk_add_f32 v[20:21], v[4:5], v[44:45] op_sel:[0,1] op_sel_hi:[1,0] neg_hi:[0,1]
	v_pk_add_f32 v[4:5], v[4:5], v[44:45] op_sel:[0,1] op_sel_hi:[1,0] neg_lo:[0,1]
	v_pk_add_f32 v[44:45], v[6:7], v[22:23]
	v_pk_add_f32 v[6:7], v[6:7], v[22:23] neg_lo:[0,1] neg_hi:[0,1]
	v_pk_fma_f32 v[40:41], v[40:41], s[38:39], v[56:57] op_sel:[0,0,1] op_sel_hi:[1,0,0] neg_lo:[1,0,0] neg_hi:[1,0,0]
	v_pk_mul_f32 v[22:23], v[6:7], s[40:41]
	v_pk_add_f32 v[56:57], v[10:11], v[26:27]
	v_pk_add_f32 v[10:11], v[10:11], v[26:27] neg_lo:[0,1] neg_hi:[0,1]
	v_pk_add_f32 v[58:59], v[60:61], v[42:43]
	v_pk_add_f32 v[42:43], v[60:61], v[42:43] neg_lo:[0,1] neg_hi:[0,1]
	v_pk_add_f32 v[60:61], v[36:37], v[62:63]
	v_pk_add_f32 v[36:37], v[36:37], v[62:63] neg_lo:[0,1] neg_hi:[0,1]
	v_pk_fma_f32 v[6:7], v[6:7], s[38:39], v[22:23] op_sel:[0,0,1] op_sel_hi:[1,0,0]
	v_pk_add_f32 v[22:23], v[8:9], v[24:25]
	v_pk_add_f32 v[24:25], v[8:9], v[24:25] neg_lo:[0,1] neg_hi:[0,1]
	v_pk_mul_f32 v[26:27], v[10:11], s[40:41]
	v_pk_mul_f32 v[62:63], v[36:37], s[40:41]
	v_pk_fma_f32 v[10:11], v[10:11], s[38:39], v[26:27] op_sel:[0,0,1] op_sel_hi:[1,0,0] neg_lo:[1,0,0] neg_hi:[1,0,0]
	v_pk_fma_f32 v[36:37], v[36:37], s[38:39], v[62:63] op_sel:[0,0,1] op_sel_hi:[1,0,0]
	v_pk_add_f32 v[62:63], v[38:39], v[46:47]
	v_pk_add_f32 v[66:67], v[20:21], v[22:23]
	v_pk_add_f32 v[20:21], v[20:21], v[22:23] neg_lo:[0,1] neg_hi:[0,1]
	v_pk_add_f32 v[22:23], v[44:45], v[56:57]
	v_pk_add_f32 v[44:45], v[44:45], v[56:57] neg_lo:[0,1] neg_hi:[0,1]
	v_pk_add_f32 v[8:9], v[4:5], v[24:25] op_sel:[0,1] op_sel_hi:[1,0] neg_hi:[0,1]
	v_pk_add_f32 v[4:5], v[4:5], v[24:25] op_sel:[0,1] op_sel_hi:[1,0] neg_lo:[0,1]
	v_pk_add_f32 v[24:25], v[6:7], v[10:11]
	v_pk_add_f32 v[10:11], v[6:7], v[10:11] neg_lo:[0,1] neg_hi:[0,1]
	v_pk_add_f32 v[26:27], v[58:59], v[62:63]
	v_pk_add_f32 v[58:59], v[58:59], v[62:63] neg_lo:[0,1] neg_hi:[0,1]
	v_pk_add_f32 v[62:63], v[60:61], v[64:65]
	v_pk_add_f32 v[60:61], v[60:61], v[64:65] neg_lo:[0,1] neg_hi:[0,1]
	v_xor_b32_e32 v57, 0x80000000, v44
	v_mov_b32_e32 v56, v45
	v_xor_b32_e32 v65, 0x80000000, v60
	v_pk_add_f32 v[130:131], v[26:27], v[62:63]
	v_pk_add_f32 v[92:93], v[26:27], v[62:63] neg_lo:[0,1] neg_hi:[0,1]
	v_mov_b32_e32 v64, v61
	v_pk_add_f32 v[62:63], v[20:21], v[56:57]
	v_pk_add_f32 v[78:79], v[20:21], v[56:57] neg_lo:[0,1] neg_hi:[0,1]
	v_pk_add_f32 v[56:57], v[4:5], v[10:11] op_sel:[0,1] op_sel_hi:[1,0] neg_hi:[0,1]
	v_pk_add_f32 v[90:91], v[4:5], v[10:11] op_sel:[0,1] op_sel_hi:[1,0] neg_lo:[0,1]
	v_pk_add_f32 v[10:11], v[14:15], v[50:51] neg_lo:[0,1] neg_hi:[0,1]
	v_pk_add_f32 v[46:47], v[38:39], v[46:47] neg_lo:[0,1] neg_hi:[0,1]
	v_pk_add_f32 v[84:85], v[58:59], v[64:65]
	v_pk_add_f32 v[86:87], v[58:59], v[64:65] neg_lo:[0,1] neg_hi:[0,1]
	v_pk_add_f32 v[80:81], v[8:9], v[24:25]
	v_pk_add_f32 v[64:65], v[8:9], v[24:25] neg_lo:[0,1] neg_hi:[0,1]
	v_pk_add_f32 v[4:5], v[12:13], v[48:49]
	v_pk_add_f32 v[6:7], v[12:13], v[48:49] neg_lo:[0,1] neg_hi:[0,1]
	v_pk_add_f32 v[8:9], v[14:15], v[50:51]
	v_pk_mul_f32 v[12:13], v[10:11], s[24:25]
	v_pk_add_f32 v[14:15], v[16:17], v[52:53] neg_lo:[0,1] neg_hi:[0,1]
	v_pk_fma_f32 v[10:11], v[10:11], s[22:23], v[12:13] op_sel:[0,0,1] op_sel_hi:[1,0,0]
	v_pk_add_f32 v[12:13], v[16:17], v[52:53]
	v_pk_mul_f32 v[16:17], v[14:15], s[40:41]
	v_pk_add_f32 v[38:39], v[42:43], v[46:47] op_sel:[0,1] op_sel_hi:[1,0] neg_hi:[0,1]
	v_pk_add_f32 v[42:43], v[42:43], v[46:47] op_sel:[0,1] op_sel_hi:[1,0] neg_lo:[0,1]
	v_pk_add_f32 v[46:47], v[36:37], v[40:41]
	v_pk_fma_f32 v[14:15], v[14:15], s[38:39], v[16:17] op_sel:[0,0,1] op_sel_hi:[1,0,0]
	v_pk_add_f32 v[16:17], v[18:19], v[54:55]
	v_pk_add_f32 v[18:19], v[18:19], v[54:55] neg_lo:[0,1] neg_hi:[0,1]
	v_pk_add_f32 v[88:89], v[38:39], v[46:47]
	v_pk_add_f32 v[68:69], v[38:39], v[46:47] neg_lo:[0,1] neg_hi:[0,1]
	v_pk_add_f32 v[96:97], v[66:67], v[22:23]
	v_pk_add_f32 v[46:47], v[66:67], v[22:23] neg_lo:[0,1] neg_hi:[0,1]
	v_pk_mul_f32 v[20:21], v[18:19], s[44:45]
	s_waitcnt lgkmcnt(1)
	v_pk_add_f32 v[24:25], v[28:29], v[70:71] neg_lo:[0,1] neg_hi:[0,1]
	v_pk_add_f32 v[26:27], v[30:31], v[72:73] neg_lo:[0,1] neg_hi:[0,1]
	v_pk_fma_f32 v[18:19], v[18:19], s[50:51], v[20:21] op_sel:[0,0,1] op_sel_hi:[1,0,0]
	v_pk_add_f32 v[20:21], v[28:29], v[70:71]
	v_pk_add_f32 v[22:23], v[30:31], v[72:73]
	v_pk_mul_f32 v[28:29], v[26:27], s[44:45]
	s_waitcnt lgkmcnt(0)
	v_pk_add_f32 v[30:31], v[32:33], v[98:99] neg_lo:[0,1] neg_hi:[0,1]
	v_pk_fma_f32 v[26:27], v[26:27], s[50:51], v[28:29] op_sel:[0,0,1] op_sel_hi:[1,0,0] neg_lo:[1,0,0] neg_hi:[1,0,0]
	v_pk_add_f32 v[28:29], v[32:33], v[98:99]
	v_pk_mul_f32 v[32:33], v[30:31], s[40:41]
	v_pk_add_f32 v[36:37], v[36:37], v[40:41] neg_lo:[0,1] neg_hi:[0,1]
	v_pk_fma_f32 v[30:31], v[30:31], s[38:39], v[32:33] op_sel:[0,0,1] op_sel_hi:[1,0,0] neg_lo:[1,0,0] neg_hi:[1,0,0]
	v_pk_add_f32 v[32:33], v[34:35], v[100:101]
	v_pk_add_f32 v[34:35], v[34:35], v[100:101] neg_lo:[0,1] neg_hi:[0,1]
	v_xor_b32_e32 v41, 0x80000000, v36
	v_mov_b32_e32 v40, v37
	v_pk_mul_f32 v[36:37], v[34:35], s[24:25]
	v_mov_b32_e32 v2, v130
	v_pk_fma_f32 v[34:35], v[34:35], s[22:23], v[36:37] op_sel:[0,0,1] op_sel_hi:[1,0,0] neg_lo:[1,0,0] neg_hi:[1,0,0]
	v_pk_add_f32 v[36:37], v[4:5], v[20:21]
	v_pk_add_f32 v[4:5], v[4:5], v[20:21] neg_lo:[0,1] neg_hi:[0,1]
	v_pk_add_f32 v[20:21], v[8:9], v[22:23]
	v_pk_add_f32 v[8:9], v[8:9], v[22:23] neg_lo:[0,1] neg_hi:[0,1]
	v_cmp_ne_u32_e64 s[0:1], 0, v144
	v_pk_mul_f32 v[22:23], v[8:9], s[40:41]
	v_pk_add_f32 v[74:75], v[42:43], v[40:41]
	v_pk_fma_f32 v[8:9], v[8:9], s[38:39], v[22:23] op_sel:[0,0,1] op_sel_hi:[1,0,0]
	v_pk_add_f32 v[22:23], v[12:13], v[28:29]
	v_pk_add_f32 v[28:29], v[12:13], v[28:29] neg_lo:[0,1] neg_hi:[0,1]
	v_pk_add_f32 v[94:95], v[42:43], v[40:41] neg_lo:[0,1] neg_hi:[0,1]
	v_pk_add_f32 v[12:13], v[16:17], v[32:33]
	v_pk_add_f32 v[16:17], v[16:17], v[32:33] op_sel:[1,1] op_sel_hi:[0,0] neg_lo:[0,1] neg_hi:[0,1]
	v_pk_mul_f32 v[32:33], v[16:17], s[40:41] op_sel:[1,0] op_sel_hi:[0,1]
	s_nop 0
	v_pk_fma_f32 v[16:17], v[16:17], s[38:39], v[32:33] op_sel:[1,0,1] op_sel_hi:[0,0,0] neg_lo:[1,0,0] neg_hi:[1,0,0]
	v_pk_add_f32 v[32:33], v[6:7], v[24:25] op_sel:[0,1] op_sel_hi:[1,0] neg_hi:[0,1]
	v_pk_add_f32 v[6:7], v[6:7], v[24:25] op_sel:[0,1] op_sel_hi:[1,0] neg_lo:[0,1]
	v_pk_add_f32 v[24:25], v[10:11], v[26:27]
	v_pk_add_f32 v[10:11], v[10:11], v[26:27] op_sel:[1,1] op_sel_hi:[0,0] neg_lo:[0,1] neg_hi:[0,1]
	v_pk_mul_f32 v[26:27], v[10:11], s[40:41] op_sel:[1,0] op_sel_hi:[0,1]
	s_nop 0
	v_pk_fma_f32 v[10:11], v[10:11], s[38:39], v[26:27] op_sel:[1,0,1] op_sel_hi:[0,0,0]
	v_pk_add_f32 v[26:27], v[14:15], v[30:31]
	v_pk_add_f32 v[30:31], v[14:15], v[30:31] neg_lo:[0,1] neg_hi:[0,1]
	s_nop 0
	v_pk_add_f32 v[14:15], v[18:19], v[34:35]
	v_pk_add_f32 v[18:19], v[18:19], v[34:35] op_sel:[1,1] op_sel_hi:[0,0] neg_lo:[0,1] neg_hi:[0,1]
	v_pk_mul_f32 v[34:35], v[18:19], s[40:41] op_sel:[1,0] op_sel_hi:[0,1]
	s_nop 0
	v_pk_fma_f32 v[18:19], v[18:19], s[38:39], v[34:35] op_sel:[1,0,1] op_sel_hi:[0,0,0] neg_lo:[1,0,0] neg_hi:[1,0,0]
	v_pk_add_f32 v[34:35], v[36:37], v[22:23]
	v_pk_add_f32 v[22:23], v[36:37], v[22:23] neg_lo:[0,1] neg_hi:[0,1]
	v_pk_add_f32 v[36:37], v[20:21], v[12:13]
	v_pk_add_f32 v[12:13], v[20:21], v[12:13] neg_lo:[0,1] neg_hi:[0,1]
	v_pk_add_f32 v[98:99], v[34:35], v[36:37]
	v_xor_b32_e32 v21, 0x80000000, v12
	v_mov_b32_e32 v20, v13
	v_pk_add_f32 v[12:13], v[4:5], v[28:29] op_sel:[0,1] op_sel_hi:[1,0] neg_hi:[0,1]
	v_pk_add_f32 v[4:5], v[4:5], v[28:29] op_sel:[0,1] op_sel_hi:[1,0] neg_lo:[0,1]
	v_pk_add_f32 v[28:29], v[8:9], v[16:17]
	v_pk_add_f32 v[8:9], v[8:9], v[16:17] neg_lo:[0,1] neg_hi:[0,1]
	v_pk_add_f32 v[100:101], v[34:35], v[36:37] neg_lo:[0,1] neg_hi:[0,1]
	v_xor_b32_e32 v17, 0x80000000, v8
	v_mov_b32_e32 v16, v9
	v_pk_add_f32 v[8:9], v[32:33], v[26:27]
	v_pk_add_f32 v[26:27], v[32:33], v[26:27] neg_lo:[0,1] neg_hi:[0,1]
	v_pk_add_f32 v[32:33], v[24:25], v[14:15]
	v_pk_add_f32 v[14:15], v[24:25], v[14:15] neg_lo:[0,1] neg_hi:[0,1]
	v_pk_add_f32 v[102:103], v[22:23], v[20:21]
	v_xor_b32_e32 v25, 0x80000000, v14
	v_mov_b32_e32 v24, v15
	v_pk_add_f32 v[14:15], v[6:7], v[30:31] op_sel:[0,1] op_sel_hi:[1,0] neg_hi:[0,1]
	v_pk_add_f32 v[6:7], v[6:7], v[30:31] op_sel:[0,1] op_sel_hi:[1,0] neg_lo:[0,1]
	v_pk_add_f32 v[30:31], v[10:11], v[18:19]
	v_pk_add_f32 v[10:11], v[10:11], v[18:19] neg_lo:[0,1] neg_hi:[0,1]
	v_pk_add_f32 v[104:105], v[22:23], v[20:21] neg_lo:[0,1] neg_hi:[0,1]
	v_xor_b32_e32 v19, 0x80000000, v10
	v_mov_b32_e32 v18, v11
	v_pk_add_f32 v[106:107], v[12:13], v[28:29]
	v_pk_add_f32 v[108:109], v[12:13], v[28:29] neg_lo:[0,1] neg_hi:[0,1]
	v_pk_add_f32 v[110:111], v[4:5], v[16:17]
	v_pk_add_f32 v[112:113], v[4:5], v[16:17] neg_lo:[0,1] neg_hi:[0,1]
	v_pk_add_f32 v[114:115], v[8:9], v[32:33]
	v_pk_add_f32 v[116:117], v[8:9], v[32:33] neg_lo:[0,1] neg_hi:[0,1]
	v_pk_add_f32 v[118:119], v[26:27], v[24:25]
	v_pk_add_f32 v[120:121], v[26:27], v[24:25] neg_lo:[0,1] neg_hi:[0,1]
	v_pk_add_f32 v[122:123], v[14:15], v[30:31]
	v_pk_add_f32 v[124:125], v[14:15], v[30:31] neg_lo:[0,1] neg_hi:[0,1]
	v_pk_add_f32 v[126:127], v[6:7], v[18:19]
	v_pk_add_f32 v[128:129], v[6:7], v[18:19] neg_lo:[0,1] neg_hi:[0,1]
	v_mov_b32_e32 v4, v131
	v_mov_b32_e32 v5, v3
	v_mov_b64_e32 v[6:7], v[2:3]
	s_and_saveexec_b64 s[50:51], s[0:1]
	s_xor_b64 s[0:1], exec, s[50:51]
	s_cbranch_execz .LBB0_562
	v_pk_add_f32 v[4:5], v[96:97], v[112:113]
	v_pk_add_f32 v[24:25], v[96:97], v[112:113] neg_lo:[0,1] neg_hi:[0,1]
	v_pk_add_f32 v[148:149], v[130:131], v[128:129]
	v_pk_add_f32 v[8:9], v[130:131], v[128:129] neg_lo:[0,1] neg_hi:[0,1]
	v_pk_add_f32 v[128:129], v[126:127], v[92:93]
	v_pk_add_f32 v[10:11], v[126:127], v[92:93] neg_lo:[0,1] neg_hi:[0,1]
	v_pk_add_f32 v[92:93], v[84:85], v[124:125]
	v_pk_add_f32 v[12:13], v[84:85], v[124:125] neg_lo:[0,1] neg_hi:[0,1]
	v_pk_add_f32 v[84:85], v[122:123], v[86:87]
	v_pk_add_f32 v[14:15], v[122:123], v[86:87] neg_lo:[0,1] neg_hi:[0,1]
	v_pk_add_f32 v[86:87], v[88:89], v[120:121]
	v_pk_add_f32 v[16:17], v[88:89], v[120:121] neg_lo:[0,1] neg_hi:[0,1]
	v_pk_add_f32 v[88:89], v[118:119], v[68:69]
	v_pk_add_f32 v[18:19], v[118:119], v[68:69] neg_lo:[0,1] neg_hi:[0,1]
	v_pk_add_f32 v[68:69], v[74:75], v[116:117]
	v_pk_add_f32 v[20:21], v[74:75], v[116:117] neg_lo:[0,1] neg_hi:[0,1]
	v_pk_add_f32 v[74:75], v[114:115], v[94:95]
	v_pk_add_f32 v[22:23], v[114:115], v[94:95] neg_lo:[0,1] neg_hi:[0,1]
	v_mov_b32_e32 v6, v4
	v_mov_b32_e32 v7, v25
	v_pk_mov_b32 v[4:5], v[4:5], v[24:25] op_sel:[1,0]
	v_pk_add_f32 v[94:95], v[110:111], v[46:47]
	v_pk_add_f32 v[24:25], v[110:111], v[46:47] neg_lo:[0,1] neg_hi:[0,1]
	v_pk_add_f32 v[46:47], v[62:63], v[108:109]
	v_pk_add_f32 v[26:27], v[62:63], v[108:109] neg_lo:[0,1] neg_hi:[0,1]
	v_pk_add_f32 v[62:63], v[106:107], v[78:79]
	v_pk_add_f32 v[28:29], v[106:107], v[78:79] neg_lo:[0,1] neg_hi:[0,1]
	v_pk_add_f32 v[78:79], v[80:81], v[104:105]
	v_pk_add_f32 v[30:31], v[80:81], v[104:105] neg_lo:[0,1] neg_hi:[0,1]
	v_pk_add_f32 v[80:81], v[102:103], v[64:65]
	v_pk_add_f32 v[32:33], v[102:103], v[64:65] neg_lo:[0,1] neg_hi:[0,1]
	v_pk_add_f32 v[64:65], v[56:57], v[100:101]
	v_pk_add_f32 v[34:35], v[56:57], v[100:101] neg_lo:[0,1] neg_hi:[0,1]
	v_pk_add_f32 v[56:57], v[98:99], v[90:91]
	v_pk_add_f32 v[36:37], v[98:99], v[90:91] neg_lo:[0,1] neg_hi:[0,1]
	v_pk_mul_f32 v[6:7], v[6:7], 0.5 op_sel_hi:[1,0]
	v_pk_mul_f32 v[4:5], v[4:5], s[46:47]
	v_mov_b32_e32 v39, v8
	v_mov_b32_e32 v38, v149
	v_mov_b32_e32 v41, v10
	v_mov_b32_e32 v40, v129
	v_mov_b32_e32 v43, v12
	v_mov_b32_e32 v42, v93
	v_mov_b32_e32 v45, v14
	v_mov_b32_e32 v44, v85
	v_mov_b32_e32 v49, v16
	v_mov_b32_e32 v48, v87
	v_mov_b32_e32 v51, v18
	v_mov_b32_e32 v50, v89
	v_mov_b32_e32 v53, v20
	v_mov_b32_e32 v52, v69
	v_mov_b32_e32 v55, v22
	v_mov_b32_e32 v54, v75
	v_mov_b32_e32 v59, v24
	v_mov_b32_e32 v58, v95
	v_mov_b32_e32 v61, v26
	v_mov_b32_e32 v60, v47
	v_mov_b32_e32 v67, v28
	v_mov_b32_e32 v66, v63
	v_mov_b32_e32 v71, v30
	v_mov_b32_e32 v70, v79
	v_mov_b32_e32 v73, v32
	v_mov_b32_e32 v72, v81
	v_mov_b32_e32 v77, v34
	v_mov_b32_e32 v76, v65
	v_mov_b32_e32 v83, v36
	v_mov_b32_e32 v82, v57
	v_mov_b32_e32 v8, v148
	v_mov_b32_e32 v10, v128
	v_mov_b32_e32 v12, v92
	v_mov_b32_e32 v14, v84
	v_mov_b32_e32 v16, v86
	v_mov_b32_e32 v18, v88
	v_mov_b32_e32 v20, v68
	v_mov_b32_e32 v22, v74
	v_mov_b32_e32 v24, v94
	v_mov_b32_e32 v26, v46
	v_mov_b32_e32 v28, v62
	v_mov_b32_e32 v30, v78
	v_mov_b32_e32 v32, v80
	v_mov_b32_e32 v34, v64
	v_mov_b32_e32 v36, v56

.LBB0_574:
	s_or_b64 exec, exec, s[0:1]
	v_mov_b32_e32 v2, v142
	s_waitcnt lgkmcnt(0)
	s_barrier
	s_mov_b32 s19, s16
	v_and_b32_e32 v4, 0xff, v2
	v_lshlrev_b32_e32 v5, 5, v2
	v_and_or_b32 v4, v5, s68, v4
	v_ashrrev_i32_e32 v5, 5, v4
	v_cvt_f32_ubyte0_e32 v2, v2
	v_lshlrev_b32_e32 v7, 3, v4
	v_mul_f32_e32 v2, 0x39000000, v2
	v_lshlrev_b32_e32 v5, 3, v5
	v_sin_f32_e32 v4, v2
	v_cos_f32_e32 v6, v2
	v_add3_u32 v2, 0, v7, v5
	ds_read_b64 v[128:129], v2
	ds_read_b64 v[130:131], v2 offset:2112
	ds_read_b64 v[144:145], v2 offset:4224
	ds_read_b64 v[148:149], v2 offset:6336
	ds_read_b64 v[150:151], v2 offset:8448
	ds_read_b64 v[152:153], v2 offset:10560
	ds_read_b64 v[154:155], v2 offset:12672
	ds_read_b64 v[156:157], v2 offset:14784
	ds_read_b64 v[158:159], v2 offset:16896
	ds_read_b64 v[160:161], v2 offset:19008
	ds_read_b64 v[162:163], v2 offset:21120
	ds_read_b64 v[164:165], v2 offset:23232
	ds_read_b64 v[166:167], v2 offset:25344
	ds_read_b64 v[168:169], v2 offset:27456
	ds_read_b64 v[170:171], v2 offset:29568
	ds_read_b64 v[172:173], v2 offset:31680
	ds_read_b64 v[174:175], v2 offset:33792
	ds_read_b64 v[176:177], v2 offset:35904
	ds_read_b64 v[178:179], v2 offset:38016
	ds_read_b64 v[180:181], v2 offset:40128
	ds_read_b64 v[182:183], v2 offset:42240
	ds_read_b64 v[184:185], v2 offset:44352
	ds_read_b64 v[186:187], v2 offset:46464
	ds_read_b64 v[188:189], v2 offset:48576
	ds_read_b64 v[190:191], v2 offset:50688
	ds_read_b64 v[192:193], v2 offset:52800
	ds_read_b64 v[194:195], v2 offset:54912
	ds_read_b64 v[196:197], v2 offset:57024
	ds_read_b64 v[198:199], v2 offset:59136
	ds_read_b64 v[204:205], v2 offset:61248
	ds_read_b64 v[206:207], v2 offset:63360
	ds_read_b64 v[208:209], v2 offset:65472
	s_waitcnt lgkmcnt(14)
	v_pk_add_f32 v[210:211], v[128:129], v[174:175]
	v_pk_add_f32 v[128:129], v[128:129], v[174:175] neg_lo:[0,1] neg_hi:[0,1]
	v_pk_add_f32 v[174:175], v[130:131], v[176:177]
	v_pk_add_f32 v[130:131], v[130:131], v[176:177] neg_lo:[0,1] neg_hi:[0,1]
	s_mov_b32 s0, s9
	v_pk_mul_f32 v[176:177], v[130:131], s[18:19]
	s_mov_b32 s41, s38
	v_pk_fma_f32 v[130:131], v[130:131], s[0:1], v[176:177] op_sel:[0,0,1] op_sel_hi:[1,0,0]
	s_waitcnt lgkmcnt(13)
	v_pk_add_f32 v[176:177], v[144:145], v[178:179]
	v_pk_add_f32 v[144:145], v[144:145], v[178:179] neg_lo:[0,1] neg_hi:[0,1]
	s_mov_b32 s43, s26
	v_pk_mul_f32 v[178:179], v[144:145], s[24:25]
	s_mov_b32 s62, s37
	v_pk_fma_f32 v[144:145], v[144:145], s[22:23], v[178:179] op_sel:[0,0,1] op_sel_hi:[1,0,0]
	s_waitcnt lgkmcnt(12)
	v_pk_add_f32 v[178:179], v[148:149], v[180:181]
	v_pk_add_f32 v[148:149], v[148:149], v[180:181] neg_lo:[0,1] neg_hi:[0,1]
	s_mov_b32 s45, s22
	v_pk_mul_f32 v[180:181], v[148:149], s[36:37]
	s_mov_b32 s50, s25
	v_pk_fma_f32 v[148:149], v[148:149], s[26:27], v[180:181] op_sel:[0,0,1] op_sel_hi:[1,0,0]
	s_waitcnt lgkmcnt(11)
	v_pk_add_f32 v[180:181], v[150:151], v[182:183]
	v_pk_add_f32 v[150:151], v[150:151], v[182:183] neg_lo:[0,1] neg_hi:[0,1]
	v_xor_b32_e32 v7, 0x80000000, v4
	v_pk_mul_f32 v[182:183], v[150:151], s[40:41]
	v_mov_b32_e32 v5, v7
	v_pk_fma_f32 v[150:151], v[150:151], s[38:39], v[182:183] op_sel:[0,0,1] op_sel_hi:[1,0,0]
	s_waitcnt lgkmcnt(10)
	v_pk_add_f32 v[182:183], v[152:153], v[184:185]
	v_pk_add_f32 v[152:153], v[152:153], v[184:185] neg_lo:[0,1] neg_hi:[0,1]
	v_pk_mul_f32 v[8:9], v[6:7], v[4:5] op_sel:[1,0] op_sel_hi:[0,1]
	v_pk_mul_f32 v[184:185], v[152:153], s[42:43]
	v_pk_fma_f32 v[8:9], v[6:7], v[6:7], v[8:9] op_sel_hi:[1,0,1]
	v_pk_fma_f32 v[152:153], v[152:153], s[62:63], v[184:185] op_sel:[0,0,1] op_sel_hi:[1,0,0]
	s_waitcnt lgkmcnt(9)
	v_pk_add_f32 v[184:185], v[154:155], v[186:187]
	v_pk_add_f32 v[154:155], v[154:155], v[186:187] neg_lo:[0,1] neg_hi:[0,1]
	v_xor_b32_e32 v14, 0x80000000, v9
	v_pk_mul_f32 v[186:187], v[154:155], s[44:45]
	v_mov_b32_e32 v15, v9
	v_pk_fma_f32 v[154:155], v[154:155], s[50:51], v[186:187] op_sel:[0,0,1] op_sel_hi:[1,0,0]
	s_waitcnt lgkmcnt(8)
	v_pk_add_f32 v[186:187], v[156:157], v[188:189]
	v_pk_add_f32 v[156:157], v[156:157], v[188:189] neg_lo:[0,1] neg_hi:[0,1]
	v_pk_mul_f32 v[12:13], v[8:9], v[14:15] op_sel:[1,0] op_sel_hi:[0,1]
	v_pk_mul_f32 v[188:189], v[156:157], s[8:9]
	v_pk_fma_f32 v[12:13], v[8:9], v[8:9], v[12:13] op_sel_hi:[1,0,1]
	v_pk_fma_f32 v[156:157], v[156:157], s[16:17], v[188:189] op_sel:[0,0,1] op_sel_hi:[1,0,0]
	s_waitcnt lgkmcnt(7)
	v_pk_add_f32 v[188:189], v[158:159], v[190:191]
	v_pk_add_f32 v[190:191], v[158:159], v[190:191] neg_lo:[0,1] neg_hi:[0,1]
	v_xor_b32_e32 v16, 0x80000000, v13
	s_waitcnt lgkmcnt(6)
	v_pk_add_f32 v[158:159], v[160:161], v[192:193]
	v_pk_add_f32 v[160:161], v[160:161], v[192:193] neg_lo:[0,1] neg_hi:[0,1]
	v_mov_b32_e32 v17, v13
	v_pk_mul_f32 v[192:193], v[160:161], s[8:9]
	v_pk_mul_f32 v[28:29], v[12:13], v[16:17] op_sel:[1,0] op_sel_hi:[0,1]
	v_pk_fma_f32 v[160:161], v[160:161], s[16:17], v[192:193] op_sel:[0,0,1] op_sel_hi:[1,0,0] neg_lo:[1,0,0] neg_hi:[1,0,0]
	s_waitcnt lgkmcnt(5)
	v_pk_add_f32 v[192:193], v[162:163], v[194:195]
	v_pk_add_f32 v[162:163], v[162:163], v[194:195] neg_lo:[0,1] neg_hi:[0,1]
	v_pk_fma_f32 v[28:29], v[12:13], v[12:13], v[28:29] op_sel_hi:[1,0,1]
	v_pk_mul_f32 v[194:195], v[162:163], s[44:45]
	v_pk_mul_f32 v[44:45], v[16:17], v[28:29] op_sel:[0,1] op_sel_hi:[1,0]
	v_pk_fma_f32 v[162:163], v[162:163], s[50:51], v[194:195] op_sel:[0,0,1] op_sel_hi:[1,0,0] neg_lo:[1,0,0] neg_hi:[1,0,0]
	s_waitcnt lgkmcnt(4)
	v_pk_add_f32 v[194:195], v[164:165], v[196:197]
	v_pk_add_f32 v[164:165], v[164:165], v[196:197] neg_lo:[0,1] neg_hi:[0,1]
	v_pk_fma_f32 v[44:45], v[12:13], v[28:29], v[44:45] op_sel_hi:[0,1,1]
	v_pk_mul_f32 v[196:197], v[164:165], s[42:43]
	v_pk_mul_f32 v[60:61], v[16:17], v[44:45] op_sel:[0,1] op_sel_hi:[1,0]
	v_pk_fma_f32 v[164:165], v[164:165], s[62:63], v[196:197] op_sel:[0,0,1] op_sel_hi:[1,0,0] neg_lo:[1,0,0] neg_hi:[1,0,0]
	s_waitcnt lgkmcnt(3)
	v_pk_add_f32 v[196:197], v[166:167], v[198:199]
	v_pk_add_f32 v[166:167], v[166:167], v[198:199] neg_lo:[0,1] neg_hi:[0,1]
	v_pk_fma_f32 v[60:61], v[12:13], v[44:45], v[60:61] op_sel_hi:[0,1,1]
	v_pk_mul_f32 v[198:199], v[166:167], s[40:41]
	v_pk_mul_f32 v[76:77], v[16:17], v[60:61] op_sel:[0,1] op_sel_hi:[1,0]
	v_pk_fma_f32 v[166:167], v[166:167], s[38:39], v[198:199] op_sel:[0,0,1] op_sel_hi:[1,0,0] neg_lo:[1,0,0] neg_hi:[1,0,0]
	s_waitcnt lgkmcnt(2)
	v_pk_add_f32 v[198:199], v[168:169], v[204:205]
	v_pk_add_f32 v[168:169], v[168:169], v[204:205] neg_lo:[0,1] neg_hi:[0,1]
	v_pk_fma_f32 v[76:77], v[12:13], v[60:61], v[76:77] op_sel_hi:[0,1,1]
	v_pk_mul_f32 v[204:205], v[168:169], s[36:37]
	v_pk_mul_f32 v[92:93], v[16:17], v[76:77] op_sel:[0,1] op_sel_hi:[1,0]
	v_pk_fma_f32 v[168:169], v[168:169], s[26:27], v[204:205] op_sel:[0,0,1] op_sel_hi:[1,0,0] neg_lo:[1,0,0] neg_hi:[1,0,0]
	s_waitcnt lgkmcnt(1)
	v_pk_add_f32 v[204:205], v[170:171], v[206:207]
	v_pk_add_f32 v[170:171], v[170:171], v[206:207] neg_lo:[0,1] neg_hi:[0,1]
	v_pk_fma_f32 v[92:93], v[12:13], v[76:77], v[92:93] op_sel_hi:[0,1,1]
	v_pk_mul_f32 v[206:207], v[170:171], s[24:25]
	v_pk_mul_f32 v[108:109], v[16:17], v[92:93] op_sel:[0,1] op_sel_hi:[1,0]
	v_pk_fma_f32 v[170:171], v[170:171], s[22:23], v[206:207] op_sel:[0,0,1] op_sel_hi:[1,0,0] neg_lo:[1,0,0] neg_hi:[1,0,0]
	s_waitcnt lgkmcnt(0)
	v_pk_add_f32 v[206:207], v[172:173], v[208:209]
	v_pk_add_f32 v[172:173], v[172:173], v[208:209] neg_lo:[0,1] neg_hi:[0,1]
	v_pk_mul_f32 v[10:11], v[4:5], v[8:9] op_sel:[0,1] op_sel_hi:[1,0]
	v_pk_mul_f32 v[208:209], v[172:173], s[18:19]
	v_pk_fma_f32 v[108:109], v[12:13], v[92:93], v[108:109] op_sel_hi:[0,1,1]
	v_pk_fma_f32 v[172:173], v[172:173], s[0:1], v[208:209] op_sel:[0,0,1] op_sel_hi:[1,0,0] neg_lo:[1,0,0] neg_hi:[1,0,0]
	v_pk_add_f32 v[208:209], v[210:211], v[188:189]
	v_pk_add_f32 v[188:189], v[210:211], v[188:189] neg_lo:[0,1] neg_hi:[0,1]
	v_pk_add_f32 v[210:211], v[174:175], v[158:159]
	v_pk_add_f32 v[158:159], v[174:175], v[158:159] neg_lo:[0,1] neg_hi:[0,1]
	v_pk_fma_f32 v[10:11], v[6:7], v[8:9], v[10:11] op_sel_hi:[0,1,1]
	v_pk_mul_f32 v[174:175], v[158:159], s[24:25]
	v_pk_mul_f32 v[18:19], v[4:5], v[12:13] op_sel:[0,1] op_sel_hi:[1,0]
	v_pk_fma_f32 v[158:159], v[158:159], s[22:23], v[174:175] op_sel:[0,0,1] op_sel_hi:[1,0,0]
	v_pk_add_f32 v[174:175], v[176:177], v[192:193]
	v_pk_add_f32 v[176:177], v[176:177], v[192:193] neg_lo:[0,1] neg_hi:[0,1]
	v_pk_mul_f32 v[32:33], v[4:5], v[28:29] op_sel:[0,1] op_sel_hi:[1,0]
	v_pk_mul_f32 v[192:193], v[176:177], s[40:41]
	v_pk_mul_f32 v[48:49], v[4:5], v[44:45] op_sel:[0,1] op_sel_hi:[1,0]
	v_pk_fma_f32 v[176:177], v[176:177], s[38:39], v[192:193] op_sel:[0,0,1] op_sel_hi:[1,0,0]
	v_pk_add_f32 v[192:193], v[178:179], v[194:195]
	v_pk_add_f32 v[178:179], v[178:179], v[194:195] neg_lo:[0,1] neg_hi:[0,1]
	v_pk_mul_f32 v[64:65], v[4:5], v[60:61] op_sel:[0,1] op_sel_hi:[1,0]
	v_pk_mul_f32 v[194:195], v[178:179], s[44:45]
	v_pk_mul_f32 v[80:81], v[4:5], v[76:77] op_sel:[0,1] op_sel_hi:[1,0]
	v_pk_fma_f32 v[178:179], v[178:179], s[50:51], v[194:195] op_sel:[0,0,1] op_sel_hi:[1,0,0]
	v_pk_add_f32 v[194:195], v[180:181], v[196:197]
	v_pk_add_f32 v[196:197], v[180:181], v[196:197] neg_lo:[0,1] neg_hi:[0,1]
	v_pk_mul_f32 v[96:97], v[4:5], v[92:93] op_sel:[0,1] op_sel_hi:[1,0]
	v_pk_add_f32 v[180:181], v[182:183], v[198:199]
	v_pk_add_f32 v[182:183], v[182:183], v[198:199] neg_lo:[0,1] neg_hi:[0,1]
	v_pk_mul_f32 v[112:113], v[4:5], v[108:109] op_sel:[0,1] op_sel_hi:[1,0]
	v_pk_mul_f32 v[198:199], v[182:183], s[44:45]
	v_xor_b32_e32 v22, 0x80000000, v11
	v_pk_fma_f32 v[182:183], v[182:183], s[50:51], v[198:199] op_sel:[0,0,1] op_sel_hi:[1,0,0] neg_lo:[1,0,0] neg_hi:[1,0,0]
	v_pk_add_f32 v[198:199], v[184:185], v[204:205]
	v_pk_add_f32 v[184:185], v[184:185], v[204:205] neg_lo:[0,1] neg_hi:[0,1]
	v_mov_b32_e32 v23, v11
	v_pk_mul_f32 v[204:205], v[184:185], s[40:41]
	v_pk_fma_f32 v[18:19], v[6:7], v[12:13], v[18:19] op_sel_hi:[0,1,1]
	v_pk_fma_f32 v[184:185], v[184:185], s[38:39], v[204:205] op_sel:[0,0,1] op_sel_hi:[1,0,0] neg_lo:[1,0,0] neg_hi:[1,0,0]
	v_pk_add_f32 v[204:205], v[186:187], v[206:207]
	v_pk_add_f32 v[186:187], v[186:187], v[206:207] neg_lo:[0,1] neg_hi:[0,1]
	v_pk_mul_f32 v[20:21], v[14:15], v[12:13] op_sel:[0,1] op_sel_hi:[1,0]
	v_pk_mul_f32 v[206:207], v[186:187], s[24:25]
	v_pk_fma_f32 v[32:33], v[6:7], v[28:29], v[32:33] op_sel_hi:[0,1,1]
	v_pk_fma_f32 v[186:187], v[186:187], s[22:23], v[206:207] op_sel:[0,0,1] op_sel_hi:[1,0,0] neg_lo:[1,0,0] neg_hi:[1,0,0]
	v_pk_add_f32 v[206:207], v[128:129], v[190:191] op_sel:[0,1] op_sel_hi:[1,0] neg_hi:[0,1]
	v_pk_add_f32 v[128:129], v[128:129], v[190:191] op_sel:[0,1] op_sel_hi:[1,0] neg_lo:[0,1]
	v_pk_add_f32 v[190:191], v[130:131], v[160:161]
	v_pk_add_f32 v[130:131], v[130:131], v[160:161] neg_lo:[0,1] neg_hi:[0,1]
	v_pk_mul_f32 v[36:37], v[14:15], v[28:29] op_sel:[0,1] op_sel_hi:[1,0]
	v_pk_mul_f32 v[160:161], v[130:131], s[24:25]
	v_pk_fma_f32 v[48:49], v[6:7], v[44:45], v[48:49] op_sel_hi:[0,1,1]
	v_pk_fma_f32 v[130:131], v[130:131], s[22:23], v[160:161] op_sel:[0,0,1] op_sel_hi:[1,0,0]
	v_pk_add_f32 v[160:161], v[144:145], v[162:163]
	v_pk_add_f32 v[144:145], v[144:145], v[162:163] neg_lo:[0,1] neg_hi:[0,1]
	v_pk_mul_f32 v[52:53], v[14:15], v[44:45] op_sel:[0,1] op_sel_hi:[1,0]
	v_pk_mul_f32 v[162:163], v[144:145], s[40:41]
	v_pk_fma_f32 v[64:65], v[6:7], v[60:61], v[64:65] op_sel_hi:[0,1,1]
	v_pk_fma_f32 v[144:145], v[144:145], s[38:39], v[162:163] op_sel:[0,0,1] op_sel_hi:[1,0,0]
	v_pk_add_f32 v[162:163], v[148:149], v[164:165]
	v_pk_add_f32 v[148:149], v[148:149], v[164:165] neg_lo:[0,1] neg_hi:[0,1]
	v_pk_mul_f32 v[68:69], v[14:15], v[60:61] op_sel:[0,1] op_sel_hi:[1,0]
	v_pk_mul_f32 v[164:165], v[148:149], s[44:45]
	v_pk_fma_f32 v[80:81], v[6:7], v[76:77], v[80:81] op_sel_hi:[0,1,1]
	v_pk_fma_f32 v[148:149], v[148:149], s[50:51], v[164:165] op_sel:[0,0,1] op_sel_hi:[1,0,0]
	v_pk_add_f32 v[164:165], v[150:151], v[166:167]
	v_pk_add_f32 v[166:167], v[150:151], v[166:167] neg_lo:[0,1] neg_hi:[0,1]
	v_pk_mul_f32 v[84:85], v[14:15], v[76:77] op_sel:[0,1] op_sel_hi:[1,0]
	v_pk_add_f32 v[150:151], v[152:153], v[168:169]
	v_pk_add_f32 v[152:153], v[152:153], v[168:169] neg_lo:[0,1] neg_hi:[0,1]
	v_pk_fma_f32 v[96:97], v[6:7], v[92:93], v[96:97] op_sel_hi:[0,1,1]
	v_pk_mul_f32 v[168:169], v[152:153], s[44:45]
	v_pk_mul_f32 v[100:101], v[14:15], v[92:93] op_sel:[0,1] op_sel_hi:[1,0]
	v_pk_fma_f32 v[152:153], v[152:153], s[50:51], v[168:169] op_sel:[0,0,1] op_sel_hi:[1,0,0] neg_lo:[1,0,0] neg_hi:[1,0,0]
	v_pk_add_f32 v[168:169], v[154:155], v[170:171]
	v_pk_add_f32 v[154:155], v[154:155], v[170:171] neg_lo:[0,1] neg_hi:[0,1]
	v_pk_fma_f32 v[112:113], v[6:7], v[108:109], v[112:113] op_sel_hi:[0,1,1]
	v_pk_mul_f32 v[170:171], v[154:155], s[40:41]
	v_pk_mul_f32 v[116:117], v[14:15], v[108:109] op_sel:[0,1] op_sel_hi:[1,0]
	v_pk_fma_f32 v[154:155], v[154:155], s[38:39], v[170:171] op_sel:[0,0,1] op_sel_hi:[1,0,0] neg_lo:[1,0,0] neg_hi:[1,0,0]
	v_pk_add_f32 v[170:171], v[156:157], v[172:173]
	v_pk_add_f32 v[156:157], v[156:157], v[172:173] neg_lo:[0,1] neg_hi:[0,1]
	v_pk_fma_f32 v[20:21], v[8:9], v[12:13], v[20:21] op_sel_hi:[0,1,1]
	v_pk_mul_f32 v[172:173], v[156:157], s[24:25]
	v_pk_mul_f32 v[24:25], v[12:13], v[22:23] op_sel:[1,0] op_sel_hi:[0,1]
	v_pk_fma_f32 v[156:157], v[156:157], s[22:23], v[172:173] op_sel:[0,0,1] op_sel_hi:[1,0,0] neg_lo:[1,0,0] neg_hi:[1,0,0]
	v_pk_add_f32 v[172:173], v[208:209], v[194:195]
	v_pk_add_f32 v[194:195], v[208:209], v[194:195] neg_lo:[0,1] neg_hi:[0,1]
	v_pk_add_f32 v[208:209], v[210:211], v[180:181]
	v_pk_add_f32 v[180:181], v[210:211], v[180:181] neg_lo:[0,1] neg_hi:[0,1]
	v_pk_fma_f32 v[36:37], v[8:9], v[28:29], v[36:37] op_sel_hi:[0,1,1]
	v_pk_mul_f32 v[210:211], v[180:181], s[40:41]
	v_pk_mul_f32 v[40:41], v[22:23], v[28:29] op_sel:[0,1] op_sel_hi:[1,0]
	v_pk_fma_f32 v[180:181], v[180:181], s[38:39], v[210:211] op_sel:[0,0,1] op_sel_hi:[1,0,0]
	v_pk_add_f32 v[210:211], v[174:175], v[198:199]
	v_pk_add_f32 v[198:199], v[174:175], v[198:199] neg_lo:[0,1] neg_hi:[0,1]
	v_pk_fma_f32 v[52:53], v[8:9], v[44:45], v[52:53] op_sel_hi:[0,1,1]
	v_pk_add_f32 v[174:175], v[192:193], v[204:205]
	v_pk_add_f32 v[192:193], v[192:193], v[204:205] neg_lo:[0,1] neg_hi:[0,1]
	v_pk_mul_f32 v[56:57], v[22:23], v[44:45] op_sel:[0,1] op_sel_hi:[1,0]
	v_pk_mul_f32 v[204:205], v[192:193], s[40:41]
	v_pk_fma_f32 v[68:69], v[8:9], v[60:61], v[68:69] op_sel_hi:[0,1,1]
	v_pk_fma_f32 v[192:193], v[192:193], s[38:39], v[204:205] op_sel:[0,0,1] op_sel_hi:[1,0,0] neg_lo:[1,0,0] neg_hi:[1,0,0]
	v_pk_add_f32 v[204:205], v[188:189], v[196:197] op_sel:[0,1] op_sel_hi:[1,0] neg_hi:[0,1]
	v_pk_add_f32 v[188:189], v[188:189], v[196:197] op_sel:[0,1] op_sel_hi:[1,0] neg_lo:[0,1]
	v_pk_add_f32 v[196:197], v[158:159], v[182:183]
	v_pk_add_f32 v[158:159], v[158:159], v[182:183] neg_lo:[0,1] neg_hi:[0,1]
	v_pk_mul_f32 v[72:73], v[22:23], v[60:61] op_sel:[0,1] op_sel_hi:[1,0]
	v_pk_mul_f32 v[182:183], v[158:159], s[40:41]
	v_pk_fma_f32 v[84:85], v[8:9], v[76:77], v[84:85] op_sel_hi:[0,1,1]
	v_pk_fma_f32 v[158:159], v[158:159], s[38:39], v[182:183] op_sel:[0,0,1] op_sel_hi:[1,0,0]
	v_pk_add_f32 v[182:183], v[176:177], v[184:185]
	v_pk_add_f32 v[184:185], v[176:177], v[184:185] neg_lo:[0,1] neg_hi:[0,1]
	v_pk_mul_f32 v[88:89], v[22:23], v[76:77] op_sel:[0,1] op_sel_hi:[1,0]
	v_pk_add_f32 v[176:177], v[178:179], v[186:187]
	v_pk_add_f32 v[178:179], v[178:179], v[186:187] neg_lo:[0,1] neg_hi:[0,1]
	v_pk_fma_f32 v[100:101], v[8:9], v[92:93], v[100:101] op_sel_hi:[0,1,1]
	v_pk_mul_f32 v[186:187], v[178:179], s[40:41]
	v_pk_mul_f32 v[104:105], v[22:23], v[92:93] op_sel:[0,1] op_sel_hi:[1,0]
	v_pk_fma_f32 v[178:179], v[178:179], s[38:39], v[186:187] op_sel:[0,0,1] op_sel_hi:[1,0,0] neg_lo:[1,0,0] neg_hi:[1,0,0]
	v_pk_add_f32 v[186:187], v[206:207], v[164:165]
	v_pk_add_f32 v[164:165], v[206:207], v[164:165] neg_lo:[0,1] neg_hi:[0,1]
	v_pk_add_f32 v[206:207], v[190:191], v[150:151]
	v_pk_add_f32 v[150:151], v[190:191], v[150:151] neg_lo:[0,1] neg_hi:[0,1]
	v_pk_fma_f32 v[116:117], v[8:9], v[108:109], v[116:117] op_sel_hi:[0,1,1]
	v_pk_mul_f32 v[190:191], v[150:151], s[40:41]
	v_pk_mul_f32 v[120:121], v[22:23], v[108:109] op_sel:[0,1] op_sel_hi:[1,0]
	v_pk_fma_f32 v[150:151], v[150:151], s[38:39], v[190:191] op_sel:[0,0,1] op_sel_hi:[1,0,0]
	v_pk_add_f32 v[190:191], v[160:161], v[168:169]
	v_pk_add_f32 v[168:169], v[160:161], v[168:169] neg_lo:[0,1] neg_hi:[0,1]
	v_xor_b32_e32 v26, 0x80000000, v19
	v_pk_add_f32 v[160:161], v[162:163], v[170:171]
	v_pk_add_f32 v[162:163], v[162:163], v[170:171] neg_lo:[0,1] neg_hi:[0,1]
	v_xor_b32_e32 v30, 0x80000000, v21
	v_pk_mul_f32 v[170:171], v[162:163], s[40:41]
	v_pk_fma_f32 v[24:25], v[12:13], v[10:11], v[24:25] op_sel_hi:[1,0,1]
	v_pk_fma_f32 v[162:163], v[162:163], s[38:39], v[170:171] op_sel:[0,0,1] op_sel_hi:[1,0,0] neg_lo:[1,0,0] neg_hi:[1,0,0]
	v_pk_add_f32 v[170:171], v[128:129], v[166:167] op_sel:[0,1] op_sel_hi:[1,0] neg_hi:[0,1]
	v_pk_add_f32 v[128:129], v[128:129], v[166:167] op_sel:[0,1] op_sel_hi:[1,0] neg_lo:[0,1]
	v_pk_add_f32 v[166:167], v[130:131], v[152:153]
	v_pk_add_f32 v[130:131], v[130:131], v[152:153] neg_lo:[0,1] neg_hi:[0,1]
	v_pk_fma_f32 v[40:41], v[10:11], v[28:29], v[40:41] op_sel_hi:[0,1,1]
	v_pk_mul_f32 v[152:153], v[130:131], s[40:41]
	v_pk_fma_f32 v[56:57], v[10:11], v[44:45], v[56:57] op_sel_hi:[0,1,1]
	v_pk_fma_f32 v[130:131], v[130:131], s[38:39], v[152:153] op_sel:[0,0,1] op_sel_hi:[1,0,0]
	v_pk_add_f32 v[152:153], v[144:145], v[154:155]
	v_pk_add_f32 v[154:155], v[144:145], v[154:155] neg_lo:[0,1] neg_hi:[0,1]
	v_pk_fma_f32 v[72:73], v[10:11], v[60:61], v[72:73] op_sel_hi:[0,1,1]
	v_pk_add_f32 v[144:145], v[148:149], v[156:157]
	v_pk_add_f32 v[148:149], v[148:149], v[156:157] neg_lo:[0,1] neg_hi:[0,1]
	v_pk_fma_f32 v[88:89], v[10:11], v[76:77], v[88:89] op_sel_hi:[0,1,1]
	v_pk_mul_f32 v[156:157], v[148:149], s[40:41]
	v_pk_fma_f32 v[104:105], v[10:11], v[92:93], v[104:105] op_sel_hi:[0,1,1]
	v_pk_fma_f32 v[148:149], v[148:149], s[38:39], v[156:157] op_sel:[0,0,1] op_sel_hi:[1,0,0] neg_lo:[1,0,0] neg_hi:[1,0,0]
	v_pk_add_f32 v[156:157], v[172:173], v[210:211]
	v_pk_add_f32 v[172:173], v[172:173], v[210:211] neg_lo:[0,1] neg_hi:[0,1]
	v_pk_add_f32 v[210:211], v[208:209], v[174:175]
	v_pk_add_f32 v[208:209], v[208:209], v[174:175] neg_lo:[0,1] neg_hi:[0,1]
	v_pk_fma_f32 v[120:121], v[10:11], v[108:109], v[120:121] op_sel_hi:[0,1,1]
	v_pk_add_f32 v[174:175], v[194:195], v[198:199] op_sel:[0,1] op_sel_hi:[1,0] neg_hi:[0,1]
	v_pk_add_f32 v[194:195], v[194:195], v[198:199] op_sel:[0,1] op_sel_hi:[1,0] neg_lo:[0,1]
	v_pk_add_f32 v[198:199], v[180:181], v[192:193]
	v_pk_add_f32 v[192:193], v[180:181], v[192:193] neg_lo:[0,1] neg_hi:[0,1]
	v_mov_b32_e32 v27, v19
	v_pk_add_f32 v[180:181], v[204:205], v[182:183]
	v_pk_add_f32 v[182:183], v[204:205], v[182:183] neg_lo:[0,1] neg_hi:[0,1]
	v_pk_add_f32 v[204:205], v[196:197], v[176:177]
	v_pk_add_f32 v[196:197], v[196:197], v[176:177] neg_lo:[0,1] neg_hi:[0,1]
	v_mov_b32_e32 v31, v21
	v_pk_add_f32 v[176:177], v[188:189], v[184:185] op_sel:[0,1] op_sel_hi:[1,0] neg_hi:[0,1]
	v_pk_add_f32 v[184:185], v[188:189], v[184:185] op_sel:[0,1] op_sel_hi:[1,0] neg_lo:[0,1]
	v_pk_add_f32 v[188:189], v[158:159], v[178:179]
	v_pk_add_f32 v[178:179], v[158:159], v[178:179] neg_lo:[0,1] neg_hi:[0,1]
	v_xor_b32_e32 v34, 0x80000000, v25
	v_pk_add_f32 v[158:159], v[186:187], v[190:191]
	v_pk_add_f32 v[186:187], v[186:187], v[190:191] neg_lo:[0,1] neg_hi:[0,1]
	v_pk_add_f32 v[190:191], v[206:207], v[160:161]
	v_pk_add_f32 v[206:207], v[206:207], v[160:161] neg_lo:[0,1] neg_hi:[0,1]
	v_xor_b32_e32 v38, 0x80000000, v29
	v_pk_add_f32 v[160:161], v[164:165], v[168:169] op_sel:[0,1] op_sel_hi:[1,0] neg_hi:[0,1]
	v_pk_add_f32 v[164:165], v[164:165], v[168:169] op_sel:[0,1] op_sel_hi:[1,0] neg_lo:[0,1]
	v_pk_add_f32 v[168:169], v[150:151], v[162:163]
	v_pk_add_f32 v[162:163], v[150:151], v[162:163] neg_lo:[0,1] neg_hi:[0,1]
	v_xor_b32_e32 v42, 0x80000000, v33
	v_pk_add_f32 v[150:151], v[170:171], v[152:153]
	v_pk_add_f32 v[152:153], v[170:171], v[152:153] neg_lo:[0,1] neg_hi:[0,1]
	v_pk_add_f32 v[170:171], v[166:167], v[144:145]
	v_pk_add_f32 v[166:167], v[166:167], v[144:145] neg_lo:[0,1] neg_hi:[0,1]
	v_xor_b32_e32 v46, 0x80000000, v37
	v_pk_add_f32 v[144:145], v[128:129], v[154:155] op_sel:[0,1] op_sel_hi:[1,0] neg_hi:[0,1]
	v_pk_add_f32 v[128:129], v[128:129], v[154:155] op_sel:[0,1] op_sel_hi:[1,0] neg_lo:[0,1]
	v_pk_add_f32 v[154:155], v[130:131], v[148:149]
	v_pk_add_f32 v[130:131], v[130:131], v[148:149] neg_lo:[0,1] neg_hi:[0,1]
	v_mov_b32_e32 v35, v25
	v_xor_b32_e32 v149, 0x80000000, v130
	v_mov_b32_e32 v148, v131
	v_pk_add_f32 v[130:131], v[156:157], v[210:211]
	v_pk_add_f32 v[156:157], v[156:157], v[210:211] neg_lo:[0,1] neg_hi:[0,1]
	v_pk_add_f32 v[210:211], v[172:173], v[208:209] op_sel:[0,1] op_sel_hi:[1,0] neg_hi:[0,1]
	v_pk_add_f32 v[172:173], v[172:173], v[208:209] op_sel:[0,1] op_sel_hi:[1,0] neg_lo:[0,1]
	v_pk_add_f32 v[208:209], v[174:175], v[198:199]
	v_pk_add_f32 v[174:175], v[174:175], v[198:199] neg_lo:[0,1] neg_hi:[0,1]
	v_pk_add_f32 v[198:199], v[194:195], v[192:193] op_sel:[0,1] op_sel_hi:[1,0] neg_hi:[0,1]
	v_pk_add_f32 v[192:193], v[194:195], v[192:193] op_sel:[0,1] op_sel_hi:[1,0] neg_lo:[0,1]
	v_pk_add_f32 v[194:195], v[180:181], v[204:205]
	v_pk_add_f32 v[180:181], v[180:181], v[204:205] neg_lo:[0,1] neg_hi:[0,1]
	v_pk_add_f32 v[204:205], v[182:183], v[196:197] op_sel:[0,1] op_sel_hi:[1,0] neg_hi:[0,1]
	v_pk_add_f32 v[182:183], v[182:183], v[196:197] op_sel:[0,1] op_sel_hi:[1,0] neg_lo:[0,1]
	v_pk_add_f32 v[196:197], v[176:177], v[188:189]
	v_pk_add_f32 v[176:177], v[176:177], v[188:189] neg_lo:[0,1] neg_hi:[0,1]
	v_pk_add_f32 v[188:189], v[184:185], v[178:179] op_sel:[0,1] op_sel_hi:[1,0] neg_hi:[0,1]
	v_pk_add_f32 v[178:179], v[184:185], v[178:179] op_sel:[0,1] op_sel_hi:[1,0] neg_lo:[0,1]
	v_pk_add_f32 v[184:185], v[158:159], v[190:191]
	v_pk_add_f32 v[158:159], v[158:159], v[190:191] neg_lo:[0,1] neg_hi:[0,1]
	v_pk_mul_f32 v[4:5], v[4:5], v[184:185] op_sel:[0,1] op_sel_hi:[1,0]
	v_pk_add_f32 v[190:191], v[186:187], v[206:207] op_sel:[0,1] op_sel_hi:[1,0] neg_hi:[0,1]
	v_pk_add_f32 v[186:187], v[186:187], v[206:207] op_sel:[0,1] op_sel_hi:[1,0] neg_lo:[0,1]
	v_pk_add_f32 v[206:207], v[160:161], v[168:169]
	v_pk_add_f32 v[160:161], v[160:161], v[168:169] neg_lo:[0,1] neg_hi:[0,1]
	v_pk_add_f32 v[168:169], v[164:165], v[162:163] op_sel:[0,1] op_sel_hi:[1,0] neg_hi:[0,1]
	v_pk_add_f32 v[162:163], v[164:165], v[162:163] op_sel:[0,1] op_sel_hi:[1,0] neg_lo:[0,1]
	v_pk_add_f32 v[164:165], v[150:151], v[170:171]
	v_pk_fma_f32 v[4:5], v[6:7], v[184:185], v[4:5] op_sel_hi:[0,1,1]
	v_pk_mul_f32 v[6:7], v[14:15], v[194:195] op_sel:[0,1] op_sel_hi:[1,0]
	v_mov_b32_e32 v39, v29
	v_pk_fma_f32 v[6:7], v[8:9], v[194:195], v[6:7] op_sel_hi:[0,1,1]
	v_pk_mul_f32 v[8:9], v[22:23], v[164:165] op_sel:[0,1] op_sel_hi:[1,0]
	v_mov_b32_e32 v43, v33
	v_pk_fma_f32 v[8:9], v[10:11], v[164:165], v[8:9] op_sel_hi:[0,1,1]
	v_pk_mul_f32 v[10:11], v[16:17], v[208:209] op_sel:[0,1] op_sel_hi:[1,0]
	v_mov_b32_e32 v47, v37
	v_pk_add_f32 v[150:151], v[150:151], v[170:171] neg_lo:[0,1] neg_hi:[0,1]
	v_pk_add_f32 v[170:171], v[152:153], v[166:167] op_sel:[0,1] op_sel_hi:[1,0] neg_hi:[0,1]
	v_pk_add_f32 v[152:153], v[152:153], v[166:167] op_sel:[0,1] op_sel_hi:[1,0] neg_lo:[0,1]
	v_pk_add_f32 v[166:167], v[144:145], v[154:155]
	v_pk_fma_f32 v[10:11], v[12:13], v[208:209], v[10:11] op_sel_hi:[0,1,1]
	v_pk_mul_f32 v[12:13], v[26:27], v[206:207] op_sel:[0,1] op_sel_hi:[1,0]
	v_pk_mul_f32 v[14:15], v[30:31], v[196:197] op_sel:[0,1] op_sel_hi:[1,0]
	v_xor_b32_e32 v50, 0x80000000, v41
	v_xor_b32_e32 v54, 0x80000000, v45
	v_xor_b32_e32 v58, 0x80000000, v49
	v_xor_b32_e32 v62, 0x80000000, v53
	v_xor_b32_e32 v66, 0x80000000, v57
	v_xor_b32_e32 v70, 0x80000000, v61
	v_xor_b32_e32 v74, 0x80000000, v65
	v_mov_b32_e32 v51, v41
	v_mov_b32_e32 v55, v45
	v_mov_b32_e32 v59, v49
	v_mov_b32_e32 v63, v53
	v_mov_b32_e32 v67, v57
	v_mov_b32_e32 v71, v61
	v_mov_b32_e32 v75, v65
	v_pk_add_f32 v[144:145], v[144:145], v[154:155] neg_lo:[0,1] neg_hi:[0,1]
	v_pk_add_f32 v[154:155], v[128:129], v[148:149]
	v_pk_fma_f32 v[12:13], v[18:19], v[206:207], v[12:13] op_sel_hi:[0,1,1]
	v_pk_fma_f32 v[14:15], v[20:21], v[196:197], v[14:15] op_sel_hi:[0,1,1]
	v_pk_mul_f32 v[16:17], v[34:35], v[166:167] op_sel:[0,1] op_sel_hi:[1,0]
	v_pk_mul_f32 v[18:19], v[38:39], v[210:211] op_sel:[0,1] op_sel_hi:[1,0]
	v_pk_mul_f32 v[20:21], v[42:43], v[190:191] op_sel:[0,1] op_sel_hi:[1,0]
	v_pk_mul_f32 v[22:23], v[46:47], v[204:205] op_sel:[0,1] op_sel_hi:[1,0]
	v_xor_b32_e32 v78, 0x80000000, v69
	v_xor_b32_e32 v82, 0x80000000, v73
	v_xor_b32_e32 v86, 0x80000000, v77
	v_xor_b32_e32 v90, 0x80000000, v81
	v_xor_b32_e32 v94, 0x80000000, v85
	v_xor_b32_e32 v98, 0x80000000, v89
	v_xor_b32_e32 v102, 0x80000000, v93
	v_xor_b32_e32 v106, 0x80000000, v97
	v_xor_b32_e32 v110, 0x80000000, v101
	v_xor_b32_e32 v114, 0x80000000, v105
	v_xor_b32_e32 v118, 0x80000000, v109
	v_xor_b32_e32 v122, 0x80000000, v113
	v_xor_b32_e32 v124, 0x80000000, v117
	v_xor_b32_e32 v126, 0x80000000, v121
	v_mov_b32_e32 v79, v69
	v_mov_b32_e32 v83, v73
	v_mov_b32_e32 v87, v77
	v_mov_b32_e32 v91, v81
	v_mov_b32_e32 v95, v85
	v_mov_b32_e32 v99, v89
	v_mov_b32_e32 v103, v93
	v_mov_b32_e32 v107, v97
	v_mov_b32_e32 v111, v101
	v_mov_b32_e32 v115, v105
	v_mov_b32_e32 v119, v109
	v_mov_b32_e32 v123, v113
	v_mov_b32_e32 v125, v117
	v_mov_b32_e32 v127, v121
	v_pk_add_f32 v[128:129], v[128:129], v[148:149] neg_lo:[0,1] neg_hi:[0,1]
	v_pk_fma_f32 v[16:17], v[24:25], v[166:167], v[16:17] op_sel_hi:[0,1,1]
	v_pk_fma_f32 v[18:19], v[28:29], v[210:211], v[18:19] op_sel_hi:[0,1,1]
	v_pk_fma_f32 v[20:21], v[32:33], v[190:191], v[20:21] op_sel_hi:[0,1,1]
	v_pk_fma_f32 v[22:23], v[36:37], v[204:205], v[22:23] op_sel_hi:[0,1,1]
	v_pk_mul_f32 v[24:25], v[50:51], v[170:171] op_sel:[0,1] op_sel_hi:[1,0]
	v_pk_mul_f32 v[26:27], v[54:55], v[198:199] op_sel:[0,1] op_sel_hi:[1,0]
	v_pk_mul_f32 v[28:29], v[58:59], v[168:169] op_sel:[0,1] op_sel_hi:[1,0]
	v_pk_mul_f32 v[30:31], v[62:63], v[188:189] op_sel:[0,1] op_sel_hi:[1,0]
	v_pk_mul_f32 v[32:33], v[66:67], v[154:155] op_sel:[0,1] op_sel_hi:[1,0]
	v_pk_mul_f32 v[34:35], v[70:71], v[156:157] op_sel:[0,1] op_sel_hi:[1,0]
	v_pk_mul_f32 v[36:37], v[74:75], v[158:159] op_sel:[0,1] op_sel_hi:[1,0]
	v_pk_fma_f32 v[24:25], v[40:41], v[170:171], v[24:25] op_sel_hi:[0,1,1]
	v_pk_fma_f32 v[26:27], v[44:45], v[198:199], v[26:27] op_sel_hi:[0,1,1]
	v_pk_fma_f32 v[28:29], v[48:49], v[168:169], v[28:29] op_sel_hi:[0,1,1]
	v_pk_fma_f32 v[30:31], v[52:53], v[188:189], v[30:31] op_sel_hi:[0,1,1]
	v_pk_fma_f32 v[32:33], v[56:57], v[154:155], v[32:33] op_sel_hi:[0,1,1]
	v_pk_fma_f32 v[34:35], v[60:61], v[156:157], v[34:35] op_sel_hi:[0,1,1]
	v_pk_fma_f32 v[36:37], v[64:65], v[158:159], v[36:37] op_sel_hi:[0,1,1]
	v_pk_mul_f32 v[38:39], v[78:79], v[180:181] op_sel:[0,1] op_sel_hi:[1,0]
	v_pk_mul_f32 v[40:41], v[82:83], v[150:151] op_sel:[0,1] op_sel_hi:[1,0]
	v_pk_mul_f32 v[42:43], v[86:87], v[174:175] op_sel:[0,1] op_sel_hi:[1,0]
	v_pk_mul_f32 v[44:45], v[90:91], v[160:161] op_sel:[0,1] op_sel_hi:[1,0]
	v_pk_mul_f32 v[46:47], v[94:95], v[176:177] op_sel:[0,1] op_sel_hi:[1,0]
	v_pk_mul_f32 v[48:49], v[98:99], v[144:145] op_sel:[0,1] op_sel_hi:[1,0]
	v_pk_mul_f32 v[50:51], v[102:103], v[172:173] op_sel:[0,1] op_sel_hi:[1,0]
	v_pk_mul_f32 v[52:53], v[106:107], v[186:187] op_sel:[0,1] op_sel_hi:[1,0]
	v_pk_mul_f32 v[54:55], v[110:111], v[182:183] op_sel:[0,1] op_sel_hi:[1,0]
	v_pk_mul_f32 v[56:57], v[114:115], v[152:153] op_sel:[0,1] op_sel_hi:[1,0]
	v_pk_mul_f32 v[58:59], v[118:119], v[192:193] op_sel:[0,1] op_sel_hi:[1,0]
	v_pk_mul_f32 v[60:61], v[122:123], v[162:163] op_sel:[0,1] op_sel_hi:[1,0]
	v_pk_mul_f32 v[62:63], v[124:125], v[178:179] op_sel:[0,1] op_sel_hi:[1,0]
	v_pk_mul_f32 v[64:65], v[126:127], v[128:129] op_sel:[0,1] op_sel_hi:[1,0]
	v_pk_fma_f32 v[38:39], v[68:69], v[180:181], v[38:39] op_sel_hi:[0,1,1]
	v_pk_fma_f32 v[40:41], v[72:73], v[150:151], v[40:41] op_sel_hi:[0,1,1]
	v_pk_fma_f32 v[42:43], v[76:77], v[174:175], v[42:43] op_sel_hi:[0,1,1]
	v_pk_fma_f32 v[44:45], v[80:81], v[160:161], v[44:45] op_sel_hi:[0,1,1]
	v_pk_fma_f32 v[46:47], v[84:85], v[176:177], v[46:47] op_sel_hi:[0,1,1]
	v_pk_fma_f32 v[48:49], v[88:89], v[144:145], v[48:49] op_sel_hi:[0,1,1]
	v_pk_fma_f32 v[50:51], v[92:93], v[172:173], v[50:51] op_sel_hi:[0,1,1]
	v_pk_fma_f32 v[52:53], v[96:97], v[186:187], v[52:53] op_sel_hi:[0,1,1]
	v_pk_fma_f32 v[54:55], v[100:101], v[182:183], v[54:55] op_sel_hi:[0,1,1]
	v_pk_fma_f32 v[56:57], v[104:105], v[152:153], v[56:57] op_sel_hi:[0,1,1]
	v_pk_fma_f32 v[58:59], v[108:109], v[192:193], v[58:59] op_sel_hi:[0,1,1]
	v_pk_fma_f32 v[60:61], v[112:113], v[162:163], v[60:61] op_sel_hi:[0,1,1]
	v_pk_fma_f32 v[62:63], v[116:117], v[178:179], v[62:63] op_sel_hi:[0,1,1]
	v_pk_fma_f32 v[64:65], v[120:121], v[128:129], v[64:65] op_sel_hi:[0,1,1]
	ds_write_b64 v2, v[130:131]
	ds_write_b64 v2, v[34:35] offset:2112
	ds_write_b64 v2, v[18:19] offset:4224
	ds_write_b64 v2, v[50:51] offset:6336
	ds_write_b64 v2, v[10:11] offset:8448
	ds_write_b64 v2, v[42:43] offset:10560
	ds_write_b64 v2, v[26:27] offset:12672
	ds_write_b64 v2, v[58:59] offset:14784
	ds_write_b64 v2, v[6:7] offset:16896
	ds_write_b64 v2, v[38:39] offset:19008
	ds_write_b64 v2, v[22:23] offset:21120
	ds_write_b64 v2, v[54:55] offset:23232
	ds_write_b64 v2, v[14:15] offset:25344
	ds_write_b64 v2, v[46:47] offset:27456
	ds_write_b64 v2, v[30:31] offset:29568
	ds_write_b64 v2, v[62:63] offset:31680
	ds_write_b64 v2, v[4:5] offset:33792
	ds_write_b64 v2, v[36:37] offset:35904
	ds_write_b64 v2, v[20:21] offset:38016
	ds_write_b64 v2, v[52:53] offset:40128
	ds_write_b64 v2, v[12:13] offset:42240
	ds_write_b64 v2, v[44:45] offset:44352
	ds_write_b64 v2, v[28:29] offset:46464
	ds_write_b64 v2, v[60:61] offset:48576
	ds_write_b64 v2, v[8:9] offset:50688
	ds_write_b64 v2, v[40:41] offset:52800
	ds_write_b64 v2, v[24:25] offset:54912
	ds_write_b64 v2, v[56:57] offset:57024
	ds_write_b64 v2, v[16:17] offset:59136
	ds_write_b64 v2, v[48:49] offset:61248
	ds_write_b64 v2, v[32:33] offset:63360
	ds_write_b64 v2, v[64:65] offset:65472
	v_mov_b32_e32 v2, v142
	s_waitcnt lgkmcnt(0)
	s_barrier
	s_nop 0
	v_and_b32_e32 v5, 15, v2
	v_cvt_f32_ubyte0_e32 v4, v5
	v_mul_f32_e32 v6, 0x3b800000, v4
	v_sin_f32_e32 v4, v6
	v_cos_f32_e32 v6, v6
	v_lshlrev_b32_e32 v64, 3, v5
	v_lshlrev_b32_e32 v2, 4, v2
	v_xor_b32_e32 v7, 0x80000000, v4
	v_mov_b32_e32 v5, v7
	v_pk_mul_f32 v[8:9], v[6:7], v[4:5] op_sel:[1,0] op_sel_hi:[0,1]
	v_pk_fma_f32 v[8:9], v[6:7], v[6:7], v[8:9] op_sel_hi:[1,0,1]
	v_and_b32_e32 v2, 0xffffff00, v2
	v_xor_b32_e32 v14, 0x80000000, v9
	v_mov_b32_e32 v15, v9
	v_pk_mul_f32 v[12:13], v[8:9], v[14:15] op_sel:[1,0] op_sel_hi:[0,1]
	v_pk_fma_f32 v[12:13], v[8:9], v[8:9], v[12:13] op_sel_hi:[1,0,1]
	v_pk_mul_f32 v[10:11], v[4:5], v[8:9] op_sel:[0,1] op_sel_hi:[1,0]
	v_xor_b32_e32 v16, 0x80000000, v13
	v_mov_b32_e32 v17, v13
	v_pk_mul_f32 v[32:33], v[12:13], v[16:17] op_sel:[1,0] op_sel_hi:[0,1]
	v_pk_fma_f32 v[32:33], v[12:13], v[12:13], v[32:33] op_sel_hi:[1,0,1]
	v_pk_mul_f32 v[18:19], v[4:5], v[12:13] op_sel:[0,1] op_sel_hi:[1,0]
	v_pk_mul_f32 v[48:49], v[16:17], v[32:33] op_sel:[0,1] op_sel_hi:[1,0]
	v_pk_mul_f32 v[36:37], v[4:5], v[32:33] op_sel:[0,1] op_sel_hi:[1,0]
	v_pk_fma_f32 v[48:49], v[12:13], v[32:33], v[48:49] op_sel_hi:[0,1,1]
	v_pk_mul_f32 v[52:53], v[4:5], v[48:49] op_sel:[0,1] op_sel_hi:[1,0]
	v_pk_fma_f32 v[10:11], v[6:7], v[8:9], v[10:11] op_sel_hi:[0,1,1]
	v_pk_fma_f32 v[18:19], v[6:7], v[12:13], v[18:19] op_sel_hi:[0,1,1]
	v_pk_fma_f32 v[36:37], v[6:7], v[32:33], v[36:37] op_sel_hi:[0,1,1]
	v_pk_fma_f32 v[52:53], v[6:7], v[48:49], v[52:53] op_sel_hi:[0,1,1]
	v_lshlrev_b32_e32 v7, 3, v2
	v_add3_u32 v7, 0, v64, v7
	v_ashrrev_i32_e32 v64, 2, v2
	v_add_u32_e32 v106, v7, v64
	ds_read2_b64 v[64:67], v106 offset1:16
	ds_read2_b64 v[68:71], v106 offset0:33 offset1:49
	ds_read2_b64 v[72:75], v106 offset0:66 offset1:82
	ds_read2_b64 v[76:79], v106 offset0:132 offset1:148
	ds_read2_b64 v[80:83], v106 offset0:99 offset1:115
	ds_read2_b64 v[84:87], v106 offset0:165 offset1:181
	ds_read2_b64 v[88:91], v106 offset0:198 offset1:214
	ds_read2_b64 v[92:95], v106 offset0:231 offset1:247
	s_waitcnt lgkmcnt(4)
	v_pk_add_f32 v[96:97], v[64:65], v[76:77]
	v_pk_add_f32 v[64:65], v[64:65], v[76:77] neg_lo:[0,1] neg_hi:[0,1]
	v_pk_add_f32 v[76:77], v[66:67], v[78:79]
	v_pk_add_f32 v[66:67], v[66:67], v[78:79] neg_lo:[0,1] neg_hi:[0,1]
	s_waitcnt lgkmcnt(1)
	v_pk_add_f32 v[98:99], v[74:75], v[90:91]
	v_pk_mul_f32 v[78:79], v[66:67], s[24:25]
	v_pk_add_f32 v[74:75], v[74:75], v[90:91] neg_lo:[0,1] neg_hi:[0,1]
	v_pk_fma_f32 v[66:67], v[66:67], s[22:23], v[78:79] op_sel:[0,0,1] op_sel_hi:[1,0,0]
	v_pk_add_f32 v[78:79], v[68:69], v[84:85]
	v_pk_add_f32 v[68:69], v[68:69], v[84:85] neg_lo:[0,1] neg_hi:[0,1]
	v_pk_mul_f32 v[90:91], v[74:75], s[44:45]
	v_pk_mul_f32 v[84:85], v[68:69], s[40:41]
	v_pk_fma_f32 v[74:75], v[74:75], s[50:51], v[90:91] op_sel:[0,0,1] op_sel_hi:[1,0,0] neg_lo:[1,0,0] neg_hi:[1,0,0]
	v_pk_fma_f32 v[68:69], v[68:69], s[38:39], v[84:85] op_sel:[0,0,1] op_sel_hi:[1,0,0]
	v_pk_add_f32 v[84:85], v[70:71], v[86:87]
	v_pk_add_f32 v[70:71], v[70:71], v[86:87] neg_lo:[0,1] neg_hi:[0,1]
	s_waitcnt lgkmcnt(0)
	v_pk_add_f32 v[90:91], v[80:81], v[92:93]
	v_pk_add_f32 v[80:81], v[80:81], v[92:93] neg_lo:[0,1] neg_hi:[0,1]
	v_pk_mul_f32 v[86:87], v[70:71], s[44:45]
	v_pk_mul_f32 v[92:93], v[80:81], s[40:41]
	v_pk_fma_f32 v[70:71], v[70:71], s[50:51], v[86:87] op_sel:[0,0,1] op_sel_hi:[1,0,0]
	v_pk_add_f32 v[86:87], v[72:73], v[88:89]
	v_pk_add_f32 v[88:89], v[72:73], v[88:89] neg_lo:[0,1] neg_hi:[0,1]
	v_pk_fma_f32 v[80:81], v[80:81], s[38:39], v[92:93] op_sel:[0,0,1] op_sel_hi:[1,0,0] neg_lo:[1,0,0] neg_hi:[1,0,0]
	v_pk_add_f32 v[92:93], v[82:83], v[94:95]
	v_pk_add_f32 v[82:83], v[82:83], v[94:95] op_sel:[1,1] op_sel_hi:[0,0] neg_lo:[0,1] neg_hi:[0,1]
	v_pk_mul_f32 v[94:95], v[82:83], s[24:25] op_sel:[1,0] op_sel_hi:[0,1]
	s_nop 0
	v_pk_fma_f32 v[82:83], v[82:83], s[22:23], v[94:95] op_sel:[1,0,1] op_sel_hi:[0,0,0] neg_lo:[1,0,0] neg_hi:[1,0,0]
	v_pk_add_f32 v[94:95], v[96:97], v[86:87]
	v_pk_add_f32 v[86:87], v[96:97], v[86:87] neg_lo:[0,1] neg_hi:[0,1]
	v_pk_add_f32 v[96:97], v[76:77], v[98:99]
	v_pk_add_f32 v[76:77], v[76:77], v[98:99] neg_lo:[0,1] neg_hi:[0,1]
	v_pk_add_f32 v[100:101], v[84:85], v[92:93]
	v_pk_add_f32 v[84:85], v[84:85], v[92:93] neg_lo:[0,1] neg_hi:[0,1]
	v_pk_add_f32 v[72:73], v[64:65], v[88:89] op_sel:[0,1] op_sel_hi:[1,0] neg_hi:[0,1]
	v_pk_add_f32 v[64:65], v[64:65], v[88:89] op_sel:[0,1] op_sel_hi:[1,0] neg_lo:[0,1]
	v_pk_add_f32 v[88:89], v[66:67], v[74:75]
	v_pk_add_f32 v[66:67], v[66:67], v[74:75] neg_lo:[0,1] neg_hi:[0,1]
	v_pk_mul_f32 v[98:99], v[76:77], s[40:41]
	v_pk_mul_f32 v[92:93], v[84:85], s[40:41]
	v_pk_mul_f32 v[74:75], v[66:67], s[40:41]
	v_pk_fma_f32 v[76:77], v[76:77], s[38:39], v[98:99] op_sel:[0,0,1] op_sel_hi:[1,0,0]
	v_pk_add_f32 v[98:99], v[78:79], v[90:91]
	v_pk_add_f32 v[90:91], v[78:79], v[90:91] neg_lo:[0,1] neg_hi:[0,1]
	v_pk_fma_f32 v[84:85], v[84:85], s[38:39], v[92:93] op_sel:[0,0,1] op_sel_hi:[1,0,0] neg_lo:[1,0,0] neg_hi:[1,0,0]
	v_pk_fma_f32 v[66:67], v[66:67], s[38:39], v[74:75] op_sel:[0,0,1] op_sel_hi:[1,0,0]
	v_pk_add_f32 v[74:75], v[68:69], v[80:81]
	v_pk_add_f32 v[92:93], v[70:71], v[82:83]
	v_pk_add_f32 v[70:71], v[70:71], v[82:83] neg_lo:[0,1] neg_hi:[0,1]
	v_pk_add_f32 v[68:69], v[68:69], v[80:81] neg_lo:[0,1] neg_hi:[0,1]
	v_pk_mul_f32 v[82:83], v[70:71], s[40:41]
	v_pk_add_f32 v[102:103], v[72:73], v[74:75]
	v_pk_add_f32 v[72:73], v[72:73], v[74:75] neg_lo:[0,1] neg_hi:[0,1]
	v_pk_add_f32 v[74:75], v[88:89], v[92:93]
	v_pk_add_f32 v[92:93], v[88:89], v[92:93] neg_lo:[0,1] neg_hi:[0,1]
	v_xor_b32_e32 v20, 0x80000000, v11
	v_mov_b32_e32 v21, v11
	v_pk_mul_f32 v[24:25], v[14:15], v[12:13] op_sel:[0,1] op_sel_hi:[1,0]
	v_xor_b32_e32 v81, 0x80000000, v68
	v_pk_fma_f32 v[70:71], v[70:71], s[38:39], v[82:83] op_sel:[0,0,1] op_sel_hi:[1,0,0] neg_lo:[1,0,0] neg_hi:[1,0,0]
	v_pk_add_f32 v[78:79], v[86:87], v[90:91] op_sel:[0,1] op_sel_hi:[1,0] neg_hi:[0,1]
	v_pk_add_f32 v[86:87], v[86:87], v[90:91] op_sel:[0,1] op_sel_hi:[1,0] neg_lo:[0,1]
	v_pk_add_f32 v[90:91], v[76:77], v[84:85]
	v_pk_add_f32 v[84:85], v[76:77], v[84:85] neg_lo:[0,1] neg_hi:[0,1]
	v_mov_b32_e32 v80, v69
	v_xor_b32_e32 v22, 0x80000000, v19
	v_mov_b32_e32 v23, v19
	v_pk_fma_f32 v[24:25], v[8:9], v[12:13], v[24:25] op_sel_hi:[0,1,1]
	v_pk_mul_f32 v[28:29], v[12:13], v[20:21] op_sel:[1,0] op_sel_hi:[0,1]
	v_pk_add_f32 v[68:69], v[64:65], v[80:81]
	v_pk_add_f32 v[64:65], v[64:65], v[80:81] neg_lo:[0,1] neg_hi:[0,1]
	v_pk_add_f32 v[80:81], v[66:67], v[70:71]
	v_pk_add_f32 v[70:71], v[66:67], v[70:71] neg_lo:[0,1] neg_hi:[0,1]
	v_pk_add_f32 v[88:89], v[72:73], v[92:93] op_sel:[0,1] op_sel_hi:[1,0] neg_hi:[0,1]
	v_xor_b32_e32 v26, 0x80000000, v25
	v_mov_b32_e32 v27, v25
	v_pk_fma_f32 v[28:29], v[12:13], v[10:11], v[28:29] op_sel_hi:[1,0,1]
	v_pk_add_f32 v[76:77], v[86:87], v[84:85] op_sel:[0,1] op_sel_hi:[1,0] neg_hi:[0,1]
	v_pk_add_f32 v[72:73], v[72:73], v[92:93] op_sel:[0,1] op_sel_hi:[1,0] neg_lo:[0,1]
	v_pk_mul_f32 v[92:93], v[22:23], v[88:89] op_sel:[0,1] op_sel_hi:[1,0]
	v_xor_b32_e32 v30, 0x80000000, v29
	v_mov_b32_e32 v31, v29
	v_pk_add_f32 v[82:83], v[94:95], v[98:99]
	v_pk_add_f32 v[94:95], v[94:95], v[98:99] neg_lo:[0,1] neg_hi:[0,1]
	v_pk_add_f32 v[98:99], v[96:97], v[100:101]
	v_pk_add_f32 v[66:67], v[64:65], v[70:71] op_sel:[0,1] op_sel_hi:[1,0] neg_hi:[0,1]
	v_pk_fma_f32 v[88:89], v[18:19], v[88:89], v[92:93] op_sel_hi:[0,1,1]
	v_pk_mul_f32 v[92:93], v[26:27], v[76:77] op_sel:[0,1] op_sel_hi:[1,0]
	v_xor_b32_e32 v34, 0x80000000, v33
	v_mov_b32_e32 v35, v33
	v_pk_mul_f32 v[40:41], v[14:15], v[32:33] op_sel:[0,1] op_sel_hi:[1,0]
	v_pk_add_f32 v[104:105], v[82:83], v[98:99]
	v_pk_add_f32 v[82:83], v[82:83], v[98:99] neg_lo:[0,1] neg_hi:[0,1]
	v_pk_fma_f32 v[76:77], v[24:25], v[76:77], v[92:93] op_sel_hi:[0,1,1]
	v_pk_mul_f32 v[92:93], v[30:31], v[66:67] op_sel:[0,1] op_sel_hi:[1,0]
	v_xor_b32_e32 v38, 0x80000000, v37
	v_mov_b32_e32 v39, v37
	v_pk_fma_f32 v[40:41], v[8:9], v[32:33], v[40:41] op_sel_hi:[0,1,1]
	v_pk_mul_f32 v[44:45], v[20:21], v[32:33] op_sel:[0,1] op_sel_hi:[1,0]
	v_pk_add_f32 v[84:85], v[86:87], v[84:85] op_sel:[0,1] op_sel_hi:[1,0] neg_lo:[0,1]
	v_pk_add_f32 v[86:87], v[102:103], v[74:75]
	v_pk_add_f32 v[74:75], v[102:103], v[74:75] neg_lo:[0,1] neg_hi:[0,1]
	v_pk_fma_f32 v[66:67], v[28:29], v[66:67], v[92:93] op_sel_hi:[0,1,1]
	v_pk_mul_f32 v[92:93], v[34:35], v[82:83] op_sel:[0,1] op_sel_hi:[1,0]
	v_xor_b32_e32 v42, 0x80000000, v41
	v_mov_b32_e32 v43, v41
	v_pk_fma_f32 v[44:45], v[10:11], v[32:33], v[44:45] op_sel_hi:[0,1,1]
	v_pk_add_f32 v[100:101], v[96:97], v[100:101] neg_lo:[0,1] neg_hi:[0,1]
	v_pk_add_f32 v[98:99], v[78:79], v[90:91]
	v_pk_add_f32 v[78:79], v[78:79], v[90:91] neg_lo:[0,1] neg_hi:[0,1]
	v_pk_fma_f32 v[82:83], v[32:33], v[82:83], v[92:93] op_sel_hi:[0,1,1]
	v_pk_mul_f32 v[92:93], v[38:39], v[74:75] op_sel:[0,1] op_sel_hi:[1,0]
	v_xor_b32_e32 v46, 0x80000000, v45
	v_mov_b32_e32 v47, v45
	v_pk_add_f32 v[90:91], v[68:69], v[80:81]
	v_pk_add_f32 v[68:69], v[68:69], v[80:81] neg_lo:[0,1] neg_hi:[0,1]
	v_pk_fma_f32 v[74:75], v[36:37], v[74:75], v[92:93] op_sel_hi:[0,1,1]
	v_pk_mul_f32 v[92:93], v[42:43], v[78:79] op_sel:[0,1] op_sel_hi:[1,0]
	v_xor_b32_e32 v50, 0x80000000, v49
	v_mov_b32_e32 v51, v49
	v_pk_mul_f32 v[56:57], v[14:15], v[48:49] op_sel:[0,1] op_sel_hi:[1,0]
	v_pk_add_f32 v[96:97], v[94:95], v[100:101] op_sel:[0,1] op_sel_hi:[1,0] neg_hi:[0,1]
	v_pk_add_f32 v[94:95], v[94:95], v[100:101] op_sel:[0,1] op_sel_hi:[1,0] neg_lo:[0,1]
	v_pk_fma_f32 v[78:79], v[40:41], v[78:79], v[92:93] op_sel_hi:[0,1,1]
	v_pk_mul_f32 v[92:93], v[46:47], v[68:69] op_sel:[0,1] op_sel_hi:[1,0]
	v_xor_b32_e32 v54, 0x80000000, v53
	v_mov_b32_e32 v55, v53
	v_pk_fma_f32 v[56:57], v[8:9], v[48:49], v[56:57] op_sel_hi:[0,1,1]
	v_pk_mul_f32 v[60:61], v[20:21], v[48:49] op_sel:[0,1] op_sel_hi:[1,0]
	v_pk_fma_f32 v[68:69], v[44:45], v[68:69], v[92:93] op_sel_hi:[0,1,1]
	v_pk_mul_f32 v[92:93], v[50:51], v[94:95] op_sel:[0,1] op_sel_hi:[1,0]
	v_xor_b32_e32 v58, 0x80000000, v57
	v_mov_b32_e32 v59, v57
	v_pk_fma_f32 v[60:61], v[10:11], v[48:49], v[60:61] op_sel_hi:[0,1,1]
	v_pk_add_f32 v[64:65], v[64:65], v[70:71] op_sel:[0,1] op_sel_hi:[1,0] neg_lo:[0,1]
	v_pk_mul_f32 v[70:71], v[4:5], v[86:87] op_sel:[0,1] op_sel_hi:[1,0]
	v_pk_fma_f32 v[92:93], v[48:49], v[94:95], v[92:93] op_sel_hi:[0,1,1]
	v_pk_mul_f32 v[94:95], v[54:55], v[72:73] op_sel:[0,1] op_sel_hi:[1,0]
	v_xor_b32_e32 v62, 0x80000000, v61
	v_mov_b32_e32 v63, v61
	v_pk_fma_f32 v[70:71], v[6:7], v[86:87], v[70:71] op_sel_hi:[0,1,1]
	v_pk_mul_f32 v[86:87], v[20:21], v[90:91] op_sel:[0,1] op_sel_hi:[1,0]
	v_pk_fma_f32 v[72:73], v[52:53], v[72:73], v[94:95] op_sel_hi:[0,1,1]
	v_pk_mul_f32 v[94:95], v[58:59], v[84:85] op_sel:[0,1] op_sel_hi:[1,0]
	v_add_u32_e32 v2, 0x2000, v2
	v_pk_mul_f32 v[80:81], v[14:15], v[98:99] op_sel:[0,1] op_sel_hi:[1,0]
	v_pk_fma_f32 v[86:87], v[10:11], v[90:91], v[86:87] op_sel_hi:[0,1,1]
	v_pk_mul_f32 v[90:91], v[16:17], v[96:97] op_sel:[0,1] op_sel_hi:[1,0]
	v_pk_fma_f32 v[84:85], v[56:57], v[84:85], v[94:95] op_sel_hi:[0,1,1]
	v_pk_mul_f32 v[94:95], v[62:63], v[64:65] op_sel:[0,1] op_sel_hi:[1,0]
	v_ashrrev_i32_e32 v2, 2, v2
	v_pk_fma_f32 v[80:81], v[8:9], v[98:99], v[80:81] op_sel_hi:[0,1,1]
	v_pk_fma_f32 v[90:91], v[12:13], v[96:97], v[90:91] op_sel_hi:[0,1,1]
	v_pk_fma_f32 v[64:65], v[60:61], v[64:65], v[94:95] op_sel_hi:[0,1,1]
	ds_write2_b64 v106, v[104:105], v[82:83] offset1:16
	ds_write2_b64 v106, v[90:91], v[92:93] offset0:33 offset1:49
	ds_write2_b64 v106, v[80:81], v[78:79] offset0:66 offset1:82
	ds_write2_b64 v106, v[76:77], v[84:85] offset0:99 offset1:115
	ds_write2_b64 v106, v[70:71], v[74:75] offset0:132 offset1:148
	ds_write2_b64 v106, v[88:89], v[72:73] offset0:165 offset1:181
	ds_write2_b64 v106, v[86:87], v[68:69] offset0:198 offset1:214
	ds_write2_b64 v106, v[66:67], v[64:65] offset0:231 offset1:247
	v_add3_u32 v2, v7, v2, s60
	ds_read2_b64 v[64:67], v2 offset1:16
	ds_read2_b64 v[68:71], v2 offset0:33 offset1:49
	ds_read2_b64 v[72:75], v2 offset0:66 offset1:82
	ds_read2_b64 v[76:79], v2 offset0:132 offset1:148
	ds_read2_b64 v[80:83], v2 offset0:99 offset1:115
	ds_read2_b64 v[84:87], v2 offset0:165 offset1:181
	ds_read2_b64 v[88:91], v2 offset0:198 offset1:214
	ds_read2_b64 v[92:95], v2 offset0:231 offset1:247
	s_waitcnt lgkmcnt(4)
	v_pk_add_f32 v[96:97], v[64:65], v[76:77]
	v_pk_add_f32 v[64:65], v[64:65], v[76:77] neg_lo:[0,1] neg_hi:[0,1]
	v_pk_add_f32 v[76:77], v[66:67], v[78:79]
	v_pk_add_f32 v[66:67], v[66:67], v[78:79] neg_lo:[0,1] neg_hi:[0,1]
	s_waitcnt lgkmcnt(1)
	v_pk_add_f32 v[98:99], v[74:75], v[90:91]
	v_pk_mul_f32 v[78:79], v[66:67], s[24:25]
	v_pk_add_f32 v[74:75], v[74:75], v[90:91] neg_lo:[0,1] neg_hi:[0,1]
	v_pk_fma_f32 v[66:67], v[66:67], s[22:23], v[78:79] op_sel:[0,0,1] op_sel_hi:[1,0,0]
	v_pk_add_f32 v[78:79], v[68:69], v[84:85]
	v_pk_add_f32 v[68:69], v[68:69], v[84:85] neg_lo:[0,1] neg_hi:[0,1]
	v_pk_mul_f32 v[90:91], v[74:75], s[44:45]
	v_pk_mul_f32 v[84:85], v[68:69], s[40:41]
	v_pk_fma_f32 v[74:75], v[74:75], s[50:51], v[90:91] op_sel:[0,0,1] op_sel_hi:[1,0,0] neg_lo:[1,0,0] neg_hi:[1,0,0]
	s_waitcnt lgkmcnt(0)
	v_pk_add_f32 v[90:91], v[80:81], v[92:93]
	v_pk_add_f32 v[80:81], v[80:81], v[92:93] neg_lo:[0,1] neg_hi:[0,1]
	v_pk_fma_f32 v[68:69], v[68:69], s[38:39], v[84:85] op_sel:[0,0,1] op_sel_hi:[1,0,0]
	v_pk_add_f32 v[84:85], v[70:71], v[86:87]
	v_pk_add_f32 v[70:71], v[70:71], v[86:87] neg_lo:[0,1] neg_hi:[0,1]
	v_pk_mul_f32 v[92:93], v[80:81], s[40:41]
	v_pk_mul_f32 v[86:87], v[70:71], s[44:45]
	v_pk_fma_f32 v[80:81], v[80:81], s[38:39], v[92:93] op_sel:[0,0,1] op_sel_hi:[1,0,0] neg_lo:[1,0,0] neg_hi:[1,0,0]
	v_pk_add_f32 v[92:93], v[82:83], v[94:95]
	v_pk_add_f32 v[82:83], v[82:83], v[94:95] neg_lo:[0,1] neg_hi:[0,1]
	v_pk_fma_f32 v[70:71], v[70:71], s[50:51], v[86:87] op_sel:[0,0,1] op_sel_hi:[1,0,0]
	v_pk_add_f32 v[86:87], v[72:73], v[88:89]
	v_pk_mul_f32 v[94:95], v[82:83], s[24:25]
	v_pk_add_f32 v[88:89], v[72:73], v[88:89] neg_lo:[0,1] neg_hi:[0,1]
	v_pk_fma_f32 v[82:83], v[82:83], s[22:23], v[94:95] op_sel:[0,0,1] op_sel_hi:[1,0,0] neg_lo:[1,0,0] neg_hi:[1,0,0]
	v_pk_add_f32 v[94:95], v[96:97], v[86:87]
	v_pk_add_f32 v[86:87], v[96:97], v[86:87] neg_lo:[0,1] neg_hi:[0,1]
	v_pk_add_f32 v[96:97], v[76:77], v[98:99]
	v_pk_add_f32 v[76:77], v[76:77], v[98:99] op_sel:[1,1] op_sel_hi:[0,0] neg_lo:[0,1] neg_hi:[0,1]
	v_pk_mul_f32 v[98:99], v[76:77], s[40:41] op_sel:[1,0] op_sel_hi:[0,1]
	v_pk_add_f32 v[100:101], v[84:85], v[92:93]
	v_pk_add_f32 v[84:85], v[84:85], v[92:93] neg_lo:[0,1] neg_hi:[0,1]
	v_pk_fma_f32 v[76:77], v[76:77], s[38:39], v[98:99] op_sel:[1,0,1] op_sel_hi:[0,0,0]
	v_pk_add_f32 v[98:99], v[78:79], v[90:91]
	v_pk_add_f32 v[90:91], v[78:79], v[90:91] neg_lo:[0,1] neg_hi:[0,1]
	v_pk_mul_f32 v[92:93], v[84:85], s[40:41]
	v_pk_add_f32 v[72:73], v[64:65], v[88:89] op_sel:[0,1] op_sel_hi:[1,0] neg_hi:[0,1]
	v_pk_add_f32 v[64:65], v[64:65], v[88:89] op_sel:[0,1] op_sel_hi:[1,0] neg_lo:[0,1]
	v_pk_add_f32 v[88:89], v[66:67], v[74:75]
	v_pk_add_f32 v[66:67], v[66:67], v[74:75] neg_lo:[0,1] neg_hi:[0,1]
	v_pk_fma_f32 v[84:85], v[84:85], s[38:39], v[92:93] op_sel:[0,0,1] op_sel_hi:[1,0,0] neg_lo:[1,0,0] neg_hi:[1,0,0]
	v_pk_mul_f32 v[74:75], v[66:67], s[40:41] op_sel:[1,1] op_sel_hi:[0,0]
	v_pk_fma_f32 v[66:67], v[66:67], s[38:39], v[74:75] op_sel_hi:[1,0,1]
	v_pk_add_f32 v[74:75], v[68:69], v[80:81]
	v_pk_add_f32 v[92:93], v[70:71], v[82:83]
	v_pk_add_f32 v[70:71], v[70:71], v[82:83] neg_lo:[0,1] neg_hi:[0,1]
	v_pk_add_f32 v[78:79], v[86:87], v[90:91] op_sel:[0,1] op_sel_hi:[1,0] neg_hi:[0,1]
	v_pk_add_f32 v[86:87], v[86:87], v[90:91] op_sel:[0,1] op_sel_hi:[1,0] neg_lo:[0,1]
	v_pk_add_f32 v[90:91], v[76:77], v[84:85]
	v_pk_add_f32 v[84:85], v[76:77], v[84:85] neg_lo:[0,1] neg_hi:[0,1]
	v_pk_add_f32 v[80:81], v[68:69], v[80:81] neg_lo:[0,1] neg_hi:[0,1]
	v_pk_mul_f32 v[82:83], v[70:71], s[40:41]
	v_pk_add_f32 v[102:103], v[72:73], v[74:75]
	v_pk_add_f32 v[72:73], v[72:73], v[74:75] neg_lo:[0,1] neg_hi:[0,1]
	v_pk_add_f32 v[74:75], v[88:89], v[92:93]
	v_pk_fma_f32 v[70:71], v[70:71], s[38:39], v[82:83] op_sel:[0,0,1] op_sel_hi:[1,0,0] neg_lo:[1,0,0] neg_hi:[1,0,0]
	v_pk_add_f32 v[82:83], v[94:95], v[98:99]
	v_pk_add_f32 v[94:95], v[94:95], v[98:99] neg_lo:[0,1] neg_hi:[0,1]
	v_pk_add_f32 v[98:99], v[96:97], v[100:101]
	v_pk_add_f32 v[76:77], v[86:87], v[84:85] op_sel:[0,1] op_sel_hi:[1,0] neg_hi:[0,1]
	v_pk_add_f32 v[84:85], v[86:87], v[84:85] op_sel:[0,1] op_sel_hi:[1,0] neg_lo:[0,1]
	v_pk_add_f32 v[86:87], v[102:103], v[74:75]
	v_pk_add_f32 v[100:101], v[96:97], v[100:101] neg_lo:[0,1] neg_hi:[0,1]
	v_pk_add_f32 v[68:69], v[64:65], v[80:81] op_sel:[0,1] op_sel_hi:[1,0] neg_hi:[0,1]
	v_pk_add_f32 v[64:65], v[64:65], v[80:81] op_sel:[0,1] op_sel_hi:[1,0] neg_lo:[0,1]
	v_pk_add_f32 v[80:81], v[66:67], v[70:71]
	v_pk_add_f32 v[104:105], v[82:83], v[98:99]
	v_pk_add_f32 v[82:83], v[82:83], v[98:99] neg_lo:[0,1] neg_hi:[0,1]
	v_pk_add_f32 v[98:99], v[78:79], v[90:91]
	v_pk_mul_f32 v[4:5], v[4:5], v[86:87] op_sel:[0,1] op_sel_hi:[1,0]
	v_pk_add_f32 v[92:93], v[88:89], v[92:93] neg_lo:[0,1] neg_hi:[0,1]
	v_pk_add_f32 v[78:79], v[78:79], v[90:91] neg_lo:[0,1] neg_hi:[0,1]
	v_pk_add_f32 v[90:91], v[68:69], v[80:81]
	v_pk_fma_f32 v[4:5], v[6:7], v[86:87], v[4:5] op_sel_hi:[0,1,1]
	v_pk_mul_f32 v[6:7], v[14:15], v[98:99] op_sel:[0,1] op_sel_hi:[1,0]
	v_pk_add_f32 v[70:71], v[66:67], v[70:71] neg_lo:[0,1] neg_hi:[0,1]
	v_pk_add_f32 v[96:97], v[94:95], v[100:101] op_sel:[0,1] op_sel_hi:[1,0] neg_hi:[0,1]
	v_pk_fma_f32 v[6:7], v[8:9], v[98:99], v[6:7] op_sel_hi:[0,1,1]
	v_pk_mul_f32 v[8:9], v[20:21], v[90:91] op_sel:[0,1] op_sel_hi:[1,0]
	v_pk_add_f32 v[88:89], v[72:73], v[92:93] op_sel:[0,1] op_sel_hi:[1,0] neg_hi:[0,1]
	v_pk_fma_f32 v[8:9], v[10:11], v[90:91], v[8:9] op_sel_hi:[0,1,1]
	v_pk_mul_f32 v[10:11], v[16:17], v[96:97] op_sel:[0,1] op_sel_hi:[1,0]
	v_pk_add_f32 v[66:67], v[64:65], v[70:71] op_sel:[0,1] op_sel_hi:[1,0] neg_hi:[0,1]
	v_pk_fma_f32 v[10:11], v[12:13], v[96:97], v[10:11] op_sel_hi:[0,1,1]
	v_pk_mul_f32 v[12:13], v[22:23], v[88:89] op_sel:[0,1] op_sel_hi:[1,0]
	v_pk_add_f32 v[94:95], v[94:95], v[100:101] op_sel:[0,1] op_sel_hi:[1,0] neg_lo:[0,1]
	v_pk_add_f32 v[74:75], v[102:103], v[74:75] neg_lo:[0,1] neg_hi:[0,1]
	v_pk_add_f32 v[72:73], v[72:73], v[92:93] op_sel:[0,1] op_sel_hi:[1,0] neg_lo:[0,1]
	v_pk_add_f32 v[68:69], v[68:69], v[80:81] neg_lo:[0,1] neg_hi:[0,1]
	v_pk_add_f32 v[64:65], v[64:65], v[70:71] op_sel:[0,1] op_sel_hi:[1,0] neg_lo:[0,1]
	v_pk_fma_f32 v[12:13], v[18:19], v[88:89], v[12:13] op_sel_hi:[0,1,1]
	v_pk_mul_f32 v[14:15], v[26:27], v[76:77] op_sel:[0,1] op_sel_hi:[1,0]
	v_pk_mul_f32 v[16:17], v[30:31], v[66:67] op_sel:[0,1] op_sel_hi:[1,0]
	v_pk_mul_f32 v[18:19], v[34:35], v[82:83] op_sel:[0,1] op_sel_hi:[1,0]
	v_pk_fma_f32 v[14:15], v[24:25], v[76:77], v[14:15] op_sel_hi:[0,1,1]
	v_pk_fma_f32 v[16:17], v[28:29], v[66:67], v[16:17] op_sel_hi:[0,1,1]
	v_pk_fma_f32 v[18:19], v[32:33], v[82:83], v[18:19] op_sel_hi:[0,1,1]
	v_pk_mul_f32 v[20:21], v[38:39], v[74:75] op_sel:[0,1] op_sel_hi:[1,0]
	v_pk_mul_f32 v[22:23], v[42:43], v[78:79] op_sel:[0,1] op_sel_hi:[1,0]
	v_pk_mul_f32 v[24:25], v[46:47], v[68:69] op_sel:[0,1] op_sel_hi:[1,0]
	v_pk_mul_f32 v[26:27], v[50:51], v[94:95] op_sel:[0,1] op_sel_hi:[1,0]
	v_pk_mul_f32 v[28:29], v[54:55], v[72:73] op_sel:[0,1] op_sel_hi:[1,0]
	v_pk_mul_f32 v[30:31], v[58:59], v[84:85] op_sel:[0,1] op_sel_hi:[1,0]
	v_pk_mul_f32 v[32:33], v[62:63], v[64:65] op_sel:[0,1] op_sel_hi:[1,0]
	v_pk_fma_f32 v[20:21], v[36:37], v[74:75], v[20:21] op_sel_hi:[0,1,1]
	v_pk_fma_f32 v[22:23], v[40:41], v[78:79], v[22:23] op_sel_hi:[0,1,1]
	v_pk_fma_f32 v[24:25], v[44:45], v[68:69], v[24:25] op_sel_hi:[0,1,1]
	v_pk_fma_f32 v[26:27], v[48:49], v[94:95], v[26:27] op_sel_hi:[0,1,1]
	v_pk_fma_f32 v[28:29], v[52:53], v[72:73], v[28:29] op_sel_hi:[0,1,1]
	v_pk_fma_f32 v[30:31], v[56:57], v[84:85], v[30:31] op_sel_hi:[0,1,1]
	v_pk_fma_f32 v[32:33], v[60:61], v[64:65], v[32:33] op_sel_hi:[0,1,1]
	ds_write2_b64 v2, v[104:105], v[18:19] offset1:16
	ds_write2_b64 v2, v[10:11], v[26:27] offset0:33 offset1:49
	ds_write2_b64 v2, v[6:7], v[22:23] offset0:66 offset1:82
	ds_write2_b64 v2, v[14:15], v[30:31] offset0:99 offset1:115
	ds_write2_b64 v2, v[4:5], v[20:21] offset0:132 offset1:148
	ds_write2_b64 v2, v[12:13], v[28:29] offset0:165 offset1:181
	ds_write2_b64 v2, v[8:9], v[24:25] offset0:198 offset1:214
	ds_write2_b64 v2, v[16:17], v[32:33] offset0:231 offset1:247
	s_waitcnt lgkmcnt(0)
	s_barrier
	s_nop 0
	v_ashrrev_i32_e32 v2, 31, v142
	v_add_u32_sdwa v2, v142, v2 dst_sel:DWORD dst_unused:UNUSED_PAD src0_sel:DWORD src1_sel:BYTE_3
	v_ashrrev_i32_e32 v145, 8, v2
	v_mul_i32_i24_e32 v2, 0x100, v145
	v_sub_u32_e32 v144, v142, v2
	v_lshlrev_b32_e32 v2, 1, v144
	v_bfrev_b32_e32 v2, v2
	v_lshrrev_b32_e32 v2, 23, v2
	v_sub_u32_e32 v2, 0x200, v2
	v_bfrev_b32_e32 v2, v2
	v_lshrrev_b32_e32 v2, 19, v2
	v_lshlrev_b32_e32 v143, 13, v145
	v_and_b32_e32 v2, 0x1ff0, v2
	v_cmp_eq_u32_e32 vcc, 0, v144
	v_lshl_add_u32 v4, v144, 5, v143
	v_lshlrev_b32_e32 v5, 3, v4
	v_cndmask_b32_e64 v2, v2, 16, vcc
	v_ashrrev_i32_e32 v4, 2, v4
	v_or_b32_e32 v2, v2, v143
	v_add3_u32 v56, 0, v5, v4
	v_ashrrev_i32_e32 v4, 5, v2
	v_lshlrev_b32_e32 v2, 3, v2
	v_lshlrev_b32_e32 v4, 3, v4
	v_add3_u32 v2, 0, v2, v4
	ds_read2_b64 v[4:7], v56 offset1:1
	ds_read2_b64 v[8:11], v56 offset0:2 offset1:3
	ds_read2_b64 v[12:15], v2 offset1:1
	ds_read2_b64 v[16:19], v2 offset0:2 offset1:3
	ds_read2_b64 v[20:23], v56 offset0:4 offset1:5
	ds_read2_b64 v[24:27], v56 offset0:6 offset1:7
	ds_read2_b64 v[28:31], v2 offset0:4 offset1:5
	ds_read2_b64 v[32:35], v2 offset0:6 offset1:7
	ds_read2_b64 v[36:39], v56 offset0:8 offset1:9
	ds_read2_b64 v[40:43], v56 offset0:10 offset1:11
	ds_read2_b64 v[44:47], v2 offset0:8 offset1:9
	ds_read2_b64 v[52:55], v2 offset0:10 offset1:11
	ds_read2_b64 v[48:51], v56 offset0:12 offset1:13
	ds_read2_b64 v[56:59], v56 offset0:14 offset1:15
	ds_read2_b64 v[62:65], v2 offset0:12 offset1:13
	ds_read2_b64 v[74:77], v2 offset0:14 offset1:15
	s_waitcnt lgkmcnt(7)
	v_pk_add_f32 v[60:61], v[4:5], v[36:37]
	v_pk_add_f32 v[4:5], v[4:5], v[36:37] neg_lo:[0,1] neg_hi:[0,1]
	v_pk_add_f32 v[36:37], v[6:7], v[38:39]
	v_pk_add_f32 v[6:7], v[6:7], v[38:39] neg_lo:[0,1] neg_hi:[0,1]
	s_waitcnt lgkmcnt(3)
	v_pk_add_f32 v[66:67], v[22:23], v[50:51]
	v_pk_mul_f32 v[38:39], v[6:7], s[24:25]
	v_pk_add_f32 v[22:23], v[22:23], v[50:51] neg_lo:[0,1] neg_hi:[0,1]
	v_pk_fma_f32 v[6:7], v[6:7], s[22:23], v[38:39] op_sel:[0,0,1] op_sel_hi:[1,0,0]
	v_pk_add_f32 v[38:39], v[8:9], v[40:41]
	v_pk_add_f32 v[8:9], v[8:9], v[40:41] neg_lo:[0,1] neg_hi:[0,1]
	v_pk_mul_f32 v[50:51], v[22:23], s[44:45]
	v_pk_mul_f32 v[40:41], v[8:9], s[40:41]
	v_pk_fma_f32 v[22:23], v[22:23], s[50:51], v[50:51] op_sel:[0,0,1] op_sel_hi:[1,0,0] neg_lo:[1,0,0] neg_hi:[1,0,0]
	v_pk_fma_f32 v[8:9], v[8:9], s[38:39], v[40:41] op_sel:[0,0,1] op_sel_hi:[1,0,0]
	v_pk_add_f32 v[40:41], v[10:11], v[42:43]
	v_pk_add_f32 v[10:11], v[10:11], v[42:43] neg_lo:[0,1] neg_hi:[0,1]
	s_waitcnt lgkmcnt(2)
	v_pk_add_f32 v[50:51], v[24:25], v[56:57]
	v_pk_add_f32 v[24:25], v[24:25], v[56:57] neg_lo:[0,1] neg_hi:[0,1]
	v_pk_mul_f32 v[42:43], v[10:11], s[44:45]
	v_pk_mul_f32 v[56:57], v[24:25], s[40:41]
	v_pk_fma_f32 v[10:11], v[10:11], s[50:51], v[42:43] op_sel:[0,0,1] op_sel_hi:[1,0,0]
	v_pk_add_f32 v[42:43], v[20:21], v[48:49]
	v_pk_add_f32 v[48:49], v[20:21], v[48:49] neg_lo:[0,1] neg_hi:[0,1]
	v_pk_fma_f32 v[24:25], v[24:25], s[38:39], v[56:57] op_sel:[0,0,1] op_sel_hi:[1,0,0] neg_lo:[1,0,0] neg_hi:[1,0,0]
	v_pk_add_f32 v[56:57], v[26:27], v[58:59]
	v_pk_add_f32 v[26:27], v[26:27], v[58:59] op_sel:[1,1] op_sel_hi:[0,0] neg_lo:[0,1] neg_hi:[0,1]
	v_pk_mul_f32 v[58:59], v[26:27], s[24:25] op_sel:[1,0] op_sel_hi:[0,1]
	v_pk_add_f32 v[68:69], v[40:41], v[56:57]
	v_pk_add_f32 v[40:41], v[40:41], v[56:57] neg_lo:[0,1] neg_hi:[0,1]
	v_pk_fma_f32 v[26:27], v[26:27], s[22:23], v[58:59] op_sel:[1,0,1] op_sel_hi:[0,0,0] neg_lo:[1,0,0] neg_hi:[1,0,0]
	v_pk_mul_f32 v[56:57], v[40:41], s[40:41]
	v_pk_add_f32 v[20:21], v[4:5], v[48:49] op_sel:[0,1] op_sel_hi:[1,0] neg_hi:[0,1]
	v_pk_add_f32 v[4:5], v[4:5], v[48:49] op_sel:[0,1] op_sel_hi:[1,0] neg_lo:[0,1]
	v_pk_add_f32 v[48:49], v[6:7], v[22:23]
	v_pk_add_f32 v[6:7], v[6:7], v[22:23] neg_lo:[0,1] neg_hi:[0,1]
	v_pk_fma_f32 v[40:41], v[40:41], s[38:39], v[56:57] op_sel:[0,0,1] op_sel_hi:[1,0,0] neg_lo:[1,0,0] neg_hi:[1,0,0]
	v_pk_mul_f32 v[22:23], v[6:7], s[40:41]
	v_pk_add_f32 v[56:57], v[10:11], v[26:27]
	v_pk_add_f32 v[10:11], v[10:11], v[26:27] neg_lo:[0,1] neg_hi:[0,1]
	v_pk_add_f32 v[58:59], v[60:61], v[42:43]
	v_pk_add_f32 v[42:43], v[60:61], v[42:43] neg_lo:[0,1] neg_hi:[0,1]
	v_pk_add_f32 v[60:61], v[36:37], v[66:67]
	v_pk_add_f32 v[36:37], v[36:37], v[66:67] neg_lo:[0,1] neg_hi:[0,1]
	v_pk_fma_f32 v[6:7], v[6:7], s[38:39], v[22:23] op_sel:[0,0,1] op_sel_hi:[1,0,0]
	v_pk_add_f32 v[22:23], v[8:9], v[24:25]
	v_pk_add_f32 v[24:25], v[8:9], v[24:25] neg_lo:[0,1] neg_hi:[0,1]
	v_pk_mul_f32 v[26:27], v[10:11], s[40:41]
	v_pk_mul_f32 v[66:67], v[36:37], s[40:41]
	v_pk_fma_f32 v[10:11], v[10:11], s[38:39], v[26:27] op_sel:[0,0,1] op_sel_hi:[1,0,0] neg_lo:[1,0,0] neg_hi:[1,0,0]
	v_pk_fma_f32 v[36:37], v[36:37], s[38:39], v[66:67] op_sel:[0,0,1] op_sel_hi:[1,0,0]
	v_pk_add_f32 v[66:67], v[38:39], v[50:51]
	v_pk_add_f32 v[8:9], v[4:5], v[24:25] op_sel:[0,1] op_sel_hi:[1,0] neg_hi:[0,1]
	v_pk_add_f32 v[4:5], v[4:5], v[24:25] op_sel:[0,1] op_sel_hi:[1,0] neg_lo:[0,1]
	v_pk_add_f32 v[24:25], v[6:7], v[10:11]
	v_pk_add_f32 v[10:11], v[6:7], v[10:11] neg_lo:[0,1] neg_hi:[0,1]
	v_pk_add_f32 v[26:27], v[58:59], v[66:67]
	v_pk_add_f32 v[58:59], v[58:59], v[66:67] neg_lo:[0,1] neg_hi:[0,1]
	v_pk_add_f32 v[66:67], v[60:61], v[68:69]
	v_pk_add_f32 v[68:69], v[60:61], v[68:69] neg_lo:[0,1] neg_hi:[0,1]
	v_pk_add_f32 v[60:61], v[4:5], v[10:11] op_sel:[0,1] op_sel_hi:[1,0] neg_hi:[0,1]
	v_pk_add_f32 v[90:91], v[4:5], v[10:11] op_sel:[0,1] op_sel_hi:[1,0] neg_lo:[0,1]
	v_pk_add_f32 v[10:11], v[14:15], v[46:47] neg_lo:[0,1] neg_hi:[0,1]
	v_pk_add_f32 v[50:51], v[38:39], v[50:51] neg_lo:[0,1] neg_hi:[0,1]
	v_pk_add_f32 v[84:85], v[58:59], v[68:69] op_sel:[0,1] op_sel_hi:[1,0] neg_hi:[0,1]
	v_pk_add_f32 v[86:87], v[58:59], v[68:69] op_sel:[0,1] op_sel_hi:[1,0] neg_lo:[0,1]
	v_pk_add_f32 v[82:83], v[8:9], v[24:25]
	v_pk_add_f32 v[68:69], v[8:9], v[24:25] neg_lo:[0,1] neg_hi:[0,1]
	v_pk_add_f32 v[4:5], v[12:13], v[44:45]
	v_pk_add_f32 v[6:7], v[12:13], v[44:45] neg_lo:[0,1] neg_hi:[0,1]
	v_pk_add_f32 v[8:9], v[14:15], v[46:47]
	v_pk_mul_f32 v[12:13], v[10:11], s[24:25]
	v_pk_add_f32 v[14:15], v[16:17], v[52:53] neg_lo:[0,1] neg_hi:[0,1]
	v_pk_add_f32 v[70:71], v[20:21], v[22:23]
	v_pk_add_f32 v[20:21], v[20:21], v[22:23] neg_lo:[0,1] neg_hi:[0,1]
	v_pk_add_f32 v[22:23], v[48:49], v[56:57]
	v_pk_add_f32 v[48:49], v[48:49], v[56:57] neg_lo:[0,1] neg_hi:[0,1]
	v_pk_fma_f32 v[10:11], v[10:11], s[22:23], v[12:13] op_sel:[0,0,1] op_sel_hi:[1,0,0]
	v_pk_add_f32 v[12:13], v[16:17], v[52:53]
	v_pk_mul_f32 v[16:17], v[14:15], s[40:41]
	v_pk_add_f32 v[38:39], v[42:43], v[50:51] op_sel:[0,1] op_sel_hi:[1,0] neg_hi:[0,1]
	v_pk_add_f32 v[42:43], v[42:43], v[50:51] op_sel:[0,1] op_sel_hi:[1,0] neg_lo:[0,1]
	v_pk_add_f32 v[50:51], v[36:37], v[40:41]
	v_xor_b32_e32 v57, 0x80000000, v48
	v_mov_b32_e32 v56, v49
	v_pk_fma_f32 v[14:15], v[14:15], s[38:39], v[16:17] op_sel:[0,0,1] op_sel_hi:[1,0,0]
	v_pk_add_f32 v[16:17], v[18:19], v[54:55]
	v_pk_add_f32 v[18:19], v[18:19], v[54:55] neg_lo:[0,1] neg_hi:[0,1]
	v_pk_add_f32 v[130:131], v[26:27], v[66:67]
	v_pk_add_f32 v[92:93], v[26:27], v[66:67] neg_lo:[0,1] neg_hi:[0,1]
	v_pk_add_f32 v[88:89], v[38:39], v[50:51]
	v_pk_add_f32 v[72:73], v[38:39], v[50:51] neg_lo:[0,1] neg_hi:[0,1]
	v_pk_add_f32 v[96:97], v[70:71], v[22:23]
	v_pk_add_f32 v[50:51], v[70:71], v[22:23] neg_lo:[0,1] neg_hi:[0,1]
	v_pk_add_f32 v[66:67], v[20:21], v[56:57]
	v_pk_add_f32 v[80:81], v[20:21], v[56:57] neg_lo:[0,1] neg_hi:[0,1]
	v_pk_mul_f32 v[20:21], v[18:19], s[44:45]
	s_waitcnt lgkmcnt(1)
	v_pk_add_f32 v[24:25], v[28:29], v[62:63] neg_lo:[0,1] neg_hi:[0,1]
	v_pk_add_f32 v[26:27], v[30:31], v[64:65] neg_lo:[0,1] neg_hi:[0,1]
	v_pk_fma_f32 v[18:19], v[18:19], s[50:51], v[20:21] op_sel:[0,0,1] op_sel_hi:[1,0,0]
	v_pk_add_f32 v[20:21], v[28:29], v[62:63]
	v_pk_add_f32 v[22:23], v[30:31], v[64:65]
	v_pk_mul_f32 v[28:29], v[26:27], s[44:45]
	s_waitcnt lgkmcnt(0)
	v_pk_add_f32 v[30:31], v[32:33], v[74:75] neg_lo:[0,1] neg_hi:[0,1]
	v_pk_fma_f32 v[26:27], v[26:27], s[50:51], v[28:29] op_sel:[0,0,1] op_sel_hi:[1,0,0] neg_lo:[1,0,0] neg_hi:[1,0,0]
	v_pk_add_f32 v[28:29], v[32:33], v[74:75]
	v_pk_mul_f32 v[32:33], v[30:31], s[40:41]
	v_pk_add_f32 v[36:37], v[36:37], v[40:41] neg_lo:[0,1] neg_hi:[0,1]
	v_pk_fma_f32 v[30:31], v[30:31], s[38:39], v[32:33] op_sel:[0,0,1] op_sel_hi:[1,0,0] neg_lo:[1,0,0] neg_hi:[1,0,0]
	v_pk_add_f32 v[32:33], v[34:35], v[76:77]
	v_pk_add_f32 v[34:35], v[34:35], v[76:77] neg_lo:[0,1] neg_hi:[0,1]
	v_xor_b32_e32 v41, 0x80000000, v36
	v_mov_b32_e32 v40, v37
	v_pk_mul_f32 v[36:37], v[34:35], s[24:25]
	v_mov_b32_e32 v2, v130
	v_pk_fma_f32 v[34:35], v[34:35], s[22:23], v[36:37] op_sel:[0,0,1] op_sel_hi:[1,0,0] neg_lo:[1,0,0] neg_hi:[1,0,0]
	v_pk_add_f32 v[36:37], v[4:5], v[20:21]
	v_pk_add_f32 v[4:5], v[4:5], v[20:21] neg_lo:[0,1] neg_hi:[0,1]
	v_pk_add_f32 v[20:21], v[8:9], v[22:23]
	v_pk_add_f32 v[8:9], v[8:9], v[22:23] neg_lo:[0,1] neg_hi:[0,1]
	v_cmp_ne_u32_e64 s[0:1], 0, v144
	v_pk_mul_f32 v[22:23], v[8:9], s[40:41]
	v_pk_add_f32 v[78:79], v[42:43], v[40:41]
	v_pk_fma_f32 v[8:9], v[8:9], s[38:39], v[22:23] op_sel:[0,0,1] op_sel_hi:[1,0,0]
	v_pk_add_f32 v[22:23], v[12:13], v[28:29]
	v_pk_add_f32 v[28:29], v[12:13], v[28:29] neg_lo:[0,1] neg_hi:[0,1]
	v_pk_add_f32 v[94:95], v[42:43], v[40:41] neg_lo:[0,1] neg_hi:[0,1]
	v_pk_add_f32 v[12:13], v[16:17], v[32:33]
	v_pk_add_f32 v[16:17], v[16:17], v[32:33] op_sel:[1,1] op_sel_hi:[0,0] neg_lo:[0,1] neg_hi:[0,1]
	v_pk_mul_f32 v[32:33], v[16:17], s[40:41] op_sel:[1,0] op_sel_hi:[0,1]
	s_nop 0
	v_pk_fma_f32 v[16:17], v[16:17], s[38:39], v[32:33] op_sel:[1,0,1] op_sel_hi:[0,0,0] neg_lo:[1,0,0] neg_hi:[1,0,0]
	v_pk_add_f32 v[32:33], v[6:7], v[24:25] op_sel:[0,1] op_sel_hi:[1,0] neg_hi:[0,1]
	v_pk_add_f32 v[6:7], v[6:7], v[24:25] op_sel:[0,1] op_sel_hi:[1,0] neg_lo:[0,1]
	v_pk_add_f32 v[24:25], v[10:11], v[26:27]
	v_pk_add_f32 v[10:11], v[10:11], v[26:27] op_sel:[1,1] op_sel_hi:[0,0] neg_lo:[0,1] neg_hi:[0,1]
	v_pk_mul_f32 v[26:27], v[10:11], s[40:41] op_sel:[1,0] op_sel_hi:[0,1]
	s_nop 0
	v_pk_fma_f32 v[10:11], v[10:11], s[38:39], v[26:27] op_sel:[1,0,1] op_sel_hi:[0,0,0]
	v_pk_add_f32 v[26:27], v[14:15], v[30:31]
	v_pk_add_f32 v[30:31], v[14:15], v[30:31] neg_lo:[0,1] neg_hi:[0,1]
	s_nop 0
	v_pk_add_f32 v[14:15], v[18:19], v[34:35]
	v_pk_add_f32 v[18:19], v[18:19], v[34:35] op_sel:[1,1] op_sel_hi:[0,0] neg_lo:[0,1] neg_hi:[0,1]
	v_pk_mul_f32 v[34:35], v[18:19], s[40:41] op_sel:[1,0] op_sel_hi:[0,1]
	s_nop 0
	v_pk_fma_f32 v[18:19], v[18:19], s[38:39], v[34:35] op_sel:[1,0,1] op_sel_hi:[0,0,0] neg_lo:[1,0,0] neg_hi:[1,0,0]
	v_pk_add_f32 v[34:35], v[36:37], v[22:23]
	v_pk_add_f32 v[22:23], v[36:37], v[22:23] neg_lo:[0,1] neg_hi:[0,1]
	v_pk_add_f32 v[36:37], v[20:21], v[12:13]
	v_pk_add_f32 v[12:13], v[20:21], v[12:13] neg_lo:[0,1] neg_hi:[0,1]
	v_pk_add_f32 v[98:99], v[34:35], v[36:37]
	v_xor_b32_e32 v21, 0x80000000, v12
	v_mov_b32_e32 v20, v13
	v_pk_add_f32 v[12:13], v[4:5], v[28:29] op_sel:[0,1] op_sel_hi:[1,0] neg_hi:[0,1]
	v_pk_add_f32 v[4:5], v[4:5], v[28:29] op_sel:[0,1] op_sel_hi:[1,0] neg_lo:[0,1]
	v_pk_add_f32 v[28:29], v[8:9], v[16:17]
	v_pk_add_f32 v[8:9], v[8:9], v[16:17] neg_lo:[0,1] neg_hi:[0,1]
	v_pk_add_f32 v[100:101], v[34:35], v[36:37] neg_lo:[0,1] neg_hi:[0,1]
	v_xor_b32_e32 v17, 0x80000000, v8
	v_mov_b32_e32 v16, v9
	v_pk_add_f32 v[8:9], v[32:33], v[26:27]
	v_pk_add_f32 v[26:27], v[32:33], v[26:27] neg_lo:[0,1] neg_hi:[0,1]
	v_pk_add_f32 v[32:33], v[24:25], v[14:15]
	v_pk_add_f32 v[14:15], v[24:25], v[14:15] neg_lo:[0,1] neg_hi:[0,1]
	v_pk_add_f32 v[102:103], v[22:23], v[20:21]
	v_xor_b32_e32 v25, 0x80000000, v14
	v_mov_b32_e32 v24, v15
	v_pk_add_f32 v[14:15], v[6:7], v[30:31] op_sel:[0,1] op_sel_hi:[1,0] neg_hi:[0,1]
	v_pk_add_f32 v[6:7], v[6:7], v[30:31] op_sel:[0,1] op_sel_hi:[1,0] neg_lo:[0,1]
	v_pk_add_f32 v[30:31], v[10:11], v[18:19]
	v_pk_add_f32 v[10:11], v[10:11], v[18:19] neg_lo:[0,1] neg_hi:[0,1]
	v_pk_add_f32 v[104:105], v[22:23], v[20:21] neg_lo:[0,1] neg_hi:[0,1]
	v_xor_b32_e32 v19, 0x80000000, v10
	v_mov_b32_e32 v18, v11
	v_pk_add_f32 v[106:107], v[12:13], v[28:29]
	v_pk_add_f32 v[108:109], v[12:13], v[28:29] neg_lo:[0,1] neg_hi:[0,1]
	v_pk_add_f32 v[110:111], v[4:5], v[16:17]
	v_pk_add_f32 v[112:113], v[4:5], v[16:17] neg_lo:[0,1] neg_hi:[0,1]
	v_pk_add_f32 v[114:115], v[8:9], v[32:33]
	v_pk_add_f32 v[116:117], v[8:9], v[32:33] neg_lo:[0,1] neg_hi:[0,1]
	v_pk_add_f32 v[118:119], v[26:27], v[24:25]
	v_pk_add_f32 v[120:121], v[26:27], v[24:25] neg_lo:[0,1] neg_hi:[0,1]
	v_pk_add_f32 v[122:123], v[14:15], v[30:31]
	v_pk_add_f32 v[124:125], v[14:15], v[30:31] neg_lo:[0,1] neg_hi:[0,1]
	v_pk_add_f32 v[126:127], v[6:7], v[18:19]
	v_pk_add_f32 v[128:129], v[6:7], v[18:19] neg_lo:[0,1] neg_hi:[0,1]
	v_mov_b32_e32 v4, v131
	v_mov_b32_e32 v5, v3
	v_mov_b64_e32 v[6:7], v[2:3]
	s_and_saveexec_b64 s[50:51], s[0:1]
	s_xor_b64 s[0:1], exec, s[50:51]
	s_cbranch_execz .LBB0_576
	v_pk_add_f32 v[4:5], v[96:97], v[112:113]
	v_pk_add_f32 v[24:25], v[96:97], v[112:113] neg_lo:[0,1] neg_hi:[0,1]
	v_pk_add_f32 v[148:149], v[130:131], v[128:129]
	v_pk_add_f32 v[8:9], v[130:131], v[128:129] neg_lo:[0,1] neg_hi:[0,1]
	v_pk_add_f32 v[128:129], v[126:127], v[92:93]
	v_pk_add_f32 v[10:11], v[126:127], v[92:93] neg_lo:[0,1] neg_hi:[0,1]
	v_pk_add_f32 v[92:93], v[84:85], v[124:125]
	v_pk_add_f32 v[12:13], v[84:85], v[124:125] neg_lo:[0,1] neg_hi:[0,1]
	v_pk_add_f32 v[84:85], v[122:123], v[86:87]
	v_pk_add_f32 v[14:15], v[122:123], v[86:87] neg_lo:[0,1] neg_hi:[0,1]
	v_pk_add_f32 v[86:87], v[88:89], v[120:121]
	v_pk_add_f32 v[16:17], v[88:89], v[120:121] neg_lo:[0,1] neg_hi:[0,1]
	v_pk_add_f32 v[88:89], v[118:119], v[72:73]
	v_pk_add_f32 v[18:19], v[118:119], v[72:73] neg_lo:[0,1] neg_hi:[0,1]
	v_pk_add_f32 v[72:73], v[78:79], v[116:117]
	v_pk_add_f32 v[20:21], v[78:79], v[116:117] neg_lo:[0,1] neg_hi:[0,1]
	v_pk_add_f32 v[78:79], v[114:115], v[94:95]
	v_pk_add_f32 v[22:23], v[114:115], v[94:95] neg_lo:[0,1] neg_hi:[0,1]
	v_mov_b32_e32 v6, v4
	v_mov_b32_e32 v7, v25
	v_pk_mov_b32 v[4:5], v[4:5], v[24:25] op_sel:[1,0]
	v_pk_add_f32 v[94:95], v[110:111], v[50:51]
	v_pk_add_f32 v[24:25], v[110:111], v[50:51] neg_lo:[0,1] neg_hi:[0,1]
	v_pk_add_f32 v[50:51], v[66:67], v[108:109]
	v_pk_add_f32 v[26:27], v[66:67], v[108:109] neg_lo:[0,1] neg_hi:[0,1]
	v_pk_add_f32 v[66:67], v[106:107], v[80:81]
	v_pk_add_f32 v[28:29], v[106:107], v[80:81] neg_lo:[0,1] neg_hi:[0,1]
	v_pk_add_f32 v[80:81], v[82:83], v[104:105]
	v_pk_add_f32 v[30:31], v[82:83], v[104:105] neg_lo:[0,1] neg_hi:[0,1]
	v_pk_add_f32 v[82:83], v[102:103], v[68:69]
	v_pk_add_f32 v[32:33], v[102:103], v[68:69] neg_lo:[0,1] neg_hi:[0,1]
	v_pk_add_f32 v[68:69], v[60:61], v[100:101]
	v_pk_add_f32 v[34:35], v[60:61], v[100:101] neg_lo:[0,1] neg_hi:[0,1]
	v_pk_add_f32 v[60:61], v[98:99], v[90:91]
	v_pk_add_f32 v[36:37], v[98:99], v[90:91] neg_lo:[0,1] neg_hi:[0,1]
	v_pk_mul_f32 v[6:7], v[6:7], 0.5 op_sel_hi:[1,0]
	v_pk_mul_f32 v[4:5], v[4:5], s[46:47]
	v_mov_b32_e32 v39, v8
	v_mov_b32_e32 v38, v149
	v_mov_b32_e32 v41, v10
	v_mov_b32_e32 v40, v129
	v_mov_b32_e32 v43, v12
	v_mov_b32_e32 v42, v93
	v_mov_b32_e32 v45, v14
	v_mov_b32_e32 v44, v85
	v_mov_b32_e32 v47, v16
	v_mov_b32_e32 v46, v87
	v_mov_b32_e32 v49, v18
	v_mov_b32_e32 v48, v89
	v_mov_b32_e32 v53, v20
	v_mov_b32_e32 v52, v73
	v_mov_b32_e32 v55, v22
	v_mov_b32_e32 v54, v79
	v_mov_b32_e32 v57, v24
	v_mov_b32_e32 v56, v95
	v_mov_b32_e32 v59, v26
	v_mov_b32_e32 v58, v51
	v_mov_b32_e32 v63, v28
	v_mov_b32_e32 v62, v67
	v_mov_b32_e32 v65, v30
	v_mov_b32_e32 v64, v81
	v_mov_b32_e32 v71, v32
	v_mov_b32_e32 v70, v83
	v_mov_b32_e32 v75, v34
	v_mov_b32_e32 v74, v69
	v_mov_b32_e32 v77, v36
	v_mov_b32_e32 v76, v61
	v_mov_b32_e32 v8, v148
	v_mov_b32_e32 v10, v128
	v_mov_b32_e32 v12, v92
	v_mov_b32_e32 v14, v84
	v_mov_b32_e32 v16, v86
	v_mov_b32_e32 v18, v88
	v_mov_b32_e32 v20, v72
	v_mov_b32_e32 v22, v78
	v_mov_b32_e32 v24, v94
	v_mov_b32_e32 v26, v50
	v_mov_b32_e32 v28, v66
	v_mov_b32_e32 v30, v80
	v_mov_b32_e32 v32, v82
	v_mov_b32_e32 v34, v68
	v_mov_b32_e32 v36, v60
